# cumulative: PH3 staging-load hoist, bf16 cvt peephole, PH6 residual epilogue de-serialised (3 batches), PH7 ctx rows with batched slab loads
# speedup vs baseline: 1.0146x; 1.0146x over previous
; #define LDS_WAIT() asm volatile("s_waitcnt lgkmcnt(0)" ::: "memory")
; __device__ __forceinline__ void transpose_item(const float* W, int K, int N, bf16* WT, int row_off, LAS float* scr, int item, int lane) {
;     ...
; #pragma unroll 8
;     for (int i = 0; i < 32; ++i) { const int kk = 2 * i + (lane >> 5); scr[kk * 33 + (lane & 31)] = W[(size_t)(k0 + kk) * N + n0 + (lane & 31)]; }
;     LDS_WAIT(); asm volatile("" ::: "memory");
.LBB0_20:
	s_lshl_b32 s19, s11, 1
	s_lshl_b32 s22, s12, 1
	v_or_b32_e32 v27, s19, v3
	v_or_b32_e32 v28, s22, v6
	s_add_i32 s23, s19, 4
	s_add_i32 s24, s22, 4
	s_add_i32 s25, s19, 8
	s_add_i32 s26, s22, 8
	s_add_i32 s27, s19, 12
	s_add_i32 s28, s22, 12
	s_add_i32 s29, s19, 16
	s_add_i32 s30, s22, 16
	s_add_i32 s31, s19, 20
	s_add_i32 s33, s22, 20
	s_add_i32 s34, s19, 24
	s_add_i32 s35, s22, 24
	s_add_i32 s52, s19, 28
	s_add_i32 s53, s22, 28
	v_mad_u64_u32 v[28:29], s[20:21], v28, s14, v[22:23]
	v_mad_u64_u32 v[32:33], s[20:21], v27, s14, v[22:23]
	v_or_b32_e32 v27, s23, v3
	v_or_b32_e32 v31, s24, v6
	v_or_b32_e32 v40, s25, v3
	v_or_b32_e32 v38, s26, v6
	v_or_b32_e32 v44, s27, v3
	v_or_b32_e32 v42, s28, v6
	v_or_b32_e32 v48, s29, v3
	v_or_b32_e32 v46, s30, v6
	v_or_b32_e32 v52, s31, v3
	v_or_b32_e32 v50, s33, v6
	v_or_b32_e32 v56, s34, v3
	v_or_b32_e32 v54, s35, v6
	v_or_b32_e32 v60, s52, v3
	v_or_b32_e32 v58, s53, v6
	v_mad_u64_u32 v[34:35], s[20:21], v31, s14, v[22:23]
	v_mad_u64_u32 v[36:37], s[20:21], v27, s14, v[22:23]
	v_mad_u64_u32 v[38:39], s[20:21], v38, s14, v[22:23]
	v_mad_u64_u32 v[40:41], s[20:21], v40, s14, v[22:23]
	v_mad_u64_u32 v[42:43], s[20:21], v42, s14, v[22:23]
	v_mad_u64_u32 v[44:45], s[20:21], v44, s14, v[22:23]
	v_mad_u64_u32 v[46:47], s[20:21], v46, s14, v[22:23]
	v_mad_u64_u32 v[48:49], s[20:21], v48, s14, v[22:23]
	v_mad_u64_u32 v[50:51], s[20:21], v50, s14, v[22:23]
	v_mad_u64_u32 v[52:53], s[20:21], v52, s14, v[22:23]
	v_mad_u64_u32 v[54:55], s[20:21], v54, s14, v[22:23]
	v_mad_u64_u32 v[56:57], s[20:21], v56, s14, v[22:23]
	v_mad_u64_u32 v[58:59], s[20:21], v58, s14, v[22:23]
	v_mad_u64_u32 v[60:61], s[20:21], v60, s14, v[22:23]
	global_load_dword v27, v[28:29], off
	global_load_dword v31, v[32:33], off
	global_load_dword v62, v[34:35], off
	global_load_dword v63, v[36:37], off
	global_load_dword v64, v[38:39], off
	global_load_dword v65, v[40:41], off
	global_load_dword v66, v[42:43], off
	global_load_dword v67, v[44:45], off
	global_load_dword v68, v[46:47], off
	global_load_dword v69, v[48:49], off
	global_load_dword v70, v[50:51], off
	global_load_dword v71, v[52:53], off
	global_load_dword v72, v[54:55], off
	global_load_dword v73, v[56:57], off
	global_load_dword v74, v[58:59], off
	global_load_dword v75, v[60:61], off
	v_or_b32_e32 v32, s19, v1
	v_or_b32_e32 v28, s22, v2
	s_add_i32 s12, s12, 16
	s_add_i32 s11, s11, 16
	s_add_i32 s13, s13, -16
	v_mad_u64_u32 v[28:29], s[20:21], v28, s7, v[8:9]
	v_mad_u64_u32 v[32:33], s[20:21], v32, s7, v[8:9]
	v_or_b32_e32 v29, s23, v1
	v_or_b32_e32 v33, s24, v2
	v_or_b32_e32 v40, s25, v1
	v_or_b32_e32 v38, s26, v2
	v_or_b32_e32 v44, s27, v1
	v_or_b32_e32 v42, s28, v2
	v_or_b32_e32 v48, s29, v1
	v_or_b32_e32 v46, s30, v2
	v_or_b32_e32 v52, s31, v1
	v_or_b32_e32 v50, s33, v2
	v_or_b32_e32 v56, s34, v1
	v_or_b32_e32 v54, s35, v2
	v_or_b32_e32 v60, s52, v1
	v_or_b32_e32 v58, s53, v2
	s_cmp_lg_u32 s13, 0
	v_mad_u64_u32 v[34:35], s[20:21], v33, s7, v[8:9]
	v_mad_u64_u32 v[36:37], s[20:21], v29, s7, v[8:9]
	v_mad_u64_u32 v[38:39], s[20:21], v38, s7, v[8:9]
	v_mad_u64_u32 v[40:41], s[20:21], v40, s7, v[8:9]
	v_mad_u64_u32 v[42:43], s[20:21], v42, s7, v[8:9]
	v_mad_u64_u32 v[44:45], s[20:21], v44, s7, v[8:9]
	v_mad_u64_u32 v[46:47], s[20:21], v46, s7, v[8:9]
	v_mad_u64_u32 v[48:49], s[20:21], v48, s7, v[8:9]
	v_mad_u64_u32 v[50:51], s[20:21], v50, s7, v[8:9]
	v_mad_u64_u32 v[52:53], s[20:21], v52, s7, v[8:9]
	v_mad_u64_u32 v[54:55], s[20:21], v54, s7, v[8:9]
	v_mad_u64_u32 v[56:57], s[20:21], v56, s7, v[8:9]
	v_mad_u64_u32 v[58:59], s[20:21], v58, s7, v[8:9]
	v_mad_u64_u32 v[60:61], s[20:21], v60, s7, v[8:9]
	s_waitcnt vmcnt(15)
	ds_write_b32 v28, v27
	s_waitcnt vmcnt(14)
	ds_write_b32 v32, v31
	s_waitcnt vmcnt(13)
	ds_write_b32 v34, v62
	s_waitcnt vmcnt(12)
	ds_write_b32 v36, v63
	s_waitcnt vmcnt(11)
	ds_write_b32 v38, v64
	s_waitcnt vmcnt(10)
	ds_write_b32 v40, v65
	s_waitcnt vmcnt(9)
	ds_write_b32 v42, v66
	s_waitcnt vmcnt(8)
	ds_write_b32 v44, v67
	s_waitcnt vmcnt(7)
	ds_write_b32 v46, v68
	s_waitcnt vmcnt(6)
	ds_write_b32 v48, v69
	s_waitcnt vmcnt(5)
	ds_write_b32 v50, v70
	s_waitcnt vmcnt(4)
	ds_write_b32 v52, v71
	s_waitcnt vmcnt(3)
	ds_write_b32 v54, v72
	s_waitcnt vmcnt(2)
	ds_write_b32 v56, v73
	s_waitcnt vmcnt(1)
	ds_write_b32 v58, v74
	s_waitcnt vmcnt(0)
	ds_write_b32 v60, v75
	s_cbranch_scc1 .LBB0_20
; #define LAS __attribute__((address_space(3)))
; __device__ __forceinline__ unsigned pk2(float lo, float hi) { return f2bf(lo) | (f2bf(hi) << 16); }
; __device__ __forceinline__ void transpose_item(const float* W, int K, int N, bf16* WT, int row_off, LAS float* scr, int item, int lane) {
;     ...
;     for (int j = 0; j < 4; ++j) { const int n = (lane >> 3) + 8 * j; const LAS float* s = scr + (8 * c) * 33 + n;
;         u32x4 o; o.x = pk2(s[0 * 33], s[1 * 33]); o.y = pk2(s[2 * 33], s[3 * 33]); o.z = pk2(s[4 * 33], s[5 * 33]); o.w = pk2(s[6 * 33], s[7 * 33]);
;         *(u32x4*)(WT + (size_t)(row_off + n0 + n) * K + k0 + 8 * c) = o; }
	s_waitcnt lgkmcnt(0)
	ds_read2_b32 v[22:23], v9 offset1:8
	ds_read2_b32 v[36:37], v9 offset0:33 offset1:41
	ds_read2_b32 v[38:39], v9 offset0:66 offset1:74
	ds_read2_b32 v[40:41], v9 offset0:99 offset1:107
	ds_read2_b32 v[42:43], v9 offset0:132 offset1:140
	ds_read2_b32 v[44:45], v9 offset0:165 offset1:173
	s_waitcnt lgkmcnt(5)
	s_waitcnt lgkmcnt(4)
	v_cvt_pk_bf16_f32 v32, v22, v36
	s_waitcnt lgkmcnt(3)
	s_waitcnt lgkmcnt(2)
	ds_read2_b32 v[46:47], v9 offset0:198 offset1:206
	ds_read2_b32 v[48:49], v9 offset0:231 offset1:239
	v_cvt_pk_bf16_f32 v33, v38, v40
	s_waitcnt lgkmcnt(3)
	s_waitcnt lgkmcnt(2)
	v_cvt_pk_bf16_f32 v34, v42, v44
	s_waitcnt lgkmcnt(1)
	s_waitcnt lgkmcnt(0)
	s_nop 0
	v_or_b32_e32 v50, s10, v5
	s_lshl_b32 s4, s4, 1
	v_cvt_pk_bf16_f32 v35, v46, v48
	v_ashrrev_i32_e32 v51, 31, v50
	v_bfe_u32 v3, v23, 16, 1
	v_lshl_add_u64 v[28:29], v[10:11], 0, s[4:5]
	v_lshlrev_b64 v[50:51], 8, v[50:51]
	v_add3_u32 v3, v23, v3, s15
	v_bfe_u32 v6, v37, 16, 1
	v_lshl_add_u64 v[50:51], v[28:29], 0, v[50:51]
	v_lshrrev_b32_e32 v3, 16, v3
	v_add3_u32 v6, v37, v6, s15
	global_store_dwordx4 v[50:51], v[32:35], off
	v_or_b32_e32 v22, s10, v24
	v_ashrrev_i32_e32 v23, 31, v22
	v_and_or_b32 v32, v6, s16, v3
	s_nop 0
	s_nop 0
	s_nop 0
	v_cvt_pk_bf16_f32 v33, v39, v41
	v_cvt_pk_bf16_f32 v34, v43, v45
	s_nop 0
	s_nop 0
	v_lshlrev_b64 v[22:23], 8, v[22:23]
	v_cvt_pk_bf16_f32 v35, v47, v49
	ds_read2_b32 v[36:37], v9 offset0:16 offset1:24
	v_lshl_add_u64 v[22:23], v[28:29], 0, v[22:23]
	global_store_dwordx4 v[22:23], v[32:35], off
	ds_read2_b32 v[22:23], v9 offset0:49 offset1:57
	ds_read2_b32 v[38:39], v9 offset0:82 offset1:90
	ds_read2_b32 v[40:41], v9 offset0:115 offset1:123
	s_waitcnt lgkmcnt(3)
	s_nop 0
	s_nop 0
	s_waitcnt lgkmcnt(2)
	ds_read2_b32 v[42:43], v9 offset0:148 offset1:156
	ds_read2_b32 v[44:45], v9 offset0:181 offset1:189
	v_cvt_pk_bf16_f32 v32, v36, v22
	s_waitcnt lgkmcnt(3)
	s_waitcnt lgkmcnt(2)
	ds_read2_b32 v[46:47], v9 offset0:214 offset1:222
	ds_read2_b32 v[48:49], v9 offset0:247 offset1:255
	v_cvt_pk_bf16_f32 v33, v38, v40
	s_waitcnt lgkmcnt(3)
	s_waitcnt lgkmcnt(2)
	v_cvt_pk_bf16_f32 v34, v42, v44
	s_waitcnt lgkmcnt(1)
	s_waitcnt lgkmcnt(0)
	v_or_b32_e32 v50, s10, v25
	v_cvt_pk_bf16_f32 v35, v46, v48
	v_ashrrev_i32_e32 v51, 31, v50
	v_bfe_u32 v3, v37, 16, 1
	v_lshlrev_b64 v[50:51], 8, v[50:51]
	v_add3_u32 v3, v37, v3, s15
	v_bfe_u32 v6, v23, 16, 1
	v_lshl_add_u64 v[50:51], v[28:29], 0, v[50:51]
	v_lshrrev_b32_e32 v3, 16, v3
	v_add3_u32 v6, v23, v6, s15
	global_store_dwordx4 v[50:51], v[32:35], off
	v_or_b32_e32 v22, s10, v26
	v_ashrrev_i32_e32 v23, 31, v22
	v_and_or_b32 v32, v6, s16, v3
	s_nop 0
	s_nop 0
	s_nop 0
	v_cvt_pk_bf16_f32 v33, v39, v41
	v_cvt_pk_bf16_f32 v34, v43, v45
	v_bfe_u32 v3, v47, 16, 1
	v_add3_u32 v3, v47, v3, s15
	v_bfe_u32 v6, v49, 16, 1
	v_lshrrev_b32_e32 v3, 16, v3
	v_add3_u32 v6, v49, v6, s15
	v_lshlrev_b64 v[22:23], 8, v[22:23]
	v_and_or_b32 v35, v6, s16, v3
	v_lshl_add_u64 v[22:23], v[28:29], 0, v[22:23]
	global_store_dwordx4 v[22:23], v[32:35], off
	s_waitcnt lgkmcnt(0)
	s_mov_b64 s[10:11], 0

; #define LDS_WAIT() asm volatile("s_waitcnt lgkmcnt(0)" ::: "memory")
; __device__ __forceinline__ void transpose_item(const float* W, int K, int N, bf16* WT, int row_off, LAS float* scr, int item, int lane) {
;     ...
; #pragma unroll 8
;     for (int i = 0; i < 32; ++i) { const int kk = 2 * i + (lane >> 5); scr[kk * 33 + (lane & 31)] = W[(size_t)(k0 + kk) * N + n0 + (lane & 31)]; }
;     LDS_WAIT(); asm volatile("" ::: "memory");
.LBB0_24:
	s_lshl_b32 s20, s11, 1
	s_lshl_b32 s21, s4, 1
	v_or_b32_e32 v6, s21, v2
	s_add_i32 s22, s20, 4
	s_add_i32 s23, s21, 4
	s_add_i32 s24, s20, 8
	s_add_i32 s25, s21, 8
	s_add_i32 s26, s20, 12
	s_add_i32 s27, s21, 12
	s_add_i32 s28, s20, 16
	s_add_i32 s29, s21, 16
	s_add_i32 s30, s20, 20
	s_add_i32 s31, s21, 20
	s_add_i32 s33, s20, 24
	s_add_i32 s34, s21, 24
	s_add_i32 s35, s20, 28
	s_add_i32 s52, s21, 28
	v_or_b32_e32 v3, s20, v1
	v_mad_u64_u32 v[28:29], s[20:21], v6, s14, v[22:23]
	v_or_b32_e32 v27, s22, v1
	v_or_b32_e32 v31, s23, v2
	v_or_b32_e32 v62, s24, v1
	v_or_b32_e32 v63, s25, v2
	v_or_b32_e32 v64, s26, v1
	v_or_b32_e32 v65, s27, v2
	v_or_b32_e32 v66, s28, v1
	v_or_b32_e32 v67, s29, v2
	v_or_b32_e32 v68, s30, v1
	v_or_b32_e32 v69, s31, v2
	v_or_b32_e32 v70, s33, v1
	v_or_b32_e32 v71, s34, v2
	v_or_b32_e32 v72, s35, v1
	v_or_b32_e32 v73, s52, v2
	v_mad_u64_u32 v[32:33], s[20:21], v3, s14, v[22:23]
	v_mad_u64_u32 v[34:35], s[20:21], v31, s14, v[22:23]
	v_mad_u64_u32 v[36:37], s[20:21], v27, s14, v[22:23]
	v_mad_u64_u32 v[38:39], s[20:21], v63, s14, v[22:23]
	v_mad_u64_u32 v[40:41], s[20:21], v62, s14, v[22:23]
	v_mad_u64_u32 v[42:43], s[20:21], v65, s14, v[22:23]
	v_mad_u64_u32 v[44:45], s[20:21], v64, s14, v[22:23]
	v_mad_u64_u32 v[46:47], s[20:21], v67, s14, v[22:23]
	v_mad_u64_u32 v[48:49], s[20:21], v66, s14, v[22:23]
	v_mad_u64_u32 v[50:51], s[20:21], v69, s14, v[22:23]
	v_mad_u64_u32 v[52:53], s[20:21], v68, s14, v[22:23]
	v_mad_u64_u32 v[54:55], s[20:21], v71, s14, v[22:23]
	v_mad_u64_u32 v[56:57], s[20:21], v70, s14, v[22:23]
	v_mad_u64_u32 v[58:59], s[20:21], v73, s14, v[22:23]
	v_mad_u64_u32 v[60:61], s[20:21], v72, s14, v[22:23]
	global_load_dword v74, v[28:29], off
	global_load_dword v75, v[32:33], off
	global_load_dword v76, v[34:35], off
	global_load_dword v77, v[36:37], off
	global_load_dword v78, v[38:39], off
	global_load_dword v79, v[40:41], off
	global_load_dword v80, v[42:43], off
	global_load_dword v81, v[44:45], off
	global_load_dword v82, v[46:47], off
	global_load_dword v83, v[48:49], off
	global_load_dword v84, v[50:51], off
	global_load_dword v85, v[52:53], off
	global_load_dword v86, v[54:55], off
	global_load_dword v87, v[56:57], off
	global_load_dword v88, v[58:59], off
	global_load_dword v89, v[60:61], off
	s_add_i32 s4, s4, 16
	s_add_i32 s11, s11, 16
	s_add_i32 s19, s19, -16
	v_mad_u64_u32 v[28:29], s[20:21], v6, s7, v[8:9]
	s_cmp_lg_u32 s19, 0
	v_mad_u64_u32 v[32:33], s[20:21], v3, s7, v[8:9]
	v_mad_u64_u32 v[34:35], s[20:21], v31, s7, v[8:9]
	v_mad_u64_u32 v[36:37], s[20:21], v27, s7, v[8:9]
	v_mad_u64_u32 v[38:39], s[20:21], v63, s7, v[8:9]
	v_mad_u64_u32 v[40:41], s[20:21], v62, s7, v[8:9]
	v_mad_u64_u32 v[42:43], s[20:21], v65, s7, v[8:9]
	v_mad_u64_u32 v[44:45], s[20:21], v64, s7, v[8:9]
	v_mad_u64_u32 v[46:47], s[20:21], v67, s7, v[8:9]
	v_mad_u64_u32 v[48:49], s[20:21], v66, s7, v[8:9]
	v_mad_u64_u32 v[50:51], s[20:21], v69, s7, v[8:9]
	v_mad_u64_u32 v[52:53], s[20:21], v68, s7, v[8:9]
	v_mad_u64_u32 v[54:55], s[20:21], v71, s7, v[8:9]
	v_mad_u64_u32 v[56:57], s[20:21], v70, s7, v[8:9]
	v_mad_u64_u32 v[58:59], s[20:21], v73, s7, v[8:9]
	v_mad_u64_u32 v[60:61], s[20:21], v72, s7, v[8:9]
	s_waitcnt vmcnt(15)
	ds_write_b32 v28, v74
	s_waitcnt vmcnt(14)
	ds_write_b32 v32, v75
	s_waitcnt vmcnt(13)
	ds_write_b32 v34, v76
	s_waitcnt vmcnt(12)
	ds_write_b32 v36, v77
	s_waitcnt vmcnt(11)
	ds_write_b32 v38, v78
	s_waitcnt vmcnt(10)
	ds_write_b32 v40, v79
	s_waitcnt vmcnt(9)
	ds_write_b32 v42, v80
	s_waitcnt vmcnt(8)
	ds_write_b32 v44, v81
	s_waitcnt vmcnt(7)
	ds_write_b32 v46, v82
	s_waitcnt vmcnt(6)
	ds_write_b32 v48, v83
	s_waitcnt vmcnt(5)
	ds_write_b32 v50, v84
	s_waitcnt vmcnt(4)
	ds_write_b32 v52, v85
	s_waitcnt vmcnt(3)
	ds_write_b32 v54, v86
	s_waitcnt vmcnt(2)
	ds_write_b32 v56, v87
	s_waitcnt vmcnt(1)
	ds_write_b32 v58, v88
	s_waitcnt vmcnt(0)
	ds_write_b32 v60, v89
	s_cbranch_scc1 .LBB0_24
; #define LAS __attribute__((address_space(3)))
; __device__ __forceinline__ unsigned pk2(float lo, float hi) { return f2bf(lo) | (f2bf(hi) << 16); }
; __device__ __forceinline__ void transpose_item(const float* W, int K, int N, bf16* WT, int row_off, LAS float* scr, int item, int lane) {
;     ...
;     for (int j = 0; j < 4; ++j) { const int n = (lane >> 3) + 8 * j; const LAS float* s = scr + (8 * c) * 33 + n;
;         u32x4 o; o.x = pk2(s[0 * 33], s[1 * 33]); o.y = pk2(s[2 * 33], s[3 * 33]); o.z = pk2(s[4 * 33], s[5 * 33]); o.w = pk2(s[6 * 33], s[7 * 33]);
;         *(u32x4*)(WT + (size_t)(row_off + n0 + n) * K + k0 + 8 * c) = o; }
	s_waitcnt lgkmcnt(0)
	ds_read2_b32 v[22:23], v9 offset1:8
	ds_read2_b32 v[36:37], v9 offset0:33 offset1:41
	ds_read2_b32 v[38:39], v9 offset0:66 offset1:74
	ds_read2_b32 v[40:41], v9 offset0:99 offset1:107
	ds_read2_b32 v[42:43], v9 offset0:132 offset1:140
	s_waitcnt lgkmcnt(4)
	s_waitcnt lgkmcnt(3)
	ds_read2_b32 v[44:45], v9 offset0:165 offset1:173
	v_cvt_pk_bf16_f32 v32, v22, v36
	s_waitcnt lgkmcnt(3)
	s_waitcnt lgkmcnt(2)
	ds_read2_b32 v[46:47], v9 offset0:198 offset1:206
	ds_read2_b32 v[48:49], v9 offset0:231 offset1:239
	v_cvt_pk_bf16_f32 v33, v38, v40
	s_waitcnt lgkmcnt(3)
	s_waitcnt lgkmcnt(2)
	v_cvt_pk_bf16_f32 v34, v42, v44
	s_waitcnt lgkmcnt(1)
	s_nop 0
	s_nop 0
	s_waitcnt lgkmcnt(0)
	s_nop 0
	s_and_b64 s[12:13], s[12:13], exec
	s_nop 0
	s_nop 0
	v_or_b32_e32 v50, s10, v5
	s_cselect_b32 s4, 0x18000, 0
	v_cvt_pk_bf16_f32 v35, v46, v48
	v_ashrrev_i32_e32 v51, 31, v50
	v_bfe_u32 v3, v23, 16, 1
	v_lshl_add_u64 v[28:29], v[12:13], 0, s[4:5]
	v_lshlrev_b64 v[50:51], 7, v[50:51]
	v_add3_u32 v3, v23, v3, s15
	v_bfe_u32 v6, v37, 16, 1
	v_lshl_add_u64 v[50:51], v[28:29], 0, v[50:51]
	v_lshrrev_b32_e32 v3, 16, v3
	v_add3_u32 v6, v37, v6, s15
	global_store_dwordx4 v[50:51], v[32:35], off
	v_or_b32_e32 v22, s10, v24
	v_ashrrev_i32_e32 v23, 31, v22
	v_and_or_b32 v32, v6, s16, v3
	s_nop 0
	s_nop 0
	s_nop 0
	v_cvt_pk_bf16_f32 v33, v39, v41
	v_cvt_pk_bf16_f32 v34, v43, v45
	s_nop 0
	s_nop 0
	v_lshlrev_b64 v[22:23], 7, v[22:23]
	v_cvt_pk_bf16_f32 v35, v47, v49
	ds_read2_b32 v[36:37], v9 offset0:16 offset1:24
	v_lshl_add_u64 v[22:23], v[28:29], 0, v[22:23]
	global_store_dwordx4 v[22:23], v[32:35], off
	ds_read2_b32 v[22:23], v9 offset0:49 offset1:57
	ds_read2_b32 v[38:39], v9 offset0:82 offset1:90
	ds_read2_b32 v[40:41], v9 offset0:115 offset1:123
	s_waitcnt lgkmcnt(3)
	s_nop 0
	s_nop 0
	s_waitcnt lgkmcnt(2)
	ds_read2_b32 v[42:43], v9 offset0:148 offset1:156
	ds_read2_b32 v[44:45], v9 offset0:181 offset1:189
	v_cvt_pk_bf16_f32 v32, v36, v22
	s_waitcnt lgkmcnt(3)
	s_waitcnt lgkmcnt(2)
	ds_read2_b32 v[46:47], v9 offset0:214 offset1:222
	ds_read2_b32 v[48:49], v9 offset0:247 offset1:255
	v_cvt_pk_bf16_f32 v33, v38, v40
	s_waitcnt lgkmcnt(3)
	s_waitcnt lgkmcnt(2)
	v_cvt_pk_bf16_f32 v34, v42, v44
	s_waitcnt lgkmcnt(1)
	s_waitcnt lgkmcnt(0)
	v_or_b32_e32 v50, s10, v25
	v_cvt_pk_bf16_f32 v35, v46, v48
	v_ashrrev_i32_e32 v51, 31, v50
	v_bfe_u32 v3, v37, 16, 1
	v_lshlrev_b64 v[50:51], 7, v[50:51]
	v_add3_u32 v3, v37, v3, s15
	v_bfe_u32 v6, v23, 16, 1
	v_lshl_add_u64 v[50:51], v[28:29], 0, v[50:51]
	v_lshrrev_b32_e32 v3, 16, v3
	v_add3_u32 v6, v23, v6, s15
	global_store_dwordx4 v[50:51], v[32:35], off
	v_or_b32_e32 v22, s10, v26
	v_ashrrev_i32_e32 v23, 31, v22
	v_and_or_b32 v32, v6, s16, v3
	s_nop 0
	s_nop 0
	s_nop 0
	v_cvt_pk_bf16_f32 v33, v39, v41
	v_cvt_pk_bf16_f32 v34, v43, v45
	v_bfe_u32 v3, v47, 16, 1
	v_add3_u32 v3, v47, v3, s15
	v_bfe_u32 v6, v49, 16, 1
	v_lshrrev_b32_e32 v3, 16, v3
	v_add3_u32 v6, v49, v6, s15
	v_lshlrev_b64 v[22:23], 7, v[22:23]
	v_and_or_b32 v35, v6, s16, v3
	v_lshl_add_u64 v[22:23], v[28:29], 0, v[22:23]
	global_store_dwordx4 v[22:23], v[32:35], off
	s_waitcnt lgkmcnt(0)

; #define LDS_WAIT() asm volatile("s_waitcnt lgkmcnt(0)" ::: "memory")
; __device__ __forceinline__ void transpose_item(const float* W, int K, int N, bf16* WT, int row_off, LAS float* scr, int item, int lane) {
;     ...
; #pragma unroll 8
;     for (int i = 0; i < 32; ++i) { const int kk = 2 * i + (lane >> 5); scr[kk * 33 + (lane & 31)] = W[(size_t)(k0 + kk) * N + n0 + (lane & 31)]; }
;     LDS_WAIT(); asm volatile("" ::: "memory");
.LBB0_29:
	s_lshl_b32 s20, s11, 1
	s_lshl_b32 s21, s4, 1
	v_or_b32_e32 v6, s21, v2
	s_add_i32 s22, s20, 4
	s_add_i32 s23, s21, 4
	s_add_i32 s24, s20, 8
	s_add_i32 s25, s21, 8
	s_add_i32 s26, s20, 12
	s_add_i32 s27, s21, 12
	s_add_i32 s28, s20, 16
	s_add_i32 s29, s21, 16
	s_add_i32 s30, s20, 20
	s_add_i32 s31, s21, 20
	s_add_i32 s33, s20, 24
	s_add_i32 s34, s21, 24
	s_add_i32 s35, s20, 28
	s_add_i32 s52, s21, 28
	v_or_b32_e32 v3, s20, v1
	v_mad_u64_u32 v[28:29], s[20:21], v6, s14, v[22:23]
	v_or_b32_e32 v27, s22, v1
	v_or_b32_e32 v31, s23, v2
	v_or_b32_e32 v62, s24, v1
	v_or_b32_e32 v63, s25, v2
	v_or_b32_e32 v64, s26, v1
	v_or_b32_e32 v65, s27, v2
	v_or_b32_e32 v66, s28, v1
	v_or_b32_e32 v67, s29, v2
	v_or_b32_e32 v68, s30, v1
	v_or_b32_e32 v69, s31, v2
	v_or_b32_e32 v70, s33, v1
	v_or_b32_e32 v71, s34, v2
	v_or_b32_e32 v72, s35, v1
	v_or_b32_e32 v73, s52, v2
	v_mad_u64_u32 v[32:33], s[20:21], v3, s14, v[22:23]
	v_mad_u64_u32 v[34:35], s[20:21], v31, s14, v[22:23]
	v_mad_u64_u32 v[36:37], s[20:21], v27, s14, v[22:23]
	v_mad_u64_u32 v[38:39], s[20:21], v63, s14, v[22:23]
	v_mad_u64_u32 v[40:41], s[20:21], v62, s14, v[22:23]
	v_mad_u64_u32 v[42:43], s[20:21], v65, s14, v[22:23]
	v_mad_u64_u32 v[44:45], s[20:21], v64, s14, v[22:23]
	v_mad_u64_u32 v[46:47], s[20:21], v67, s14, v[22:23]
	v_mad_u64_u32 v[48:49], s[20:21], v66, s14, v[22:23]
	v_mad_u64_u32 v[50:51], s[20:21], v69, s14, v[22:23]
	v_mad_u64_u32 v[52:53], s[20:21], v68, s14, v[22:23]
	v_mad_u64_u32 v[54:55], s[20:21], v71, s14, v[22:23]
	v_mad_u64_u32 v[56:57], s[20:21], v70, s14, v[22:23]
	v_mad_u64_u32 v[58:59], s[20:21], v73, s14, v[22:23]
	v_mad_u64_u32 v[60:61], s[20:21], v72, s14, v[22:23]
	global_load_dword v74, v[28:29], off
	global_load_dword v75, v[32:33], off
	global_load_dword v76, v[34:35], off
	global_load_dword v77, v[36:37], off
	global_load_dword v78, v[38:39], off
	global_load_dword v79, v[40:41], off
	global_load_dword v80, v[42:43], off
	global_load_dword v81, v[44:45], off
	global_load_dword v82, v[46:47], off
	global_load_dword v83, v[48:49], off
	global_load_dword v84, v[50:51], off
	global_load_dword v85, v[52:53], off
	global_load_dword v86, v[54:55], off
	global_load_dword v87, v[56:57], off
	global_load_dword v88, v[58:59], off
	global_load_dword v89, v[60:61], off
	s_add_i32 s4, s4, 16
	s_add_i32 s11, s11, 16
	s_add_i32 s19, s19, -16
	v_mad_u64_u32 v[28:29], s[20:21], v6, s7, v[8:9]
	s_cmp_lg_u32 s19, 0
	v_mad_u64_u32 v[32:33], s[20:21], v3, s7, v[8:9]
	v_mad_u64_u32 v[34:35], s[20:21], v31, s7, v[8:9]
	v_mad_u64_u32 v[36:37], s[20:21], v27, s7, v[8:9]
	v_mad_u64_u32 v[38:39], s[20:21], v63, s7, v[8:9]
	v_mad_u64_u32 v[40:41], s[20:21], v62, s7, v[8:9]
	v_mad_u64_u32 v[42:43], s[20:21], v65, s7, v[8:9]
	v_mad_u64_u32 v[44:45], s[20:21], v64, s7, v[8:9]
	v_mad_u64_u32 v[46:47], s[20:21], v67, s7, v[8:9]
	v_mad_u64_u32 v[48:49], s[20:21], v66, s7, v[8:9]
	v_mad_u64_u32 v[50:51], s[20:21], v69, s7, v[8:9]
	v_mad_u64_u32 v[52:53], s[20:21], v68, s7, v[8:9]
	v_mad_u64_u32 v[54:55], s[20:21], v71, s7, v[8:9]
	v_mad_u64_u32 v[56:57], s[20:21], v70, s7, v[8:9]
	v_mad_u64_u32 v[58:59], s[20:21], v73, s7, v[8:9]
	v_mad_u64_u32 v[60:61], s[20:21], v72, s7, v[8:9]
	s_waitcnt vmcnt(15)
	ds_write_b32 v28, v74
	s_waitcnt vmcnt(14)
	ds_write_b32 v32, v75
	s_waitcnt vmcnt(13)
	ds_write_b32 v34, v76
	s_waitcnt vmcnt(12)
	ds_write_b32 v36, v77
	s_waitcnt vmcnt(11)
	ds_write_b32 v38, v78
	s_waitcnt vmcnt(10)
	ds_write_b32 v40, v79
	s_waitcnt vmcnt(9)
	ds_write_b32 v42, v80
	s_waitcnt vmcnt(8)
	ds_write_b32 v44, v81
	s_waitcnt vmcnt(7)
	ds_write_b32 v46, v82
	s_waitcnt vmcnt(6)
	ds_write_b32 v48, v83
	s_waitcnt vmcnt(5)
	ds_write_b32 v50, v84
	s_waitcnt vmcnt(4)
	ds_write_b32 v52, v85
	s_waitcnt vmcnt(3)
	ds_write_b32 v54, v86
	s_waitcnt vmcnt(2)
	ds_write_b32 v56, v87
	s_waitcnt vmcnt(1)
	ds_write_b32 v58, v88
	s_waitcnt vmcnt(0)
	ds_write_b32 v60, v89
	s_cbranch_scc1 .LBB0_29
; #define LAS __attribute__((address_space(3)))
; __device__ __forceinline__ unsigned pk2(float lo, float hi) { return f2bf(lo) | (f2bf(hi) << 16); }
; __device__ __forceinline__ void transpose_item(const float* W, int K, int N, bf16* WT, int row_off, LAS float* scr, int item, int lane) {
;     ...
;     for (int j = 0; j < 4; ++j) { const int n = (lane >> 3) + 8 * j; const LAS float* s = scr + (8 * c) * 33 + n;
;         u32x4 o; o.x = pk2(s[0 * 33], s[1 * 33]); o.y = pk2(s[2 * 33], s[3 * 33]); o.z = pk2(s[4 * 33], s[5 * 33]); o.w = pk2(s[6 * 33], s[7 * 33]);
;         *(u32x4*)(WT + (size_t)(row_off + n0 + n) * K + k0 + 8 * c) = o; }
	s_waitcnt lgkmcnt(0)
	ds_read2_b32 v[22:23], v9 offset1:8
	ds_read2_b32 v[36:37], v9 offset0:33 offset1:41
	ds_read2_b32 v[38:39], v9 offset0:66 offset1:74
	ds_read2_b32 v[40:41], v9 offset0:99 offset1:107
	ds_read2_b32 v[42:43], v9 offset0:132 offset1:140
	s_waitcnt lgkmcnt(4)
	s_waitcnt lgkmcnt(3)
	ds_read2_b32 v[44:45], v9 offset0:165 offset1:173
	v_cvt_pk_bf16_f32 v32, v22, v36
	s_waitcnt lgkmcnt(3)
	s_waitcnt lgkmcnt(2)
	ds_read2_b32 v[46:47], v9 offset0:198 offset1:206
	ds_read2_b32 v[48:49], v9 offset0:231 offset1:239
	v_cvt_pk_bf16_f32 v33, v38, v40
	s_waitcnt lgkmcnt(3)
	s_waitcnt lgkmcnt(2)
	v_cvt_pk_bf16_f32 v34, v42, v44
	s_waitcnt lgkmcnt(1)
	s_nop 0
	s_nop 0
	s_waitcnt lgkmcnt(0)
	s_nop 0
	s_and_b64 s[12:13], s[12:13], exec
	s_nop 0
	s_nop 0
	v_or_b32_e32 v50, s10, v5
	s_cselect_b32 s4, 0x18000, 0
	v_cvt_pk_bf16_f32 v35, v46, v48
	v_ashrrev_i32_e32 v51, 31, v50
	v_bfe_u32 v3, v23, 16, 1
	v_lshl_add_u64 v[28:29], v[14:15], 0, s[4:5]
	v_lshlrev_b64 v[50:51], 7, v[50:51]
	v_add3_u32 v3, v23, v3, s15
	v_bfe_u32 v6, v37, 16, 1
	v_lshl_add_u64 v[50:51], v[28:29], 0, v[50:51]
	v_lshrrev_b32_e32 v3, 16, v3
	v_add3_u32 v6, v37, v6, s15
	global_store_dwordx4 v[50:51], v[32:35], off
	v_or_b32_e32 v22, s10, v24
	v_ashrrev_i32_e32 v23, 31, v22
	v_and_or_b32 v32, v6, s16, v3
	s_nop 0
	s_nop 0
	s_nop 0
	v_cvt_pk_bf16_f32 v33, v39, v41
	v_cvt_pk_bf16_f32 v34, v43, v45
	s_nop 0
	s_nop 0
	v_lshlrev_b64 v[22:23], 7, v[22:23]
	v_cvt_pk_bf16_f32 v35, v47, v49
	ds_read2_b32 v[36:37], v9 offset0:16 offset1:24
	v_lshl_add_u64 v[22:23], v[28:29], 0, v[22:23]
	global_store_dwordx4 v[22:23], v[32:35], off
	ds_read2_b32 v[22:23], v9 offset0:49 offset1:57
	ds_read2_b32 v[38:39], v9 offset0:82 offset1:90
	ds_read2_b32 v[40:41], v9 offset0:115 offset1:123
	s_waitcnt lgkmcnt(3)
	s_nop 0
	s_nop 0
	s_waitcnt lgkmcnt(2)
	ds_read2_b32 v[42:43], v9 offset0:148 offset1:156
	ds_read2_b32 v[44:45], v9 offset0:181 offset1:189
	v_cvt_pk_bf16_f32 v32, v36, v22
	s_waitcnt lgkmcnt(3)
	s_waitcnt lgkmcnt(2)
	ds_read2_b32 v[46:47], v9 offset0:214 offset1:222
	ds_read2_b32 v[48:49], v9 offset0:247 offset1:255
	v_cvt_pk_bf16_f32 v33, v38, v40
	s_waitcnt lgkmcnt(3)
	s_waitcnt lgkmcnt(2)
	v_cvt_pk_bf16_f32 v34, v42, v44
	s_waitcnt lgkmcnt(1)
	s_waitcnt lgkmcnt(0)
	v_or_b32_e32 v50, s10, v25
	v_cvt_pk_bf16_f32 v35, v46, v48
	v_ashrrev_i32_e32 v51, 31, v50
	v_bfe_u32 v3, v37, 16, 1
	v_lshlrev_b64 v[50:51], 7, v[50:51]
	v_add3_u32 v3, v37, v3, s15
	v_bfe_u32 v6, v23, 16, 1
	v_lshl_add_u64 v[50:51], v[28:29], 0, v[50:51]
	v_lshrrev_b32_e32 v3, 16, v3
	v_add3_u32 v6, v23, v6, s15
	global_store_dwordx4 v[50:51], v[32:35], off
	v_or_b32_e32 v22, s10, v26
	v_ashrrev_i32_e32 v23, 31, v22
	v_and_or_b32 v32, v6, s16, v3
	s_nop 0
	s_nop 0
	s_nop 0
	v_cvt_pk_bf16_f32 v33, v39, v41
	v_cvt_pk_bf16_f32 v34, v43, v45
	v_bfe_u32 v3, v47, 16, 1
	v_add3_u32 v3, v47, v3, s15
	v_bfe_u32 v6, v49, 16, 1
	v_lshrrev_b32_e32 v3, 16, v3
	v_add3_u32 v6, v49, v6, s15
	v_lshlrev_b64 v[22:23], 7, v[22:23]
	v_and_or_b32 v35, v6, s16, v3
	v_lshl_add_u64 v[22:23], v[28:29], 0, v[22:23]
	global_store_dwordx4 v[22:23], v[32:35], off
	s_waitcnt lgkmcnt(0)

; #define LDS_WAIT() asm volatile("s_waitcnt lgkmcnt(0)" ::: "memory")
; __device__ __forceinline__ void transpose_item(const float* W, int K, int N, bf16* WT, int row_off, LAS float* scr, int item, int lane) {
;     ...
; #pragma unroll 8
;     for (int i = 0; i < 32; ++i) { const int kk = 2 * i + (lane >> 5); scr[kk * 33 + (lane & 31)] = W[(size_t)(k0 + kk) * N + n0 + (lane & 31)]; }
;     LDS_WAIT(); asm volatile("" ::: "memory");
.LBB0_34:
	s_lshl_b32 s19, s4, 1
	s_lshl_b32 s22, s11, 1
	v_or_b32_e32 v27, s19, v3
	v_or_b32_e32 v28, s22, v6
	s_add_i32 s23, s19, 4
	s_add_i32 s24, s22, 4
	s_add_i32 s25, s19, 8
	s_add_i32 s26, s22, 8
	s_add_i32 s27, s19, 12
	s_add_i32 s28, s22, 12
	s_add_i32 s29, s19, 16
	s_add_i32 s30, s22, 16
	s_add_i32 s31, s19, 20
	s_add_i32 s33, s22, 20
	s_add_i32 s34, s19, 24
	s_add_i32 s35, s22, 24
	s_add_i32 s52, s19, 28
	s_add_i32 s53, s22, 28
	v_mad_i64_i32 v[28:29], s[20:21], v28, s17, v[22:23]
	v_mad_i64_i32 v[32:33], s[20:21], v27, s17, v[22:23]
	v_or_b32_e32 v27, s23, v3
	v_or_b32_e32 v31, s24, v6
	v_or_b32_e32 v40, s25, v3
	v_or_b32_e32 v38, s26, v6
	v_or_b32_e32 v44, s27, v3
	v_or_b32_e32 v42, s28, v6
	v_or_b32_e32 v48, s29, v3
	v_or_b32_e32 v46, s30, v6
	v_or_b32_e32 v52, s31, v3
	v_or_b32_e32 v50, s33, v6
	v_or_b32_e32 v56, s34, v3
	v_or_b32_e32 v54, s35, v6
	v_or_b32_e32 v60, s52, v3
	v_or_b32_e32 v58, s53, v6
	v_mad_i64_i32 v[34:35], s[20:21], v31, s17, v[22:23]
	v_mad_i64_i32 v[36:37], s[20:21], v27, s17, v[22:23]
	v_mad_i64_i32 v[38:39], s[20:21], v38, s17, v[22:23]
	v_mad_i64_i32 v[40:41], s[20:21], v40, s17, v[22:23]
	v_mad_i64_i32 v[42:43], s[20:21], v42, s17, v[22:23]
	v_mad_i64_i32 v[44:45], s[20:21], v44, s17, v[22:23]
	v_mad_i64_i32 v[46:47], s[20:21], v46, s17, v[22:23]
	v_mad_i64_i32 v[48:49], s[20:21], v48, s17, v[22:23]
	v_mad_i64_i32 v[50:51], s[20:21], v50, s17, v[22:23]
	v_mad_i64_i32 v[52:53], s[20:21], v52, s17, v[22:23]
	v_mad_i64_i32 v[54:55], s[20:21], v54, s17, v[22:23]
	v_mad_i64_i32 v[56:57], s[20:21], v56, s17, v[22:23]
	v_mad_i64_i32 v[58:59], s[20:21], v58, s17, v[22:23]
	v_mad_i64_i32 v[60:61], s[20:21], v60, s17, v[22:23]
	global_load_dword v27, v[28:29], off
	global_load_dword v31, v[32:33], off
	global_load_dword v62, v[34:35], off
	global_load_dword v63, v[36:37], off
	global_load_dword v64, v[38:39], off
	global_load_dword v65, v[40:41], off
	global_load_dword v66, v[42:43], off
	global_load_dword v67, v[44:45], off
	global_load_dword v68, v[46:47], off
	global_load_dword v69, v[48:49], off
	global_load_dword v70, v[50:51], off
	global_load_dword v71, v[52:53], off
	global_load_dword v72, v[54:55], off
	global_load_dword v73, v[56:57], off
	global_load_dword v74, v[58:59], off
	global_load_dword v75, v[60:61], off
	v_or_b32_e32 v32, s19, v1
	v_or_b32_e32 v28, s22, v2
	s_add_i32 s11, s11, 16
	s_add_i32 s4, s4, 16
	s_add_i32 s13, s13, -16
	v_mad_u64_u32 v[28:29], s[20:21], v28, s7, v[8:9]
	v_mad_u64_u32 v[32:33], s[20:21], v32, s7, v[8:9]
	v_or_b32_e32 v29, s23, v1
	v_or_b32_e32 v33, s24, v2
	v_or_b32_e32 v40, s25, v1
	v_or_b32_e32 v38, s26, v2
	v_or_b32_e32 v44, s27, v1
	v_or_b32_e32 v42, s28, v2
	v_or_b32_e32 v48, s29, v1
	v_or_b32_e32 v46, s30, v2
	v_or_b32_e32 v52, s31, v1
	v_or_b32_e32 v50, s33, v2
	v_or_b32_e32 v56, s34, v1
	v_or_b32_e32 v54, s35, v2
	v_or_b32_e32 v60, s52, v1
	v_or_b32_e32 v58, s53, v2
	s_cmp_lg_u32 s13, 0
	v_mad_u64_u32 v[34:35], s[20:21], v33, s7, v[8:9]
	v_mad_u64_u32 v[36:37], s[20:21], v29, s7, v[8:9]
	v_mad_u64_u32 v[38:39], s[20:21], v38, s7, v[8:9]
	v_mad_u64_u32 v[40:41], s[20:21], v40, s7, v[8:9]
	v_mad_u64_u32 v[42:43], s[20:21], v42, s7, v[8:9]
	v_mad_u64_u32 v[44:45], s[20:21], v44, s7, v[8:9]
	v_mad_u64_u32 v[46:47], s[20:21], v46, s7, v[8:9]
	v_mad_u64_u32 v[48:49], s[20:21], v48, s7, v[8:9]
	v_mad_u64_u32 v[50:51], s[20:21], v50, s7, v[8:9]
	v_mad_u64_u32 v[52:53], s[20:21], v52, s7, v[8:9]
	v_mad_u64_u32 v[54:55], s[20:21], v54, s7, v[8:9]
	v_mad_u64_u32 v[56:57], s[20:21], v56, s7, v[8:9]
	v_mad_u64_u32 v[58:59], s[20:21], v58, s7, v[8:9]
	v_mad_u64_u32 v[60:61], s[20:21], v60, s7, v[8:9]
	s_waitcnt vmcnt(15)
	ds_write_b32 v28, v27
	s_waitcnt vmcnt(14)
	ds_write_b32 v32, v31
	s_waitcnt vmcnt(13)
	ds_write_b32 v34, v62
	s_waitcnt vmcnt(12)
	ds_write_b32 v36, v63
	s_waitcnt vmcnt(11)
	ds_write_b32 v38, v64
	s_waitcnt vmcnt(10)
	ds_write_b32 v40, v65
	s_waitcnt vmcnt(9)
	ds_write_b32 v42, v66
	s_waitcnt vmcnt(8)
	ds_write_b32 v44, v67
	s_waitcnt vmcnt(7)
	ds_write_b32 v46, v68
	s_waitcnt vmcnt(6)
	ds_write_b32 v48, v69
	s_waitcnt vmcnt(5)
	ds_write_b32 v50, v70
	s_waitcnt vmcnt(4)
	ds_write_b32 v52, v71
	s_waitcnt vmcnt(3)
	ds_write_b32 v54, v72
	s_waitcnt vmcnt(2)
	ds_write_b32 v56, v73
	s_waitcnt vmcnt(1)
	ds_write_b32 v58, v74
	s_waitcnt vmcnt(0)
	ds_write_b32 v60, v75
	s_cbranch_scc1 .LBB0_34
; #define LAS __attribute__((address_space(3)))
; __device__ __forceinline__ unsigned pk2(float lo, float hi) { return f2bf(lo) | (f2bf(hi) << 16); }
; __device__ __forceinline__ void transpose_item(const float* W, int K, int N, bf16* WT, int row_off, LAS float* scr, int item, int lane) {
;     ...
;     for (int j = 0; j < 4; ++j) { const int n = (lane >> 3) + 8 * j; const LAS float* s = scr + (8 * c) * 33 + n;
;         u32x4 o; o.x = pk2(s[0 * 33], s[1 * 33]); o.y = pk2(s[2 * 33], s[3 * 33]); o.z = pk2(s[4 * 33], s[5 * 33]); o.w = pk2(s[6 * 33], s[7 * 33]);
;         *(u32x4*)(WT + (size_t)(row_off + n0 + n) * K + k0 + 8 * c) = o; }
	s_waitcnt lgkmcnt(0)
	ds_read2_b32 v[22:23], v9 offset1:8
	ds_read2_b32 v[36:37], v9 offset0:33 offset1:41
	ds_read2_b32 v[38:39], v9 offset0:66 offset1:74
	ds_read2_b32 v[40:41], v9 offset0:99 offset1:107
	ds_read2_b32 v[42:43], v9 offset0:132 offset1:140
	ds_read2_b32 v[44:45], v9 offset0:165 offset1:173
	s_waitcnt lgkmcnt(5)
	s_waitcnt lgkmcnt(4)
	v_cvt_pk_bf16_f32 v32, v22, v36
	s_waitcnt lgkmcnt(3)
	s_waitcnt lgkmcnt(2)
	ds_read2_b32 v[46:47], v9 offset0:198 offset1:206
	ds_read2_b32 v[48:49], v9 offset0:231 offset1:239
	v_cvt_pk_bf16_f32 v33, v38, v40
	s_waitcnt lgkmcnt(3)
	s_waitcnt lgkmcnt(2)
	v_cvt_pk_bf16_f32 v34, v42, v44
	s_waitcnt lgkmcnt(1)
	s_waitcnt lgkmcnt(0)
	s_nop 0
	v_or_b32_e32 v50, s10, v5
	s_ashr_i32 s13, s12, 31
	v_cvt_pk_bf16_f32 v35, v46, v48
	v_ashrrev_i32_e32 v51, 31, v50
	v_bfe_u32 v3, v23, 16, 1
	v_lshl_add_u64 v[28:29], s[12:13], 1, v[16:17]
	v_lshlrev_b64 v[50:51], 12, v[50:51]
	v_add3_u32 v3, v23, v3, s15
	v_bfe_u32 v6, v37, 16, 1
	v_lshl_add_u64 v[50:51], v[28:29], 0, v[50:51]
	v_lshrrev_b32_e32 v3, 16, v3
	v_add3_u32 v6, v37, v6, s15
	global_store_dwordx4 v[50:51], v[32:35], off
	v_or_b32_e32 v22, s10, v24
	v_ashrrev_i32_e32 v23, 31, v22
	v_and_or_b32 v32, v6, s16, v3
	s_nop 0
	s_nop 0
	s_nop 0
	v_cvt_pk_bf16_f32 v33, v39, v41
	v_cvt_pk_bf16_f32 v34, v43, v45
	s_nop 0
	s_nop 0
	v_lshlrev_b64 v[22:23], 12, v[22:23]
	v_cvt_pk_bf16_f32 v35, v47, v49
	ds_read2_b32 v[36:37], v9 offset0:16 offset1:24
	v_lshl_add_u64 v[22:23], v[28:29], 0, v[22:23]
	global_store_dwordx4 v[22:23], v[32:35], off
	ds_read2_b32 v[22:23], v9 offset0:49 offset1:57
	ds_read2_b32 v[38:39], v9 offset0:82 offset1:90
	ds_read2_b32 v[40:41], v9 offset0:115 offset1:123
	s_waitcnt lgkmcnt(3)
	s_nop 0
	s_nop 0
	s_waitcnt lgkmcnt(2)
	ds_read2_b32 v[42:43], v9 offset0:148 offset1:156
	ds_read2_b32 v[44:45], v9 offset0:181 offset1:189
	v_cvt_pk_bf16_f32 v32, v36, v22
	s_waitcnt lgkmcnt(3)
	s_waitcnt lgkmcnt(2)
	ds_read2_b32 v[46:47], v9 offset0:214 offset1:222
	ds_read2_b32 v[48:49], v9 offset0:247 offset1:255
	v_cvt_pk_bf16_f32 v33, v38, v40
	s_waitcnt lgkmcnt(3)
	s_waitcnt lgkmcnt(2)
	v_cvt_pk_bf16_f32 v34, v42, v44
	s_waitcnt lgkmcnt(1)
	s_waitcnt lgkmcnt(0)
	v_or_b32_e32 v50, s10, v25
	v_cvt_pk_bf16_f32 v35, v46, v48
	v_ashrrev_i32_e32 v51, 31, v50
	v_bfe_u32 v3, v37, 16, 1
	v_lshlrev_b64 v[50:51], 12, v[50:51]
	v_add3_u32 v3, v37, v3, s15
	v_bfe_u32 v6, v23, 16, 1
	v_lshl_add_u64 v[50:51], v[28:29], 0, v[50:51]
	v_lshrrev_b32_e32 v3, 16, v3
	v_add3_u32 v6, v23, v6, s15
	global_store_dwordx4 v[50:51], v[32:35], off
	v_or_b32_e32 v22, s10, v26
	v_ashrrev_i32_e32 v23, 31, v22
	v_and_or_b32 v32, v6, s16, v3
	s_nop 0
	s_nop 0
	s_nop 0
	v_cvt_pk_bf16_f32 v33, v39, v41
	v_cvt_pk_bf16_f32 v34, v43, v45
	v_bfe_u32 v3, v47, 16, 1
	v_add3_u32 v3, v47, v3, s15
	v_bfe_u32 v6, v49, 16, 1
	v_lshrrev_b32_e32 v3, 16, v3
	v_add3_u32 v6, v49, v6, s15
	v_lshlrev_b64 v[22:23], 12, v[22:23]
	v_and_or_b32 v35, v6, s16, v3
	v_lshl_add_u64 v[22:23], v[28:29], 0, v[22:23]
	global_store_dwordx4 v[22:23], v[32:35], off
	s_waitcnt lgkmcnt(0)
	s_branch .LBB0_15

; __device__ __forceinline__ float sigmoid_f(float x) { return __builtin_amdgcn_rcpf(1.f + __expf(-x)); }
; __device__ __forceinline__ float tanh_f(float x) { const float e = __expf(2.f * x); return 1.f - 2.f * __builtin_amdgcn_rcpf(e + 1.f); }
; __device__ __forceinline__ void rwkv_proj_phase(const bf16* Z, const float* shift, const float* w0, const float* a0, const float* kkp, const float* kap, const float* rkp, ...
;     for (int it = blockIdx.x; it < 132 * 3; it += gridDim.x) {
;         int fr = lane & 15, g = lane >> 4;
;         asm volatile("" : "+v"(fr), "+v"(g));
;         const int tt = it / 3, hg = it % 3;
;         const int m = tt * 128 + wave * 16 + fr;
;         int b, tpos, len, s;
;         if (m < ML) { b = m >> 13; tpos = m & 8191; len = SEQ; s = CTXL + tpos; } else { b = (m - ML) >> 8; tpos = (m - ML) & 255; len = CTXL; s = tpos; }
;         const bool hp = tpos > 0, hn = tpos < len - 1;
;         const long offm = hp ? -(long)INCP : 0, offp = hn ? (long)INCP : 0; const float fm = hp ? 1.f : 0.f, fn = hn ? 1.f : 0.f;
;         const bf16* zr = Z + (size_t)m * INCP + ZB0;
;         bf16x8 xf[12];
; #pragma unroll
;         for (int ks = 0; ks < 12; ++ks) {
;             const int col = 2304 + 32 * ks + 8 * g;
;             const u32x4 c0 = *(const u32x4*)(zr + col), cm = *(const u32x4*)(zr + offm + col), cp = *(const u32x4*)(zr + offp + col);
;             float val[8];
; #pragma unroll
;             for (int q = 0; q < 2; ++q) { const f32x4 t0 = *(const f32x4*)(shift + col + 4 * q) * fm, t1 = *(const f32x4*)(shift + BCOLS + col + 4 * q), t2 = *(const f32x4*)(shift + 2 * BCOLS + col + 4 * q) * fn;
;                 const unsigned m0 = q ? cm.z : cm.x, m1 = q ? cm.w : cm.y, z0 = q ? c0.z : c0.x, z1 = q ? c0.w : c0.y, p0 = q ? cp.z : cp.x, p1 = q ? cp.w : cp.y;
;                 val[4 * q + 0] = t0.x * bflo(m0) + t1.x * bflo(z0) + t2.x * bflo(p0);
;                 val[4 * q + 1] = t0.y * bfhi(m0) + t1.y * bfhi(z0) + t2.y * bfhi(p0);
;                 val[4 * q + 2] = t0.z * bflo(m1) + t1.z * bflo(z1) + t2.z * bflo(p1);
;                 val[4 * q + 3] = t0.w * bfhi(m1) + t1.w * bfhi(z1) + t2.w * bfhi(p1); }
; #pragma unroll
;             for (int e = 0; e < 8; ++e) { if (ks < 4) val[e] = tanh_f(val[e]); else if (ks >= 8) val[e] = sigmoid_f(val[e]); }
.LBB0_258:
	s_mul_hi_i32 s6, s83, 0x55555556
	s_lshr_b32 s0, s6, 31
	s_add_i32 s6, s6, s0
	s_lshl_b32 s84, s6, 7
	v_mov_b32_e32 v178, v158
	v_mov_b32_e32 v179, v159
	s_add_i32 s0, s84, s58
	s_nop 0
	v_add_u32_e32 v67, s0, v179
	s_movk_i32 s0, 0x3fff
	v_cmp_lt_i32_e32 vcc, s0, v67
	s_and_saveexec_b64 s[0:1], vcc
	s_xor_b64 s[0:1], exec, s[0:1]
	v_add_u32_e32 v0, 0xffffc000, v67
	v_lshrrev_b32_e32 v69, 8, v0
	v_and_b32_e32 v102, 0xff, v67
	s_or_saveexec_b64 s[0:1], s[0:1]
	v_mov_b32_e32 v0, 0xff
	v_mov_b32_e32 v1, v102
	s_xor_b64 exec, exec, s[0:1]
	v_and_b32_e32 v1, 0x1fff, v67
	v_ashrrev_i32_e32 v69, 13, v67
	v_mov_b32_e32 v0, 0x1fff
	v_add_u32_e32 v102, 0x100, v1
	s_or_b64 exec, exec, s[0:1]
	v_lshlrev_b32_e32 v76, 3, v178
	v_cmp_eq_u32_e32 vcc, 0, v1
	v_cmp_lt_u32_e64 s[0:1], v1, v0
	v_add_u32_e32 v4, 0x900, v76
	v_cndmask_b32_e64 v3, -1, 0, vcc
	v_cndmask_b32_e64 v2, v165, 0, vcc
	v_cndmask_b32_e64 v88, 0, v166, s[0:1]
	v_mad_i64_i32 v[0:1], s[28:29], v67, s63, v[96:97]
	v_ashrrev_i32_e32 v5, 31, v4
	v_lshl_add_u64 v[74:75], v[0:1], 0, s[34:35]
	v_lshl_add_u64 v[2:3], v[0:1], 0, v[2:3]
	v_lshl_add_u64 v[0:1], v[0:1], 0, v[88:89]
	v_lshlrev_b64 v[28:29], 2, v[4:5]
	v_lshl_add_u64 v[70:71], v[2:3], 0, s[34:35]
	v_lshl_add_u64 v[72:73], v[0:1], 0, s[34:35]
	v_lshlrev_b64 v[12:13], 1, v[4:5]
	v_lshl_add_u64 v[20:21], s[38:39], 0, v[28:29]
	v_lshl_add_u64 v[24:25], s[10:11], 0, v[28:29]
	v_lshl_add_u64 v[0:1], v[74:75], 0, v[12:13]
	global_load_dwordx4 v[4:7], v[20:21], off
	global_load_dwordx4 v[8:11], v[24:25], off
	v_lshl_add_u64 v[16:17], v[70:71], 0, v[12:13]
	v_lshl_add_u64 v[12:13], v[72:73], 0, v[12:13]
	global_load_dwordx4 v[0:3], v[0:1], off
	s_nop 0
	global_load_dwordx4 v[12:15], v[12:13], off
	s_nop 0
	global_load_dwordx4 v[16:19], v[16:17], off
	s_nop 0
	global_load_dwordx4 v[20:23], v[20:21], off offset:16
	s_nop 0
	global_load_dwordx4 v[24:27], v[24:25], off offset:16
	v_lshl_add_u64 v[32:33], s[8:9], 0, v[28:29]
	global_load_dwordx4 v[28:31], v[32:33], off
	s_nop 0
	global_load_dwordx4 v[32:35], v[32:33], off offset:16
	v_cndmask_b32_e64 v68, 1.0, 0, vcc
	v_cndmask_b32_e64 v66, 0, 1.0, s[0:1]
	s_mul_i32 s6, s6, 3
	s_sub_i32 s6, s83, s6
	s_mov_b32 s85, 0
	s_lshl_b32 s86, s6, 2
	v_mul_lo_u32 v180, v69, 12
	s_waitcnt vmcnt(8)
	v_pk_mul_f32 v[4:5], v[68:69], v[4:5] op_sel_hi:[0,1]
	s_waitcnt vmcnt(7)
	v_pk_mul_f32 v[8:9], v[66:67], v[8:9] op_sel_hi:[0,1]
	v_pk_mul_f32 v[6:7], v[68:69], v[6:7] op_sel_hi:[0,1]
	v_pk_mul_f32 v[10:11], v[66:67], v[10:11] op_sel_hi:[0,1]
	s_waitcnt vmcnt(5)
	v_and_b32_e32 v37, 0xffff0000, v12
	s_waitcnt vmcnt(4)
	v_and_b32_e32 v36, 0xffff0000, v16
	s_waitcnt vmcnt(3)
	v_pk_mul_f32 v[20:21], v[68:69], v[20:21] op_sel_hi:[0,1]
	s_waitcnt vmcnt(2)
	v_pk_mul_f32 v[24:25], v[66:67], v[24:25] op_sel_hi:[0,1]
	v_mov_b32_e32 v48, v5
	v_mov_b32_e32 v49, v9
	v_and_b32_e32 v52, 0xffff0000, v0
	v_and_b32_e32 v41, 0xffff0000, v13
	v_and_b32_e32 v40, 0xffff0000, v17
	v_and_b32_e32 v45, 0xffff0000, v14
	v_and_b32_e32 v44, 0xffff0000, v18
	v_mov_b32_e32 v51, v10
	v_mov_b32_e32 v10, v7
	v_mov_b32_e32 v7, v24
	v_mov_b32_e32 v24, v21
	v_pk_mul_f32 v[36:37], v[48:49], v[36:37]
	v_lshlrev_b32_e32 v53, 16, v1
	v_lshlrev_b32_e32 v39, 16, v13
	v_lshlrev_b32_e32 v38, 16, v17
	v_and_b32_e32 v1, 0xffff0000, v1
	v_lshlrev_b32_e32 v13, 16, v2
	v_and_b32_e32 v2, 0xffff0000, v2
	v_mov_b32_e32 v50, v6
	v_pk_mul_f32 v[10:11], v[10:11], v[40:41]
	v_pk_mul_f32 v[24:25], v[24:25], v[44:45]
	s_waitcnt vmcnt(1)
	v_fma_f32 v5, v29, v52, v36
	v_pk_mul_f32 v[22:23], v[68:69], v[22:23] op_sel_hi:[0,1]
	v_pk_mul_f32 v[26:27], v[66:67], v[26:27] op_sel_hi:[0,1]
	v_lshlrev_b32_e32 v43, 16, v14
	v_lshlrev_b32_e32 v42, 16, v18
	v_mov_b32_e32 v6, v20
	v_pk_mul_f32 v[38:39], v[50:51], v[38:39]
	v_fma_f32 v1, v31, v1, v10
	s_waitcnt vmcnt(0)
	v_fma_f32 v2, v33, v2, v24
	v_add_f32_e32 v36, v5, v37
	v_lshlrev_b32_e32 v14, 16, v3
	v_mov_b32_e32 v21, v26
	v_pk_mul_f32 v[6:7], v[6:7], v[42:43]
	v_fma_f32 v9, v30, v53, v38
	v_add_f32_e32 v38, v1, v11
	v_add_f32_e32 v42, v2, v25
	v_and_b32_e32 v1, 0xffff0000, v3
	v_and_b32_e32 v3, 0xffff0000, v15
	v_and_b32_e32 v2, 0xffff0000, v19
	v_mov_b32_e32 v26, v23
	v_add_f32_e32 v36, v36, v36
	v_lshlrev_b32_e32 v47, 16, v15
	v_lshlrev_b32_e32 v46, 16, v19
	v_mov_b32_e32 v20, v22
	v_fma_f32 v6, v32, v13, v6
	v_pk_mul_f32 v[2:3], v[26:27], v[2:3]
	v_mov_b32_e32 v5, v8
	v_add_u32_e32 v8, 0x920, v76
	v_mul_f32_e32 v36, 0x3fb8aa3b, v36
	v_pk_mul_f32 v[20:21], v[20:21], v[46:47]
	v_add_f32_e32 v37, v9, v39
	v_add_f32_e32 v39, v6, v7
	v_fma_f32 v2, v35, v1, v2
	v_lshlrev_b32_e32 v6, 16, v0
	v_lshlrev_b32_e32 v1, 16, v12
	v_lshlrev_b32_e32 v0, 16, v16
	v_ashrrev_i32_e32 v9, 31, v8
	v_exp_f32_e32 v36, v36
	v_fma_f32 v10, v34, v14, v20
	v_pk_mul_f32 v[0:1], v[4:5], v[0:1]
	v_lshlrev_b64 v[24:25], 1, v[8:9]
	v_lshlrev_b64 v[32:33], 2, v[8:9]
	v_add_f32_e32 v43, v10, v21
	v_fma_f32 v0, v28, v6, v0
	v_lshl_add_u64 v[4:5], v[74:75], 0, v[24:25]
	v_lshl_add_u64 v[12:13], s[38:39], 0, v[32:33]
	v_lshl_add_u64 v[20:21], s[10:11], 0, v[32:33]
	global_load_dwordx4 v[4:7], v[4:5], off
	s_nop 0
	global_load_dwordx4 v[8:11], v[12:13], off offset:16
	s_nop 0
	global_load_dwordx4 v[12:15], v[12:13], off
	s_nop 0
	global_load_dwordx4 v[16:19], v[20:21], off offset:16
	s_nop 0
	global_load_dwordx4 v[20:23], v[20:21], off
	v_lshl_add_u64 v[28:29], v[70:71], 0, v[24:25]
	v_lshl_add_u64 v[24:25], v[72:73], 0, v[24:25]
	v_add_f32_e32 v0, v0, v1
	global_load_dwordx4 v[24:27], v[24:25], off
	s_nop 0
	global_load_dwordx4 v[28:31], v[28:29], off
	v_add_f32_e32 v40, v0, v0
	v_add_f32_e32 v44, v2, v3
	v_add_f32_e32 v3, 1.0, v36
	v_add_f32_e32 v36, v37, v37
; __device__ __forceinline__ unsigned pk2(float lo, float hi) { return f2bf(lo) | (f2bf(hi) << 16); }
; __device__ __forceinline__ float sigmoid_f(float x) { return __builtin_amdgcn_rcpf(1.f + __expf(-x)); }
; __device__ __forceinline__ float tanh_f(float x) { const float e = __expf(2.f * x); return 1.f - 2.f * __builtin_amdgcn_rcpf(e + 1.f); }
; __device__ __forceinline__ void rwkv_proj_phase(const bf16* Z, const float* shift, const float* w0, const float* a0, const float* kkp, const float* kap, const float* rkp, ...
;     ...
;         for (int ks = 0; ks < 12; ++ks) {
;             const int col = 2304 + 32 * ks + 8 * g;
;             const u32x4 c0 = *(const u32x4*)(zr + col), cm = *(const u32x4*)(zr + offm + col), cp = *(const u32x4*)(zr + offp + col);
;             float val[8];
; #pragma unroll
;             for (int q = 0; q < 2; ++q) { const f32x4 t0 = *(const f32x4*)(shift + col + 4 * q) * fm, t1 = *(const f32x4*)(shift + BCOLS + col + 4 * q), t2 = *(const f32x4*)(shift + 2 * BCOLS + col + 4 * q) * fn;
;                 const unsigned m0 = q ? cm.z : cm.x, m1 = q ? cm.w : cm.y, z0 = q ? c0.z : c0.x, z1 = q ? c0.w : c0.y, p0 = q ? cp.z : cp.x, p1 = q ? cp.w : cp.y;
;                 val[4 * q + 0] = t0.x * bflo(m0) + t1.x * bflo(z0) + t2.x * bflo(p0);
;                 val[4 * q + 1] = t0.y * bfhi(m0) + t1.y * bfhi(z0) + t2.y * bfhi(p0);
;                 val[4 * q + 2] = t0.z * bflo(m1) + t1.z * bflo(z1) + t2.z * bflo(p1);
;                 val[4 * q + 3] = t0.w * bfhi(m1) + t1.w * bfhi(z1) + t2.w * bfhi(p1); }
; #pragma unroll
;             for (int e = 0; e < 8; ++e) { if (ks < 4) val[e] = tanh_f(val[e]); else if (ks >= 8) val[e] = sigmoid_f(val[e]); }
;             u32x4 pk; pk.x = pk2(val[0], val[1]); pk.y = pk2(val[2], val[3]); pk.z = pk2(val[4], val[5]); pk.w = pk2(val[6], val[7]);
;             xf[ks] = __builtin_bit_cast(bf16x8, pk);
;             if (ks & 1) asm volatile("" ::: "memory");
	v_add_f32_e32 v37, v38, v38
	v_lshl_add_u64 v[0:1], s[8:9], 0, v[32:33]
	v_mul_f32_e32 v40, 0x3fb8aa3b, v40
	v_mul_f32_e32 v36, 0x3fb8aa3b, v36
	v_mul_f32_e32 v37, 0x3fb8aa3b, v37
	global_load_dwordx4 v[32:35], v[0:1], off
	v_exp_f32_e32 v40, v40
	v_exp_f32_e32 v36, v36
	v_exp_f32_e32 v37, v37
	v_add_f32_e32 v2, 1.0, v40
	v_rcp_f32_e32 v40, v3
	v_add_f32_e32 v3, 1.0, v36
	v_add_f32_e32 v36, 1.0, v37
	v_rcp_f32_e32 v41, v36
	v_add_f32_e32 v36, v39, v39
	v_mul_f32_e32 v36, 0x3fb8aa3b, v36
	v_exp_f32_e32 v45, v36
	v_add_f32_e32 v36, v42, v42
	v_mul_f32_e32 v36, 0x3fb8aa3b, v36
	v_exp_f32_e32 v42, v36
	global_load_dwordx4 v[36:39], v[0:1], off offset:16
	v_add_f32_e32 v0, 1.0, v45
	v_rcp_f32_e32 v2, v2
	v_add_f32_e32 v1, 1.0, v42
	v_add_f32_e32 v42, v43, v43
	v_mul_f32_e32 v42, 0x3fb8aa3b, v42
	v_exp_f32_e32 v43, v42
	v_add_f32_e32 v42, v44, v44
	v_mul_f32_e32 v42, 0x3fb8aa3b, v42
	v_exp_f32_e32 v44, v42
	v_rcp_f32_e32 v42, v1
	v_add_f32_e32 v1, 1.0, v43
	v_rcp_f32_e32 v3, v3
	v_add_f32_e32 v43, 1.0, v44
	v_rcp_f32_e32 v43, v43
	v_rcp_f32_e32 v0, v0
	v_rcp_f32_e32 v1, v1
	v_pk_fma_f32 v[40:41], v[40:41], 2.0, 1.0 op_sel_hi:[1,0,0] neg_lo:[1,0,0] neg_hi:[1,0,0]
	v_pk_fma_f32 v[42:43], v[42:43], 2.0, 1.0 op_sel_hi:[1,0,0] neg_lo:[1,0,0] neg_hi:[1,0,0]
	v_pk_fma_f32 v[2:3], v[2:3], 2.0, 1.0 op_sel_hi:[1,0,0] neg_lo:[1,0,0] neg_hi:[1,0,0]
	v_pk_fma_f32 v[0:1], v[0:1], 2.0, 1.0 op_sel_hi:[1,0,0] neg_lo:[1,0,0] neg_hi:[1,0,0]
	s_nop 0
	s_nop 0
	v_bfe_u32 v46, v41, 16, 1
	v_bfe_u32 v47, v40, 16, 1
	v_add3_u32 v40, v40, v47, s77
	v_add3_u32 v41, v41, v46, s77
	v_bfe_u32 v44, v2, 16, 1
	v_bfe_u32 v45, v3, 16, 1
	v_add3_u32 v3, v3, v45, s77
	v_add3_u32 v2, v2, v44, s77
	v_lshrrev_b32_e32 v44, 16, v2
	v_lshrrev_b32_e32 v45, 16, v3
	v_cvt_pk_bf16_f32 v3, v1, v43
	v_cvt_pk_bf16_f32 v2, v0, v42
	v_and_or_b32 v1, v41, s76, v45
	v_and_or_b32 v0, v40, s76, v44
	s_waitcnt vmcnt(7)
	v_pk_mul_f32 v[8:9], v[68:69], v[8:9] op_sel_hi:[0,1]
	s_waitcnt vmcnt(6)
	v_pk_mul_f32 v[12:13], v[68:69], v[12:13] op_sel_hi:[0,1]
	v_mov_b32_e32 v42, v13
	s_waitcnt vmcnt(4)
	v_pk_mul_f32 v[20:21], v[66:67], v[20:21] op_sel_hi:[0,1]
	v_mov_b32_e32 v43, v21
	v_and_b32_e32 v44, 0xffff0000, v4
	s_waitcnt vmcnt(3)
	v_and_b32_e32 v41, 0xffff0000, v24
	s_waitcnt vmcnt(2)
	v_and_b32_e32 v40, 0xffff0000, v28
	v_pk_mul_f32 v[40:41], v[42:43], v[40:41]
	v_pk_mul_f32 v[14:15], v[68:69], v[14:15] op_sel_hi:[0,1]
	v_pk_mul_f32 v[22:23], v[66:67], v[22:23] op_sel_hi:[0,1]
	v_mov_b32_e32 v42, v14
	v_mov_b32_e32 v43, v22
	v_mov_b32_e32 v22, v15
	v_pk_mul_f32 v[16:17], v[66:67], v[16:17] op_sel_hi:[0,1]
	v_pk_mul_f32 v[10:11], v[68:69], v[10:11] op_sel_hi:[0,1]
	s_waitcnt vmcnt(1)
	v_fma_f32 v13, v33, v44, v40
	v_add_f32_e32 v44, v13, v41
	v_lshlrev_b32_e32 v41, 16, v25
	v_lshlrev_b32_e32 v40, 16, v29
	v_lshlrev_b32_e32 v13, 16, v5
	v_pk_mul_f32 v[40:41], v[42:43], v[40:41]
	v_and_b32_e32 v5, 0xffff0000, v5
	v_fma_f32 v13, v34, v13, v40
	v_add_f32_e32 v42, v13, v41
	v_and_b32_e32 v41, 0xffff0000, v25
	v_and_b32_e32 v40, 0xffff0000, v29
	v_pk_mul_f32 v[14:15], v[22:23], v[40:41]
	v_mov_b32_e32 v22, v8
	v_fma_f32 v5, v35, v5, v14
	v_add_f32_e32 v40, v5, v15
	v_pk_mul_f32 v[14:15], v[66:67], v[18:19] op_sel_hi:[0,1]
	v_lshlrev_b32_e32 v19, 16, v26
	v_lshlrev_b32_e32 v18, 16, v30
	v_mov_b32_e32 v23, v16
	v_lshlrev_b32_e32 v5, 16, v6
	v_pk_mul_f32 v[18:19], v[22:23], v[18:19]
	v_mov_b32_e32 v16, v9
	s_waitcnt vmcnt(0)
	v_fma_f32 v5, v36, v5, v18
	v_add_f32_e32 v41, v5, v19
	v_and_b32_e32 v19, 0xffff0000, v26
	v_and_b32_e32 v18, 0xffff0000, v30
	v_and_b32_e32 v5, 0xffff0000, v6
	v_pk_mul_f32 v[8:9], v[16:17], v[18:19]
	v_mov_b32_e32 v16, v10
	v_fma_f32 v5, v37, v5, v8
	v_add_f32_e32 v43, v5, v9
	v_lshlrev_b32_e32 v9, 16, v27
	v_lshlrev_b32_e32 v8, 16, v31
	v_mov_b32_e32 v17, v14
	v_lshlrev_b32_e32 v5, 16, v7
	v_pk_mul_f32 v[8:9], v[16:17], v[8:9]
	v_and_b32_e32 v6, 0xffff0000, v31
	v_fma_f32 v5, v38, v5, v8
	v_add_f32_e32 v46, v5, v9
	v_and_b32_e32 v5, 0xffff0000, v7
	v_and_b32_e32 v7, 0xffff0000, v27
	v_mov_b32_e32 v14, v11
	v_pk_mul_f32 v[6:7], v[14:15], v[6:7]
	v_lshlrev_b32_e32 v8, 16, v4
	v_fma_f32 v6, v39, v5, v6
	v_lshlrev_b32_e32 v5, 16, v24
	v_lshlrev_b32_e32 v4, 16, v28
	v_mov_b32_e32 v13, v20
	v_pk_mul_f32 v[4:5], v[12:13], v[4:5]
	v_add_u32_e32 v12, 0x940, v76
	v_ashrrev_i32_e32 v13, 31, v12
	v_lshlrev_b64 v[28:29], 1, v[12:13]
	v_lshlrev_b64 v[36:37], 2, v[12:13]
	v_fma_f32 v4, v32, v8, v4
	v_lshl_add_u64 v[8:9], v[74:75], 0, v[28:29]
	v_lshl_add_u64 v[16:17], s[38:39], 0, v[36:37]
	v_lshl_add_u64 v[24:25], s[10:11], 0, v[36:37]
	global_load_dwordx4 v[8:11], v[8:9], off
	s_nop 0
	global_load_dwordx4 v[12:15], v[16:17], off offset:16
	s_nop 0
	global_load_dwordx4 v[16:19], v[16:17], off
	s_nop 0
	global_load_dwordx4 v[20:23], v[24:25], off offset:16
	s_nop 0
	global_load_dwordx4 v[24:27], v[24:25], off
	v_lshl_add_u64 v[32:33], v[70:71], 0, v[28:29]
	v_lshl_add_u64 v[28:29], v[72:73], 0, v[28:29]
	global_load_dwordx4 v[28:31], v[28:29], off
	s_nop 0
	global_load_dwordx4 v[32:35], v[32:33], off
	v_add_f32_e32 v4, v4, v5
	v_add_f32_e32 v40, v40, v40
	v_add_f32_e32 v45, v4, v4
	v_lshl_add_u64 v[4:5], s[8:9], 0, v[36:37]
	v_mul_f32_e32 v40, 0x3fb8aa3b, v40
	global_load_dwordx4 v[36:39], v[4:5], off
	v_mul_f32_e32 v45, 0x3fb8aa3b, v45
	v_exp_f32_e32 v40, v40
	v_exp_f32_e32 v45, v45
	v_add_f32_e32 v44, v44, v44
	v_mul_f32_e32 v44, 0x3fb8aa3b, v44
	v_add_f32_e32 v42, v42, v42
	v_exp_f32_e32 v44, v44
	v_mul_f32_e32 v42, 0x3fb8aa3b, v42
	v_add_f32_e32 v40, 1.0, v40
	v_add_f32_e32 v47, v6, v7
	v_add_f32_e32 v6, 1.0, v45
	v_exp_f32_e32 v42, v42
	v_rcp_f32_e32 v45, v40
	v_add_f32_e32 v40, v41, v41
; __device__ __forceinline__ unsigned pk2(float lo, float hi) { return f2bf(lo) | (f2bf(hi) << 16); }
; __device__ __forceinline__ float sigmoid_f(float x) { return __builtin_amdgcn_rcpf(1.f + __expf(-x)); }
; __device__ __forceinline__ float tanh_f(float x) { const float e = __expf(2.f * x); return 1.f - 2.f * __builtin_amdgcn_rcpf(e + 1.f); }
; __device__ __forceinline__ void rwkv_proj_phase(const bf16* Z, const float* shift, const float* w0, const float* a0, const float* kkp, const float* kap, const float* rkp, ...
;     ...
;         for (int ks = 0; ks < 12; ++ks) {
;             const int col = 2304 + 32 * ks + 8 * g;
;             const u32x4 c0 = *(const u32x4*)(zr + col), cm = *(const u32x4*)(zr + offm + col), cp = *(const u32x4*)(zr + offp + col);
;             float val[8];
; #pragma unroll
;             for (int q = 0; q < 2; ++q) { const f32x4 t0 = *(const f32x4*)(shift + col + 4 * q) * fm, t1 = *(const f32x4*)(shift + BCOLS + col + 4 * q), t2 = *(const f32x4*)(shift + 2 * BCOLS + col + 4 * q) * fn;
;                 const unsigned m0 = q ? cm.z : cm.x, m1 = q ? cm.w : cm.y, z0 = q ? c0.z : c0.x, z1 = q ? c0.w : c0.y, p0 = q ? cp.z : cp.x, p1 = q ? cp.w : cp.y;
;                 val[4 * q + 0] = t0.x * bflo(m0) + t1.x * bflo(z0) + t2.x * bflo(p0);
;                 val[4 * q + 1] = t0.y * bfhi(m0) + t1.y * bfhi(z0) + t2.y * bfhi(p0);
;                 val[4 * q + 2] = t0.z * bflo(m1) + t1.z * bflo(z1) + t2.z * bflo(p1);
;                 val[4 * q + 3] = t0.w * bfhi(m1) + t1.w * bfhi(z1) + t2.w * bfhi(p1); }
; #pragma unroll
;             for (int e = 0; e < 8; ++e) { if (ks < 4) val[e] = tanh_f(val[e]); else if (ks >= 8) val[e] = sigmoid_f(val[e]); }
;             u32x4 pk; pk.x = pk2(val[0], val[1]); pk.y = pk2(val[2], val[3]); pk.z = pk2(val[4], val[5]); pk.w = pk2(val[6], val[7]);
;             xf[ks] = __builtin_bit_cast(bf16x8, pk);
;             if (ks & 1) asm volatile("" ::: "memory");
	v_mul_f32_e32 v40, 0x3fb8aa3b, v40
	v_exp_f32_e32 v48, v40
	v_add_f32_e32 v40, v43, v43
	v_add_f32_e32 v7, 1.0, v44
	v_mul_f32_e32 v40, 0x3fb8aa3b, v40
	v_rcp_f32_e32 v44, v7
	v_add_f32_e32 v7, 1.0, v42
	v_exp_f32_e32 v49, v40
	global_load_dwordx4 v[40:43], v[4:5], off offset:16
	v_add_f32_e32 v46, v46, v46
	v_mul_f32_e32 v46, 0x3fb8aa3b, v46
	v_add_f32_e32 v4, 1.0, v48
	v_exp_f32_e32 v48, v46
	v_add_f32_e32 v46, v47, v47
	v_mul_f32_e32 v46, 0x3fb8aa3b, v46
	v_exp_f32_e32 v47, v46
	v_add_f32_e32 v5, 1.0, v49
	v_rcp_f32_e32 v46, v5
	v_add_f32_e32 v5, 1.0, v48
	v_add_f32_e32 v47, 1.0, v47
	v_rcp_f32_e32 v47, v47
	v_rcp_f32_e32 v6, v6
	v_rcp_f32_e32 v7, v7
	v_rcp_f32_e32 v4, v4
	v_rcp_f32_e32 v5, v5
	v_pk_fma_f32 v[44:45], v[44:45], 2.0, 1.0 op_sel_hi:[1,0,0] neg_lo:[1,0,0] neg_hi:[1,0,0]
	v_pk_fma_f32 v[46:47], v[46:47], 2.0, 1.0 op_sel_hi:[1,0,0] neg_lo:[1,0,0] neg_hi:[1,0,0]
	v_pk_fma_f32 v[6:7], v[6:7], 2.0, 1.0 op_sel_hi:[1,0,0] neg_lo:[1,0,0] neg_hi:[1,0,0]
	v_pk_fma_f32 v[4:5], v[4:5], 2.0, 1.0 op_sel_hi:[1,0,0] neg_lo:[1,0,0] neg_hi:[1,0,0]
	s_nop 0
	s_nop 0
	v_bfe_u32 v50, v45, 16, 1
	v_bfe_u32 v51, v44, 16, 1
	v_add3_u32 v44, v44, v51, s77
	v_add3_u32 v45, v45, v50, s77
	v_bfe_u32 v48, v6, 16, 1
	v_bfe_u32 v49, v7, 16, 1
	v_add3_u32 v7, v7, v49, s77
	v_add3_u32 v6, v6, v48, s77
	v_lshrrev_b32_e32 v48, 16, v6
	v_lshrrev_b32_e32 v49, 16, v7
	v_cvt_pk_bf16_f32 v7, v5, v47
	v_cvt_pk_bf16_f32 v6, v4, v46
	v_and_or_b32 v5, v45, s76, v49
	v_and_or_b32 v4, v44, s76, v48
	s_waitcnt vmcnt(7)
	v_pk_mul_f32 v[12:13], v[68:69], v[12:13] op_sel_hi:[0,1]
	s_waitcnt vmcnt(6)
	v_pk_mul_f32 v[16:17], v[68:69], v[16:17] op_sel_hi:[0,1]
	v_mov_b32_e32 v46, v17
	s_waitcnt vmcnt(4)
	v_pk_mul_f32 v[24:25], v[66:67], v[24:25] op_sel_hi:[0,1]
	v_mov_b32_e32 v47, v25
	s_waitcnt vmcnt(3)
	v_and_b32_e32 v45, 0xffff0000, v28
	s_waitcnt vmcnt(2)
	v_and_b32_e32 v44, 0xffff0000, v32
	v_and_b32_e32 v48, 0xffff0000, v8
	v_pk_mul_f32 v[44:45], v[46:47], v[44:45]
	v_pk_mul_f32 v[18:19], v[68:69], v[18:19] op_sel_hi:[0,1]
	v_pk_mul_f32 v[26:27], v[66:67], v[26:27] op_sel_hi:[0,1]
	v_mov_b32_e32 v46, v18
	s_waitcnt vmcnt(1)
	v_fma_f32 v17, v37, v48, v44
	v_add_f32_e32 v48, v17, v45
	v_lshlrev_b32_e32 v45, 16, v29
	v_lshlrev_b32_e32 v44, 16, v33
	v_mov_b32_e32 v47, v26
	v_lshlrev_b32_e32 v17, 16, v9
	v_pk_mul_f32 v[44:45], v[46:47], v[44:45]
	v_mov_b32_e32 v26, v19
	v_fma_f32 v17, v38, v17, v44
	v_add_f32_e32 v46, v17, v45
	v_and_b32_e32 v45, 0xffff0000, v29
	v_and_b32_e32 v44, 0xffff0000, v33
	v_and_b32_e32 v9, 0xffff0000, v9
	v_pk_mul_f32 v[18:19], v[26:27], v[44:45]
	v_pk_mul_f32 v[20:21], v[66:67], v[20:21] op_sel_hi:[0,1]
	v_fma_f32 v9, v39, v9, v18
	v_add_f32_e32 v44, v9, v19
	v_pk_mul_f32 v[18:19], v[66:67], v[22:23] op_sel_hi:[0,1]
	v_lshlrev_b32_e32 v23, 16, v30
	v_lshlrev_b32_e32 v22, 16, v34
	v_mov_b32_e32 v26, v12
	v_mov_b32_e32 v27, v20
	v_lshlrev_b32_e32 v9, 16, v10
	v_pk_mul_f32 v[22:23], v[26:27], v[22:23]
	v_mov_b32_e32 v20, v13
	s_waitcnt vmcnt(0)
	v_fma_f32 v9, v40, v9, v22
	v_add_f32_e32 v45, v9, v23
	v_and_b32_e32 v23, 0xffff0000, v30
	v_and_b32_e32 v22, 0xffff0000, v34
	v_and_b32_e32 v9, 0xffff0000, v10
	v_pk_mul_f32 v[12:13], v[20:21], v[22:23]
	v_pk_mul_f32 v[14:15], v[68:69], v[14:15] op_sel_hi:[0,1]
	v_fma_f32 v9, v41, v9, v12
	v_add_f32_e32 v47, v9, v13
	v_lshlrev_b32_e32 v13, 16, v31
	v_lshlrev_b32_e32 v12, 16, v35
	v_mov_b32_e32 v20, v14
	v_mov_b32_e32 v21, v18
	v_lshlrev_b32_e32 v9, 16, v11
	v_pk_mul_f32 v[12:13], v[20:21], v[12:13]
	v_and_b32_e32 v10, 0xffff0000, v35
	v_fma_f32 v9, v42, v9, v12
	v_add_f32_e32 v50, v9, v13
	v_and_b32_e32 v9, 0xffff0000, v11
	v_and_b32_e32 v11, 0xffff0000, v31
	v_mov_b32_e32 v18, v15
	v_pk_mul_f32 v[10:11], v[18:19], v[10:11]
	v_lshlrev_b32_e32 v12, 16, v8
	v_fma_f32 v10, v43, v9, v10
	v_lshlrev_b32_e32 v9, 16, v28
	v_lshlrev_b32_e32 v8, 16, v32
	v_mov_b32_e32 v17, v24
	v_pk_mul_f32 v[8:9], v[16:17], v[8:9]
	v_add_u32_e32 v16, 0x960, v76
	v_ashrrev_i32_e32 v17, 31, v16
	v_lshlrev_b64 v[32:33], 1, v[16:17]
	v_lshlrev_b64 v[40:41], 2, v[16:17]
	v_fma_f32 v8, v36, v12, v8
	v_lshl_add_u64 v[12:13], v[74:75], 0, v[32:33]
	v_lshl_add_u64 v[20:21], s[38:39], 0, v[40:41]
	v_lshl_add_u64 v[28:29], s[10:11], 0, v[40:41]
	global_load_dwordx4 v[12:15], v[12:13], off
	s_nop 0
	global_load_dwordx4 v[16:19], v[20:21], off offset:16
	s_nop 0
	global_load_dwordx4 v[20:23], v[20:21], off
	s_nop 0
	global_load_dwordx4 v[24:27], v[28:29], off offset:16
	s_nop 0
	global_load_dwordx4 v[28:31], v[28:29], off
	v_lshl_add_u64 v[36:37], v[70:71], 0, v[32:33]
	v_lshl_add_u64 v[32:33], v[72:73], 0, v[32:33]
	global_load_dwordx4 v[32:35], v[32:33], off
	s_nop 0
	global_load_dwordx4 v[36:39], v[36:37], off
	v_add_f32_e32 v8, v8, v9
	v_add_f32_e32 v44, v44, v44
	v_add_f32_e32 v49, v8, v8
	v_lshl_add_u64 v[8:9], s[8:9], 0, v[40:41]
	v_mul_f32_e32 v44, 0x3fb8aa3b, v44
	global_load_dwordx4 v[40:43], v[8:9], off
	v_mul_f32_e32 v49, 0x3fb8aa3b, v49
	v_exp_f32_e32 v44, v44
	v_exp_f32_e32 v49, v49
	v_add_f32_e32 v48, v48, v48
	v_mul_f32_e32 v48, 0x3fb8aa3b, v48
	v_add_f32_e32 v46, v46, v46
	v_exp_f32_e32 v48, v48
	v_mul_f32_e32 v46, 0x3fb8aa3b, v46
	v_add_f32_e32 v44, 1.0, v44
	v_add_f32_e32 v51, v10, v11
	v_add_f32_e32 v10, 1.0, v49
	v_exp_f32_e32 v46, v46
	v_rcp_f32_e32 v49, v44
	v_add_f32_e32 v44, v45, v45
	v_mul_f32_e32 v44, 0x3fb8aa3b, v44
	v_exp_f32_e32 v52, v44
	v_add_f32_e32 v44, v47, v47
	v_add_f32_e32 v11, 1.0, v48
	v_mul_f32_e32 v44, 0x3fb8aa3b, v44
	v_rcp_f32_e32 v48, v11
	v_add_f32_e32 v11, 1.0, v46
	v_exp_f32_e32 v53, v44
	global_load_dwordx4 v[44:47], v[8:9], off offset:16
	v_add_f32_e32 v50, v50, v50
	v_mul_f32_e32 v50, 0x3fb8aa3b, v50
	v_add_f32_e32 v8, 1.0, v52
	v_exp_f32_e32 v52, v50
	v_add_f32_e32 v50, v51, v51
	v_mul_f32_e32 v50, 0x3fb8aa3b, v50
	v_exp_f32_e32 v51, v50
	v_add_f32_e32 v9, 1.0, v53
	v_rcp_f32_e32 v50, v9
	v_add_f32_e32 v9, 1.0, v52
	v_add_f32_e32 v51, 1.0, v51
	v_rcp_f32_e32 v51, v51
	v_rcp_f32_e32 v10, v10
	v_rcp_f32_e32 v11, v11
	v_rcp_f32_e32 v8, v8
	v_rcp_f32_e32 v9, v9
	v_pk_fma_f32 v[48:49], v[48:49], 2.0, 1.0 op_sel_hi:[1,0,0] neg_lo:[1,0,0] neg_hi:[1,0,0]
	v_pk_fma_f32 v[50:51], v[50:51], 2.0, 1.0 op_sel_hi:[1,0,0] neg_lo:[1,0,0] neg_hi:[1,0,0]
	v_pk_fma_f32 v[10:11], v[10:11], 2.0, 1.0 op_sel_hi:[1,0,0] neg_lo:[1,0,0] neg_hi:[1,0,0]
	v_pk_fma_f32 v[8:9], v[8:9], 2.0, 1.0 op_sel_hi:[1,0,0] neg_lo:[1,0,0] neg_hi:[1,0,0]
	s_nop 0
	s_nop 0
	v_bfe_u32 v54, v49, 16, 1
	v_bfe_u32 v55, v48, 16, 1
	v_add3_u32 v48, v48, v55, s77
	v_add3_u32 v49, v49, v54, s77
	v_bfe_u32 v52, v10, 16, 1
	v_bfe_u32 v53, v11, 16, 1
	v_add3_u32 v11, v11, v53, s77
	v_add3_u32 v10, v10, v52, s77
	v_lshrrev_b32_e32 v52, 16, v10
	v_lshrrev_b32_e32 v53, 16, v11
	v_cvt_pk_bf16_f32 v11, v9, v51
	v_cvt_pk_bf16_f32 v10, v8, v50
	v_and_or_b32 v9, v49, s76, v53
	v_and_or_b32 v8, v48, s76, v52
	s_waitcnt vmcnt(7)
; __device__ __forceinline__ unsigned pk2(float lo, float hi) { return f2bf(lo) | (f2bf(hi) << 16); }
; __device__ __forceinline__ float sigmoid_f(float x) { return __builtin_amdgcn_rcpf(1.f + __expf(-x)); }
; __device__ __forceinline__ float tanh_f(float x) { const float e = __expf(2.f * x); return 1.f - 2.f * __builtin_amdgcn_rcpf(e + 1.f); }
; __device__ __forceinline__ void rwkv_proj_phase(const bf16* Z, const float* shift, const float* w0, const float* a0, const float* kkp, const float* kap, const float* rkp, ...
;     ...
;         for (int ks = 0; ks < 12; ++ks) {
;             const int col = 2304 + 32 * ks + 8 * g;
;             const u32x4 c0 = *(const u32x4*)(zr + col), cm = *(const u32x4*)(zr + offm + col), cp = *(const u32x4*)(zr + offp + col);
;             float val[8];
; #pragma unroll
;             for (int q = 0; q < 2; ++q) { const f32x4 t0 = *(const f32x4*)(shift + col + 4 * q) * fm, t1 = *(const f32x4*)(shift + BCOLS + col + 4 * q), t2 = *(const f32x4*)(shift + 2 * BCOLS + col + 4 * q) * fn;
;                 const unsigned m0 = q ? cm.z : cm.x, m1 = q ? cm.w : cm.y, z0 = q ? c0.z : c0.x, z1 = q ? c0.w : c0.y, p0 = q ? cp.z : cp.x, p1 = q ? cp.w : cp.y;
;                 val[4 * q + 0] = t0.x * bflo(m0) + t1.x * bflo(z0) + t2.x * bflo(p0);
;                 val[4 * q + 1] = t0.y * bfhi(m0) + t1.y * bfhi(z0) + t2.y * bfhi(p0);
;                 val[4 * q + 2] = t0.z * bflo(m1) + t1.z * bflo(z1) + t2.z * bflo(p1);
;                 val[4 * q + 3] = t0.w * bfhi(m1) + t1.w * bfhi(z1) + t2.w * bfhi(p1); }
; #pragma unroll
;             for (int e = 0; e < 8; ++e) { if (ks < 4) val[e] = tanh_f(val[e]); else if (ks >= 8) val[e] = sigmoid_f(val[e]); }
;             u32x4 pk; pk.x = pk2(val[0], val[1]); pk.y = pk2(val[2], val[3]); pk.z = pk2(val[4], val[5]); pk.w = pk2(val[6], val[7]);
;             xf[ks] = __builtin_bit_cast(bf16x8, pk);
;             if (ks & 1) asm volatile("" ::: "memory");
	v_pk_mul_f32 v[16:17], v[68:69], v[16:17] op_sel_hi:[0,1]
	s_waitcnt vmcnt(6)
	v_pk_mul_f32 v[20:21], v[68:69], v[20:21] op_sel_hi:[0,1]
	v_mov_b32_e32 v50, v21
	s_waitcnt vmcnt(4)
	v_pk_mul_f32 v[28:29], v[66:67], v[28:29] op_sel_hi:[0,1]
	v_mov_b32_e32 v51, v29
	s_waitcnt vmcnt(3)
	v_and_b32_e32 v49, 0xffff0000, v32
	s_waitcnt vmcnt(2)
	v_and_b32_e32 v48, 0xffff0000, v36
	v_and_b32_e32 v52, 0xffff0000, v12
	v_pk_mul_f32 v[48:49], v[50:51], v[48:49]
	v_pk_mul_f32 v[22:23], v[68:69], v[22:23] op_sel_hi:[0,1]
	v_pk_mul_f32 v[30:31], v[66:67], v[30:31] op_sel_hi:[0,1]
	v_mov_b32_e32 v50, v22
	s_waitcnt vmcnt(1)
	v_fma_f32 v21, v41, v52, v48
	v_add_f32_e32 v41, v21, v49
	v_lshlrev_b32_e32 v49, 16, v33
	v_lshlrev_b32_e32 v48, 16, v37
	v_mov_b32_e32 v51, v30
	v_lshlrev_b32_e32 v21, 16, v13
	v_pk_mul_f32 v[48:49], v[50:51], v[48:49]
	v_mov_b32_e32 v30, v23
	v_fma_f32 v21, v42, v21, v48
	v_add_f32_e32 v52, v21, v49
	v_and_b32_e32 v49, 0xffff0000, v33
	v_and_b32_e32 v48, 0xffff0000, v37
	v_and_b32_e32 v13, 0xffff0000, v13
	v_pk_mul_f32 v[22:23], v[30:31], v[48:49]
	v_pk_mul_f32 v[24:25], v[66:67], v[24:25] op_sel_hi:[0,1]
	v_fma_f32 v13, v43, v13, v22
	v_add_f32_e32 v53, v13, v23
	v_pk_mul_f32 v[22:23], v[66:67], v[26:27] op_sel_hi:[0,1]
	v_lshlrev_b32_e32 v27, 16, v34
	v_lshlrev_b32_e32 v26, 16, v38
	v_mov_b32_e32 v30, v16
	v_mov_b32_e32 v31, v24
	v_lshlrev_b32_e32 v13, 16, v14
	v_pk_mul_f32 v[26:27], v[30:31], v[26:27]
	v_mov_b32_e32 v24, v17
	s_waitcnt vmcnt(0)
	v_fma_f32 v13, v44, v13, v26
	v_add_f32_e32 v54, v13, v27
	v_and_b32_e32 v27, 0xffff0000, v34
	v_and_b32_e32 v26, 0xffff0000, v38
	v_and_b32_e32 v13, 0xffff0000, v14
	v_pk_mul_f32 v[16:17], v[24:25], v[26:27]
	v_pk_mul_f32 v[18:19], v[68:69], v[18:19] op_sel_hi:[0,1]
	v_fma_f32 v13, v45, v13, v16
	v_add_f32_e32 v55, v13, v17
	v_lshlrev_b32_e32 v17, 16, v35
	v_lshlrev_b32_e32 v16, 16, v39
	v_mov_b32_e32 v24, v18
	v_mov_b32_e32 v25, v22
	v_lshlrev_b32_e32 v13, 16, v15
	v_pk_mul_f32 v[16:17], v[24:25], v[16:17]
	v_and_b32_e32 v14, 0xffff0000, v39
	v_fma_f32 v13, v46, v13, v16
	v_add_f32_e32 v56, v13, v17
	v_and_b32_e32 v13, 0xffff0000, v15
	v_and_b32_e32 v15, 0xffff0000, v35
	v_mov_b32_e32 v22, v19
	v_pk_mul_f32 v[14:15], v[22:23], v[14:15]
	v_lshlrev_b32_e32 v16, 16, v12
	v_fma_f32 v14, v47, v13, v14
	v_lshlrev_b32_e32 v13, 16, v32
	v_lshlrev_b32_e32 v12, 16, v36
	v_mov_b32_e32 v21, v28
	v_pk_mul_f32 v[12:13], v[20:21], v[12:13]
	v_add_f32_e32 v57, v14, v15
	v_fma_f32 v12, v40, v16, v12
	v_add_f32_e32 v12, v12, v13
	v_add_f32_e32 v12, v12, v12
	v_mul_f32_e32 v24, 0x3fb8aa3b, v12
	v_add_u32_e32 v12, 0x980, v76
	v_ashrrev_i32_e32 v13, 31, v12
	v_exp_f32_e32 v38, v24
	v_lshlrev_b64 v[36:37], 2, v[12:13]
	v_lshl_add_u64 v[16:17], s[38:39], 0, v[36:37]
	v_lshlrev_b64 v[12:13], 1, v[12:13]
	v_lshl_add_u64 v[18:19], s[10:11], 0, v[36:37]
	global_load_dwordx4 v[20:23], v[16:17], off offset:16
	global_load_dwordx4 v[28:31], v[16:17], off
	global_load_dwordx4 v[32:35], v[18:19], off offset:16
	global_load_dwordx4 v[44:47], v[18:19], off
	v_lshl_add_u64 v[16:17], v[74:75], 0, v[12:13]
	v_lshl_add_u64 v[24:25], v[70:71], 0, v[12:13]
	v_lshl_add_u64 v[14:15], s[8:9], 0, v[36:37]
	global_load_dwordx4 v[16:19], v[16:17], off
	s_nop 0
	global_load_dwordx4 v[24:27], v[24:25], off
	v_add_f32_e32 v58, 1.0, v38
	global_load_dwordx4 v[36:39], v[14:15], off offset:16
	global_load_dwordx4 v[48:51], v[14:15], off
	v_add_f32_e32 v40, v41, v41
	v_lshl_add_u64 v[12:13], v[72:73], 0, v[12:13]
	v_mul_f32_e32 v14, 0x3fb8aa3b, v40
	global_load_dwordx4 v[40:43], v[12:13], off
	v_exp_f32_e32 v14, v14
	v_rcp_f32_e32 v12, v58
	v_add_f32_e32 v13, 1.0, v14
	v_add_f32_e32 v14, v52, v52
	v_mul_f32_e32 v14, 0x3fb8aa3b, v14
	v_exp_f32_e32 v15, v14
	v_add_f32_e32 v14, v53, v53
	v_mul_f32_e32 v14, 0x3fb8aa3b, v14
	v_exp_f32_e32 v52, v14
	v_rcp_f32_e32 v14, v13
	v_add_f32_e32 v13, 1.0, v15
	v_add_f32_e32 v53, v55, v55
	v_add_f32_e32 v15, 1.0, v52
	v_add_f32_e32 v52, v54, v54
	v_add_f32_e32 v54, v56, v56
	v_mul_f32_e32 v54, 0x3fb8aa3b, v54
	v_mul_f32_e32 v53, 0x3fb8aa3b, v53
	v_exp_f32_e32 v55, v54
	v_add_f32_e32 v54, v57, v57
	v_exp_f32_e32 v53, v53
	v_mul_f32_e32 v54, 0x3fb8aa3b, v54
	v_mul_f32_e32 v52, 0x3fb8aa3b, v52
	v_exp_f32_e32 v56, v54
	v_exp_f32_e32 v52, v52
	v_add_f32_e32 v53, 1.0, v53
	v_rcp_f32_e32 v54, v53
	v_add_f32_e32 v53, 1.0, v55
	v_add_f32_e32 v55, 1.0, v56
	v_rcp_f32_e32 v15, v15
	v_add_f32_e32 v52, 1.0, v52
	v_rcp_f32_e32 v55, v55
	v_rcp_f32_e32 v13, v13
	v_rcp_f32_e32 v52, v52
	v_rcp_f32_e32 v53, v53
	v_pk_fma_f32 v[14:15], v[14:15], 2.0, 1.0 op_sel_hi:[1,0,0] neg_lo:[1,0,0] neg_hi:[1,0,0]
	v_pk_fma_f32 v[54:55], v[54:55], 2.0, 1.0 op_sel_hi:[1,0,0] neg_lo:[1,0,0] neg_hi:[1,0,0]
	v_pk_fma_f32 v[12:13], v[12:13], 2.0, 1.0 op_sel_hi:[1,0,0] neg_lo:[1,0,0] neg_hi:[1,0,0]
	v_pk_fma_f32 v[52:53], v[52:53], 2.0, 1.0 op_sel_hi:[1,0,0] neg_lo:[1,0,0] neg_hi:[1,0,0]
	v_bfe_u32 v56, v55, 16, 1
	v_bfe_u32 v57, v54, 16, 1
	v_bfe_u32 v58, v15, 16, 1
	v_bfe_u32 v59, v14, 16, 1
	v_add3_u32 v59, v14, v59, s77
	v_add3_u32 v58, v15, v58, s77
	v_add3_u32 v14, v54, v57, s77
	v_add3_u32 v15, v55, v56, s77
	v_bfe_u32 v54, v12, 16, 1
	v_bfe_u32 v55, v13, 16, 1
	v_bfe_u32 v56, v52, 16, 1
	v_bfe_u32 v57, v53, 16, 1
	v_add3_u32 v53, v53, v57, s77
	v_add3_u32 v52, v52, v56, s77
	v_add3_u32 v13, v13, v55, s77
	v_add3_u32 v12, v12, v54, s77
	v_lshrrev_b32_e32 v12, 16, v12
	v_lshrrev_b32_e32 v13, 16, v13
	v_lshrrev_b32_e32 v52, 16, v52
	v_lshrrev_b32_e32 v53, 16, v53
	v_and_or_b32 v15, v15, s76, v53
	v_and_or_b32 v14, v14, s76, v52
	v_and_or_b32 v13, v58, s76, v13
	v_and_or_b32 v12, v59, s76, v12
	s_waitcnt vmcnt(8)
; __device__ __forceinline__ unsigned pk2(float lo, float hi) { return f2bf(lo) | (f2bf(hi) << 16); }
; __device__ __forceinline__ float sigmoid_f(float x) { return __builtin_amdgcn_rcpf(1.f + __expf(-x)); }
; __device__ __forceinline__ float tanh_f(float x) { const float e = __expf(2.f * x); return 1.f - 2.f * __builtin_amdgcn_rcpf(e + 1.f); }
; __device__ __forceinline__ void rwkv_proj_phase(const bf16* Z, const float* shift, const float* w0, const float* a0, const float* kkp, const float* kap, const float* rkp, ...
;     ...
;         for (int ks = 0; ks < 12; ++ks) {
;             const int col = 2304 + 32 * ks + 8 * g;
;             const u32x4 c0 = *(const u32x4*)(zr + col), cm = *(const u32x4*)(zr + offm + col), cp = *(const u32x4*)(zr + offp + col);
;             float val[8];
; #pragma unroll
;             for (int q = 0; q < 2; ++q) { const f32x4 t0 = *(const f32x4*)(shift + col + 4 * q) * fm, t1 = *(const f32x4*)(shift + BCOLS + col + 4 * q), t2 = *(const f32x4*)(shift + 2 * BCOLS + col + 4 * q) * fn;
;                 const unsigned m0 = q ? cm.z : cm.x, m1 = q ? cm.w : cm.y, z0 = q ? c0.z : c0.x, z1 = q ? c0.w : c0.y, p0 = q ? cp.z : cp.x, p1 = q ? cp.w : cp.y;
;                 val[4 * q + 0] = t0.x * bflo(m0) + t1.x * bflo(z0) + t2.x * bflo(p0);
;                 val[4 * q + 1] = t0.y * bfhi(m0) + t1.y * bfhi(z0) + t2.y * bfhi(p0);
;                 val[4 * q + 2] = t0.z * bflo(m1) + t1.z * bflo(z1) + t2.z * bflo(p1);
;                 val[4 * q + 3] = t0.w * bfhi(m1) + t1.w * bfhi(z1) + t2.w * bfhi(p1); }
; #pragma unroll
;             for (int e = 0; e < 8; ++e) { if (ks < 4) val[e] = tanh_f(val[e]); else if (ks >= 8) val[e] = sigmoid_f(val[e]); }
;             u32x4 pk; pk.x = pk2(val[0], val[1]); pk.y = pk2(val[2], val[3]); pk.z = pk2(val[4], val[5]); pk.w = pk2(val[6], val[7]);
;             xf[ks] = __builtin_bit_cast(bf16x8, pk);
;             if (ks & 1) asm volatile("" ::: "memory");
	v_pk_mul_f32 v[108:109], v[68:69], v[22:23] op_sel_hi:[0,1]
	s_waitcnt vmcnt(7)
	v_pk_mul_f32 v[64:65], v[68:69], v[30:31] op_sel_hi:[0,1]
	v_pk_mul_f32 v[86:87], v[68:69], v[28:29] op_sel_hi:[0,1]
	v_pk_mul_f32 v[110:111], v[68:69], v[20:21] op_sel_hi:[0,1]
	v_mov_b32_e32 v22, v86
	v_mov_b32_e32 v23, v64
	s_waitcnt vmcnt(4)
	v_lshlrev_b32_e32 v29, 16, v17
	v_lshlrev_b32_e32 v28, 16, v16
	s_waitcnt vmcnt(3)
	v_lshlrev_b32_e32 v21, 16, v25
	s_waitcnt vmcnt(1)
	v_mov_b32_e32 v30, v48
	v_mov_b32_e32 v31, v50
	v_lshlrev_b32_e32 v20, 16, v24
	v_pk_mul_f32 v[28:29], v[30:31], v[28:29]
	v_pk_mul_f32 v[114:115], v[66:67], v[32:33] op_sel_hi:[0,1]
	v_pk_fma_f32 v[32:33], v[22:23], v[20:21], v[28:29]
	v_add_u32_e32 v20, 0x9a0, v76
	v_ashrrev_i32_e32 v21, 31, v20
	v_pk_mul_f32 v[106:107], v[66:67], v[44:45] op_sel_hi:[0,1]
	v_lshlrev_b64 v[44:45], 2, v[20:21]
	v_pk_mul_f32 v[104:105], v[66:67], v[46:47] op_sel_hi:[0,1]
	v_lshl_add_u64 v[22:23], s[38:39], 0, v[44:45]
	v_lshl_add_u64 v[28:29], s[10:11], 0, v[44:45]
	v_lshlrev_b64 v[46:47], 1, v[20:21]
	v_pk_mul_f32 v[112:113], v[66:67], v[34:35] op_sel_hi:[0,1]
	s_waitcnt vmcnt(0)
	v_lshlrev_b32_e32 v35, 16, v41
	global_load_dwordx4 v[52:55], v[22:23], off offset:16
	global_load_dwordx4 v[56:59], v[22:23], off
	global_load_dwordx4 v[60:63], v[28:29], off offset:16
	global_load_dwordx4 v[78:81], v[28:29], off
	v_lshlrev_b32_e32 v34, 16, v40
	v_lshl_add_u64 v[20:21], v[74:75], 0, v[46:47]
	v_lshl_add_u64 v[28:29], v[70:71], 0, v[46:47]
	v_mov_b32_e32 v82, v106
	v_mov_b32_e32 v83, v104
	v_lshl_add_u64 v[44:45], s[8:9], 0, v[44:45]
	global_load_dwordx4 v[20:23], v[20:21], off
	s_nop 0
	global_load_dwordx4 v[28:31], v[28:29], off
	v_pk_fma_f32 v[116:117], v[82:83], v[34:35], v[32:33]
	global_load_dwordx4 v[32:35], v[44:45], off offset:16
	global_load_dwordx4 v[82:85], v[44:45], off
	v_lshl_add_u64 v[44:45], v[72:73], 0, v[46:47]
	global_load_dwordx4 v[44:47], v[44:45], off
	v_and_b32_e32 v17, 0xffff0000, v17
	v_and_b32_e32 v16, 0xffff0000, v16
	v_mov_b32_e32 v50, v49
	v_and_b32_e32 v25, 0xffff0000, v25
	v_and_b32_e32 v24, 0xffff0000, v24
	v_mov_b32_e32 v64, v87
	v_pk_mul_f32 v[16:17], v[50:51], v[16:17]
	v_mov_b32_e32 v104, v107
	v_pk_fma_f32 v[16:17], v[64:65], v[24:25], v[16:17]
	v_and_b32_e32 v25, 0xffff0000, v41
	v_and_b32_e32 v24, 0xffff0000, v40
	v_lshlrev_b32_e32 v49, 16, v19
	v_lshlrev_b32_e32 v48, 16, v18
	v_mov_b32_e32 v50, v36
	v_mov_b32_e32 v51, v38
	v_and_b32_e32 v19, 0xffff0000, v19
	v_and_b32_e32 v18, 0xffff0000, v18
	v_mov_b32_e32 v38, v37
	v_pk_fma_f32 v[16:17], v[104:105], v[24:25], v[16:17]
	v_lshlrev_b32_e32 v25, 16, v27
	v_lshlrev_b32_e32 v24, 16, v26
	v_mov_b32_e32 v40, v110
	v_mov_b32_e32 v41, v108
	v_pk_mul_f32 v[48:49], v[50:51], v[48:49]
	v_and_b32_e32 v27, 0xffff0000, v27
	v_and_b32_e32 v26, 0xffff0000, v26
	v_mov_b32_e32 v108, v111
	v_pk_mul_f32 v[18:19], v[38:39], v[18:19]
	v_pk_fma_f32 v[24:25], v[40:41], v[24:25], v[48:49]
	v_mov_b32_e32 v49, v112
	v_pk_fma_f32 v[18:19], v[108:109], v[26:27], v[18:19]
	v_and_b32_e32 v27, 0xffff0000, v43
	v_and_b32_e32 v26, 0xffff0000, v42
	v_mov_b32_e32 v112, v115
	v_lshlrev_b32_e32 v41, 16, v43
	v_lshlrev_b32_e32 v40, 16, v42
	v_mov_b32_e32 v48, v114
	v_pk_fma_f32 v[18:19], v[112:113], v[26:27], v[18:19]
	v_pk_fma_f32 v[24:25], v[48:49], v[40:41], v[24:25]
	v_cvt_pk_bf16_f32 v19, v25, v19
	v_cvt_pk_bf16_f32 v18, v24, v18
	v_cvt_pk_bf16_f32 v17, v117, v17
	v_cvt_pk_bf16_f32 v16, v116, v16
	s_waitcnt vmcnt(8)
	v_pk_mul_f32 v[112:113], v[68:69], v[54:55] op_sel_hi:[0,1]
	s_waitcnt vmcnt(7)
	v_pk_mul_f32 v[64:65], v[68:69], v[58:59] op_sel_hi:[0,1]
	v_pk_mul_f32 v[86:87], v[68:69], v[56:57] op_sel_hi:[0,1]
	v_mov_b32_e32 v26, v86
	v_mov_b32_e32 v27, v64
	s_waitcnt vmcnt(5)
	v_pk_mul_f32 v[108:109], v[66:67], v[80:81] op_sel_hi:[0,1]
	v_pk_mul_f32 v[110:111], v[66:67], v[78:79] op_sel_hi:[0,1]
	v_pk_mul_f32 v[114:115], v[68:69], v[52:53] op_sel_hi:[0,1]
	v_pk_mul_f32 v[116:117], v[66:67], v[62:63] op_sel_hi:[0,1]
	s_waitcnt vmcnt(4)
	v_lshlrev_b32_e32 v37, 16, v21
	v_lshlrev_b32_e32 v36, 16, v20
	s_waitcnt vmcnt(3)
	v_lshlrev_b32_e32 v25, 16, v29
	s_waitcnt vmcnt(1)
	v_mov_b32_e32 v38, v82
	v_mov_b32_e32 v39, v84
	v_lshlrev_b32_e32 v24, 16, v28
	v_pk_mul_f32 v[36:37], v[38:39], v[36:37]
	v_pk_mul_f32 v[118:119], v[66:67], v[60:61] op_sel_hi:[0,1]
	v_pk_fma_f32 v[40:41], v[26:27], v[24:25], v[36:37]
	v_add_u32_e32 v24, 0x9c0, v76
	v_ashrrev_i32_e32 v25, 31, v24
	v_lshlrev_b64 v[48:49], 2, v[24:25]
	v_lshl_add_u64 v[26:27], s[38:39], 0, v[48:49]
	v_lshl_add_u64 v[36:37], s[10:11], 0, v[48:49]
	v_lshlrev_b64 v[50:51], 1, v[24:25]
	s_waitcnt vmcnt(0)
; __device__ __forceinline__ unsigned pk2(float lo, float hi) { return f2bf(lo) | (f2bf(hi) << 16); }
; __device__ __forceinline__ float sigmoid_f(float x) { return __builtin_amdgcn_rcpf(1.f + __expf(-x)); }
; __device__ __forceinline__ float tanh_f(float x) { const float e = __expf(2.f * x); return 1.f - 2.f * __builtin_amdgcn_rcpf(e + 1.f); }
; __device__ __forceinline__ void rwkv_proj_phase(const bf16* Z, const float* shift, const float* w0, const float* a0, const float* kkp, const float* kap, const float* rkp, ...
;     ...
;         for (int ks = 0; ks < 12; ++ks) {
;             const int col = 2304 + 32 * ks + 8 * g;
;             const u32x4 c0 = *(const u32x4*)(zr + col), cm = *(const u32x4*)(zr + offm + col), cp = *(const u32x4*)(zr + offp + col);
;             float val[8];
; #pragma unroll
;             for (int q = 0; q < 2; ++q) { const f32x4 t0 = *(const f32x4*)(shift + col + 4 * q) * fm, t1 = *(const f32x4*)(shift + BCOLS + col + 4 * q), t2 = *(const f32x4*)(shift + 2 * BCOLS + col + 4 * q) * fn;
;                 const unsigned m0 = q ? cm.z : cm.x, m1 = q ? cm.w : cm.y, z0 = q ? c0.z : c0.x, z1 = q ? c0.w : c0.y, p0 = q ? cp.z : cp.x, p1 = q ? cp.w : cp.y;
;                 val[4 * q + 0] = t0.x * bflo(m0) + t1.x * bflo(z0) + t2.x * bflo(p0);
;                 val[4 * q + 1] = t0.y * bfhi(m0) + t1.y * bfhi(z0) + t2.y * bfhi(p0);
;                 val[4 * q + 2] = t0.z * bflo(m1) + t1.z * bflo(z1) + t2.z * bflo(p1);
;                 val[4 * q + 3] = t0.w * bfhi(m1) + t1.w * bfhi(z1) + t2.w * bfhi(p1); }
; #pragma unroll
;             for (int e = 0; e < 8; ++e) { if (ks < 4) val[e] = tanh_f(val[e]); else if (ks >= 8) val[e] = sigmoid_f(val[e]); }
;             u32x4 pk; pk.x = pk2(val[0], val[1]); pk.y = pk2(val[2], val[3]); pk.z = pk2(val[4], val[5]); pk.w = pk2(val[6], val[7]);
;             xf[ks] = __builtin_bit_cast(bf16x8, pk);
;             if (ks & 1) asm volatile("" ::: "memory");
	v_lshlrev_b32_e32 v43, 16, v45
	global_load_dwordx4 v[52:55], v[26:27], off offset:16
	global_load_dwordx4 v[56:59], v[26:27], off
	global_load_dwordx4 v[60:63], v[36:37], off offset:16
	global_load_dwordx4 v[78:81], v[36:37], off
	v_lshlrev_b32_e32 v42, 16, v44
	v_lshl_add_u64 v[24:25], v[74:75], 0, v[50:51]
	v_lshl_add_u64 v[36:37], v[70:71], 0, v[50:51]
	v_mov_b32_e32 v104, v110
	v_mov_b32_e32 v105, v108
	v_lshl_add_u64 v[48:49], s[8:9], 0, v[48:49]
	global_load_dwordx4 v[24:27], v[24:25], off
	s_nop 0
	global_load_dwordx4 v[36:39], v[36:37], off
	v_pk_fma_f32 v[120:121], v[104:105], v[42:43], v[40:41]
	global_load_dwordx4 v[40:43], v[48:49], off offset:16
	global_load_dwordx4 v[104:107], v[48:49], off
	v_lshl_add_u64 v[48:49], v[72:73], 0, v[50:51]
	global_load_dwordx4 v[48:51], v[48:49], off
	v_and_b32_e32 v21, 0xffff0000, v21
	v_and_b32_e32 v20, 0xffff0000, v20
	v_mov_b32_e32 v84, v83
	v_and_b32_e32 v29, 0xffff0000, v29
	v_and_b32_e32 v28, 0xffff0000, v28
	v_mov_b32_e32 v64, v87
	v_pk_mul_f32 v[20:21], v[84:85], v[20:21]
	v_mov_b32_e32 v108, v111
	v_pk_fma_f32 v[20:21], v[64:65], v[28:29], v[20:21]
	v_and_b32_e32 v29, 0xffff0000, v45
	v_and_b32_e32 v28, 0xffff0000, v44
	v_lshlrev_b32_e32 v65, 16, v23
	v_lshlrev_b32_e32 v64, 16, v22
	v_mov_b32_e32 v82, v32
	v_mov_b32_e32 v83, v34
	v_and_b32_e32 v23, 0xffff0000, v23
	v_and_b32_e32 v22, 0xffff0000, v22
	v_mov_b32_e32 v34, v33
	v_pk_fma_f32 v[20:21], v[108:109], v[28:29], v[20:21]
	v_lshlrev_b32_e32 v29, 16, v31
	v_lshlrev_b32_e32 v28, 16, v30
	v_mov_b32_e32 v44, v114
	v_mov_b32_e32 v45, v112
	v_pk_mul_f32 v[64:65], v[82:83], v[64:65]
	v_and_b32_e32 v31, 0xffff0000, v31
	v_and_b32_e32 v30, 0xffff0000, v30
	v_mov_b32_e32 v112, v115
	v_pk_mul_f32 v[22:23], v[34:35], v[22:23]
	v_pk_fma_f32 v[28:29], v[44:45], v[28:29], v[64:65]
	v_mov_b32_e32 v65, v116
	v_pk_fma_f32 v[22:23], v[112:113], v[30:31], v[22:23]
	v_and_b32_e32 v31, 0xffff0000, v47
	v_and_b32_e32 v30, 0xffff0000, v46
	v_mov_b32_e32 v116, v119
	v_lshlrev_b32_e32 v45, 16, v47
	v_lshlrev_b32_e32 v44, 16, v46
	v_mov_b32_e32 v64, v118
	v_pk_fma_f32 v[22:23], v[116:117], v[30:31], v[22:23]
	v_pk_fma_f32 v[28:29], v[64:65], v[44:45], v[28:29]
	v_cvt_pk_bf16_f32 v23, v29, v23
	v_cvt_pk_bf16_f32 v22, v28, v22
	v_cvt_pk_bf16_f32 v21, v121, v21
	v_cvt_pk_bf16_f32 v20, v120, v20
	s_waitcnt vmcnt(8)
	v_pk_mul_f32 v[112:113], v[68:69], v[54:55] op_sel_hi:[0,1]
	s_waitcnt vmcnt(7)
	v_pk_mul_f32 v[86:87], v[68:69], v[58:59] op_sel_hi:[0,1]
	v_pk_mul_f32 v[56:57], v[68:69], v[56:57] op_sel_hi:[0,1]
	v_mov_b32_e32 v30, v56
	v_mov_b32_e32 v31, v86
	s_waitcnt vmcnt(6)
	v_pk_mul_f32 v[116:117], v[66:67], v[62:63] op_sel_hi:[0,1]
	s_waitcnt vmcnt(5)
	v_pk_mul_f32 v[108:109], v[66:67], v[80:81] op_sel_hi:[0,1]
	v_pk_mul_f32 v[110:111], v[66:67], v[78:79] op_sel_hi:[0,1]
	v_pk_mul_f32 v[114:115], v[68:69], v[52:53] op_sel_hi:[0,1]
	s_waitcnt vmcnt(4)
	v_lshlrev_b32_e32 v33, 16, v25
	v_lshlrev_b32_e32 v32, 16, v24
	s_waitcnt vmcnt(3)
	v_lshlrev_b32_e32 v29, 16, v37
	s_waitcnt vmcnt(1)
	v_mov_b32_e32 v34, v104
	v_mov_b32_e32 v35, v106
	v_lshlrev_b32_e32 v28, 16, v36
	v_pk_mul_f32 v[32:33], v[34:35], v[32:33]
	s_waitcnt vmcnt(0)
	v_lshlrev_b32_e32 v65, 16, v49
	v_pk_fma_f32 v[62:63], v[30:31], v[28:29], v[32:33]
	v_add_u32_e32 v28, 0x9e0, v76
	v_ashrrev_i32_e32 v29, 31, v28
	v_lshlrev_b64 v[82:83], 2, v[28:29]
	v_lshl_add_u64 v[30:31], s[38:39], 0, v[82:83]
	v_lshl_add_u64 v[58:59], s[10:11], 0, v[82:83]
	global_load_dwordx4 v[32:35], v[30:31], off offset:16
	global_load_dwordx4 v[44:47], v[30:31], off
	global_load_dwordx4 v[52:55], v[58:59], off offset:16
	global_load_dwordx4 v[78:81], v[58:59], off
	v_lshlrev_b64 v[120:121], 1, v[28:29]
	v_lshlrev_b32_e32 v64, 16, v48
	v_lshl_add_u64 v[28:29], v[74:75], 0, v[120:121]
	v_lshl_add_u64 v[58:59], v[70:71], 0, v[120:121]
	v_mov_b32_e32 v84, v110
	v_mov_b32_e32 v85, v108
	v_lshl_add_u64 v[82:83], s[8:9], 0, v[82:83]
	v_pk_mul_f32 v[118:119], v[66:67], v[60:61] op_sel_hi:[0,1]
	global_load_dwordx4 v[28:31], v[28:29], off
	s_nop 0
	global_load_dwordx4 v[58:61], v[58:59], off
	v_pk_fma_f32 v[122:123], v[84:85], v[64:65], v[62:63]
	global_load_dwordx4 v[62:65], v[82:83], off offset:16
	s_nop 0
	global_load_dwordx4 v[82:85], v[82:83], off
	v_and_b32_e32 v25, 0xffff0000, v25
	v_and_b32_e32 v24, 0xffff0000, v24
	v_mov_b32_e32 v106, v105
	v_and_b32_e32 v37, 0xffff0000, v37
	v_and_b32_e32 v36, 0xffff0000, v36
	v_mov_b32_e32 v86, v57
	v_pk_mul_f32 v[24:25], v[106:107], v[24:25]
	v_mov_b32_e32 v108, v111
	v_pk_fma_f32 v[24:25], v[86:87], v[36:37], v[24:25]
	v_and_b32_e32 v37, 0xffff0000, v49
	v_and_b32_e32 v36, 0xffff0000, v48
	v_lshlrev_b32_e32 v57, 16, v27
	v_lshlrev_b32_e32 v56, 16, v26
	v_mov_b32_e32 v86, v40
	v_mov_b32_e32 v87, v42
	v_pk_fma_f32 v[24:25], v[108:109], v[36:37], v[24:25]
	v_lshlrev_b32_e32 v37, 16, v39
	v_lshlrev_b32_e32 v36, 16, v38
	v_mov_b32_e32 v48, v114
	v_mov_b32_e32 v49, v112
	v_pk_mul_f32 v[56:57], v[86:87], v[56:57]
	v_and_b32_e32 v27, 0xffff0000, v27
	v_pk_fma_f32 v[36:37], v[48:49], v[36:37], v[56:57]
	v_lshl_add_u64 v[48:49], v[72:73], 0, v[120:121]
	global_load_dwordx4 v[104:107], v[48:49], off
	v_and_b32_e32 v26, 0xffff0000, v26
	v_mov_b32_e32 v42, v41
	v_lshlrev_b32_e32 v49, 16, v51
	v_lshlrev_b32_e32 v48, 16, v50
	v_mov_b32_e32 v56, v118
	v_mov_b32_e32 v57, v116
	v_and_b32_e32 v39, 0xffff0000, v39
	v_and_b32_e32 v38, 0xffff0000, v38
	v_mov_b32_e32 v112, v115
	v_pk_mul_f32 v[26:27], v[42:43], v[26:27]
	v_pk_fma_f32 v[36:37], v[56:57], v[48:49], v[36:37]
	v_pk_fma_f32 v[26:27], v[112:113], v[38:39], v[26:27]
	v_and_b32_e32 v39, 0xffff0000, v51
	v_and_b32_e32 v38, 0xffff0000, v50
	v_mov_b32_e32 v116, v119
	v_bfe_u32 v41, v24, 16, 1
	v_pk_fma_f32 v[26:27], v[116:117], v[38:39], v[26:27]
	v_add3_u32 v24, v24, v41, s77
	v_cvt_pk_bf16_f32 v27, v37, v27
	v_cvt_pk_bf16_f32 v26, v36, v26
	v_bfe_u32 v38, v122, 16, 1
	v_add3_u32 v38, v122, v38, s77
	v_lshrrev_b32_e32 v38, 16, v38
	v_cvt_pk_bf16_f32 v25, v123, v25
	s_waitcnt vmcnt(8)
; __device__ __forceinline__ unsigned pk2(float lo, float hi) { return f2bf(lo) | (f2bf(hi) << 16); }
; __device__ __forceinline__ float sigmoid_f(float x) { return __builtin_amdgcn_rcpf(1.f + __expf(-x)); }
; __device__ __forceinline__ float tanh_f(float x) { const float e = __expf(2.f * x); return 1.f - 2.f * __builtin_amdgcn_rcpf(e + 1.f); }
; __device__ __forceinline__ void rwkv_proj_phase(const bf16* Z, const float* shift, const float* w0, const float* a0, const float* kkp, const float* kap, const float* rkp, ...
;     ...
;         for (int ks = 0; ks < 12; ++ks) {
;             const int col = 2304 + 32 * ks + 8 * g;
;             const u32x4 c0 = *(const u32x4*)(zr + col), cm = *(const u32x4*)(zr + offm + col), cp = *(const u32x4*)(zr + offp + col);
;             float val[8];
; #pragma unroll
;             for (int q = 0; q < 2; ++q) { const f32x4 t0 = *(const f32x4*)(shift + col + 4 * q) * fm, t1 = *(const f32x4*)(shift + BCOLS + col + 4 * q), t2 = *(const f32x4*)(shift + 2 * BCOLS + col + 4 * q) * fn;
;                 const unsigned m0 = q ? cm.z : cm.x, m1 = q ? cm.w : cm.y, z0 = q ? c0.z : c0.x, z1 = q ? c0.w : c0.y, p0 = q ? cp.z : cp.x, p1 = q ? cp.w : cp.y;
;                 val[4 * q + 0] = t0.x * bflo(m0) + t1.x * bflo(z0) + t2.x * bflo(p0);
;                 val[4 * q + 1] = t0.y * bfhi(m0) + t1.y * bfhi(z0) + t2.y * bfhi(p0);
;                 val[4 * q + 2] = t0.z * bflo(m1) + t1.z * bflo(z1) + t2.z * bflo(p1);
;                 val[4 * q + 3] = t0.w * bfhi(m1) + t1.w * bfhi(z1) + t2.w * bfhi(p1); }
; #pragma unroll
;             for (int e = 0; e < 8; ++e) { if (ks < 4) val[e] = tanh_f(val[e]); else if (ks >= 8) val[e] = sigmoid_f(val[e]); }
;             u32x4 pk; pk.x = pk2(val[0], val[1]); pk.y = pk2(val[2], val[3]); pk.z = pk2(val[4], val[5]); pk.w = pk2(val[6], val[7]);
;             xf[ks] = __builtin_bit_cast(bf16x8, pk);
;             if (ks & 1) asm volatile("" ::: "memory");
	v_pk_mul_f32 v[124:125], v[68:69], v[32:33] op_sel_hi:[0,1]
	s_waitcnt vmcnt(7)
	v_pk_mul_f32 v[42:43], v[68:69], v[44:45] op_sel_hi:[0,1]
	v_add_u32_e32 v44, 0xa00, v76
	v_ashrrev_i32_e32 v45, 31, v44
	v_pk_mul_f32 v[36:37], v[68:69], v[46:47] op_sel_hi:[0,1]
	v_lshlrev_b64 v[46:47], 1, v[44:45]
	v_lshlrev_b64 v[116:117], 2, v[44:45]
	v_lshl_add_u64 v[32:33], v[74:75], 0, v[46:47]
	v_lshl_add_u64 v[44:45], s[38:39], 0, v[116:117]
	s_waitcnt vmcnt(5)
	v_pk_mul_f32 v[86:87], v[66:67], v[80:81] op_sel_hi:[0,1]
	v_pk_mul_f32 v[120:121], v[66:67], v[78:79] op_sel_hi:[0,1]
	v_pk_mul_f32 v[122:123], v[68:69], v[34:35] op_sel_hi:[0,1]
	v_pk_mul_f32 v[126:127], v[66:67], v[54:55] op_sel_hi:[0,1]
	global_load_dwordx4 v[32:35], v[32:33], off
	v_lshl_add_u64 v[54:55], s[10:11], 0, v[116:117]
	global_load_dwordx4 v[48:51], v[44:45], off offset:16
	global_load_dwordx4 v[78:81], v[44:45], off
	global_load_dwordx4 v[108:111], v[54:55], off offset:16
	global_load_dwordx4 v[112:115], v[54:55], off
	v_lshl_add_u64 v[44:45], v[70:71], 0, v[46:47]
	v_lshl_add_u64 v[46:47], v[72:73], 0, v[46:47]
	global_load_dwordx4 v[54:57], v[46:47], off
	s_nop 0
	global_load_dwordx4 v[44:47], v[44:45], off
	v_and_or_b32 v24, v24, s76, v38
	s_waitcnt vmcnt(11)
	v_lshlrev_b32_e32 v39, 16, v29
	v_lshlrev_b32_e32 v38, 16, v28
	s_waitcnt vmcnt(8)
	v_mov_b32_e32 v40, v82
	v_mov_b32_e32 v41, v84
	v_lshl_add_u64 v[116:117], s[8:9], 0, v[116:117]
	v_pk_mul_f32 v[132:133], v[40:41], v[38:39]
	global_load_dwordx4 v[38:41], v[116:117], off offset:16
	s_nop 0
	global_load_dwordx4 v[116:119], v[116:117], off
	v_and_b32_e32 v29, 0xffff0000, v29
	v_and_b32_e32 v28, 0xffff0000, v28
	v_mov_b32_e32 v84, v83
	v_lshlrev_b32_e32 v129, 16, v59
	v_lshlrev_b32_e32 v128, 16, v58
	v_mov_b32_e32 v130, v42
	v_mov_b32_e32 v131, v36
	v_and_b32_e32 v59, 0xffff0000, v59
	v_and_b32_e32 v58, 0xffff0000, v58
	v_mov_b32_e32 v36, v43
	v_pk_mul_f32 v[28:29], v[84:85], v[28:29]
	v_pk_fma_f32 v[128:129], v[130:131], v[128:129], v[132:133]
	v_mov_b32_e32 v133, v86
	v_pk_fma_f32 v[28:29], v[36:37], v[58:59], v[28:29]
	s_waitcnt vmcnt(9)
	v_and_b32_e32 v37, 0xffff0000, v105
	v_and_b32_e32 v36, 0xffff0000, v104
	v_mov_b32_e32 v86, v121
	v_lshlrev_b32_e32 v59, 16, v31
	v_lshlrev_b32_e32 v58, 16, v30
	v_mov_b32_e32 v82, v62
	v_mov_b32_e32 v83, v64
	v_pk_mul_f32 v[52:53], v[66:67], v[52:53] op_sel_hi:[0,1]
	v_pk_fma_f32 v[28:29], v[86:87], v[36:37], v[28:29]
	v_lshlrev_b32_e32 v37, 16, v61
	v_lshlrev_b32_e32 v36, 16, v60
	v_mov_b32_e32 v42, v124
	v_mov_b32_e32 v43, v122
	v_pk_mul_f32 v[58:59], v[82:83], v[58:59]
	v_and_b32_e32 v31, 0xffff0000, v31
	v_pk_fma_f32 v[36:37], v[42:43], v[36:37], v[58:59]
	v_lshlrev_b32_e32 v43, 16, v107
	v_lshlrev_b32_e32 v42, 16, v106
	v_mov_b32_e32 v58, v52
	v_mov_b32_e32 v59, v126
	v_and_b32_e32 v30, 0xffff0000, v30
	v_mov_b32_e32 v64, v63
	v_pk_fma_f32 v[36:37], v[58:59], v[42:43], v[36:37]
	v_and_b32_e32 v43, 0xffff0000, v61
	v_and_b32_e32 v42, 0xffff0000, v60
	v_mov_b32_e32 v122, v125
	v_pk_mul_f32 v[30:31], v[64:65], v[30:31]
	v_mov_b32_e32 v126, v53
	v_pk_fma_f32 v[30:31], v[122:123], v[42:43], v[30:31]
	v_and_b32_e32 v43, 0xffff0000, v107
	v_and_b32_e32 v42, 0xffff0000, v106
	v_lshlrev_b32_e32 v131, 16, v105
	v_lshlrev_b32_e32 v130, 16, v104
	v_mov_b32_e32 v132, v120
	v_pk_fma_f32 v[30:31], v[126:127], v[42:43], v[30:31]
	v_pk_fma_f32 v[128:129], v[132:133], v[130:131], v[128:129]
	v_cvt_pk_bf16_f32 v29, v129, v29
	v_cvt_pk_bf16_f32 v28, v128, v28
	s_waitcnt vmcnt(6)
	v_pk_mul_f32 v[42:43], v[68:69], v[78:79] op_sel_hi:[0,1]
	v_mov_b32_e32 v62, v42
	s_waitcnt vmcnt(4)
	v_pk_mul_f32 v[58:59], v[66:67], v[112:113] op_sel_hi:[0,1]
	v_mov_b32_e32 v63, v58
	s_waitcnt vmcnt(3)
	v_lshlrev_b32_e32 v61, 16, v54
	s_waitcnt vmcnt(2)
	v_lshlrev_b32_e32 v60, 16, v44
	v_lshlrev_b32_e32 v64, 16, v32
	v_pk_mul_f32 v[60:61], v[62:63], v[60:61]
	v_mov_b32_e32 v58, v43
	s_waitcnt vmcnt(0)
	v_fma_f32 v42, v116, v64, v60
	v_add_f32_e32 v77, v42, v61
	v_and_b32_e32 v61, 0xffff0000, v54
	v_and_b32_e32 v60, 0xffff0000, v44
	v_and_b32_e32 v32, 0xffff0000, v32
	v_pk_mul_f32 v[42:43], v[58:59], v[60:61]
	v_cvt_pk_bf16_f32 v31, v37, v31
	v_cvt_pk_bf16_f32 v30, v36, v30
	v_pk_mul_f32 v[36:37], v[68:69], v[80:81] op_sel_hi:[0,1]
	v_pk_mul_f32 v[52:53], v[66:67], v[114:115] op_sel_hi:[0,1]
	v_fma_f32 v32, v117, v32, v42
	v_add_f32_e32 v88, v32, v43
	v_lshlrev_b32_e32 v43, 16, v55
	v_lshlrev_b32_e32 v42, 16, v45
	v_mov_b32_e32 v58, v36
	v_mov_b32_e32 v59, v52
	v_lshlrev_b32_e32 v32, 16, v33
	v_pk_mul_f32 v[42:43], v[58:59], v[42:43]
	v_and_b32_e32 v36, 0xffff0000, v33
	v_fma_f32 v32, v118, v32, v42
	v_add_f32_e32 v112, v32, v43
	v_and_b32_e32 v33, 0xffff0000, v55
	v_and_b32_e32 v32, 0xffff0000, v45
	v_mov_b32_e32 v52, v37
	v_pk_mul_f32 v[32:33], v[52:53], v[32:33]
	v_pk_mul_f32 v[42:43], v[66:67], v[108:109] op_sel_hi:[0,1]
	v_fma_f32 v32, v119, v36, v32
	v_pk_mul_f32 v[36:37], v[68:69], v[48:49] op_sel_hi:[0,1]
	v_lshlrev_b32_e32 v45, 16, v56
	v_lshlrev_b32_e32 v44, 16, v46
	v_mov_b32_e32 v48, v36
	v_mov_b32_e32 v49, v42
	v_add_f32_e32 v113, v32, v33
	v_pk_mul_f32 v[32:33], v[68:69], v[50:51] op_sel_hi:[0,1]
	v_lshlrev_b32_e32 v50, 16, v34
	v_pk_mul_f32 v[44:45], v[48:49], v[44:45]
	v_mov_b32_e32 v42, v37
	v_fma_f32 v36, v38, v50, v44
	v_add_f32_e32 v114, v36, v45
	v_and_b32_e32 v45, 0xffff0000, v56
	v_and_b32_e32 v44, 0xffff0000, v46
	v_pk_mul_f32 v[36:37], v[42:43], v[44:45]
	v_add_u32_e32 v42, 0xa20, v76
	v_and_b32_e32 v34, 0xffff0000, v34
	v_ashrrev_i32_e32 v43, 31, v42
	v_fma_f32 v34, v39, v34, v36
	v_lshlrev_b64 v[44:45], 1, v[42:43]
	v_lshlrev_b64 v[42:43], 2, v[42:43]
	v_add_f32_e32 v46, v34, v37
; __device__ __forceinline__ unsigned pk2(float lo, float hi) { return f2bf(lo) | (f2bf(hi) << 16); }
; __device__ __forceinline__ float sigmoid_f(float x) { return __builtin_amdgcn_rcpf(1.f + __expf(-x)); }
; __device__ __forceinline__ float tanh_f(float x) { const float e = __expf(2.f * x); return 1.f - 2.f * __builtin_amdgcn_rcpf(e + 1.f); }
; __device__ __forceinline__ void rwkv_proj_phase(const bf16* Z, const float* shift, const float* w0, const float* a0, const float* kkp, const float* kap, const float* rkp, ...
;     ...
;         for (int ks = 0; ks < 12; ++ks) {
;             const int col = 2304 + 32 * ks + 8 * g;
;             const u32x4 c0 = *(const u32x4*)(zr + col), cm = *(const u32x4*)(zr + offm + col), cp = *(const u32x4*)(zr + offp + col);
;             float val[8];
; #pragma unroll
;             for (int q = 0; q < 2; ++q) { const f32x4 t0 = *(const f32x4*)(shift + col + 4 * q) * fm, t1 = *(const f32x4*)(shift + BCOLS + col + 4 * q), t2 = *(const f32x4*)(shift + 2 * BCOLS + col + 4 * q) * fn;
;                 const unsigned m0 = q ? cm.z : cm.x, m1 = q ? cm.w : cm.y, z0 = q ? c0.z : c0.x, z1 = q ? c0.w : c0.y, p0 = q ? cp.z : cp.x, p1 = q ? cp.w : cp.y;
;                 val[4 * q + 0] = t0.x * bflo(m0) + t1.x * bflo(z0) + t2.x * bflo(p0);
;                 val[4 * q + 1] = t0.y * bfhi(m0) + t1.y * bfhi(z0) + t2.y * bfhi(p0);
;                 val[4 * q + 2] = t0.z * bflo(m1) + t1.z * bflo(z1) + t2.z * bflo(p1);
;                 val[4 * q + 3] = t0.w * bfhi(m1) + t1.w * bfhi(z1) + t2.w * bfhi(p1); }
; #pragma unroll
;             for (int e = 0; e < 8; ++e) { if (ks < 4) val[e] = tanh_f(val[e]); else if (ks >= 8) val[e] = sigmoid_f(val[e]); }
;             u32x4 pk; pk.x = pk2(val[0], val[1]); pk.y = pk2(val[2], val[3]); pk.z = pk2(val[4], val[5]); pk.w = pk2(val[6], val[7]);
;             xf[ks] = __builtin_bit_cast(bf16x8, pk);
;             if (ks & 1) asm volatile("" ::: "memory");
	v_lshl_add_u64 v[36:37], v[74:75], 0, v[44:45]
	v_lshl_add_u64 v[48:49], s[38:39], 0, v[42:43]
	global_load_dwordx4 v[36:39], v[36:37], off
	v_lshl_add_u64 v[50:51], s[10:11], 0, v[42:43]
	global_load_dwordx4 v[58:61], v[48:49], off offset:16
	global_load_dwordx4 v[62:65], v[48:49], off
	global_load_dwordx4 v[78:81], v[50:51], off offset:16
	global_load_dwordx4 v[82:85], v[50:51], off
	v_lshl_add_u64 v[48:49], v[70:71], 0, v[44:45]
	v_lshl_add_u64 v[44:45], v[72:73], 0, v[44:45]
	global_load_dwordx4 v[52:55], v[44:45], off
	s_nop 0
	global_load_dwordx4 v[48:51], v[48:49], off
	v_lshl_add_u64 v[104:105], s[8:9], 0, v[42:43]
	global_load_dwordx4 v[42:45], v[104:105], off offset:16
	s_nop 0
	global_load_dwordx4 v[104:107], v[104:105], off
	v_pk_mul_f32 v[86:87], v[66:67], v[110:111] op_sel_hi:[0,1]
	v_lshlrev_b32_e32 v109, 16, v57
	v_lshlrev_b32_e32 v108, 16, v47
	v_mov_b32_e32 v110, v32
	v_mov_b32_e32 v111, v86
	v_lshlrev_b32_e32 v34, 16, v35
	v_pk_mul_f32 v[108:109], v[110:111], v[108:109]
	v_and_b32_e32 v56, 0xffff0000, v35
	v_fma_f32 v32, v40, v34, v108
	v_add_f32_e32 v40, v32, v109
	v_and_b32_e32 v35, 0xffff0000, v57
	v_and_b32_e32 v34, 0xffff0000, v47
	v_mov_b32_e32 v86, v33
	v_mul_f32_e32 v32, 0xbfb8aa3b, v77
	v_exp_f32_e32 v47, v32
	v_pk_mul_f32 v[32:33], v[86:87], v[34:35]
	v_mul_f32_e32 v34, 0xbfb8aa3b, v88
	v_fma_f32 v32, v41, v56, v32
	v_add_f32_e32 v32, v32, v33
	v_mul_f32_e32 v41, 0xbfb8aa3b, v113
	v_mul_f32_e32 v46, 0xbfb8aa3b, v46
	v_mul_f32_e32 v32, 0xbfb8aa3b, v32
	v_add_f32_e32 v33, 1.0, v47
	v_exp_f32_e32 v34, v34
	v_mul_f32_e32 v35, 0xbfb8aa3b, v112
	v_exp_f32_e32 v41, v41
	v_mul_f32_e32 v47, 0xbfb8aa3b, v114
	v_exp_f32_e32 v46, v46
	v_exp_f32_e32 v32, v32
	v_mul_f32_e32 v40, 0xbfb8aa3b, v40
	v_exp_f32_e32 v35, v35
	v_exp_f32_e32 v47, v47
	v_exp_f32_e32 v40, v40
	v_add_f32_e32 v34, 1.0, v34
	v_add_f32_e32 v41, 1.0, v41
	v_add_f32_e32 v46, 1.0, v46
	v_add_f32_e32 v32, 1.0, v32
	v_rcp_f32_e32 v34, v34
	v_add_f32_e32 v35, 1.0, v35
	v_rcp_f32_e32 v41, v41
	v_add_f32_e32 v47, 1.0, v47
	v_rcp_f32_e32 v32, v32
	v_rcp_f32_e32 v46, v46
	v_add_f32_e32 v40, 1.0, v40
	v_rcp_f32_e32 v33, v33
	v_rcp_f32_e32 v35, v35
	v_rcp_f32_e32 v47, v47
	v_rcp_f32_e32 v40, v40
	v_bfe_u32 v56, v32, 16, 1
	v_bfe_u32 v57, v46, 16, 1
	v_bfe_u32 v77, v41, 16, 1
	v_bfe_u32 v86, v34, 16, 1
	v_add3_u32 v86, v34, v86, s77
	v_add3_u32 v41, v41, v77, s77
	v_add3_u32 v34, v46, v57, s77
	v_add3_u32 v32, v32, v56, s77
	v_bfe_u32 v46, v35, 16, 1
	v_bfe_u32 v56, v40, 16, 1
	v_bfe_u32 v57, v33, 16, 1
	v_bfe_u32 v77, v47, 16, 1
	v_add3_u32 v40, v40, v56, s77
	v_add3_u32 v35, v35, v46, s77
	v_add3_u32 v46, v47, v77, s77
	v_add3_u32 v33, v33, v57, s77
	v_lshrrev_b32_e32 v47, 16, v35
	v_lshrrev_b32_e32 v35, 16, v40
	v_lshrrev_b32_e32 v40, 16, v33
	v_lshrrev_b32_e32 v33, 16, v46
	v_and_or_b32 v34, v34, s76, v33
	v_and_or_b32 v33, v41, s76, v47
	v_and_or_b32 v35, v32, s76, v35
	v_and_or_b32 v32, v86, s76, v40
	s_waitcnt vmcnt(6)
	v_pk_mul_f32 v[46:47], v[68:69], v[62:63] op_sel_hi:[0,1]
	v_pk_mul_f32 v[40:41], v[68:69], v[64:65] op_sel_hi:[0,1]
	s_waitcnt vmcnt(4)
	v_pk_mul_f32 v[62:63], v[66:67], v[82:83] op_sel_hi:[0,1]
	v_mov_b32_e32 v82, v46
	s_waitcnt vmcnt(3)
	v_lshlrev_b32_e32 v65, 16, v52
	s_waitcnt vmcnt(2)
	v_lshlrev_b32_e32 v64, 16, v48
	v_mov_b32_e32 v83, v62
	v_lshlrev_b32_e32 v77, 16, v36
	v_pk_mul_f32 v[64:65], v[82:83], v[64:65]
	v_mov_b32_e32 v62, v47
	s_waitcnt vmcnt(0)
	v_fma_f32 v46, v104, v77, v64
	v_add_f32_e32 v77, v46, v65
	v_and_b32_e32 v65, 0xffff0000, v52
	v_and_b32_e32 v64, 0xffff0000, v48
	v_and_b32_e32 v36, 0xffff0000, v36
	v_pk_mul_f32 v[46:47], v[62:63], v[64:65]
	v_pk_mul_f32 v[56:57], v[66:67], v[84:85] op_sel_hi:[0,1]
	v_fma_f32 v36, v105, v36, v46
	v_add_f32_e32 v88, v36, v47
	v_lshlrev_b32_e32 v47, 16, v53
	v_lshlrev_b32_e32 v46, 16, v49
	v_mov_b32_e32 v62, v40
	v_mov_b32_e32 v63, v56
	v_lshlrev_b32_e32 v36, 16, v37
	v_pk_mul_f32 v[46:47], v[62:63], v[46:47]
	v_and_b32_e32 v40, 0xffff0000, v37
	v_fma_f32 v36, v106, v36, v46
	v_add_f32_e32 v116, v36, v47
	v_and_b32_e32 v37, 0xffff0000, v53
	v_and_b32_e32 v36, 0xffff0000, v49
	v_mov_b32_e32 v56, v41
	v_pk_mul_f32 v[36:37], v[56:57], v[36:37]
	v_pk_mul_f32 v[46:47], v[66:67], v[78:79] op_sel_hi:[0,1]
	v_fma_f32 v36, v107, v40, v36
	v_pk_mul_f32 v[40:41], v[68:69], v[58:59] op_sel_hi:[0,1]
	v_lshlrev_b32_e32 v49, 16, v54
	v_lshlrev_b32_e32 v48, 16, v50
	v_mov_b32_e32 v56, v40
	v_mov_b32_e32 v57, v46
	v_lshlrev_b32_e32 v58, 16, v38
	v_pk_mul_f32 v[48:49], v[56:57], v[48:49]
	v_mov_b32_e32 v46, v41
	v_fma_f32 v40, v42, v58, v48
	v_add_f32_e32 v118, v40, v49
	v_and_b32_e32 v49, 0xffff0000, v54
	v_and_b32_e32 v48, 0xffff0000, v50
	v_pk_mul_f32 v[40:41], v[46:47], v[48:49]
	v_add_u32_e32 v46, 0xa40, v76
	v_and_b32_e32 v38, 0xffff0000, v38
	v_ashrrev_i32_e32 v47, 31, v46
	v_fma_f32 v38, v43, v38, v40
	v_lshlrev_b64 v[48:49], 1, v[46:47]
	v_lshlrev_b64 v[46:47], 2, v[46:47]
	v_add_f32_e32 v50, v38, v41
	v_lshl_add_u64 v[40:41], v[74:75], 0, v[48:49]
	v_lshl_add_u64 v[56:57], s[38:39], 0, v[46:47]
	v_pk_mul_f32 v[52:53], v[66:67], v[80:81] op_sel_hi:[0,1]
	global_load_dwordx4 v[40:43], v[40:41], off
	v_lshl_add_u64 v[58:59], s[10:11], 0, v[46:47]
	global_load_dwordx4 v[78:81], v[56:57], off offset:16
	global_load_dwordx4 v[82:85], v[56:57], off
	global_load_dwordx4 v[104:107], v[58:59], off offset:16
	global_load_dwordx4 v[108:111], v[58:59], off
	v_lshl_add_u64 v[56:57], v[70:71], 0, v[48:49]
	v_lshl_add_u64 v[48:49], v[72:73], 0, v[48:49]
	v_add_f32_e32 v117, v36, v37
	v_pk_mul_f32 v[36:37], v[68:69], v[60:61] op_sel_hi:[0,1]
	global_load_dwordx4 v[60:63], v[48:49], off
	s_nop 0
; __device__ __forceinline__ unsigned pk2(float lo, float hi) { return f2bf(lo) | (f2bf(hi) << 16); }
; __device__ __forceinline__ float sigmoid_f(float x) { return __builtin_amdgcn_rcpf(1.f + __expf(-x)); }
; __device__ __forceinline__ float tanh_f(float x) { const float e = __expf(2.f * x); return 1.f - 2.f * __builtin_amdgcn_rcpf(e + 1.f); }
; __device__ __forceinline__ void rwkv_proj_phase(const bf16* Z, const float* shift, const float* w0, const float* a0, const float* kkp, const float* kap, const float* rkp, ...
;     ...
;         for (int ks = 0; ks < 12; ++ks) {
;             const int col = 2304 + 32 * ks + 8 * g;
;             const u32x4 c0 = *(const u32x4*)(zr + col), cm = *(const u32x4*)(zr + offm + col), cp = *(const u32x4*)(zr + offp + col);
;             float val[8];
; #pragma unroll
;             for (int q = 0; q < 2; ++q) { const f32x4 t0 = *(const f32x4*)(shift + col + 4 * q) * fm, t1 = *(const f32x4*)(shift + BCOLS + col + 4 * q), t2 = *(const f32x4*)(shift + 2 * BCOLS + col + 4 * q) * fn;
;                 const unsigned m0 = q ? cm.z : cm.x, m1 = q ? cm.w : cm.y, z0 = q ? c0.z : c0.x, z1 = q ? c0.w : c0.y, p0 = q ? cp.z : cp.x, p1 = q ? cp.w : cp.y;
;                 val[4 * q + 0] = t0.x * bflo(m0) + t1.x * bflo(z0) + t2.x * bflo(p0);
;                 val[4 * q + 1] = t0.y * bfhi(m0) + t1.y * bfhi(z0) + t2.y * bfhi(p0);
;                 val[4 * q + 2] = t0.z * bflo(m1) + t1.z * bflo(z1) + t2.z * bflo(p1);
;                 val[4 * q + 3] = t0.w * bfhi(m1) + t1.w * bfhi(z1) + t2.w * bfhi(p1); }
; #pragma unroll
;             for (int e = 0; e < 8; ++e) { if (ks < 4) val[e] = tanh_f(val[e]); else if (ks >= 8) val[e] = sigmoid_f(val[e]); }
;             u32x4 pk; pk.x = pk2(val[0], val[1]); pk.y = pk2(val[2], val[3]); pk.z = pk2(val[4], val[5]); pk.w = pk2(val[6], val[7]);
;             xf[ks] = __builtin_bit_cast(bf16x8, pk);
;             if (ks & 1) asm volatile("" ::: "memory");
	global_load_dwordx4 v[56:59], v[56:57], off
	v_lshl_add_u64 v[86:87], s[8:9], 0, v[46:47]
	global_load_dwordx4 v[46:49], v[86:87], off offset:16
	global_load_dwordx4 v[112:115], v[86:87], off
	v_lshlrev_b32_e32 v65, 16, v55
	v_lshlrev_b32_e32 v64, 16, v51
	v_mov_b32_e32 v86, v36
	v_mov_b32_e32 v87, v52
	v_lshlrev_b32_e32 v38, 16, v39
	v_pk_mul_f32 v[64:65], v[86:87], v[64:65]
	v_and_b32_e32 v54, 0xffff0000, v39
	v_fma_f32 v36, v44, v38, v64
	v_add_f32_e32 v44, v36, v65
	v_and_b32_e32 v39, 0xffff0000, v55
	v_and_b32_e32 v38, 0xffff0000, v51
	v_mov_b32_e32 v52, v37
	v_mul_f32_e32 v36, 0xbfb8aa3b, v77
	v_exp_f32_e32 v51, v36
	v_pk_mul_f32 v[36:37], v[52:53], v[38:39]
	v_mul_f32_e32 v38, 0xbfb8aa3b, v88
	v_fma_f32 v36, v45, v54, v36
	v_add_f32_e32 v36, v36, v37
	v_mul_f32_e32 v45, 0xbfb8aa3b, v117
	v_mul_f32_e32 v50, 0xbfb8aa3b, v50
	v_mul_f32_e32 v36, 0xbfb8aa3b, v36
	v_add_f32_e32 v37, 1.0, v51
	v_exp_f32_e32 v38, v38
	v_mul_f32_e32 v39, 0xbfb8aa3b, v116
	v_exp_f32_e32 v45, v45
	v_mul_f32_e32 v51, 0xbfb8aa3b, v118
	v_exp_f32_e32 v50, v50
	v_exp_f32_e32 v36, v36
	v_mul_f32_e32 v44, 0xbfb8aa3b, v44
	v_exp_f32_e32 v39, v39
	v_exp_f32_e32 v51, v51
	v_exp_f32_e32 v44, v44
	v_add_f32_e32 v38, 1.0, v38
	v_add_f32_e32 v45, 1.0, v45
	v_add_f32_e32 v50, 1.0, v50
	v_add_f32_e32 v36, 1.0, v36
	v_rcp_f32_e32 v38, v38
	v_add_f32_e32 v39, 1.0, v39
	v_rcp_f32_e32 v45, v45
	v_add_f32_e32 v51, 1.0, v51
	v_rcp_f32_e32 v36, v36
	v_rcp_f32_e32 v50, v50
	v_add_f32_e32 v44, 1.0, v44
	v_rcp_f32_e32 v37, v37
	v_rcp_f32_e32 v39, v39
	v_rcp_f32_e32 v51, v51
	v_rcp_f32_e32 v44, v44
	v_bfe_u32 v52, v36, 16, 1
	v_bfe_u32 v53, v50, 16, 1
	v_bfe_u32 v54, v45, 16, 1
	v_bfe_u32 v55, v38, 16, 1
	v_add3_u32 v55, v38, v55, s77
	v_add3_u32 v45, v45, v54, s77
	v_add3_u32 v38, v50, v53, s77
	v_add3_u32 v36, v36, v52, s77
	v_bfe_u32 v50, v39, 16, 1
	v_bfe_u32 v52, v44, 16, 1
	v_bfe_u32 v53, v37, 16, 1
	v_bfe_u32 v54, v51, 16, 1
	v_add3_u32 v44, v44, v52, s77
	v_add3_u32 v39, v39, v50, s77
	v_add3_u32 v50, v51, v54, s77
	v_add3_u32 v37, v37, v53, s77
	v_lshrrev_b32_e32 v51, 16, v39
	v_lshrrev_b32_e32 v39, 16, v44
	v_lshrrev_b32_e32 v44, 16, v37
	v_lshrrev_b32_e32 v37, 16, v50
	v_and_or_b32 v39, v36, s76, v39
	v_and_or_b32 v38, v38, s76, v37
	v_and_or_b32 v37, v45, s76, v51
	v_and_or_b32 v36, v55, s76, v44
	s_waitcnt vmcnt(6)
	v_pk_mul_f32 v[50:51], v[68:69], v[82:83] op_sel_hi:[0,1]
	s_waitcnt vmcnt(4)
	v_pk_mul_f32 v[54:55], v[66:67], v[108:109] op_sel_hi:[0,1]
	v_mov_b32_e32 v82, v50
	v_mov_b32_e32 v83, v54
	v_lshlrev_b32_e32 v77, 16, v40
	s_waitcnt vmcnt(3)
	v_lshlrev_b32_e32 v65, 16, v60
	s_waitcnt vmcnt(2)
	v_lshlrev_b32_e32 v64, 16, v56
	v_pk_mul_f32 v[64:65], v[82:83], v[64:65]
	v_mov_b32_e32 v54, v51
	s_waitcnt vmcnt(0)
	v_fma_f32 v50, v112, v77, v64
	v_add_f32_e32 v88, v50, v65
	v_and_b32_e32 v65, 0xffff0000, v60
	v_and_b32_e32 v64, 0xffff0000, v56
	v_and_b32_e32 v40, 0xffff0000, v40
	v_pk_mul_f32 v[50:51], v[54:55], v[64:65]
	v_pk_mul_f32 v[44:45], v[68:69], v[84:85] op_sel_hi:[0,1]
	v_pk_mul_f32 v[52:53], v[66:67], v[110:111] op_sel_hi:[0,1]
	v_fma_f32 v40, v113, v40, v50
	v_add_f32_e32 v112, v40, v51
	v_lshlrev_b32_e32 v51, 16, v61
	v_lshlrev_b32_e32 v50, 16, v57
	v_mov_b32_e32 v54, v44
	v_mov_b32_e32 v55, v52
	v_lshlrev_b32_e32 v40, 16, v41
	v_pk_mul_f32 v[50:51], v[54:55], v[50:51]
	v_and_b32_e32 v44, 0xffff0000, v41
	v_fma_f32 v40, v114, v40, v50
	v_add_f32_e32 v113, v40, v51
	v_and_b32_e32 v41, 0xffff0000, v61
	v_and_b32_e32 v40, 0xffff0000, v57
	v_mov_b32_e32 v52, v45
	v_pk_mul_f32 v[40:41], v[52:53], v[40:41]
	v_pk_mul_f32 v[50:51], v[66:67], v[104:105] op_sel_hi:[0,1]
	v_fma_f32 v40, v115, v44, v40
	v_pk_mul_f32 v[44:45], v[68:69], v[78:79] op_sel_hi:[0,1]
	v_lshlrev_b32_e32 v53, 16, v62
	v_lshlrev_b32_e32 v52, 16, v58
	v_mov_b32_e32 v54, v44
	v_mov_b32_e32 v55, v50
	v_lshlrev_b32_e32 v56, 16, v42
	v_pk_mul_f32 v[52:53], v[54:55], v[52:53]
	v_mov_b32_e32 v50, v45
	v_fma_f32 v44, v46, v56, v52
	v_add_f32_e32 v115, v44, v53
	v_and_b32_e32 v53, 0xffff0000, v62
	v_and_b32_e32 v52, 0xffff0000, v58
	v_pk_mul_f32 v[44:45], v[50:51], v[52:53]
	v_add_u32_e32 v50, 0xa60, v76
	v_and_b32_e32 v42, 0xffff0000, v42
	v_ashrrev_i32_e32 v51, 31, v50
	v_fma_f32 v42, v47, v42, v44
	v_lshlrev_b64 v[64:65], 1, v[50:51]
	v_lshlrev_b64 v[86:87], 2, v[50:51]
	v_add_f32_e32 v58, v42, v45
	v_lshl_add_u64 v[44:45], v[74:75], 0, v[64:65]
	v_lshl_add_u64 v[54:55], s[38:39], 0, v[86:87]
	v_lshl_add_u64 v[78:79], s[10:11], 0, v[86:87]
	v_add_f32_e32 v114, v40, v41
	v_pk_mul_f32 v[40:41], v[68:69], v[80:81] op_sel_hi:[0,1]
	global_load_dwordx4 v[44:47], v[44:45], off
	s_nop 0
	global_load_dwordx4 v[50:53], v[54:55], off offset:16
	s_nop 0
	global_load_dwordx4 v[54:57], v[54:55], off
	s_nop 0
	global_load_dwordx4 v[74:77], v[78:79], off offset:16
	s_nop 0
	global_load_dwordx4 v[78:81], v[78:79], off
	v_lshl_add_u64 v[82:83], v[70:71], 0, v[64:65]
	v_lshl_add_u64 v[64:65], v[72:73], 0, v[64:65]
	global_load_dwordx4 v[70:73], v[64:65], off
	s_nop 0
	global_load_dwordx4 v[82:85], v[82:83], off
	v_lshl_add_u64 v[86:87], s[8:9], 0, v[86:87]
	v_pk_mul_f32 v[60:61], v[66:67], v[106:107] op_sel_hi:[0,1]
	global_load_dwordx4 v[104:107], v[86:87], off offset:16
	global_load_dwordx4 v[108:111], v[86:87], off
	v_lshlrev_b32_e32 v65, 16, v63
	v_lshlrev_b32_e32 v64, 16, v59
	v_mov_b32_e32 v86, v40
	v_mov_b32_e32 v87, v60
	v_lshlrev_b32_e32 v42, 16, v43
	v_pk_mul_f32 v[64:65], v[86:87], v[64:65]
	v_and_b32_e32 v62, 0xffff0000, v43
	v_fma_f32 v40, v48, v42, v64
	v_add_f32_e32 v48, v40, v65
	v_and_b32_e32 v43, 0xffff0000, v63
	v_and_b32_e32 v42, 0xffff0000, v59
	v_mov_b32_e32 v60, v41
	v_mul_f32_e32 v40, 0xbfb8aa3b, v88
; __device__ __forceinline__ unsigned pk2(float lo, float hi) { return f2bf(lo) | (f2bf(hi) << 16); }
; __device__ __forceinline__ float sigmoid_f(float x) { return __builtin_amdgcn_rcpf(1.f + __expf(-x)); }
; __device__ __forceinline__ float tanh_f(float x) { const float e = __expf(2.f * x); return 1.f - 2.f * __builtin_amdgcn_rcpf(e + 1.f); }
; __device__ __forceinline__ void rwkv_proj_phase(const bf16* Z, const float* shift, const float* w0, const float* a0, const float* kkp, const float* kap, const float* rkp, ...
;     ...
;         for (int ks = 0; ks < 12; ++ks) {
;             const int col = 2304 + 32 * ks + 8 * g;
;             const u32x4 c0 = *(const u32x4*)(zr + col), cm = *(const u32x4*)(zr + offm + col), cp = *(const u32x4*)(zr + offp + col);
;             float val[8];
; #pragma unroll
;             for (int q = 0; q < 2; ++q) { const f32x4 t0 = *(const f32x4*)(shift + col + 4 * q) * fm, t1 = *(const f32x4*)(shift + BCOLS + col + 4 * q), t2 = *(const f32x4*)(shift + 2 * BCOLS + col + 4 * q) * fn;
;                 const unsigned m0 = q ? cm.z : cm.x, m1 = q ? cm.w : cm.y, z0 = q ? c0.z : c0.x, z1 = q ? c0.w : c0.y, p0 = q ? cp.z : cp.x, p1 = q ? cp.w : cp.y;
;                 val[4 * q + 0] = t0.x * bflo(m0) + t1.x * bflo(z0) + t2.x * bflo(p0);
;                 val[4 * q + 1] = t0.y * bfhi(m0) + t1.y * bfhi(z0) + t2.y * bfhi(p0);
;                 val[4 * q + 2] = t0.z * bflo(m1) + t1.z * bflo(z1) + t2.z * bflo(p1);
;                 val[4 * q + 3] = t0.w * bfhi(m1) + t1.w * bfhi(z1) + t2.w * bfhi(p1); }
; #pragma unroll
;             for (int e = 0; e < 8; ++e) { if (ks < 4) val[e] = tanh_f(val[e]); else if (ks >= 8) val[e] = sigmoid_f(val[e]); }
;             u32x4 pk; pk.x = pk2(val[0], val[1]); pk.y = pk2(val[2], val[3]); pk.z = pk2(val[4], val[5]); pk.w = pk2(val[6], val[7]);
;             xf[ks] = __builtin_bit_cast(bf16x8, pk);
;             if (ks & 1) asm volatile("" ::: "memory");
	v_exp_f32_e32 v59, v40
	v_pk_mul_f32 v[40:41], v[60:61], v[42:43]
	v_mul_f32_e32 v42, 0xbfb8aa3b, v112
	v_fma_f32 v40, v49, v62, v40
	v_add_f32_e32 v40, v40, v41
	v_mul_f32_e32 v49, 0xbfb8aa3b, v114
	v_mul_f32_e32 v58, 0xbfb8aa3b, v58
	v_mul_f32_e32 v40, 0xbfb8aa3b, v40
	v_add_f32_e32 v41, 1.0, v59
	v_exp_f32_e32 v42, v42
	v_mul_f32_e32 v43, 0xbfb8aa3b, v113
	v_exp_f32_e32 v49, v49
	v_mul_f32_e32 v59, 0xbfb8aa3b, v115
	v_exp_f32_e32 v58, v58
	v_exp_f32_e32 v40, v40
	v_mul_f32_e32 v48, 0xbfb8aa3b, v48
	v_exp_f32_e32 v43, v43
	v_exp_f32_e32 v59, v59
	v_exp_f32_e32 v48, v48
	v_add_f32_e32 v42, 1.0, v42
	v_add_f32_e32 v49, 1.0, v49
	v_add_f32_e32 v58, 1.0, v58
	v_add_f32_e32 v40, 1.0, v40
	v_rcp_f32_e32 v42, v42
	v_add_f32_e32 v43, 1.0, v43
	v_rcp_f32_e32 v49, v49
	v_add_f32_e32 v59, 1.0, v59
	v_rcp_f32_e32 v40, v40
	v_rcp_f32_e32 v58, v58
	v_add_f32_e32 v48, 1.0, v48
	v_rcp_f32_e32 v41, v41
	v_rcp_f32_e32 v43, v43
	v_rcp_f32_e32 v59, v59
	v_rcp_f32_e32 v48, v48
	v_bfe_u32 v60, v40, 16, 1
	v_bfe_u32 v61, v58, 16, 1
	v_bfe_u32 v62, v49, 16, 1
	v_bfe_u32 v63, v42, 16, 1
	v_add3_u32 v63, v42, v63, s77
	v_add3_u32 v49, v49, v62, s77
	v_add3_u32 v42, v58, v61, s77
	v_add3_u32 v40, v40, v60, s77
	v_bfe_u32 v58, v43, 16, 1
	v_bfe_u32 v60, v48, 16, 1
	v_bfe_u32 v61, v41, 16, 1
	v_bfe_u32 v62, v59, 16, 1
	v_add3_u32 v48, v48, v60, s77
	v_add3_u32 v43, v43, v58, s77
	v_add3_u32 v58, v59, v62, s77
	v_add3_u32 v41, v41, v61, s77
	v_lshrrev_b32_e32 v59, 16, v43
	v_lshrrev_b32_e32 v43, 16, v48
	v_lshrrev_b32_e32 v48, 16, v41
	v_lshrrev_b32_e32 v41, 16, v58
	v_and_or_b32 v42, v42, s76, v41
	v_and_or_b32 v41, v49, s76, v59
	v_and_or_b32 v43, v40, s76, v43
	v_and_or_b32 v40, v63, s76, v48
	s_waitcnt vmcnt(6)
	v_pk_mul_f32 v[54:55], v[68:69], v[54:55] op_sel_hi:[0,1]
	v_mov_b32_e32 v62, v54
	s_waitcnt vmcnt(4)
	v_pk_mul_f32 v[58:59], v[66:67], v[78:79] op_sel_hi:[0,1]
	v_mov_b32_e32 v63, v58
	s_waitcnt vmcnt(3)
	v_lshlrev_b32_e32 v61, 16, v70
	s_waitcnt vmcnt(2)
	v_lshlrev_b32_e32 v60, 16, v82
	v_lshlrev_b32_e32 v64, 16, v44
	v_pk_mul_f32 v[60:61], v[62:63], v[60:61]
	v_mov_b32_e32 v58, v55
	s_waitcnt vmcnt(0)
	v_fma_f32 v54, v108, v64, v60
	v_add_f32_e32 v62, v54, v61
	v_and_b32_e32 v61, 0xffff0000, v70
	v_and_b32_e32 v60, 0xffff0000, v82
	v_and_b32_e32 v44, 0xffff0000, v44
	v_pk_mul_f32 v[54:55], v[58:59], v[60:61]
	v_pk_mul_f32 v[48:49], v[68:69], v[56:57] op_sel_hi:[0,1]
	v_pk_mul_f32 v[56:57], v[66:67], v[80:81] op_sel_hi:[0,1]
	v_fma_f32 v44, v109, v44, v54
	v_add_f32_e32 v60, v44, v55
	v_lshlrev_b32_e32 v55, 16, v71
	v_lshlrev_b32_e32 v54, 16, v83
	v_mov_b32_e32 v58, v48
	v_mov_b32_e32 v59, v56
	v_lshlrev_b32_e32 v44, 16, v45
	v_pk_mul_f32 v[54:55], v[58:59], v[54:55]
	v_and_b32_e32 v48, 0xffff0000, v45
	v_fma_f32 v44, v110, v44, v54
	v_add_f32_e32 v58, v44, v55
	v_and_b32_e32 v45, 0xffff0000, v71
	v_and_b32_e32 v44, 0xffff0000, v83
	v_mov_b32_e32 v56, v49
	v_pk_mul_f32 v[44:45], v[56:57], v[44:45]
	v_lshlrev_b32_e32 v55, 16, v72
	v_fma_f32 v44, v111, v48, v44
	v_add_f32_e32 v59, v44, v45
	v_pk_mul_f32 v[44:45], v[68:69], v[52:53] op_sel_hi:[0,1]
	v_pk_mul_f32 v[48:49], v[68:69], v[50:51] op_sel_hi:[0,1]
	v_pk_mul_f32 v[52:53], v[66:67], v[74:75] op_sel_hi:[0,1]
	v_lshlrev_b32_e32 v54, 16, v84
	v_mov_b32_e32 v56, v48
	v_mov_b32_e32 v57, v52
	v_lshlrev_b32_e32 v61, 16, v46
	v_pk_mul_f32 v[54:55], v[56:57], v[54:55]
	v_mov_b32_e32 v52, v49
	v_fma_f32 v48, v104, v61, v54
	v_add_f32_e32 v56, v48, v55
	v_and_b32_e32 v55, 0xffff0000, v72
	v_and_b32_e32 v54, 0xffff0000, v84
	v_and_b32_e32 v46, 0xffff0000, v46
	v_pk_mul_f32 v[48:49], v[52:53], v[54:55]
	v_pk_mul_f32 v[50:51], v[66:67], v[76:77] op_sel_hi:[0,1]
	v_fma_f32 v46, v105, v46, v48
	v_add_f32_e32 v54, v46, v49
	v_lshlrev_b32_e32 v49, 16, v73
	v_lshlrev_b32_e32 v48, 16, v85
	v_mov_b32_e32 v52, v44
	v_mov_b32_e32 v53, v50
	v_lshlrev_b32_e32 v46, 16, v47
	v_pk_mul_f32 v[48:49], v[52:53], v[48:49]
	v_mov_b32_e32 v50, v45
	v_fma_f32 v44, v106, v46, v48
	v_add_f32_e32 v48, v44, v49
	v_and_b32_e32 v49, 0xffff0000, v47
	v_and_b32_e32 v47, 0xffff0000, v73
	v_and_b32_e32 v46, 0xffff0000, v85
	v_mul_f32_e32 v44, 0xbfb8aa3b, v62
	v_exp_f32_e32 v52, v44
	v_pk_mul_f32 v[44:45], v[50:51], v[46:47]
	v_mul_f32_e32 v46, 0xbfb8aa3b, v60
	v_fma_f32 v44, v107, v49, v44
	v_add_f32_e32 v44, v44, v45
	v_mul_f32_e32 v49, 0xbfb8aa3b, v59
	v_mul_f32_e32 v51, 0xbfb8aa3b, v54
	v_mul_f32_e32 v44, 0xbfb8aa3b, v44
	v_exp_f32_e32 v46, v46
	v_mul_f32_e32 v47, 0xbfb8aa3b, v58
	v_exp_f32_e32 v49, v49
	v_mul_f32_e32 v50, 0xbfb8aa3b, v56
	v_exp_f32_e32 v51, v51
	v_exp_f32_e32 v44, v44
	v_mul_f32_e32 v48, 0xbfb8aa3b, v48
	v_exp_f32_e32 v47, v47
	v_exp_f32_e32 v50, v50
	v_exp_f32_e32 v48, v48
	v_add_f32_e32 v46, 1.0, v46
	v_add_f32_e32 v49, 1.0, v49
	v_add_f32_e32 v51, 1.0, v51
	v_add_f32_e32 v44, 1.0, v44
	v_add_f32_e32 v45, 1.0, v52
	v_rcp_f32_e32 v46, v46
	v_add_f32_e32 v47, 1.0, v47
	v_rcp_f32_e32 v49, v49
	v_add_f32_e32 v50, 1.0, v50
	v_rcp_f32_e32 v44, v44
	v_rcp_f32_e32 v51, v51
	v_add_f32_e32 v48, 1.0, v48
	v_rcp_f32_e32 v45, v45
	v_rcp_f32_e32 v47, v47
	v_rcp_f32_e32 v50, v50
	v_rcp_f32_e32 v48, v48
	v_bfe_u32 v52, v44, 16, 1
	v_bfe_u32 v53, v51, 16, 1
	v_bfe_u32 v54, v49, 16, 1
	v_bfe_u32 v55, v46, 16, 1
	v_add3_u32 v55, v46, v55, s77
	v_add3_u32 v49, v49, v54, s77
	v_add3_u32 v46, v51, v53, s77
	v_add3_u32 v44, v44, v52, s77
	v_bfe_u32 v51, v47, 16, 1
	v_bfe_u32 v52, v48, 16, 1
	v_bfe_u32 v53, v45, 16, 1
	v_bfe_u32 v54, v50, 16, 1
	v_add3_u32 v48, v48, v52, s77
	v_add3_u32 v47, v47, v51, s77
	v_add3_u32 v50, v50, v54, s77
	v_add3_u32 v45, v45, v53, s77
	v_lshrrev_b32_e32 v51, 16, v47
	v_lshrrev_b32_e32 v47, 16, v48
	v_lshrrev_b32_e32 v48, 16, v45
	v_lshrrev_b32_e32 v45, 16, v50
	v_and_or_b32 v47, v44, s76, v47
	v_and_or_b32 v46, v46, s76, v45
	v_and_or_b32 v45, v49, s76, v51
	v_and_or_b32 v44, v55, s76, v48
	v_mad_i64_i32 v[104:105], s[0:1], v67, s78, v[98:99]
	v_mad_i64_i32 v[106:107], s[0:1], v67, s78, v[100:101]

; #define LAS __attribute__((address_space(3)))
; __device__ __forceinline__ unsigned pk2(float lo, float hi) { return f2bf(lo) | (f2bf(hi) << 16); }
; __device__ __forceinline__ void rwkv_proj_phase(const bf16* Z, const float* shift, const float* w0, const float* a0, const float* kkp, const float* kap, const float* rkp, ...
;     ...
;                 for (int i = 0; i < 6; ++i) { const int cid = tid + 512 * i, tok = cid / 24, ch = cid % 24, wh = ch >> 3, col = wh * BW + h * 64 + (ch & 7) * 8;
;                     const int mm = tt * 128 + tok; int tp, ln; if (mm < ML) { tp = mm & 8191; ln = SEQ; } else { tp = (mm - ML) & 255; ln = CTXL; }
;                     const bool hp_ = tp > 0, hn_ = tp < ln - 1; const float fm_ = hp_ ? 1.f : 0.f, fn_ = hn_ ? 1.f : 0.f;
;                     const bf16* zz = Z + (size_t)mm * INCP + ZB0 + col;
;                     const u32x4 c0 = *(const u32x4*)zz, cm = *(const u32x4*)(zz - (hp_ ? INCP : 0)), cp = *(const u32x4*)(zz + (hn_ ? INCP : 0));
;                     float val[8];
; #pragma unroll
;                     for (int qq = 0; qq < 2; ++qq) { const f32x4 t0 = *(const f32x4*)(shift + col + 4 * qq) * fm_, t1 = *(const f32x4*)(shift + BCOLS + col + 4 * qq), t2 = *(const f32x4*)(shift + 2 * BCOLS + col + 4 * qq) * fn_;
;                         const unsigned m0 = qq ? cm.z : cm.x, m1 = qq ? cm.w : cm.y, z0 = qq ? c0.z : c0.x, z1 = qq ? c0.w : c0.y, p0 = qq ? cp.z : cp.x, p1 = qq ? cp.w : cp.y;
;                         val[4 * qq + 0] = t0.x * bflo(m0) + t1.x * bflo(z0) + t2.x * bflo(p0);
;                         val[4 * qq + 1] = t0.y * bfhi(m0) + t1.y * bfhi(z0) + t2.y * bfhi(p0);
;                         val[4 * qq + 2] = t0.z * bflo(m1) + t1.z * bflo(z1) + t2.z * bflo(p1);
;                         val[4 * qq + 3] = t0.w * bfhi(m1) + t1.w * bfhi(z1) + t2.w * bfhi(p1); }
;                     u32x4 pk; pk.x = pk2(val[0], val[1]); pk.y = pk2(val[2], val[3]); pk.z = pk2(val[4], val[5]); pk.w = pk2(val[6], val[7]);
;                     *(LAS u32x4*)(lds + tok * 400 + ch * 16) = pk; }
.LBB0_264:
	v_add_u32_e32 v112, s28, v174
	v_mul_hi_u32 v48, v112, s79
	v_lshrrev_b32_e32 v113, 4, v48
	v_mul_lo_u32 v48, v113, 24
	v_sub_u32_e32 v114, v112, v48
	v_lshrrev_b32_e32 v48, 3, v114
	v_mul_lo_u32 v48, v48, s60
	v_add_u32_e32 v48, s7, v48
	v_lshlrev_b32_e32 v49, 3, v114
	v_and_or_b32 v60, v49, 56, v48
	v_add_u32_e32 v48, s84, v113
	v_cmp_gt_i32_e32 vcc, s80, v48
	v_mov_b64_e32 v[84:85], s[30:31]
	v_ashrrev_i32_e32 v61, 31, v60
	v_cndmask_b32_e32 v49, v173, v175, vcc
	v_and_b32_e32 v50, v49, v48
	v_cmp_eq_u32_e32 vcc, 0, v50
	v_cmp_eq_u32_e64 s[0:1], v50, v49
	v_mad_i64_i32 v[48:49], s[52:53], v48, s63, v[84:85]
	v_lshl_add_u64 v[56:57], v[60:61], 1, v[48:49]
	v_cndmask_b32_e64 v53, -1, 0, vcc
	v_cndmask_b32_e64 v52, v165, 0, vcc
	v_lshl_add_u64 v[52:53], v[56:57], 0, v[52:53]
	v_cndmask_b32_e64 v88, v166, 0, s[0:1]
	v_lshlrev_b64 v[60:61], 2, v[60:61]
	global_load_dwordx4 v[48:51], v[56:57], off offset:2048
	v_lshl_add_u64 v[64:65], s[38:39], 0, v[60:61]
	global_load_dwordx4 v[52:55], v[52:53], off offset:2048
	v_lshl_add_u64 v[56:57], v[56:57], 0, v[88:89]
	global_load_dwordx4 v[56:59], v[56:57], off offset:2048
	v_lshl_add_u64 v[68:69], s[8:9], 0, v[60:61]
	v_lshl_add_u64 v[76:77], s[10:11], 0, v[60:61]
	global_load_dwordx4 v[60:63], v[64:65], off offset:16
	s_nop 0
	global_load_dwordx4 v[64:67], v[64:65], off
	v_cndmask_b32_e64 v80, 1.0, 0, vcc
	v_cndmask_b32_e64 v82, 1.0, 0, s[0:1]
	s_addk_i32 s28, 0x400
	s_cmpk_eq_i32 s28, 0xc00
	global_load_dwordx4 v[224:227], v[68:69], off offset:16
	global_load_dwordx4 v[228:231], v[68:69], off
	global_load_dwordx4 v[232:235], v[76:77], off offset:16
	global_load_dwordx4 v[236:239], v[76:77], off
	s_waitcnt vmcnt(5)
	v_pk_mul_f32 v[62:63], v[62:63], v[80:81] op_sel_hi:[1,0]
	s_waitcnt vmcnt(4)
	v_pk_mul_f32 v[86:87], v[66:67], v[80:81] op_sel_hi:[1,0]
	v_pk_mul_f32 v[108:109], v[64:65], v[80:81] op_sel_hi:[1,0]
	v_pk_mul_f32 v[60:61], v[60:61], v[80:81] op_sel_hi:[1,0]
	v_lshlrev_b32_e32 v81, 16, v53
	v_lshlrev_b32_e32 v80, 16, v52
	v_and_b32_e32 v53, 0xffff0000, v53
	v_and_b32_e32 v52, 0xffff0000, v52
	s_waitcnt vmcnt(2)
	v_mov_b32_e32 v110, v228
	s_waitcnt vmcnt(1)
	v_pk_mul_f32 v[234:235], v[234:235], v[82:83] op_sel_hi:[1,0]
	s_waitcnt vmcnt(0)
	v_pk_mul_f32 v[238:239], v[238:239], v[82:83] op_sel_hi:[1,0]
	v_pk_mul_f32 v[236:237], v[236:237], v[82:83] op_sel_hi:[1,0]
	v_pk_mul_f32 v[232:233], v[232:233], v[82:83] op_sel_hi:[1,0]
	v_mov_b32_e32 v82, v108
	v_mov_b32_e32 v83, v86
	v_mov_b32_e32 v86, v109
	v_pk_mul_f32 v[80:81], v[82:83], v[80:81]
	v_lshlrev_b32_e32 v83, 16, v49
	v_lshlrev_b32_e32 v82, 16, v48
	v_mov_b32_e32 v111, v230
	v_pk_mul_f32 v[52:53], v[86:87], v[52:53]
	v_and_b32_e32 v49, 0xffff0000, v49
	v_and_b32_e32 v48, 0xffff0000, v48
	v_mov_b32_e32 v230, v229
	v_pk_fma_f32 v[80:81], v[110:111], v[82:83], v[80:81]
	v_mov_b32_e32 v111, v238
	v_pk_fma_f32 v[48:49], v[230:231], v[48:49], v[52:53]
	v_and_b32_e32 v53, 0xffff0000, v57
	v_and_b32_e32 v52, 0xffff0000, v56
	v_mov_b32_e32 v238, v237
	v_lshlrev_b32_e32 v83, 16, v57
	v_lshlrev_b32_e32 v82, 16, v56
	v_pk_fma_f32 v[48:49], v[238:239], v[52:53], v[48:49]
	v_lshlrev_b32_e32 v53, 16, v55
	v_lshlrev_b32_e32 v52, 16, v54
	v_mov_b32_e32 v56, v60
	v_mov_b32_e32 v57, v62
	v_and_b32_e32 v55, 0xffff0000, v55
	v_and_b32_e32 v54, 0xffff0000, v54
	v_mov_b32_e32 v62, v61
	v_pk_mul_f32 v[52:53], v[56:57], v[52:53]
	v_lshlrev_b32_e32 v57, 16, v51
	v_lshlrev_b32_e32 v56, 16, v50
	v_mov_b32_e32 v228, v224
	v_mov_b32_e32 v229, v226
	v_pk_mul_f32 v[54:55], v[62:63], v[54:55]
	v_and_b32_e32 v51, 0xffff0000, v51
	v_and_b32_e32 v50, 0xffff0000, v50
	v_mov_b32_e32 v226, v225
	v_pk_fma_f32 v[52:53], v[228:229], v[56:57], v[52:53]
	v_lshlrev_b32_e32 v57, 16, v59
	v_lshlrev_b32_e32 v56, 16, v58
	v_mov_b32_e32 v228, v232
	v_mov_b32_e32 v229, v234
	v_pk_fma_f32 v[50:51], v[226:227], v[50:51], v[54:55]
	v_and_b32_e32 v55, 0xffff0000, v59
	v_and_b32_e32 v54, 0xffff0000, v58
	v_mov_b32_e32 v234, v233
	v_mov_b32_e32 v110, v236
	v_pk_fma_f32 v[52:53], v[228:229], v[56:57], v[52:53]
	v_pk_fma_f32 v[50:51], v[234:235], v[54:55], v[50:51]
	v_pk_fma_f32 v[80:81], v[110:111], v[82:83], v[80:81]
	v_cvt_pk_bf16_f32 v51, v53, v51
	v_cvt_pk_bf16_f32 v50, v52, v50
	v_mul_lo_u32 v52, v113, s81
	v_lshlrev_b32_e32 v53, 4, v114
	v_cvt_pk_bf16_f32 v49, v81, v49
	v_cvt_pk_bf16_f32 v48, v80, v48
	v_add3_u32 v52, 0, v52, v53
	ds_write_b128 v52, v[48:51]
	v_add_u32_e32 v48, 0x200, v112
	v_mul_hi_u32 v49, v48, s79
	v_lshrrev_b32_e32 v110, 4, v49
	v_mul_lo_u32 v49, v110, 24
	v_sub_u32_e32 v111, v48, v49
	v_lshrrev_b32_e32 v48, 3, v111
	v_mul_lo_u32 v48, v48, s60
	v_add_u32_e32 v48, s7, v48
	v_lshlrev_b32_e32 v49, 3, v111
	v_and_or_b32 v60, v49, 56, v48
	v_add_u32_e32 v48, s84, v110
	v_cmp_gt_i32_e32 vcc, s80, v48
	v_ashrrev_i32_e32 v61, 31, v60
	s_nop 0
	v_cndmask_b32_e32 v49, v173, v175, vcc
	v_and_b32_e32 v50, v49, v48
	v_cmp_eq_u32_e32 vcc, 0, v50
	v_cmp_eq_u32_e64 s[0:1], v50, v49
	v_mad_i64_i32 v[48:49], s[52:53], v48, s63, v[84:85]
	v_lshl_add_u64 v[56:57], v[60:61], 1, v[48:49]
	v_cndmask_b32_e64 v53, -1, 0, vcc
	v_cndmask_b32_e64 v52, v165, 0, vcc
	v_lshl_add_u64 v[52:53], v[56:57], 0, v[52:53]
	v_cndmask_b32_e64 v88, v166, 0, s[0:1]
	v_lshlrev_b64 v[60:61], 2, v[60:61]
	global_load_dwordx4 v[48:51], v[56:57], off offset:2048
	v_lshl_add_u64 v[64:65], s[38:39], 0, v[60:61]
	global_load_dwordx4 v[52:55], v[52:53], off offset:2048
	v_lshl_add_u64 v[56:57], v[56:57], 0, v[88:89]
	global_load_dwordx4 v[56:59], v[56:57], off offset:2048
	v_lshl_add_u64 v[68:69], s[8:9], 0, v[60:61]
	v_lshl_add_u64 v[76:77], s[10:11], 0, v[60:61]
	global_load_dwordx4 v[60:63], v[64:65], off offset:16
	s_nop 0
	global_load_dwordx4 v[64:67], v[64:65], off
	v_cndmask_b32_e64 v80, 1.0, 0, vcc
	v_cndmask_b32_e64 v82, 1.0, 0, s[0:1]
	global_load_dwordx4 v[224:227], v[68:69], off offset:16
	global_load_dwordx4 v[228:231], v[68:69], off
	global_load_dwordx4 v[232:235], v[76:77], off offset:16
	global_load_dwordx4 v[236:239], v[76:77], off
	s_waitcnt vmcnt(5)
; #define LAS __attribute__((address_space(3)))
; __device__ __forceinline__ void rwkv_proj_phase(const bf16* Z, const float* shift, const float* w0, const float* a0, const float* kkp, const float* kap, const float* rkp, ...
;     ...
;                 for (int i = 0; i < 6; ++i) { const int cid = tid + 512 * i, tok = cid / 24, ch = cid % 24, wh = ch >> 3, col = wh * BW + h * 64 + (ch & 7) * 8;
;                     const int mm = tt * 128 + tok; int tp, ln; if (mm < ML) { tp = mm & 8191; ln = SEQ; } else { tp = (mm - ML) & 255; ln = CTXL; }
;                     const bool hp_ = tp > 0, hn_ = tp < ln - 1; const float fm_ = hp_ ? 1.f : 0.f, fn_ = hn_ ? 1.f : 0.f;
;                     const bf16* zz = Z + (size_t)mm * INCP + ZB0 + col;
;                     const u32x4 c0 = *(const u32x4*)zz, cm = *(const u32x4*)(zz - (hp_ ? INCP : 0)), cp = *(const u32x4*)(zz + (hn_ ? INCP : 0));
;                     float val[8];
; #pragma unroll
;                     for (int qq = 0; qq < 2; ++qq) { const f32x4 t0 = *(const f32x4*)(shift + col + 4 * qq) * fm_, t1 = *(const f32x4*)(shift + BCOLS + col + 4 * qq), t2 = *(const f32x4*)(shift + 2 * BCOLS + col + 4 * qq) * fn_;
;                         const unsigned m0 = qq ? cm.z : cm.x, m1 = qq ? cm.w : cm.y, z0 = qq ? c0.z : c0.x, z1 = qq ? c0.w : c0.y, p0 = qq ? cp.z : cp.x, p1 = qq ? cp.w : cp.y;
;                         val[4 * qq + 0] = t0.x * bflo(m0) + t1.x * bflo(z0) + t2.x * bflo(p0);
;                         val[4 * qq + 1] = t0.y * bfhi(m0) + t1.y * bfhi(z0) + t2.y * bfhi(p0);
;                         val[4 * qq + 2] = t0.z * bflo(m1) + t1.z * bflo(z1) + t2.z * bflo(p1);
;                         val[4 * qq + 3] = t0.w * bfhi(m1) + t1.w * bfhi(z1) + t2.w * bfhi(p1); }
;                     u32x4 pk; pk.x = pk2(val[0], val[1]); pk.y = pk2(val[2], val[3]); pk.z = pk2(val[4], val[5]); pk.w = pk2(val[6], val[7]);
;                     *(LAS u32x4*)(lds + tok * 400 + ch * 16) = pk; }
; #pragma unroll
;                 for (int i = 0; i < 6; ++i) { const int cid = tid + 512 * i;
;                     if (i < 4) { const int cc = cid & 1023, dd = cc >> 9, n = (cc >> 3) & 63, c8 = cc & 7; const bf16* src = ((i < 2) ? w2T : a2T) + ((size_t)(dd * BW + h * 64 + n) * 64 + c8 * 8);
;                         *(LAS u32x4*)(lds + 51200 + ((i < 2) ? 0 : 18432) + (dd * 64 + n) * 144 + c8 * 16) = *(const u32x4*)src; }
	v_pk_mul_f32 v[62:63], v[62:63], v[80:81] op_sel_hi:[1,0]
	s_waitcnt vmcnt(4)
	v_pk_mul_f32 v[84:85], v[66:67], v[80:81] op_sel_hi:[1,0]
	v_pk_mul_f32 v[86:87], v[64:65], v[80:81] op_sel_hi:[1,0]
	v_pk_mul_f32 v[60:61], v[60:61], v[80:81] op_sel_hi:[1,0]
	v_lshlrev_b32_e32 v81, 16, v53
	v_lshlrev_b32_e32 v80, 16, v52
	v_and_b32_e32 v53, 0xffff0000, v53
	v_and_b32_e32 v52, 0xffff0000, v52
	s_waitcnt vmcnt(2)
	v_mov_b32_e32 v108, v228
	s_waitcnt vmcnt(1)
	v_pk_mul_f32 v[234:235], v[234:235], v[82:83] op_sel_hi:[1,0]
	s_waitcnt vmcnt(0)
	v_pk_mul_f32 v[238:239], v[238:239], v[82:83] op_sel_hi:[1,0]
	v_pk_mul_f32 v[236:237], v[236:237], v[82:83] op_sel_hi:[1,0]
	v_pk_mul_f32 v[232:233], v[232:233], v[82:83] op_sel_hi:[1,0]
	v_mov_b32_e32 v82, v86
	v_mov_b32_e32 v83, v84
	v_mov_b32_e32 v84, v87
	v_pk_mul_f32 v[80:81], v[82:83], v[80:81]
	v_lshlrev_b32_e32 v83, 16, v49
	v_lshlrev_b32_e32 v82, 16, v48
	v_mov_b32_e32 v109, v230
	v_pk_mul_f32 v[52:53], v[84:85], v[52:53]
	v_and_b32_e32 v49, 0xffff0000, v49
	v_and_b32_e32 v48, 0xffff0000, v48
	v_mov_b32_e32 v230, v229
	v_pk_fma_f32 v[80:81], v[108:109], v[82:83], v[80:81]
	v_mov_b32_e32 v109, v238
	v_pk_fma_f32 v[48:49], v[230:231], v[48:49], v[52:53]
	v_and_b32_e32 v53, 0xffff0000, v57
	v_and_b32_e32 v52, 0xffff0000, v56
	v_mov_b32_e32 v238, v237
	v_lshlrev_b32_e32 v83, 16, v57
	v_lshlrev_b32_e32 v82, 16, v56
	v_pk_fma_f32 v[48:49], v[238:239], v[52:53], v[48:49]
	v_lshlrev_b32_e32 v53, 16, v55
	v_lshlrev_b32_e32 v52, 16, v54
	v_mov_b32_e32 v56, v60
	v_mov_b32_e32 v57, v62
	v_and_b32_e32 v55, 0xffff0000, v55
	v_and_b32_e32 v54, 0xffff0000, v54
	v_mov_b32_e32 v62, v61
	v_pk_mul_f32 v[52:53], v[56:57], v[52:53]
	v_lshlrev_b32_e32 v57, 16, v51
	v_lshlrev_b32_e32 v56, 16, v50
	v_mov_b32_e32 v228, v224
	v_mov_b32_e32 v229, v226
	v_pk_mul_f32 v[54:55], v[62:63], v[54:55]
	v_and_b32_e32 v51, 0xffff0000, v51
	v_and_b32_e32 v50, 0xffff0000, v50
	v_mov_b32_e32 v226, v225
	v_pk_fma_f32 v[52:53], v[228:229], v[56:57], v[52:53]
	v_lshlrev_b32_e32 v57, 16, v59
	v_lshlrev_b32_e32 v56, 16, v58
	v_mov_b32_e32 v228, v232
	v_mov_b32_e32 v229, v234
	v_pk_fma_f32 v[50:51], v[226:227], v[50:51], v[54:55]
	v_and_b32_e32 v55, 0xffff0000, v59
	v_and_b32_e32 v54, 0xffff0000, v58
	v_mov_b32_e32 v234, v233
	v_mov_b32_e32 v108, v236
	v_pk_fma_f32 v[52:53], v[228:229], v[56:57], v[52:53]
	v_pk_fma_f32 v[50:51], v[234:235], v[54:55], v[50:51]
	v_bfe_u32 v56, v49, 16, 1
	v_bfe_u32 v57, v48, 16, 1
	v_pk_fma_f32 v[80:81], v[108:109], v[82:83], v[80:81]
	v_bfe_u32 v54, v51, 16, 1
	v_bfe_u32 v55, v50, 16, 1
	v_add3_u32 v48, v48, v57, s77
	v_add3_u32 v49, v49, v56, s77
	v_bfe_u32 v56, v52, 16, 1
	v_bfe_u32 v57, v53, 16, 1
	v_add3_u32 v50, v50, v55, s77
	v_add3_u32 v51, v51, v54, s77
	v_bfe_u32 v54, v80, 16, 1
	v_bfe_u32 v55, v81, 16, 1
	v_add3_u32 v53, v53, v57, s77
	v_add3_u32 v52, v52, v56, s77
	v_add3_u32 v55, v81, v55, s77
	v_add3_u32 v54, v80, v54, s77
	v_lshrrev_b32_e32 v52, 16, v52
	v_lshrrev_b32_e32 v53, 16, v53
	v_lshrrev_b32_e32 v54, 16, v54
	v_lshrrev_b32_e32 v55, 16, v55
	v_and_or_b32 v51, v51, s76, v53
	v_and_or_b32 v50, v50, s76, v52
	v_mul_lo_u32 v52, v110, s81
	v_lshlrev_b32_e32 v53, 4, v111
	v_and_or_b32 v49, v49, s76, v55
	v_and_or_b32 v48, v48, s76, v54
	v_add3_u32 v52, 0, v52, v53
	ds_write_b128 v52, v[48:51]
	s_cbranch_scc0 .LBB0_264
	v_or_b32_e32 v50, s7, v160
	v_add_u32_e32 v48, v50, v161
	v_add_u32_e32 v50, v50, v162
	v_or_b32_e32 v64, s7, v163
	v_add_u32_e32 v66, s7, v164
	v_ashrrev_i32_e32 v49, 31, v48
	v_ashrrev_i32_e32 v51, 31, v50
	v_ashrrev_i32_e32 v65, 31, v64
	v_ashrrev_i32_e32 v67, 31, v66
	v_lshlrev_b64 v[56:57], 7, v[48:49]
	v_lshlrev_b64 v[58:59], 7, v[50:51]
	v_lshlrev_b64 v[64:65], 8, v[64:65]
	v_lshlrev_b64 v[66:67], 8, v[66:67]
	v_lshl_add_u64 v[48:49], v[92:93], 0, v[56:57]
	v_lshl_add_u64 v[52:53], v[92:93], 0, v[58:59]
	v_lshl_add_u64 v[56:57], v[94:95], 0, v[56:57]
	v_lshl_add_u64 v[60:61], v[94:95], 0, v[58:59]
	v_lshl_add_u64 v[64:65], v[90:91], 0, v[64:65]
	v_lshl_add_u64 v[68:69], v[90:91], 0, v[66:67]
	global_load_dwordx4 v[48:51], v[48:49], off
	s_nop 0
	global_load_dwordx4 v[52:55], v[52:53], off
	s_nop 0
	global_load_dwordx4 v[56:59], v[56:57], off
	s_nop 0
	global_load_dwordx4 v[60:63], v[60:61], off
	s_nop 0
	global_load_dwordx4 v[64:67], v[64:65], off
	s_nop 0
	global_load_dwordx4 v[68:71], v[68:69], off
	v_lshlrev_b32_e32 v72, 2, v178
	v_add_u32_e32 v120, s7, v72
	v_ashrrev_i32_e32 v121, 31, v120
	v_lshlrev_b64 v[74:75], 2, v[120:121]
	v_lshl_add_u64 v[112:113], s[44:45], 0, v[74:75]
	v_lshl_add_u64 v[110:111], s[40:41], 0, v[74:75]
	v_lshlrev_b32_e32 v184, 4, v178
	s_movk_i32 s0, 0x110
	v_mul_lo_u32 v185, v179, s61
	s_movk_i32 s1, 0x2100
	v_add_u32_e32 v186, s62, v184
	v_add3_u32 v188, 0, v185, v184
	v_readlane_b32 s12, v246, 39
	v_ashrrev_i32_e32 v73, 31, v72
	v_lshl_add_u64 v[118:119], s[50:51], 0, v[74:75]
	v_readlane_b32 s13, v246, 40
	v_readlane_b32 s14, v246, 41
	v_readlane_b32 s15, v246, 42
	v_lshl_add_u64 v[116:117], s[12:13], 0, v[74:75]
	v_add_u32_e32 v189, 0x2d00, v185
	v_lshl_add_u64 v[114:115], s[14:15], 0, v[74:75]
	v_lshlrev_b64 v[120:121], 1, v[120:121]
	s_add_i32 s85, s85, 1
	s_cmp_eq_u32 s85, 4
	v_readlane_b32 s16, v246, 43
	v_readlane_b32 s17, v246, 44
	v_readlane_b32 s18, v246, 45
	v_readlane_b32 s19, v246, 46
	v_readlane_b32 s20, v246, 47
	v_readlane_b32 s21, v246, 48
	v_readlane_b32 s22, v246, 49
	v_readlane_b32 s23, v246, 50
	v_readlane_b32 s24, v246, 51
	v_readlane_b32 s25, v246, 52
	v_readlane_b32 s26, v246, 53
	v_readlane_b32 s27, v246, 54
	s_waitcnt vmcnt(5)
	ds_write_b128 v167, v[48:51] offset:51200
	s_waitcnt vmcnt(4)
	ds_write_b128 v168, v[52:55] offset:51200
	s_waitcnt vmcnt(3)
	ds_write_b128 v169, v[56:59]
	s_waitcnt vmcnt(2)
	ds_write_b128 v170, v[60:63]
	s_waitcnt vmcnt(1)
	ds_write_b128 v171, v[64:67]
	s_waitcnt vmcnt(0)
	ds_write_b128 v172, v[68:71]
	s_waitcnt lgkmcnt(0)
	s_barrier
; #define LAS __attribute__((address_space(3)))
; __device__ __forceinline__ void rwkv_proj_phase(const bf16* Z, const float* shift, const float* w0, const float* a0, const float* kkp, const float* kap, const float* rkp, ...
;     ...
;             const LAS unsigned char* rkv = lds + (wave * 16 + fr) * 400 + 8 * g;
;             f32x4 kc[4]; float ss = 0.f;
; #pragma unroll
;             for (int nb = 0; nb < 4; ++nb) {
;                 const int c = h * 64 + nb * 16 + 4 * g;
;                 kc[nb] = bf4(*(const LAS u32x2*)(rkv + 128 + nb * 32));
;                 const f32x4 t = kc[nb] * *(const f32x4*)(kkp + c);
;                 ss += (t.x * t.x + t.y * t.y) + (t.z * t.z + t.w * t.w);
;             }
;             ss += __shfl_xor(ss, 16); ss += __shfl_xor(ss, 32);
;             const float inv = rsqrtf(fmaxf(ss, 1e-12f));
;             bf16* sp = SOP + ((size_t)((b * NH + h) * SL + s)) * 576 + 4 * g;
;             float bon = 0.f;
; #pragma unroll
;             for (int nb = 0; nb < 4; ++nb) {
;                 const int n = h * 64 + nb * 16 + fr;
;                 f32x4 accw[2], acca[2], accg = (f32x4){0.f, 0.f, 0.f, 0.f};
; #pragma unroll
;                 for (int d = 0; d < 2; ++d) { accw[d] = (f32x4){0.f, 0.f, 0.f, 0.f}; acca[d] = (f32x4){0.f, 0.f, 0.f, 0.f};
; #pragma unroll
;                     for (int ksl = 0; ksl < 2; ++ksl) {
;                         const bf16x8 wf = *(const LAS bf16x8*)(lds + 51200 + (d * 64 + nb * 16 + fr) * 144 + (32 * ksl + 8 * g) * 2);
;                         const bf16x8 af = *(const LAS bf16x8*)(lds + 51200 + 18432 + (d * 64 + nb * 16 + fr) * 144 + (32 * ksl + 8 * g) * 2);
;                         accw[d] = MFMA16(wf, xf[2 * d + ksl], accw[d]);
;                         acca[d] = MFMA16(af, xf[4 + 2 * d + ksl], acca[d]); } }
; #pragma unroll
;                 for (int ksl = 0; ksl < 4; ++ksl) { const bf16x8 gf = *(const LAS bf16x8*)(lds + 51200 + 36864 + (nb * 16 + fr) * 272 + (32 * ksl + 8 * g) * 2); accg = MFMA16(gf, xf[8 + ksl], accg); }
;                 const int c = h * 64 + nb * 16 + 4 * g;
;                 const f32x4 rc = bf4(*(const LAS u32x2*)(rkv + nb * 32)), vc = bf4(*(const LAS u32x2*)(rkv + 256 + nb * 32));
;                 const f32x4 w00 = *(const f32x4*)(w0 + c), w01 = *(const f32x4*)(w0 + BW + c), a00 = *(const f32x4*)(a0 + c), a01 = *(const f32x4*)(a0 + BW + c);
	global_load_dwordx4 v[122:125], v[112:113], off
	global_load_dwordx4 v[126:129], v[112:113], off offset:3072
	global_load_dwordx4 v[130:133], v[110:111], off
	global_load_dwordx4 v[134:137], v[110:111], off offset:3072
	v_and_b32_e32 v51, 64, v176
	v_xor_b32_e32 v53, 16, v176
	v_add_u32_e32 v58, 64, v51
	v_add_u32_e32 v50, s58, v179
	v_xor_b32_e32 v54, 32, v176
	v_add_u32_e32 v55, s6, v180
	v_mul_lo_u32 v56, v179, s0
	v_cmp_lt_i32_e32 vcc, v53, v58
	v_lshlrev_b32_e32 v52, 3, v178
	v_mov_b64_e32 v[48:49], s[4:5]
	s_movk_i32 s6, 0x480
	v_mul_lo_u32 v57, v50, s81
	v_mad_u64_u32 v[50:51], s[0:1], v55, s1, v[102:103]
	v_add_u32_e32 v55, 0x2400, v185
	v_add3_u32 v183, s59, v184, v56
	v_cndmask_b32_e32 v56, v176, v53, vcc
	v_cmp_lt_i32_e32 vcc, v54, v58
	v_add_u32_e32 v66, v186, v185
	v_add3_u32 v187, 0, v57, v52
	v_cndmask_b32_e32 v57, v176, v54, vcc
	v_mad_i64_i32 v[64:65], s[0:1], v50, s6, v[48:49]
	ds_read_b128 v[48:51], v188 offset:51200
	v_add_u32_e32 v67, v186, v55
	v_add3_u32 v68, s62, v55, v184
	ds_read_b128 v[52:55], v66
	v_lshlrev_b32_e32 v182, 2, v56
	v_lshlrev_b32_e32 v181, 2, v57
	ds_read_b128 v[56:59], v188 offset:51264
	ds_read_b128 v[60:63], v188 offset:60416
	v_lshl_add_u64 v[108:109], v[72:73], 1, v[64:65]
	ds_read_b128 v[80:83], v66 offset:64
	ds_read_b128 v[64:67], v67
	ds_read_b128 v[84:87], v188 offset:60480
	ds_read2_b64 v[76:79], v187 offset0:16 offset1:20
	ds_read_b128 v[142:145], v68 offset:64
	global_load_dwordx4 v[190:193], v[118:119], off
	global_load_dwordx4 v[72:75], v[118:119], off offset:64
	s_waitcnt lgkmcnt(8)
	v_mfma_f32_16x16x32_bf16 v[48:51], v[48:51], v[0:3], 0
	s_waitcnt lgkmcnt(7)
	v_mfma_f32_16x16x32_bf16 v[52:55], v[52:55], v[16:19], 0
	s_waitcnt lgkmcnt(5)
	v_mfma_f32_16x16x32_bf16 v[138:141], v[60:63], v[8:11], 0
	s_waitcnt lgkmcnt(3)
	v_mfma_f32_16x16x32_bf16 v[146:149], v[64:67], v[24:27], 0
	ds_read2_b64 v[64:67], v187 offset0:24 offset1:28
	global_load_dwordx4 v[68:71], v[118:119], off offset:128
	global_load_dwordx4 v[60:63], v[118:119], off offset:192
	ds_read_b128 v[194:197], v183
	ds_read_b128 v[198:201], v183 offset:64
	v_mfma_f32_16x16x32_bf16 v[152:155], v[56:59], v[4:7], v[48:51]
	v_mfma_f32_16x16x32_bf16 v[202:205], v[80:83], v[20:23], v[52:55]
	ds_read_b128 v[206:209], v183 offset:128
	ds_read_b128 v[80:83], v183 offset:192
	s_nop 0
	ds_read2_b64 v[52:55], v187 offset1:4
	ds_read2_b64 v[48:51], v187 offset0:32 offset1:36
	s_waitcnt lgkmcnt(1)
	v_and_b32_e32 v222, 0xffff0000, v53
	v_mfma_f32_16x16x32_bf16 v[138:141], v[84:87], v[12:15], v[138:141]
	global_load_dwordx4 v[84:87], v[116:117], off
	global_load_dwordx4 v[56:59], v[114:115], off
	s_nop 0
	global_store_dwordx2 v[108:109], v[52:53], off
	s_waitcnt lgkmcnt(0)
	global_store_dwordx2 v[108:109], v[48:49], off offset:128
	s_waitcnt vmcnt(11)
	v_add_f32_e32 v88, v202, v122
	v_mfma_f32_16x16x32_bf16 v[142:145], v[142:145], v[28:31], v[146:149]
	v_mul_f32_e32 v88, 0xbfb8aa3b, v88
	v_exp_f32_e32 v88, v88
	v_add_f32_e32 v123, v203, v123
	v_add_f32_e32 v124, v204, v124
	v_add_f32_e32 v125, v205, v125
	s_waitcnt vmcnt(10)
	s_nop 1
	v_add_f32_e32 v122, v142, v126
	v_mul_f32_e32 v122, 0xbfb8aa3b, v122
	v_add_f32_e32 v129, v145, v129
	v_mul_f32_e32 v123, 0xbfb8aa3b, v123
	v_mul_f32_e32 v124, 0xbfb8aa3b, v124
	v_mul_f32_e32 v125, 0xbfb8aa3b, v125
	v_exp_f32_e32 v122, v122
	s_waitcnt vmcnt(9)
	v_add_f32_e32 v126, v152, v130
	s_waitcnt vmcnt(8)
	v_add_f32_e32 v130, v138, v134
	v_add_f32_e32 v134, v139, v135
	v_add_f32_e32 v135, v140, v136
	v_mul_f32_e32 v136, 0xbfb8aa3b, v129
	v_exp_f32_e32 v123, v123
	v_exp_f32_e32 v124, v124
	v_exp_f32_e32 v125, v125
	v_add_f32_e32 v88, 1.0, v88
	v_add_f32_e32 v128, v144, v128
	v_mul_f32_e32 v126, 0xbfb8aa3b, v126
	v_rcp_f32_e32 v150, v88
	v_exp_f32_e32 v88, v136
	v_mul_f32_e32 v128, 0xbfb8aa3b, v128
	v_exp_f32_e32 v126, v126
	v_exp_f32_e32 v128, v128
	v_add_f32_e32 v122, 1.0, v122
	v_add_f32_e32 v132, v154, v132
	v_add_f32_e32 v123, 1.0, v123
	v_add_f32_e32 v124, 1.0, v124
	v_rcp_f32_e32 v146, v122
	v_add_f32_e32 v122, 1.0, v125
	v_add_f32_e32 v131, v153, v131
	v_mul_f32_e32 v130, 0xbfb8aa3b, v130
	v_mul_f32_e32 v132, 0xbfb8aa3b, v132
	v_rcp_f32_e32 v152, v123
	v_rcp_f32_e32 v151, v124
	v_rcp_f32_e32 v153, v122
	v_add_f32_e32 v88, 1.0, v88
	v_mfma_f32_16x16x32_bf16 v[122:125], v[194:197], v[32:35], 0
	v_add_f32_e32 v127, v143, v127
	v_mul_f32_e32 v131, 0xbfb8aa3b, v131
	v_exp_f32_e32 v129, v130
	v_exp_f32_e32 v132, v132
	v_add_f32_e32 v126, 1.0, v126
	v_rcp_f32_e32 v149, v88
	v_add_f32_e32 v88, v155, v133
	v_mul_f32_e32 v127, 0xbfb8aa3b, v127
	v_mul_f32_e32 v134, 0xbfb8aa3b, v134
	v_mul_f32_e32 v135, 0xbfb8aa3b, v135
	v_exp_f32_e32 v130, v131
	v_add_f32_e32 v138, 1.0, v128
	v_rcp_f32_e32 v128, v126
	v_mul_f32_e32 v88, 0xbfb8aa3b, v88
	v_add_f32_e32 v126, v141, v137
	v_exp_f32_e32 v127, v127
	v_exp_f32_e32 v131, v134
	v_exp_f32_e32 v134, v135
	v_exp_f32_e32 v88, v88
	v_mul_f32_e32 v126, 0xbfb8aa3b, v126
	v_exp_f32_e32 v126, v126
	v_mfma_f32_16x16x32_bf16 v[122:125], v[198:201], v[36:39], v[122:125]
	v_add_f32_e32 v129, 1.0, v129
	v_add_f32_e32 v132, 1.0, v132
	v_add_f32_e32 v135, 1.0, v130
	v_rcp_f32_e32 v130, v129
	v_rcp_f32_e32 v129, v132
	v_lshlrev_b32_e32 v132, 16, v76
	v_lshlrev_b32_e32 v136, 16, v77
	v_and_b32_e32 v77, 0xffff0000, v77
	v_and_b32_e32 v76, 0xffff0000, v76
	v_add_f32_e32 v127, 1.0, v127
	v_add_f32_e32 v131, 1.0, v131
	v_add_f32_e32 v139, 1.0, v134
	v_add_f32_e32 v88, 1.0, v88
	v_mov_b32_e32 v137, v77
	v_mov_b32_e32 v133, v76
	v_rcp_f32_e32 v148, v127
	v_rcp_f32_e32 v134, v135
	v_rcp_f32_e32 v140, v131
	v_rcp_f32_e32 v147, v138
	v_rcp_f32_e32 v131, v139
	v_rcp_f32_e32 v135, v88
	v_add_f32_e32 v88, 1.0, v126
	v_mfma_f32_16x16x32_bf16 v[124:127], v[206:209], v[40:43], v[122:125]
	s_waitcnt vmcnt(7)
; #define LAS __attribute__((address_space(3)))
; __device__ __forceinline__ void rwkv_proj_phase(const bf16* Z, const float* shift, const float* w0, const float* a0, const float* kkp, const float* kap, const float* rkp, ...
;     ...
;             for (int nb = 0; nb < 4; ++nb) {
;                 const int n = h * 64 + nb * 16 + fr;
;                 f32x4 accw[2], acca[2], accg = (f32x4){0.f, 0.f, 0.f, 0.f};
; #pragma unroll
;                 for (int d = 0; d < 2; ++d) { accw[d] = (f32x4){0.f, 0.f, 0.f, 0.f}; acca[d] = (f32x4){0.f, 0.f, 0.f, 0.f};
; #pragma unroll
;                     for (int ksl = 0; ksl < 2; ++ksl) {
;                         const bf16x8 wf = *(const LAS bf16x8*)(lds + 51200 + (d * 64 + nb * 16 + fr) * 144 + (32 * ksl + 8 * g) * 2);
;                         const bf16x8 af = *(const LAS bf16x8*)(lds + 51200 + 18432 + (d * 64 + nb * 16 + fr) * 144 + (32 * ksl + 8 * g) * 2);
;                         accw[d] = MFMA16(wf, xf[2 * d + ksl], accw[d]);
;                         acca[d] = MFMA16(af, xf[4 + 2 * d + ksl], acca[d]); } }
; #pragma unroll
;                 for (int ksl = 0; ksl < 4; ++ksl) { const bf16x8 gf = *(const LAS bf16x8*)(lds + 51200 + 36864 + (nb * 16 + fr) * 272 + (32 * ksl + 8 * g) * 2); accg = MFMA16(gf, xf[8 + ksl], accg); }
;                 const int c = h * 64 + nb * 16 + 4 * g;
;                 const f32x4 rc = bf4(*(const LAS u32x2*)(rkv + nb * 32)), vc = bf4(*(const LAS u32x2*)(rkv + 256 + nb * 32));
;                 const f32x4 w00 = *(const f32x4*)(w0 + c), w01 = *(const f32x4*)(w0 + BW + c), a00 = *(const f32x4*)(a0 + c), a01 = *(const f32x4*)(a0 + BW + c);
;                 const f32x4 kk4 = *(const f32x4*)(kkp + c), ka4 = *(const f32x4*)(kap + c), rk4 = *(const f32x4*)(rkp + c);
;                 float o[9][4];
; #pragma unroll
;                 for (int e = 0; e < 4; ++e) {
;                     const float ad0 = sigmoid_f(a00[e] + acca[0][e]), ad1 = sigmoid_f(a01[e] + acca[1][e]);
;                     const float lw0 = -0.60653066f * sigmoid_f(w00[e] + accw[0][e]), lw1 = -0.60653066f * sigmoid_f(w01[e] + accw[1][e]);
;                     const float k = kc[nb][e], kk = k * kk4[e] * inv;
;                     const float kd0 = k * (1.f + (ad0 - 1.f) * ka4[e]), kd1 = k * (1.f + (ad1 - 1.f) * ka4[e]);
;                     bon += rc[e] * (kd0 + kd1) * rk4[e];
	v_pk_mul_f32 v[138:139], v[190:191], v[132:133]
	v_pk_mul_f32 v[128:129], v[128:129], s[54:55] op_sel_hi:[1,0]
	v_pk_mul_f32 v[138:139], v[138:139], v[138:139]
	v_pk_mul_f32 v[122:123], v[192:193], v[136:137]
	v_rcp_f32_e32 v141, v88
	v_pk_mul_f32 v[122:123], v[122:123], v[122:123]
	v_pk_mul_f32 v[134:135], v[134:135], s[54:55] op_sel_hi:[1,0]
	v_pk_mov_b32 v[142:143], v[138:139], v[122:123] op_sel:[1,0]
	v_mov_b32_e32 v139, v123
	v_pk_add_f32 v[122:123], v[142:143], v[138:139]
	v_and_b32_sdwa v88, v129, v177 dst_sel:DWORD dst_unused:UNUSED_PAD src0_sel:WORD_1 src1_sel:DWORD
	v_pk_add_f32 v[122:123], v[122:123], v[122:123] op_sel:[0,1] op_sel_hi:[1,0]
	v_add3_u32 v88, v129, v88, s77
	v_and_b32_sdwa v123, v128, v177 dst_sel:DWORD dst_unused:UNUSED_PAD src0_sel:WORD_1 src1_sel:DWORD
	v_add3_u32 v123, v128, v123, s77
	v_and_b32_sdwa v128, v135, v177 dst_sel:DWORD dst_unused:UNUSED_PAD src0_sel:WORD_1 src1_sel:DWORD
	v_and_b32_sdwa v129, v134, v177 dst_sel:DWORD dst_unused:UNUSED_PAD src0_sel:WORD_1 src1_sel:DWORD
	v_add3_u32 v128, v135, v128, s77
	v_add3_u32 v129, v134, v129, s77
	v_and_b32_e32 v128, 0xffff0000, v128
	v_and_b32_e32 v134, 0xffff0000, v129
	v_or_b32_sdwa v129, v128, v88 dst_sel:DWORD dst_unused:UNUSED_PAD src0_sel:DWORD src1_sel:WORD_1
	v_or_b32_sdwa v128, v134, v123 dst_sel:DWORD dst_unused:UNUSED_PAD src0_sel:DWORD src1_sel:WORD_1
	v_mov_b32_e32 v133, v136
	v_mov_b32_e32 v136, v190
	v_mov_b32_e32 v137, v192
	global_store_dwordx2 v[108:109], v[128:129], off offset:384
	v_pk_add_f32 v[128:129], v[150:151], -1.0 op_sel_hi:[1,0]
	s_waitcnt vmcnt(4)
	v_mov_b32_e32 v134, v84
	v_mov_b32_e32 v135, v86
	v_pk_mul_f32 v[154:155], v[136:137], v[132:133]
	v_pk_fma_f32 v[136:137], v[134:135], v[128:129], 1.0 op_sel_hi:[1,1,0]
	v_pk_add_f32 v[128:129], v[152:153], -1.0 op_sel_hi:[1,0]
	v_mov_b32_e32 v86, v85
	v_pk_fma_f32 v[138:139], v[86:87], v[128:129], 1.0 op_sel_hi:[1,1,0]
	v_pk_mul_f32 v[84:85], v[136:137], v[132:133]
	v_pk_mul_f32 v[128:129], v[138:139], v[76:77]
	s_nop 0
	s_nop 0
	s_nop 0
	s_nop 0
	s_nop 0
	s_nop 0
	v_cvt_pk_bf16_f32 v85, v85, v129
	v_cvt_pk_bf16_f32 v84, v84, v128
	global_store_dwordx2 v[108:109], v[84:85], off offset:512
	v_pk_mul_f32 v[84:85], v[130:131], s[54:55] op_sel_hi:[1,0]
	v_pk_mul_f32 v[128:129], v[140:141], s[54:55] op_sel_hi:[1,0]
	s_nop 0
	s_nop 0
	s_nop 0
	s_nop 0
	s_nop 0
	s_nop 0
	s_nop 0
	s_nop 0
	s_nop 0
	s_nop 0
	v_cvt_pk_bf16_f32 v85, v85, v129
	v_cvt_pk_bf16_f32 v84, v84, v128
	v_pk_add_f32 v[128:129], v[148:149], -1.0 op_sel_hi:[1,0]
	global_store_dwordx2 v[108:109], v[84:85], off offset:768
	v_pk_add_f32 v[84:85], v[146:147], -1.0 op_sel_hi:[1,0]
	v_pk_fma_f32 v[86:87], v[86:87], v[128:129], 1.0 op_sel_hi:[1,1,0]
	v_pk_fma_f32 v[84:85], v[134:135], v[84:85], 1.0 op_sel_hi:[1,1,0]
	v_pk_mul_f32 v[140:141], v[86:87], v[76:77]
	v_pk_mul_f32 v[142:143], v[84:85], v[132:133]
	v_add_u32_e32 v88, 0x900, v185
	s_nop 0
	s_nop 0
	s_nop 0
	s_nop 0
	v_add3_u32 v123, 0, v88, v184
	v_mov_b32_e32 v192, v191
	v_cvt_pk_bf16_f32 v135, v143, v141
	v_cvt_pk_bf16_f32 v134, v142, v140
	ds_read_b128 v[84:87], v123 offset:51200
	v_pk_mul_f32 v[156:157], v[192:193], v[76:77]
	v_add_u32_e32 v88, v186, v88
	v_mfma_f32_16x16x32_bf16 v[190:193], v[80:83], v[44:47], v[124:127]
	ds_read_b128 v[128:131], v88
	ds_read_b128 v[80:83], v123 offset:51264
	v_lshlrev_b32_e32 v144, 16, v78
	s_waitcnt lgkmcnt(2)
	v_mfma_f32_16x16x32_bf16 v[84:87], v[84:87], v[0:3], 0
	v_lshlrev_b32_e32 v208, 16, v79
	s_nop 1
	s_nop 0
	s_nop 0
	ds_read_b128 v[124:127], v88 offset:64
	s_waitcnt lgkmcnt(2)
	v_mfma_f32_16x16x32_bf16 v[128:131], v[128:131], v[16:19], 0
	v_and_b32_e32 v79, 0xffff0000, v79
	v_and_b32_e32 v78, 0xffff0000, v78
	v_mov_b32_e32 v209, v79
	v_mov_b32_e32 v145, v78
	s_nop 0
	s_waitcnt lgkmcnt(1)
	v_mfma_f32_16x16x32_bf16 v[80:83], v[80:83], v[4:7], v[84:87]
	v_mul_f32_e64 v74, v74, v208
	v_mul_f32_e64 v75, v75, v209
	v_pk_mul_f32 v[72:73], v[72:73], v[144:145]
	s_nop 0
	s_nop 0
	s_nop 0
	s_nop 0
	v_pk_mul_f32 v[74:75], v[74:75], v[74:75]
	v_pk_mul_f32 v[72:73], v[72:73], v[72:73]
	v_cvt_pk_bf16_f32 v206, v190, v191
	s_nop 0
	s_waitcnt lgkmcnt(0)
	v_mfma_f32_16x16x32_bf16 v[84:87], v[124:127], v[20:23], v[128:131]
	v_pk_mov_b32 v[124:125], v[72:73], v[74:75] op_sel:[1,0]
	v_mov_b32_e32 v73, v75
	global_store_dwordx2 v[108:109], v[134:135], off offset:896
	v_and_b32_e32 v130, 0xffff0000, v64
	v_pk_add_f32 v[72:73], v[124:125], v[72:73]
	v_lshlrev_b32_e32 v134, 16, v64
	v_and_b32_e32 v131, 0xffff0000, v65
	v_mov_b32_e32 v135, v130
	v_pk_add_f32 v[74:75], v[72:73], v[72:73] op_sel:[0,1] op_sel_hi:[1,0]
	v_lshlrev_b32_e32 v72, 16, v65
	v_mov_b32_e32 v73, v131
	v_pk_mul_f32 v[68:69], v[68:69], v[134:135]
	v_pk_mul_f32 v[64:65], v[70:71], v[72:73]
	v_mul_f32_e32 v70, v69, v69
	v_and_b32_e32 v125, 0xffff0000, v67
	v_and_b32_e32 v124, 0xffff0000, v66
	v_pk_fma_f32 v[68:69], v[68:69], v[68:69], v[70:71] op_sel_hi:[1,1,0]
	v_mul_f32_e32 v70, v65, v65
	v_lshlrev_b32_e32 v126, 16, v66
	v_lshlrev_b32_e32 v128, 16, v67
	v_mov_b32_e32 v129, v125
	v_mov_b32_e32 v127, v124
	v_add_u32_e32 v123, v186, v189
	v_pk_fma_f32 v[64:65], v[64:65], v[64:65], v[70:71] op_sel_hi:[1,1,0]
	v_pk_mul_f32 v[62:63], v[62:63], v[128:129]
	v_pk_mul_f32 v[60:61], v[60:61], v[126:127]
	ds_read_b128 v[194:197], v188 offset:62720
	ds_read_b128 v[198:201], v123
	ds_read_b128 v[202:205], v188 offset:62784
	v_mul_f32_e32 v123, v60, v60
	v_mul_f32_e32 v75, v61, v61
	v_mul_f32_e32 v69, v62, v62
	v_mul_f32_e32 v65, v63, v63
	v_pk_add_f32 v[60:61], v[122:123], v[74:75]
	v_pk_add_f32 v[62:63], v[68:69], v[64:65]
	s_nop 0
	v_pk_add_f32 v[60:61], v[60:61], v[62:63]
	s_waitcnt lgkmcnt(1)
; __device__ __forceinline__ void rwkv_proj_phase(const bf16* Z, const float* shift, const float* w0, const float* a0, const float* kkp, const float* kap, const float* rkp, ...
;     ...
;             f32x4 kc[4]; float ss = 0.f;
; #pragma unroll
;             for (int nb = 0; nb < 4; ++nb) {
;                 const int c = h * 64 + nb * 16 + 4 * g;
;                 kc[nb] = bf4(*(const LAS u32x2*)(rkv + 128 + nb * 32));
;                 const f32x4 t = kc[nb] * *(const f32x4*)(kkp + c);
;                 ss += (t.x * t.x + t.y * t.y) + (t.z * t.z + t.w * t.w);
;             }
;             ss += __shfl_xor(ss, 16); ss += __shfl_xor(ss, 32);
;             const float inv = rsqrtf(fmaxf(ss, 1e-12f));
;             bf16* sp = SOP + ((size_t)((b * NH + h) * SL + s)) * 576 + 4 * g;
;             float bon = 0.f;
; #pragma unroll
;             for (int nb = 0; nb < 4; ++nb) {
;                 const int n = h * 64 + nb * 16 + fr;
;                 f32x4 accw[2], acca[2], accg = (f32x4){0.f, 0.f, 0.f, 0.f};
; #pragma unroll
;                 for (int d = 0; d < 2; ++d) { accw[d] = (f32x4){0.f, 0.f, 0.f, 0.f}; acca[d] = (f32x4){0.f, 0.f, 0.f, 0.f};
; #pragma unroll
;                     for (int ksl = 0; ksl < 2; ++ksl) {
;                         const bf16x8 wf = *(const LAS bf16x8*)(lds + 51200 + (d * 64 + nb * 16 + fr) * 144 + (32 * ksl + 8 * g) * 2);
;                         const bf16x8 af = *(const LAS bf16x8*)(lds + 51200 + 18432 + (d * 64 + nb * 16 + fr) * 144 + (32 * ksl + 8 * g) * 2);
;                         accw[d] = MFMA16(wf, xf[2 * d + ksl], accw[d]);
;                         acca[d] = MFMA16(af, xf[4 + 2 * d + ksl], acca[d]); } }
; #pragma unroll
;                 for (int ksl = 0; ksl < 4; ++ksl) { const bf16x8 gf = *(const LAS bf16x8*)(lds + 51200 + 36864 + (nb * 16 + fr) * 272 + (32 * ksl + 8 * g) * 2); accg = MFMA16(gf, xf[8 + ksl], accg); }
;                 const int c = h * 64 + nb * 16 + 4 * g;
;                 const f32x4 rc = bf4(*(const LAS u32x2*)(rkv + nb * 32)), vc = bf4(*(const LAS u32x2*)(rkv + 256 + nb * 32));
;                 const f32x4 w00 = *(const f32x4*)(w0 + c), w01 = *(const f32x4*)(w0 + BW + c), a00 = *(const f32x4*)(a0 + c), a01 = *(const f32x4*)(a0 + BW + c);
;                 const f32x4 kk4 = *(const f32x4*)(kkp + c), ka4 = *(const f32x4*)(kap + c), rk4 = *(const f32x4*)(rkp + c);
;                 float o[9][4];
	v_mfma_f32_16x16x32_bf16 v[64:67], v[198:201], v[24:27], 0
	v_add_f32_e32 v68, v60, v61
	ds_bpermute_b32 v69, v182, v68
	v_add3_u32 v60, s62, v189, v184
	ds_read_b128 v[60:63], v60 offset:64
	v_lshl_add_u64 v[122:123], v[104:105], 0, v[120:121]
	v_mfma_f32_16x16x32_bf16 v[194:197], v[194:197], v[8:11], 0
	s_waitcnt lgkmcnt(1)
	v_add_f32_e32 v73, v68, v69
	ds_bpermute_b32 v74, v181, v73
	s_nop 0
	v_cvt_pk_bf16_f32 v207, v192, v193
	s_waitcnt lgkmcnt(1)
	v_mfma_f32_16x16x32_bf16 v[190:193], v[60:63], v[28:31], v[64:67]
	s_waitcnt lgkmcnt(0)
	v_add_f32_e32 v73, v73, v74
	v_max_f32_e32 v73, 0x2b8cbccc, v73
	v_rsq_f32_e32 v88, v73
	ds_read_b128 v[60:63], v183 offset:4352
	v_mfma_f32_16x16x32_bf16 v[68:71], v[202:205], v[12:15], v[194:197]
	v_mov_b32_e32 v145, v208
	v_pk_mul_f32 v[66:67], v[156:157], v[88:89] op_sel_hi:[1,0] neg_lo:[0,1] neg_hi:[0,1]
	v_pk_mul_f32 v[64:65], v[154:155], v[88:89] op_sel_hi:[1,0] neg_lo:[0,1] neg_hi:[0,1]
	s_nop 0
	s_nop 0
	s_nop 0
	s_nop 0
	s_nop 0
	s_nop 0
	s_nop 0
	s_nop 0
	s_nop 0
	v_cvt_pk_bf16_f32 v75, v65, v67
	v_cvt_pk_bf16_f32 v74, v64, v66
	global_store_dwordx2 v[108:109], v[74:75], off offset:256
	v_pk_mul_f32 v[74:75], v[64:65], v[150:151] neg_lo:[1,0] neg_hi:[1,0]
	v_pk_mul_f32 v[150:151], v[66:67], v[152:153] neg_lo:[1,0] neg_hi:[1,0]
	s_nop 0
	s_nop 0
	s_nop 0
	s_nop 0
	s_nop 0
	s_nop 0
	s_nop 0
	s_nop 0
	s_nop 0
	v_cvt_pk_bf16_f32 v75, v75, v151
	v_cvt_pk_bf16_f32 v74, v74, v150
	v_pk_mul_f32 v[64:65], v[64:65], v[146:147] neg_lo:[1,0] neg_hi:[1,0]
	global_store_dwordx2 v[108:109], v[74:75], off offset:640
	v_pk_mul_f32 v[66:67], v[66:67], v[148:149] neg_lo:[1,0] neg_hi:[1,0]
	s_nop 0
	s_nop 0
	s_nop 0
	s_nop 0
	s_nop 0
	s_nop 0
	s_nop 0
	s_nop 0
	s_nop 0
	v_cvt_pk_bf16_f32 v65, v65, v67
	v_cvt_pk_bf16_f32 v64, v64, v66
	global_store_dwordx2 v[108:109], v[64:65], off offset:1024
	global_store_dwordx2 v[122:123], v[206:207], off
	global_load_dwordx4 v[146:149], v[112:113], off offset:64
	ds_read_b128 v[64:67], v183 offset:4416
	global_load_dwordx4 v[150:153], v[112:113], off offset:3136
	global_load_dwordx4 v[154:157], v[110:111], off offset:64
	global_load_dwordx4 v[198:201], v[110:111], off offset:3136
	ds_read_b128 v[194:197], v183 offset:4480
	s_waitcnt lgkmcnt(2)
	v_mfma_f32_16x16x32_bf16 v[60:63], v[60:63], v[32:35], 0
	global_load_dwordx4 v[202:205], v[116:117], off offset:64
	v_add_u32_e32 v73, 0x1200, v185
	v_mov_b32_e32 v135, v72
	s_waitcnt lgkmcnt(1)
	v_mfma_f32_16x16x32_bf16 v[60:63], v[64:67], v[36:39], v[60:63]
	ds_read_b128 v[64:67], v183 offset:4544
	s_waitcnt vmcnt(2)
	v_add_f32_e32 v74, v80, v154
	s_waitcnt lgkmcnt(1)
	v_mfma_f32_16x16x32_bf16 v[60:63], v[194:197], v[40:43], v[60:63]
	global_load_dwordx4 v[194:197], v[118:119], off offset:64
	v_mul_f32_e32 v74, 0xbfb8aa3b, v74
	s_waitcnt vmcnt(2)
	v_add_f32_e32 v68, v68, v198
	s_waitcnt lgkmcnt(0)
	v_mfma_f32_16x16x32_bf16 v[60:63], v[64:67], v[44:47], v[60:63]
	v_exp_f32_e32 v74, v74
	v_mul_f32_e32 v68, 0xbfb8aa3b, v68
	v_exp_f32_e32 v75, v68
	v_add_f32_e32 v70, v70, v200
	v_mul_f32_e32 v70, 0xbfb8aa3b, v70
	s_nop 2
	s_nop 0
	s_nop 0
	s_nop 0
	s_nop 0
	s_nop 0
	v_cvt_pk_bf16_f32 v60, v60, v61
	v_bfe_u32 v61, v62, 16, 1
	v_add3_u32 v61, v62, v61, s77
	v_bfe_u32 v62, v63, 16, 1
	v_add3_u32 v62, v63, v62, s77
	v_add_f32_e32 v63, v190, v150
	v_mul_f32_e32 v63, 0xbfb8aa3b, v63
	v_exp_f32_e32 v63, v63
	v_lshrrev_b32_e32 v61, 16, v61
	v_and_or_b32 v61, v62, s76, v61
	v_add_f32_e32 v62, v84, v146
	v_add_f32_e32 v63, 1.0, v63
	v_rcp_f32_e32 v68, v63
	v_add_f32_e32 v63, 1.0, v74
	v_rcp_f32_e32 v74, v63
	v_add_f32_e32 v63, 1.0, v75
	v_rcp_f32_e32 v84, v63
	v_add_f32_e32 v63, v85, v147
	v_mul_f32_e32 v63, 0xbfb8aa3b, v63
	v_add_f32_e32 v75, v191, v151
	v_exp_f32_e32 v70, v70
	v_exp_f32_e32 v63, v63
	v_mul_f32_e32 v75, 0xbfb8aa3b, v75
	v_exp_f32_e32 v75, v75
	v_add_f32_e32 v70, 1.0, v70
	v_add_f32_e32 v63, 1.0, v63
	v_rcp_f32_e32 v85, v70
	v_add_f32_e32 v70, v87, v149
	v_rcp_f32_e32 v150, v63
	v_add_f32_e32 v63, 1.0, v75
	v_add_f32_e32 v75, v81, v155
	v_mul_f32_e32 v70, 0xbfb8aa3b, v70
	v_add_f32_e32 v81, v193, v153
	v_exp_f32_e32 v70, v70
	v_mul_f32_e32 v81, 0xbfb8aa3b, v81
	v_exp_f32_e32 v81, v81
	v_mul_f32_e32 v75, 0xbfb8aa3b, v75
	v_exp_f32_e32 v75, v75
	v_add_f32_e32 v70, 1.0, v70
	v_rcp_f32_e32 v151, v70
	v_add_f32_e32 v70, 1.0, v81
	v_add_f32_e32 v81, v83, v157
	v_add_f32_e32 v69, v69, v199
	v_mul_f32_e32 v81, 0xbfb8aa3b, v81
	v_add_f32_e32 v71, v71, v201
	v_mul_f32_e32 v69, 0xbfb8aa3b, v69
	v_rcp_f32_e32 v154, v63
	v_add_f32_e32 v63, 1.0, v75
	v_add_f32_e32 v75, v82, v156
	v_exp_f32_e32 v81, v81
	v_mul_f32_e32 v71, 0xbfb8aa3b, v71
	v_exp_f32_e32 v69, v69
	v_mul_f32_e32 v75, 0xbfb8aa3b, v75
	v_exp_f32_e32 v71, v71
	v_exp_f32_e32 v75, v75
	v_rcp_f32_e32 v155, v70
	v_add_f32_e32 v70, 1.0, v81
	v_rcp_f32_e32 v80, v63
	v_add_f32_e32 v63, 1.0, v69
	v_rcp_f32_e32 v81, v70
	v_add_f32_e32 v70, 1.0, v71
	v_rcp_f32_e32 v190, v63
	v_add_f32_e32 v63, v86, v148
	v_add_f32_e32 v75, 1.0, v75
	v_rcp_f32_e32 v191, v70
	v_mul_f32_e32 v62, 0xbfb8aa3b, v62
	s_waitcnt vmcnt(0)
; #define LAS __attribute__((address_space(3)))
; __device__ __forceinline__ void rwkv_proj_phase(const bf16* Z, const float* shift, const float* w0, const float* a0, const float* kkp, const float* kap, const float* rkp, ...
;     ...
;             for (int nb = 0; nb < 4; ++nb) {
;                 const int n = h * 64 + nb * 16 + fr;
;                 f32x4 accw[2], acca[2], accg = (f32x4){0.f, 0.f, 0.f, 0.f};
; #pragma unroll
;                 for (int d = 0; d < 2; ++d) { accw[d] = (f32x4){0.f, 0.f, 0.f, 0.f}; acca[d] = (f32x4){0.f, 0.f, 0.f, 0.f};
; #pragma unroll
;                     for (int ksl = 0; ksl < 2; ++ksl) {
;                         const bf16x8 wf = *(const LAS bf16x8*)(lds + 51200 + (d * 64 + nb * 16 + fr) * 144 + (32 * ksl + 8 * g) * 2);
;                         const bf16x8 af = *(const LAS bf16x8*)(lds + 51200 + 18432 + (d * 64 + nb * 16 + fr) * 144 + (32 * ksl + 8 * g) * 2);
;                         accw[d] = MFMA16(wf, xf[2 * d + ksl], accw[d]);
;                         acca[d] = MFMA16(af, xf[4 + 2 * d + ksl], acca[d]); } }
; #pragma unroll
;                 for (int ksl = 0; ksl < 4; ++ksl) { const bf16x8 gf = *(const LAS bf16x8*)(lds + 51200 + 36864 + (nb * 16 + fr) * 272 + (32 * ksl + 8 * g) * 2); accg = MFMA16(gf, xf[8 + ksl], accg); }
;                 const int c = h * 64 + nb * 16 + 4 * g;
;                 const f32x4 rc = bf4(*(const LAS u32x2*)(rkv + nb * 32)), vc = bf4(*(const LAS u32x2*)(rkv + 256 + nb * 32));
;                 const f32x4 w00 = *(const f32x4*)(w0 + c), w01 = *(const f32x4*)(w0 + BW + c), a00 = *(const f32x4*)(a0 + c), a01 = *(const f32x4*)(a0 + BW + c);
;                 const f32x4 kk4 = *(const f32x4*)(kkp + c), ka4 = *(const f32x4*)(kap + c), rk4 = *(const f32x4*)(rkp + c);
;                 float o[9][4];
; #pragma unroll
;                 for (int e = 0; e < 4; ++e) {
;                     const float ad0 = sigmoid_f(a00[e] + acca[0][e]), ad1 = sigmoid_f(a01[e] + acca[1][e]);
;                     const float lw0 = -0.60653066f * sigmoid_f(w00[e] + accw[0][e]), lw1 = -0.60653066f * sigmoid_f(w01[e] + accw[1][e]);
;                     const float k = kc[nb][e], kk = k * kk4[e] * inv;
;                     const float kd0 = k * (1.f + (ad0 - 1.f) * ka4[e]), kd1 = k * (1.f + (ad1 - 1.f) * ka4[e]);
;                     bon += rc[e] * (kd0 + kd1) * rk4[e];
	v_mov_b32_e32 v146, v194
	v_mov_b32_e32 v147, v196
	v_mov_b32_e32 v196, v195
	v_pk_mul_f32 v[146:147], v[146:147], v[144:145] neg_lo:[0,1] neg_hi:[0,1]
	v_pk_mul_f32 v[70:71], v[196:197], v[78:79] neg_lo:[0,1] neg_hi:[0,1]
	v_pk_mul_f32 v[146:147], v[88:89], v[146:147] op_sel_hi:[0,1]
	v_mul_f32_e32 v63, 0xbfb8aa3b, v63
	v_rcp_f32_e32 v75, v75
	v_pk_mul_f32 v[70:71], v[88:89], v[70:71] op_sel_hi:[0,1]
	s_nop 0
	v_exp_f32_e32 v62, v62
	v_exp_f32_e32 v63, v63
	s_nop 0
	s_nop 0
	s_nop 0
	s_nop 0
	s_nop 0
	s_nop 0
	s_nop 0
	s_nop 0
	s_nop 0
	v_cvt_pk_bf16_f32 v83, v147, v71
	v_cvt_pk_bf16_f32 v82, v146, v70
	v_pk_mul_f32 v[74:75], v[74:75], s[54:55] op_sel_hi:[1,0]
	global_load_dwordx4 v[64:67], v[114:115], off offset:64
	v_add_f32_e32 v62, 1.0, v62
	v_add_f32_e32 v63, 1.0, v63
	global_store_dwordx2 v[108:109], v[54:55], off offset:32
	global_store_dwordx2 v[108:109], v[50:51], off offset:160
	global_store_dwordx2 v[108:109], v[82:83], off offset:288
	v_pk_mul_f32 v[80:81], v[80:81], s[54:55] op_sel_hi:[1,0]
	s_nop 0
	s_nop 0
	v_rcp_f32_e32 v62, v62
	v_rcp_f32_e32 v63, v63
	s_nop 0
	s_nop 0
	s_nop 0
	s_nop 0
	s_nop 0
	s_nop 0
	s_nop 0
	s_nop 0
	v_cvt_pk_bf16_f32 v75, v75, v81
	v_cvt_pk_bf16_f32 v74, v74, v80
	global_store_dwordx2 v[108:109], v[74:75], off offset:416
	v_pk_add_f32 v[74:75], v[62:63], -1.0 op_sel_hi:[1,0]
	v_mov_b32_e32 v86, v202
	v_mov_b32_e32 v87, v204
	v_pk_fma_f32 v[74:75], v[86:87], v[74:75], 1.0 op_sel_hi:[1,1,0]
	v_mov_b32_e32 v204, v203
	v_pk_mul_f32 v[80:81], v[74:75], v[144:145]
	v_pk_add_f32 v[74:75], v[150:151], -1.0 op_sel_hi:[1,0]
	v_pk_mul_f32 v[62:63], v[146:147], v[62:63] neg_lo:[1,0] neg_hi:[1,0]
	v_pk_fma_f32 v[74:75], v[204:205], v[74:75], 1.0 op_sel_hi:[1,1,0]
	v_add_f32_e32 v69, v192, v152
	v_pk_mul_f32 v[82:83], v[74:75], v[78:79]
	s_nop 0
	s_nop 0
	s_nop 0
	s_nop 0
	s_nop 0
	s_nop 0
	v_cvt_pk_bf16_f32 v75, v81, v83
	v_cvt_pk_bf16_f32 v74, v80, v82
	global_store_dwordx2 v[108:109], v[74:75], off offset:544
	v_pk_mul_f32 v[74:75], v[70:71], v[150:151] neg_lo:[1,0] neg_hi:[1,0]
	s_nop 0
	s_nop 0
	v_mul_f32_e32 v69, 0xbfb8aa3b, v69
	s_nop 0
	s_nop 0
	s_nop 0
	s_nop 0
	v_exp_f32_e32 v69, v69
	s_nop 0
	s_nop 0
	s_nop 0
	s_nop 0
	v_cvt_pk_bf16_f32 v63, v63, v75
	v_cvt_pk_bf16_f32 v62, v62, v74
	global_store_dwordx2 v[108:109], v[62:63], off offset:672
	v_pk_mul_f32 v[62:63], v[84:85], s[54:55] op_sel_hi:[1,0]
	v_add_f32_e32 v69, 1.0, v69
	v_pk_mul_f32 v[74:75], v[190:191], s[54:55] op_sel_hi:[1,0]
	s_nop 0
	s_nop 0
	v_rcp_f32_e32 v69, v69
	s_nop 0
	s_nop 0
	s_nop 0
	s_nop 0
	s_nop 0
	s_nop 0
	s_nop 0
	s_nop 0
	v_cvt_pk_bf16_f32 v63, v63, v75
	v_cvt_pk_bf16_f32 v62, v62, v74
	global_store_dwordx2 v[108:109], v[62:63], off offset:800
	v_pk_add_f32 v[62:63], v[68:69], -1.0 op_sel_hi:[1,0]
	v_and_b32_e32 v127, 0xffff0000, v52
	v_pk_fma_f32 v[62:63], v[86:87], v[62:63], 1.0 op_sel_hi:[1,1,0]
	v_lshlrev_b32_e32 v129, 16, v53
	v_pk_mul_f32 v[84:85], v[62:63], v[144:145]
	v_pk_add_f32 v[62:63], v[154:155], -1.0 op_sel_hi:[1,0]
	s_nop 0
	v_pk_fma_f32 v[62:63], v[204:205], v[62:63], 1.0 op_sel_hi:[1,1,0]
	s_nop 0
	v_pk_mul_f32 v[86:87], v[62:63], v[78:79]
	s_nop 0
	s_nop 0
	s_nop 0
	s_nop 0
	s_nop 0
	s_nop 0
	s_nop 0
	s_nop 0
	s_nop 0
	s_nop 0
	v_cvt_pk_bf16_f32 v63, v85, v87
	v_cvt_pk_bf16_f32 v62, v84, v86
	global_store_dwordx2 v[108:109], v[62:63], off offset:928
	v_pk_mul_f32 v[62:63], v[146:147], v[68:69] neg_lo:[1,0] neg_hi:[1,0]
	v_pk_mul_f32 v[68:69], v[70:71], v[154:155] neg_lo:[1,0] neg_hi:[1,0]
	s_nop 0
	s_nop 0
	s_nop 0
	s_nop 0
	s_nop 0
	s_nop 0
	s_nop 0
	s_nop 0
	s_nop 0
	v_cvt_pk_bf16_f32 v63, v63, v69
	v_cvt_pk_bf16_f32 v62, v62, v68
	global_store_dwordx2 v[108:109], v[62:63], off offset:1056
	global_store_dwordx2 v[122:123], v[60:61], off offset:32
	global_load_dwordx4 v[144:147], v[112:113], off offset:128
	global_load_dwordx4 v[148:151], v[112:113], off offset:3200
	global_load_dwordx4 v[152:155], v[110:111], off offset:128
	global_load_dwordx4 v[194:197], v[110:111], off offset:3200
	v_add3_u32 v74, 0, v73, v184
	v_add_u32_e32 v73, v186, v73
	ds_read_b128 v[60:63], v74 offset:51200
	ds_read_b128 v[190:193], v74 offset:51264
	ds_read_b128 v[68:71], v73
	ds_read_b128 v[198:201], v73 offset:64
	s_waitcnt lgkmcnt(3)
	v_mfma_f32_16x16x32_bf16 v[60:63], v[60:63], v[0:3], 0
	v_add_u32_e32 v73, 0x3600, v185
	v_add_u32_e32 v74, v186, v73
	global_load_dwordx4 v[202:205], v[118:119], off offset:128
	s_waitcnt lgkmcnt(1)
	v_mfma_f32_16x16x32_bf16 v[68:71], v[68:71], v[16:19], 0
	ds_read_b128 v[206:209], v188 offset:65088
	s_waitcnt vmcnt(0)
	v_mov_b32_e32 v156, v202
	v_mfma_f32_16x16x32_bf16 v[190:193], v[190:193], v[4:7], v[60:63]
	v_mov_b32_e32 v157, v204
	v_mov_b32_e32 v204, v203
	v_pk_mul_f32 v[156:157], v[156:157], v[134:135] neg_lo:[0,1] neg_hi:[0,1]
	ds_read_b128 v[60:63], v188 offset:65024
	s_waitcnt lgkmcnt(2)
	v_mfma_f32_16x16x32_bf16 v[198:201], v[198:201], v[20:23], v[68:71]
	s_nop 2
	ds_read_b128 v[68:71], v74
	v_lshlrev_b32_e32 v74, 16, v52
	v_add3_u32 v52, s62, v73, v184
	ds_read_b128 v[210:213], v52 offset:64
	s_waitcnt lgkmcnt(2)
	v_mfma_f32_16x16x32_bf16 v[60:63], v[60:63], v[8:11], 0
	v_fma_f32 v52, v136, v132, v142
	v_fma_f32 v53, v137, v133, v143
	v_pk_fma_f32 v[132:133], v[138:139], v[76:77], v[140:141]
	v_add_f32_e32 v145, v199, v145
	s_waitcnt lgkmcnt(1)
	v_mfma_f32_16x16x32_bf16 v[68:71], v[68:71], v[24:27], 0
	v_mul_f32_e32 v145, 0xbfb8aa3b, v145
	v_exp_f32_e32 v145, v145
	v_add_f32_e32 v72, v198, v144
	v_mfma_f32_16x16x32_bf16 v[206:209], v[206:209], v[12:15], v[60:63]
	v_mul_f32_e32 v72, 0xbfb8aa3b, v72
	v_add_f32_e32 v145, 1.0, v145
	v_rcp_f32_e32 v188, v145
	s_waitcnt lgkmcnt(0)
; #define LAS __attribute__((address_space(3)))
; __device__ __forceinline__ void rwkv_proj_phase(const bf16* Z, const float* shift, const float* w0, const float* a0, const float* kkp, const float* kap, const float* rkp, ...
;     ...
;             for (int nb = 0; nb < 4; ++nb) {
;                 const int n = h * 64 + nb * 16 + fr;
;                 f32x4 accw[2], acca[2], accg = (f32x4){0.f, 0.f, 0.f, 0.f};
; #pragma unroll
;                 for (int d = 0; d < 2; ++d) { accw[d] = (f32x4){0.f, 0.f, 0.f, 0.f}; acca[d] = (f32x4){0.f, 0.f, 0.f, 0.f};
; #pragma unroll
;                     for (int ksl = 0; ksl < 2; ++ksl) {
;                         const bf16x8 wf = *(const LAS bf16x8*)(lds + 51200 + (d * 64 + nb * 16 + fr) * 144 + (32 * ksl + 8 * g) * 2);
;                         const bf16x8 af = *(const LAS bf16x8*)(lds + 51200 + 18432 + (d * 64 + nb * 16 + fr) * 144 + (32 * ksl + 8 * g) * 2);
;                         accw[d] = MFMA16(wf, xf[2 * d + ksl], accw[d]);
;                         acca[d] = MFMA16(af, xf[4 + 2 * d + ksl], acca[d]); } }
; #pragma unroll
;                 for (int ksl = 0; ksl < 4; ++ksl) { const bf16x8 gf = *(const LAS bf16x8*)(lds + 51200 + 36864 + (nb * 16 + fr) * 272 + (32 * ksl + 8 * g) * 2); accg = MFMA16(gf, xf[8 + ksl], accg); }
;                 const int c = h * 64 + nb * 16 + 4 * g;
;                 const f32x4 rc = bf4(*(const LAS u32x2*)(rkv + nb * 32)), vc = bf4(*(const LAS u32x2*)(rkv + 256 + nb * 32));
;                 const f32x4 w00 = *(const f32x4*)(w0 + c), w01 = *(const f32x4*)(w0 + BW + c), a00 = *(const f32x4*)(a0 + c), a01 = *(const f32x4*)(a0 + BW + c);
;                 const f32x4 kk4 = *(const f32x4*)(kkp + c), ka4 = *(const f32x4*)(kap + c), rk4 = *(const f32x4*)(rkp + c);
;                 float o[9][4];
; #pragma unroll
;                 for (int e = 0; e < 4; ++e) {
;                     const float ad0 = sigmoid_f(a00[e] + acca[0][e]), ad1 = sigmoid_f(a01[e] + acca[1][e]);
;                     const float lw0 = -0.60653066f * sigmoid_f(w00[e] + accw[0][e]), lw1 = -0.60653066f * sigmoid_f(w01[e] + accw[1][e]);
;                     const float k = kc[nb][e], kk = k * kk4[e] * inv;
;                     const float kd0 = k * (1.f + (ad0 - 1.f) * ka4[e]), kd1 = k * (1.f + (ad1 - 1.f) * ka4[e]);
;                     bon += rc[e] * (kd0 + kd1) * rk4[e];
	v_mfma_f32_16x16x32_bf16 v[136:139], v[210:213], v[28:31], v[68:71]
	ds_read_b128 v[140:143], v183 offset:8704
	ds_read_b128 v[210:213], v183 offset:8768
	ds_read_b128 v[214:217], v183 offset:8832
	ds_read_b128 v[76:79], v183 offset:8896
	ds_read2_b64 v[68:71], v187 offset0:8 offset1:12
	ds_read2_b64 v[60:63], v187 offset0:40 offset1:44
	global_load_dwordx4 v[218:221], v[116:117], off offset:128
	v_add_f32_e32 v145, v191, v153
	v_add_f32_e32 v137, v137, v149
	v_mul_f32_e32 v137, 0xbfb8aa3b, v137
	v_exp_f32_e32 v137, v137
	v_mul_f32_e32 v145, 0xbfb8aa3b, v145
	v_add_f32_e32 v149, v207, v195
	v_exp_f32_e32 v145, v145
	v_mul_f32_e32 v149, 0xbfb8aa3b, v149
	v_exp_f32_e32 v149, v149
	v_add_f32_e32 v137, 1.0, v137
	v_exp_f32_e32 v144, v72
	v_add_f32_e32 v72, v136, v148
	v_add_f32_e32 v148, v190, v152
	v_rcp_f32_e32 v190, v137
	v_add_f32_e32 v137, 1.0, v145
	v_add_f32_e32 v152, v206, v194
	v_rcp_f32_e32 v194, v137
	v_add_f32_e32 v137, 1.0, v149
	v_rcp_f32_e32 v198, v137
	v_add_f32_e32 v137, v200, v146
	v_mul_f32_e32 v137, 0xbfb8aa3b, v137
	v_add_f32_e32 v138, v138, v150
	v_exp_f32_e32 v137, v137
	v_mul_f32_e32 v138, 0xbfb8aa3b, v138
	v_exp_f32_e32 v138, v138
	v_add_f32_e32 v146, v208, v196
	v_add_f32_e32 v137, 1.0, v137
	v_rcp_f32_e32 v145, v137
	v_add_f32_e32 v137, 1.0, v138
	v_add_f32_e32 v138, v192, v154
	v_mul_f32_e32 v138, 0xbfb8aa3b, v138
	v_exp_f32_e32 v138, v138
	v_mul_f32_e32 v146, 0xbfb8aa3b, v146
	v_exp_f32_e32 v146, v146
	v_add_f32_e32 v139, v139, v151
	v_add_f32_e32 v138, 1.0, v138
	v_rcp_f32_e32 v149, v138
	v_add_f32_e32 v138, 1.0, v146
	v_rcp_f32_e32 v153, v138
	v_add_f32_e32 v138, v201, v147
	v_mul_f32_e32 v138, 0xbfb8aa3b, v138
	v_exp_f32_e32 v138, v138
	v_mul_f32_e32 v139, 0xbfb8aa3b, v139
	v_exp_f32_e32 v139, v139
	v_mul_f32_e32 v148, 0xbfb8aa3b, v148
	v_add_f32_e32 v138, 1.0, v138
	v_rcp_f32_e32 v189, v138
	v_add_f32_e32 v138, 1.0, v139
	v_rcp_f32_e32 v191, v138
	v_add_f32_e32 v138, v193, v155
	v_mul_f32_e32 v138, 0xbfb8aa3b, v138
	v_exp_f32_e32 v150, v138
	v_add_f32_e32 v138, v209, v197
	v_mul_f32_e32 v138, 0xbfb8aa3b, v138
	v_exp_f32_e32 v151, v138
	v_exp_f32_e32 v148, v148
	s_waitcnt lgkmcnt(5)
	v_mfma_f32_16x16x32_bf16 v[138:141], v[140:143], v[32:35], 0
	v_add_f32_e32 v142, 1.0, v150
	v_rcp_f32_e32 v195, v142
	v_add_f32_e32 v142, 1.0, v151
	v_add_f32_e32 v148, 1.0, v148
	v_pk_mul_f32 v[146:147], v[88:89], v[156:157] op_sel_hi:[0,1]
	v_rcp_f32_e32 v199, v142
	v_pk_mul_f32 v[142:143], v[204:205], v[130:131] neg_lo:[0,1] neg_hi:[0,1]
	v_rcp_f32_e32 v148, v148
	v_pk_mul_f32 v[142:143], v[88:89], v[142:143] op_sel_hi:[0,1]
	s_nop 0
	s_nop 0
	s_nop 0
	s_nop 0
	s_nop 0
	s_nop 0
	s_nop 0
	s_nop 0
	s_nop 0
	s_nop 0
	v_mul_f32_e32 v72, 0xbfb8aa3b, v72
	v_cvt_pk_bf16_f32 v151, v147, v143
	v_cvt_pk_bf16_f32 v150, v146, v142
	v_pk_mul_f32 v[148:149], v[148:149], s[54:55] op_sel_hi:[1,0]
	v_mul_f32_e32 v52, v52, v74
	v_exp_f32_e32 v136, v72
	global_load_dwordx4 v[72:75], v[114:115], off offset:128
	v_add_f32_e32 v144, 1.0, v144
	s_waitcnt lgkmcnt(1)
	global_store_dwordx2 v[108:109], v[68:69], off offset:64
	s_waitcnt lgkmcnt(0)
	global_store_dwordx2 v[108:109], v[60:61], off offset:192
	global_store_dwordx2 v[108:109], v[150:151], off offset:320
	v_pk_mul_f32 v[150:151], v[194:195], s[54:55] op_sel_hi:[1,0]
	s_nop 0
	s_nop 0
	v_rcp_f32_e32 v144, v144
	s_nop 0
	s_nop 0
	s_nop 0
	s_nop 0
	s_nop 0
	s_nop 0
	s_nop 0
	s_nop 0
	v_cvt_pk_bf16_f32 v149, v149, v151
	v_cvt_pk_bf16_f32 v148, v148, v150
	global_store_dwordx2 v[108:109], v[148:149], off offset:448
	v_pk_add_f32 v[148:149], v[144:145], -1.0 op_sel_hi:[1,0]
	s_waitcnt vmcnt(5)
	v_mov_b32_e32 v150, v218
	v_mov_b32_e32 v151, v220
	v_pk_fma_f32 v[148:149], v[150:151], v[148:149], 1.0 op_sel_hi:[1,1,0]
	v_pk_add_f32 v[154:155], v[188:189], -1.0 op_sel_hi:[1,0]
	v_mov_b32_e32 v220, v219
	v_pk_mul_f32 v[148:149], v[148:149], v[134:135]
	v_pk_fma_f32 v[154:155], v[220:221], v[154:155], 1.0 op_sel_hi:[1,1,0]
	v_mul_f32_e32 v152, 0xbfb8aa3b, v152
	v_pk_mul_f32 v[154:155], v[154:155], v[130:131]
	v_and_b32_sdwa v157, v148, v177 dst_sel:DWORD dst_unused:UNUSED_PAD src0_sel:WORD_1 src1_sel:DWORD
	v_exp_f32_e32 v152, v152
	v_add3_u32 v187, v148, v157, s77
	s_nop 0
	v_and_b32_sdwa v192, v154, v177 dst_sel:DWORD dst_unused:UNUSED_PAD src0_sel:WORD_1 src1_sel:DWORD
	s_nop 0
	s_nop 0
	v_add3_u32 v192, v154, v192, s77
	s_nop 0
	s_nop 0
	v_and_b32_e32 v192, 0xffff0000, v192
	v_cvt_pk_bf16_f32 v157, v149, v155
	v_or_b32_sdwa v156, v192, v187 dst_sel:DWORD dst_unused:UNUSED_PAD src0_sel:DWORD src1_sel:WORD_1
	v_pk_mul_f32 v[144:145], v[146:147], v[144:145] neg_lo:[1,0] neg_hi:[1,0]
	v_add_f32_e32 v152, 1.0, v152
	global_store_dwordx2 v[108:109], v[156:157], off offset:576
	v_pk_mul_f32 v[156:157], v[142:143], v[188:189] neg_lo:[1,0] neg_hi:[1,0]
	v_and_b32_sdwa v187, v145, v177 dst_sel:DWORD dst_unused:UNUSED_PAD src0_sel:WORD_1 src1_sel:DWORD
	v_and_b32_sdwa v188, v144, v177 dst_sel:DWORD dst_unused:UNUSED_PAD src0_sel:WORD_1 src1_sel:DWORD
	v_rcp_f32_e32 v152, v152
	v_add3_u32 v144, v144, v188, s77
	v_add3_u32 v145, v145, v187, s77
	v_and_b32_sdwa v187, v157, v177 dst_sel:DWORD dst_unused:UNUSED_PAD src0_sel:WORD_1 src1_sel:DWORD
	v_and_b32_sdwa v188, v156, v177 dst_sel:DWORD dst_unused:UNUSED_PAD src0_sel:WORD_1 src1_sel:DWORD
	v_add3_u32 v157, v157, v187, s77
	v_add3_u32 v156, v156, v188, s77
	v_and_b32_e32 v157, 0xffff0000, v157
	v_and_b32_e32 v156, 0xffff0000, v156
	v_or_b32_sdwa v145, v157, v145 dst_sel:DWORD dst_unused:UNUSED_PAD src0_sel:DWORD src1_sel:WORD_1
	v_or_b32_sdwa v144, v156, v144 dst_sel:DWORD dst_unused:UNUSED_PAD src0_sel:DWORD src1_sel:WORD_1
	global_store_dwordx2 v[108:109], v[144:145], off offset:704
; #define LAS __attribute__((address_space(3)))
; __device__ __forceinline__ void rwkv_proj_phase(const bf16* Z, const float* shift, const float* w0, const float* a0, const float* kkp, const float* kap, const float* rkp, ...
;     ...
;             for (int nb = 0; nb < 4; ++nb) {
;                 const int n = h * 64 + nb * 16 + fr;
;                 f32x4 accw[2], acca[2], accg = (f32x4){0.f, 0.f, 0.f, 0.f};
; #pragma unroll
;                 for (int d = 0; d < 2; ++d) { accw[d] = (f32x4){0.f, 0.f, 0.f, 0.f}; acca[d] = (f32x4){0.f, 0.f, 0.f, 0.f};
; #pragma unroll
;                     for (int ksl = 0; ksl < 2; ++ksl) {
;                         const bf16x8 wf = *(const LAS bf16x8*)(lds + 51200 + (d * 64 + nb * 16 + fr) * 144 + (32 * ksl + 8 * g) * 2);
;                         const bf16x8 af = *(const LAS bf16x8*)(lds + 51200 + 18432 + (d * 64 + nb * 16 + fr) * 144 + (32 * ksl + 8 * g) * 2);
;                         accw[d] = MFMA16(wf, xf[2 * d + ksl], accw[d]);
;                         acca[d] = MFMA16(af, xf[4 + 2 * d + ksl], acca[d]); } }
; #pragma unroll
;                 for (int ksl = 0; ksl < 4; ++ksl) { const bf16x8 gf = *(const LAS bf16x8*)(lds + 51200 + 36864 + (nb * 16 + fr) * 272 + (32 * ksl + 8 * g) * 2); accg = MFMA16(gf, xf[8 + ksl], accg); }
;                 const int c = h * 64 + nb * 16 + 4 * g;
;                 const f32x4 rc = bf4(*(const LAS u32x2*)(rkv + nb * 32)), vc = bf4(*(const LAS u32x2*)(rkv + 256 + nb * 32));
;                 const f32x4 w00 = *(const f32x4*)(w0 + c), w01 = *(const f32x4*)(w0 + BW + c), a00 = *(const f32x4*)(a0 + c), a01 = *(const f32x4*)(a0 + BW + c);
;                 const f32x4 kk4 = *(const f32x4*)(kkp + c), ka4 = *(const f32x4*)(kap + c), rk4 = *(const f32x4*)(rkp + c);
;                 float o[9][4];
; #pragma unroll
;                 for (int e = 0; e < 4; ++e) {
;                     const float ad0 = sigmoid_f(a00[e] + acca[0][e]), ad1 = sigmoid_f(a01[e] + acca[1][e]);
;                     const float lw0 = -0.60653066f * sigmoid_f(w00[e] + accw[0][e]), lw1 = -0.60653066f * sigmoid_f(w01[e] + accw[1][e]);
;                     const float k = kc[nb][e], kk = k * kk4[e] * inv;
;                     const float kd0 = k * (1.f + (ad0 - 1.f) * ka4[e]), kd1 = k * (1.f + (ad1 - 1.f) * ka4[e]);
;                     bon += rc[e] * (kd0 + kd1) * rk4[e];
	v_pk_mul_f32 v[144:145], v[152:153], s[54:55] op_sel_hi:[1,0]
	v_add_f32_e32 v136, 1.0, v136
	v_pk_mul_f32 v[152:153], v[198:199], s[54:55] op_sel_hi:[1,0]
	v_and_b32_sdwa v156, v145, v177 dst_sel:DWORD dst_unused:UNUSED_PAD src0_sel:WORD_1 src1_sel:DWORD
	v_and_b32_sdwa v157, v144, v177 dst_sel:DWORD dst_unused:UNUSED_PAD src0_sel:WORD_1 src1_sel:DWORD
	v_rcp_f32_e32 v136, v136
	v_rcp_f32_e32 v137, v137
	v_add3_u32 v144, v144, v157, s77
	v_add3_u32 v145, v145, v156, s77
	v_and_b32_sdwa v156, v153, v177 dst_sel:DWORD dst_unused:UNUSED_PAD src0_sel:WORD_1 src1_sel:DWORD
	v_and_b32_sdwa v157, v152, v177 dst_sel:DWORD dst_unused:UNUSED_PAD src0_sel:WORD_1 src1_sel:DWORD
	v_add3_u32 v153, v153, v156, s77
	v_add3_u32 v152, v152, v157, s77
	v_and_b32_e32 v153, 0xffff0000, v153
	v_and_b32_e32 v152, 0xffff0000, v152
	v_or_b32_sdwa v145, v153, v145 dst_sel:DWORD dst_unused:UNUSED_PAD src0_sel:DWORD src1_sel:WORD_1
	v_or_b32_sdwa v144, v152, v144 dst_sel:DWORD dst_unused:UNUSED_PAD src0_sel:DWORD src1_sel:WORD_1
	global_store_dwordx2 v[108:109], v[144:145], off offset:832
	v_pk_add_f32 v[144:145], v[136:137], -1.0 op_sel_hi:[1,0]
	v_mfma_f32_16x16x32_bf16 v[138:141], v[210:213], v[36:39], v[138:141]
	v_fma_f32 v144, v150, v144, 1.0
	v_fma_f32 v145, v151, v145, 1.0
	v_mul_f32_e32 v127, v132, v127
	v_pk_mul_f32 v[144:145], v[144:145], v[134:135]
	v_pk_add_f32 v[134:135], v[190:191], -1.0 op_sel_hi:[1,0]
	v_mfma_f32_16x16x32_bf16 v[138:141], v[214:217], v[40:43], v[138:141]
	v_fma_f32 v134, v220, v134, 1.0
	v_fma_f32 v135, v221, v135, 1.0
	v_mul_f32_e32 v53, v53, v129
	v_pk_mul_f32 v[150:151], v[134:135], v[130:131]
	s_nop 0
	s_nop 0
	s_nop 0
	s_nop 0
	s_nop 0
	s_nop 0
	s_nop 0
	s_nop 0
	v_cvt_pk_bf16_f32 v131, v145, v151
	v_cvt_pk_bf16_f32 v130, v144, v150
	global_store_dwordx2 v[108:109], v[130:131], off offset:960
	v_pk_mul_f32 v[130:131], v[146:147], v[136:137] neg_lo:[1,0] neg_hi:[1,0]
	v_pk_mul_f32 v[134:135], v[142:143], v[190:191] neg_lo:[1,0] neg_hi:[1,0]
	s_nop 0
	s_nop 0
	s_nop 0
	s_nop 0
	s_nop 0
	s_nop 0
	v_mfma_f32_16x16x32_bf16 v[76:79], v[76:79], v[44:47], v[138:141]
	s_nop 0
	s_nop 0
	s_nop 0
	s_nop 0
	v_cvt_pk_bf16_f32 v131, v131, v135
	v_cvt_pk_bf16_f32 v130, v130, v134
	global_store_dwordx2 v[108:109], v[130:131], off offset:1088
	s_nop 0
	s_nop 0
	s_nop 0
	s_nop 0
	s_nop 0
	s_nop 0
	v_cvt_pk_bf16_f32 v76, v76, v77
	v_cvt_pk_bf16_f32 v77, v78, v79
	global_store_dwordx2 v[122:123], v[76:77], off offset:64
	global_load_dwordx4 v[76:79], v[112:113], off offset:192
	v_fma_f32 v129, v56, v52, 0
	global_load_dwordx4 v[134:137], v[112:113], off offset:3264
	v_fmac_f32_e32 v129, v57, v127
	v_mul_f32_e32 v112, v133, v222
	v_fmac_f32_e32 v129, v58, v53
	global_load_dwordx4 v[130:133], v[110:111], off offset:192
	v_fmac_f32_e32 v129, v59, v112
	global_load_dwordx4 v[110:113], v[110:111], off offset:3264
	v_lshlrev_b32_e32 v52, 16, v54
	v_and_b32_e32 v53, 0xffff0000, v54
	v_add_u32_e32 v54, 0x1b00, v185
	v_add3_u32 v127, 0, v54, v184
	v_add_u32_e32 v142, v186, v54
	v_add_u32_e32 v54, 0x3f00, v185
	v_add3_u32 v143, s82, v184, v54
	v_add_u32_e32 v146, v186, v54
	v_add3_u32 v147, s82, v54, v184
	v_add3_u32 v152, s62, v54, v184
	v_add_f32_e32 v54, v80, v84
	v_mul_f32_e32 v58, v54, v52
	v_add_f32_e32 v52, v82, v86
	v_mov_b32_e32 v82, v81
	v_mov_b32_e32 v86, v85
	v_mul_f32_e32 v59, v52, v53
	v_and_b32_e32 v53, 0xffff0000, v55
	v_lshlrev_b32_e32 v52, 16, v55
	v_pk_add_f32 v[54:55], v[82:83], v[86:87]
	v_fmac_f32_e32 v129, v64, v58
	v_pk_mul_f32 v[52:53], v[54:55], v[52:53]
	v_fmac_f32_e32 v129, v65, v59
	v_pk_mul_f32 v[56:57], v[66:67], v[52:53]
	ds_read_b128 v[52:55], v127 offset:51200
	ds_read_b128 v[64:67], v127 offset:51264
	v_add_f32_e32 v56, v56, v129
	v_add_f32_e32 v129, v57, v56
	ds_read_b128 v[56:59], v142
	v_mov_b32_e32 v80, v148
	v_mov_b32_e32 v81, v154
	v_mov_b32_e32 v82, v144
	v_mov_b32_e32 v83, v150
	v_pk_add_f32 v[86:87], v[80:81], v[82:83]
	ds_read_b128 v[80:83], v142 offset:64
	s_waitcnt lgkmcnt(3)
	v_mfma_f32_16x16x32_bf16 v[52:55], v[52:55], v[0:3], 0
	v_and_b32_e32 v85, 0xffff0000, v68
	v_lshlrev_b32_e32 v84, 16, v68
	v_pk_mul_f32 v[84:85], v[86:87], v[84:85]
	global_load_dwordx4 v[138:141], v[118:119], off offset:192
	s_waitcnt lgkmcnt(1)
	v_mfma_f32_16x16x32_bf16 v[56:59], v[56:59], v[16:19], 0
	s_waitcnt vmcnt(15)
	v_pk_mul_f32 v[118:119], v[72:73], v[84:85]
	ds_read_b128 v[84:87], v143
	v_mov_b32_e32 v150, v145
	v_mfma_f32_16x16x32_bf16 v[64:67], v[64:67], v[4:7], v[52:55]
	v_mov_b32_e32 v154, v149
	v_and_b32_e32 v73, 0xffff0000, v69
	v_lshlrev_b32_e32 v72, 16, v69
	ds_read_b128 v[52:55], v146
	s_waitcnt lgkmcnt(2)
	v_mfma_f32_16x16x32_bf16 v[80:83], v[80:83], v[20:23], v[56:59]
	ds_read_b128 v[142:145], v152 offset:64
	v_pk_add_f32 v[68:69], v[154:155], v[150:151]
	v_add_f32_e32 v118, v129, v118
	ds_read_b128 v[56:59], v147 offset:64
	s_waitcnt lgkmcnt(3)
	v_mfma_f32_16x16x32_bf16 v[84:87], v[84:87], v[8:11], 0
	v_mul_f32_e64 v68, v68, v72
	v_mul_f32_e64 v69, v69, v73
	v_mov_b32_e32 v127, v128
	v_pk_mul_f32 v[68:69], v[74:75], v[68:69]
	s_waitcnt lgkmcnt(2)
	v_mfma_f32_16x16x32_bf16 v[52:55], v[52:55], v[24:27], 0
	s_waitcnt vmcnt(2)
	v_add_f32_e32 v64, v64, v130
	s_waitcnt lgkmcnt(0)
	v_mfma_f32_16x16x32_bf16 v[72:75], v[56:59], v[12:15], v[84:87]
	v_add_f32_e32 v56, v119, v118
	v_add_f32_e32 v56, v68, v56
	v_add_f32_e32 v154, v69, v56
	v_mfma_f32_16x16x32_bf16 v[84:87], v[142:145], v[28:31], v[52:55]
	ds_read_b128 v[142:145], v183 offset:13056
	ds_read_b128 v[146:149], v183 offset:13120
	ds_read_b128 v[150:153], v183 offset:13184
	ds_read_b128 v[52:55], v183 offset:13248
	global_load_dwordx4 v[116:119], v[116:117], off offset:192
	v_add_f32_e32 v56, v80, v76
	v_mul_f32_e32 v56, 0xbfb8aa3b, v56
	v_exp_f32_e32 v68, v56
	v_add_f32_e32 v56, v84, v134
	v_mul_f32_e32 v56, 0xbfb8aa3b, v56
	v_exp_f32_e32 v69, v56
	global_load_dwordx4 v[56:59], v[114:115], off offset:192
	v_add_f32_e32 v65, v65, v131
	v_add_f32_e32 v68, 1.0, v68
	v_mul_f32_e32 v64, 0xbfb8aa3b, v64
	v_mul_f32_e32 v65, 0xbfb8aa3b, v65
	s_waitcnt vmcnt(3)
; #define LAS __attribute__((address_space(3)))
; __device__ __forceinline__ unsigned pk2(float lo, float hi) { return f2bf(lo) | (f2bf(hi) << 16); }
; __device__ __forceinline__ float sigmoid_f(float x) { return __builtin_amdgcn_rcpf(1.f + __expf(-x)); }
; __device__ __forceinline__ f32x4 bf4(u32x2 w) { return (f32x4){bflo(w.x), bfhi(w.x), bflo(w.y), bfhi(w.y)}; }
; __device__ __forceinline__ void rwkv_proj_phase(const bf16* Z, const float* shift, const float* w0, const float* a0, const float* kkp, const float* kap, const float* rkp, ...
;     ...
;                 const f32x4 rc = bf4(*(const LAS u32x2*)(rkv + nb * 32)), vc = bf4(*(const LAS u32x2*)(rkv + 256 + nb * 32));
;                 const f32x4 w00 = *(const f32x4*)(w0 + c), w01 = *(const f32x4*)(w0 + BW + c), a00 = *(const f32x4*)(a0 + c), a01 = *(const f32x4*)(a0 + BW + c);
;                 const f32x4 kk4 = *(const f32x4*)(kkp + c), ka4 = *(const f32x4*)(kap + c), rk4 = *(const f32x4*)(rkp + c);
;                 float o[9][4];
; #pragma unroll
;                 for (int e = 0; e < 4; ++e) {
;                     const float ad0 = sigmoid_f(a00[e] + acca[0][e]), ad1 = sigmoid_f(a01[e] + acca[1][e]);
;                     const float lw0 = -0.60653066f * sigmoid_f(w00[e] + accw[0][e]), lw1 = -0.60653066f * sigmoid_f(w01[e] + accw[1][e]);
;                     const float k = kc[nb][e], kk = k * kk4[e] * inv;
;                     const float kd0 = k * (1.f + (ad0 - 1.f) * ka4[e]), kd1 = k * (1.f + (ad1 - 1.f) * ka4[e]);
;                     bon += rc[e] * (kd0 + kd1) * rk4[e];
;                     o[0][e] = rc[e]; o[1][e] = vc[e]; o[2][e] = -kk; o[3][e] = lw0; o[4][e] = kd0; o[5][e] = kk * ad0; o[6][e] = lw1; o[7][e] = kd1; o[8][e] = kk * ad1;
;                 }
; #pragma unroll
;                 for (int vv = 0; vv < 9; ++vv) { u32x2 w; w.x = pk2(o[vv][0], o[vv][1]); w.y = pk2(o[vv][2], o[vv][3]); *(u32x2*)(sp + vv * 64 + nb * 16) = w; }
;                 { u32x2 w; w.x = pk2(accg[0], accg[1]); w.y = pk2(accg[2], accg[3]); *(u32x2*)(G + (size_t)m * BW + c) = w; }
	v_add_f32_e32 v73, v73, v111
	v_rcp_f32_e32 v76, v68
	v_add_f32_e32 v68, 1.0, v69
	v_exp_f32_e32 v69, v64
	v_exp_f32_e32 v65, v65
	v_mul_f32_e32 v73, 0xbfb8aa3b, v73
	v_exp_f32_e32 v73, v73
	v_add_f32_e32 v64, v72, v110
	v_mul_f32_e32 v64, 0xbfb8aa3b, v64
	v_exp_f32_e32 v80, v64
	v_rcp_f32_e32 v64, v68
	v_add_f32_e32 v68, 1.0, v69
	v_add_f32_e32 v69, v81, v77
	v_add_f32_e32 v65, 1.0, v65
	v_mul_f32_e32 v69, 0xbfb8aa3b, v69
	v_rcp_f32_e32 v114, v65
	v_add_f32_e32 v65, 1.0, v73
	v_exp_f32_e32 v77, v69
	v_add_f32_e32 v69, v85, v135
	v_rcp_f32_e32 v128, v65
	v_add_f32_e32 v65, v82, v78
	v_mul_f32_e32 v69, 0xbfb8aa3b, v69
	v_mul_f32_e32 v65, 0xbfb8aa3b, v65
	v_add_f32_e32 v73, v86, v136
	v_exp_f32_e32 v81, v69
	v_exp_f32_e32 v65, v65
	v_mul_f32_e32 v73, 0xbfb8aa3b, v73
	v_exp_f32_e32 v73, v73
	v_add_f32_e32 v77, 1.0, v77
	v_rcp_f32_e32 v84, v77
	v_add_f32_e32 v77, 1.0, v81
	v_add_f32_e32 v65, 1.0, v65
	v_add_f32_e32 v66, v66, v132
	v_rcp_f32_e32 v110, v77
	v_rcp_f32_e32 v77, v65
	v_add_f32_e32 v65, 1.0, v73
	v_mul_f32_e32 v66, 0xbfb8aa3b, v66
	v_add_f32_e32 v73, v74, v112
	v_exp_f32_e32 v66, v66
	v_mul_f32_e32 v73, 0xbfb8aa3b, v73
	v_exp_f32_e32 v74, v73
	v_rcp_f32_e32 v72, v68
	v_add_f32_e32 v66, 1.0, v66
	v_rcp_f32_e32 v73, v66
	v_add_f32_e32 v66, 1.0, v74
	v_rcp_f32_e32 v81, v66
	v_add_f32_e32 v66, v83, v79
	v_mul_f32_e32 v66, 0xbfb8aa3b, v66
	v_add_f32_e32 v74, v87, v137
	v_exp_f32_e32 v66, v66
	v_mul_f32_e32 v74, 0xbfb8aa3b, v74
	v_exp_f32_e32 v74, v74
	v_add_f32_e32 v68, 1.0, v80
	v_add_f32_e32 v66, 1.0, v66
	v_rcp_f32_e32 v85, v66
	v_add_f32_e32 v66, 1.0, v74
	v_rcp_f32_e32 v111, v66
	v_add_f32_e32 v66, v67, v133
	v_mul_f32_e32 v66, 0xbfb8aa3b, v66
	v_exp_f32_e32 v74, v66
	v_add_f32_e32 v66, v75, v113
	v_mul_f32_e32 v66, 0xbfb8aa3b, v66
	v_exp_f32_e32 v75, v66
	v_rcp_f32_e32 v80, v68
	s_waitcnt vmcnt(2)
	v_mov_b32_e32 v68, v138
	v_mov_b32_e32 v69, v140
	v_add_f32_e32 v74, 1.0, v74
	v_mov_b32_e32 v140, v139
	v_pk_mul_f32 v[68:69], v[68:69], v[126:127] neg_lo:[0,1] neg_hi:[0,1]
	v_rcp_f32_e32 v115, v74
	v_add_f32_e32 v74, 1.0, v75
	v_pk_mul_f32 v[78:79], v[88:89], v[68:69] op_sel_hi:[0,1]
	v_rcp_f32_e32 v129, v74
	v_pk_mul_f32 v[74:75], v[140:141], v[124:125] neg_lo:[0,1] neg_hi:[0,1]
	s_nop 0
	v_pk_mul_f32 v[74:75], v[88:89], v[74:75] op_sel_hi:[0,1]
	s_nop 0
	s_nop 0
	s_nop 0
	s_nop 0
	s_nop 0
	s_nop 0
	s_nop 0
	s_nop 0
	s_nop 0
	v_cvt_pk_bf16_f32 v83, v79, v75
	v_cvt_pk_bf16_f32 v82, v78, v74
	v_pk_mul_f32 v[72:73], v[72:73], s[54:55] op_sel_hi:[1,0]
	global_store_dwordx2 v[108:109], v[70:71], off offset:96
	global_store_dwordx2 v[108:109], v[62:63], off offset:224
	global_store_dwordx2 v[108:109], v[82:83], off offset:352
	v_pk_mul_f32 v[82:83], v[114:115], s[54:55] op_sel_hi:[1,0]
	s_nop 0
	s_nop 0
	s_nop 0
	s_nop 0
	s_nop 0
	s_nop 0
	s_nop 0
	s_nop 0
	s_nop 0
	s_nop 0
	v_cvt_pk_bf16_f32 v73, v73, v83
	v_cvt_pk_bf16_f32 v72, v72, v82
	s_waitcnt vmcnt(4)
	v_mov_b32_e32 v83, v118
	v_pk_add_f32 v[86:87], v[84:85], -1.0 op_sel_hi:[1,0]
	v_mov_b32_e32 v118, v117
	global_store_dwordx2 v[108:109], v[72:73], off offset:480
	v_pk_add_f32 v[72:73], v[76:77], -1.0 op_sel_hi:[1,0]
	v_mov_b32_e32 v82, v116
	v_pk_fma_f32 v[86:87], v[118:119], v[86:87], 1.0 op_sel_hi:[1,1,0]
	v_pk_fma_f32 v[72:73], v[82:83], v[72:73], 1.0 op_sel_hi:[1,1,0]
	v_pk_mul_f32 v[86:87], v[86:87], v[124:125]
	v_pk_mul_f32 v[72:73], v[72:73], v[126:127]
	s_nop 0
	v_and_b32_sdwa v114, v86, v177 dst_sel:DWORD dst_unused:UNUSED_PAD src0_sel:WORD_1 src1_sel:DWORD
	s_nop 0
	v_and_b32_sdwa v112, v72, v177 dst_sel:DWORD dst_unused:UNUSED_PAD src0_sel:WORD_1 src1_sel:DWORD
	s_nop 0
	v_add3_u32 v114, v86, v114, s77
	v_add3_u32 v112, v72, v112, s77
	s_nop 0
	s_nop 0
	v_and_b32_e32 v114, 0xffff0000, v114
	v_cvt_pk_bf16_f32 v113, v73, v87
	v_or_b32_sdwa v112, v114, v112 dst_sel:DWORD dst_unused:UNUSED_PAD src0_sel:DWORD src1_sel:WORD_1
	v_pk_mul_f32 v[76:77], v[78:79], v[76:77] neg_lo:[1,0] neg_hi:[1,0]
	global_store_dwordx2 v[108:109], v[112:113], off offset:608
	v_pk_mul_f32 v[84:85], v[74:75], v[84:85] neg_lo:[1,0] neg_hi:[1,0]
	v_and_b32_sdwa v88, v77, v177 dst_sel:DWORD dst_unused:UNUSED_PAD src0_sel:WORD_1 src1_sel:DWORD
	s_nop 0
	s_nop 0
	v_add3_u32 v77, v77, v88, s77
	v_and_b32_sdwa v88, v85, v177 dst_sel:DWORD dst_unused:UNUSED_PAD src0_sel:WORD_1 src1_sel:DWORD
	s_nop 0
	v_add3_u32 v85, v85, v88, s77
	s_nop 0
	v_and_b32_e32 v85, 0xffff0000, v85
	s_nop 0
	v_or_b32_sdwa v77, v85, v77 dst_sel:DWORD dst_unused:UNUSED_PAD src0_sel:DWORD src1_sel:WORD_1
	v_cvt_pk_bf16_f32 v76, v76, v84
	s_waitcnt lgkmcnt(3)
	v_mfma_f32_16x16x32_bf16 v[66:69], v[142:145], v[32:35], 0
	global_store_dwordx2 v[108:109], v[76:77], off offset:736
	v_pk_mul_f32 v[76:77], v[80:81], s[54:55] op_sel_hi:[1,0]
	v_pk_mul_f32 v[80:81], v[128:129], s[54:55] op_sel_hi:[1,0]
	s_nop 0
	s_nop 0
	v_rcp_f32_e32 v65, v65
	s_nop 0
	s_nop 0
	s_nop 0
	s_nop 0
	s_nop 0
	s_nop 0
	s_waitcnt lgkmcnt(2)
	v_mfma_f32_16x16x32_bf16 v[66:69], v[146:149], v[36:39], v[66:69]
	s_nop 0
	s_nop 0
	v_cvt_pk_bf16_f32 v77, v77, v81
	v_cvt_pk_bf16_f32 v76, v76, v80
	global_store_dwordx2 v[108:109], v[76:77], off offset:864
	v_pk_add_f32 v[76:77], v[64:65], -1.0 op_sel_hi:[1,0]
	v_pk_add_f32 v[80:81], v[110:111], -1.0 op_sel_hi:[1,0]
	v_pk_fma_f32 v[76:77], v[82:83], v[76:77], 1.0 op_sel_hi:[1,1,0]
	v_pk_fma_f32 v[80:81], v[118:119], v[80:81], 1.0 op_sel_hi:[1,1,0]
	s_waitcnt lgkmcnt(1)
; #define LAS __attribute__((address_space(3)))
; __device__ __forceinline__ unsigned pk2(float lo, float hi) { return f2bf(lo) | (f2bf(hi) << 16); }
; __device__ __forceinline__ f32x4 bf4(u32x2 w) { return (f32x4){bflo(w.x), bfhi(w.x), bflo(w.y), bfhi(w.y)}; }
; __device__ __forceinline__ void rwkv_proj_phase(const bf16* Z, const float* shift, const float* w0, const float* a0, const float* kkp, const float* kap, const float* rkp, ...
;     for (int it = blockIdx.x; it < 132 * 3; it += gridDim.x) {
;     ...
;                 { u32x2 w; w.x = pk2(accg[0], accg[1]); w.y = pk2(accg[2], accg[3]); *(u32x2*)(G + (size_t)m * BW + c) = w; }
;             }
;             bon += __shfl_xor(bon, 16); bon += __shfl_xor(bon, 32);
; #pragma unroll
;             for (int nb = 0; nb < 4; ++nb) { const int c = h * 64 + nb * 16 + 4 * g;
;                 const f32x4 t = bf4(*(const LAS u32x2*)(rkv + 256 + nb * 32)) * bon;
;                 u32x2 w; w.x = pk2(t.x, t.y); w.y = pk2(t.z, t.w); *(u32x2*)(BV + (size_t)m * BW + c) = w; }
;             asm volatile("" ::: "memory");
;         }
	v_mfma_f32_16x16x32_bf16 v[66:69], v[150:153], v[40:43], v[66:69]
	v_mul_f32_e64 v76, v76, v126
	v_mul_f32_e64 v77, v77, v127
	v_pk_mul_f32 v[80:81], v[80:81], v[124:125]
	v_mov_b32_e32 v84, v72
	v_mov_b32_e32 v85, v86
	v_mov_b32_e32 v112, v76
	v_mov_b32_e32 v113, v80
	v_and_b32_e32 v83, 0xffff0000, v70
	v_lshlrev_b32_e32 v82, 16, v70
	v_pk_add_f32 v[84:85], v[84:85], v[112:113]
	v_mov_b32_e32 v86, v73
	v_pk_mul_f32 v[82:83], v[84:85], v[82:83]
	v_mov_b32_e32 v70, v77
	s_waitcnt vmcnt(7)
	v_pk_mul_f32 v[56:57], v[56:57], v[82:83]
	v_and_b32_e32 v83, 0xffff0000, v71
	v_lshlrev_b32_e32 v82, 16, v71
	v_mov_b32_e32 v71, v81
	s_waitcnt lgkmcnt(0)
	v_mfma_f32_16x16x32_bf16 v[52:55], v[52:55], v[44:47], v[66:69]
	v_add_f32_e64 v70, v86, v70
	v_add_f32_e64 v71, v87, v71
	v_add_f32_e32 v56, v154, v56
	v_pk_mul_f32 v[70:71], v[70:71], v[82:83]
	v_add_f32_e32 v56, v57, v56
	v_pk_mul_f32 v[58:59], v[58:59], v[70:71]
	s_nop 1
	s_nop 0
	v_add_f32_e32 v56, v58, v56
	v_add_f32_e32 v56, v59, v56
	s_nop 0
	s_nop 0
	s_nop 0
	ds_bpermute_b32 v57, v182, v56
	s_nop 0
	s_nop 0
	s_nop 0
	s_nop 0
	v_cvt_pk_bf16_f32 v52, v52, v53
	v_bfe_u32 v53, v54, 16, 1
	v_cvt_pk_bf16_f32 v71, v77, v81
	v_cvt_pk_bf16_f32 v70, v76, v80
	v_pk_mul_f32 v[64:65], v[78:79], v[64:65] neg_lo:[1,0] neg_hi:[1,0]
	v_add3_u32 v53, v54, v53, s77
	s_waitcnt lgkmcnt(0)
	v_add_f32_e32 v54, v56, v57
	global_store_dwordx2 v[108:109], v[70:71], off offset:992
	v_pk_mul_f32 v[70:71], v[74:75], v[110:111] neg_lo:[1,0] neg_hi:[1,0]
	v_and_b32_sdwa v72, v65, v177 dst_sel:DWORD dst_unused:UNUSED_PAD src0_sel:WORD_1 src1_sel:DWORD
	v_and_b32_sdwa v73, v64, v177 dst_sel:DWORD dst_unused:UNUSED_PAD src0_sel:WORD_1 src1_sel:DWORD
	ds_bpermute_b32 v56, v181, v54
	v_add3_u32 v64, v64, v73, s77
	v_add3_u32 v65, v65, v72, s77
	v_and_b32_sdwa v72, v71, v177 dst_sel:DWORD dst_unused:UNUSED_PAD src0_sel:WORD_1 src1_sel:DWORD
	v_and_b32_sdwa v73, v70, v177 dst_sel:DWORD dst_unused:UNUSED_PAD src0_sel:WORD_1 src1_sel:DWORD
	v_add3_u32 v71, v71, v72, s77
	v_add3_u32 v70, v70, v73, s77
	v_bfe_u32 v57, v55, 16, 1
	v_and_b32_e32 v71, 0xffff0000, v71
	v_and_b32_e32 v70, 0xffff0000, v70
	v_lshrrev_b32_e32 v53, 16, v53
	v_add3_u32 v55, v55, v57, s77
	v_or_b32_sdwa v65, v71, v65 dst_sel:DWORD dst_unused:UNUSED_PAD src0_sel:DWORD src1_sel:WORD_1
	v_or_b32_sdwa v64, v70, v64 dst_sel:DWORD dst_unused:UNUSED_PAD src0_sel:DWORD src1_sel:WORD_1
	v_and_or_b32 v53, v55, s76, v53
	global_store_dwordx2 v[108:109], v[64:65], off offset:1120
	global_store_dwordx2 v[122:123], v[52:53], off offset:96
	s_waitcnt lgkmcnt(0)
	v_add_f32_e32 v52, v54, v56
	v_lshlrev_b32_e32 v54, 16, v48
	v_and_b32_e32 v55, 0xffff0000, v48
	v_lshlrev_b32_e32 v48, 16, v49
	v_and_b32_e32 v49, 0xffff0000, v49
	v_pk_mul_f32 v[54:55], v[52:53], v[54:55] op_sel_hi:[0,1]
	v_pk_mul_f32 v[48:49], v[52:53], v[48:49] op_sel_hi:[0,1]
	v_cvt_pk_bf16_f32 v54, v54, v55
	v_bfe_u32 v53, v48, 16, 1
	v_add3_u32 v48, v48, v53, s77
	v_bfe_u32 v53, v49, 16, 1
	v_lshrrev_b32_e32 v48, 16, v48
	v_add3_u32 v49, v49, v53, s77
	v_and_or_b32 v55, v49, s76, v48
	v_lshl_add_u64 v[48:49], v[106:107], 0, v[120:121]
	global_store_dwordx2 v[48:49], v[54:55], off
	v_lshlrev_b32_e32 v54, 16, v50
	v_and_b32_e32 v55, 0xffff0000, v50
	v_lshlrev_b32_e32 v50, 16, v51
	v_and_b32_e32 v51, 0xffff0000, v51
	v_pk_mul_f32 v[54:55], v[52:53], v[54:55] op_sel_hi:[0,1]
	v_pk_mul_f32 v[50:51], v[52:53], v[50:51] op_sel_hi:[0,1]
	v_cvt_pk_bf16_f32 v54, v54, v55
	v_bfe_u32 v53, v50, 16, 1
	v_add3_u32 v50, v50, v53, s77
	v_bfe_u32 v53, v51, 16, 1
	v_lshrrev_b32_e32 v50, 16, v50
	v_add3_u32 v51, v51, v53, s77
	v_and_or_b32 v55, v51, s76, v50
	v_lshlrev_b32_e32 v50, 16, v60
	v_and_b32_e32 v51, 0xffff0000, v60
	global_store_dwordx2 v[48:49], v[54:55], off offset:32
	v_lshlrev_b32_e32 v54, 16, v61
	v_and_b32_e32 v55, 0xffff0000, v61
	v_pk_mul_f32 v[50:51], v[52:53], v[50:51] op_sel_hi:[0,1]
	v_pk_mul_f32 v[54:55], v[52:53], v[54:55] op_sel_hi:[0,1]
	v_cvt_pk_bf16_f32 v50, v50, v51
	v_bfe_u32 v51, v54, 16, 1
	v_add3_u32 v51, v54, v51, s77
	v_bfe_u32 v53, v55, 16, 1
	v_lshrrev_b32_e32 v51, 16, v51
	v_add3_u32 v53, v55, v53, s77
	v_and_or_b32 v51, v53, s76, v51
	global_store_dwordx2 v[48:49], v[50:51], off offset:64
	v_lshlrev_b32_e32 v50, 16, v62
	v_and_b32_e32 v51, 0xffff0000, v62
	v_lshlrev_b32_e32 v54, 16, v63
	v_and_b32_e32 v55, 0xffff0000, v63
	v_pk_mul_f32 v[50:51], v[52:53], v[50:51] op_sel_hi:[0,1]
	v_pk_mul_f32 v[54:55], v[52:53], v[54:55] op_sel_hi:[0,1]
	v_cvt_pk_bf16_f32 v50, v50, v51
	v_bfe_u32 v51, v54, 16, 1
	v_add3_u32 v51, v54, v51, s77
	v_bfe_u32 v52, v55, 16, 1
	v_lshrrev_b32_e32 v51, 16, v51
	v_add3_u32 v52, v55, v52, s77
	v_and_or_b32 v51, v52, s76, v51
	global_store_dwordx2 v[48:49], v[50:51], off offset:96
	s_cbranch_scc0 .LBB0_263
	v_readlane_b32 s64, v246, 31
	v_readlane_b32 s70, v246, 37
	s_add_i32 s83, s83, s70
	s_cmpk_gt_i32 s83, 0x18b
	v_readlane_b32 s65, v246, 32
	v_readlane_b32 s66, v246, 33
	v_readlane_b32 s67, v246, 34
	v_readlane_b32 s68, v246, 35
	v_readlane_b32 s69, v246, 36
	v_readlane_b32 s71, v246, 38
	s_cbranch_scc0 .LBB0_258

; __device__ __forceinline__ unsigned pk2(float lo, float hi) { return f2bf(lo) | (f2bf(hi) << 16); }
; __device__ __forceinline__ void na_item(int item, const bf16* Z, const float* rpb, bf16* CC, LAS unsigned char* lds, int tid, int wave, int lane) {
;     ...
;     lrun += __shfl_xor(lrun, 16); lrun += __shfl_xor(lrun, 32);
;     const float il = 1.f / lrun;
;     bf16* op = CC + mq * D + 1280 + h * 64 + 4 * g;
; #pragma unroll
;     for (int nb = 0; nb < 4; ++nb) { u32x2 w; w.x = pk2(oacc[nb][0] * il, oacc[nb][1] * il); w.y = pk2(oacc[nb][2] * il, oacc[nb][3] * il); *(u32x2*)(op + nb * 16) = w; }
;     ...
;             if ((int)blockIdx.x >= 140) for (int it = (int)blockIdx.x - 140; it < NA_EARLY; it += (int)gridDim.x - 140) na_item(it, Z, in.p[20] + (size_t)l * NH * 465, AC, lds, tid, wave, lane); }
.LBB0_269:
	s_waitcnt vmcnt(2)
	ds_bpermute_b32 v3, v123, v87
	v_readlane_b32 s64, v246, 31
	v_lshlrev_b64 v[0:1], 12, v[88:89]
	v_mov_b32_e32 v2, v44
	v_readlane_b32 s66, v246, 33
	s_waitcnt lgkmcnt(0)
	v_add_f32_e32 v4, v87, v3
	ds_bpermute_b32 v5, v124, v4
	v_mov_b32_e32 v3, v46
	v_readlane_b32 s67, v246, 34
	v_mov_b32_e32 v46, v45
	s_add_i32 s6, s28, s6
	s_waitcnt lgkmcnt(0)
	v_add_f32_e32 v6, v4, v5
	v_div_scale_f32 v7, s[4:5], v6, v6, 1.0
	v_rcp_f32_e32 v8, v7
	v_div_scale_f32 v9, vcc, 1.0, v6, 1.0
	v_lshl_add_u64 v[0:1], s[66:67], 0, v[0:1]
	v_fma_f32 v10, -v7, v8, 1.0
	v_fmac_f32_e32 v8, v10, v8
	v_mul_f32_e32 v10, v9, v8
	v_fma_f32 v11, -v7, v10, v9
	v_fmac_f32_e32 v10, v11, v8
	v_fma_f32 v7, -v7, v10, v9
	v_div_fmas_f32 v7, v7, v8, v10
	v_div_fixup_f32 v6, v7, v6, 1.0
	v_pk_mul_f32 v[2:3], v[2:3], v[6:7] op_sel_hi:[1,0]
	v_lshl_add_u64 v[0:1], s[84:85], 1, v[0:1]
	v_pk_mul_f32 v[8:9], v[46:47], v[6:7] op_sel_hi:[1,0]
	v_and_b32_sdwa v7, v3, v127 dst_sel:DWORD dst_unused:UNUSED_PAD src0_sel:WORD_1 src1_sel:DWORD
	v_and_b32_sdwa v10, v2, v127 dst_sel:DWORD dst_unused:UNUSED_PAD src0_sel:WORD_1 src1_sel:DWORD
	v_lshl_add_u64 v[0:1], v[70:71], 1, v[0:1]
	s_mov_b64 s[4:5], 0x6700a00
	v_add3_u32 v2, v2, v10, s33
	v_add3_u32 v3, v3, v7, s33
	v_and_b32_sdwa v7, v9, v127 dst_sel:DWORD dst_unused:UNUSED_PAD src0_sel:WORD_1 src1_sel:DWORD
	v_and_b32_sdwa v10, v8, v127 dst_sel:DWORD dst_unused:UNUSED_PAD src0_sel:WORD_1 src1_sel:DWORD
	v_lshl_add_u64 v[4:5], v[0:1], 0, s[4:5]
	v_add3_u32 v7, v9, v7, s33
	v_add3_u32 v8, v8, v10, s33
	s_mov_b32 s4, 0x6700000
	v_and_b32_e32 v7, 0xffff0000, v7
	v_and_b32_e32 v8, 0xffff0000, v8
	v_add_co_u32_e32 v0, vcc, s4, v0
	v_or_b32_sdwa v3, v7, v3 dst_sel:DWORD dst_unused:UNUSED_PAD src0_sel:DWORD src1_sel:WORD_1
	v_or_b32_sdwa v2, v8, v2 dst_sel:DWORD dst_unused:UNUSED_PAD src0_sel:DWORD src1_sel:WORD_1
	v_addc_co_u32_e32 v1, vcc, 0, v1, vcc
	global_store_dwordx2 v[0:1], v[2:3], off offset:2560
	v_mov_b32_e32 v0, v32
	v_mov_b32_e32 v1, v34
	v_pk_mul_f32 v[0:1], v[0:1], v[6:7] op_sel_hi:[1,0]
	v_mov_b32_e32 v34, v33
	v_pk_mul_f32 v[2:3], v[34:35], v[6:7] op_sel_hi:[1,0]
	v_and_b32_sdwa v7, v1, v127 dst_sel:DWORD dst_unused:UNUSED_PAD src0_sel:WORD_1 src1_sel:DWORD
	s_nop 0
	s_nop 0
	v_add3_u32 v1, v1, v7, s33
	v_and_b32_sdwa v7, v3, v127 dst_sel:DWORD dst_unused:UNUSED_PAD src0_sel:WORD_1 src1_sel:DWORD
	s_nop 0
	v_add3_u32 v3, v3, v7, s33
	s_nop 0
	v_and_b32_e32 v3, 0xffff0000, v3
	s_nop 0
	v_or_b32_sdwa v1, v3, v1 dst_sel:DWORD dst_unused:UNUSED_PAD src0_sel:DWORD src1_sel:WORD_1
	v_cvt_pk_bf16_f32 v0, v0, v2
	global_store_dwordx2 v[4:5], v[0:1], off offset:32
	v_mov_b32_e32 v0, v28
	v_mov_b32_e32 v1, v30
	v_pk_mul_f32 v[0:1], v[0:1], v[6:7] op_sel_hi:[1,0]
	v_mov_b32_e32 v30, v29
	v_pk_mul_f32 v[2:3], v[30:31], v[6:7] op_sel_hi:[1,0]
	v_and_b32_sdwa v7, v1, v127 dst_sel:DWORD dst_unused:UNUSED_PAD src0_sel:WORD_1 src1_sel:DWORD
	v_and_b32_sdwa v8, v0, v127 dst_sel:DWORD dst_unused:UNUSED_PAD src0_sel:WORD_1 src1_sel:DWORD
	v_add3_u32 v0, v0, v8, s33
	v_add3_u32 v1, v1, v7, s33
	v_and_b32_sdwa v7, v3, v127 dst_sel:DWORD dst_unused:UNUSED_PAD src0_sel:WORD_1 src1_sel:DWORD
	v_and_b32_sdwa v8, v2, v127 dst_sel:DWORD dst_unused:UNUSED_PAD src0_sel:WORD_1 src1_sel:DWORD
	v_add3_u32 v3, v3, v7, s33
	v_add3_u32 v2, v2, v8, s33
	v_and_b32_e32 v3, 0xffff0000, v3
	v_and_b32_e32 v2, 0xffff0000, v2
	v_or_b32_sdwa v1, v3, v1 dst_sel:DWORD dst_unused:UNUSED_PAD src0_sel:DWORD src1_sel:WORD_1
	v_or_b32_sdwa v0, v2, v0 dst_sel:DWORD dst_unused:UNUSED_PAD src0_sel:DWORD src1_sel:WORD_1
	global_store_dwordx2 v[4:5], v[0:1], off offset:64
	v_mov_b32_e32 v0, v24
	v_mov_b32_e32 v1, v26
	v_pk_mul_f32 v[0:1], v[0:1], v[6:7] op_sel_hi:[1,0]
	v_mov_b32_e32 v26, v25
	v_pk_mul_f32 v[2:3], v[26:27], v[6:7] op_sel_hi:[1,0]
	v_and_b32_sdwa v6, v1, v127 dst_sel:DWORD dst_unused:UNUSED_PAD src0_sel:WORD_1 src1_sel:DWORD
	v_and_b32_sdwa v7, v0, v127 dst_sel:DWORD dst_unused:UNUSED_PAD src0_sel:WORD_1 src1_sel:DWORD
	v_add3_u32 v0, v0, v7, s33
	v_add3_u32 v1, v1, v6, s33
	v_and_b32_sdwa v6, v3, v127 dst_sel:DWORD dst_unused:UNUSED_PAD src0_sel:WORD_1 src1_sel:DWORD
	v_and_b32_sdwa v7, v2, v127 dst_sel:DWORD dst_unused:UNUSED_PAD src0_sel:WORD_1 src1_sel:DWORD
	v_add3_u32 v3, v3, v6, s33
	v_add3_u32 v2, v2, v7, s33
	v_and_b32_e32 v3, 0xffff0000, v3
	v_and_b32_e32 v2, 0xffff0000, v2
	v_or_b32_sdwa v1, v3, v1 dst_sel:DWORD dst_unused:UNUSED_PAD src0_sel:DWORD src1_sel:WORD_1
	v_or_b32_sdwa v0, v2, v0 dst_sel:DWORD dst_unused:UNUSED_PAD src0_sel:DWORD src1_sel:WORD_1
	s_cmpk_lt_i32 s6, 0x1d0
	v_readlane_b32 s65, v246, 32
	v_readlane_b32 s68, v246, 35
	v_readlane_b32 s69, v246, 36
	v_readlane_b32 s70, v246, 37
	v_readlane_b32 s71, v246, 38
	global_store_dwordx2 v[4:5], v[0:1], off offset:96
	s_cbranch_scc0 .LBB0_346

; #define LAS __attribute__((address_space(3)))
; __device__ __forceinline__ unsigned pk2(float lo, float hi) { return f2bf(lo) | (f2bf(hi) << 16); }
; #define MFMA16(a, b, c) __builtin_amdgcn_mfma_f32_16x16x32_bf16((a), (b), (c), 0, 0, 0)
; __device__ __forceinline__ void na_item(int item, const bf16* Z, const float* rpb, bf16* CC, LAS unsigned char* lds, int tid, int wave, int lane) {
;     ...
;             bf16x8 pf[2];
; #pragma unroll
;             for (int ks = 0; ks < 2; ++ks) { u32x4 w; w.x = pk2(sc[2 * ks][0], sc[2 * ks][1]); w.y = pk2(sc[2 * ks][2], sc[2 * ks][3]); w.z = pk2(sc[2 * ks + 1][0], sc[2 * ks + 1][1]); w.w = pk2(sc[2 * ks + 1][2], sc[2 * ks + 1][3]);
;                 pf[ks] = __builtin_bit_cast(bf16x8, w); }
; #pragma unroll
;             for (int nb = 0; nb < 4; ++nb) oacc[nb] = oacc[nb] * alpha;
; #pragma unroll
;             for (int ks = 0; ks < 2; ++ks) {
;                 const bool kson = !loc || (2 * ks + 1 >= nlo && 2 * ks <= nhi);
;                 if (kson) {
; #pragma unroll
;                     for (int nb = 0; nb < 4; ++nb) { const LAS bf16* vp = Vt + (nb * 16 + fr) * KSTR + 32 * ks + 4 * g;
;                         const u32x2 lo = *(const LAS u32x2*)vp, hi = *(const LAS u32x2*)(vp + 16);
;                         u32x4 w; w.x = lo.x; w.y = lo.y; w.z = hi.x; w.w = hi.y;
;                         oacc[nb] = MFMA16(__builtin_bit_cast(bf16x8, w), pf[ks], oacc[nb]); }
;                 }
;             }
.LBB0_341:
	v_add_u32_e32 v95, v120, v122
	v_add_u32_e32 v131, v120, v103
	s_andn2_b64 vcc, exec, s[86:87]
	v_add_u32_e32 v130, 0x2000, v95
	v_add_u32_e32 v129, 0x2800, v95
	v_add_u32_e32 v128, 0x3000, v95
	v_add_u32_e32 v95, 0x2000, v131
	s_cbranch_vccnz .LBB0_343
	v_bfe_u32 v131, v0, 16, 1
	v_add3_u32 v0, v0, v131, s33
	v_bfe_u32 v131, v1, 16, 1
	v_lshrrev_b32_e32 v0, 16, v0
	v_add3_u32 v1, v1, v131, s33
	v_and_or_b32 v0, v1, s63, v0
	v_cvt_pk_bf16_f32 v1, v2, v3
	v_cvt_pk_bf16_f32 v2, v4, v5
	s_nop 0
	s_nop 0
	v_cvt_pk_bf16_f32 v3, v6, v7
	ds_read2_b64 v[4:7], v129 offset0:160 offset1:164
	ds_read2_b64 v[132:135], v130 offset0:128 offset1:132
	s_waitcnt lgkmcnt(1)
	v_mfma_f32_16x16x32_bf16 v[32:35], v[4:7], v[0:3], v[32:35]
	ds_read2_b64 v[4:7], v128 offset0:192 offset1:196
	s_waitcnt lgkmcnt(0)
	v_mfma_f32_16x16x32_bf16 v[28:31], v[4:7], v[0:3], v[28:31]
	ds_read2_b64 v[4:7], v95 offset0:128 offset1:132
	v_mfma_f32_16x16x32_bf16 v[44:47], v[132:135], v[0:3], v[44:47]
	s_waitcnt lgkmcnt(0)
	v_mfma_f32_16x16x32_bf16 v[24:27], v[4:7], v[0:3], v[24:27]
.LBB0_343:
	s_andn2_b64 vcc, exec, s[88:89]
	s_cbranch_vccnz .LBB0_345
	s_nop 0
	s_nop 0
	s_nop 0
	s_nop 0
	s_nop 0
	v_cvt_pk_bf16_f32 v0, v8, v9
	ds_read2_b64 v[4:7], v130 offset0:136 offset1:140
	v_cvt_pk_bf16_f32 v1, v10, v11
	v_cvt_pk_bf16_f32 v2, v12, v13
	v_bfe_u32 v3, v14, 16, 1
	v_add3_u32 v3, v14, v3, s33
	v_bfe_u32 v8, v15, 16, 1
	v_lshrrev_b32_e32 v3, 16, v3
	v_add3_u32 v8, v15, v8, s33
	v_and_or_b32 v3, v8, s63, v3
	s_waitcnt lgkmcnt(0)
	s_nop 0
	v_mfma_f32_16x16x32_bf16 v[44:47], v[4:7], v[0:3], v[44:47]
	ds_read2_b64 v[4:7], v129 offset0:168 offset1:172
	s_waitcnt lgkmcnt(0)
	v_mfma_f32_16x16x32_bf16 v[32:35], v[4:7], v[0:3], v[32:35]
	ds_read2_b64 v[4:7], v128 offset0:200 offset1:204
	s_waitcnt lgkmcnt(0)
	v_mfma_f32_16x16x32_bf16 v[28:31], v[4:7], v[0:3], v[28:31]
	ds_read2_b64 v[4:7], v95 offset0:136 offset1:140
	s_waitcnt lgkmcnt(0)
	v_mfma_f32_16x16x32_bf16 v[24:27], v[4:7], v[0:3], v[24:27]

; __device__ __forceinline__ unsigned pk2(float lo, float hi) { return f2bf(lo) | (f2bf(hi) << 16); }
; __device__ __forceinline__ void na_item(int item, const bf16* Z, const float* rpb, bf16* CC, LAS unsigned char* lds, int tid, int wave, int lane) {
;     ...
;     lrun += __shfl_xor(lrun, 16); lrun += __shfl_xor(lrun, 32);
;     const float il = 1.f / lrun;
;     bf16* op = CC + mq * D + 1280 + h * 64 + 4 * g;
; #pragma unroll
;     for (int nb = 0; nb < 4; ++nb) { u32x2 w; w.x = pk2(oacc[nb][0] * il, oacc[nb][1] * il); w.y = pk2(oacc[nb][2] * il, oacc[nb][3] * il); *(u32x2*)(op + nb * 16) = w; }
.LBB0_404:
	s_waitcnt vmcnt(2)
	v_and_b32_e32 v1, 64, v140
	v_xor_b32_e32 v0, 16, v140
	v_add_u32_e32 v1, 64, v1
	v_cmp_lt_i32_e32 vcc, v0, v1
	v_xor_b32_e32 v2, 32, v140
	s_nop 0
	v_cndmask_b32_e32 v0, v140, v0, vcc
	v_lshlrev_b32_e32 v0, 2, v0
	ds_bpermute_b32 v0, v0, v91
	v_cmp_lt_i32_e32 vcc, v2, v1
	s_waitcnt lgkmcnt(0)
	v_add_f32_e32 v0, v91, v0
	v_cndmask_b32_e32 v1, v140, v2, vcc
	v_lshlrev_b32_e32 v1, 2, v1
	ds_bpermute_b32 v1, v1, v0
	s_waitcnt lgkmcnt(0)
	v_add_f32_e32 v2, v0, v1
	v_div_scale_f32 v3, s[0:1], v2, v2, 1.0
	v_rcp_f32_e32 v4, v3
	v_div_scale_f32 v5, vcc, 1.0, v2, 1.0
	v_lshlrev_b64 v[0:1], 12, v[96:97]
	v_fma_f32 v6, -v3, v4, 1.0
	v_fmac_f32_e32 v4, v6, v4
	v_mul_f32_e32 v6, v5, v4
	v_fma_f32 v7, -v3, v6, v5
	v_fmac_f32_e32 v6, v7, v4
	v_fma_f32 v3, -v3, v6, v5
	v_div_fmas_f32 v3, v3, v4, v6
	v_div_fixup_f32 v2, v3, v2, 1.0
	v_mov_b32_e32 v4, v44
	v_mov_b32_e32 v5, v46
	v_pk_mul_f32 v[4:5], v[4:5], v[2:3] op_sel_hi:[1,0]
	v_mov_b32_e32 v46, v45
	v_pk_mul_f32 v[6:7], v[46:47], v[2:3] op_sel_hi:[1,0]
	v_and_b32_sdwa v3, v5, v139 dst_sel:DWORD dst_unused:UNUSED_PAD src0_sel:WORD_1 src1_sel:DWORD
	s_nop 0
	s_nop 0
	v_add3_u32 v3, v5, v3, s29
	v_and_b32_sdwa v5, v7, v139 dst_sel:DWORD dst_unused:UNUSED_PAD src0_sel:WORD_1 src1_sel:DWORD
	s_nop 0
	v_lshl_add_u64 v[0:1], s[30:31], 0, v[0:1]
	v_add3_u32 v5, v7, v5, s29
	s_nop 0
	v_lshl_add_u64 v[0:1], s[86:87], 1, v[0:1]
	v_and_b32_e32 v5, 0xffff0000, v5
	s_nop 0
	v_lshl_add_u64 v[0:1], v[74:75], 1, v[0:1]
	v_or_b32_sdwa v5, v5, v3 dst_sel:DWORD dst_unused:UNUSED_PAD src0_sel:DWORD src1_sel:WORD_1
	v_cvt_pk_bf16_f32 v4, v4, v6
	global_store_dwordx2 v[0:1], v[4:5], off offset:2560
	v_mov_b32_e32 v4, v40
	v_mov_b32_e32 v5, v42
	v_pk_mul_f32 v[4:5], v[4:5], v[2:3] op_sel_hi:[1,0]
	v_mov_b32_e32 v42, v41
	v_pk_mul_f32 v[6:7], v[42:43], v[2:3] op_sel_hi:[1,0]
	v_and_b32_sdwa v3, v5, v139 dst_sel:DWORD dst_unused:UNUSED_PAD src0_sel:WORD_1 src1_sel:DWORD
	s_nop 0
	s_nop 0
	v_add3_u32 v3, v5, v3, s29
	v_and_b32_sdwa v5, v7, v139 dst_sel:DWORD dst_unused:UNUSED_PAD src0_sel:WORD_1 src1_sel:DWORD
	s_nop 0
	v_add3_u32 v5, v7, v5, s29
	s_nop 0
	v_and_b32_e32 v5, 0xffff0000, v5
	s_nop 0
	v_or_b32_sdwa v5, v5, v3 dst_sel:DWORD dst_unused:UNUSED_PAD src0_sel:DWORD src1_sel:WORD_1
	v_cvt_pk_bf16_f32 v4, v4, v6
	global_store_dwordx2 v[0:1], v[4:5], off offset:2592
	v_mov_b32_e32 v4, v36
	v_mov_b32_e32 v5, v38
	v_pk_mul_f32 v[4:5], v[4:5], v[2:3] op_sel_hi:[1,0]
	v_mov_b32_e32 v38, v37
	v_pk_mul_f32 v[6:7], v[38:39], v[2:3] op_sel_hi:[1,0]
	v_and_b32_sdwa v3, v5, v139 dst_sel:DWORD dst_unused:UNUSED_PAD src0_sel:WORD_1 src1_sel:DWORD
	v_and_b32_sdwa v8, v4, v139 dst_sel:DWORD dst_unused:UNUSED_PAD src0_sel:WORD_1 src1_sel:DWORD
	v_add3_u32 v4, v4, v8, s29
	v_add3_u32 v3, v5, v3, s29
	v_and_b32_sdwa v5, v7, v139 dst_sel:DWORD dst_unused:UNUSED_PAD src0_sel:WORD_1 src1_sel:DWORD
	v_and_b32_sdwa v8, v6, v139 dst_sel:DWORD dst_unused:UNUSED_PAD src0_sel:WORD_1 src1_sel:DWORD
	v_add3_u32 v5, v7, v5, s29
	v_add3_u32 v6, v6, v8, s29
	v_and_b32_e32 v5, 0xffff0000, v5
	v_and_b32_e32 v6, 0xffff0000, v6
	v_or_b32_sdwa v5, v5, v3 dst_sel:DWORD dst_unused:UNUSED_PAD src0_sel:DWORD src1_sel:WORD_1
	v_or_b32_sdwa v4, v6, v4 dst_sel:DWORD dst_unused:UNUSED_PAD src0_sel:DWORD src1_sel:WORD_1
	global_store_dwordx2 v[0:1], v[4:5], off offset:2624
	v_mov_b32_e32 v4, v32
	v_mov_b32_e32 v5, v34
	v_pk_mul_f32 v[4:5], v[4:5], v[2:3] op_sel_hi:[1,0]
	v_mov_b32_e32 v34, v33
	v_pk_mul_f32 v[2:3], v[34:35], v[2:3] op_sel_hi:[1,0]
	v_and_b32_sdwa v6, v5, v139 dst_sel:DWORD dst_unused:UNUSED_PAD src0_sel:WORD_1 src1_sel:DWORD
	v_and_b32_sdwa v7, v4, v139 dst_sel:DWORD dst_unused:UNUSED_PAD src0_sel:WORD_1 src1_sel:DWORD
	v_add3_u32 v4, v4, v7, s29
	v_add3_u32 v5, v5, v6, s29
	v_and_b32_sdwa v6, v3, v139 dst_sel:DWORD dst_unused:UNUSED_PAD src0_sel:WORD_1 src1_sel:DWORD
	v_and_b32_sdwa v7, v2, v139 dst_sel:DWORD dst_unused:UNUSED_PAD src0_sel:WORD_1 src1_sel:DWORD
	v_add3_u32 v3, v3, v6, s29
	v_add3_u32 v2, v2, v7, s29
	v_and_b32_e32 v3, 0xffff0000, v3
	v_and_b32_e32 v2, 0xffff0000, v2
	v_or_b32_sdwa v3, v3, v5 dst_sel:DWORD dst_unused:UNUSED_PAD src0_sel:DWORD src1_sel:WORD_1
	v_or_b32_sdwa v2, v2, v4 dst_sel:DWORD dst_unused:UNUSED_PAD src0_sel:DWORD src1_sel:WORD_1
	global_store_dwordx2 v[0:1], v[2:3], off offset:2656

; __device__ __forceinline__ float gelu_f(float x) { const float y = 0.7978845608f * (x + 0.044715f * x * x * x); return 0.5f * x * (1.f + tanh_f(y)); }
; __device__ __forceinline__ void gmlp_item(int item, const bf16* Z, const bf16* gmws, const float* gmbs, bf16* CC, LAS unsigned char* lds, int tid, int wave, int lane) {
;     ...
;     const int cidx = item >> 3, gi = item & 7, fr = lane & 15, g = lane >> 4;
;     __syncthreads();
;     { const int j = tid >> 2, part = tid & 3; const bf16* zp = Z + (size_t)(cidx * 128 + j) * INCP + 512 + gi * 64 + 16 * part;
;       const u32x4 a = *(const u32x4*)zp, bq = *(const u32x4*)(zp + 8);
;       float x[16]; const unsigned w[8] = {a.x, a.y, a.z, a.w, bq.x, bq.y, bq.z, bq.w};
;       float s = 0.f;
; #pragma unroll
;       for (int e = 0; e < 8; ++e) { x[2 * e] = gelu_f(bflo(w[e])); x[2 * e + 1] = gelu_f(bfhi(w[e])); s += x[2 * e] + x[2 * e + 1]; }
;       s += __shfl_xor(s, 1); s += __shfl_xor(s, 2); const float mu = s * (1.f / 64.f); float s2 = 0.f;
.LBB0_406:
	s_cmpk_gt_i32 s83, 0x62f
	v_mbcnt_hi_u32_b32 v140, -1, v138
	s_mov_b64 s[4:5], -1
	s_cbranch_scc0 .LBB0_408
	s_lshl_b32 s0, s83, 4
	s_addk_i32 s0, 0x1d00
	s_and_b32 s0, s0, 0x7f80
	v_add_u32_e32 v0, s0, v69
	v_mul_u32_u24_e32 v0, 0x1800, v0
	v_lshlrev_b32_e32 v64, 1, v0
	s_lshl_b32 s1, s83, 7
	v_lshl_add_u64 v[0:1], s[34:35], 0, v[64:65]
	s_and_b32 s54, s1, 0x380
	v_lshl_add_u64 v[0:1], v[0:1], 0, s[54:55]
	v_mov_b32_e32 v91, v65
	v_lshl_add_u64 v[0:1], v[0:1], 0, v[90:91]
	s_barrier
	global_load_dwordx4 v[4:7], v[0:1], off offset:1024
	s_nop 0
	global_load_dwordx4 v[0:3], v[0:1], off offset:1040
	s_mov_b32 s1, 0x800000
	v_add_u32_e32 v64, s54, v73
	s_waitcnt vmcnt(1)
	v_lshlrev_b32_e32 v9, 16, v5
	v_lshlrev_b32_e32 v8, 16, v4
	v_and_b32_e32 v10, 0xffff0000, v4
	v_and_b32_e32 v11, 0xffff0000, v5
	v_mul_f32_e32 v16, 0x3d372713, v8
	v_mul_f32_e32 v18, 0x3d372713, v10
	v_mul_f32_e32 v20, 0x3d372713, v9
	v_lshlrev_b32_e32 v13, 16, v7
	v_lshlrev_b32_e32 v12, 16, v6
	v_and_b32_e32 v15, 0xffff0000, v7
	v_and_b32_e32 v14, 0xffff0000, v6
	v_mov_b32_e32 v17, v8
	v_mov_b32_e32 v19, v10
	v_mov_b32_e32 v21, v9
	v_pk_mul_f32 v[6:7], v[8:9], 0.5 op_sel_hi:[1,0]
	v_mul_f32_e32 v22, 0x3d372713, v11
	v_pk_mul_f32 v[4:5], v[10:11], 0.5 op_sel_hi:[1,0]
	v_mul_f32_e32 v8, v16, v8
	v_mul_f32_e32 v10, v18, v10
	v_mul_f32_e32 v9, v20, v9
	v_mov_b32_e32 v23, v11
	v_mul_f32_e32 v11, v22, v11
	v_fmac_f32_e32 v17, v8, v17
	v_fmac_f32_e32 v19, v10, v19
	v_fmac_f32_e32 v21, v9, v21
	v_fmac_f32_e32 v23, v11, v23
	v_mul_f32_e32 v8, 0x3f4c422a, v17
	v_mul_f32_e32 v9, 0x3f4c422a, v19
	v_mul_f32_e32 v10, 0x3f4c422a, v21
	v_mul_f32_e32 v11, 0x3f4c422a, v23
	v_add_f32_e32 v8, v8, v8
	v_add_f32_e32 v9, v9, v9
	v_add_f32_e32 v10, v10, v10
	v_mul_f32_e32 v24, 0x3d372713, v12
	v_mul_f32_e32 v26, 0x3d372713, v14
	v_mul_f32_e32 v28, 0x3d372713, v13
	v_add_f32_e32 v11, v11, v11
	v_mul_f32_e32 v8, 0x3fb8aa3b, v8
	v_mul_f32_e32 v9, 0x3fb8aa3b, v9
	v_mul_f32_e32 v10, 0x3fb8aa3b, v10
	v_mov_b32_e32 v25, v12
	v_mov_b32_e32 v27, v14
	v_mov_b32_e32 v29, v13
	v_mul_f32_e32 v16, v24, v12
	v_mul_f32_e32 v18, v26, v14
	v_mul_f32_e32 v20, v28, v13
	v_mul_f32_e32 v11, 0x3fb8aa3b, v11
	v_exp_f32_e32 v8, v8
	v_exp_f32_e32 v9, v9
	v_exp_f32_e32 v10, v10
	v_fmac_f32_e32 v25, v16, v25
	v_fmac_f32_e32 v27, v18, v27
	v_fmac_f32_e32 v29, v20, v29
	v_exp_f32_e32 v11, v11
	v_mul_f32_e32 v16, 0x3f4c422a, v25
	v_mul_f32_e32 v17, 0x3f4c422a, v27
	v_mul_f32_e32 v18, 0x3f4c422a, v29
	v_add_f32_e32 v16, v16, v16
	v_add_f32_e32 v17, v17, v17
	v_add_f32_e32 v18, v18, v18
	v_mul_f32_e32 v30, 0x3d372713, v15
	v_mul_f32_e32 v16, 0x3fb8aa3b, v16
	v_mul_f32_e32 v17, 0x3fb8aa3b, v17
	v_mul_f32_e32 v18, 0x3fb8aa3b, v18
	v_add_f32_e32 v8, 1.0, v8
	v_add_f32_e32 v9, 1.0, v9
	v_add_f32_e32 v20, 1.0, v10
	v_mov_b32_e32 v31, v15
	v_mul_f32_e32 v22, v30, v15
	v_exp_f32_e32 v16, v16
	v_exp_f32_e32 v17, v17
	v_exp_f32_e32 v18, v18
	v_add_f32_e32 v11, 1.0, v11
	v_rcp_f32_e32 v8, v8
	v_rcp_f32_e32 v10, v9
	v_rcp_f32_e32 v9, v20
	v_fmac_f32_e32 v31, v22, v31
	v_rcp_f32_e32 v11, v11
	v_mul_f32_e32 v19, 0x3f4c422a, v31
	v_add_f32_e32 v19, v19, v19
	v_mul_f32_e32 v19, 0x3fb8aa3b, v19
	v_add_f32_e32 v16, 1.0, v16
	v_add_f32_e32 v21, 1.0, v17
	v_add_f32_e32 v17, 1.0, v18
	v_pk_fma_f32 v[8:9], v[8:9], 2.0, 1.0 op_sel_hi:[1,0,0] neg_lo:[1,0,0] neg_hi:[1,0,0]
	v_rcp_f32_e32 v16, v16
	v_rcp_f32_e32 v17, v17
	v_pk_fma_f32 v[10:11], v[10:11], 2.0, 1.0 op_sel_hi:[1,0,0] neg_lo:[1,0,0] neg_hi:[1,0,0]
	v_pk_add_f32 v[8:9], v[8:9], 1.0 op_sel_hi:[1,0]
	v_exp_f32_e32 v19, v19
	v_pk_add_f32 v[10:11], v[10:11], 1.0 op_sel_hi:[1,0]
	v_pk_mul_f32 v[8:9], v[6:7], v[8:9]
	v_rcp_f32_e32 v18, v21
	v_pk_fma_f32 v[6:7], v[4:5], v[10:11], v[8:9]
	s_waitcnt vmcnt(0)
	v_lshlrev_b32_e32 v21, 16, v2
	v_add_f32_e32 v6, 0, v6
	v_add_f32_e32 v20, v7, v6
	v_pk_mul_f32 v[6:7], v[12:13], 0.5 op_sel_hi:[1,0]
	v_pk_fma_f32 v[12:13], v[16:17], 2.0, 1.0 op_sel_hi:[1,0,0] neg_lo:[1,0,0] neg_hi:[1,0,0]
	v_add_f32_e32 v16, 1.0, v19
	v_rcp_f32_e32 v19, v16
	v_pk_add_f32 v[12:13], v[12:13], 1.0 op_sel_hi:[1,0]
	v_lshlrev_b32_e32 v29, 16, v0
	v_pk_mul_f32 v[6:7], v[6:7], v[12:13]
	v_pk_mul_f32 v[12:13], v[14:15], 0.5 op_sel_hi:[1,0]
	v_pk_fma_f32 v[14:15], v[18:19], 2.0, 1.0 op_sel_hi:[1,0,0] neg_lo:[1,0,0] neg_hi:[1,0,0]
	v_and_b32_e32 v28, 0xffff0000, v0
	v_pk_add_f32 v[14:15], v[14:15], 1.0 op_sel_hi:[1,0]
	v_mul_f32_e32 v0, 0x3d372713, v29
	v_pk_fma_f32 v[16:17], v[12:13], v[14:15], v[6:7]
	v_mul_f32_e32 v0, v0, v29
	v_add_f32_e32 v16, v16, v20
	v_add_f32_e32 v36, v17, v16
	v_and_b32_e32 v17, 64, v140
	v_xor_b32_e32 v16, 1, v140
	v_add_u32_e32 v37, 64, v17
	v_cmp_lt_i32_e32 vcc, v16, v37
	v_lshlrev_b32_e32 v17, 16, v3
	v_mov_b32_e32 v18, v17
	v_cndmask_b32_e32 v16, v140, v16, vcc
	v_lshlrev_b32_e32 v38, 2, v16
	v_and_b32_e32 v16, 0xffff0000, v3
	v_mul_f32_e32 v3, 0x3d372713, v17
	v_mul_f32_e32 v3, v3, v17
	v_fmac_f32_e32 v18, v3, v18
	v_mul_f32_e32 v3, 0x3f4c422a, v18
	v_mul_f32_e32 v18, 0x3d372713, v16
	v_mul_f32_e32 v18, v18, v16
	v_mov_b32_e32 v19, v16
	v_fmac_f32_e32 v19, v18, v19
	v_add_f32_e32 v3, v3, v3
	v_mul_f32_e32 v18, 0x3f4c422a, v19
	v_mul_f32_e32 v3, 0x3fb8aa3b, v3
	v_add_f32_e32 v18, v18, v18
	v_exp_f32_e32 v3, v3
	v_mul_f32_e32 v18, 0x3fb8aa3b, v18
	v_exp_f32_e32 v18, v18
	v_and_b32_e32 v20, 0xffff0000, v2
	v_add_f32_e32 v3, 1.0, v3
	v_rcp_f32_e32 v19, v3
	v_add_f32_e32 v3, 1.0, v18
	v_mul_f32_e32 v2, 0x3d372713, v21
	v_rcp_f32_e32 v18, v3
	v_mul_f32_e32 v2, v2, v21
	v_mov_b32_e32 v3, v21
	v_fmac_f32_e32 v3, v2, v3
	v_mul_f32_e32 v2, 0x3f4c422a, v3
	v_add_f32_e32 v2, v2, v2
	v_mul_f32_e32 v2, 0x3fb8aa3b, v2
	v_exp_f32_e32 v22, v2
; __device__ __forceinline__ float gelu_f(float x) { const float y = 0.7978845608f * (x + 0.044715f * x * x * x); return 0.5f * x * (1.f + tanh_f(y)); }
; __device__ __forceinline__ void gmlp_item(int item, const bf16* Z, const bf16* gmws, const float* gmbs, bf16* CC, LAS unsigned char* lds, int tid, int wave, int lane) {
;     ...
;       for (int e = 0; e < 8; ++e) { x[2 * e] = gelu_f(bflo(w[e])); x[2 * e + 1] = gelu_f(bfhi(w[e])); s += x[2 * e] + x[2 * e + 1]; }
;       s += __shfl_xor(s, 1); s += __shfl_xor(s, 2); const float mu = s * (1.f / 64.f); float s2 = 0.f;
; #pragma unroll
;       for (int e = 0; e < 16; ++e) { x[e] -= mu; s2 += x[e] * x[e]; }
;       s2 += __shfl_xor(s2, 1); s2 += __shfl_xor(s2, 2); const float rstd = rsqrtf(s2 * (1.f / 64.f) + LN_EPS);
	v_mul_f32_e32 v2, 0x3d372713, v20
	v_mul_f32_e32 v2, v2, v20
	v_mov_b32_e32 v3, v20
	v_fmac_f32_e32 v3, v2, v3
	v_mul_f32_e32 v2, 0x3f4c422a, v3
	v_add_f32_e32 v2, v2, v2
	v_mul_f32_e32 v2, 0x3fb8aa3b, v2
	v_exp_f32_e32 v23, v2
	v_pk_fma_f32 v[2:3], v[18:19], 2.0, 1.0 op_sel_hi:[1,0,0] neg_lo:[1,0,0] neg_hi:[1,0,0]
	v_add_f32_e32 v18, 1.0, v22
	v_rcp_f32_e32 v19, v18
	v_add_f32_e32 v18, 1.0, v23
	v_rcp_f32_e32 v18, v18
	v_pk_mul_f32 v[16:17], v[16:17], 0.5 op_sel_hi:[1,0]
	v_pk_add_f32 v[2:3], v[2:3], 1.0 op_sel_hi:[1,0]
	v_pk_mul_f32 v[20:21], v[20:21], 0.5 op_sel_hi:[1,0]
	v_pk_fma_f32 v[18:19], v[18:19], 2.0, 1.0 op_sel_hi:[1,0,0] neg_lo:[1,0,0] neg_hi:[1,0,0]
	v_pk_mul_f32 v[22:23], v[16:17], v[2:3]
	v_pk_add_f32 v[18:19], v[18:19], 1.0 op_sel_hi:[1,0]
	v_mov_b32_e32 v26, v22
	v_pk_mul_f32 v[24:25], v[20:21], v[18:19]
	v_pk_mul_f32 v[4:5], v[4:5], v[10:11]
	v_mov_b32_e32 v27, v24
	v_mov_b32_e32 v24, v23
	v_pk_add_f32 v[22:23], v[26:27], v[24:25]
	v_lshlrev_b32_e32 v25, 16, v1
	v_and_b32_e32 v24, 0xffff0000, v1
	v_mul_f32_e32 v1, 0x3d372713, v25
	v_mul_f32_e32 v1, v1, v25
	v_mov_b32_e32 v26, v25
	v_fmac_f32_e32 v26, v1, v26
	v_mul_f32_e32 v1, 0x3f4c422a, v26
	v_mul_f32_e32 v26, 0x3d372713, v24
	v_mul_f32_e32 v26, v26, v24
	v_mov_b32_e32 v27, v24
	v_fmac_f32_e32 v27, v26, v27
	v_add_f32_e32 v1, v1, v1
	v_mul_f32_e32 v26, 0x3f4c422a, v27
	v_mul_f32_e32 v1, 0x3fb8aa3b, v1
	v_add_f32_e32 v26, v26, v26
	v_exp_f32_e32 v1, v1
	v_mul_f32_e32 v26, 0x3fb8aa3b, v26
	v_exp_f32_e32 v26, v26
	v_pk_mul_f32 v[24:25], v[24:25], 0.5 op_sel_hi:[1,0]
	v_add_f32_e32 v1, 1.0, v1
	v_rcp_f32_e32 v27, v1
	v_add_f32_e32 v1, 1.0, v26
	v_rcp_f32_e32 v26, v1
	v_mov_b32_e32 v1, v29
	v_fmac_f32_e32 v1, v0, v1
	v_mul_f32_e32 v0, 0x3f4c422a, v1
	v_add_f32_e32 v0, v0, v0
	v_mul_f32_e32 v0, 0x3fb8aa3b, v0
	v_exp_f32_e32 v30, v0
	v_mul_f32_e32 v0, 0x3d372713, v28
	v_mul_f32_e32 v0, v0, v28
	v_mov_b32_e32 v1, v28
	v_fmac_f32_e32 v1, v0, v1
	v_mul_f32_e32 v0, 0x3f4c422a, v1
	v_add_f32_e32 v0, v0, v0
	v_mul_f32_e32 v0, 0x3fb8aa3b, v0
	v_exp_f32_e32 v31, v0
	v_pk_fma_f32 v[0:1], v[26:27], 2.0, 1.0 op_sel_hi:[1,0,0] neg_lo:[1,0,0] neg_hi:[1,0,0]
	v_add_f32_e32 v26, 1.0, v30
	v_rcp_f32_e32 v27, v26
	v_add_f32_e32 v26, 1.0, v31
	v_rcp_f32_e32 v26, v26
	v_pk_add_f32 v[0:1], v[0:1], 1.0 op_sel_hi:[1,0]
	v_pk_mul_f32 v[28:29], v[28:29], 0.5 op_sel_hi:[1,0]
	v_pk_mul_f32 v[30:31], v[24:25], v[0:1]
	v_pk_fma_f32 v[26:27], v[26:27], 2.0, 1.0 op_sel_hi:[1,0,0] neg_lo:[1,0,0] neg_hi:[1,0,0]
	v_mov_b32_e32 v34, v30
	v_pk_add_f32 v[26:27], v[26:27], 1.0 op_sel_hi:[1,0]
	v_pk_mul_f32 v[10:11], v[12:13], v[14:15]
	v_pk_mul_f32 v[32:33], v[28:29], v[26:27]
	s_nop 0
	v_mov_b32_e32 v35, v32
	v_mov_b32_e32 v32, v31
	v_pk_add_f32 v[30:31], v[34:35], v[32:33]
	s_nop 0
	v_add_f32_e32 v31, v31, v36
	v_add_f32_e32 v30, v30, v31
	v_add_f32_e32 v23, v23, v30
	v_add_f32_e32 v22, v22, v23
	ds_bpermute_b32 v23, v38, v22
	v_xor_b32_e32 v30, 2, v140
	v_cmp_lt_i32_e32 vcc, v30, v37
	s_waitcnt lgkmcnt(0)
	v_add_f32_e32 v22, v22, v23
	v_cndmask_b32_e32 v30, v140, v30, vcc
	v_lshlrev_b32_e32 v30, 2, v30
	ds_bpermute_b32 v23, v30, v22
	s_waitcnt lgkmcnt(0)
	v_add_f32_e32 v13, v22, v23
	v_fmamk_f32 v4, v13, 0xbc800000, v4
	v_fmamk_f32 v8, v13, 0xbc800000, v8
	v_mul_f32_e32 v31, v4, v4
	v_fmac_f32_e32 v31, v8, v8
	v_fmac_f32_e32 v9, 0xbc800000, v13
	v_fmac_f32_e32 v31, v9, v9
	v_fmac_f32_e32 v5, 0xbc800000, v13
	v_fmac_f32_e32 v31, v5, v5
	v_fmamk_f32 v6, v13, 0xbc800000, v6
	v_fmac_f32_e32 v31, v6, v6
	v_fmamk_f32 v10, v13, 0xbc800000, v10
	v_mul_f32_e32 v12, 0x3c800000, v13
	v_fmac_f32_e32 v31, v10, v10
	v_fmac_f32_e32 v7, 0xbc800000, v13
	v_fmac_f32_e32 v31, v7, v7
	v_fmac_f32_e32 v11, 0xbc800000, v13
	v_pk_fma_f32 v[14:15], v[28:29], v[26:27], v[12:13] op_sel_hi:[1,1,0] neg_lo:[0,0,1] neg_hi:[0,0,1]
	v_fmac_f32_e32 v31, v11, v11
	v_pk_mul_f32 v[22:23], v[14:15], v[14:15]
	s_nop 0
	v_add_f32_e32 v13, v23, v31
	v_add_f32_e32 v13, v22, v13
	v_pk_fma_f32 v[0:1], v[24:25], v[0:1], v[12:13] op_sel_hi:[1,1,0] neg_lo:[0,0,1] neg_hi:[0,0,1]
	s_nop 0
	v_pk_mul_f32 v[22:23], v[0:1], v[0:1]
	s_nop 0
	v_add_f32_e32 v13, v23, v13
	v_add_f32_e32 v13, v22, v13
	v_pk_fma_f32 v[18:19], v[20:21], v[18:19], v[12:13] op_sel_hi:[1,1,0] neg_lo:[0,0,1] neg_hi:[0,0,1]
	s_nop 0
	v_pk_mul_f32 v[20:21], v[18:19], v[18:19]
	s_nop 0
	v_add_f32_e32 v13, v21, v13
	v_pk_fma_f32 v[2:3], v[16:17], v[2:3], v[12:13] op_sel_hi:[1,1,0] neg_lo:[0,0,1] neg_hi:[0,0,1]
	v_add_f32_e32 v20, v20, v13
	v_pk_mul_f32 v[12:13], v[2:3], v[2:3]
	s_nop 0
	v_add_f32_e32 v13, v13, v20
	v_add_f32_e32 v12, v12, v13
	ds_bpermute_b32 v13, v38, v12
	s_waitcnt lgkmcnt(0)
	v_add_f32_e32 v12, v12, v13
	ds_bpermute_b32 v13, v30, v12
	s_waitcnt lgkmcnt(0)
; #define LAS __attribute__((address_space(3)))
; __device__ __forceinline__ unsigned f2bf(float f) { unsigned u = __builtin_bit_cast(unsigned, f); return (u + 0x7fffu + ((u >> 16) & 1u)) >> 16; }
; #define MFMA16(a, b, c) __builtin_amdgcn_mfma_f32_16x16x32_bf16((a), (b), (c), 0, 0, 0)
; __device__ __forceinline__ f32x4 bf4(u32x2 w) { return (f32x4){bflo(w.x), bfhi(w.x), bflo(w.y), bfhi(w.y)}; }
; __device__ __forceinline__ void gmlp_item(int item, const bf16* Z, const bf16* gmws, const float* gmbs, bf16* CC, LAS unsigned char* lds, int tid, int wave, int lane) {
;     ...
;       s2 += __shfl_xor(s2, 1); s2 += __shfl_xor(s2, 2); const float rstd = rsqrtf(s2 * (1.f / 64.f) + LN_EPS);
; #pragma unroll
;       for (int e = 0; e < 16; ++e) vt[(16 * part + e) * VSTR + j] = (bf16)f2bf(x[e] * rstd); }
;     __syncthreads();
;     f32x4 acc[4];
; #pragma unroll
;     for (int nb = 0; nb < 4; ++nb) acc[nb] = (f32x4){0.f, 0.f, 0.f, 0.f};
;     const int i = wave * 16 + fr;
; #pragma unroll
;     for (int ks = 0; ks < 4; ++ks) { const bf16x8 wf = *(const bf16x8*)(gmws + (size_t)(gi * 128 + i) * 128 + 32 * ks + 8 * g);
; #pragma unroll
;         for (int nb = 0; nb < 4; ++nb) { const bf16x8 vf = *(const LAS bf16x8*)(vt + (nb * 16 + fr) * VSTR + 32 * ks + 8 * g); acc[nb] = MFMA16(vf, wf, acc[nb]); } }
;     const float bs = gmbs[gi * 128 + i];
;     const size_t m = (size_t)cidx * 128 + i;
; #pragma unroll
;     for (int nb = 0; nb < 4; ++nb) { const int c = nb * 16 + 4 * g; const f32x4 u = bf4(*(const u32x2*)(Z + m * INCP + gi * 64 + c));
	v_add_f32_e32 v12, v12, v13
	v_fmamk_f32 v12, v12, 0x3c800000, v133
	v_mul_f32_e32 v13, 0x4b800000, v12
	v_cmp_gt_f32_e32 vcc, s1, v12
	s_nop 1
	v_cndmask_b32_e32 v12, v12, v13, vcc
	v_rsq_f32_e32 v12, v12
	s_nop 0
	v_mul_f32_e32 v13, 0x45800000, v12
	v_cndmask_b32_e32 v12, v12, v13, vcc
	v_mul_f32_e32 v8, v8, v12
	v_bfe_u32 v13, v8, 16, 1
	v_add3_u32 v8, v8, v13, s29
	v_mul_f32_e32 v4, v4, v12
	ds_write_b16_d16_hi v134, v8
	v_bfe_u32 v8, v4, 16, 1
	v_add3_u32 v4, v4, v8, s29
	ds_write_b16_d16_hi v134, v4 offset:272
	v_mul_f32_e32 v4, v9, v12
	v_bfe_u32 v8, v4, 16, 1
	v_add3_u32 v4, v4, v8, s29
	ds_write_b16_d16_hi v134, v4 offset:544
	v_mul_f32_e32 v4, v5, v12
	v_bfe_u32 v5, v4, 16, 1
	v_add3_u32 v4, v4, v5, s29
	ds_write_b16_d16_hi v134, v4 offset:816
	v_mul_f32_e32 v4, v6, v12
	v_bfe_u32 v5, v4, 16, 1
	v_add3_u32 v4, v4, v5, s29
	ds_write_b16_d16_hi v134, v4 offset:1088
	v_mul_f32_e32 v4, v10, v12
	v_bfe_u32 v5, v4, 16, 1
	v_add3_u32 v4, v4, v5, s29
	ds_write_b16_d16_hi v134, v4 offset:1360
	v_mul_f32_e32 v4, v7, v12
	v_bfe_u32 v5, v4, 16, 1
	v_add3_u32 v4, v4, v5, s29
	ds_write_b16_d16_hi v134, v4 offset:1632
	v_mul_f32_e32 v4, v11, v12
	v_bfe_u32 v5, v4, 16, 1
	v_add3_u32 v4, v4, v5, s29
	ds_write_b16_d16_hi v134, v4 offset:1904
	v_mul_f32_e32 v4, v15, v12
	v_bfe_u32 v5, v4, 16, 1
	v_add3_u32 v4, v4, v5, s29
	ds_write_b16_d16_hi v134, v4 offset:2176
	v_mul_f32_e32 v4, v14, v12
	v_bfe_u32 v5, v4, 16, 1
	v_add3_u32 v4, v4, v5, s29
	v_mul_f32_e32 v1, v1, v12
	ds_write_b16_d16_hi v134, v4 offset:2448
	v_bfe_u32 v4, v1, 16, 1
	v_add3_u32 v1, v1, v4, s29
	v_mul_f32_e32 v0, v0, v12
	ds_write_b16_d16_hi v134, v1 offset:2720
	v_bfe_u32 v1, v0, 16, 1
	v_add3_u32 v0, v0, v1, s29
	ds_write_b16_d16_hi v134, v0 offset:2992
	v_mul_f32_e32 v0, v19, v12
	v_bfe_u32 v1, v0, 16, 1
	v_add3_u32 v0, v0, v1, s29
	ds_write_b16_d16_hi v134, v0 offset:3264
	v_mul_f32_e32 v0, v18, v12
	v_bfe_u32 v1, v0, 16, 1
	v_add3_u32 v0, v0, v1, s29
	ds_write_b16_d16_hi v134, v0 offset:3536
	v_mul_f32_e32 v0, v3, v12
	v_bfe_u32 v1, v0, 16, 1
	v_add3_u32 v0, v0, v1, s29
	ds_write_b16_d16_hi v134, v0 offset:3808
	v_mul_f32_e32 v0, v2, v12
	v_bfe_u32 v1, v0, 16, 1
	v_add3_u32 v0, v0, v1, s29
	ds_write_b16_d16_hi v134, v0 offset:4080
	v_lshlrev_b64 v[0:1], 8, v[64:65]
	v_lshl_add_u64 v[40:41], v[66:67], 0, v[0:1]
	s_waitcnt lgkmcnt(0)
	s_barrier
	global_load_dwordx4 v[0:3], v[40:41], off
	global_load_dwordx4 v[4:7], v[40:41], off offset:64
	ds_read_b128 v[8:11], v135
	ds_read_b128 v[12:15], v135 offset:64
	ds_read_b128 v[16:19], v135 offset:4352
	ds_read_b128 v[20:23], v135 offset:4416
	s_waitcnt vmcnt(1) lgkmcnt(3)
	v_mfma_f32_16x16x32_bf16 v[8:11], v[8:11], v[0:3], 0
	ds_read_b128 v[24:27], v135 offset:8704
	ds_read_b128 v[28:31], v135 offset:8768
	ds_read_b128 v[32:35], v136
	ds_read_b128 v[36:39], v136 offset:64
	s_waitcnt lgkmcnt(5)
	v_mfma_f32_16x16x32_bf16 v[16:19], v[16:19], v[0:3], 0
	s_waitcnt vmcnt(0)
	v_mfma_f32_16x16x32_bf16 v[8:11], v[12:15], v[4:7], v[8:11]
	s_waitcnt lgkmcnt(4)
	v_mfma_f32_16x16x32_bf16 v[12:15], v[20:23], v[4:7], v[16:19]
	s_nop 3
	global_load_dwordx4 v[16:19], v[40:41], off offset:128
	s_waitcnt lgkmcnt(3)
	v_mfma_f32_16x16x32_bf16 v[24:27], v[24:27], v[0:3], 0
	s_waitcnt lgkmcnt(2)
	v_mfma_f32_16x16x32_bf16 v[20:23], v[28:31], v[4:7], v[24:27]
	global_load_dwordx4 v[28:31], v[40:41], off offset:192
	s_waitcnt lgkmcnt(1)
	v_mfma_f32_16x16x32_bf16 v[0:3], v[32:35], v[0:3], 0
	s_waitcnt lgkmcnt(0)
	v_mfma_f32_16x16x32_bf16 v[0:3], v[36:39], v[4:7], v[0:3]
	ds_read_b128 v[4:7], v135 offset:128
	ds_read_b128 v[24:27], v135 offset:192
	s_waitcnt vmcnt(1) lgkmcnt(1)
	v_mfma_f32_16x16x32_bf16 v[4:7], v[4:7], v[16:19], v[8:11]
	s_nop 2
	ds_read_b128 v[8:11], v135 offset:4480
	ds_read_b128 v[32:35], v135 offset:4544
	s_waitcnt lgkmcnt(1)
	v_mfma_f32_16x16x32_bf16 v[8:11], v[8:11], v[16:19], v[12:15]
	s_nop 2
	ds_read_b128 v[12:15], v135 offset:8832
	ds_read_b128 v[36:39], v135 offset:8896
	s_waitcnt lgkmcnt(1)
	v_mfma_f32_16x16x32_bf16 v[40:43], v[12:15], v[16:19], v[20:23]
	ds_read_b128 v[12:15], v136 offset:128
	ds_read_b128 v[44:47], v136 offset:192
	s_nop 0
	v_lshlrev_b64 v[20:21], 1, v[74:75]
	s_waitcnt lgkmcnt(1)
	v_mfma_f32_16x16x32_bf16 v[0:3], v[12:15], v[16:19], v[0:3]
	v_lshl_add_u64 v[16:17], v[64:65], 2, s[36:37]
	v_add_u32_e32 v64, s0, v73
	global_load_dword v16, v[16:17], off
	s_waitcnt vmcnt(1)
	v_mfma_f32_16x16x32_bf16 v[12:15], v[24:27], v[28:31], v[4:7]
	v_lshlrev_b64 v[18:19], 12, v[64:65]
	v_lshl_add_u64 v[18:19], s[30:31], 0, v[18:19]
	v_lshl_add_u64 v[18:19], v[18:19], 0, s[54:55]
	v_mov_b64_e32 v[4:5], s[34:35]
	v_mad_u64_u32 v[4:5], s[0:1], v64, s3, v[4:5]
	v_lshl_add_u64 v[24:25], v[4:5], 0, s[54:55]
	v_lshl_add_u64 v[26:27], v[24:25], 0, v[20:21]
	global_load_dwordx2 v[22:23], v[26:27], off
	v_mfma_f32_16x16x32_bf16 v[8:11], v[32:35], v[28:31], v[8:11]
	v_lshl_add_u64 v[24:25], v[24:25], 0, v[92:93]
	v_mfma_f32_16x16x32_bf16 v[4:7], v[36:39], v[28:31], v[40:43]
	s_waitcnt lgkmcnt(0)
	v_mfma_f32_16x16x32_bf16 v[0:3], v[44:47], v[28:31], v[0:3]
	global_load_dwordx2 v[28:29], v[26:27], off offset:32
	s_nop 0
	global_load_dwordx2 v[26:27], v[26:27], off offset:64
	s_nop 0
	global_load_dwordx2 v[24:25], v[24:25], off
	s_waitcnt vmcnt(3)
; __device__ __forceinline__ unsigned pk2(float lo, float hi) { return f2bf(lo) | (f2bf(hi) << 16); }
; __device__ __forceinline__ float gelu_f(float x) { const float y = 0.7978845608f * (x + 0.044715f * x * x * x); return 0.5f * x * (1.f + tanh_f(y)); }
; __device__ __forceinline__ f32x4 bf4(u32x2 w) { return (f32x4){bflo(w.x), bfhi(w.x), bflo(w.y), bfhi(w.y)}; }
; __device__ __forceinline__ void gmlp_item(int item, const bf16* Z, const bf16* gmws, const float* gmbs, bf16* CC, LAS unsigned char* lds, int tid, int wave, int lane) {
;     ...
;     for (int nb = 0; nb < 4; ++nb) { const int c = nb * 16 + 4 * g; const f32x4 u = bf4(*(const u32x2*)(Z + m * INCP + gi * 64 + c));
;         u32x2 w; w.x = pk2(gelu_f(u.x) * (acc[nb][0] + bs), gelu_f(u.y) * (acc[nb][1] + bs)); w.y = pk2(gelu_f(u.z) * (acc[nb][2] + bs), gelu_f(u.w) * (acc[nb][3] + bs));
;         *(u32x2*)(CC + m * D + gi * 64 + c) = w; }
	v_lshlrev_b32_e32 v30, 16, v22
	v_mul_f32_e32 v17, 0x3d372713, v30
	v_and_b32_e32 v22, 0xffff0000, v22
	v_mul_f32_e32 v17, v17, v30
	v_mov_b32_e32 v31, v30
	v_mul_f32_e32 v32, 0x3d372713, v22
	v_fmac_f32_e32 v31, v17, v31
	v_mul_f32_e32 v32, v32, v22
	v_mov_b32_e32 v33, v22
	v_mul_f32_e32 v17, 0x3f4c422a, v31
	v_lshlrev_b32_e32 v31, 16, v23
	v_fmac_f32_e32 v33, v32, v33
	v_mul_f32_e32 v32, 0x3f4c422a, v33
	v_mul_f32_e32 v33, 0x3d372713, v31
	v_mul_f32_e32 v33, v33, v31
	v_mov_b32_e32 v34, v31
	v_fmac_f32_e32 v34, v33, v34
	v_add_f32_e32 v17, v17, v17
	v_mul_f32_e32 v33, 0x3f4c422a, v34
	v_mul_f32_e32 v17, 0x3fb8aa3b, v17
	v_add_f32_e32 v33, v33, v33
	v_exp_f32_e32 v17, v17
	v_add_f32_e32 v32, v32, v32
	v_mul_f32_e32 v33, 0x3fb8aa3b, v33
	v_exp_f32_e32 v33, v33
	v_mul_f32_e32 v32, 0x3fb8aa3b, v32
	v_exp_f32_e32 v34, v32
	v_add_f32_e32 v17, 1.0, v17
	v_rcp_f32_e32 v32, v17
	v_add_f32_e32 v17, 1.0, v33
	v_and_b32_e32 v23, 0xffff0000, v23
	v_rcp_f32_e32 v33, v17
	v_add_f32_e32 v17, 1.0, v34
	v_rcp_f32_e32 v34, v17
	v_mul_f32_e32 v17, 0x3d372713, v23
	v_mul_f32_e32 v17, v17, v23
	v_mov_b32_e32 v35, v23
	v_fmac_f32_e32 v35, v17, v35
	v_mul_f32_e32 v17, 0x3f4c422a, v35
	v_add_f32_e32 v17, v17, v17
	v_mul_f32_e32 v17, 0x3fb8aa3b, v17
	v_exp_f32_e32 v17, v17
	v_pk_fma_f32 v[32:33], v[32:33], 2.0, 1.0 op_sel_hi:[1,0,0] neg_lo:[1,0,0] neg_hi:[1,0,0]
	v_pk_mul_f32 v[30:31], v[30:31], 0.5 op_sel_hi:[1,0]
	v_pk_add_f32 v[32:33], v[32:33], 1.0 op_sel_hi:[1,0]
	v_pk_mul_f32 v[22:23], v[22:23], 0.5 op_sel_hi:[1,0]
	v_pk_mul_f32 v[30:31], v[30:31], v[32:33]
	v_mov_b32_e32 v32, v12
	v_add_f32_e32 v12, 1.0, v17
	v_rcp_f32_e32 v35, v12
	v_mov_b32_e32 v33, v14
	v_pk_add_f32 v[32:33], v[32:33], v[16:17] op_sel_hi:[1,0]
	v_mov_b32_e32 v14, v13
	v_pk_mul_f32 v[30:31], v[32:33], v[30:31]
	v_pk_fma_f32 v[32:33], v[34:35], 2.0, 1.0 op_sel_hi:[1,0,0] neg_lo:[1,0,0] neg_hi:[1,0,0]
	v_pk_add_f32 v[12:13], v[14:15], v[16:17] op_sel_hi:[1,0]
	v_pk_add_f32 v[32:33], v[32:33], 1.0 op_sel_hi:[1,0]
	v_pk_mul_f32 v[22:23], v[22:23], v[32:33]
	v_pk_mul_f32 v[12:13], v[12:13], v[22:23]
	s_nop 0
	s_nop 0
	s_nop 0
	s_nop 0
	s_nop 0
	s_nop 0
	v_cvt_pk_bf16_f32 v13, v31, v13
	v_cvt_pk_bf16_f32 v12, v30, v12
	v_lshl_add_u64 v[14:15], v[18:19], 0, v[20:21]
	global_store_dwordx2 v[14:15], v[12:13], off
	s_waitcnt vmcnt(3)
	v_lshlrev_b32_e32 v12, 16, v28
	v_mul_f32_e32 v13, 0x3d372713, v12
	v_mul_f32_e32 v13, v13, v12
	v_mov_b32_e32 v17, v12
	v_fmac_f32_e32 v17, v13, v17
	v_mul_f32_e32 v13, 0x3f4c422a, v17
	v_and_b32_e32 v20, 0xffff0000, v28
	v_add_f32_e32 v13, v13, v13
	v_mul_f32_e32 v22, 0x3d372713, v20
	v_mul_f32_e32 v13, 0x3fb8aa3b, v13
	v_mul_f32_e32 v22, v22, v20
	v_mov_b32_e32 v23, v20
	v_exp_f32_e32 v17, v13
	v_lshlrev_b32_e32 v13, 16, v29
	v_fmac_f32_e32 v23, v22, v23
	v_mul_f32_e32 v22, 0x3f4c422a, v23
	v_mul_f32_e32 v23, 0x3d372713, v13
	v_mul_f32_e32 v23, v23, v13
	v_mov_b32_e32 v28, v13
	v_fmac_f32_e32 v28, v23, v28
	v_mul_f32_e32 v23, 0x3f4c422a, v28
	v_add_f32_e32 v23, v23, v23
	v_add_f32_e32 v22, v22, v22
	v_mul_f32_e32 v23, 0x3fb8aa3b, v23
	v_exp_f32_e32 v23, v23
	v_mul_f32_e32 v22, 0x3fb8aa3b, v22
	v_exp_f32_e32 v28, v22
	v_add_f32_e32 v17, 1.0, v17
	v_rcp_f32_e32 v22, v17
	v_add_f32_e32 v17, 1.0, v23
	v_and_b32_e32 v21, 0xffff0000, v29
	v_rcp_f32_e32 v23, v17
	v_add_f32_e32 v17, 1.0, v28
	v_rcp_f32_e32 v28, v17
	v_mul_f32_e32 v17, 0x3d372713, v21
	v_mul_f32_e32 v17, v17, v21
	v_mov_b32_e32 v29, v21
	v_fmac_f32_e32 v29, v17, v29
	v_mul_f32_e32 v17, 0x3f4c422a, v29
	v_add_f32_e32 v17, v17, v17
	v_mul_f32_e32 v17, 0x3fb8aa3b, v17
	v_exp_f32_e32 v17, v17
	v_pk_fma_f32 v[22:23], v[22:23], 2.0, 1.0 op_sel_hi:[1,0,0] neg_lo:[1,0,0] neg_hi:[1,0,0]
	v_pk_mul_f32 v[12:13], v[12:13], 0.5 op_sel_hi:[1,0]
	v_pk_add_f32 v[22:23], v[22:23], 1.0 op_sel_hi:[1,0]
	v_pk_mul_f32 v[20:21], v[20:21], 0.5 op_sel_hi:[1,0]
	v_pk_mul_f32 v[12:13], v[12:13], v[22:23]
	v_mov_b32_e32 v22, v8
	v_add_f32_e32 v8, 1.0, v17
	v_rcp_f32_e32 v29, v8
	v_mov_b32_e32 v23, v10
	v_pk_add_f32 v[22:23], v[22:23], v[16:17] op_sel_hi:[1,0]
	v_mov_b32_e32 v10, v9
	v_pk_mul_f32 v[12:13], v[22:23], v[12:13]
	v_pk_fma_f32 v[22:23], v[28:29], 2.0, 1.0 op_sel_hi:[1,0,0] neg_lo:[1,0,0] neg_hi:[1,0,0]
	v_pk_add_f32 v[8:9], v[10:11], v[16:17] op_sel_hi:[1,0]
	v_pk_add_f32 v[22:23], v[22:23], 1.0 op_sel_hi:[1,0]
	v_and_b32_sdwa v10, v13, v139 dst_sel:DWORD dst_unused:UNUSED_PAD src0_sel:WORD_1 src1_sel:DWORD
	v_pk_mul_f32 v[20:21], v[20:21], v[22:23]
	v_and_b32_sdwa v11, v12, v139 dst_sel:DWORD dst_unused:UNUSED_PAD src0_sel:WORD_1 src1_sel:DWORD
	v_pk_mul_f32 v[8:9], v[8:9], v[20:21]
	v_add3_u32 v11, v12, v11, s29
	v_add3_u32 v10, v13, v10, s29
	v_and_b32_sdwa v12, v9, v139 dst_sel:DWORD dst_unused:UNUSED_PAD src0_sel:WORD_1 src1_sel:DWORD
	v_and_b32_sdwa v13, v8, v139 dst_sel:DWORD dst_unused:UNUSED_PAD src0_sel:WORD_1 src1_sel:DWORD
	v_add3_u32 v9, v9, v12, s29
	v_add3_u32 v8, v8, v13, s29
	v_and_b32_e32 v9, 0xffff0000, v9
	v_and_b32_e32 v8, 0xffff0000, v8
	v_or_b32_sdwa v9, v9, v10 dst_sel:DWORD dst_unused:UNUSED_PAD src0_sel:DWORD src1_sel:WORD_1
	v_or_b32_sdwa v8, v8, v11 dst_sel:DWORD dst_unused:UNUSED_PAD src0_sel:DWORD src1_sel:WORD_1
	global_store_dwordx2 v[14:15], v[8:9], off offset:32
	s_waitcnt vmcnt(3)
; __device__ __forceinline__ unsigned pk2(float lo, float hi) { return f2bf(lo) | (f2bf(hi) << 16); }
; __device__ __forceinline__ float gelu_f(float x) { const float y = 0.7978845608f * (x + 0.044715f * x * x * x); return 0.5f * x * (1.f + tanh_f(y)); }
; __device__ __forceinline__ f32x4 bf4(u32x2 w) { return (f32x4){bflo(w.x), bfhi(w.x), bflo(w.y), bfhi(w.y)}; }
; __device__ __forceinline__ void gmlp_item(int item, const bf16* Z, const bf16* gmws, const float* gmbs, bf16* CC, LAS unsigned char* lds, int tid, int wave, int lane) {
;     ...
;     for (int nb = 0; nb < 4; ++nb) { const int c = nb * 16 + 4 * g; const f32x4 u = bf4(*(const u32x2*)(Z + m * INCP + gi * 64 + c));
;         u32x2 w; w.x = pk2(gelu_f(u.x) * (acc[nb][0] + bs), gelu_f(u.y) * (acc[nb][1] + bs)); w.y = pk2(gelu_f(u.z) * (acc[nb][2] + bs), gelu_f(u.w) * (acc[nb][3] + bs));
;         *(u32x2*)(CC + m * D + gi * 64 + c) = w; }
	v_lshlrev_b32_e32 v8, 16, v26
	v_mul_f32_e32 v9, 0x3d372713, v8
	v_mul_f32_e32 v9, v9, v8
	v_mov_b32_e32 v10, v8
	v_fmac_f32_e32 v10, v9, v10
	v_mul_f32_e32 v9, 0x3f4c422a, v10
	v_and_b32_e32 v10, 0xffff0000, v26
	v_add_f32_e32 v9, v9, v9
	v_mul_f32_e32 v13, 0x3d372713, v10
	v_mul_f32_e32 v9, 0x3fb8aa3b, v9
	v_mul_f32_e32 v13, v13, v10
	v_mov_b32_e32 v17, v10
	v_exp_f32_e32 v12, v9
	v_lshlrev_b32_e32 v9, 16, v27
	v_fmac_f32_e32 v17, v13, v17
	v_mul_f32_e32 v13, 0x3f4c422a, v17
	v_mul_f32_e32 v17, 0x3d372713, v9
	v_mul_f32_e32 v17, v17, v9
	v_mov_b32_e32 v20, v9
	v_fmac_f32_e32 v20, v17, v20
	v_mul_f32_e32 v17, 0x3f4c422a, v20
	v_add_f32_e32 v13, v13, v13
	v_add_f32_e32 v17, v17, v17
	v_mul_f32_e32 v17, 0x3fb8aa3b, v17
	v_mul_f32_e32 v13, 0x3fb8aa3b, v13
	v_exp_f32_e32 v17, v17
	v_exp_f32_e32 v20, v13
	v_and_b32_e32 v11, 0xffff0000, v27
	v_mov_b32_e32 v21, v11
	v_add_f32_e32 v13, 1.0, v17
	v_add_f32_e32 v17, 1.0, v20
	v_rcp_f32_e32 v20, v17
	v_mul_f32_e32 v17, 0x3d372713, v11
	v_mul_f32_e32 v17, v17, v11
	v_fmac_f32_e32 v21, v17, v21
	v_add_f32_e32 v12, 1.0, v12
	v_mul_f32_e32 v17, 0x3f4c422a, v21
	v_rcp_f32_e32 v12, v12
	v_rcp_f32_e32 v13, v13
	v_add_f32_e32 v17, v17, v17
	v_mul_f32_e32 v17, 0x3fb8aa3b, v17
	v_exp_f32_e32 v17, v17
	v_pk_fma_f32 v[12:13], v[12:13], 2.0, 1.0 op_sel_hi:[1,0,0] neg_lo:[1,0,0] neg_hi:[1,0,0]
	v_pk_mul_f32 v[8:9], v[8:9], 0.5 op_sel_hi:[1,0]
	v_pk_add_f32 v[12:13], v[12:13], 1.0 op_sel_hi:[1,0]
	v_pk_mul_f32 v[10:11], v[10:11], 0.5 op_sel_hi:[1,0]
	v_pk_mul_f32 v[8:9], v[8:9], v[12:13]
	v_mov_b32_e32 v12, v4
	v_add_f32_e32 v4, 1.0, v17
	v_rcp_f32_e32 v21, v4
	v_mov_b32_e32 v13, v6
	v_pk_add_f32 v[12:13], v[12:13], v[16:17] op_sel_hi:[1,0]
	v_mov_b32_e32 v6, v5
	v_pk_mul_f32 v[8:9], v[12:13], v[8:9]
	v_pk_fma_f32 v[12:13], v[20:21], 2.0, 1.0 op_sel_hi:[1,0,0] neg_lo:[1,0,0] neg_hi:[1,0,0]
	v_pk_add_f32 v[4:5], v[6:7], v[16:17] op_sel_hi:[1,0]
	v_pk_add_f32 v[12:13], v[12:13], 1.0 op_sel_hi:[1,0]
	v_and_b32_sdwa v6, v9, v139 dst_sel:DWORD dst_unused:UNUSED_PAD src0_sel:WORD_1 src1_sel:DWORD
	v_pk_mul_f32 v[10:11], v[10:11], v[12:13]
	v_and_b32_sdwa v7, v8, v139 dst_sel:DWORD dst_unused:UNUSED_PAD src0_sel:WORD_1 src1_sel:DWORD
	v_pk_mul_f32 v[4:5], v[4:5], v[10:11]
	v_add3_u32 v7, v8, v7, s29
	v_add3_u32 v6, v9, v6, s29
	v_and_b32_sdwa v8, v5, v139 dst_sel:DWORD dst_unused:UNUSED_PAD src0_sel:WORD_1 src1_sel:DWORD
	v_and_b32_sdwa v9, v4, v139 dst_sel:DWORD dst_unused:UNUSED_PAD src0_sel:WORD_1 src1_sel:DWORD
	v_add3_u32 v5, v5, v8, s29
	v_add3_u32 v4, v4, v9, s29
	v_and_b32_e32 v5, 0xffff0000, v5
	v_and_b32_e32 v4, 0xffff0000, v4
	v_or_b32_sdwa v5, v5, v6 dst_sel:DWORD dst_unused:UNUSED_PAD src0_sel:DWORD src1_sel:WORD_1
	v_or_b32_sdwa v4, v4, v7 dst_sel:DWORD dst_unused:UNUSED_PAD src0_sel:DWORD src1_sel:WORD_1
	global_store_dwordx2 v[14:15], v[4:5], off offset:64
	s_waitcnt vmcnt(3)
	v_lshlrev_b32_e32 v4, 16, v24
	v_mul_f32_e32 v5, 0x3d372713, v4
	v_mul_f32_e32 v5, v5, v4
	v_mov_b32_e32 v6, v4
	v_fmac_f32_e32 v6, v5, v6
	v_mul_f32_e32 v5, 0x3f4c422a, v6
	v_and_b32_e32 v6, 0xffff0000, v24
	v_add_f32_e32 v5, v5, v5
	v_mul_f32_e32 v9, 0x3d372713, v6
	v_mul_f32_e32 v5, 0x3fb8aa3b, v5
	v_mul_f32_e32 v9, v9, v6
	v_mov_b32_e32 v10, v6
	v_exp_f32_e32 v8, v5
	v_lshlrev_b32_e32 v5, 16, v25
	v_fmac_f32_e32 v10, v9, v10
	v_mul_f32_e32 v9, 0x3f4c422a, v10
	v_mul_f32_e32 v10, 0x3d372713, v5
	v_mul_f32_e32 v10, v10, v5
	v_mov_b32_e32 v11, v5
	v_fmac_f32_e32 v11, v10, v11
	v_mul_f32_e32 v10, 0x3f4c422a, v11
	v_add_f32_e32 v9, v9, v9
	v_add_f32_e32 v10, v10, v10
	v_mul_f32_e32 v10, 0x3fb8aa3b, v10
	v_mul_f32_e32 v9, 0x3fb8aa3b, v9
	v_exp_f32_e32 v10, v10
	v_exp_f32_e32 v11, v9
	v_and_b32_e32 v7, 0xffff0000, v25
	v_mov_b32_e32 v12, v7
	v_add_f32_e32 v9, 1.0, v10
	v_add_f32_e32 v10, 1.0, v11
	v_mul_f32_e32 v11, 0x3d372713, v7
	v_mul_f32_e32 v11, v11, v7
	v_fmac_f32_e32 v12, v11, v12
	v_add_f32_e32 v8, 1.0, v8
	v_mul_f32_e32 v11, 0x3f4c422a, v12
	v_rcp_f32_e32 v8, v8
	v_rcp_f32_e32 v9, v9
	v_add_f32_e32 v11, v11, v11
	v_mul_f32_e32 v11, 0x3fb8aa3b, v11
	v_exp_f32_e32 v11, v11
	v_pk_fma_f32 v[8:9], v[8:9], 2.0, 1.0 op_sel_hi:[1,0,0] neg_lo:[1,0,0] neg_hi:[1,0,0]
	v_pk_mul_f32 v[4:5], v[4:5], 0.5 op_sel_hi:[1,0]
	v_pk_add_f32 v[8:9], v[8:9], 1.0 op_sel_hi:[1,0]
	v_rcp_f32_e32 v10, v10
	v_pk_mul_f32 v[4:5], v[4:5], v[8:9]
	v_mov_b32_e32 v8, v0
	v_add_f32_e32 v0, 1.0, v11
	v_rcp_f32_e32 v11, v0
	v_mov_b32_e32 v9, v2
	v_pk_add_f32 v[8:9], v[16:17], v[8:9] op_sel_hi:[0,1]
	v_pk_mul_f32 v[4:5], v[8:9], v[4:5]
	v_pk_fma_f32 v[8:9], v[10:11], 2.0, 1.0 op_sel_hi:[1,0,0] neg_lo:[1,0,0] neg_hi:[1,0,0]
	v_pk_mul_f32 v[6:7], v[6:7], 0.5 op_sel_hi:[1,0]
	v_pk_add_f32 v[8:9], v[8:9], 1.0 op_sel_hi:[1,0]
	v_mov_b32_e32 v2, v1
	v_pk_mul_f32 v[6:7], v[6:7], v[8:9]
	v_pk_add_f32 v[0:1], v[16:17], v[2:3] op_sel_hi:[0,1]
	v_pk_mul_f32 v[0:1], v[0:1], v[6:7]
	v_and_b32_sdwa v2, v5, v139 dst_sel:DWORD dst_unused:UNUSED_PAD src0_sel:WORD_1 src1_sel:DWORD
	v_and_b32_sdwa v3, v4, v139 dst_sel:DWORD dst_unused:UNUSED_PAD src0_sel:WORD_1 src1_sel:DWORD
	v_add3_u32 v3, v4, v3, s29
	v_add3_u32 v2, v5, v2, s29
	v_and_b32_sdwa v4, v1, v139 dst_sel:DWORD dst_unused:UNUSED_PAD src0_sel:WORD_1 src1_sel:DWORD
	v_and_b32_sdwa v5, v0, v139 dst_sel:DWORD dst_unused:UNUSED_PAD src0_sel:WORD_1 src1_sel:DWORD
	v_add3_u32 v1, v1, v4, s29
	v_add3_u32 v0, v0, v5, s29
	v_and_b32_e32 v1, 0xffff0000, v1
	v_and_b32_e32 v0, 0xffff0000, v0
	v_or_b32_sdwa v1, v1, v2 dst_sel:DWORD dst_unused:UNUSED_PAD src0_sel:DWORD src1_sel:WORD_1
	v_or_b32_sdwa v0, v0, v3 dst_sel:DWORD dst_unused:UNUSED_PAD src0_sel:DWORD src1_sel:WORD_1
	v_lshl_add_u64 v[2:3], v[18:19], 0, v[92:93]
	global_store_dwordx2 v[2:3], v[0:1], off
	s_cbranch_execnz .LBB0_405
	s_branch .LBB0_409

; #define LAS __attribute__((address_space(3)))
; __device__ __forceinline__ unsigned pk2(float lo, float hi) { return f2bf(lo) | (f2bf(hi) << 16); }
; #define MFMA16(a, b, c) __builtin_amdgcn_mfma_f32_16x16x32_bf16((a), (b), (c), 0, 0, 0)
; __device__ __forceinline__ void na_item(int item, const bf16* Z, const float* rpb, bf16* CC, LAS unsigned char* lds, int tid, int wave, int lane) {
;     ...
;             bf16x8 pf[2];
; #pragma unroll
;             for (int ks = 0; ks < 2; ++ks) { u32x4 w; w.x = pk2(sc[2 * ks][0], sc[2 * ks][1]); w.y = pk2(sc[2 * ks][2], sc[2 * ks][3]); w.z = pk2(sc[2 * ks + 1][0], sc[2 * ks + 1][1]); w.w = pk2(sc[2 * ks + 1][2], sc[2 * ks + 1][3]);
;                 pf[ks] = __builtin_bit_cast(bf16x8, w); }
; #pragma unroll
;             for (int nb = 0; nb < 4; ++nb) oacc[nb] = oacc[nb] * alpha;
; #pragma unroll
;             for (int ks = 0; ks < 2; ++ks) {
;                 const bool kson = !loc || (2 * ks + 1 >= nlo && 2 * ks <= nhi);
;                 if (kson) {
; #pragma unroll
;                     for (int nb = 0; nb < 4; ++nb) { const LAS bf16* vp = Vt + (nb * 16 + fr) * KSTR + 32 * ks + 4 * g;
;                         const u32x2 lo = *(const LAS u32x2*)vp, hi = *(const LAS u32x2*)(vp + 16);
;                         u32x4 w; w.x = lo.x; w.y = lo.y; w.z = hi.x; w.w = hi.y;
;                         oacc[nb] = MFMA16(__builtin_bit_cast(bf16x8, w), pf[ks], oacc[nb]); }
;                 }
;             }
.LBB0_485:
	v_add_u32_e32 v95, v129, v131
	v_add_u32_e32 v143, v129, v132
	s_andn2_b64 vcc, exec, s[88:89]
	v_add_u32_e32 v142, 0x2000, v95
	v_add_u32_e32 v141, 0x2800, v95
	v_add_u32_e32 v103, 0x3000, v95
	v_add_u32_e32 v95, 0x2000, v143
	s_cbranch_vccnz .LBB0_487
	v_bfe_u32 v143, v0, 16, 1
	v_add3_u32 v0, v0, v143, s29
	v_bfe_u32 v143, v1, 16, 1
	v_lshrrev_b32_e32 v0, 16, v0
	v_add3_u32 v1, v1, v143, s29
	v_and_or_b32 v0, v1, s28, v0
	v_cvt_pk_bf16_f32 v1, v2, v3
	v_cvt_pk_bf16_f32 v2, v4, v5
	s_nop 0
	s_nop 0
	s_nop 0
	v_cvt_pk_bf16_f32 v3, v6, v7
	ds_read2_b64 v[4:7], v142 offset0:128 offset1:132
	s_waitcnt lgkmcnt(0)
	v_mfma_f32_16x16x32_bf16 v[44:47], v[4:7], v[0:3], v[44:47]
	ds_read2_b64 v[4:7], v141 offset0:160 offset1:164
	s_waitcnt lgkmcnt(0)
	v_mfma_f32_16x16x32_bf16 v[40:43], v[4:7], v[0:3], v[40:43]
	ds_read2_b64 v[4:7], v103 offset0:192 offset1:196
	s_waitcnt lgkmcnt(0)
	v_mfma_f32_16x16x32_bf16 v[36:39], v[4:7], v[0:3], v[36:39]
	ds_read2_b64 v[4:7], v95 offset0:128 offset1:132
	s_waitcnt lgkmcnt(0)
	v_mfma_f32_16x16x32_bf16 v[32:35], v[4:7], v[0:3], v[32:35]
.LBB0_487:
	s_andn2_b64 vcc, exec, s[90:91]
	s_cbranch_vccnz .LBB0_489
	s_nop 0
	s_nop 0
	s_nop 0
	s_nop 0
	s_nop 0
	v_cvt_pk_bf16_f32 v0, v8, v9
	ds_read2_b64 v[4:7], v142 offset0:136 offset1:140
	v_cvt_pk_bf16_f32 v1, v10, v11
	v_cvt_pk_bf16_f32 v2, v12, v13
	v_bfe_u32 v3, v14, 16, 1
	v_add3_u32 v3, v14, v3, s29
	v_bfe_u32 v8, v15, 16, 1
	v_lshrrev_b32_e32 v3, 16, v3
	v_add3_u32 v8, v15, v8, s29
	v_and_or_b32 v3, v8, s28, v3
	s_waitcnt lgkmcnt(0)
	s_nop 0
	v_mfma_f32_16x16x32_bf16 v[44:47], v[4:7], v[0:3], v[44:47]
	ds_read2_b64 v[4:7], v141 offset0:168 offset1:172
	s_waitcnt lgkmcnt(0)
	v_mfma_f32_16x16x32_bf16 v[40:43], v[4:7], v[0:3], v[40:43]
	ds_read2_b64 v[4:7], v103 offset0:200 offset1:204
	s_waitcnt lgkmcnt(0)
	v_mfma_f32_16x16x32_bf16 v[36:39], v[4:7], v[0:3], v[36:39]
	ds_read2_b64 v[4:7], v95 offset0:136 offset1:140
	s_waitcnt lgkmcnt(0)
	v_mfma_f32_16x16x32_bf16 v[32:35], v[4:7], v[0:3], v[32:35]

; #define LAS __attribute__((address_space(3)))
; __device__ __forceinline__ void transpose_item(const float* W, int K, int N, bf16* WT, int row_off, LAS float* scr, int item, int lane) {
;     const int nblk = N / 32, kb = item / nblk, nb = item % nblk, k0 = 64 * kb, n0 = 32 * nb;
; #pragma unroll 8
;     for (int i = 0; i < 32; ++i) { const int kk = 2 * i + (lane >> 5); scr[kk * 33 + (lane & 31)] = W[(size_t)(k0 + kk) * N + n0 + (lane & 31)]; }
.LBB0_502:
	s_lshl_b32 s28, s0, 1
	s_lshl_b32 s29, s8, 1
	v_or_b32_e32 v4, s29, v20
	s_add_i32 s30, s28, 4
	s_add_i32 s31, s29, 4
	s_waitcnt vmcnt(4)
	v_mov_b32_e32 v29, v5
	s_add_i32 s34, s29, 8
	v_lshlrev_b64 v[42:43], 13, v[4:5]
	v_or_b32_e32 v28, s30, v3
	v_or_b32_e32 v4, s31, v20
	v_mov_b32_e32 v27, v5
	v_or_b32_e32 v26, s28, v3
	s_add_i32 s52, s29, 12
	v_lshlrev_b64 v[28:29], 13, v[28:29]
	v_lshlrev_b64 v[44:45], 13, v[4:5]
	v_or_b32_e32 v4, s34, v20
	s_add_i32 s33, s28, 8
	s_add_i32 s35, s28, 12
	s_add_i32 s54, s29, 16
	v_lshlrev_b64 v[26:27], 13, v[26:27]
	v_lshl_add_u64 v[42:43], v[18:19], 0, v[42:43]
	v_lshl_add_u64 v[28:29], v[18:19], 0, v[28:29]
	v_lshlrev_b64 v[46:47], 13, v[4:5]
	v_or_b32_e32 v4, s52, v20
	v_mov_b32_e32 v31, v5
	v_mov_b32_e32 v33, v5
	s_add_i32 s56, s29, 20
	v_or_b32_e32 v30, s33, v3
	v_or_b32_e32 v32, s35, v3
	v_lshl_add_u64 v[26:27], v[18:19], 0, v[26:27]
	v_lshl_add_u64 v[44:45], v[18:19], 0, v[44:45]
	global_load_dword v58, v[42:43], off
	global_load_dword v59, v[26:27], off
	global_load_dword v60, v[44:45], off
	global_load_dword v61, v[28:29], off
	v_lshlrev_b64 v[28:29], 13, v[4:5]
	v_or_b32_e32 v4, s54, v20
	s_add_i32 s53, s28, 16
	s_add_i32 s55, s28, 20
	s_add_i32 s58, s29, 24
	v_lshlrev_b64 v[30:31], 13, v[30:31]
	v_lshlrev_b64 v[32:33], 13, v[32:33]
	v_lshl_add_u64 v[26:27], v[18:19], 0, v[46:47]
	v_lshl_add_u64 v[28:29], v[18:19], 0, v[28:29]
	v_lshlrev_b64 v[42:43], 13, v[4:5]
	v_or_b32_e32 v4, s56, v20
	v_mov_b32_e32 v35, v5
	v_mov_b32_e32 v37, v5
	s_add_i32 s57, s28, 24
	s_add_i32 s59, s28, 28
	s_add_i32 s60, s29, 28
	v_or_b32_e32 v34, s53, v3
	v_or_b32_e32 v36, s55, v3
	v_lshl_add_u64 v[30:31], v[18:19], 0, v[30:31]
	v_lshl_add_u64 v[32:33], v[18:19], 0, v[32:33]
	global_load_dword v62, v[26:27], off
	global_load_dword v63, v[30:31], off
	global_load_dword v64, v[28:29], off
	global_load_dword v65, v[32:33], off
	v_lshlrev_b64 v[28:29], 13, v[4:5]
	v_or_b32_e32 v4, s58, v20
	v_mov_b32_e32 v39, v5
	v_mov_b32_e32 v41, v5
	v_or_b32_e32 v38, s57, v3
	v_or_b32_e32 v40, s59, v3
	v_lshlrev_b64 v[34:35], 13, v[34:35]
	v_lshlrev_b64 v[36:37], 13, v[36:37]
	v_lshl_add_u64 v[26:27], v[18:19], 0, v[42:43]
	v_lshl_add_u64 v[28:29], v[18:19], 0, v[28:29]
	v_lshlrev_b64 v[30:31], 13, v[4:5]
	v_or_b32_e32 v4, s60, v20
	v_lshlrev_b64 v[38:39], 13, v[38:39]
	v_lshlrev_b64 v[40:41], 13, v[40:41]
	v_lshl_add_u64 v[34:35], v[18:19], 0, v[34:35]
	v_lshl_add_u64 v[36:37], v[18:19], 0, v[36:37]
	global_load_dword v66, v[26:27], off
	global_load_dword v67, v[34:35], off
	global_load_dword v68, v[28:29], off
	global_load_dword v69, v[36:37], off
	v_lshl_add_u64 v[26:27], v[18:19], 0, v[30:31]
	v_lshlrev_b64 v[28:29], 13, v[4:5]
	v_lshl_add_u64 v[38:39], v[18:19], 0, v[38:39]
	v_lshl_add_u64 v[40:41], v[18:19], 0, v[40:41]
	v_lshl_add_u64 v[28:29], v[18:19], 0, v[28:29]
	global_load_dword v4, v[26:27], off
	global_load_dword v70, v[38:39], off
	global_load_dword v71, v[28:29], off
	global_load_dword v72, v[40:41], off
	v_or_b32_e32 v28, s28, v1
	v_or_b32_e32 v26, s29, v0
	s_add_i32 s8, s8, 16
	s_add_i32 s0, s0, 16
	s_add_i32 s9, s9, -16
	v_mad_u64_u32 v[26:27], s[28:29], v26, s7, v[2:3]
	v_mad_u64_u32 v[28:29], s[28:29], v28, s7, v[2:3]
	v_or_b32_e32 v27, s30, v1
	v_or_b32_e32 v29, s31, v0
	v_or_b32_e32 v36, s33, v1
	v_or_b32_e32 v34, s34, v0
	v_or_b32_e32 v40, s35, v1
	v_or_b32_e32 v38, s52, v0
	v_or_b32_e32 v44, s53, v1
	v_or_b32_e32 v42, s54, v0
	v_or_b32_e32 v48, s55, v1
	v_or_b32_e32 v46, s56, v0
	v_or_b32_e32 v52, s57, v1
	v_or_b32_e32 v50, s58, v0
	v_or_b32_e32 v56, s59, v1
	v_or_b32_e32 v54, s60, v0
	s_cmp_lg_u32 s9, 0
	v_mad_u64_u32 v[30:31], s[28:29], v29, s7, v[2:3]
	v_mad_u64_u32 v[32:33], s[28:29], v27, s7, v[2:3]
	v_mad_u64_u32 v[34:35], s[28:29], v34, s7, v[2:3]
	v_mad_u64_u32 v[36:37], s[28:29], v36, s7, v[2:3]
	v_mad_u64_u32 v[38:39], s[28:29], v38, s7, v[2:3]
	v_mad_u64_u32 v[40:41], s[28:29], v40, s7, v[2:3]
	v_mad_u64_u32 v[42:43], s[28:29], v42, s7, v[2:3]
	v_mad_u64_u32 v[44:45], s[28:29], v44, s7, v[2:3]
	v_mad_u64_u32 v[46:47], s[28:29], v46, s7, v[2:3]
	v_mad_u64_u32 v[48:49], s[28:29], v48, s7, v[2:3]
	v_mad_u64_u32 v[50:51], s[28:29], v50, s7, v[2:3]
	v_mad_u64_u32 v[52:53], s[28:29], v52, s7, v[2:3]
	v_mad_u64_u32 v[54:55], s[28:29], v54, s7, v[2:3]
	v_mad_u64_u32 v[56:57], s[28:29], v56, s7, v[2:3]
	s_waitcnt vmcnt(15)
	ds_write_b32 v26, v58
	s_waitcnt vmcnt(14)
	ds_write_b32 v28, v59
	s_waitcnt vmcnt(13)
	ds_write_b32 v30, v60
	s_waitcnt vmcnt(12)
	ds_write_b32 v32, v61
	s_waitcnt vmcnt(11)
	ds_write_b32 v34, v62
	s_waitcnt vmcnt(10)
	ds_write_b32 v36, v63
	s_waitcnt vmcnt(9)
	ds_write_b32 v38, v64
	s_waitcnt vmcnt(8)
	ds_write_b32 v40, v65
	s_waitcnt vmcnt(7)
	ds_write_b32 v42, v66
	s_waitcnt vmcnt(6)
	ds_write_b32 v44, v67
	s_waitcnt vmcnt(5)
	ds_write_b32 v46, v68
	s_waitcnt vmcnt(4)
	ds_write_b32 v48, v69
	s_waitcnt vmcnt(3)
	ds_write_b32 v50, v4
	s_waitcnt vmcnt(2)
	ds_write_b32 v52, v70
	s_waitcnt vmcnt(1)
	ds_write_b32 v54, v71
	s_waitcnt vmcnt(0)
	ds_write_b32 v56, v72
	s_cbranch_scc1 .LBB0_502
; #define LAS __attribute__((address_space(3)))
; __device__ __forceinline__ unsigned pk2(float lo, float hi) { return f2bf(lo) | (f2bf(hi) << 16); }
; __device__ __forceinline__ void transpose_item(const float* W, int K, int N, bf16* WT, int row_off, LAS float* scr, int item, int lane) {
;     ...
;     const int c = lane & 7;
; #pragma unroll
;     for (int j = 0; j < 4; ++j) { const int n = (lane >> 3) + 8 * j; const LAS float* s = scr + (8 * c) * 33 + n;
;         u32x4 o; o.x = pk2(s[0 * 33], s[1 * 33]); o.y = pk2(s[2 * 33], s[3 * 33]); o.z = pk2(s[4 * 33], s[5 * 33]); o.w = pk2(s[6 * 33], s[7 * 33]);
;         *(u32x4*)(WT + (size_t)(row_off + n0 + n) * K + k0 + 8 * c) = o; }
	s_waitcnt lgkmcnt(0)
	ds_read2_b32 v[18:19], v22 offset1:8
	ds_read2_b32 v[32:33], v22 offset0:33 offset1:41
	ds_read2_b32 v[34:35], v22 offset0:66 offset1:74
	ds_read2_b32 v[36:37], v22 offset0:99 offset1:107
	ds_read2_b32 v[38:39], v22 offset0:132 offset1:140
	ds_read2_b32 v[40:41], v22 offset0:165 offset1:173
	s_waitcnt lgkmcnt(5)
	s_waitcnt lgkmcnt(4)
	v_cvt_pk_bf16_f32 v26, v18, v32
	s_waitcnt lgkmcnt(3)
	s_waitcnt lgkmcnt(2)
	ds_read2_b32 v[42:43], v22 offset0:198 offset1:206
	ds_read2_b32 v[44:45], v22 offset0:231 offset1:239
	v_cvt_pk_bf16_f32 v27, v34, v36
	s_waitcnt lgkmcnt(3)
	s_waitcnt lgkmcnt(2)
	v_cvt_pk_bf16_f32 v28, v38, v40
	s_waitcnt lgkmcnt(1)
	s_waitcnt lgkmcnt(0)
	s_nop 0
	s_nop 0
	s_nop 0
	s_lshl_b32 s0, s5, 1
	v_cvt_pk_bf16_f32 v29, v42, v44
	v_or_b32_e32 v3, s4, v21
	v_lshl_add_u64 v[30:31], v[6:7], 0, s[0:1]
	v_lshlrev_b32_e32 v4, 14, v3
	v_bfe_u32 v3, v19, 16, 1
	v_lshl_add_u64 v[46:47], v[30:31], 0, v[4:5]
	v_add3_u32 v3, v19, v3, s10
	v_bfe_u32 v4, v33, 16, 1
	v_lshrrev_b32_e32 v3, 16, v3
	v_add3_u32 v4, v33, v4, s10
	global_store_dwordx4 v[46:47], v[26:29], off
	ds_read2_b32 v[18:19], v22 offset0:16 offset1:24
	s_nop 0
	v_and_or_b32 v26, v4, s11, v3
	s_nop 0
	s_nop 0
	s_nop 0
	s_nop 0
	s_nop 0
	v_cvt_pk_bf16_f32 v27, v35, v37
	v_cvt_pk_bf16_f32 v28, v39, v41
	s_nop 0
	s_nop 0
	v_cvt_pk_bf16_f32 v29, v43, v45
	v_or_b32_e32 v3, s4, v23
	v_lshlrev_b32_e32 v4, 14, v3
	v_lshl_add_u64 v[32:33], v[30:31], 0, v[4:5]
	global_store_dwordx4 v[32:33], v[26:29], off
	ds_read2_b32 v[32:33], v22 offset0:49 offset1:57
	ds_read2_b32 v[34:35], v22 offset0:82 offset1:90
	ds_read2_b32 v[36:37], v22 offset0:115 offset1:123
	s_waitcnt lgkmcnt(3)
	s_nop 0
	s_nop 0
	s_waitcnt lgkmcnt(2)
	ds_read2_b32 v[38:39], v22 offset0:148 offset1:156
	ds_read2_b32 v[40:41], v22 offset0:181 offset1:189
	v_cvt_pk_bf16_f32 v26, v18, v32
	s_waitcnt lgkmcnt(3)
	s_waitcnt lgkmcnt(2)
	ds_read2_b32 v[42:43], v22 offset0:214 offset1:222
	ds_read2_b32 v[44:45], v22 offset0:247 offset1:255
	v_cvt_pk_bf16_f32 v27, v34, v36
	s_waitcnt lgkmcnt(3)
	s_waitcnt lgkmcnt(2)
	v_cvt_pk_bf16_f32 v28, v38, v40
	s_waitcnt lgkmcnt(1)
	s_waitcnt lgkmcnt(0)
	v_cvt_pk_bf16_f32 v29, v42, v44
	v_or_b32_e32 v3, s4, v24
	v_lshlrev_b32_e32 v4, 14, v3
	s_nop 0
	v_lshl_add_u64 v[46:47], v[30:31], 0, v[4:5]
	s_nop 0
	s_nop 0
	s_nop 0
	s_nop 0
	global_store_dwordx4 v[46:47], v[26:29], off
	s_nop 1
	v_cvt_pk_bf16_f32 v26, v19, v33
	s_nop 0
	s_nop 0
	s_nop 0
	s_nop 0
	s_nop 0
	v_cvt_pk_bf16_f32 v27, v35, v37
	v_cvt_pk_bf16_f32 v28, v39, v41
	s_nop 0
	s_nop 0
	v_cvt_pk_bf16_f32 v29, v43, v45
	v_or_b32_e32 v3, s4, v25
	v_lshlrev_b32_e32 v4, 14, v3
	v_lshl_add_u64 v[18:19], v[30:31], 0, v[4:5]
	global_store_dwordx4 v[18:19], v[26:29], off
	s_waitcnt lgkmcnt(0)
	s_mov_b64 s[4:5], 0

; #define LAS __attribute__((address_space(3)))
; __device__ __forceinline__ void transpose_item(const float* W, int K, int N, bf16* WT, int row_off, LAS float* scr, int item, int lane) {
;     const int nblk = N / 32, kb = item / nblk, nb = item % nblk, k0 = 64 * kb, n0 = 32 * nb;
; #pragma unroll 8
;     for (int i = 0; i < 32; ++i) { const int kk = 2 * i + (lane >> 5); scr[kk * 33 + (lane & 31)] = W[(size_t)(k0 + kk) * N + n0 + (lane & 31)]; }
.LBB0_506:
	s_lshl_b32 s28, s0, 1
	s_lshl_b32 s29, s8, 1
	v_or_b32_e32 v4, s29, v20
	s_add_i32 s30, s28, 4
	s_add_i32 s31, s29, 4
	s_waitcnt vmcnt(4)
	v_mov_b32_e32 v29, v5
	s_add_i32 s34, s29, 8
	v_lshlrev_b64 v[42:43], 15, v[4:5]
	v_or_b32_e32 v28, s30, v3
	v_or_b32_e32 v4, s31, v20
	v_mov_b32_e32 v27, v5
	v_or_b32_e32 v26, s28, v3
	s_add_i32 s52, s29, 12
	v_lshlrev_b64 v[28:29], 15, v[28:29]
	v_lshlrev_b64 v[44:45], 15, v[4:5]
	v_or_b32_e32 v4, s34, v20
	s_add_i32 s33, s28, 8
	s_add_i32 s35, s28, 12
	s_add_i32 s54, s29, 16
	v_lshlrev_b64 v[26:27], 15, v[26:27]
	v_lshl_add_u64 v[42:43], v[18:19], 0, v[42:43]
	v_lshl_add_u64 v[28:29], v[18:19], 0, v[28:29]
	v_lshlrev_b64 v[46:47], 15, v[4:5]
	v_or_b32_e32 v4, s52, v20
	v_mov_b32_e32 v31, v5
	v_mov_b32_e32 v33, v5
	s_add_i32 s56, s29, 20
	v_or_b32_e32 v30, s33, v3
	v_or_b32_e32 v32, s35, v3
	v_lshl_add_u64 v[26:27], v[18:19], 0, v[26:27]
	v_lshl_add_u64 v[44:45], v[18:19], 0, v[44:45]
	global_load_dword v58, v[42:43], off
	global_load_dword v59, v[26:27], off
	global_load_dword v60, v[44:45], off
	global_load_dword v61, v[28:29], off
	v_lshlrev_b64 v[28:29], 15, v[4:5]
	v_or_b32_e32 v4, s54, v20
	s_add_i32 s53, s28, 16
	s_add_i32 s55, s28, 20
	s_add_i32 s58, s29, 24
	v_lshlrev_b64 v[30:31], 15, v[30:31]
	v_lshlrev_b64 v[32:33], 15, v[32:33]
	v_lshl_add_u64 v[26:27], v[18:19], 0, v[46:47]
	v_lshl_add_u64 v[28:29], v[18:19], 0, v[28:29]
	v_lshlrev_b64 v[42:43], 15, v[4:5]
	v_or_b32_e32 v4, s56, v20
	v_mov_b32_e32 v35, v5
	v_mov_b32_e32 v37, v5
	s_add_i32 s57, s28, 24
	s_add_i32 s59, s28, 28
	s_add_i32 s60, s29, 28
	v_or_b32_e32 v34, s53, v3
	v_or_b32_e32 v36, s55, v3
	v_lshl_add_u64 v[30:31], v[18:19], 0, v[30:31]
	v_lshl_add_u64 v[32:33], v[18:19], 0, v[32:33]
	global_load_dword v62, v[26:27], off
	global_load_dword v63, v[30:31], off
	global_load_dword v64, v[28:29], off
	global_load_dword v65, v[32:33], off
	v_lshlrev_b64 v[28:29], 15, v[4:5]
	v_or_b32_e32 v4, s58, v20
	v_mov_b32_e32 v39, v5
	v_mov_b32_e32 v41, v5
	v_or_b32_e32 v38, s57, v3
	v_or_b32_e32 v40, s59, v3
	v_lshlrev_b64 v[34:35], 15, v[34:35]
	v_lshlrev_b64 v[36:37], 15, v[36:37]
	v_lshl_add_u64 v[26:27], v[18:19], 0, v[42:43]
	v_lshl_add_u64 v[28:29], v[18:19], 0, v[28:29]
	v_lshlrev_b64 v[30:31], 15, v[4:5]
	v_or_b32_e32 v4, s60, v20
	v_lshlrev_b64 v[38:39], 15, v[38:39]
	v_lshlrev_b64 v[40:41], 15, v[40:41]
	v_lshl_add_u64 v[34:35], v[18:19], 0, v[34:35]
	v_lshl_add_u64 v[36:37], v[18:19], 0, v[36:37]
	global_load_dword v66, v[26:27], off
	global_load_dword v67, v[34:35], off
	global_load_dword v68, v[28:29], off
	global_load_dword v69, v[36:37], off
	v_lshl_add_u64 v[26:27], v[18:19], 0, v[30:31]
	v_lshlrev_b64 v[28:29], 15, v[4:5]
	v_lshl_add_u64 v[38:39], v[18:19], 0, v[38:39]
	v_lshl_add_u64 v[40:41], v[18:19], 0, v[40:41]
	v_lshl_add_u64 v[28:29], v[18:19], 0, v[28:29]
	global_load_dword v4, v[26:27], off
	global_load_dword v70, v[38:39], off
	global_load_dword v71, v[28:29], off
	global_load_dword v72, v[40:41], off
	v_or_b32_e32 v28, s28, v1
	v_or_b32_e32 v26, s29, v0
	s_add_i32 s8, s8, 16
	s_add_i32 s0, s0, 16
	s_add_i32 s9, s9, -16
	v_mad_u64_u32 v[26:27], s[28:29], v26, s7, v[2:3]
	v_mad_u64_u32 v[28:29], s[28:29], v28, s7, v[2:3]
	v_or_b32_e32 v27, s30, v1
	v_or_b32_e32 v29, s31, v0
	v_or_b32_e32 v36, s33, v1
	v_or_b32_e32 v34, s34, v0
	v_or_b32_e32 v40, s35, v1
	v_or_b32_e32 v38, s52, v0
	v_or_b32_e32 v44, s53, v1
	v_or_b32_e32 v42, s54, v0
	v_or_b32_e32 v48, s55, v1
	v_or_b32_e32 v46, s56, v0
	v_or_b32_e32 v52, s57, v1
	v_or_b32_e32 v50, s58, v0
	v_or_b32_e32 v56, s59, v1
	v_or_b32_e32 v54, s60, v0
	s_cmp_lg_u32 s9, 0
	v_mad_u64_u32 v[30:31], s[28:29], v29, s7, v[2:3]
	v_mad_u64_u32 v[32:33], s[28:29], v27, s7, v[2:3]
	v_mad_u64_u32 v[34:35], s[28:29], v34, s7, v[2:3]
	v_mad_u64_u32 v[36:37], s[28:29], v36, s7, v[2:3]
	v_mad_u64_u32 v[38:39], s[28:29], v38, s7, v[2:3]
	v_mad_u64_u32 v[40:41], s[28:29], v40, s7, v[2:3]
	v_mad_u64_u32 v[42:43], s[28:29], v42, s7, v[2:3]
	v_mad_u64_u32 v[44:45], s[28:29], v44, s7, v[2:3]
	v_mad_u64_u32 v[46:47], s[28:29], v46, s7, v[2:3]
	v_mad_u64_u32 v[48:49], s[28:29], v48, s7, v[2:3]
	v_mad_u64_u32 v[50:51], s[28:29], v50, s7, v[2:3]
	v_mad_u64_u32 v[52:53], s[28:29], v52, s7, v[2:3]
	v_mad_u64_u32 v[54:55], s[28:29], v54, s7, v[2:3]
	v_mad_u64_u32 v[56:57], s[28:29], v56, s7, v[2:3]
	s_waitcnt vmcnt(15)
	ds_write_b32 v26, v58
	s_waitcnt vmcnt(14)
	ds_write_b32 v28, v59
	s_waitcnt vmcnt(13)
	ds_write_b32 v30, v60
	s_waitcnt vmcnt(12)
	ds_write_b32 v32, v61
	s_waitcnt vmcnt(11)
	ds_write_b32 v34, v62
	s_waitcnt vmcnt(10)
	ds_write_b32 v36, v63
	s_waitcnt vmcnt(9)
	ds_write_b32 v38, v64
	s_waitcnt vmcnt(8)
	ds_write_b32 v40, v65
	s_waitcnt vmcnt(7)
	ds_write_b32 v42, v66
	s_waitcnt vmcnt(6)
	ds_write_b32 v44, v67
	s_waitcnt vmcnt(5)
	ds_write_b32 v46, v68
	s_waitcnt vmcnt(4)
	ds_write_b32 v48, v69
	s_waitcnt vmcnt(3)
	ds_write_b32 v50, v4
	s_waitcnt vmcnt(2)
	ds_write_b32 v52, v70
	s_waitcnt vmcnt(1)
	ds_write_b32 v54, v71
	s_waitcnt vmcnt(0)
	ds_write_b32 v56, v72
	s_cbranch_scc1 .LBB0_506
; #define LAS __attribute__((address_space(3)))
; __device__ __forceinline__ unsigned pk2(float lo, float hi) { return f2bf(lo) | (f2bf(hi) << 16); }
; __device__ __forceinline__ void transpose_item(const float* W, int K, int N, bf16* WT, int row_off, LAS float* scr, int item, int lane) {
;     ...
;     const int c = lane & 7;
; #pragma unroll
;     for (int j = 0; j < 4; ++j) { const int n = (lane >> 3) + 8 * j; const LAS float* s = scr + (8 * c) * 33 + n;
;         u32x4 o; o.x = pk2(s[0 * 33], s[1 * 33]); o.y = pk2(s[2 * 33], s[3 * 33]); o.z = pk2(s[4 * 33], s[5 * 33]); o.w = pk2(s[6 * 33], s[7 * 33]);
;         *(u32x4*)(WT + (size_t)(row_off + n0 + n) * K + k0 + 8 * c) = o; }
	s_waitcnt lgkmcnt(0)
	ds_read2_b32 v[18:19], v22 offset1:8
	ds_read2_b32 v[32:33], v22 offset0:33 offset1:41
	ds_read2_b32 v[34:35], v22 offset0:66 offset1:74
	ds_read2_b32 v[36:37], v22 offset0:99 offset1:107
	ds_read2_b32 v[38:39], v22 offset0:132 offset1:140
	ds_read2_b32 v[40:41], v22 offset0:165 offset1:173
	s_waitcnt lgkmcnt(5)
	s_waitcnt lgkmcnt(4)
	v_cvt_pk_bf16_f32 v26, v18, v32
	s_waitcnt lgkmcnt(3)
	s_waitcnt lgkmcnt(2)
	ds_read2_b32 v[42:43], v22 offset0:198 offset1:206
	ds_read2_b32 v[44:45], v22 offset0:231 offset1:239
	v_cvt_pk_bf16_f32 v27, v34, v36
	s_waitcnt lgkmcnt(3)
	s_waitcnt lgkmcnt(2)
	v_cvt_pk_bf16_f32 v28, v38, v40
	s_waitcnt lgkmcnt(1)
	s_waitcnt lgkmcnt(0)
	s_nop 0
	s_nop 0
	s_nop 0
	s_lshl_b32 s0, s5, 1
	v_cvt_pk_bf16_f32 v29, v42, v44
	v_or_b32_e32 v3, s4, v21
	v_lshl_add_u64 v[30:31], v[8:9], 0, s[0:1]
	v_lshlrev_b32_e32 v4, 12, v3
	v_bfe_u32 v3, v19, 16, 1
	v_lshl_add_u64 v[46:47], v[30:31], 0, v[4:5]
	v_add3_u32 v3, v19, v3, s10
	v_bfe_u32 v4, v33, 16, 1
	v_lshrrev_b32_e32 v3, 16, v3
	v_add3_u32 v4, v33, v4, s10
	global_store_dwordx4 v[46:47], v[26:29], off
	ds_read2_b32 v[18:19], v22 offset0:16 offset1:24
	s_nop 0
	v_and_or_b32 v26, v4, s11, v3
	s_nop 0
	s_nop 0
	s_nop 0
	s_nop 0
	s_nop 0
	v_cvt_pk_bf16_f32 v27, v35, v37
	v_cvt_pk_bf16_f32 v28, v39, v41
	s_nop 0
	s_nop 0
	v_cvt_pk_bf16_f32 v29, v43, v45
	v_or_b32_e32 v3, s4, v23
	v_lshlrev_b32_e32 v4, 12, v3
	v_lshl_add_u64 v[32:33], v[30:31], 0, v[4:5]
	global_store_dwordx4 v[32:33], v[26:29], off
	ds_read2_b32 v[32:33], v22 offset0:49 offset1:57
	ds_read2_b32 v[34:35], v22 offset0:82 offset1:90
	ds_read2_b32 v[36:37], v22 offset0:115 offset1:123
	s_waitcnt lgkmcnt(3)
	s_nop 0
	s_nop 0
	s_waitcnt lgkmcnt(2)
	ds_read2_b32 v[38:39], v22 offset0:148 offset1:156
	ds_read2_b32 v[40:41], v22 offset0:181 offset1:189
	v_cvt_pk_bf16_f32 v26, v18, v32
	s_waitcnt lgkmcnt(3)
	s_waitcnt lgkmcnt(2)
	ds_read2_b32 v[42:43], v22 offset0:214 offset1:222
	ds_read2_b32 v[44:45], v22 offset0:247 offset1:255
	v_cvt_pk_bf16_f32 v27, v34, v36
	s_waitcnt lgkmcnt(3)
	s_waitcnt lgkmcnt(2)
	v_cvt_pk_bf16_f32 v28, v38, v40
	s_waitcnt lgkmcnt(1)
	s_waitcnt lgkmcnt(0)
	v_cvt_pk_bf16_f32 v29, v42, v44
	v_or_b32_e32 v3, s4, v24
	v_lshlrev_b32_e32 v4, 12, v3
	s_nop 0
	v_lshl_add_u64 v[46:47], v[30:31], 0, v[4:5]
	s_nop 0
	s_nop 0
	s_nop 0
	s_nop 0
	global_store_dwordx4 v[46:47], v[26:29], off
	s_nop 1
	v_cvt_pk_bf16_f32 v26, v19, v33
	s_nop 0
	s_nop 0
	s_nop 0
	s_nop 0
	s_nop 0
	v_cvt_pk_bf16_f32 v27, v35, v37
	v_cvt_pk_bf16_f32 v28, v39, v41
	s_nop 0
	s_nop 0
	v_cvt_pk_bf16_f32 v29, v43, v45
	v_or_b32_e32 v3, s4, v25
	v_lshlrev_b32_e32 v4, 12, v3
	v_lshl_add_u64 v[18:19], v[30:31], 0, v[4:5]
	global_store_dwordx4 v[18:19], v[26:29], off
	s_waitcnt lgkmcnt(0)

; #define LAS __attribute__((address_space(3)))
; #define LDS_WAIT() asm volatile("s_waitcnt lgkmcnt(0)" ::: "memory")
; __device__ __forceinline__ void transpose_item(const float* W, int K, int N, bf16* WT, int row_off, LAS float* scr, int item, int lane) {
;     const int nblk = N / 32, kb = item / nblk, nb = item % nblk, k0 = 64 * kb, n0 = 32 * nb;
; #pragma unroll 8
;     for (int i = 0; i < 32; ++i) { const int kk = 2 * i + (lane >> 5); scr[kk * 33 + (lane & 31)] = W[(size_t)(k0 + kk) * N + n0 + (lane & 31)]; }
;     LDS_WAIT(); asm volatile("" ::: "memory");
.LBB0_511:
	s_lshl_b32 s28, s0, 1
	s_lshl_b32 s29, s5, 1
	s_waitcnt vmcnt(4)
	v_or_b32_e32 v28, s29, v4
	s_add_i32 s30, s28, 4
	s_add_i32 s31, s29, 4
	s_add_i32 s33, s28, 8
	s_add_i32 s34, s29, 8
	s_add_i32 s35, s28, 12
	s_add_i32 s52, s29, 12
	s_add_i32 s53, s28, 16
	s_add_i32 s54, s29, 16
	s_add_i32 s55, s28, 20
	s_add_i32 s56, s29, 20
	s_add_i32 s57, s28, 24
	s_add_i32 s58, s29, 24
	s_add_i32 s59, s28, 28
	s_add_i32 s60, s29, 28
	v_or_b32_e32 v26, s28, v3
	v_ashrrev_i32_e32 v29, 31, v28
	v_or_b32_e32 v30, s30, v3
	v_or_b32_e32 v32, s31, v4
	v_or_b32_e32 v34, s33, v3
	v_or_b32_e32 v36, s34, v4
	v_or_b32_e32 v38, s35, v3
	v_or_b32_e32 v40, s52, v4
	v_or_b32_e32 v42, s53, v3
	v_or_b32_e32 v44, s54, v4
	v_or_b32_e32 v46, s55, v3
	v_or_b32_e32 v48, s56, v4
	v_or_b32_e32 v50, s57, v3
	v_or_b32_e32 v52, s58, v4
	v_or_b32_e32 v54, s59, v3
	v_or_b32_e32 v56, s60, v4
	v_ashrrev_i32_e32 v27, 31, v26
	v_lshlrev_b64 v[28:29], 13, v[28:29]
	v_ashrrev_i32_e32 v33, 31, v32
	v_ashrrev_i32_e32 v31, 31, v30
	v_ashrrev_i32_e32 v37, 31, v36
	v_ashrrev_i32_e32 v35, 31, v34
	v_ashrrev_i32_e32 v41, 31, v40
	v_ashrrev_i32_e32 v39, 31, v38
	v_ashrrev_i32_e32 v45, 31, v44
	v_ashrrev_i32_e32 v43, 31, v42
	v_ashrrev_i32_e32 v49, 31, v48
	v_ashrrev_i32_e32 v47, 31, v46
	v_ashrrev_i32_e32 v53, 31, v52
	v_ashrrev_i32_e32 v51, 31, v50
	v_ashrrev_i32_e32 v57, 31, v56
	v_ashrrev_i32_e32 v55, 31, v54
	v_lshlrev_b64 v[26:27], 13, v[26:27]
	v_lshl_add_u64 v[28:29], v[18:19], 0, v[28:29]
	v_lshlrev_b64 v[30:31], 13, v[30:31]
	v_lshlrev_b64 v[32:33], 13, v[32:33]
	v_lshlrev_b64 v[34:35], 13, v[34:35]
	v_lshlrev_b64 v[36:37], 13, v[36:37]
	v_lshlrev_b64 v[38:39], 13, v[38:39]
	v_lshlrev_b64 v[40:41], 13, v[40:41]
	v_lshlrev_b64 v[42:43], 13, v[42:43]
	v_lshlrev_b64 v[44:45], 13, v[44:45]
	v_lshlrev_b64 v[46:47], 13, v[46:47]
	v_lshlrev_b64 v[48:49], 13, v[48:49]
	v_lshlrev_b64 v[50:51], 13, v[50:51]
	v_lshlrev_b64 v[52:53], 13, v[52:53]
	v_lshlrev_b64 v[54:55], 13, v[54:55]
	v_lshlrev_b64 v[56:57], 13, v[56:57]
	v_lshl_add_u64 v[26:27], v[18:19], 0, v[26:27]
	v_lshl_add_u64 v[32:33], v[18:19], 0, v[32:33]
	v_lshl_add_u64 v[30:31], v[18:19], 0, v[30:31]
	v_lshl_add_u64 v[36:37], v[18:19], 0, v[36:37]
	v_lshl_add_u64 v[34:35], v[18:19], 0, v[34:35]
	v_lshl_add_u64 v[40:41], v[18:19], 0, v[40:41]
	v_lshl_add_u64 v[38:39], v[18:19], 0, v[38:39]
	v_lshl_add_u64 v[44:45], v[18:19], 0, v[44:45]
	v_lshl_add_u64 v[42:43], v[18:19], 0, v[42:43]
	v_lshl_add_u64 v[48:49], v[18:19], 0, v[48:49]
	v_lshl_add_u64 v[46:47], v[18:19], 0, v[46:47]
	v_lshl_add_u64 v[52:53], v[18:19], 0, v[52:53]
	v_lshl_add_u64 v[50:51], v[18:19], 0, v[50:51]
	v_lshl_add_u64 v[56:57], v[18:19], 0, v[56:57]
	v_lshl_add_u64 v[54:55], v[18:19], 0, v[54:55]
	global_load_dword v20, v[28:29], off
	global_load_dword v58, v[26:27], off
	global_load_dword v59, v[32:33], off
	global_load_dword v60, v[30:31], off
	global_load_dword v61, v[36:37], off
	global_load_dword v62, v[34:35], off
	global_load_dword v63, v[40:41], off
	global_load_dword v64, v[38:39], off
	global_load_dword v65, v[44:45], off
	global_load_dword v66, v[42:43], off
	global_load_dword v67, v[48:49], off
	global_load_dword v68, v[46:47], off
	global_load_dword v69, v[52:53], off
	global_load_dword v70, v[50:51], off
	global_load_dword v71, v[56:57], off
	global_load_dword v72, v[54:55], off
	v_or_b32_e32 v28, s28, v1
	v_or_b32_e32 v26, s29, v0
	s_add_i32 s5, s5, 16
	s_add_i32 s0, s0, 16
	s_add_i32 s9, s9, -16
	v_mad_u64_u32 v[26:27], s[28:29], v26, s7, v[2:3]
	v_mad_u64_u32 v[28:29], s[28:29], v28, s7, v[2:3]
	v_or_b32_e32 v27, s30, v1
	v_or_b32_e32 v29, s31, v0
	v_or_b32_e32 v36, s33, v1
	v_or_b32_e32 v34, s34, v0
	v_or_b32_e32 v40, s35, v1
	v_or_b32_e32 v38, s52, v0
	v_or_b32_e32 v44, s53, v1
	v_or_b32_e32 v42, s54, v0
	v_or_b32_e32 v48, s55, v1
	v_or_b32_e32 v46, s56, v0
	v_or_b32_e32 v52, s57, v1
	v_or_b32_e32 v50, s58, v0
	v_or_b32_e32 v56, s59, v1
	v_or_b32_e32 v54, s60, v0
	s_cmp_lg_u32 s9, 0
	v_mad_u64_u32 v[30:31], s[28:29], v29, s7, v[2:3]
	v_mad_u64_u32 v[32:33], s[28:29], v27, s7, v[2:3]
	v_mad_u64_u32 v[34:35], s[28:29], v34, s7, v[2:3]
	v_mad_u64_u32 v[36:37], s[28:29], v36, s7, v[2:3]
	v_mad_u64_u32 v[38:39], s[28:29], v38, s7, v[2:3]
	v_mad_u64_u32 v[40:41], s[28:29], v40, s7, v[2:3]
	v_mad_u64_u32 v[42:43], s[28:29], v42, s7, v[2:3]
	v_mad_u64_u32 v[44:45], s[28:29], v44, s7, v[2:3]
	v_mad_u64_u32 v[46:47], s[28:29], v46, s7, v[2:3]
	v_mad_u64_u32 v[48:49], s[28:29], v48, s7, v[2:3]
	v_mad_u64_u32 v[50:51], s[28:29], v50, s7, v[2:3]
	v_mad_u64_u32 v[52:53], s[28:29], v52, s7, v[2:3]
	v_mad_u64_u32 v[54:55], s[28:29], v54, s7, v[2:3]
	v_mad_u64_u32 v[56:57], s[28:29], v56, s7, v[2:3]
	s_waitcnt vmcnt(15)
	ds_write_b32 v26, v20
	s_waitcnt vmcnt(14)
	ds_write_b32 v28, v58
	s_waitcnt vmcnt(13)
	ds_write_b32 v30, v59
	s_waitcnt vmcnt(12)
	ds_write_b32 v32, v60
	s_waitcnt vmcnt(11)
	ds_write_b32 v34, v61
	s_waitcnt vmcnt(10)
	ds_write_b32 v36, v62
	s_waitcnt vmcnt(9)
	ds_write_b32 v38, v63
	s_waitcnt vmcnt(8)
	ds_write_b32 v40, v64
	s_waitcnt vmcnt(7)
	ds_write_b32 v42, v65
	s_waitcnt vmcnt(6)
	ds_write_b32 v44, v66
	s_waitcnt vmcnt(5)
	ds_write_b32 v46, v67
	s_waitcnt vmcnt(4)
	ds_write_b32 v48, v68
	s_waitcnt vmcnt(3)
	ds_write_b32 v50, v69
	s_waitcnt vmcnt(2)
	ds_write_b32 v52, v70
	s_waitcnt vmcnt(1)
	ds_write_b32 v54, v71
	s_waitcnt vmcnt(0)
	ds_write_b32 v56, v72
	s_cbranch_scc1 .LBB0_511
; #define LAS __attribute__((address_space(3)))
; #define LDS_WAIT() asm volatile("s_waitcnt lgkmcnt(0)" ::: "memory")
; __device__ __forceinline__ unsigned pk2(float lo, float hi) { return f2bf(lo) | (f2bf(hi) << 16); }
; __device__ __forceinline__ void transpose_item(const float* W, int K, int N, bf16* WT, int row_off, LAS float* scr, int item, int lane) {
;     ...
;     const int c = lane & 7;
; #pragma unroll
;     for (int j = 0; j < 4; ++j) { const int n = (lane >> 3) + 8 * j; const LAS float* s = scr + (8 * c) * 33 + n;
;         u32x4 o; o.x = pk2(s[0 * 33], s[1 * 33]); o.y = pk2(s[2 * 33], s[3 * 33]); o.z = pk2(s[4 * 33], s[5 * 33]); o.w = pk2(s[6 * 33], s[7 * 33]);
;         *(u32x4*)(WT + (size_t)(row_off + n0 + n) * K + k0 + 8 * c) = o; }
;     LDS_WAIT(); asm volatile("" ::: "memory");
	s_waitcnt lgkmcnt(0)
	ds_read2_b32 v[18:19], v22 offset1:8
	ds_read2_b32 v[32:33], v22 offset0:33 offset1:41
	ds_read2_b32 v[34:35], v22 offset0:66 offset1:74
	ds_read2_b32 v[36:37], v22 offset0:99 offset1:107
	ds_read2_b32 v[38:39], v22 offset0:132 offset1:140
	ds_read2_b32 v[40:41], v22 offset0:165 offset1:173
	s_waitcnt lgkmcnt(5)
	s_waitcnt lgkmcnt(4)
	v_cvt_pk_bf16_f32 v26, v18, v32
	s_waitcnt lgkmcnt(3)
	s_waitcnt lgkmcnt(2)
	ds_read2_b32 v[42:43], v22 offset0:198 offset1:206
	ds_read2_b32 v[44:45], v22 offset0:231 offset1:239
	v_cvt_pk_bf16_f32 v27, v34, v36
	s_waitcnt lgkmcnt(3)
	s_waitcnt lgkmcnt(2)
	v_cvt_pk_bf16_f32 v28, v38, v40
	s_waitcnt lgkmcnt(1)
	s_waitcnt lgkmcnt(0)
	s_nop 0
	v_or_b32_e32 v46, s4, v21
	s_ashr_i32 s9, s8, 31
	v_cvt_pk_bf16_f32 v29, v42, v44
	v_ashrrev_i32_e32 v47, 31, v46
	v_bfe_u32 v3, v19, 16, 1
	v_lshl_add_u64 v[30:31], s[8:9], 1, v[10:11]
	v_lshlrev_b64 v[46:47], 12, v[46:47]
	v_add3_u32 v3, v19, v3, s10
	v_bfe_u32 v4, v33, 16, 1
	v_lshl_add_u64 v[46:47], v[30:31], 0, v[46:47]
	v_lshrrev_b32_e32 v3, 16, v3
	v_add3_u32 v4, v33, v4, s10
	global_store_dwordx4 v[46:47], v[26:29], off
	v_or_b32_e32 v18, s4, v23
	v_ashrrev_i32_e32 v19, 31, v18
	v_and_or_b32 v26, v4, s11, v3
	s_nop 0
	s_nop 0
	s_nop 0
	v_cvt_pk_bf16_f32 v27, v35, v37
	v_cvt_pk_bf16_f32 v28, v39, v41
	s_nop 0
	s_nop 0
	v_lshlrev_b64 v[18:19], 12, v[18:19]
	v_cvt_pk_bf16_f32 v29, v43, v45
	ds_read2_b32 v[32:33], v22 offset0:16 offset1:24
	v_lshl_add_u64 v[18:19], v[30:31], 0, v[18:19]
	global_store_dwordx4 v[18:19], v[26:29], off
	ds_read2_b32 v[18:19], v22 offset0:49 offset1:57
	ds_read2_b32 v[34:35], v22 offset0:82 offset1:90
	ds_read2_b32 v[36:37], v22 offset0:115 offset1:123
	s_waitcnt lgkmcnt(3)
	s_nop 0
	s_nop 0
	s_waitcnt lgkmcnt(2)
	ds_read2_b32 v[38:39], v22 offset0:148 offset1:156
	ds_read2_b32 v[40:41], v22 offset0:181 offset1:189
	v_cvt_pk_bf16_f32 v26, v32, v18
	s_waitcnt lgkmcnt(3)
	s_waitcnt lgkmcnt(2)
	ds_read2_b32 v[42:43], v22 offset0:214 offset1:222
	ds_read2_b32 v[44:45], v22 offset0:247 offset1:255
	v_cvt_pk_bf16_f32 v27, v34, v36
	s_waitcnt lgkmcnt(3)
	s_waitcnt lgkmcnt(2)
	v_cvt_pk_bf16_f32 v28, v38, v40
	s_waitcnt lgkmcnt(1)
	s_waitcnt lgkmcnt(0)
	v_or_b32_e32 v46, s4, v24
	v_cvt_pk_bf16_f32 v29, v42, v44
	v_ashrrev_i32_e32 v47, 31, v46
	v_bfe_u32 v3, v33, 16, 1
	v_lshlrev_b64 v[46:47], 12, v[46:47]
	v_add3_u32 v3, v33, v3, s10
	v_bfe_u32 v4, v19, 16, 1
	v_lshl_add_u64 v[46:47], v[30:31], 0, v[46:47]
	v_lshrrev_b32_e32 v3, 16, v3
	v_add3_u32 v4, v19, v4, s10
	global_store_dwordx4 v[46:47], v[26:29], off
	v_or_b32_e32 v18, s4, v25
	v_ashrrev_i32_e32 v19, 31, v18
	v_and_or_b32 v26, v4, s11, v3
	s_nop 0
	s_nop 0
	s_nop 0
	v_cvt_pk_bf16_f32 v27, v35, v37
	v_cvt_pk_bf16_f32 v28, v39, v41
	v_bfe_u32 v3, v43, 16, 1
	v_add3_u32 v3, v43, v3, s10
	v_bfe_u32 v4, v45, 16, 1
	v_lshrrev_b32_e32 v3, 16, v3
	v_add3_u32 v4, v45, v4, s10
	v_lshlrev_b64 v[18:19], 12, v[18:19]
	v_and_or_b32 v29, v4, s11, v3
	v_lshl_add_u64 v[18:19], v[30:31], 0, v[18:19]
	global_store_dwordx4 v[18:19], v[26:29], off
	s_waitcnt lgkmcnt(0)
	s_branch .LBB0_498

;     __device__ __forceinline__ void operator()(const pg8::f32x4 (&acc)[2][2][4][2], const pg8::Unit& u, int wr, int wc, int fr, int fq) const {
;         const int R0 = u.pm * 256; const float* src; float* dst; int mv;
;         if (R0 < ML) { src = srcL + (size_t)R0 * D; dst = dstL + (size_t)R0 * D; mv = (R0 >= SEQ) ? 1 : 0; }
;         else { src = srcC + (size_t)(R0 - ML) * D; dst = dstC + (size_t)(R0 - ML) * D; mv = 2; }
;         const int col0 = u.pn * 256 + wc * 32 + 4 * fq; const float* gt = gate + mv * NMOD + col0;
;         pg8::f32x4 gv[2][2];
; #pragma unroll
;         for (int bj = 0; bj < 2; ++bj)
; #pragma unroll
;             for (int n = 0; n < 2; ++n) gv[bj][n] = *(const pg8::f32x4*)(gt + bj * 128 + n * 16);
; #pragma unroll
;         for (int ai = 0; ai < 2; ++ai)
; #pragma unroll
;             for (int m = 0; m < 4; ++m) { const size_t off = (size_t)(wr * 64 + fr + ai * 128 + m * 16) * D + col0;
; #pragma unroll
;                 for (int bj = 0; bj < 2; ++bj)
; #pragma unroll
;                     for (int n = 0; n < 2; ++n) { const pg8::f32x4 s = *(const pg8::f32x4*)(src + off + bj * 128 + n * 16);
;                         *(pg8::f32x4*)(dst + off + bj * 128 + n * 16) = s * ALPHA + gv[bj][n] * acc[ai][bj][m][n]; }
;                 asm volatile("" ::: "memory"); }
;     }
.LBB0_717:
	v_lshl_or_b32 v172, s53, 8, v181
	v_ashrrev_i32_e32 v173, 31, v172
	s_lshl_b32 s4, s78, 2
	s_add_u32 s56, s90, s4
	s_addc_u32 s57, s91, 0
	v_lshl_add_u64 v[128:129], v[172:173], 2, s[56:57]
	global_load_dwordx4 v[140:143], v[128:129], off
	global_load_dwordx4 v[136:139], v[128:129], off offset:64
	global_load_dwordx4 v[132:135], v[128:129], off offset:512
	s_nop 0
	global_load_dwordx4 v[128:131], v[128:129], off offset:576
	s_andn2_b64 vcc, exec, s[0:1]
	s_mov_b64 s[0:1], -1
	v_lshl_add_u64 v[226:227], v[148:149], 0, v[172:173]
	v_lshlrev_b64 v[226:227], 2, v[226:227]
	v_lshl_add_u64 v[226:227], s[88:89], 0, v[226:227]
	global_load_dwordx4 v[186:189], v[226:227], off
	global_load_dwordx4 v[190:193], v[226:227], off offset:64
	global_load_dwordx4 v[194:197], v[226:227], off offset:512
	global_load_dwordx4 v[198:201], v[226:227], off offset:576
	v_lshl_add_u64 v[226:227], v[150:151], 0, v[172:173]
	v_lshlrev_b64 v[226:227], 2, v[226:227]
	v_lshl_add_u64 v[226:227], s[88:89], 0, v[226:227]
	global_load_dwordx4 v[202:205], v[226:227], off
	global_load_dwordx4 v[206:209], v[226:227], off offset:64
	global_load_dwordx4 v[210:213], v[226:227], off offset:512
	global_load_dwordx4 v[214:217], v[226:227], off offset:576
	v_lshl_add_u64 v[228:229], v[148:149], 0, v[172:173]
	v_lshlrev_b64 v[228:229], 2, v[228:229]
	v_lshl_add_u64 v[228:229], s[86:87], 0, v[228:229]
	s_waitcnt vmcnt(7)
	v_pk_mul_f32 v[188:189], v[188:189], s[34:35] op_sel_hi:[1,0]
	v_pk_mul_f32 v[186:187], v[186:187], s[34:35] op_sel_hi:[1,0]
	v_pk_fma_f32 v[188:189], v[126:127], v[142:143], v[188:189]
	v_pk_fma_f32 v[186:187], v[124:125], v[140:141], v[186:187]
	global_store_dwordx4 v[228:229], v[186:189], off
	s_waitcnt vmcnt(7)
	v_pk_mul_f32 v[192:193], v[192:193], s[34:35] op_sel_hi:[1,0]
	v_pk_mul_f32 v[190:191], v[190:191], s[34:35] op_sel_hi:[1,0]
	v_pk_fma_f32 v[192:193], v[122:123], v[138:139], v[192:193]
	v_pk_fma_f32 v[190:191], v[120:121], v[136:137], v[190:191]
	global_store_dwordx4 v[228:229], v[190:193], off offset:64
	s_waitcnt vmcnt(7)
	v_pk_mul_f32 v[196:197], v[196:197], s[34:35] op_sel_hi:[1,0]
	v_pk_mul_f32 v[194:195], v[194:195], s[34:35] op_sel_hi:[1,0]
	v_pk_fma_f32 v[196:197], v[118:119], v[134:135], v[196:197]
	v_pk_fma_f32 v[194:195], v[116:117], v[132:133], v[194:195]
	global_store_dwordx4 v[228:229], v[194:197], off offset:512
	s_waitcnt vmcnt(7)
	v_pk_mul_f32 v[200:201], v[200:201], s[34:35] op_sel_hi:[1,0]
	v_pk_mul_f32 v[198:199], v[198:199], s[34:35] op_sel_hi:[1,0]
	v_pk_fma_f32 v[200:201], v[110:111], v[130:131], v[200:201]
	v_pk_fma_f32 v[198:199], v[108:109], v[128:129], v[198:199]
	global_store_dwordx4 v[228:229], v[198:201], off offset:576
	s_nop 1
	v_lshl_add_u64 v[228:229], v[150:151], 0, v[172:173]
	v_lshlrev_b64 v[228:229], 2, v[228:229]
	v_lshl_add_u64 v[228:229], s[86:87], 0, v[228:229]
	s_waitcnt vmcnt(7)
	v_pk_mul_f32 v[204:205], v[204:205], s[34:35] op_sel_hi:[1,0]
	v_pk_mul_f32 v[202:203], v[202:203], s[34:35] op_sel_hi:[1,0]
	v_pk_fma_f32 v[204:205], v[114:115], v[142:143], v[204:205]
	v_pk_fma_f32 v[202:203], v[112:113], v[140:141], v[202:203]
	global_store_dwordx4 v[228:229], v[202:205], off
	s_waitcnt vmcnt(7)
	v_pk_mul_f32 v[208:209], v[208:209], s[34:35] op_sel_hi:[1,0]
	v_pk_mul_f32 v[206:207], v[206:207], s[34:35] op_sel_hi:[1,0]
	v_pk_fma_f32 v[208:209], v[106:107], v[138:139], v[208:209]
	v_pk_fma_f32 v[206:207], v[104:105], v[136:137], v[206:207]
	global_store_dwordx4 v[228:229], v[206:209], off offset:64
	s_waitcnt vmcnt(7)
	v_pk_mul_f32 v[212:213], v[212:213], s[34:35] op_sel_hi:[1,0]
	v_pk_mul_f32 v[210:211], v[210:211], s[34:35] op_sel_hi:[1,0]
	v_pk_fma_f32 v[212:213], v[102:103], v[134:135], v[212:213]
	v_pk_fma_f32 v[210:211], v[100:101], v[132:133], v[210:211]
	global_store_dwordx4 v[228:229], v[210:213], off offset:512
	s_waitcnt vmcnt(7)
	v_pk_mul_f32 v[216:217], v[216:217], s[34:35] op_sel_hi:[1,0]
	v_pk_mul_f32 v[214:215], v[214:215], s[34:35] op_sel_hi:[1,0]
	v_pk_fma_f32 v[216:217], v[94:95], v[130:131], v[216:217]
	v_pk_fma_f32 v[214:215], v[92:93], v[128:129], v[214:215]
	global_store_dwordx4 v[228:229], v[214:217], off offset:576
	s_nop 1
	v_lshl_add_u64 v[226:227], v[152:153], 0, v[172:173]
	v_lshlrev_b64 v[226:227], 2, v[226:227]
	v_lshl_add_u64 v[226:227], s[88:89], 0, v[226:227]
	global_load_dwordx4 v[124:127], v[226:227], off
	global_load_dwordx4 v[120:123], v[226:227], off offset:64
	global_load_dwordx4 v[116:119], v[226:227], off offset:512
	global_load_dwordx4 v[108:111], v[226:227], off offset:576
	v_lshl_add_u64 v[226:227], v[154:155], 0, v[172:173]
	v_lshlrev_b64 v[226:227], 2, v[226:227]
	v_lshl_add_u64 v[226:227], s[88:89], 0, v[226:227]
	global_load_dwordx4 v[112:115], v[226:227], off
	global_load_dwordx4 v[104:107], v[226:227], off offset:64
	global_load_dwordx4 v[100:103], v[226:227], off offset:512
	global_load_dwordx4 v[92:95], v[226:227], off offset:576
	v_lshl_add_u64 v[226:227], v[156:157], 0, v[172:173]
	v_lshlrev_b64 v[226:227], 2, v[226:227]
	v_lshl_add_u64 v[226:227], s[88:89], 0, v[226:227]
	global_load_dwordx4 v[218:221], v[226:227], off
	global_load_dwordx4 v[222:225], v[226:227], off offset:64
	global_load_dwordx4 v[230:233], v[226:227], off offset:512
	global_load_dwordx4 v[186:189], v[226:227], off offset:576
	v_lshl_add_u64 v[228:229], v[152:153], 0, v[172:173]
	v_lshlrev_b64 v[228:229], 2, v[228:229]
	v_lshl_add_u64 v[228:229], s[86:87], 0, v[228:229]
	s_waitcnt vmcnt(11)
	v_pk_mul_f32 v[126:127], v[126:127], s[34:35] op_sel_hi:[1,0]
	v_pk_mul_f32 v[124:125], v[124:125], s[34:35] op_sel_hi:[1,0]
	v_pk_fma_f32 v[126:127], v[98:99], v[142:143], v[126:127]
	v_pk_fma_f32 v[124:125], v[96:97], v[140:141], v[124:125]
	global_store_dwordx4 v[228:229], v[124:127], off
	s_waitcnt vmcnt(11)
;     __device__ __forceinline__ void operator()(const pg8::f32x4 (&acc)[2][2][4][2], const pg8::Unit& u, int wr, int wc, int fr, int fq) const {
;         const int R0 = u.pm * 256; const float* src; float* dst; int mv;
;         if (R0 < ML) { src = srcL + (size_t)R0 * D; dst = dstL + (size_t)R0 * D; mv = (R0 >= SEQ) ? 1 : 0; }
;         else { src = srcC + (size_t)(R0 - ML) * D; dst = dstC + (size_t)(R0 - ML) * D; mv = 2; }
;         const int col0 = u.pn * 256 + wc * 32 + 4 * fq; const float* gt = gate + mv * NMOD + col0;
;         pg8::f32x4 gv[2][2];
; #pragma unroll
;         for (int bj = 0; bj < 2; ++bj)
; #pragma unroll
;             for (int n = 0; n < 2; ++n) gv[bj][n] = *(const pg8::f32x4*)(gt + bj * 128 + n * 16);
; #pragma unroll
;         for (int ai = 0; ai < 2; ++ai)
; #pragma unroll
;             for (int m = 0; m < 4; ++m) { const size_t off = (size_t)(wr * 64 + fr + ai * 128 + m * 16) * D + col0;
; #pragma unroll
;                 for (int bj = 0; bj < 2; ++bj)
; #pragma unroll
;                     for (int n = 0; n < 2; ++n) { const pg8::f32x4 s = *(const pg8::f32x4*)(src + off + bj * 128 + n * 16);
;                         *(pg8::f32x4*)(dst + off + bj * 128 + n * 16) = s * ALPHA + gv[bj][n] * acc[ai][bj][m][n]; }
;                 asm volatile("" ::: "memory"); }
;     }
	v_pk_mul_f32 v[122:123], v[122:123], s[34:35] op_sel_hi:[1,0]
	v_pk_mul_f32 v[120:121], v[120:121], s[34:35] op_sel_hi:[1,0]
	v_pk_fma_f32 v[122:123], v[90:91], v[138:139], v[122:123]
	v_pk_fma_f32 v[120:121], v[88:89], v[136:137], v[120:121]
	global_store_dwordx4 v[228:229], v[120:123], off offset:64
	s_waitcnt vmcnt(11)
	v_pk_mul_f32 v[118:119], v[118:119], s[34:35] op_sel_hi:[1,0]
	v_pk_mul_f32 v[116:117], v[116:117], s[34:35] op_sel_hi:[1,0]
	v_pk_fma_f32 v[118:119], v[86:87], v[134:135], v[118:119]
	v_pk_fma_f32 v[116:117], v[84:85], v[132:133], v[116:117]
	global_store_dwordx4 v[228:229], v[116:119], off offset:512
	s_waitcnt vmcnt(11)
	v_pk_mul_f32 v[110:111], v[110:111], s[34:35] op_sel_hi:[1,0]
	v_pk_mul_f32 v[108:109], v[108:109], s[34:35] op_sel_hi:[1,0]
	v_pk_fma_f32 v[110:111], v[78:79], v[130:131], v[110:111]
	v_pk_fma_f32 v[108:109], v[76:77], v[128:129], v[108:109]
	global_store_dwordx4 v[228:229], v[108:111], off offset:576
	s_nop 1
	v_lshl_add_u64 v[228:229], v[154:155], 0, v[172:173]
	v_lshlrev_b64 v[228:229], 2, v[228:229]
	v_lshl_add_u64 v[228:229], s[86:87], 0, v[228:229]
	s_waitcnt vmcnt(11)
	v_pk_mul_f32 v[114:115], v[114:115], s[34:35] op_sel_hi:[1,0]
	v_pk_mul_f32 v[112:113], v[112:113], s[34:35] op_sel_hi:[1,0]
	v_pk_fma_f32 v[114:115], v[82:83], v[142:143], v[114:115]
	v_pk_fma_f32 v[112:113], v[80:81], v[140:141], v[112:113]
	global_store_dwordx4 v[228:229], v[112:115], off
	s_waitcnt vmcnt(11)
	v_pk_mul_f32 v[106:107], v[106:107], s[34:35] op_sel_hi:[1,0]
	v_pk_mul_f32 v[104:105], v[104:105], s[34:35] op_sel_hi:[1,0]
	v_pk_fma_f32 v[106:107], v[74:75], v[138:139], v[106:107]
	v_pk_fma_f32 v[104:105], v[72:73], v[136:137], v[104:105]
	global_store_dwordx4 v[228:229], v[104:107], off offset:64
	s_waitcnt vmcnt(11)
	v_pk_mul_f32 v[102:103], v[102:103], s[34:35] op_sel_hi:[1,0]
	v_pk_mul_f32 v[100:101], v[100:101], s[34:35] op_sel_hi:[1,0]
	v_pk_fma_f32 v[102:103], v[70:71], v[134:135], v[102:103]
	v_pk_fma_f32 v[100:101], v[68:69], v[132:133], v[100:101]
	global_store_dwordx4 v[228:229], v[100:103], off offset:512
	s_waitcnt vmcnt(11)
	v_pk_mul_f32 v[94:95], v[94:95], s[34:35] op_sel_hi:[1,0]
	v_pk_mul_f32 v[92:93], v[92:93], s[34:35] op_sel_hi:[1,0]
	v_pk_fma_f32 v[94:95], v[66:67], v[130:131], v[94:95]
	v_pk_fma_f32 v[92:93], v[64:65], v[128:129], v[92:93]
	global_store_dwordx4 v[228:229], v[92:95], off offset:576
	s_nop 1
	v_lshl_add_u64 v[228:229], v[156:157], 0, v[172:173]
	v_lshlrev_b64 v[228:229], 2, v[228:229]
	v_lshl_add_u64 v[228:229], s[86:87], 0, v[228:229]
	s_waitcnt vmcnt(11)
	v_pk_mul_f32 v[220:221], v[220:221], s[34:35] op_sel_hi:[1,0]
	v_pk_mul_f32 v[218:219], v[218:219], s[34:35] op_sel_hi:[1,0]
	v_pk_fma_f32 v[220:221], v[62:63], v[142:143], v[220:221]
	v_pk_fma_f32 v[218:219], v[60:61], v[140:141], v[218:219]
	global_store_dwordx4 v[228:229], v[218:221], off
	s_waitcnt vmcnt(11)
	v_pk_mul_f32 v[224:225], v[224:225], s[34:35] op_sel_hi:[1,0]
	v_pk_mul_f32 v[222:223], v[222:223], s[34:35] op_sel_hi:[1,0]
	v_pk_fma_f32 v[224:225], v[58:59], v[138:139], v[224:225]
	v_pk_fma_f32 v[222:223], v[56:57], v[136:137], v[222:223]
	global_store_dwordx4 v[228:229], v[222:225], off offset:64
	s_waitcnt vmcnt(11)
	v_pk_mul_f32 v[232:233], v[232:233], s[34:35] op_sel_hi:[1,0]
	v_pk_mul_f32 v[230:231], v[230:231], s[34:35] op_sel_hi:[1,0]
	v_pk_fma_f32 v[232:233], v[54:55], v[134:135], v[232:233]
	v_pk_fma_f32 v[230:231], v[52:53], v[132:133], v[230:231]
	global_store_dwordx4 v[228:229], v[230:233], off offset:512
	s_waitcnt vmcnt(11)
	v_pk_mul_f32 v[188:189], v[188:189], s[34:35] op_sel_hi:[1,0]
	v_pk_mul_f32 v[186:187], v[186:187], s[34:35] op_sel_hi:[1,0]
	v_pk_fma_f32 v[188:189], v[46:47], v[130:131], v[188:189]
	v_pk_fma_f32 v[186:187], v[44:45], v[128:129], v[186:187]
	global_store_dwordx4 v[228:229], v[186:189], off offset:576
	s_nop 1
	v_lshl_add_u64 v[226:227], v[158:159], 0, v[172:173]
	v_lshlrev_b64 v[226:227], 2, v[226:227]
	v_lshl_add_u64 v[226:227], s[88:89], 0, v[226:227]
	global_load_dwordx4 v[190:193], v[226:227], off
	global_load_dwordx4 v[194:197], v[226:227], off offset:64
	global_load_dwordx4 v[198:201], v[226:227], off offset:512
	global_load_dwordx4 v[202:205], v[226:227], off offset:576
	v_lshl_add_u64 v[226:227], v[160:161], 0, v[172:173]
	v_lshlrev_b64 v[226:227], 2, v[226:227]
	v_lshl_add_u64 v[226:227], s[88:89], 0, v[226:227]
	global_load_dwordx4 v[206:209], v[226:227], off
	global_load_dwordx4 v[210:213], v[226:227], off offset:64
	global_load_dwordx4 v[214:217], v[226:227], off offset:512
	global_load_dwordx4 v[96:99], v[226:227], off offset:576
	v_lshl_add_u64 v[226:227], v[162:163], 0, v[172:173]
	v_lshlrev_b64 v[226:227], 2, v[226:227]
	v_lshl_add_u64 v[226:227], s[88:89], 0, v[226:227]
	global_load_dwordx4 v[88:91], v[226:227], off
	global_load_dwordx4 v[84:87], v[226:227], off offset:64
	global_load_dwordx4 v[76:79], v[226:227], off offset:512
	global_load_dwordx4 v[80:83], v[226:227], off offset:576
	v_lshl_add_u64 v[228:229], v[158:159], 0, v[172:173]
	v_lshlrev_b64 v[228:229], 2, v[228:229]
	v_lshl_add_u64 v[228:229], s[86:87], 0, v[228:229]
	s_waitcnt vmcnt(11)
;     __device__ __forceinline__ void operator()(const pg8::f32x4 (&acc)[2][2][4][2], const pg8::Unit& u, int wr, int wc, int fr, int fq) const {
;         const int R0 = u.pm * 256; const float* src; float* dst; int mv;
;         if (R0 < ML) { src = srcL + (size_t)R0 * D; dst = dstL + (size_t)R0 * D; mv = (R0 >= SEQ) ? 1 : 0; }
;         else { src = srcC + (size_t)(R0 - ML) * D; dst = dstC + (size_t)(R0 - ML) * D; mv = 2; }
;         const int col0 = u.pn * 256 + wc * 32 + 4 * fq; const float* gt = gate + mv * NMOD + col0;
;         pg8::f32x4 gv[2][2];
; #pragma unroll
;         for (int bj = 0; bj < 2; ++bj)
; #pragma unroll
;             for (int n = 0; n < 2; ++n) gv[bj][n] = *(const pg8::f32x4*)(gt + bj * 128 + n * 16);
; #pragma unroll
;         for (int ai = 0; ai < 2; ++ai)
; #pragma unroll
;             for (int m = 0; m < 4; ++m) { const size_t off = (size_t)(wr * 64 + fr + ai * 128 + m * 16) * D + col0;
; #pragma unroll
;                 for (int bj = 0; bj < 2; ++bj)
; #pragma unroll
;                     for (int n = 0; n < 2; ++n) { const pg8::f32x4 s = *(const pg8::f32x4*)(src + off + bj * 128 + n * 16);
;                         *(pg8::f32x4*)(dst + off + bj * 128 + n * 16) = s * ALPHA + gv[bj][n] * acc[ai][bj][m][n]; }
;                 asm volatile("" ::: "memory"); }
;     }
	v_pk_mul_f32 v[192:193], v[192:193], s[34:35] op_sel_hi:[1,0]
	v_pk_mul_f32 v[190:191], v[190:191], s[34:35] op_sel_hi:[1,0]
	v_pk_fma_f32 v[192:193], v[50:51], v[142:143], v[192:193]
	v_pk_fma_f32 v[190:191], v[48:49], v[140:141], v[190:191]
	global_store_dwordx4 v[228:229], v[190:193], off
	s_waitcnt vmcnt(11)
	v_pk_mul_f32 v[196:197], v[196:197], s[34:35] op_sel_hi:[1,0]
	v_pk_mul_f32 v[194:195], v[194:195], s[34:35] op_sel_hi:[1,0]
	v_pk_fma_f32 v[196:197], v[42:43], v[138:139], v[196:197]
	v_pk_fma_f32 v[194:195], v[40:41], v[136:137], v[194:195]
	global_store_dwordx4 v[228:229], v[194:197], off offset:64
	s_waitcnt vmcnt(11)
	v_pk_mul_f32 v[200:201], v[200:201], s[34:35] op_sel_hi:[1,0]
	v_pk_mul_f32 v[198:199], v[198:199], s[34:35] op_sel_hi:[1,0]
	v_pk_fma_f32 v[200:201], v[38:39], v[134:135], v[200:201]
	v_pk_fma_f32 v[198:199], v[36:37], v[132:133], v[198:199]
	global_store_dwordx4 v[228:229], v[198:201], off offset:512
	s_waitcnt vmcnt(11)
	v_pk_mul_f32 v[204:205], v[204:205], s[34:35] op_sel_hi:[1,0]
	v_pk_mul_f32 v[202:203], v[202:203], s[34:35] op_sel_hi:[1,0]
	v_pk_fma_f32 v[204:205], v[30:31], v[130:131], v[204:205]
	v_pk_fma_f32 v[202:203], v[28:29], v[128:129], v[202:203]
	global_store_dwordx4 v[228:229], v[202:205], off offset:576
	s_nop 1
	v_lshl_add_u64 v[228:229], v[160:161], 0, v[172:173]
	v_lshlrev_b64 v[228:229], 2, v[228:229]
	v_lshl_add_u64 v[228:229], s[86:87], 0, v[228:229]
	s_waitcnt vmcnt(11)
	v_pk_mul_f32 v[208:209], v[208:209], s[34:35] op_sel_hi:[1,0]
	v_pk_mul_f32 v[206:207], v[206:207], s[34:35] op_sel_hi:[1,0]
	v_pk_fma_f32 v[208:209], v[34:35], v[142:143], v[208:209]
	v_pk_fma_f32 v[206:207], v[32:33], v[140:141], v[206:207]
	global_store_dwordx4 v[228:229], v[206:209], off
	s_waitcnt vmcnt(11)
	v_pk_mul_f32 v[212:213], v[212:213], s[34:35] op_sel_hi:[1,0]
	v_pk_mul_f32 v[210:211], v[210:211], s[34:35] op_sel_hi:[1,0]
	v_pk_fma_f32 v[212:213], v[26:27], v[138:139], v[212:213]
	v_pk_fma_f32 v[210:211], v[24:25], v[136:137], v[210:211]
	global_store_dwordx4 v[228:229], v[210:213], off offset:64
	s_waitcnt vmcnt(11)
	v_pk_mul_f32 v[216:217], v[216:217], s[34:35] op_sel_hi:[1,0]
	v_pk_mul_f32 v[214:215], v[214:215], s[34:35] op_sel_hi:[1,0]
	v_pk_fma_f32 v[216:217], v[22:23], v[134:135], v[216:217]
	v_pk_fma_f32 v[214:215], v[20:21], v[132:133], v[214:215]
	global_store_dwordx4 v[228:229], v[214:217], off offset:512
	s_waitcnt vmcnt(11)
	v_pk_mul_f32 v[98:99], v[98:99], s[34:35] op_sel_hi:[1,0]
	v_pk_mul_f32 v[96:97], v[96:97], s[34:35] op_sel_hi:[1,0]
	v_pk_fma_f32 v[98:99], v[14:15], v[130:131], v[98:99]
	v_pk_fma_f32 v[96:97], v[12:13], v[128:129], v[96:97]
	global_store_dwordx4 v[228:229], v[96:99], off offset:576
	s_nop 1
	v_lshl_add_u64 v[228:229], v[162:163], 0, v[172:173]
	v_lshlrev_b64 v[228:229], 2, v[228:229]
	v_lshl_add_u64 v[228:229], s[86:87], 0, v[228:229]
	s_waitcnt vmcnt(11)
	v_pk_mul_f32 v[90:91], v[90:91], s[34:35] op_sel_hi:[1,0]
	v_pk_mul_f32 v[88:89], v[88:89], s[34:35] op_sel_hi:[1,0]
	v_pk_fma_f32 v[90:91], v[18:19], v[142:143], v[90:91]
	v_pk_fma_f32 v[88:89], v[16:17], v[140:141], v[88:89]
	global_store_dwordx4 v[228:229], v[88:91], off
	s_waitcnt vmcnt(11)
	v_pk_mul_f32 v[86:87], v[86:87], s[34:35] op_sel_hi:[1,0]
	v_pk_mul_f32 v[84:85], v[84:85], s[34:35] op_sel_hi:[1,0]
	v_pk_fma_f32 v[86:87], v[10:11], v[138:139], v[86:87]
	v_pk_fma_f32 v[84:85], v[8:9], v[136:137], v[84:85]
	global_store_dwordx4 v[228:229], v[84:87], off offset:64
	s_waitcnt vmcnt(11)
	v_pk_mul_f32 v[78:79], v[78:79], s[34:35] op_sel_hi:[1,0]
	v_pk_mul_f32 v[76:77], v[76:77], s[34:35] op_sel_hi:[1,0]
	v_pk_fma_f32 v[78:79], v[6:7], v[134:135], v[78:79]
	v_pk_fma_f32 v[76:77], v[4:5], v[132:133], v[76:77]
	global_store_dwordx4 v[228:229], v[76:79], off offset:512
	s_waitcnt vmcnt(11)
	v_pk_mul_f32 v[82:83], v[82:83], s[34:35] op_sel_hi:[1,0]
	v_pk_mul_f32 v[80:81], v[80:81], s[34:35] op_sel_hi:[1,0]
	v_pk_fma_f32 v[82:83], v[2:3], v[130:131], v[82:83]
	v_pk_fma_f32 v[80:81], v[0:1], v[128:129], v[80:81]
	global_store_dwordx4 v[228:229], v[80:83], off offset:576
	s_nop 1
	s_cbranch_vccnz .LBB0_702
	s_andn2_b64 vcc, exec, s[8:9]
	s_cbranch_vccnz .LBB0_701
	s_barrier
	s_branch .LBB0_701

;     f32x4 nv[8];
;     if (gw < nrows) { const float* s0_ = (gw < ML) ? srcL + (size_t)gw * D : srcC + (size_t)(gw - ML) * D;
; #pragma unroll
;         for (int j = 0; j < 8; ++j) nv[j] = *(const f32x4*)(s0_ + lane * 4 + 256 * j); }
;     for (int m = gw; m < nrows; m += NGW) {
;         float* dst; int mv;
;         if (m < ML) { dst = dstL + (size_t)m * D; mv = (m >= SEQ) ? 1 : 0; }
;         else { dst = dstC + (size_t)(m - ML) * D; mv = 2; }
;         f32x4 v[8];
; #pragma unroll
;         for (int j = 0; j < 8; ++j) v[j] = nv[j];
;         { const int mn = m + NGW;
;           if (mn < nrows) { const float* s1_ = (mn < ML) ? srcL + (size_t)mn * D : srcC + (size_t)(mn - ML) * D;
; #pragma unroll
;               for (int j = 0; j < 8; ++j) nv[j] = *(const f32x4*)(s1_ + lane * 4 + 256 * j); } }
.LBB0_791:
	s_cmp_lt_i32 s72, 8
	s_cselect_b64 s[0:1], -1, 0
	s_cmp_gt_i32 s73, 7
	s_cselect_b64 s[4:5], -1, 0
	s_and_b64 s[0:1], s[0:1], s[4:5]
	s_andn2_b64 vcc, exec, s[0:1]
	s_cbranch_vccnz .LBB0_858
	v_readfirstlane_b32 s0, v174
	v_readlane_b32 s1, v246, 0
	s_lshr_b32 s0, s0, 6
	s_lshl_b32 s1, s1, 3
	s_add_i32 s84, s0, s1
	s_cmpk_gt_i32 s84, 0x3fff
	s_cbranch_scc1 .LBB0_804
	v_readlane_b32 s52, v246, 31
	v_readlane_b32 s58, v246, 37
	v_readlane_b32 s54, v246, 33
	s_lshl_b32 s0, s58, 3
	v_readlane_b32 s55, v246, 34
	v_readlane_b32 s56, v246, 35
	v_readlane_b32 s57, v246, 36
	v_readlane_b32 s59, v246, 38
	s_add_u32 s3, s54, 0x6300000
	s_addc_u32 s35, s55, 0
	s_add_i32 s1, s84, 0xffffc000
	s_ashr_i32 s85, s84, 31
	v_readlane_b32 s56, v246, 15
	s_cmpk_lt_i32 s84, 0x4000
	v_readlane_b32 s60, v246, 19
	v_readlane_b32 s61, v246, 20
	v_readlane_b32 s53, v246, 32
	s_cselect_b32 s7, s85, 0
	s_cselect_b32 s6, s84, s1
	s_mov_b64 s[8:9], s[60:61]
	s_cselect_b32 s1, s53, s9
	s_cselect_b32 s2, s52, s8
	s_lshl_b64 s[6:7], s[6:7], 13
	v_lshlrev_b32_e32 v0, 2, v174
	s_add_u32 s6, s2, s6
	s_waitcnt vmcnt(4)
	v_and_b32_e32 v70, 0xfc, v0
	s_addc_u32 s7, s1, s7
	v_mov_b32_e32 v73, 0
	v_lshlrev_b32_e32 v72, 2, v70
	v_lshl_add_u64 v[0:1], s[6:7], 0, v[72:73]
	s_movk_i32 s76, 0x1000
	v_add_co_u32_e32 v0, vcc, s76, v0
	global_load_dwordx4 v[56:59], v72, s[6:7]
	global_load_dwordx4 v[60:63], v72, s[6:7] offset:1024
	global_load_dwordx4 v[32:35], v72, s[6:7] offset:2048
	global_load_dwordx4 v[36:39], v72, s[6:7] offset:3072
	v_addc_co_u32_e32 v1, vcc, 0, v1, vcc
	global_load_dwordx4 v[48:51], v[0:1], off
	global_load_dwordx4 v[44:47], v[0:1], off offset:1024
	global_load_dwordx4 v[40:43], v[0:1], off offset:2048
	global_load_dwordx4 v[52:55], v[0:1], off offset:3072
	v_lshl_add_u64 v[0:1], s[54:55], 0, v[72:73]
	s_mov_b64 s[6:7], 0x1b800000
	v_lshl_add_u64 v[74:75], v[0:1], 0, s[6:7]
	v_mbcnt_lo_u32_b32 v0, -1, 0
	v_mbcnt_hi_u32_b32 v0, -1, v0
	v_and_b32_e32 v1, 64, v0
	v_add_u32_e32 v1, 64, v1
	v_xor_b32_e32 v2, 1, v0
	v_cmp_lt_i32_e32 vcc, v2, v1
	v_readlane_b32 s8, v246, 39
	v_readlane_b32 s20, v246, 51
	v_cndmask_b32_e32 v2, v0, v2, vcc
	v_lshlrev_b32_e32 v71, 2, v2
	v_xor_b32_e32 v2, 2, v0
	v_cmp_lt_i32_e32 vcc, v2, v1
	v_readlane_b32 s21, v246, 52
	v_readlane_b32 s22, v246, 53
	v_cndmask_b32_e32 v2, v0, v2, vcc
	v_lshlrev_b32_e32 v105, 2, v2
	v_xor_b32_e32 v2, 4, v0
	v_cmp_lt_i32_e32 vcc, v2, v1
	v_readlane_b32 s23, v246, 54
	v_lshl_add_u64 v[76:77], s[20:21], 0, v[72:73]
	v_cndmask_b32_e32 v2, v0, v2, vcc
	v_lshlrev_b32_e32 v108, 2, v2
	v_xor_b32_e32 v2, 8, v0
	v_lshl_add_u64 v[78:79], s[22:23], 0, v[72:73]
	s_mov_b64 s[6:7], 0x1000
	v_cmp_lt_i32_e32 vcc, v2, v1
	v_lshl_add_u64 v[80:81], v[76:77], 0, s[6:7]
	v_lshl_add_u64 v[82:83], v[78:79], 0, s[6:7]
	s_mov_b64 s[6:7], 0x1400
	v_cndmask_b32_e32 v2, v0, v2, vcc
	v_lshl_add_u64 v[84:85], v[76:77], 0, s[6:7]
	v_lshl_add_u64 v[86:87], v[78:79], 0, s[6:7]
	s_mov_b64 s[6:7], 0x1800
	v_lshlrev_b32_e32 v109, 2, v2
	v_xor_b32_e32 v2, 16, v0
	v_lshl_add_u64 v[88:89], v[76:77], 0, s[6:7]
	v_lshl_add_u64 v[90:91], v[78:79], 0, s[6:7]
	s_mov_b64 s[6:7], 0x1c00
	v_cmp_lt_i32_e32 vcc, v2, v1
	v_lshl_add_u64 v[92:93], v[76:77], 0, s[6:7]
	v_lshl_add_u64 v[94:95], v[78:79], 0, s[6:7]
	v_cndmask_b32_e32 v2, v0, v2, vcc
	s_lshl_b64 s[6:7], s[84:85], 13
	v_readlane_b32 s9, v246, 40
	v_lshlrev_b32_e32 v110, 2, v2
	v_xor_b32_e32 v2, 32, v0
	s_add_u32 s8, s52, s6
	v_readlane_b32 s10, v246, 41
	v_readlane_b32 s11, v246, 42
	v_cmp_lt_i32_e32 vcc, v2, v1
	s_addc_u32 s9, s53, s7
	s_ashr_i32 s1, s0, 31
	v_cndmask_b32_e32 v0, v0, v2, vcc
	s_lshl_b64 s[10:11], s[0:1], 13
	s_lshl_b64 s[6:7], s[84:85], 12
	v_lshlrev_b32_e32 v111, 2, v0
	v_and_b32_e32 v0, 63, v174
	s_add_u32 s6, s54, s6
	v_lshlrev_b32_e32 v72, 3, v0
	s_addc_u32 s7, s55, s7
	v_lshl_add_u64 v[0:1], s[6:7], 0, v[72:73]
	s_mov_b64 s[6:7], 0x6700000
	s_add_i32 s77, s84, s0
	s_mov_b32 s5, 0
	v_lshl_add_u64 v[96:97], v[0:1], 0, s[6:7]
	s_lshl_b64 s[30:31], s[0:1], 12
	s_ashr_i32 s78, s77, 31
	s_mov_b32 s34, 0x3fb504f3
	s_mov_b32 s79, 0x800000
	s_mov_b32 s80, 0x1800000
	s_mov_b32 s81, 0x1801000
	s_mov_b32 s82, 0x1c00000
	s_mov_b32 s83, 0x1c01000
	v_mov_b32_e32 v112, 0x3727c5ac
	s_mov_b64 s[52:53], 0x8000
	s_mov_b64 s[54:55], 0x6000
	s_movk_i32 s85, 0x7fff
	s_mov_b32 s86, 0xffff0000
	s_mov_b32 s87, 0x9000
	s_movk_i32 s88, 0x7000
	v_readlane_b32 s57, v246, 16
	v_readlane_b32 s58, v246, 17
	v_readlane_b32 s59, v246, 18
	v_readlane_b32 s62, v246, 21
	v_readlane_b32 s63, v246, 22
	v_readlane_b32 s64, v246, 23
	v_readlane_b32 s65, v246, 24
	v_readlane_b32 s66, v246, 25
	v_readlane_b32 s67, v246, 26
	v_readlane_b32 s68, v246, 27
	v_readlane_b32 s69, v246, 28
	v_readlane_b32 s70, v246, 29
	v_readlane_b32 s71, v246, 30
	v_readlane_b32 s12, v246, 43
	v_readlane_b32 s13, v246, 44
	v_readlane_b32 s14, v246, 45
	v_readlane_b32 s15, v246, 46
	v_readlane_b32 s16, v246, 47
	v_readlane_b32 s17, v246, 48
	v_readlane_b32 s18, v246, 49
	v_readlane_b32 s19, v246, 50
	s_branch .LBB0_796

; __device__ __forceinline__ float wave_sum(float v) {
; #pragma unroll
;     for (int o = 1; o < 64; o <<= 1) v += __shfl_xor(v, o);
;     return v;
;     ...
;         if (do_ln) {
;             float s = 0.f;
; #pragma unroll
;             for (int j = 0; j < 8; ++j) s += (v[j].x + v[j].y) + (v[j].z + v[j].w);
;             const float mean = wave_sum(s) * (1.f / D); float s2 = 0.f;
; #pragma unroll
;             for (int j = 0; j < 8; ++j) { v[j] = v[j] - mean; s2 += (v[j].x * v[j].x + v[j].y * v[j].y) + (v[j].z * v[j].z + v[j].w * v[j].w); }
;             const float rstd = rsqrtf(wave_sum(s2) * (1.f / D) + LN_EPS);
; #pragma unroll
;             for (int j = 0; j < 8; ++j) { const f32x4 gg = *(const f32x4*)(lng + lane * 4 + 256 * j), bb = *(const f32x4*)(lnb + lane * 4 + 256 * j);
;                 v[j] = v[j] * rstd * gg + bb; *(f32x4*)(dst + lane * 4 + 256 * j) = v[j]; }
.LBB0_795:
	v_pk_add_f32 v[106:107], v[102:103], v[56:57]
	v_pk_add_f32 v[114:115], v[100:101], v[58:59]
	v_add_f32_e32 v49, v36, v37
	v_pk_add_f32 v[106:107], v[106:107], v[114:115]
	v_mov_b32_e32 v62, v52
	v_add_f32_e32 v35, 0, v107
	v_add_f32_e32 v99, v106, v35
	v_pk_add_f32 v[106:107], v[68:69], v[32:33]
	v_add_f32_e32 v35, v38, v39
	v_pk_add_f32 v[106:107], v[106:107], v[106:107] op_sel_hi:[0,1]
	v_mov_b32_e32 v51, v107
	v_pk_add_f32 v[114:115], v[48:49], v[34:35]
	v_pk_add_f32 v[106:107], v[50:51], v[98:99]
	v_mov_b32_e32 v66, v53
	v_pk_add_f32 v[106:107], v[114:115], v[106:107]
	v_pk_add_f32 v[114:115], v[64:65], v[44:45]
	v_pk_add_f32 v[106:107], v[106:107], v[106:107] op_sel_hi:[0,1]
	v_pk_add_f32 v[114:115], v[114:115], v[114:115] op_sel_hi:[0,1]
	v_mov_b32_e32 v46, v54
	v_mov_b32_e32 v60, v55
	v_add_f32_e32 v63, v40, v41
	v_add_f32_e32 v67, v42, v43
	v_mov_b32_e32 v47, v115
	v_mov_b32_e32 v61, v107
	v_pk_add_f32 v[62:63], v[62:63], v[66:67]
	v_pk_add_f32 v[46:47], v[46:47], v[60:61]
	v_readlane_b32 s64, v246, 31
	v_pk_add_f32 v[46:47], v[62:63], v[46:47]
	s_lshl_b32 s2, s60, 2
	v_add_f32_e32 v35, v46, v47
	ds_bpermute_b32 v46, v71, v35
	v_readlane_b32 s66, v246, 33
	v_readlane_b32 s67, v246, 34
	s_add_u32 s6, s66, s2
	s_addc_u32 s7, s67, 0
	s_waitcnt lgkmcnt(0)
	v_add_f32_e32 v35, v35, v46
	ds_bpermute_b32 v46, v105, v35
	s_add_u32 s8, s8, s10
	s_addc_u32 s9, s9, s11
	s_add_u32 s77, s77, s0
	s_addc_u32 s78, s78, s1
	s_waitcnt lgkmcnt(0)
	v_add_f32_e32 v35, v35, v46
	ds_bpermute_b32 v46, v108, v35
	s_mov_b32 s84, s61
	v_readlane_b32 s65, v246, 32
	v_readlane_b32 s68, v246, 35
	v_readlane_b32 s69, v246, 36
	s_waitcnt lgkmcnt(0)
	v_add_f32_e32 v35, v35, v46
	ds_bpermute_b32 v46, v109, v35
	v_readlane_b32 s70, v246, 37
	v_readlane_b32 s71, v246, 38
	s_waitcnt lgkmcnt(0)
	v_add_f32_e32 v35, v35, v46
	ds_bpermute_b32 v46, v110, v35
	s_waitcnt lgkmcnt(0)
	v_add_f32_e32 v35, v35, v46
	ds_bpermute_b32 v46, v111, v35
	s_waitcnt lgkmcnt(0)
	v_add_f32_e32 v35, v35, v46
	v_fmac_f32_e32 v57, 0xba000000, v35
	v_fmac_f32_e32 v56, 0xba000000, v35
	v_fmac_f32_e32 v103, 0xba000000, v35
	v_fmac_f32_e32 v102, 0xba000000, v35
	v_mov_b32_e32 v66, v57
	v_mov_b32_e32 v67, v56
	v_fmac_f32_e32 v59, 0xba000000, v35
	v_fmac_f32_e32 v101, 0xba000000, v35
	v_fmac_f32_e32 v58, 0xba000000, v35
	v_fmac_f32_e32 v100, 0xba000000, v35
	v_mov_b32_e32 v47, v56
	v_mov_b32_e32 v61, v57
	v_mov_b32_e32 v62, v103
	v_mov_b32_e32 v63, v102
	v_pk_mul_f32 v[56:57], v[66:67], v[66:67]
	v_mov_b32_e32 v46, v102
	v_mov_b32_e32 v60, v103
	v_pk_fma_f32 v[66:67], v[62:63], v[62:63], v[56:57]
	v_mov_b32_e32 v56, v100
	v_mov_b32_e32 v62, v101
	v_mov_b32_e32 v102, v101
	v_mov_b32_e32 v103, v100
	v_mov_b32_e32 v100, v59
	v_mov_b32_e32 v101, v58
	v_mov_b32_e32 v57, v58
	v_mov_b32_e32 v63, v59
	v_pk_mul_f32 v[58:59], v[100:101], v[100:101]
	v_fmac_f32_e32 v68, 0xba000000, v35
	v_pk_fma_f32 v[58:59], v[102:103], v[102:103], v[58:59]
	v_fmac_f32_e32 v33, 0xba000000, v35
	v_pk_add_f32 v[58:59], v[66:67], v[58:59]
	v_fmac_f32_e32 v69, 0xba000000, v35
	v_pk_add_f32 v[66:67], v[58:59], v[58:59] op_sel_hi:[0,1]
	v_fmac_f32_e32 v32, 0xba000000, v35
	v_mov_b32_e32 v58, v69
	v_mov_b32_e32 v59, v33
	v_mov_b32_e32 v33, v68
	v_fmac_f32_e32 v36, 0xba000000, v35
	v_pk_mul_f32 v[100:101], v[58:59], v[58:59]
	v_pk_mul_f32 v[68:69], v[32:33], v[32:33]
	v_fmac_f32_e32 v37, 0xba000000, v35
	v_fmac_f32_e32 v38, 0xba000000, v35
	v_mul_f32_e32 v66, v36, v36
	v_pk_mov_b32 v[102:103], v[68:69], v[100:101] op_sel:[1,0]
	v_mov_b32_e32 v69, v101
	v_fmac_f32_e32 v39, 0xba000000, v35
	v_pk_fma_f32 v[100:101], v[36:37], v[36:37], v[66:67] op_sel_hi:[1,1,0]
	v_mul_f32_e32 v66, v38, v38
	v_pk_add_f32 v[68:69], v[102:103], v[68:69]
	v_pk_fma_f32 v[102:103], v[38:39], v[38:39], v[66:67] op_sel_hi:[1,1,0]
	v_fmac_f32_e32 v34, 0xba000000, v35
	v_fmac_f32_e32 v48, 0xba000000, v35
	v_pk_add_f32 v[68:69], v[68:69], v[68:69] op_sel_hi:[0,1]
	v_fmac_f32_e32 v98, 0xba000000, v35
	v_fmac_f32_e32 v50, 0xba000000, v35
	v_mul_f32_e32 v100, v48, v48
	v_mul_f32_e32 v102, v34, v34
	v_fmac_f32_e32 v64, 0xba000000, v35
	v_fmac_f32_e32 v45, 0xba000000, v35
	v_fmac_f32_e32 v65, 0xba000000, v35
	v_mul_f32_e32 v68, v50, v50
	v_mul_f32_e32 v66, v98, v98
	v_pk_add_f32 v[100:101], v[100:101], v[102:103]
	v_fmac_f32_e32 v44, 0xba000000, v35
	v_mov_b32_e32 v102, v65
	v_mov_b32_e32 v103, v45
	v_mov_b32_e32 v45, v64
	v_pk_add_f32 v[66:67], v[68:69], v[66:67]
	v_pk_mul_f32 v[68:69], v[102:103], v[102:103]
	v_pk_mul_f32 v[64:65], v[44:45], v[44:45]
	v_pk_add_f32 v[66:67], v[100:101], v[66:67]
	v_pk_mov_b32 v[100:101], v[64:65], v[68:69] op_sel:[1,0]
	v_mov_b32_e32 v65, v69
	v_pk_add_f32 v[64:65], v[100:101], v[64:65]
	v_fmac_f32_e32 v40, 0xba000000, v35
	v_pk_add_f32 v[64:65], v[64:65], v[64:65] op_sel_hi:[0,1]
	v_fmac_f32_e32 v41, 0xba000000, v35
	v_fmac_f32_e32 v42, 0xba000000, v35
	v_mul_f32_e32 v64, v40, v40
	v_fmac_f32_e32 v43, 0xba000000, v35
	v_pk_fma_f32 v[68:69], v[40:41], v[40:41], v[64:65] op_sel_hi:[1,1,0]
	v_mul_f32_e32 v64, v42, v42
	v_pk_add_f32 v[66:67], v[66:67], v[66:67] op_sel_hi:[0,1]
	v_pk_fma_f32 v[106:107], v[42:43], v[42:43], v[64:65] op_sel_hi:[1,1,0]
	v_fmamk_f32 v101, v35, 0xba000000, v55
	v_fmamk_f32 v100, v35, 0xba000000, v54
	v_fmamk_f32 v53, v35, 0xba000000, v53
	v_fmac_f32_e32 v52, 0xba000000, v35
	v_mul_f32_e32 v68, v52, v52
	v_mul_f32_e32 v106, v53, v53
	v_mul_f32_e32 v64, v100, v100
	v_mul_f32_e32 v66, v101, v101
	v_pk_add_f32 v[54:55], v[68:69], v[106:107]
	v_pk_add_f32 v[64:65], v[64:65], v[66:67]
	v_lshl_add_u64 v[106:107], s[62:63], 0, v[72:73]
	v_pk_add_f32 v[54:55], v[54:55], v[64:65]
	global_load_dwordx4 v[64:67], v[76:77], off
	global_load_dwordx4 v[114:117], v[78:79], off
	v_add_f32_e32 v35, v54, v55
	ds_bpermute_b32 v49, v71, v35
	v_mov_b32_e32 v51, v98
	s_waitcnt lgkmcnt(0)
; __device__ __forceinline__ unsigned pk2(float lo, float hi) { return f2bf(lo) | (f2bf(hi) << 16); }
;     ...
;             const float rstd = rsqrtf(wave_sum(s2) * (1.f / D) + LN_EPS);
; #pragma unroll
;             for (int j = 0; j < 8; ++j) { const f32x4 gg = *(const f32x4*)(lng + lane * 4 + 256 * j), bb = *(const f32x4*)(lnb + lane * 4 + 256 * j);
;                 v[j] = v[j] * rstd * gg + bb; *(f32x4*)(dst + lane * 4 + 256 * j) = v[j]; }
;         }
;         if (do_mod) {
;             const float* sh = modl + mv * NMOD + shc * D; const float* sc = modl + mv * NMOD + scc * D;
; #pragma unroll
;             for (int j = 0; j < 8; ++j) { const f32x4 s1 = *(const f32x4*)(sc + lane * 4 + 256 * j), h1 = *(const f32x4*)(sh + lane * 4 + 256 * j);
;                 const f32x4 a = v[j] * (s1 + 1.f) + h1; u32x2 o; o.x = pk2(a.x, a.y); o.y = pk2(a.z, a.w);
;                 *(u32x2*)(aout + (size_t)m * D + lane * 4 + 256 * j) = o; }
	v_add_f32_e32 v35, v35, v49
	ds_bpermute_b32 v49, v105, v35
	s_waitcnt lgkmcnt(0)
	v_add_f32_e32 v35, v35, v49
	ds_bpermute_b32 v49, v108, v35
	s_waitcnt lgkmcnt(0)
	v_add_f32_e32 v35, v35, v49
	ds_bpermute_b32 v49, v109, v35
	s_waitcnt lgkmcnt(0)
	v_add_f32_e32 v35, v35, v49
	ds_bpermute_b32 v49, v110, v35
	s_waitcnt lgkmcnt(0)
	v_add_f32_e32 v35, v35, v49
	ds_bpermute_b32 v49, v111, v35
	s_waitcnt lgkmcnt(0)
	v_add_f32_e32 v35, v35, v49
	v_fmamk_f32 v35, v35, 0x3a000000, v112
	v_cmp_gt_f32_e32 vcc, s79, v35
	v_mul_f32_e32 v49, 0x4b800000, v35
	s_nop 0
	v_cndmask_b32_e32 v35, v35, v49, vcc
	v_rsq_f32_e32 v35, v35
	s_nop 0
	v_mul_f32_e32 v49, 0x45800000, v35
	v_cndmask_b32_e32 v104, v35, v49, vcc
	v_pk_mul_f32 v[54:55], v[60:61], v[104:105] op_sel_hi:[1,0]
	v_pk_mul_f32 v[60:61], v[62:63], v[104:105] op_sel_hi:[1,0]
	v_pk_mul_f32 v[46:47], v[46:47], v[104:105] op_sel_hi:[1,0]
	v_pk_mul_f32 v[32:33], v[32:33], v[104:105] op_sel_hi:[1,0]
	v_pk_mul_f32 v[36:37], v[36:37], v[104:105] op_sel_hi:[1,0]
	v_mov_b32_e32 v49, v34
	v_pk_mul_f32 v[34:35], v[48:49], v[104:105] op_sel_hi:[1,0]
	v_add_co_u32_e32 v98, vcc, s76, v106
	v_pk_mul_f32 v[44:45], v[44:45], v[104:105] op_sel_hi:[1,0]
	s_nop 0
	v_addc_co_u32_e32 v99, vcc, 0, v107, vcc
	v_pk_mul_f32 v[42:43], v[42:43], v[104:105] op_sel_hi:[1,0]
	v_pk_mul_f32 v[40:41], v[40:41], v[104:105] op_sel_hi:[1,0]
	v_pk_mul_f32 v[100:101], v[100:101], v[104:105] op_sel_hi:[1,0]
	v_pk_mul_f32 v[52:53], v[52:53], v[104:105] op_sel_hi:[1,0]
	s_waitcnt vmcnt(0)
	v_pk_fma_f32 v[68:69], v[66:67], v[60:61], v[116:117]
	v_pk_fma_f32 v[66:67], v[64:65], v[54:55], v[114:115]
	global_store_dwordx4 v72, v[66:69], s[62:63]
	global_load_dwordx4 v[62:65], v[76:77], off offset:1024
	global_load_dwordx4 v[114:117], v[78:79], off offset:1024
	v_pk_mul_f32 v[54:55], v[56:57], v[104:105] op_sel_hi:[1,0]
	s_waitcnt vmcnt(0)
	v_pk_fma_f32 v[62:63], v[62:63], v[46:47], v[114:115]
	v_pk_fma_f32 v[64:65], v[64:65], v[54:55], v[116:117]
	global_store_dwordx4 v72, v[62:65], s[62:63] offset:1024
	global_load_dwordx4 v[54:57], v[76:77], off offset:2048
	global_load_dwordx4 v[114:117], v[78:79], off offset:2048
	v_pk_mul_f32 v[46:47], v[58:59], v[104:105] op_sel_hi:[1,0]
	s_waitcnt vmcnt(0)
	v_pk_fma_f32 v[58:59], v[54:55], v[32:33], v[114:115]
	v_pk_fma_f32 v[60:61], v[56:57], v[46:47], v[116:117]
	global_store_dwordx4 v72, v[58:61], s[62:63] offset:2048
	global_load_dwordx4 v[54:57], v[76:77], off offset:3072
	global_load_dwordx4 v[114:117], v[78:79], off offset:3072
	v_pk_mul_f32 v[32:33], v[38:39], v[104:105] op_sel_hi:[1,0]
	v_pk_mul_f32 v[46:47], v[102:103], v[104:105] op_sel_hi:[1,0]
	s_waitcnt vmcnt(0)
	v_pk_fma_f32 v[54:55], v[54:55], v[36:37], v[114:115]
	v_pk_fma_f32 v[56:57], v[56:57], v[32:33], v[116:117]
	global_store_dwordx4 v72, v[54:57], s[62:63] offset:3072
	global_load_dwordx4 v[36:39], v[80:81], off
	global_load_dwordx4 v[114:117], v[82:83], off
	v_pk_mul_f32 v[32:33], v[50:51], v[104:105] op_sel_hi:[1,0]
	s_waitcnt vmcnt(0)
	v_pk_fma_f32 v[48:49], v[36:37], v[34:35], v[114:115]
	v_pk_fma_f32 v[50:51], v[38:39], v[32:33], v[116:117]
	global_store_dwordx4 v[98:99], v[48:51], off
	global_load_dwordx4 v[32:35], v[84:85], off
	global_load_dwordx4 v[36:39], v[86:87], off
	s_waitcnt vmcnt(0)
	v_pk_fma_f32 v[44:45], v[32:33], v[44:45], v[36:37]
	v_pk_fma_f32 v[46:47], v[34:35], v[46:47], v[38:39]
	global_store_dwordx4 v[98:99], v[44:47], off offset:1024
	global_load_dwordx4 v[32:35], v[88:89], off
	global_load_dwordx4 v[36:39], v[90:91], off
	s_waitcnt vmcnt(0)
	v_pk_fma_f32 v[36:37], v[32:33], v[40:41], v[36:37]
	v_pk_fma_f32 v[38:39], v[34:35], v[42:43], v[38:39]
	global_store_dwordx4 v[98:99], v[36:39], off offset:2048
	global_load_dwordx4 v[32:35], v[92:93], off
	global_load_dwordx4 v[40:43], v[94:95], off
	s_waitcnt vmcnt(0)
	v_pk_fma_f32 v[34:35], v[34:35], v[100:101], v[42:43]
	v_lshl_add_u64 v[42:43], s[6:7], 0, v[72:73]
	v_pk_fma_f32 v[32:33], v[32:33], v[52:53], v[40:41]
	v_add_co_u32_e32 v40, vcc, s87, v42
	global_store_dwordx4 v[98:99], v[32:35], off offset:3072
	s_nop 0
	v_addc_co_u32_e32 v41, vcc, 0, v43, vcc
	v_lshl_add_u64 v[52:53], v[42:43], 0, s[52:53]
	v_lshl_add_u64 v[98:99], v[42:43], 0, s[54:55]
	v_add_co_u32_e32 v42, vcc, s88, v42
	global_load_dwordx4 v[100:103], v[40:41], off offset:-4096
	s_nop 0
	v_addc_co_u32_e32 v43, vcc, 0, v43, vcc
	global_load_dwordx4 v[114:117], v[42:43], off offset:-4096
	s_andn2_b64 vcc, exec, s[58:59]
	s_waitcnt vmcnt(1)
	v_pk_add_f32 v[100:101], v[100:101], 1.0 op_sel_hi:[1,0]
	v_pk_add_f32 v[102:103], v[102:103], 1.0 op_sel_hi:[1,0]
	s_waitcnt vmcnt(0)
; __device__ __forceinline__ unsigned pk2(float lo, float hi) { return f2bf(lo) | (f2bf(hi) << 16); }
;     ...
;         if (do_mod) {
;             const float* sh = modl + mv * NMOD + shc * D; const float* sc = modl + mv * NMOD + scc * D;
; #pragma unroll
;             for (int j = 0; j < 8; ++j) { const f32x4 s1 = *(const f32x4*)(sc + lane * 4 + 256 * j), h1 = *(const f32x4*)(sh + lane * 4 + 256 * j);
;                 const f32x4 a = v[j] * (s1 + 1.f) + h1; u32x2 o; o.x = pk2(a.x, a.y); o.y = pk2(a.z, a.w);
;                 *(u32x2*)(aout + (size_t)m * D + lane * 4 + 256 * j) = o; }
;         }
	v_pk_fma_f32 v[66:67], v[100:101], v[66:67], v[114:115]
	s_nop 0
	v_bfe_u32 v72, v66, 16, 1
	v_add3_u32 v66, v66, v72, s85
	v_bfe_u32 v72, v67, 16, 1
	v_pk_fma_f32 v[68:69], v[102:103], v[68:69], v[116:117]
	v_lshrrev_b32_e32 v66, 16, v66
	v_add3_u32 v67, v67, v72, s85
	v_and_or_b32 v66, v67, s86, v66
	s_nop 0
	s_nop 0
	s_nop 0
	v_cvt_pk_bf16_f32 v67, v68, v69
	global_store_dwordx2 v[96:97], v[66:67], off
	global_load_dwordx4 v[66:69], v[52:53], off offset:1024
	s_nop 0
	global_load_dwordx4 v[100:103], v[98:99], off offset:1024
	s_waitcnt vmcnt(1)
	v_pk_add_f32 v[66:67], v[66:67], 1.0 op_sel_hi:[1,0]
	s_waitcnt vmcnt(0)
	v_pk_fma_f32 v[62:63], v[66:67], v[62:63], v[100:101]
	v_pk_add_f32 v[68:69], v[68:69], 1.0 op_sel_hi:[1,0]
	v_pk_fma_f32 v[64:65], v[68:69], v[64:65], v[102:103]
	v_cvt_pk_bf16_f32 v62, v62, v63
	s_nop 0
	s_nop 0
	s_nop 0
	v_cvt_pk_bf16_f32 v63, v64, v65
	global_store_dwordx2 v[96:97], v[62:63], off offset:512
	global_load_dwordx4 v[62:65], v[52:53], off offset:2048
	s_nop 0
	global_load_dwordx4 v[66:69], v[98:99], off offset:2048
	s_waitcnt vmcnt(1)
	v_pk_add_f32 v[62:63], v[62:63], 1.0 op_sel_hi:[1,0]
	s_waitcnt vmcnt(0)
	v_pk_fma_f32 v[58:59], v[62:63], v[58:59], v[66:67]
	v_pk_add_f32 v[64:65], v[64:65], 1.0 op_sel_hi:[1,0]
	v_pk_fma_f32 v[60:61], v[64:65], v[60:61], v[68:69]
	v_cvt_pk_bf16_f32 v58, v58, v59
	s_nop 0
	s_nop 0
	s_nop 0
	v_cvt_pk_bf16_f32 v59, v60, v61
	global_store_dwordx2 v[96:97], v[58:59], off offset:1024
	global_load_dwordx4 v[58:61], v[52:53], off offset:3072
	s_nop 0
	global_load_dwordx4 v[62:65], v[98:99], off offset:3072
	s_waitcnt vmcnt(1)
	v_pk_add_f32 v[58:59], v[58:59], 1.0 op_sel_hi:[1,0]
	v_pk_add_f32 v[52:53], v[60:61], 1.0 op_sel_hi:[1,0]
	s_waitcnt vmcnt(0)
	v_pk_fma_f32 v[54:55], v[58:59], v[54:55], v[62:63]
	v_pk_fma_f32 v[52:53], v[52:53], v[56:57], v[64:65]
	v_cvt_pk_bf16_f32 v54, v54, v55
	s_nop 0
	s_nop 0
	s_nop 0
	v_cvt_pk_bf16_f32 v55, v52, v53
	global_store_dwordx2 v[96:97], v[54:55], off offset:1536
	global_load_dwordx4 v[52:55], v[40:41], off
	s_nop 0
	global_load_dwordx4 v[56:59], v[42:43], off
	v_mov_b64_e32 v[62:63], v[6:7]
	v_mov_b64_e32 v[60:61], v[4:5]
	s_waitcnt vmcnt(1)
	v_pk_add_f32 v[52:53], v[52:53], 1.0 op_sel_hi:[1,0]
	s_waitcnt vmcnt(0)
	v_pk_fma_f32 v[48:49], v[48:49], v[52:53], v[56:57]
	v_pk_add_f32 v[54:55], v[54:55], 1.0 op_sel_hi:[1,0]
	v_pk_fma_f32 v[50:51], v[50:51], v[54:55], v[58:59]
	v_cvt_pk_bf16_f32 v48, v48, v49
	s_nop 0
	s_nop 0
	s_nop 0
	v_cvt_pk_bf16_f32 v49, v50, v51
	global_store_dwordx2 v[96:97], v[48:49], off offset:2048
	global_load_dwordx4 v[48:51], v[40:41], off offset:1024
	s_nop 0
	global_load_dwordx4 v[52:55], v[42:43], off offset:1024
	v_mov_b64_e32 v[58:59], v[2:3]
	v_mov_b64_e32 v[56:57], v[0:1]
	s_waitcnt vmcnt(1)
	v_pk_add_f32 v[48:49], v[48:49], 1.0 op_sel_hi:[1,0]
	s_waitcnt vmcnt(0)
	v_pk_fma_f32 v[44:45], v[44:45], v[48:49], v[52:53]
	v_pk_add_f32 v[50:51], v[50:51], 1.0 op_sel_hi:[1,0]
	v_pk_fma_f32 v[46:47], v[46:47], v[50:51], v[54:55]
	v_cvt_pk_bf16_f32 v44, v44, v45
	s_nop 0
	s_nop 0
	s_nop 0
	v_cvt_pk_bf16_f32 v45, v46, v47
	global_store_dwordx2 v[96:97], v[44:45], off offset:2560
	global_load_dwordx4 v[44:47], v[40:41], off offset:2048
	s_nop 0
	global_load_dwordx4 v[48:51], v[42:43], off offset:2048
	v_mov_b64_e32 v[54:55], v[30:31]
	v_mov_b64_e32 v[52:53], v[28:29]
	s_waitcnt vmcnt(1)
	v_pk_add_f32 v[44:45], v[44:45], 1.0 op_sel_hi:[1,0]
	s_waitcnt vmcnt(0)
	v_pk_fma_f32 v[36:37], v[36:37], v[44:45], v[48:49]
	v_pk_add_f32 v[46:47], v[46:47], 1.0 op_sel_hi:[1,0]
	v_pk_fma_f32 v[38:39], v[38:39], v[46:47], v[50:51]
	v_cvt_pk_bf16_f32 v36, v36, v37
	s_nop 0
	s_nop 0
	s_nop 0
	v_cvt_pk_bf16_f32 v37, v38, v39
	global_store_dwordx2 v[96:97], v[36:37], off offset:3072
	global_load_dwordx4 v[36:39], v[40:41], off offset:3072
	s_nop 0
	global_load_dwordx4 v[40:43], v[42:43], off offset:3072
	v_mov_b64_e32 v[46:47], v[22:23]
	v_mov_b64_e32 v[50:51], v[18:19]
	v_mov_b64_e32 v[44:45], v[20:21]
	v_mov_b64_e32 v[48:49], v[16:17]
	s_waitcnt vmcnt(1)
	v_pk_add_f32 v[36:37], v[36:37], 1.0 op_sel_hi:[1,0]
	s_waitcnt vmcnt(0)
	v_pk_fma_f32 v[32:33], v[32:33], v[36:37], v[40:41]
	v_pk_add_f32 v[38:39], v[38:39], 1.0 op_sel_hi:[1,0]
	v_pk_fma_f32 v[34:35], v[34:35], v[38:39], v[42:43]
	v_cvt_pk_bf16_f32 v32, v32, v33
	s_nop 0
	v_cvt_pk_bf16_f32 v33, v34, v35
	global_store_dwordx2 v[96:97], v[32:33], off offset:3584
	v_mov_b64_e32 v[42:43], v[26:27]
	v_mov_b64_e32 v[38:39], v[14:15]
	v_mov_b64_e32 v[34:35], v[10:11]
	v_lshl_add_u64 v[96:97], v[96:97], 0, s[30:31]
	v_mov_b64_e32 v[40:41], v[24:25]
	v_mov_b64_e32 v[36:37], v[12:13]
	v_mov_b64_e32 v[32:33], v[8:9]
	s_cbranch_vccz .LBB0_804

;     ...
;     for (int m = gw; m < nrows; m += NGW) {
;         float* dst; int mv;
;         if (m < ML) { dst = dstL + (size_t)m * D; mv = (m >= SEQ) ? 1 : 0; }
;         else { dst = dstC + (size_t)(m - ML) * D; mv = 2; }
;         f32x4 v[8];
; #pragma unroll
;         for (int j = 0; j < 8; ++j) v[j] = nv[j];
;         { const int mn = m + NGW;
;           if (mn < nrows) { const float* s1_ = (mn < ML) ? srcL + (size_t)mn * D : srcC + (size_t)(mn - ML) * D;
; #pragma unroll
;               for (int j = 0; j < 8; ++j) nv[j] = *(const f32x4*)(s1_ + lane * 4 + 256 * j); } }
.LBB0_800:
	s_add_i32 s61, s84, s0
	s_cmpk_gt_i32 s61, 0x3fff
	s_cselect_b64 s[58:59], -1, 0
	s_waitcnt vmcnt(0)
	v_mov_b64_e32 v[28:29], v[52:53]
	v_mov_b64_e32 v[24:25], v[40:41]
	v_mov_b64_e32 v[20:21], v[44:45]
	v_mov_b64_e32 v[16:17], v[48:49]
	v_mov_b64_e32 v[12:13], v[36:37]
	v_mov_b64_e32 v[8:9], v[32:33]
	v_mov_b64_e32 v[4:5], v[60:61]
	v_mov_b64_e32 v[0:1], v[56:57]
	s_and_b64 vcc, exec, s[58:59]
	v_lshlrev_b32_e32 v72, 2, v70
	v_mov_b64_e32 v[30:31], v[54:55]
	v_mov_b64_e32 v[26:27], v[42:43]
	v_mov_b64_e32 v[22:23], v[46:47]
	v_mov_b64_e32 v[18:19], v[50:51]
	v_mov_b64_e32 v[14:15], v[38:39]
	v_mov_b64_e32 v[10:11], v[34:35]
	v_mov_b64_e32 v[6:7], v[62:63]
	v_mov_b64_e32 v[2:3], v[58:59]
	s_cbranch_vccnz .LBB0_802
	s_add_i32 s2, s61, 0xffffc000
	v_readlane_b32 s12, v246, 15
	s_cmpk_lt_i32 s61, 0x4000
	v_readlane_b32 s64, v246, 31
	v_readlane_b32 s13, v246, 16
	v_readlane_b32 s16, v246, 19
	v_readlane_b32 s17, v246, 20
	s_cselect_b32 s7, s78, 0
	s_cselect_b32 s6, s77, s2
	v_readlane_b32 s65, v246, 32
	s_mov_b64 s[12:13], s[16:17]
	s_cselect_b32 s2, s65, s13
	s_cselect_b32 s4, s64, s12
	s_lshl_b64 s[6:7], s[6:7], 13
	s_add_u32 s6, s4, s6
	s_addc_u32 s7, s2, s7
	v_lshl_add_u64 v[16:17], s[6:7], 0, v[72:73]
	v_add_co_u32_e32 v28, vcc, 0x1000, v16
	global_load_dwordx4 v[0:3], v72, s[6:7]
	global_load_dwordx4 v[4:7], v72, s[6:7] offset:1024
	global_load_dwordx4 v[8:11], v72, s[6:7] offset:2048
	global_load_dwordx4 v[12:15], v72, s[6:7] offset:3072
	v_addc_co_u32_e32 v29, vcc, 0, v17, vcc
	global_load_dwordx4 v[16:19], v[28:29], off
	global_load_dwordx4 v[20:23], v[28:29], off offset:1024
	global_load_dwordx4 v[24:27], v[28:29], off offset:2048
	s_nop 0
	global_load_dwordx4 v[28:31], v[28:29], off offset:3072
	v_readlane_b32 s66, v246, 33
	v_readlane_b32 s67, v246, 34
	v_readlane_b32 s68, v246, 35
	v_readlane_b32 s69, v246, 36
	v_readlane_b32 s70, v246, 37
	v_readlane_b32 s71, v246, 38
	v_readlane_b32 s14, v246, 17
	v_readlane_b32 s15, v246, 18
	v_readlane_b32 s18, v246, 21
	v_readlane_b32 s19, v246, 22
	v_readlane_b32 s20, v246, 23
	v_readlane_b32 s21, v246, 24
	v_readlane_b32 s22, v246, 25
	v_readlane_b32 s23, v246, 26
	v_readlane_b32 s24, v246, 27
	v_readlane_b32 s25, v246, 28
	v_readlane_b32 s26, v246, 29
	v_readlane_b32 s27, v246, 30

;     f32x4 nv[8];
;     if (gw < nrows) { const float* s0_ = (gw < ML) ? srcL + (size_t)gw * D : srcC + (size_t)(gw - ML) * D;
; #pragma unroll
;         for (int j = 0; j < 8; ++j) nv[j] = *(const f32x4*)(s0_ + lane * 4 + 256 * j); }
;     for (int m = gw; m < nrows; m += NGW) {
;         float* dst; int mv;
;         if (m < ML) { dst = dstL + (size_t)m * D; mv = (m >= SEQ) ? 1 : 0; }
;         else { dst = dstC + (size_t)(m - ML) * D; mv = 2; }
;         f32x4 v[8];
; #pragma unroll
;         for (int j = 0; j < 8; ++j) v[j] = nv[j];
;         { const int mn = m + NGW;
;           if (mn < nrows) { const float* s1_ = (mn < ML) ? srcL + (size_t)mn * D : srcC + (size_t)(mn - ML) * D;
; #pragma unroll
;               for (int j = 0; j < 8; ++j) nv[j] = *(const f32x4*)(s1_ + lane * 4 + 256 * j); } }
;         if (nslab > 0 && m >= ML) {
; #pragma unroll
;             for (int j = 0; j < 8; ++j) v[j] = v[j] * ALPHA;
;             for (int sidx = 0; sidx < nslab; ++sidx) { const float* sp = slab + ((size_t)sidx * (2 * CTXL) + (m - ML)) * D + lane * 4;
; #pragma unroll
;                 for (int j = 0; j < 8; ++j) v[j] += *(const f32x4*)(sp + 256 * j); }
;         }
.LBB0_804:
	v_readfirstlane_b32 s60, v174
	v_readlane_b32 s61, v246, 0
	s_nop 3
	s_lshr_b32 s60, s60, 6
	s_lshl_b32 s61, s61, 3
	s_add_i32 s60, s60, s61
	s_cmpk_lt_i32 s60, 0x200
	s_cbranch_scc0 .Lcx7_done
	v_readlane_b32 s64, v246, 33
	v_readlane_b32 s65, v246, 34
	v_readlane_b32 s66, v246, 51
	v_readlane_b32 s67, v246, 52
	v_readlane_b32 s78, v246, 53
	v_readlane_b32 s79, v246, 54
	v_readlane_b32 s62, v246, 19
	v_readlane_b32 s63, v246, 20
	v_and_b32_e32 v240, 63, v174
	v_lshlrev_b32_e32 v241, 3, v240
	v_lshlrev_b32_e32 v240, 4, v240
	v_mov_b32_e32 v64, 0x3fb504f3
	s_nop 4
	s_lshl_b32 s58, s60, 13
	s_add_u32 s18, s62, s58
	s_addc_u32 s19, s63, 0
	s_add_u32 s20, s18, 0x1000
	s_addc_u32 s21, s19, 0
	global_load_dwordx4 v[0:3], v240, s[18:19]
	global_load_dwordx4 v[4:7], v240, s[18:19] offset:1024
	global_load_dwordx4 v[8:11], v240, s[18:19] offset:2048
	global_load_dwordx4 v[12:15], v240, s[18:19] offset:3072
	global_load_dwordx4 v[16:19], v240, s[20:21]
	global_load_dwordx4 v[20:23], v240, s[20:21] offset:1024
	global_load_dwordx4 v[24:27], v240, s[20:21] offset:2048
	global_load_dwordx4 v[28:31], v240, s[20:21] offset:3072
	s_add_u32 s80, s66, 0x1000
	s_addc_u32 s81, s67, 0
	s_add_u32 s82, s78, 0x1000
	s_addc_u32 s83, s79, 0
	global_load_dwordx4 v[96:99], v240, s[66:67]
	global_load_dwordx4 v[100:103], v240, s[66:67] offset:1024
	global_load_dwordx4 v[104:107], v240, s[66:67] offset:2048
	global_load_dwordx4 v[108:111], v240, s[66:67] offset:3072
	global_load_dwordx4 v[112:115], v240, s[80:81]
	global_load_dwordx4 v[116:119], v240, s[80:81] offset:1024
	global_load_dwordx4 v[120:123], v240, s[80:81] offset:2048
	global_load_dwordx4 v[124:127], v240, s[80:81] offset:3072
	global_load_dwordx4 v[128:131], v240, s[78:79]
	global_load_dwordx4 v[132:135], v240, s[78:79] offset:1024
	global_load_dwordx4 v[136:139], v240, s[78:79] offset:2048
	global_load_dwordx4 v[140:143], v240, s[78:79] offset:3072
	global_load_dwordx4 v[144:147], v240, s[82:83]
	global_load_dwordx4 v[148:151], v240, s[82:83] offset:1024
	global_load_dwordx4 v[152:155], v240, s[82:83] offset:2048
	global_load_dwordx4 v[156:159], v240, s[82:83] offset:3072
	s_add_u32 s22, s64, 0x1b800000
	s_addc_u32 s23, s65, 0
	s_add_u32 s22, s22, s58
	s_addc_u32 s23, s23, 0
	s_add_u32 s24, s22, 0x0
	s_addc_u32 s25, s23, 0
	s_add_u32 s26, s24, 0x1000
	s_addc_u32 s27, s25, 0
	global_load_dwordx4 v[176:179], v240, s[24:25]
	global_load_dwordx4 v[180:183], v240, s[24:25] offset:1024
	global_load_dwordx4 v[184:187], v240, s[24:25] offset:2048
	global_load_dwordx4 v[188:191], v240, s[24:25] offset:3072
	global_load_dwordx4 v[192:195], v240, s[26:27]
	global_load_dwordx4 v[196:199], v240, s[26:27] offset:1024
	global_load_dwordx4 v[200:203], v240, s[26:27] offset:2048
	global_load_dwordx4 v[204:207], v240, s[26:27] offset:3072
	s_add_u32 s28, s22, 0x400000
	s_addc_u32 s29, s23, 0
	s_add_u32 s30, s28, 0x1000
	s_addc_u32 s31, s29, 0
	global_load_dwordx4 v[208:211], v240, s[28:29]
	global_load_dwordx4 v[212:215], v240, s[28:29] offset:1024
	global_load_dwordx4 v[216:219], v240, s[28:29] offset:2048
	global_load_dwordx4 v[220:223], v240, s[28:29] offset:3072
	global_load_dwordx4 v[224:227], v240, s[30:31]
	global_load_dwordx4 v[228:231], v240, s[30:31] offset:1024
	global_load_dwordx4 v[232:235], v240, s[30:31] offset:2048
	global_load_dwordx4 v[236:239], v240, s[30:31] offset:3072
	s_waitcnt vmcnt(15)
	v_pk_fma_f32 v[0:1], v[0:1], v[64:65], v[176:177] op_sel_hi:[1,0,1]
	v_pk_fma_f32 v[2:3], v[2:3], v[64:65], v[178:179] op_sel_hi:[1,0,1]
	s_waitcnt vmcnt(14)
	v_pk_fma_f32 v[4:5], v[4:5], v[64:65], v[180:181] op_sel_hi:[1,0,1]
	v_pk_fma_f32 v[6:7], v[6:7], v[64:65], v[182:183] op_sel_hi:[1,0,1]
	s_waitcnt vmcnt(13)
	v_pk_fma_f32 v[8:9], v[8:9], v[64:65], v[184:185] op_sel_hi:[1,0,1]
	v_pk_fma_f32 v[10:11], v[10:11], v[64:65], v[186:187] op_sel_hi:[1,0,1]
	s_waitcnt vmcnt(12)
	v_pk_fma_f32 v[12:13], v[12:13], v[64:65], v[188:189] op_sel_hi:[1,0,1]
	v_pk_fma_f32 v[14:15], v[14:15], v[64:65], v[190:191] op_sel_hi:[1,0,1]
	s_waitcnt vmcnt(11)
	v_pk_fma_f32 v[16:17], v[16:17], v[64:65], v[192:193] op_sel_hi:[1,0,1]
	v_pk_fma_f32 v[18:19], v[18:19], v[64:65], v[194:195] op_sel_hi:[1,0,1]
	s_waitcnt vmcnt(10)
	v_pk_fma_f32 v[20:21], v[20:21], v[64:65], v[196:197] op_sel_hi:[1,0,1]
	v_pk_fma_f32 v[22:23], v[22:23], v[64:65], v[198:199] op_sel_hi:[1,0,1]
	s_waitcnt vmcnt(9)
	v_pk_fma_f32 v[24:25], v[24:25], v[64:65], v[200:201] op_sel_hi:[1,0,1]
	v_pk_fma_f32 v[26:27], v[26:27], v[64:65], v[202:203] op_sel_hi:[1,0,1]
	s_waitcnt vmcnt(8)
	v_pk_fma_f32 v[28:29], v[28:29], v[64:65], v[204:205] op_sel_hi:[1,0,1]
	v_pk_fma_f32 v[30:31], v[30:31], v[64:65], v[206:207] op_sel_hi:[1,0,1]
	s_waitcnt vmcnt(7)
	v_pk_add_f32 v[0:1], v[0:1], v[208:209]
	v_pk_add_f32 v[2:3], v[2:3], v[210:211]
	s_waitcnt vmcnt(6)
	v_pk_add_f32 v[4:5], v[4:5], v[212:213]
	v_pk_add_f32 v[6:7], v[6:7], v[214:215]
	s_waitcnt vmcnt(5)
	v_pk_add_f32 v[8:9], v[8:9], v[216:217]
	v_pk_add_f32 v[10:11], v[10:11], v[218:219]
	s_waitcnt vmcnt(4)
	v_pk_add_f32 v[12:13], v[12:13], v[220:221]
	v_pk_add_f32 v[14:15], v[14:15], v[222:223]
	s_waitcnt vmcnt(3)
	v_pk_add_f32 v[16:17], v[16:17], v[224:225]
	v_pk_add_f32 v[18:19], v[18:19], v[226:227]
	s_waitcnt vmcnt(2)
	v_pk_add_f32 v[20:21], v[20:21], v[228:229]
	v_pk_add_f32 v[22:23], v[22:23], v[230:231]
	s_waitcnt vmcnt(1)
	v_pk_add_f32 v[24:25], v[24:25], v[232:233]
	v_pk_add_f32 v[26:27], v[26:27], v[234:235]
	s_waitcnt vmcnt(0)
;     ...
;         if (nslab > 0 && m >= ML) {
; #pragma unroll
;             for (int j = 0; j < 8; ++j) v[j] = v[j] * ALPHA;
;             for (int sidx = 0; sidx < nslab; ++sidx) { const float* sp = slab + ((size_t)sidx * (2 * CTXL) + (m - ML)) * D + lane * 4;
; #pragma unroll
;                 for (int j = 0; j < 8; ++j) v[j] += *(const f32x4*)(sp + 256 * j); }
;         }
	v_pk_add_f32 v[28:29], v[28:29], v[236:237]
	v_pk_add_f32 v[30:31], v[30:31], v[238:239]
	s_add_u32 s24, s22, 0x800000
	s_addc_u32 s25, s23, 0
	s_add_u32 s26, s24, 0x1000
	s_addc_u32 s27, s25, 0
	global_load_dwordx4 v[176:179], v240, s[24:25]
	global_load_dwordx4 v[180:183], v240, s[24:25] offset:1024
	global_load_dwordx4 v[184:187], v240, s[24:25] offset:2048
	global_load_dwordx4 v[188:191], v240, s[24:25] offset:3072
	global_load_dwordx4 v[192:195], v240, s[26:27]
	global_load_dwordx4 v[196:199], v240, s[26:27] offset:1024
	global_load_dwordx4 v[200:203], v240, s[26:27] offset:2048
	global_load_dwordx4 v[204:207], v240, s[26:27] offset:3072
	s_add_u32 s28, s22, 0xc00000
	s_addc_u32 s29, s23, 0
	s_add_u32 s30, s28, 0x1000
	s_addc_u32 s31, s29, 0
	global_load_dwordx4 v[208:211], v240, s[28:29]
	global_load_dwordx4 v[212:215], v240, s[28:29] offset:1024
	global_load_dwordx4 v[216:219], v240, s[28:29] offset:2048
	global_load_dwordx4 v[220:223], v240, s[28:29] offset:3072
	global_load_dwordx4 v[224:227], v240, s[30:31]
	global_load_dwordx4 v[228:231], v240, s[30:31] offset:1024
	global_load_dwordx4 v[232:235], v240, s[30:31] offset:2048
	global_load_dwordx4 v[236:239], v240, s[30:31] offset:3072
	s_waitcnt vmcnt(15)
	v_pk_add_f32 v[0:1], v[0:1], v[176:177]
	v_pk_add_f32 v[2:3], v[2:3], v[178:179]
	s_waitcnt vmcnt(14)
	v_pk_add_f32 v[4:5], v[4:5], v[180:181]
	v_pk_add_f32 v[6:7], v[6:7], v[182:183]
	s_waitcnt vmcnt(13)
	v_pk_add_f32 v[8:9], v[8:9], v[184:185]
	v_pk_add_f32 v[10:11], v[10:11], v[186:187]
	s_waitcnt vmcnt(12)
	v_pk_add_f32 v[12:13], v[12:13], v[188:189]
	v_pk_add_f32 v[14:15], v[14:15], v[190:191]
	s_waitcnt vmcnt(11)
	v_pk_add_f32 v[16:17], v[16:17], v[192:193]
	v_pk_add_f32 v[18:19], v[18:19], v[194:195]
	s_waitcnt vmcnt(10)
	v_pk_add_f32 v[20:21], v[20:21], v[196:197]
	v_pk_add_f32 v[22:23], v[22:23], v[198:199]
	s_waitcnt vmcnt(9)
	v_pk_add_f32 v[24:25], v[24:25], v[200:201]
	v_pk_add_f32 v[26:27], v[26:27], v[202:203]
	s_waitcnt vmcnt(8)
	v_pk_add_f32 v[28:29], v[28:29], v[204:205]
	v_pk_add_f32 v[30:31], v[30:31], v[206:207]
	s_waitcnt vmcnt(7)
	v_pk_add_f32 v[0:1], v[0:1], v[208:209]
	v_pk_add_f32 v[2:3], v[2:3], v[210:211]
	s_waitcnt vmcnt(6)
	v_pk_add_f32 v[4:5], v[4:5], v[212:213]
	v_pk_add_f32 v[6:7], v[6:7], v[214:215]
	s_waitcnt vmcnt(5)
	v_pk_add_f32 v[8:9], v[8:9], v[216:217]
	v_pk_add_f32 v[10:11], v[10:11], v[218:219]
	s_waitcnt vmcnt(4)
	v_pk_add_f32 v[12:13], v[12:13], v[220:221]
	v_pk_add_f32 v[14:15], v[14:15], v[222:223]
	s_waitcnt vmcnt(3)
	v_pk_add_f32 v[16:17], v[16:17], v[224:225]
	v_pk_add_f32 v[18:19], v[18:19], v[226:227]
	s_waitcnt vmcnt(2)
	v_pk_add_f32 v[20:21], v[20:21], v[228:229]
	v_pk_add_f32 v[22:23], v[22:23], v[230:231]
	s_waitcnt vmcnt(1)
	v_pk_add_f32 v[24:25], v[24:25], v[232:233]
	v_pk_add_f32 v[26:27], v[26:27], v[234:235]
	s_waitcnt vmcnt(0)
	v_pk_add_f32 v[28:29], v[28:29], v[236:237]
	v_pk_add_f32 v[30:31], v[30:31], v[238:239]
	s_add_u32 s24, s22, 0x1000000
	s_addc_u32 s25, s23, 0
	s_add_u32 s26, s24, 0x1000
	s_addc_u32 s27, s25, 0
	global_load_dwordx4 v[176:179], v240, s[24:25]
	global_load_dwordx4 v[180:183], v240, s[24:25] offset:1024
	global_load_dwordx4 v[184:187], v240, s[24:25] offset:2048
	global_load_dwordx4 v[188:191], v240, s[24:25] offset:3072
	global_load_dwordx4 v[192:195], v240, s[26:27]
	global_load_dwordx4 v[196:199], v240, s[26:27] offset:1024
	global_load_dwordx4 v[200:203], v240, s[26:27] offset:2048
	global_load_dwordx4 v[204:207], v240, s[26:27] offset:3072
	s_add_u32 s28, s22, 0x1400000
	s_addc_u32 s29, s23, 0
	s_add_u32 s30, s28, 0x1000
	s_addc_u32 s31, s29, 0
	global_load_dwordx4 v[208:211], v240, s[28:29]
	global_load_dwordx4 v[212:215], v240, s[28:29] offset:1024
	global_load_dwordx4 v[216:219], v240, s[28:29] offset:2048
	global_load_dwordx4 v[220:223], v240, s[28:29] offset:3072
	global_load_dwordx4 v[224:227], v240, s[30:31]
	global_load_dwordx4 v[228:231], v240, s[30:31] offset:1024
	global_load_dwordx4 v[232:235], v240, s[30:31] offset:2048
	global_load_dwordx4 v[236:239], v240, s[30:31] offset:3072
	s_waitcnt vmcnt(15)
	v_pk_add_f32 v[0:1], v[0:1], v[176:177]
	v_pk_add_f32 v[2:3], v[2:3], v[178:179]
	s_waitcnt vmcnt(14)
	v_pk_add_f32 v[4:5], v[4:5], v[180:181]
	v_pk_add_f32 v[6:7], v[6:7], v[182:183]
	s_waitcnt vmcnt(13)
	v_pk_add_f32 v[8:9], v[8:9], v[184:185]
	v_pk_add_f32 v[10:11], v[10:11], v[186:187]
	s_waitcnt vmcnt(12)
	v_pk_add_f32 v[12:13], v[12:13], v[188:189]
	v_pk_add_f32 v[14:15], v[14:15], v[190:191]
	s_waitcnt vmcnt(11)
	v_pk_add_f32 v[16:17], v[16:17], v[192:193]
	v_pk_add_f32 v[18:19], v[18:19], v[194:195]
	s_waitcnt vmcnt(10)
	v_pk_add_f32 v[20:21], v[20:21], v[196:197]
	v_pk_add_f32 v[22:23], v[22:23], v[198:199]
	s_waitcnt vmcnt(9)
	v_pk_add_f32 v[24:25], v[24:25], v[200:201]
	v_pk_add_f32 v[26:27], v[26:27], v[202:203]
	s_waitcnt vmcnt(8)
	v_pk_add_f32 v[28:29], v[28:29], v[204:205]
	v_pk_add_f32 v[30:31], v[30:31], v[206:207]
	s_waitcnt vmcnt(7)
	v_pk_add_f32 v[0:1], v[0:1], v[208:209]
	v_pk_add_f32 v[2:3], v[2:3], v[210:211]
	s_waitcnt vmcnt(6)
	v_pk_add_f32 v[4:5], v[4:5], v[212:213]
	v_pk_add_f32 v[6:7], v[6:7], v[214:215]
	s_waitcnt vmcnt(5)
	v_pk_add_f32 v[8:9], v[8:9], v[216:217]
	v_pk_add_f32 v[10:11], v[10:11], v[218:219]
	s_waitcnt vmcnt(4)
	v_pk_add_f32 v[12:13], v[12:13], v[220:221]
	v_pk_add_f32 v[14:15], v[14:15], v[222:223]
	s_waitcnt vmcnt(3)
	v_pk_add_f32 v[16:17], v[16:17], v[224:225]
	v_pk_add_f32 v[18:19], v[18:19], v[226:227]
	s_waitcnt vmcnt(2)
	v_pk_add_f32 v[20:21], v[20:21], v[228:229]
	v_pk_add_f32 v[22:23], v[22:23], v[230:231]
	s_waitcnt vmcnt(1)
;     ...
;         if (nslab > 0 && m >= ML) {
; #pragma unroll
;             for (int j = 0; j < 8; ++j) v[j] = v[j] * ALPHA;
;             for (int sidx = 0; sidx < nslab; ++sidx) { const float* sp = slab + ((size_t)sidx * (2 * CTXL) + (m - ML)) * D + lane * 4;
; #pragma unroll
;                 for (int j = 0; j < 8; ++j) v[j] += *(const f32x4*)(sp + 256 * j); }
;         }
;         if (do_ln) {
;             float s = 0.f;
; #pragma unroll
;             for (int j = 0; j < 8; ++j) s += (v[j].x + v[j].y) + (v[j].z + v[j].w);
;             const float mean = wave_sum(s) * (1.f / D); float s2 = 0.f;
	v_pk_add_f32 v[24:25], v[24:25], v[232:233]
	v_pk_add_f32 v[26:27], v[26:27], v[234:235]
	s_waitcnt vmcnt(0)
	v_pk_add_f32 v[28:29], v[28:29], v[236:237]
	v_pk_add_f32 v[30:31], v[30:31], v[238:239]
	s_add_u32 s24, s22, 0x1800000
	s_addc_u32 s25, s23, 0
	s_add_u32 s26, s24, 0x1000
	s_addc_u32 s27, s25, 0
	global_load_dwordx4 v[176:179], v240, s[24:25]
	global_load_dwordx4 v[180:183], v240, s[24:25] offset:1024
	global_load_dwordx4 v[184:187], v240, s[24:25] offset:2048
	global_load_dwordx4 v[188:191], v240, s[24:25] offset:3072
	global_load_dwordx4 v[192:195], v240, s[26:27]
	global_load_dwordx4 v[196:199], v240, s[26:27] offset:1024
	global_load_dwordx4 v[200:203], v240, s[26:27] offset:2048
	global_load_dwordx4 v[204:207], v240, s[26:27] offset:3072
	s_add_u32 s28, s22, 0x1c00000
	s_addc_u32 s29, s23, 0
	s_add_u32 s30, s28, 0x1000
	s_addc_u32 s31, s29, 0
	global_load_dwordx4 v[208:211], v240, s[28:29]
	global_load_dwordx4 v[212:215], v240, s[28:29] offset:1024
	global_load_dwordx4 v[216:219], v240, s[28:29] offset:2048
	global_load_dwordx4 v[220:223], v240, s[28:29] offset:3072
	global_load_dwordx4 v[224:227], v240, s[30:31]
	global_load_dwordx4 v[228:231], v240, s[30:31] offset:1024
	global_load_dwordx4 v[232:235], v240, s[30:31] offset:2048
	global_load_dwordx4 v[236:239], v240, s[30:31] offset:3072
	s_waitcnt vmcnt(15)
	v_pk_add_f32 v[0:1], v[0:1], v[176:177]
	v_pk_add_f32 v[2:3], v[2:3], v[178:179]
	s_waitcnt vmcnt(14)
	v_pk_add_f32 v[4:5], v[4:5], v[180:181]
	v_pk_add_f32 v[6:7], v[6:7], v[182:183]
	s_waitcnt vmcnt(13)
	v_pk_add_f32 v[8:9], v[8:9], v[184:185]
	v_pk_add_f32 v[10:11], v[10:11], v[186:187]
	s_waitcnt vmcnt(12)
	v_pk_add_f32 v[12:13], v[12:13], v[188:189]
	v_pk_add_f32 v[14:15], v[14:15], v[190:191]
	s_waitcnt vmcnt(11)
	v_pk_add_f32 v[16:17], v[16:17], v[192:193]
	v_pk_add_f32 v[18:19], v[18:19], v[194:195]
	s_waitcnt vmcnt(10)
	v_pk_add_f32 v[20:21], v[20:21], v[196:197]
	v_pk_add_f32 v[22:23], v[22:23], v[198:199]
	s_waitcnt vmcnt(9)
	v_pk_add_f32 v[24:25], v[24:25], v[200:201]
	v_pk_add_f32 v[26:27], v[26:27], v[202:203]
	s_waitcnt vmcnt(8)
	v_pk_add_f32 v[28:29], v[28:29], v[204:205]
	v_pk_add_f32 v[30:31], v[30:31], v[206:207]
	s_waitcnt vmcnt(7)
	v_pk_add_f32 v[0:1], v[0:1], v[208:209]
	v_pk_add_f32 v[2:3], v[2:3], v[210:211]
	s_waitcnt vmcnt(6)
	v_pk_add_f32 v[4:5], v[4:5], v[212:213]
	v_pk_add_f32 v[6:7], v[6:7], v[214:215]
	s_waitcnt vmcnt(5)
	v_pk_add_f32 v[8:9], v[8:9], v[216:217]
	v_pk_add_f32 v[10:11], v[10:11], v[218:219]
	s_waitcnt vmcnt(4)
	v_pk_add_f32 v[12:13], v[12:13], v[220:221]
	v_pk_add_f32 v[14:15], v[14:15], v[222:223]
	s_waitcnt vmcnt(3)
	v_pk_add_f32 v[16:17], v[16:17], v[224:225]
	v_pk_add_f32 v[18:19], v[18:19], v[226:227]
	s_waitcnt vmcnt(2)
	v_pk_add_f32 v[20:21], v[20:21], v[228:229]
	v_pk_add_f32 v[22:23], v[22:23], v[230:231]
	s_waitcnt vmcnt(1)
	v_pk_add_f32 v[24:25], v[24:25], v[232:233]
	v_pk_add_f32 v[26:27], v[26:27], v[234:235]
	s_waitcnt vmcnt(0)
	v_pk_add_f32 v[28:29], v[28:29], v[236:237]
	v_pk_add_f32 v[30:31], v[30:31], v[238:239]
	v_mov_b32_e32 v226, 0x3a000000
	v_mov_b32_e32 v227, 0x3727c5ac
	s_add_u32 s10, s64, 0x1e000
	s_addc_u32 s11, s65, 0
	s_add_u32 s12, s10, 0x1000
	s_addc_u32 s13, s11, 0
	s_add_u32 s14, s64, 0x20000
	s_addc_u32 s15, s65, 0
	s_add_u32 s16, s14, 0x1000
	s_addc_u32 s17, s15, 0
	global_load_dwordx4 v[176:179], v240, s[10:11]
	global_load_dwordx4 v[180:183], v240, s[10:11] offset:1024
	global_load_dwordx4 v[184:187], v240, s[10:11] offset:2048
	global_load_dwordx4 v[188:191], v240, s[10:11] offset:3072
	global_load_dwordx4 v[192:195], v240, s[12:13]
	global_load_dwordx4 v[196:199], v240, s[12:13] offset:1024
	global_load_dwordx4 v[200:203], v240, s[12:13] offset:2048
	global_load_dwordx4 v[204:207], v240, s[12:13] offset:3072
	global_load_dwordx4 v[32:35], v240, s[14:15]
	global_load_dwordx4 v[36:39], v240, s[14:15] offset:1024
	global_load_dwordx4 v[40:43], v240, s[14:15] offset:2048
	global_load_dwordx4 v[44:47], v240, s[14:15] offset:3072
	global_load_dwordx4 v[48:51], v240, s[16:17]
	global_load_dwordx4 v[52:55], v240, s[16:17] offset:1024
	global_load_dwordx4 v[56:59], v240, s[16:17] offset:2048
	global_load_dwordx4 v[60:63], v240, s[16:17] offset:3072
	s_add_u32 s84, s64, 0x6300000
	s_addc_u32 s85, s65, 0
	s_add_u32 s84, s84, s58
	s_addc_u32 s85, s85, 0
	s_add_u32 s86, s84, 0x1000
	s_addc_u32 s87, s85, 0
	s_add_i32 s59, s60, 0x4000
	s_lshl_b32 s59, s59, 12
	s_add_u32 s96, s64, 0x6700000
	s_addc_u32 s97, s65, 0
	s_add_u32 s96, s96, s59
	s_addc_u32 s97, s97, 0
	v_pk_add_f32 v[208:209], v[0:1], v[2:3]
	v_pk_add_f32 v[210:211], v[4:5], v[6:7]
	v_pk_add_f32 v[212:213], v[8:9], v[10:11]
	v_pk_add_f32 v[214:215], v[12:13], v[14:15]
	v_pk_add_f32 v[216:217], v[16:17], v[18:19]
	v_pk_add_f32 v[218:219], v[20:21], v[22:23]
	v_pk_add_f32 v[220:221], v[24:25], v[26:27]
	v_pk_add_f32 v[222:223], v[28:29], v[30:31]
	v_pk_add_f32 v[208:209], v[208:209], v[210:211]
	v_pk_add_f32 v[212:213], v[212:213], v[214:215]
	v_pk_add_f32 v[216:217], v[216:217], v[218:219]
	v_pk_add_f32 v[220:221], v[220:221], v[222:223]
	v_pk_add_f32 v[208:209], v[208:209], v[212:213]
	v_pk_add_f32 v[216:217], v[216:217], v[220:221]
	v_pk_add_f32 v[208:209], v[208:209], v[216:217]
	v_add_f32_e32 v242, v208, v209
	s_nop 1
	v_add_f32_dpp v242, v242, v242 row_ror:8 row_mask:0xf bank_mask:0xf bound_ctrl:1
	s_nop 1
	v_add_f32_dpp v242, v242, v242 row_ror:4 row_mask:0xf bank_mask:0xf bound_ctrl:1
	s_nop 1
	v_add_f32_dpp v242, v242, v242 row_ror:2 row_mask:0xf bank_mask:0xf bound_ctrl:1
	s_nop 1
	v_add_f32_dpp v242, v242, v242 row_ror:1 row_mask:0xf bank_mask:0xf bound_ctrl:1
	s_nop 1
; template <int CTRL> __device__ __forceinline__ float dpp_mov(float x) { return __builtin_bit_cast(float, __builtin_amdgcn_update_dpp(0, __builtin_bit_cast(int, x), CTRL, 0xf, 0xf, true)); }
; __device__ __forceinline__ float allreduce16(float x) {
;     x += dpp_mov<0x128>(x); x += dpp_mov<0x124>(x); x += dpp_mov<0x122>(x); x += dpp_mov<0x121>(x); return x;
; }
;     ...
;         if (do_ln) {
;             float s = 0.f;
; #pragma unroll
;             for (int j = 0; j < 8; ++j) s += (v[j].x + v[j].y) + (v[j].z + v[j].w);
;             const float mean = wave_sum(s) * (1.f / D); float s2 = 0.f;
; #pragma unroll
;             for (int j = 0; j < 8; ++j) { v[j] = v[j] - mean; s2 += (v[j].x * v[j].x + v[j].y * v[j].y) + (v[j].z * v[j].z + v[j].w * v[j].w); }
;             const float rstd = rsqrtf(wave_sum(s2) * (1.f / D) + LN_EPS);
	v_readlane_b32 s52, v242, 0
	v_readlane_b32 s53, v242, 16
	v_readlane_b32 s54, v242, 32
	v_readlane_b32 s55, v242, 48
	s_nop 1
	v_mov_b32_e32 v243, s52
	v_add_f32_e32 v243, s53, v243
	v_add_f32_e32 v243, s54, v243
	v_add_f32_e32 v243, s55, v243
	v_mul_f32_e32 v244, v226, v243
	v_pk_add_f32 v[0:1], v[0:1], v[244:245] op_sel_hi:[1,0] neg_lo:[0,1] neg_hi:[0,1]
	v_pk_add_f32 v[2:3], v[2:3], v[244:245] op_sel_hi:[1,0] neg_lo:[0,1] neg_hi:[0,1]
	v_pk_add_f32 v[4:5], v[4:5], v[244:245] op_sel_hi:[1,0] neg_lo:[0,1] neg_hi:[0,1]
	v_pk_add_f32 v[6:7], v[6:7], v[244:245] op_sel_hi:[1,0] neg_lo:[0,1] neg_hi:[0,1]
	v_pk_add_f32 v[8:9], v[8:9], v[244:245] op_sel_hi:[1,0] neg_lo:[0,1] neg_hi:[0,1]
	v_pk_add_f32 v[10:11], v[10:11], v[244:245] op_sel_hi:[1,0] neg_lo:[0,1] neg_hi:[0,1]
	v_pk_add_f32 v[12:13], v[12:13], v[244:245] op_sel_hi:[1,0] neg_lo:[0,1] neg_hi:[0,1]
	v_pk_add_f32 v[14:15], v[14:15], v[244:245] op_sel_hi:[1,0] neg_lo:[0,1] neg_hi:[0,1]
	v_pk_add_f32 v[16:17], v[16:17], v[244:245] op_sel_hi:[1,0] neg_lo:[0,1] neg_hi:[0,1]
	v_pk_add_f32 v[18:19], v[18:19], v[244:245] op_sel_hi:[1,0] neg_lo:[0,1] neg_hi:[0,1]
	v_pk_add_f32 v[20:21], v[20:21], v[244:245] op_sel_hi:[1,0] neg_lo:[0,1] neg_hi:[0,1]
	v_pk_add_f32 v[22:23], v[22:23], v[244:245] op_sel_hi:[1,0] neg_lo:[0,1] neg_hi:[0,1]
	v_pk_add_f32 v[24:25], v[24:25], v[244:245] op_sel_hi:[1,0] neg_lo:[0,1] neg_hi:[0,1]
	v_pk_add_f32 v[26:27], v[26:27], v[244:245] op_sel_hi:[1,0] neg_lo:[0,1] neg_hi:[0,1]
	v_pk_add_f32 v[28:29], v[28:29], v[244:245] op_sel_hi:[1,0] neg_lo:[0,1] neg_hi:[0,1]
	v_pk_add_f32 v[30:31], v[30:31], v[244:245] op_sel_hi:[1,0] neg_lo:[0,1] neg_hi:[0,1]
	v_pk_mul_f32 v[208:209], v[0:1], v[0:1]
	v_pk_mul_f32 v[210:211], v[2:3], v[2:3]
	v_pk_mul_f32 v[212:213], v[4:5], v[4:5]
	v_pk_mul_f32 v[214:215], v[6:7], v[6:7]
	v_pk_fma_f32 v[208:209], v[8:9], v[8:9], v[208:209]
	v_pk_fma_f32 v[210:211], v[10:11], v[10:11], v[210:211]
	v_pk_fma_f32 v[212:213], v[12:13], v[12:13], v[212:213]
	v_pk_fma_f32 v[214:215], v[14:15], v[14:15], v[214:215]
	v_pk_fma_f32 v[208:209], v[16:17], v[16:17], v[208:209]
	v_pk_fma_f32 v[210:211], v[18:19], v[18:19], v[210:211]
	v_pk_fma_f32 v[212:213], v[20:21], v[20:21], v[212:213]
	v_pk_fma_f32 v[214:215], v[22:23], v[22:23], v[214:215]
	v_pk_fma_f32 v[208:209], v[24:25], v[24:25], v[208:209]
	v_pk_fma_f32 v[210:211], v[26:27], v[26:27], v[210:211]
	v_pk_fma_f32 v[212:213], v[28:29], v[28:29], v[212:213]
	v_pk_fma_f32 v[214:215], v[30:31], v[30:31], v[214:215]
	v_pk_add_f32 v[208:209], v[208:209], v[210:211]
	v_pk_add_f32 v[212:213], v[212:213], v[214:215]
	v_pk_add_f32 v[208:209], v[208:209], v[212:213]
	v_add_f32_e32 v242, v208, v209
	s_nop 1
	v_add_f32_dpp v242, v242, v242 row_ror:8 row_mask:0xf bank_mask:0xf bound_ctrl:1
	s_nop 1
	v_add_f32_dpp v242, v242, v242 row_ror:4 row_mask:0xf bank_mask:0xf bound_ctrl:1
	s_nop 1
	v_add_f32_dpp v242, v242, v242 row_ror:2 row_mask:0xf bank_mask:0xf bound_ctrl:1
	s_nop 1
	v_add_f32_dpp v242, v242, v242 row_ror:1 row_mask:0xf bank_mask:0xf bound_ctrl:1
	s_nop 1
	v_readlane_b32 s52, v242, 0
	v_readlane_b32 s53, v242, 16
	v_readlane_b32 s54, v242, 32
	v_readlane_b32 s55, v242, 48
	s_nop 1
	v_mov_b32_e32 v243, s52
	v_add_f32_e32 v243, s53, v243
	v_add_f32_e32 v243, s54, v243
	v_add_f32_e32 v243, s55, v243
	v_fma_f32 v224, v243, v226, v227
	v_rsq_f32_e32 v224, v224
	s_waitcnt vmcnt(0)
; __device__ __forceinline__ unsigned pk2(float lo, float hi) { return f2bf(lo) | (f2bf(hi) << 16); }
;     ...
;             const float rstd = rsqrtf(wave_sum(s2) * (1.f / D) + LN_EPS);
; #pragma unroll
;             for (int j = 0; j < 8; ++j) { const f32x4 gg = *(const f32x4*)(lng + lane * 4 + 256 * j), bb = *(const f32x4*)(lnb + lane * 4 + 256 * j);
;                 v[j] = v[j] * rstd * gg + bb; *(f32x4*)(dst + lane * 4 + 256 * j) = v[j]; }
;         }
;         if (do_mod) {
;             const float* sh = modl + mv * NMOD + shc * D; const float* sc = modl + mv * NMOD + scc * D;
; #pragma unroll
;             for (int j = 0; j < 8; ++j) { const f32x4 s1 = *(const f32x4*)(sc + lane * 4 + 256 * j), h1 = *(const f32x4*)(sh + lane * 4 + 256 * j);
;                 const f32x4 a = v[j] * (s1 + 1.f) + h1; u32x2 o; o.x = pk2(a.x, a.y); o.y = pk2(a.z, a.w);
;                 *(u32x2*)(aout + (size_t)m * D + lane * 4 + 256 * j) = o; }
;         }
	v_pk_add_f32 v[32:33], v[32:33], 1.0 op_sel_hi:[1,0]
	v_pk_add_f32 v[34:35], v[34:35], 1.0 op_sel_hi:[1,0]
	v_pk_add_f32 v[36:37], v[36:37], 1.0 op_sel_hi:[1,0]
	v_pk_add_f32 v[38:39], v[38:39], 1.0 op_sel_hi:[1,0]
	v_pk_add_f32 v[40:41], v[40:41], 1.0 op_sel_hi:[1,0]
	v_pk_add_f32 v[42:43], v[42:43], 1.0 op_sel_hi:[1,0]
	v_pk_add_f32 v[44:45], v[44:45], 1.0 op_sel_hi:[1,0]
	v_pk_add_f32 v[46:47], v[46:47], 1.0 op_sel_hi:[1,0]
	v_pk_add_f32 v[48:49], v[48:49], 1.0 op_sel_hi:[1,0]
	v_pk_add_f32 v[50:51], v[50:51], 1.0 op_sel_hi:[1,0]
	v_pk_add_f32 v[52:53], v[52:53], 1.0 op_sel_hi:[1,0]
	v_pk_add_f32 v[54:55], v[54:55], 1.0 op_sel_hi:[1,0]
	v_pk_add_f32 v[56:57], v[56:57], 1.0 op_sel_hi:[1,0]
	v_pk_add_f32 v[58:59], v[58:59], 1.0 op_sel_hi:[1,0]
	v_pk_add_f32 v[60:61], v[60:61], 1.0 op_sel_hi:[1,0]
	v_pk_add_f32 v[62:63], v[62:63], 1.0 op_sel_hi:[1,0]
	v_pk_mul_f32 v[208:209], v[0:1], v[224:225] op_sel_hi:[1,0]
	v_pk_mul_f32 v[210:211], v[2:3], v[224:225] op_sel_hi:[1,0]
	v_pk_fma_f32 v[0:1], v[208:209], v[96:97], v[128:129]
	v_pk_fma_f32 v[2:3], v[210:211], v[98:99], v[130:131]
	global_store_dwordx4 v240, v[0:3], s[84:85]
	v_pk_mul_f32 v[208:209], v[4:5], v[224:225] op_sel_hi:[1,0]
	v_pk_mul_f32 v[210:211], v[6:7], v[224:225] op_sel_hi:[1,0]
	v_pk_fma_f32 v[4:5], v[208:209], v[100:101], v[132:133]
	v_pk_fma_f32 v[6:7], v[210:211], v[102:103], v[134:135]
	global_store_dwordx4 v240, v[4:7], s[84:85] offset:1024
	v_pk_mul_f32 v[208:209], v[8:9], v[224:225] op_sel_hi:[1,0]
	v_pk_mul_f32 v[210:211], v[10:11], v[224:225] op_sel_hi:[1,0]
	v_pk_fma_f32 v[8:9], v[208:209], v[104:105], v[136:137]
	v_pk_fma_f32 v[10:11], v[210:211], v[106:107], v[138:139]
	global_store_dwordx4 v240, v[8:11], s[84:85] offset:2048
	v_pk_mul_f32 v[208:209], v[12:13], v[224:225] op_sel_hi:[1,0]
	v_pk_mul_f32 v[210:211], v[14:15], v[224:225] op_sel_hi:[1,0]
	v_pk_fma_f32 v[12:13], v[208:209], v[108:109], v[140:141]
	v_pk_fma_f32 v[14:15], v[210:211], v[110:111], v[142:143]
	global_store_dwordx4 v240, v[12:15], s[84:85] offset:3072
	v_pk_mul_f32 v[208:209], v[16:17], v[224:225] op_sel_hi:[1,0]
	v_pk_mul_f32 v[210:211], v[18:19], v[224:225] op_sel_hi:[1,0]
	v_pk_fma_f32 v[16:17], v[208:209], v[112:113], v[144:145]
	v_pk_fma_f32 v[18:19], v[210:211], v[114:115], v[146:147]
	global_store_dwordx4 v240, v[16:19], s[86:87]
	v_pk_mul_f32 v[208:209], v[20:21], v[224:225] op_sel_hi:[1,0]
	v_pk_mul_f32 v[210:211], v[22:23], v[224:225] op_sel_hi:[1,0]
	v_pk_fma_f32 v[20:21], v[208:209], v[116:117], v[148:149]
	v_pk_fma_f32 v[22:23], v[210:211], v[118:119], v[150:151]
	global_store_dwordx4 v240, v[20:23], s[86:87] offset:1024
	v_pk_mul_f32 v[208:209], v[24:25], v[224:225] op_sel_hi:[1,0]
	v_pk_mul_f32 v[210:211], v[26:27], v[224:225] op_sel_hi:[1,0]
	v_pk_fma_f32 v[24:25], v[208:209], v[120:121], v[152:153]
	v_pk_fma_f32 v[26:27], v[210:211], v[122:123], v[154:155]
	global_store_dwordx4 v240, v[24:27], s[86:87] offset:2048
	v_pk_mul_f32 v[208:209], v[28:29], v[224:225] op_sel_hi:[1,0]
	v_pk_mul_f32 v[210:211], v[30:31], v[224:225] op_sel_hi:[1,0]
	v_pk_fma_f32 v[28:29], v[208:209], v[124:125], v[156:157]
	v_pk_fma_f32 v[30:31], v[210:211], v[126:127], v[158:159]
	global_store_dwordx4 v240, v[28:31], s[86:87] offset:3072
	v_pk_fma_f32 v[208:209], v[0:1], v[32:33], v[176:177]
	v_pk_fma_f32 v[210:211], v[2:3], v[34:35], v[178:179]
	v_cvt_pk_bf16_f32 v212, v208, v209
	v_cvt_pk_bf16_f32 v213, v210, v211
	global_store_dwordx2 v241, v[212:213], s[96:97]
	v_pk_fma_f32 v[208:209], v[4:5], v[36:37], v[180:181]
	v_pk_fma_f32 v[210:211], v[6:7], v[38:39], v[182:183]
	v_cvt_pk_bf16_f32 v212, v208, v209
	v_cvt_pk_bf16_f32 v213, v210, v211
	global_store_dwordx2 v241, v[212:213], s[96:97] offset:512
	v_pk_fma_f32 v[208:209], v[8:9], v[40:41], v[184:185]
	v_pk_fma_f32 v[210:211], v[10:11], v[42:43], v[186:187]
	v_cvt_pk_bf16_f32 v212, v208, v209
	v_cvt_pk_bf16_f32 v213, v210, v211
	global_store_dwordx2 v241, v[212:213], s[96:97] offset:1024
	v_pk_fma_f32 v[208:209], v[12:13], v[44:45], v[188:189]
	v_pk_fma_f32 v[210:211], v[14:15], v[46:47], v[190:191]
	v_cvt_pk_bf16_f32 v212, v208, v209
	v_cvt_pk_bf16_f32 v213, v210, v211
	global_store_dwordx2 v241, v[212:213], s[96:97] offset:1536
	v_pk_fma_f32 v[208:209], v[16:17], v[48:49], v[192:193]
	v_pk_fma_f32 v[210:211], v[18:19], v[50:51], v[194:195]
	v_cvt_pk_bf16_f32 v212, v208, v209
	v_cvt_pk_bf16_f32 v213, v210, v211
	global_store_dwordx2 v241, v[212:213], s[96:97] offset:2048
	v_pk_fma_f32 v[208:209], v[20:21], v[52:53], v[196:197]
	v_pk_fma_f32 v[210:211], v[22:23], v[54:55], v[198:199]
	v_cvt_pk_bf16_f32 v212, v208, v209
	v_cvt_pk_bf16_f32 v213, v210, v211
	global_store_dwordx2 v241, v[212:213], s[96:97] offset:2560
	v_pk_fma_f32 v[208:209], v[24:25], v[56:57], v[200:201]
	v_pk_fma_f32 v[210:211], v[26:27], v[58:59], v[202:203]
	v_cvt_pk_bf16_f32 v212, v208, v209
	v_cvt_pk_bf16_f32 v213, v210, v211
	global_store_dwordx2 v241, v[212:213], s[96:97] offset:3072
	v_pk_fma_f32 v[208:209], v[28:29], v[60:61], v[204:205]
	v_pk_fma_f32 v[210:211], v[30:31], v[62:63], v[206:207]
	v_cvt_pk_bf16_f32 v212, v208, v209
	v_cvt_pk_bf16_f32 v213, v210, v211
	global_store_dwordx2 v241, v[212:213], s[96:97] offset:3584
	s_nop 1

; __device__ __forceinline__ float wave_sum(float v) {
; #pragma unroll
;     for (int o = 1; o < 64; o <<= 1) v += __shfl_xor(v, o);
;     return v;
;     ...
;         if (do_ln) {
;             float s = 0.f;
; #pragma unroll
;             for (int j = 0; j < 8; ++j) s += (v[j].x + v[j].y) + (v[j].z + v[j].w);
;             const float mean = wave_sum(s) * (1.f / D); float s2 = 0.f;
; #pragma unroll
;             for (int j = 0; j < 8; ++j) { v[j] = v[j] - mean; s2 += (v[j].x * v[j].x + v[j].y * v[j].y) + (v[j].z * v[j].z + v[j].w * v[j].w); }
;             const float rstd = rsqrtf(wave_sum(s2) * (1.f / D) + LN_EPS);
; #pragma unroll
;             for (int j = 0; j < 8; ++j) { const f32x4 gg = *(const f32x4*)(lng + lane * 4 + 256 * j), bb = *(const f32x4*)(lnb + lane * 4 + 256 * j);
;                 v[j] = v[j] * rstd * gg + bb; *(f32x4*)(dst + lane * 4 + 256 * j) = v[j]; }
.LBB0_1031:
	v_mov_b32_e32 v64, v56
	v_mov_b32_e32 v65, v60
	v_mov_b32_e32 v66, v57
	v_mov_b32_e32 v67, v61
	v_pk_add_f32 v[64:65], v[64:65], v[66:67]
	v_mov_b32_e32 v66, v58
	v_mov_b32_e32 v67, v62
	v_mov_b32_e32 v96, v59
	v_mov_b32_e32 v97, v63
	v_pk_add_f32 v[66:67], v[66:67], v[96:97]
	v_mov_b32_e32 v96, v52
	v_pk_add_f32 v[64:65], v[64:65], v[66:67]
	v_mov_b32_e32 v66, v53
	v_mov_b32_e32 v67, v54
	v_mov_b32_e32 v97, v55
	v_pk_add_f32 v[66:67], v[66:67], v[96:97]
	v_add_f32_e32 v65, 0, v65
	v_pk_add_f32 v[66:67], v[66:67], v[66:67] op_sel_hi:[0,1]
	v_add_f32_e32 v65, v64, v65
	v_add_f32_e32 v97, v48, v49
	v_add_f32_e32 v107, v50, v51
	v_mov_b32_e32 v96, v44
	v_mov_b32_e32 v106, v45
	v_mov_b32_e32 v66, v46
	v_mov_b32_e32 v64, v47
	v_pk_add_f32 v[96:97], v[96:97], v[106:107]
	v_pk_add_f32 v[64:65], v[66:67], v[64:65]
	v_mov_b32_e32 v66, v41
	v_pk_add_f32 v[64:65], v[96:97], v[64:65]
	v_mov_b32_e32 v67, v42
	v_mov_b32_e32 v96, v40
	v_mov_b32_e32 v97, v43
	v_pk_add_f32 v[66:67], v[66:67], v[96:97]
	v_pk_add_f32 v[64:65], v[64:65], v[64:65] op_sel_hi:[0,1]
	v_pk_add_f32 v[66:67], v[66:67], v[66:67] op_sel_hi:[0,1]
	v_add_f32_e32 v97, v36, v37
	v_add_f32_e32 v107, v38, v39
	v_mov_b32_e32 v96, v32
	v_mov_b32_e32 v106, v33
	v_mov_b32_e32 v66, v34
	v_mov_b32_e32 v64, v35
	v_pk_add_f32 v[96:97], v[96:97], v[106:107]
	v_pk_add_f32 v[64:65], v[66:67], v[64:65]
	s_lshl_b32 s1, s52, 2
	v_pk_add_f32 v[64:65], v[96:97], v[64:65]
	s_add_u32 s52, s29, s1
	v_add_f32_e32 v64, v64, v65
	ds_bpermute_b32 v65, v98, v64
	s_addc_u32 s53, s33, 0
	s_ashr_i32 s35, s34, 31
	s_lshl_b64 s[34:35], s[34:35], 12
	s_add_i32 s0, s0, s6
	s_waitcnt lgkmcnt(0)
	v_add_f32_e32 v64, v64, v65
	ds_bpermute_b32 v65, v99, v64
	s_waitcnt lgkmcnt(0)
	v_add_f32_e32 v64, v64, v65
	ds_bpermute_b32 v65, v100, v64
	s_waitcnt lgkmcnt(0)
	v_add_f32_e32 v64, v64, v65
	ds_bpermute_b32 v65, v101, v64
	s_waitcnt lgkmcnt(0)
	v_add_f32_e32 v64, v64, v65
	ds_bpermute_b32 v65, v102, v64
	s_waitcnt lgkmcnt(0)
	v_add_f32_e32 v64, v64, v65
	ds_bpermute_b32 v65, v103, v64
	s_waitcnt lgkmcnt(0)
	v_add_f32_e32 v105, v64, v65
	v_fmac_f32_e32 v61, 0xba000000, v105
	v_fmac_f32_e32 v57, 0xba000000, v105
	v_fmac_f32_e32 v63, 0xba000000, v105
	v_fmac_f32_e32 v60, 0xba000000, v105
	v_fmac_f32_e32 v59, 0xba000000, v105
	v_fmac_f32_e32 v56, 0xba000000, v105
	v_mov_b32_e32 v66, v61
	v_mov_b32_e32 v67, v57
	v_fmac_f32_e32 v62, 0xba000000, v105
	v_fmac_f32_e32 v58, 0xba000000, v105
	v_mov_b32_e32 v64, v60
	v_mov_b32_e32 v65, v56
	v_pk_mul_f32 v[66:67], v[66:67], v[66:67]
	v_mov_b32_e32 v96, v63
	v_mov_b32_e32 v97, v59
	v_pk_fma_f32 v[64:65], v[64:65], v[64:65], v[66:67]
	v_mov_b32_e32 v66, v62
	v_mov_b32_e32 v67, v58
	v_pk_mul_f32 v[96:97], v[96:97], v[96:97]
	v_fmac_f32_e32 v53, 0xba000000, v105
	v_pk_fma_f32 v[66:67], v[66:67], v[66:67], v[96:97]
	v_fmac_f32_e32 v52, 0xba000000, v105
	v_pk_add_f32 v[64:65], v[64:65], v[66:67]
	v_fmac_f32_e32 v55, 0xba000000, v105
	v_fmac_f32_e32 v54, 0xba000000, v105
	v_pk_add_f32 v[64:65], v[64:65], v[64:65] op_sel_hi:[0,1]
	v_pk_mul_f32 v[66:67], v[54:55], v[54:55]
	v_pk_mul_f32 v[96:97], v[52:53], v[52:53]
	v_fmac_f32_e32 v48, 0xba000000, v105
	v_pk_mov_b32 v[106:107], v[96:97], v[66:67] op_sel:[1,0]
	v_mov_b32_e32 v97, v67
	v_fmac_f32_e32 v49, 0xba000000, v105
	v_fmac_f32_e32 v50, 0xba000000, v105
	v_mul_f32_e32 v64, v48, v48
	v_pk_add_f32 v[66:67], v[106:107], v[96:97]
	v_fmac_f32_e32 v51, 0xba000000, v105
	v_pk_fma_f32 v[96:97], v[48:49], v[48:49], v[64:65] op_sel_hi:[1,1,0]
	v_mul_f32_e32 v64, v50, v50
	v_pk_add_f32 v[66:67], v[66:67], v[66:67] op_sel_hi:[0,1]
	v_pk_fma_f32 v[106:107], v[50:51], v[50:51], v[64:65] op_sel_hi:[1,1,0]
	v_fmac_f32_e32 v47, 0xba000000, v105
	v_fmac_f32_e32 v46, 0xba000000, v105
	v_fmac_f32_e32 v45, 0xba000000, v105
	v_fmac_f32_e32 v44, 0xba000000, v105
	v_mul_f32_e32 v96, v44, v44
	v_mul_f32_e32 v106, v45, v45
	v_mul_f32_e32 v66, v46, v46
	v_mul_f32_e32 v64, v47, v47
	v_pk_add_f32 v[96:97], v[96:97], v[106:107]
	v_pk_add_f32 v[64:65], v[66:67], v[64:65]
	v_fmac_f32_e32 v41, 0xba000000, v105
	v_pk_add_f32 v[96:97], v[96:97], v[64:65]
	global_load_dwordx4 v[64:67], v[72:73], off
	global_load_dwordx4 v[106:109], v[74:75], off
	v_fmac_f32_e32 v40, 0xba000000, v105
	v_fmac_f32_e32 v43, 0xba000000, v105
	v_fmac_f32_e32 v42, 0xba000000, v105
	v_pk_add_f32 v[96:97], v[96:97], v[96:97] op_sel_hi:[0,1]
	v_pk_mul_f32 v[110:111], v[42:43], v[42:43]
	v_pk_mul_f32 v[112:113], v[40:41], v[40:41]
	v_fmac_f32_e32 v36, 0xba000000, v105
	v_pk_mov_b32 v[114:115], v[112:113], v[110:111] op_sel:[1,0]
	v_mov_b32_e32 v113, v111
	v_fmac_f32_e32 v37, 0xba000000, v105
	v_fmac_f32_e32 v38, 0xba000000, v105
	v_mul_f32_e32 v96, v36, v36
	v_pk_add_f32 v[110:111], v[114:115], v[112:113]
	v_fmac_f32_e32 v39, 0xba000000, v105
	v_pk_fma_f32 v[112:113], v[36:37], v[36:37], v[96:97] op_sel_hi:[1,1,0]
	v_mul_f32_e32 v96, v38, v38
	v_pk_add_f32 v[110:111], v[110:111], v[110:111] op_sel_hi:[0,1]
	v_pk_fma_f32 v[114:115], v[38:39], v[38:39], v[96:97] op_sel_hi:[1,1,0]
	v_fmamk_f32 v117, v105, 0xba000000, v35
	v_fmamk_f32 v116, v105, 0xba000000, v34
	v_fmamk_f32 v33, v105, 0xba000000, v33
	v_fmac_f32_e32 v32, 0xba000000, v105
	v_mul_f32_e32 v112, v32, v32
	v_mul_f32_e32 v114, v33, v33
	v_mul_f32_e32 v110, v116, v116
	v_mul_f32_e32 v96, v117, v117
	v_pk_add_f32 v[34:35], v[112:113], v[114:115]
	v_pk_add_f32 v[96:97], v[110:111], v[96:97]
	s_nop 0
	v_pk_add_f32 v[34:35], v[34:35], v[96:97]
	s_nop 0
	v_add_f32_e32 v34, v34, v35
	ds_bpermute_b32 v35, v98, v34
	s_waitcnt lgkmcnt(0)
	v_add_f32_e32 v34, v34, v35
	ds_bpermute_b32 v35, v99, v34
	s_waitcnt lgkmcnt(0)
; __device__ __forceinline__ unsigned pk2(float lo, float hi) { return f2bf(lo) | (f2bf(hi) << 16); }
;     ...
;             const float mean = wave_sum(s) * (1.f / D); float s2 = 0.f;
; #pragma unroll
;             for (int j = 0; j < 8; ++j) { v[j] = v[j] - mean; s2 += (v[j].x * v[j].x + v[j].y * v[j].y) + (v[j].z * v[j].z + v[j].w * v[j].w); }
;             const float rstd = rsqrtf(wave_sum(s2) * (1.f / D) + LN_EPS);
; #pragma unroll
;             for (int j = 0; j < 8; ++j) { const f32x4 gg = *(const f32x4*)(lng + lane * 4 + 256 * j), bb = *(const f32x4*)(lnb + lane * 4 + 256 * j);
;                 v[j] = v[j] * rstd * gg + bb; *(f32x4*)(dst + lane * 4 + 256 * j) = v[j]; }
;         }
;         if (do_mod) {
;             const float* sh = modl + mv * NMOD + shc * D; const float* sc = modl + mv * NMOD + scc * D;
; #pragma unroll
;             for (int j = 0; j < 8; ++j) { const f32x4 s1 = *(const f32x4*)(sc + lane * 4 + 256 * j), h1 = *(const f32x4*)(sh + lane * 4 + 256 * j);
;                 const f32x4 a = v[j] * (s1 + 1.f) + h1; u32x2 o; o.x = pk2(a.x, a.y); o.y = pk2(a.z, a.w);
;                 *(u32x2*)(aout + (size_t)m * D + lane * 4 + 256 * j) = o; }
;         }
	v_add_f32_e32 v34, v34, v35
	ds_bpermute_b32 v35, v100, v34
	s_waitcnt lgkmcnt(0)
	v_add_f32_e32 v34, v34, v35
	ds_bpermute_b32 v35, v101, v34
	s_waitcnt lgkmcnt(0)
	v_add_f32_e32 v34, v34, v35
	ds_bpermute_b32 v35, v102, v34
	s_waitcnt lgkmcnt(0)
	v_add_f32_e32 v34, v34, v35
	ds_bpermute_b32 v35, v103, v34
	s_waitcnt lgkmcnt(0)
	v_add_f32_e32 v34, v34, v35
	v_fmamk_f32 v34, v34, 0x3a000000, v104
	v_mul_f32_e32 v35, 0x4b800000, v34
	v_cmp_gt_f32_e32 vcc, s76, v34
	s_nop 1
	v_cndmask_b32_e32 v34, v34, v35, vcc
	v_rsq_f32_e32 v34, v34
	s_nop 0
	v_mul_f32_e32 v35, 0x45800000, v34
	v_cndmask_b32_e32 v96, v34, v35, vcc
	v_pk_mul_f32 v[34:35], v[60:61], v[96:97] op_sel_hi:[1,0]
	v_pk_mul_f32 v[60:61], v[62:63], v[96:97] op_sel_hi:[1,0]
	v_pk_mul_f32 v[56:57], v[56:57], v[96:97] op_sel_hi:[1,0]
	s_waitcnt vmcnt(0)
	v_pk_fma_f32 v[62:63], v[66:67], v[60:61], v[108:109]
	v_pk_fma_f32 v[60:61], v[64:65], v[34:35], v[106:107]
	global_store_dwordx4 v68, v[60:63], s[54:55]
	global_load_dwordx4 v[64:67], v[72:73], off offset:1024
	global_load_dwordx4 v[106:109], v[74:75], off offset:1024
	v_pk_mul_f32 v[34:35], v[58:59], v[96:97] op_sel_hi:[1,0]
	v_pk_mul_f32 v[52:53], v[52:53], v[96:97] op_sel_hi:[1,0]
	v_pk_mul_f32 v[48:49], v[48:49], v[96:97] op_sel_hi:[1,0]
	v_pk_mul_f32 v[44:45], v[44:45], v[96:97] op_sel_hi:[1,0]
	v_pk_mul_f32 v[40:41], v[40:41], v[96:97] op_sel_hi:[1,0]
	v_pk_mul_f32 v[38:39], v[38:39], v[96:97] op_sel_hi:[1,0]
	v_pk_mul_f32 v[112:113], v[116:117], v[96:97] op_sel_hi:[1,0]
	v_pk_mul_f32 v[32:33], v[32:33], v[96:97] op_sel_hi:[1,0]
	s_waitcnt vmcnt(0)
	v_pk_fma_f32 v[56:57], v[64:65], v[56:57], v[106:107]
	v_pk_fma_f32 v[58:59], v[66:67], v[34:35], v[108:109]
	global_store_dwordx4 v68, v[56:59], s[54:55] offset:1024
	global_load_dwordx4 v[64:67], v[72:73], off offset:2048
	global_load_dwordx4 v[106:109], v[74:75], off offset:2048
	v_pk_mul_f32 v[34:35], v[54:55], v[96:97] op_sel_hi:[1,0]
	s_waitcnt vmcnt(0)
	v_pk_fma_f32 v[52:53], v[64:65], v[52:53], v[106:107]
	v_pk_fma_f32 v[54:55], v[66:67], v[34:35], v[108:109]
	global_store_dwordx4 v68, v[52:55], s[54:55] offset:2048
	global_load_dwordx4 v[64:67], v[72:73], off offset:3072
	global_load_dwordx4 v[106:109], v[74:75], off offset:3072
	v_pk_mul_f32 v[34:35], v[50:51], v[96:97] op_sel_hi:[1,0]
	s_waitcnt vmcnt(0)
	v_pk_fma_f32 v[48:49], v[64:65], v[48:49], v[106:107]
	v_pk_fma_f32 v[50:51], v[66:67], v[34:35], v[108:109]
	global_store_dwordx4 v68, v[48:51], s[54:55] offset:3072
	global_load_dwordx4 v[64:67], v[78:79], off
	global_load_dwordx4 v[106:109], v[80:81], off
	v_lshl_add_u64 v[34:35], s[54:55], 0, v[68:69]
	v_add_co_u32_e32 v110, vcc, s58, v34
	s_waitcnt vmcnt(0)
	v_pk_fma_f32 v[44:45], v[64:65], v[44:45], v[106:107]
	v_addc_co_u32_e32 v111, vcc, 0, v35, vcc
	v_pk_mul_f32 v[34:35], v[46:47], v[96:97] op_sel_hi:[1,0]
	s_nop 0
	v_pk_fma_f32 v[46:47], v[66:67], v[34:35], v[108:109]
	global_store_dwordx4 v[110:111], v[44:47], off
	global_load_dwordx4 v[64:67], v[82:83], off
	global_load_dwordx4 v[106:109], v[84:85], off
	v_pk_mul_f32 v[34:35], v[42:43], v[96:97] op_sel_hi:[1,0]
	s_waitcnt vmcnt(0)
	v_pk_fma_f32 v[40:41], v[64:65], v[40:41], v[106:107]
	v_pk_fma_f32 v[42:43], v[66:67], v[34:35], v[108:109]
	global_store_dwordx4 v[110:111], v[40:43], off offset:1024
	global_load_dwordx4 v[64:67], v[86:87], off
	global_load_dwordx4 v[106:109], v[88:89], off
	v_pk_mul_f32 v[34:35], v[36:37], v[96:97] op_sel_hi:[1,0]
	v_lshl_add_u64 v[96:97], v[76:77], 0, s[34:35]
	s_mov_b32 s34, s4
	s_waitcnt vmcnt(0)
	v_pk_fma_f32 v[34:35], v[64:65], v[34:35], v[106:107]
	v_pk_fma_f32 v[36:37], v[66:67], v[38:39], v[108:109]
	global_store_dwordx4 v[110:111], v[34:37], off offset:2048
	global_load_dwordx4 v[64:67], v[90:91], off
	global_load_dwordx4 v[106:109], v[92:93], off
	v_lshl_add_u64 v[38:39], s[52:53], 0, v[68:69]
	v_add_co_u32_e32 v114, vcc, s59, v38
	s_waitcnt vmcnt(0)
	v_pk_fma_f32 v[64:65], v[64:65], v[32:33], v[106:107]
	v_pk_fma_f32 v[66:67], v[66:67], v[112:113], v[108:109]
	v_addc_co_u32_e32 v115, vcc, 0, v39, vcc
	global_store_dwordx4 v[110:111], v[64:67], off offset:3072
	global_load_dwordx4 v[106:109], v[114:115], off offset:-4096
	s_nop 0
	global_load_dwordx4 v[110:113], v68, s[52:53]
	v_lshl_add_u64 v[32:33], v[38:39], 0, s[10:11]
	s_waitcnt vmcnt(1)
	v_pk_add_f32 v[108:109], v[108:109], 1.0 op_sel_hi:[1,0]
	v_pk_add_f32 v[106:107], v[106:107], 1.0 op_sel_hi:[1,0]
	s_waitcnt vmcnt(0)
	v_pk_fma_f32 v[62:63], v[108:109], v[62:63], v[112:113]
	v_pk_fma_f32 v[60:61], v[106:107], v[60:61], v[110:111]
	v_bfe_u32 v105, v60, 16, 1
	v_bfe_u32 v106, v61, 16, 1
	v_add3_u32 v60, v60, v105, s77
	v_add3_u32 v61, v61, v106, s77
	v_lshrrev_b32_e32 v60, 16, v60
	s_nop 0
	v_and_or_b32 v60, v61, s78, v60
	v_cvt_pk_bf16_f32 v61, v62, v63
	global_store_dwordx2 v[96:97], v[60:61], off
	global_load_dwordx4 v[60:63], v[32:33], off offset:1024
	s_nop 0
	global_load_dwordx4 v[106:109], v68, s[52:53] offset:1024
	s_waitcnt vmcnt(1)
; __device__ __forceinline__ unsigned pk2(float lo, float hi) { return f2bf(lo) | (f2bf(hi) << 16); }
;     ...
;         if (do_mod) {
;             const float* sh = modl + mv * NMOD + shc * D; const float* sc = modl + mv * NMOD + scc * D;
; #pragma unroll
;             for (int j = 0; j < 8; ++j) { const f32x4 s1 = *(const f32x4*)(sc + lane * 4 + 256 * j), h1 = *(const f32x4*)(sh + lane * 4 + 256 * j);
;                 const f32x4 a = v[j] * (s1 + 1.f) + h1; u32x2 o; o.x = pk2(a.x, a.y); o.y = pk2(a.z, a.w);
;                 *(u32x2*)(aout + (size_t)m * D + lane * 4 + 256 * j) = o; }
;         }
	v_pk_add_f32 v[62:63], v[62:63], 1.0 op_sel_hi:[1,0]
	v_pk_add_f32 v[60:61], v[60:61], 1.0 op_sel_hi:[1,0]
	s_waitcnt vmcnt(0)
	v_pk_fma_f32 v[58:59], v[62:63], v[58:59], v[108:109]
	v_pk_fma_f32 v[56:57], v[60:61], v[56:57], v[106:107]
	s_nop 0
	s_nop 0
	v_cvt_pk_bf16_f32 v56, v56, v57
	v_cvt_pk_bf16_f32 v57, v58, v59
	global_store_dwordx2 v[96:97], v[56:57], off offset:512
	global_load_dwordx4 v[56:59], v[32:33], off offset:2048
	s_nop 0
	global_load_dwordx4 v[60:63], v68, s[52:53] offset:2048
	s_waitcnt vmcnt(1)
	v_pk_add_f32 v[58:59], v[58:59], 1.0 op_sel_hi:[1,0]
	v_pk_add_f32 v[56:57], v[56:57], 1.0 op_sel_hi:[1,0]
	s_waitcnt vmcnt(0)
	v_pk_fma_f32 v[54:55], v[58:59], v[54:55], v[62:63]
	v_pk_fma_f32 v[52:53], v[56:57], v[52:53], v[60:61]
	s_nop 0
	s_nop 0
	v_cvt_pk_bf16_f32 v52, v52, v53
	v_cvt_pk_bf16_f32 v53, v54, v55
	global_store_dwordx2 v[96:97], v[52:53], off offset:1024
	global_load_dwordx4 v[52:55], v[32:33], off offset:3072
	s_nop 0
	global_load_dwordx4 v[56:59], v68, s[52:53] offset:3072
	v_mov_b64_e32 v[62:63], v[2:3]
	v_mov_b64_e32 v[60:61], v[0:1]
	s_waitcnt vmcnt(1)
	v_pk_add_f32 v[32:33], v[54:55], 1.0 op_sel_hi:[1,0]
	v_pk_add_f32 v[52:53], v[52:53], 1.0 op_sel_hi:[1,0]
	s_waitcnt vmcnt(0)
	v_pk_fma_f32 v[32:33], v[32:33], v[50:51], v[58:59]
	v_pk_fma_f32 v[48:49], v[52:53], v[48:49], v[56:57]
	v_bfe_u32 v52, v32, 16, 1
	v_bfe_u32 v53, v33, 16, 1
	v_add3_u32 v32, v32, v52, s77
	v_add3_u32 v33, v33, v53, s77
	s_nop 0
	v_lshrrev_b32_e32 v50, 16, v32
	v_cvt_pk_bf16_f32 v32, v48, v49
	v_and_or_b32 v33, v33, s78, v50
	global_store_dwordx2 v[96:97], v[32:33], off offset:1536
	v_add_co_u32_e32 v32, vcc, s58, v38
	global_load_dwordx4 v[48:51], v[114:115], off
	s_nop 0
	v_addc_co_u32_e32 v33, vcc, 0, v39, vcc
	global_load_dwordx4 v[52:55], v[32:33], off
	v_mov_b64_e32 v[58:59], v[6:7]
	v_mov_b64_e32 v[56:57], v[4:5]
	s_andn2_b64 vcc, exec, s[30:31]
	s_waitcnt vmcnt(1)
	v_pk_add_f32 v[38:39], v[50:51], 1.0 op_sel_hi:[1,0]
	v_pk_add_f32 v[48:49], v[48:49], 1.0 op_sel_hi:[1,0]
	s_waitcnt vmcnt(0)
	v_pk_fma_f32 v[38:39], v[46:47], v[38:39], v[54:55]
	v_pk_fma_f32 v[44:45], v[44:45], v[48:49], v[52:53]
	v_bfe_u32 v48, v38, 16, 1
	v_bfe_u32 v49, v39, 16, 1
	v_add3_u32 v38, v38, v48, s77
	v_add3_u32 v39, v39, v49, s77
	v_lshrrev_b32_e32 v46, 16, v38
	v_cvt_pk_bf16_f32 v38, v44, v45
	v_and_or_b32 v39, v39, s78, v46
	global_store_dwordx2 v[96:97], v[38:39], off offset:2048
	global_load_dwordx4 v[44:47], v[114:115], off offset:1024
	global_load_dwordx4 v[48:51], v[32:33], off offset:1024
	v_mov_b64_e32 v[54:55], v[10:11]
	v_mov_b64_e32 v[52:53], v[8:9]
	s_waitcnt vmcnt(1)
	v_pk_add_f32 v[38:39], v[46:47], 1.0 op_sel_hi:[1,0]
	v_pk_add_f32 v[44:45], v[44:45], 1.0 op_sel_hi:[1,0]
	s_waitcnt vmcnt(0)
	v_pk_fma_f32 v[38:39], v[42:43], v[38:39], v[50:51]
	v_pk_fma_f32 v[40:41], v[40:41], v[44:45], v[48:49]
	v_bfe_u32 v44, v38, 16, 1
	v_bfe_u32 v45, v39, 16, 1
	v_add3_u32 v38, v38, v44, s77
	v_add3_u32 v39, v39, v45, s77
	s_nop 0
	v_lshrrev_b32_e32 v42, 16, v38
	v_cvt_pk_bf16_f32 v38, v40, v41
	v_and_or_b32 v39, v39, s78, v42
	global_store_dwordx2 v[96:97], v[38:39], off offset:2560
	global_load_dwordx4 v[38:41], v[114:115], off offset:2048
	s_nop 0
	global_load_dwordx4 v[42:45], v[32:33], off offset:2048
	v_mov_b64_e32 v[50:51], v[14:15]
	v_mov_b64_e32 v[48:49], v[12:13]
	s_waitcnt vmcnt(1)
	v_pk_add_f32 v[40:41], v[40:41], 1.0 op_sel_hi:[1,0]
	v_pk_add_f32 v[38:39], v[38:39], 1.0 op_sel_hi:[1,0]
	s_waitcnt vmcnt(0)
	v_pk_fma_f32 v[36:37], v[36:37], v[40:41], v[44:45]
	v_pk_fma_f32 v[34:35], v[34:35], v[38:39], v[42:43]
	v_cvt_pk_bf16_f32 v34, v34, v35
	v_cvt_pk_bf16_f32 v35, v36, v37
	global_store_dwordx2 v[96:97], v[34:35], off offset:3072
	global_load_dwordx4 v[106:109], v[114:115], off offset:3072
	global_load_dwordx4 v[110:113], v[32:33], off offset:3072
	v_mov_b64_e32 v[34:35], v[30:31]
	v_mov_b64_e32 v[38:39], v[26:27]
	v_mov_b64_e32 v[42:43], v[22:23]
	v_mov_b64_e32 v[46:47], v[18:19]
	v_mov_b64_e32 v[32:33], v[28:29]
	v_mov_b64_e32 v[36:37], v[24:25]
	v_mov_b64_e32 v[40:41], v[20:21]
	v_mov_b64_e32 v[44:45], v[16:17]
	s_waitcnt vmcnt(1)
	v_pk_add_f32 v[0:1], v[108:109], 1.0 op_sel_hi:[1,0]
	v_pk_add_f32 v[2:3], v[106:107], 1.0 op_sel_hi:[1,0]
	s_waitcnt vmcnt(0)
	v_pk_fma_f32 v[0:1], v[66:67], v[0:1], v[112:113]
	v_pk_fma_f32 v[2:3], v[64:65], v[2:3], v[110:111]
	v_bfe_u32 v6, v0, 16, 1
	v_bfe_u32 v4, v2, 16, 1
	v_bfe_u32 v5, v3, 16, 1
	v_bfe_u32 v7, v1, 16, 1
	v_add3_u32 v2, v2, v4, s77
	v_add3_u32 v0, v0, v6, s77
	v_add3_u32 v3, v3, v5, s77
	v_add3_u32 v1, v1, v7, s77
	v_lshrrev_b32_e32 v2, 16, v2
	v_lshrrev_b32_e32 v4, 16, v0
	v_and_or_b32 v0, v3, s78, v2
	v_and_or_b32 v1, v1, s78, v4
	global_store_dwordx2 v[96:97], v[0:1], off offset:3584
	s_cbranch_vccz .LBB0_1041

; #define LAS __attribute__((address_space(3)))
; #define LDS_WAIT() asm volatile("s_waitcnt lgkmcnt(0)" ::: "memory")
; __device__ __forceinline__ void transpose_item(const float* W, int K, int N, bf16* WT, int row_off, LAS float* scr, int item, int lane) {
;     const int nblk = N / 32, kb = item / nblk, nb = item % nblk, k0 = 64 * kb, n0 = 32 * nb;
; #pragma unroll 8
;     for (int i = 0; i < 32; ++i) { const int kk = 2 * i + (lane >> 5); scr[kk * 33 + (lane & 31)] = W[(size_t)(k0 + kk) * N + n0 + (lane & 31)]; }
;     LDS_WAIT(); asm volatile("" ::: "memory");
.LBB0_1048:
	s_lshl_b32 s2, s5, 1
	s_lshl_b32 s33, s8, 1
	v_or_b32_e32 v26, s33, v4
	s_add_i32 s48, s2, 4
	s_add_i32 s49, s33, 4
	s_add_i32 s52, s2, 8
	s_add_i32 s53, s33, 8
	s_add_i32 s54, s2, 12
	s_add_i32 s55, s33, 12
	s_add_i32 s56, s2, 16
	s_add_i32 s57, s33, 16
	s_add_i32 s58, s2, 20
	s_add_i32 s59, s33, 20
	s_add_i32 s60, s2, 24
	s_add_i32 s61, s33, 24
	s_add_i32 s62, s2, 28
	s_add_i32 s63, s33, 28
	v_or_b32_e32 v28, s2, v3
	v_mad_u64_u32 v[26:27], s[34:35], v26, s10, v[20:21]
	v_or_b32_e32 v32, s48, v3
	v_or_b32_e32 v30, s49, v4
	v_or_b32_e32 v36, s52, v3
	v_or_b32_e32 v34, s53, v4
	v_or_b32_e32 v40, s54, v3
	v_or_b32_e32 v38, s55, v4
	v_or_b32_e32 v44, s56, v3
	v_or_b32_e32 v42, s57, v4
	v_or_b32_e32 v48, s58, v3
	v_or_b32_e32 v46, s59, v4
	v_or_b32_e32 v52, s60, v3
	v_or_b32_e32 v50, s61, v4
	v_or_b32_e32 v56, s62, v3
	v_or_b32_e32 v54, s63, v4
	v_mad_u64_u32 v[28:29], s[34:35], v28, s10, v[20:21]
	v_mad_u64_u32 v[30:31], s[34:35], v30, s10, v[20:21]
	v_mad_u64_u32 v[32:33], s[34:35], v32, s10, v[20:21]
	v_mad_u64_u32 v[34:35], s[34:35], v34, s10, v[20:21]
	v_mad_u64_u32 v[36:37], s[34:35], v36, s10, v[20:21]
	v_mad_u64_u32 v[38:39], s[34:35], v38, s10, v[20:21]
	v_mad_u64_u32 v[40:41], s[34:35], v40, s10, v[20:21]
	v_mad_u64_u32 v[42:43], s[34:35], v42, s10, v[20:21]
	v_mad_u64_u32 v[44:45], s[34:35], v44, s10, v[20:21]
	v_mad_u64_u32 v[46:47], s[34:35], v46, s10, v[20:21]
	v_mad_u64_u32 v[48:49], s[34:35], v48, s10, v[20:21]
	v_mad_u64_u32 v[50:51], s[34:35], v50, s10, v[20:21]
	v_mad_u64_u32 v[52:53], s[34:35], v52, s10, v[20:21]
	v_mad_u64_u32 v[54:55], s[34:35], v54, s10, v[20:21]
	v_mad_u64_u32 v[56:57], s[34:35], v56, s10, v[20:21]
	global_load_dword v58, v[26:27], off
	global_load_dword v59, v[28:29], off
	global_load_dword v60, v[30:31], off
	global_load_dword v61, v[32:33], off
	global_load_dword v62, v[34:35], off
	global_load_dword v63, v[36:37], off
	global_load_dword v64, v[38:39], off
	global_load_dword v65, v[40:41], off
	global_load_dword v66, v[42:43], off
	global_load_dword v67, v[44:45], off
	global_load_dword v68, v[46:47], off
	global_load_dword v69, v[48:49], off
	global_load_dword v70, v[50:51], off
	global_load_dword v72, v[52:53], off
	global_load_dword v73, v[54:55], off
	global_load_dword v74, v[56:57], off
	v_or_b32_e32 v28, s2, v1
	v_or_b32_e32 v26, s33, v0
	s_add_i32 s8, s8, 16
	s_add_i32 s5, s5, 16
	s_add_i32 s9, s9, -16
	v_mad_u64_u32 v[26:27], s[34:35], v26, s7, v[6:7]
	v_mad_u64_u32 v[28:29], s[34:35], v28, s7, v[6:7]
	v_or_b32_e32 v27, s48, v1
	v_or_b32_e32 v29, s49, v0
	v_or_b32_e32 v36, s52, v1
	v_or_b32_e32 v34, s53, v0
	v_or_b32_e32 v40, s54, v1
	v_or_b32_e32 v38, s55, v0
	v_or_b32_e32 v44, s56, v1
	v_or_b32_e32 v42, s57, v0
	v_or_b32_e32 v48, s58, v1
	v_or_b32_e32 v46, s59, v0
	v_or_b32_e32 v52, s60, v1
	v_or_b32_e32 v50, s61, v0
	v_or_b32_e32 v56, s62, v1
	v_or_b32_e32 v54, s63, v0
	s_cmp_lg_u32 s9, 0
	v_mad_u64_u32 v[30:31], s[34:35], v29, s7, v[6:7]
	v_mad_u64_u32 v[32:33], s[34:35], v27, s7, v[6:7]
	v_mad_u64_u32 v[34:35], s[34:35], v34, s7, v[6:7]
	v_mad_u64_u32 v[36:37], s[34:35], v36, s7, v[6:7]
	v_mad_u64_u32 v[38:39], s[34:35], v38, s7, v[6:7]
	v_mad_u64_u32 v[40:41], s[34:35], v40, s7, v[6:7]
	v_mad_u64_u32 v[42:43], s[34:35], v42, s7, v[6:7]
	v_mad_u64_u32 v[44:45], s[34:35], v44, s7, v[6:7]
	v_mad_u64_u32 v[46:47], s[34:35], v46, s7, v[6:7]
	v_mad_u64_u32 v[48:49], s[34:35], v48, s7, v[6:7]
	v_mad_u64_u32 v[50:51], s[34:35], v50, s7, v[6:7]
	v_mad_u64_u32 v[52:53], s[34:35], v52, s7, v[6:7]
	v_mad_u64_u32 v[54:55], s[34:35], v54, s7, v[6:7]
	v_mad_u64_u32 v[56:57], s[34:35], v56, s7, v[6:7]
	s_waitcnt vmcnt(15)
	ds_write_b32 v26, v58
	s_waitcnt vmcnt(14)
	ds_write_b32 v28, v59
	s_waitcnt vmcnt(13)
	ds_write_b32 v30, v60
	s_waitcnt vmcnt(12)
	ds_write_b32 v32, v61
	s_waitcnt vmcnt(11)
	ds_write_b32 v34, v62
	s_waitcnt vmcnt(10)
	ds_write_b32 v36, v63
	s_waitcnt vmcnt(9)
	ds_write_b32 v38, v64
	s_waitcnt vmcnt(8)
	ds_write_b32 v40, v65
	s_waitcnt vmcnt(7)
	ds_write_b32 v42, v66
	s_waitcnt vmcnt(6)
	ds_write_b32 v44, v67
	s_waitcnt vmcnt(5)
	ds_write_b32 v46, v68
	s_waitcnt vmcnt(4)
	ds_write_b32 v48, v69
	s_waitcnt vmcnt(3)
	ds_write_b32 v50, v70
	s_waitcnt vmcnt(2)
	ds_write_b32 v52, v72
	s_waitcnt vmcnt(1)
	ds_write_b32 v54, v73
	s_waitcnt vmcnt(0)
	ds_write_b32 v56, v74
	s_cbranch_scc1 .LBB0_1048
; #define LAS __attribute__((address_space(3)))
; #define LDS_WAIT() asm volatile("s_waitcnt lgkmcnt(0)" ::: "memory")
; __device__ __forceinline__ unsigned pk2(float lo, float hi) { return f2bf(lo) | (f2bf(hi) << 16); }
; __device__ __forceinline__ void transpose_item(const float* W, int K, int N, bf16* WT, int row_off, LAS float* scr, int item, int lane) {
;     ...
;     const int c = lane & 7;
; #pragma unroll
;     for (int j = 0; j < 4; ++j) { const int n = (lane >> 3) + 8 * j; const LAS float* s = scr + (8 * c) * 33 + n;
;         u32x4 o; o.x = pk2(s[0 * 33], s[1 * 33]); o.y = pk2(s[2 * 33], s[3 * 33]); o.z = pk2(s[4 * 33], s[5 * 33]); o.w = pk2(s[6 * 33], s[7 * 33]);
;         *(u32x4*)(WT + (size_t)(row_off + n0 + n) * K + k0 + 8 * c) = o; }
;     LDS_WAIT(); asm volatile("" ::: "memory");
	s_waitcnt lgkmcnt(0)
	ds_read2_b32 v[20:21], v22 offset1:8
	ds_read2_b32 v[32:33], v22 offset0:33 offset1:41
	ds_read2_b32 v[34:35], v22 offset0:66 offset1:74
	ds_read2_b32 v[36:37], v22 offset0:99 offset1:107
	ds_read2_b32 v[38:39], v22 offset0:132 offset1:140
	ds_read2_b32 v[40:41], v22 offset0:165 offset1:173
	s_waitcnt lgkmcnt(5)
	s_waitcnt lgkmcnt(4)
	v_cvt_pk_bf16_f32 v26, v20, v32
	s_waitcnt lgkmcnt(3)
	s_waitcnt lgkmcnt(2)
	ds_read2_b32 v[42:43], v22 offset0:198 offset1:206
	ds_read2_b32 v[44:45], v22 offset0:231 offset1:239
	v_cvt_pk_bf16_f32 v27, v34, v36
	s_waitcnt lgkmcnt(3)
	s_waitcnt lgkmcnt(2)
	v_cvt_pk_bf16_f32 v28, v38, v40
	s_waitcnt lgkmcnt(1)
	s_waitcnt lgkmcnt(0)
	s_nop 0
	v_or_b32_e32 v46, s4, v7
	s_lshl_b32 s0, s0, 1
	v_cvt_pk_bf16_f32 v29, v42, v44
	v_ashrrev_i32_e32 v47, 31, v46
	v_bfe_u32 v3, v21, 16, 1
	v_lshl_add_u64 v[30:31], v[8:9], 0, s[0:1]
	v_lshlrev_b64 v[46:47], 8, v[46:47]
	v_add3_u32 v3, v21, v3, s11
	v_bfe_u32 v4, v33, 16, 1
	v_lshl_add_u64 v[46:47], v[30:31], 0, v[46:47]
	v_lshrrev_b32_e32 v3, 16, v3
	v_add3_u32 v4, v33, v4, s11
	global_store_dwordx4 v[46:47], v[26:29], off
	v_or_b32_e32 v20, s4, v23
	v_ashrrev_i32_e32 v21, 31, v20
	v_and_or_b32 v26, v4, s28, v3
	s_nop 0
	s_nop 0
	s_nop 0
	v_cvt_pk_bf16_f32 v27, v35, v37
	v_cvt_pk_bf16_f32 v28, v39, v41
	s_nop 0
	s_nop 0
	v_lshlrev_b64 v[20:21], 8, v[20:21]
	v_cvt_pk_bf16_f32 v29, v43, v45
	ds_read2_b32 v[32:33], v22 offset0:16 offset1:24
	v_lshl_add_u64 v[20:21], v[30:31], 0, v[20:21]
	global_store_dwordx4 v[20:21], v[26:29], off
	ds_read2_b32 v[20:21], v22 offset0:49 offset1:57
	ds_read2_b32 v[34:35], v22 offset0:82 offset1:90
	ds_read2_b32 v[36:37], v22 offset0:115 offset1:123
	s_waitcnt lgkmcnt(3)
	s_nop 0
	s_nop 0
	s_waitcnt lgkmcnt(2)
	ds_read2_b32 v[38:39], v22 offset0:148 offset1:156
	ds_read2_b32 v[40:41], v22 offset0:181 offset1:189
	v_cvt_pk_bf16_f32 v26, v32, v20
	s_waitcnt lgkmcnt(3)
	s_waitcnt lgkmcnt(2)
	ds_read2_b32 v[42:43], v22 offset0:214 offset1:222
	ds_read2_b32 v[44:45], v22 offset0:247 offset1:255
	v_cvt_pk_bf16_f32 v27, v34, v36
	s_waitcnt lgkmcnt(3)
	s_waitcnt lgkmcnt(2)
	v_cvt_pk_bf16_f32 v28, v38, v40
	s_waitcnt lgkmcnt(1)
	s_waitcnt lgkmcnt(0)
	v_or_b32_e32 v46, s4, v24
	v_cvt_pk_bf16_f32 v29, v42, v44
	v_ashrrev_i32_e32 v47, 31, v46
	v_bfe_u32 v3, v33, 16, 1
	v_lshlrev_b64 v[46:47], 8, v[46:47]
	v_add3_u32 v3, v33, v3, s11
	v_bfe_u32 v4, v21, 16, 1
	v_lshl_add_u64 v[46:47], v[30:31], 0, v[46:47]
	v_lshrrev_b32_e32 v3, 16, v3
	v_add3_u32 v4, v21, v4, s11
	global_store_dwordx4 v[46:47], v[26:29], off
	v_or_b32_e32 v20, s4, v25
	v_ashrrev_i32_e32 v21, 31, v20
	v_and_or_b32 v26, v4, s28, v3
	s_nop 0
	s_nop 0
	s_nop 0
	v_cvt_pk_bf16_f32 v27, v35, v37
	v_cvt_pk_bf16_f32 v28, v39, v41
	v_bfe_u32 v3, v43, 16, 1
	v_add3_u32 v3, v43, v3, s11
	v_bfe_u32 v4, v45, 16, 1
	v_lshrrev_b32_e32 v3, 16, v3
	v_add3_u32 v4, v45, v4, s11
	v_lshlrev_b64 v[20:21], 8, v[20:21]
	v_and_or_b32 v29, v4, s28, v3
	v_lshl_add_u64 v[20:21], v[30:31], 0, v[20:21]
	global_store_dwordx4 v[20:21], v[26:29], off
	s_waitcnt lgkmcnt(0)
	s_mov_b64 s[4:5], 0

; #define LAS __attribute__((address_space(3)))
; #define LDS_WAIT() asm volatile("s_waitcnt lgkmcnt(0)" ::: "memory")
; __device__ __forceinline__ void transpose_item(const float* W, int K, int N, bf16* WT, int row_off, LAS float* scr, int item, int lane) {
;     const int nblk = N / 32, kb = item / nblk, nb = item % nblk, k0 = 64 * kb, n0 = 32 * nb;
; #pragma unroll 8
;     for (int i = 0; i < 32; ++i) { const int kk = 2 * i + (lane >> 5); scr[kk * 33 + (lane & 31)] = W[(size_t)(k0 + kk) * N + n0 + (lane & 31)]; }
;     LDS_WAIT(); asm volatile("" ::: "memory");
.LBB0_1052:
	s_lshl_b32 s2, s5, 1
	s_lshl_b32 s34, s0, 1
	v_or_b32_e32 v3, s2, v1
	v_or_b32_e32 v4, s34, v0
	s_add_i32 s48, s2, 4
	s_add_i32 s49, s34, 4
	s_add_i32 s52, s2, 8
	s_add_i32 s53, s34, 8
	s_add_i32 s54, s2, 12
	s_add_i32 s55, s34, 12
	s_add_i32 s56, s2, 16
	s_add_i32 s57, s34, 16
	s_add_i32 s58, s2, 20
	s_add_i32 s59, s34, 20
	s_add_i32 s60, s2, 24
	s_add_i32 s61, s34, 24
	s_add_i32 s2, s2, 28
	s_add_i32 s62, s34, 28
	v_mad_u64_u32 v[26:27], s[34:35], v4, s10, v[20:21]
	v_or_b32_e32 v58, s48, v1
	v_or_b32_e32 v59, s49, v0
	v_or_b32_e32 v60, s52, v1
	v_or_b32_e32 v61, s53, v0
	v_or_b32_e32 v62, s54, v1
	v_or_b32_e32 v63, s55, v0
	v_or_b32_e32 v64, s56, v1
	v_or_b32_e32 v65, s57, v0
	v_or_b32_e32 v66, s58, v1
	v_or_b32_e32 v67, s59, v0
	v_or_b32_e32 v68, s60, v1
	v_or_b32_e32 v69, s61, v0
	v_or_b32_e32 v70, s2, v1
	v_or_b32_e32 v72, s62, v0
	v_mad_u64_u32 v[28:29], s[34:35], v3, s10, v[20:21]
	v_mad_u64_u32 v[30:31], s[34:35], v59, s10, v[20:21]
	v_mad_u64_u32 v[32:33], s[34:35], v58, s10, v[20:21]
	v_mad_u64_u32 v[34:35], s[34:35], v61, s10, v[20:21]
	v_mad_u64_u32 v[36:37], s[34:35], v60, s10, v[20:21]
	v_mad_u64_u32 v[38:39], s[34:35], v63, s10, v[20:21]
	v_mad_u64_u32 v[40:41], s[34:35], v62, s10, v[20:21]
	v_mad_u64_u32 v[42:43], s[34:35], v65, s10, v[20:21]
	v_mad_u64_u32 v[44:45], s[34:35], v64, s10, v[20:21]
	v_mad_u64_u32 v[46:47], s[34:35], v67, s10, v[20:21]
	v_mad_u64_u32 v[48:49], s[34:35], v66, s10, v[20:21]
	v_mad_u64_u32 v[50:51], s[34:35], v69, s10, v[20:21]
	v_mad_u64_u32 v[52:53], s[34:35], v68, s10, v[20:21]
	v_mad_u64_u32 v[54:55], s[34:35], v72, s10, v[20:21]
	v_mad_u64_u32 v[56:57], s[34:35], v70, s10, v[20:21]
	global_load_dword v73, v[26:27], off
	global_load_dword v74, v[28:29], off
	global_load_dword v75, v[30:31], off
	global_load_dword v76, v[32:33], off
	global_load_dword v77, v[34:35], off
	global_load_dword v78, v[36:37], off
	global_load_dword v79, v[38:39], off
	global_load_dword v80, v[40:41], off
	global_load_dword v81, v[42:43], off
	global_load_dword v82, v[44:45], off
	global_load_dword v83, v[46:47], off
	global_load_dword v84, v[48:49], off
	global_load_dword v85, v[50:51], off
	global_load_dword v86, v[52:53], off
	global_load_dword v87, v[54:55], off
	global_load_dword v88, v[56:57], off
	s_add_i32 s0, s0, 16
	s_add_i32 s5, s5, 16
	s_add_i32 s33, s33, -16
	v_mad_u64_u32 v[26:27], s[34:35], v4, s7, v[6:7]
	s_cmp_lg_u32 s33, 0
	v_mad_u64_u32 v[28:29], s[34:35], v3, s7, v[6:7]
	v_mad_u64_u32 v[30:31], s[34:35], v59, s7, v[6:7]
	v_mad_u64_u32 v[32:33], s[34:35], v58, s7, v[6:7]
	v_mad_u64_u32 v[34:35], s[34:35], v61, s7, v[6:7]
	v_mad_u64_u32 v[36:37], s[34:35], v60, s7, v[6:7]
	v_mad_u64_u32 v[38:39], s[34:35], v63, s7, v[6:7]
	v_mad_u64_u32 v[40:41], s[34:35], v62, s7, v[6:7]
	v_mad_u64_u32 v[42:43], s[34:35], v65, s7, v[6:7]
	v_mad_u64_u32 v[44:45], s[34:35], v64, s7, v[6:7]
	v_mad_u64_u32 v[46:47], s[34:35], v67, s7, v[6:7]
	v_mad_u64_u32 v[48:49], s[34:35], v66, s7, v[6:7]
	v_mad_u64_u32 v[50:51], s[34:35], v69, s7, v[6:7]
	v_mad_u64_u32 v[52:53], s[34:35], v68, s7, v[6:7]
	v_mad_u64_u32 v[54:55], s[34:35], v72, s7, v[6:7]
	v_mad_u64_u32 v[56:57], s[34:35], v70, s7, v[6:7]
	s_waitcnt vmcnt(15)
	ds_write_b32 v26, v73
	s_waitcnt vmcnt(14)
	ds_write_b32 v28, v74
	s_waitcnt vmcnt(13)
	ds_write_b32 v30, v75
	s_waitcnt vmcnt(12)
	ds_write_b32 v32, v76
	s_waitcnt vmcnt(11)
	ds_write_b32 v34, v77
	s_waitcnt vmcnt(10)
	ds_write_b32 v36, v78
	s_waitcnt vmcnt(9)
	ds_write_b32 v38, v79
	s_waitcnt vmcnt(8)
	ds_write_b32 v40, v80
	s_waitcnt vmcnt(7)
	ds_write_b32 v42, v81
	s_waitcnt vmcnt(6)
	ds_write_b32 v44, v82
	s_waitcnt vmcnt(5)
	ds_write_b32 v46, v83
	s_waitcnt vmcnt(4)
	ds_write_b32 v48, v84
	s_waitcnt vmcnt(3)
	ds_write_b32 v50, v85
	s_waitcnt vmcnt(2)
	ds_write_b32 v52, v86
	s_waitcnt vmcnt(1)
	ds_write_b32 v54, v87
	s_waitcnt vmcnt(0)
	ds_write_b32 v56, v88
	s_cbranch_scc1 .LBB0_1052
; #define LAS __attribute__((address_space(3)))
; #define LDS_WAIT() asm volatile("s_waitcnt lgkmcnt(0)" ::: "memory")
; __device__ __forceinline__ unsigned pk2(float lo, float hi) { return f2bf(lo) | (f2bf(hi) << 16); }
; __device__ __forceinline__ void transpose_item(const float* W, int K, int N, bf16* WT, int row_off, LAS float* scr, int item, int lane) {
;     ...
;     const int c = lane & 7;
; #pragma unroll
;     for (int j = 0; j < 4; ++j) { const int n = (lane >> 3) + 8 * j; const LAS float* s = scr + (8 * c) * 33 + n;
;         u32x4 o; o.x = pk2(s[0 * 33], s[1 * 33]); o.y = pk2(s[2 * 33], s[3 * 33]); o.z = pk2(s[4 * 33], s[5 * 33]); o.w = pk2(s[6 * 33], s[7 * 33]);
;         *(u32x4*)(WT + (size_t)(row_off + n0 + n) * K + k0 + 8 * c) = o; }
;     LDS_WAIT(); asm volatile("" ::: "memory");
	s_waitcnt lgkmcnt(0)
	ds_read2_b32 v[20:21], v22 offset1:8
	ds_read2_b32 v[32:33], v22 offset0:33 offset1:41
	ds_read2_b32 v[34:35], v22 offset0:66 offset1:74
	ds_read2_b32 v[36:37], v22 offset0:99 offset1:107
	ds_read2_b32 v[38:39], v22 offset0:132 offset1:140
	s_waitcnt lgkmcnt(4)
	s_waitcnt lgkmcnt(3)
	ds_read2_b32 v[40:41], v22 offset0:165 offset1:173
	v_cvt_pk_bf16_f32 v26, v20, v32
	s_waitcnt lgkmcnt(3)
	s_waitcnt lgkmcnt(2)
	ds_read2_b32 v[42:43], v22 offset0:198 offset1:206
	ds_read2_b32 v[44:45], v22 offset0:231 offset1:239
	v_cvt_pk_bf16_f32 v27, v34, v36
	s_waitcnt lgkmcnt(3)
	s_waitcnt lgkmcnt(2)
	v_cvt_pk_bf16_f32 v28, v38, v40
	s_waitcnt lgkmcnt(1)
	s_nop 0
	s_nop 0
	s_waitcnt lgkmcnt(0)
	s_nop 0
	s_and_b64 s[8:9], s[8:9], exec
	s_nop 0
	s_nop 0
	v_or_b32_e32 v46, s4, v7
	s_cselect_b32 s0, 0x18000, 0
	v_cvt_pk_bf16_f32 v29, v42, v44
	v_ashrrev_i32_e32 v47, 31, v46
	v_bfe_u32 v3, v21, 16, 1
	v_lshl_add_u64 v[30:31], v[10:11], 0, s[0:1]
	v_lshlrev_b64 v[46:47], 7, v[46:47]
	v_add3_u32 v3, v21, v3, s11
	v_bfe_u32 v4, v33, 16, 1
	v_lshl_add_u64 v[46:47], v[30:31], 0, v[46:47]
	v_lshrrev_b32_e32 v3, 16, v3
	v_add3_u32 v4, v33, v4, s11
	global_store_dwordx4 v[46:47], v[26:29], off
	v_or_b32_e32 v20, s4, v23
	v_ashrrev_i32_e32 v21, 31, v20
	v_and_or_b32 v26, v4, s28, v3
	s_nop 0
	s_nop 0
	s_nop 0
	v_cvt_pk_bf16_f32 v27, v35, v37
	v_cvt_pk_bf16_f32 v28, v39, v41
	s_nop 0
	s_nop 0
	v_lshlrev_b64 v[20:21], 7, v[20:21]
	v_cvt_pk_bf16_f32 v29, v43, v45
	ds_read2_b32 v[32:33], v22 offset0:16 offset1:24
	v_lshl_add_u64 v[20:21], v[30:31], 0, v[20:21]
	global_store_dwordx4 v[20:21], v[26:29], off
	ds_read2_b32 v[20:21], v22 offset0:49 offset1:57
	ds_read2_b32 v[34:35], v22 offset0:82 offset1:90
	ds_read2_b32 v[36:37], v22 offset0:115 offset1:123
	s_waitcnt lgkmcnt(3)
	s_nop 0
	s_nop 0
	s_waitcnt lgkmcnt(2)
	ds_read2_b32 v[38:39], v22 offset0:148 offset1:156
	ds_read2_b32 v[40:41], v22 offset0:181 offset1:189
	v_cvt_pk_bf16_f32 v26, v32, v20
	s_waitcnt lgkmcnt(3)
	s_waitcnt lgkmcnt(2)
	ds_read2_b32 v[42:43], v22 offset0:214 offset1:222
	ds_read2_b32 v[44:45], v22 offset0:247 offset1:255
	v_cvt_pk_bf16_f32 v27, v34, v36
	s_waitcnt lgkmcnt(3)
	s_waitcnt lgkmcnt(2)
	v_cvt_pk_bf16_f32 v28, v38, v40
	s_waitcnt lgkmcnt(1)
	s_waitcnt lgkmcnt(0)
	v_or_b32_e32 v46, s4, v24
	v_cvt_pk_bf16_f32 v29, v42, v44
	v_ashrrev_i32_e32 v47, 31, v46
	v_bfe_u32 v3, v33, 16, 1
	v_lshlrev_b64 v[46:47], 7, v[46:47]
	v_add3_u32 v3, v33, v3, s11
	v_bfe_u32 v4, v21, 16, 1
	v_lshl_add_u64 v[46:47], v[30:31], 0, v[46:47]
	v_lshrrev_b32_e32 v3, 16, v3
	v_add3_u32 v4, v21, v4, s11
	global_store_dwordx4 v[46:47], v[26:29], off
	v_or_b32_e32 v20, s4, v25
	v_ashrrev_i32_e32 v21, 31, v20
	v_and_or_b32 v26, v4, s28, v3
	s_nop 0
	s_nop 0
	s_nop 0
	v_cvt_pk_bf16_f32 v27, v35, v37
	v_cvt_pk_bf16_f32 v28, v39, v41
	v_bfe_u32 v3, v43, 16, 1
	v_add3_u32 v3, v43, v3, s11
	v_bfe_u32 v4, v45, 16, 1
	v_lshrrev_b32_e32 v3, 16, v3
	v_add3_u32 v4, v45, v4, s11
	v_lshlrev_b64 v[20:21], 7, v[20:21]
	v_and_or_b32 v29, v4, s28, v3
	v_lshl_add_u64 v[20:21], v[30:31], 0, v[20:21]
	global_store_dwordx4 v[20:21], v[26:29], off
	s_waitcnt lgkmcnt(0)

; #define LAS __attribute__((address_space(3)))
; #define LDS_WAIT() asm volatile("s_waitcnt lgkmcnt(0)" ::: "memory")
; __device__ __forceinline__ void transpose_item(const float* W, int K, int N, bf16* WT, int row_off, LAS float* scr, int item, int lane) {
;     const int nblk = N / 32, kb = item / nblk, nb = item % nblk, k0 = 64 * kb, n0 = 32 * nb;
; #pragma unroll 8
;     for (int i = 0; i < 32; ++i) { const int kk = 2 * i + (lane >> 5); scr[kk * 33 + (lane & 31)] = W[(size_t)(k0 + kk) * N + n0 + (lane & 31)]; }
;     LDS_WAIT(); asm volatile("" ::: "memory");
.LBB0_1057:
	s_lshl_b32 s2, s5, 1
	s_lshl_b32 s34, s0, 1
	v_or_b32_e32 v3, s2, v1
	v_or_b32_e32 v4, s34, v0
	s_add_i32 s48, s2, 4
	s_add_i32 s49, s34, 4
	s_add_i32 s52, s2, 8
	s_add_i32 s53, s34, 8
	s_add_i32 s54, s2, 12
	s_add_i32 s55, s34, 12
	s_add_i32 s56, s2, 16
	s_add_i32 s57, s34, 16
	s_add_i32 s58, s2, 20
	s_add_i32 s59, s34, 20
	s_add_i32 s60, s2, 24
	s_add_i32 s61, s34, 24
	s_add_i32 s2, s2, 28
	s_add_i32 s62, s34, 28
	v_mad_u64_u32 v[26:27], s[34:35], v4, s10, v[20:21]
	v_or_b32_e32 v58, s48, v1
	v_or_b32_e32 v59, s49, v0
	v_or_b32_e32 v60, s52, v1
	v_or_b32_e32 v61, s53, v0
	v_or_b32_e32 v62, s54, v1
	v_or_b32_e32 v63, s55, v0
	v_or_b32_e32 v64, s56, v1
	v_or_b32_e32 v65, s57, v0
	v_or_b32_e32 v66, s58, v1
	v_or_b32_e32 v67, s59, v0
	v_or_b32_e32 v68, s60, v1
	v_or_b32_e32 v69, s61, v0
	v_or_b32_e32 v70, s2, v1
	v_or_b32_e32 v72, s62, v0
	v_mad_u64_u32 v[28:29], s[34:35], v3, s10, v[20:21]
	v_mad_u64_u32 v[30:31], s[34:35], v59, s10, v[20:21]
	v_mad_u64_u32 v[32:33], s[34:35], v58, s10, v[20:21]
	v_mad_u64_u32 v[34:35], s[34:35], v61, s10, v[20:21]
	v_mad_u64_u32 v[36:37], s[34:35], v60, s10, v[20:21]
	v_mad_u64_u32 v[38:39], s[34:35], v63, s10, v[20:21]
	v_mad_u64_u32 v[40:41], s[34:35], v62, s10, v[20:21]
	v_mad_u64_u32 v[42:43], s[34:35], v65, s10, v[20:21]
	v_mad_u64_u32 v[44:45], s[34:35], v64, s10, v[20:21]
	v_mad_u64_u32 v[46:47], s[34:35], v67, s10, v[20:21]
	v_mad_u64_u32 v[48:49], s[34:35], v66, s10, v[20:21]
	v_mad_u64_u32 v[50:51], s[34:35], v69, s10, v[20:21]
	v_mad_u64_u32 v[52:53], s[34:35], v68, s10, v[20:21]
	v_mad_u64_u32 v[54:55], s[34:35], v72, s10, v[20:21]
	v_mad_u64_u32 v[56:57], s[34:35], v70, s10, v[20:21]
	global_load_dword v73, v[26:27], off
	global_load_dword v74, v[28:29], off
	global_load_dword v75, v[30:31], off
	global_load_dword v76, v[32:33], off
	global_load_dword v77, v[34:35], off
	global_load_dword v78, v[36:37], off
	global_load_dword v79, v[38:39], off
	global_load_dword v80, v[40:41], off
	global_load_dword v81, v[42:43], off
	global_load_dword v82, v[44:45], off
	global_load_dword v83, v[46:47], off
	global_load_dword v84, v[48:49], off
	global_load_dword v85, v[50:51], off
	global_load_dword v86, v[52:53], off
	global_load_dword v87, v[54:55], off
	global_load_dword v88, v[56:57], off
	s_add_i32 s0, s0, 16
	s_add_i32 s5, s5, 16
	s_add_i32 s33, s33, -16
	v_mad_u64_u32 v[26:27], s[34:35], v4, s7, v[6:7]
	s_cmp_lg_u32 s33, 0
	v_mad_u64_u32 v[28:29], s[34:35], v3, s7, v[6:7]
	v_mad_u64_u32 v[30:31], s[34:35], v59, s7, v[6:7]
	v_mad_u64_u32 v[32:33], s[34:35], v58, s7, v[6:7]
	v_mad_u64_u32 v[34:35], s[34:35], v61, s7, v[6:7]
	v_mad_u64_u32 v[36:37], s[34:35], v60, s7, v[6:7]
	v_mad_u64_u32 v[38:39], s[34:35], v63, s7, v[6:7]
	v_mad_u64_u32 v[40:41], s[34:35], v62, s7, v[6:7]
	v_mad_u64_u32 v[42:43], s[34:35], v65, s7, v[6:7]
	v_mad_u64_u32 v[44:45], s[34:35], v64, s7, v[6:7]
	v_mad_u64_u32 v[46:47], s[34:35], v67, s7, v[6:7]
	v_mad_u64_u32 v[48:49], s[34:35], v66, s7, v[6:7]
	v_mad_u64_u32 v[50:51], s[34:35], v69, s7, v[6:7]
	v_mad_u64_u32 v[52:53], s[34:35], v68, s7, v[6:7]
	v_mad_u64_u32 v[54:55], s[34:35], v72, s7, v[6:7]
	v_mad_u64_u32 v[56:57], s[34:35], v70, s7, v[6:7]
	s_waitcnt vmcnt(15)
	ds_write_b32 v26, v73
	s_waitcnt vmcnt(14)
	ds_write_b32 v28, v74
	s_waitcnt vmcnt(13)
	ds_write_b32 v30, v75
	s_waitcnt vmcnt(12)
	ds_write_b32 v32, v76
	s_waitcnt vmcnt(11)
	ds_write_b32 v34, v77
	s_waitcnt vmcnt(10)
	ds_write_b32 v36, v78
	s_waitcnt vmcnt(9)
	ds_write_b32 v38, v79
	s_waitcnt vmcnt(8)
	ds_write_b32 v40, v80
	s_waitcnt vmcnt(7)
	ds_write_b32 v42, v81
	s_waitcnt vmcnt(6)
	ds_write_b32 v44, v82
	s_waitcnt vmcnt(5)
	ds_write_b32 v46, v83
	s_waitcnt vmcnt(4)
	ds_write_b32 v48, v84
	s_waitcnt vmcnt(3)
	ds_write_b32 v50, v85
	s_waitcnt vmcnt(2)
	ds_write_b32 v52, v86
	s_waitcnt vmcnt(1)
	ds_write_b32 v54, v87
	s_waitcnt vmcnt(0)
	ds_write_b32 v56, v88
	s_cbranch_scc1 .LBB0_1057
; #define LAS __attribute__((address_space(3)))
; #define LDS_WAIT() asm volatile("s_waitcnt lgkmcnt(0)" ::: "memory")
; __device__ __forceinline__ unsigned pk2(float lo, float hi) { return f2bf(lo) | (f2bf(hi) << 16); }
; __device__ __forceinline__ void transpose_item(const float* W, int K, int N, bf16* WT, int row_off, LAS float* scr, int item, int lane) {
;     ...
;     LDS_WAIT(); asm volatile("" ::: "memory");
;     const int c = lane & 7;
; #pragma unroll
;     for (int j = 0; j < 4; ++j) { const int n = (lane >> 3) + 8 * j; const LAS float* s = scr + (8 * c) * 33 + n;
;         u32x4 o; o.x = pk2(s[0 * 33], s[1 * 33]); o.y = pk2(s[2 * 33], s[3 * 33]); o.z = pk2(s[4 * 33], s[5 * 33]); o.w = pk2(s[6 * 33], s[7 * 33]);
;         *(u32x4*)(WT + (size_t)(row_off + n0 + n) * K + k0 + 8 * c) = o; }
;     LDS_WAIT(); asm volatile("" ::: "memory");
	s_waitcnt lgkmcnt(0)
	ds_read2_b32 v[20:21], v22 offset1:8
	ds_read2_b32 v[32:33], v22 offset0:33 offset1:41
	ds_read2_b32 v[34:35], v22 offset0:66 offset1:74
	ds_read2_b32 v[36:37], v22 offset0:99 offset1:107
	ds_read2_b32 v[38:39], v22 offset0:132 offset1:140
	s_waitcnt lgkmcnt(4)
	s_waitcnt lgkmcnt(3)
	ds_read2_b32 v[40:41], v22 offset0:165 offset1:173
	v_cvt_pk_bf16_f32 v26, v20, v32
	s_waitcnt lgkmcnt(3)
	s_waitcnt lgkmcnt(2)
	ds_read2_b32 v[42:43], v22 offset0:198 offset1:206
	ds_read2_b32 v[44:45], v22 offset0:231 offset1:239
	v_cvt_pk_bf16_f32 v27, v34, v36
	s_waitcnt lgkmcnt(3)
	s_waitcnt lgkmcnt(2)
	v_cvt_pk_bf16_f32 v28, v38, v40
	s_waitcnt lgkmcnt(1)
	s_nop 0
	s_nop 0
	s_waitcnt lgkmcnt(0)
	s_nop 0
	s_and_b64 s[8:9], s[8:9], exec
	s_nop 0
	s_nop 0
	v_or_b32_e32 v46, s4, v7
	s_cselect_b32 s0, 0x18000, 0
	v_cvt_pk_bf16_f32 v29, v42, v44
	v_ashrrev_i32_e32 v47, 31, v46
	v_bfe_u32 v3, v21, 16, 1
	v_lshl_add_u64 v[30:31], v[12:13], 0, s[0:1]
	v_lshlrev_b64 v[46:47], 7, v[46:47]
	v_add3_u32 v3, v21, v3, s11
	v_bfe_u32 v4, v33, 16, 1
	v_lshl_add_u64 v[46:47], v[30:31], 0, v[46:47]
	v_lshrrev_b32_e32 v3, 16, v3
	v_add3_u32 v4, v33, v4, s11
	global_store_dwordx4 v[46:47], v[26:29], off
	v_or_b32_e32 v20, s4, v23
	v_ashrrev_i32_e32 v21, 31, v20
	v_and_or_b32 v26, v4, s28, v3
	s_nop 0
	s_nop 0
	s_nop 0
	v_cvt_pk_bf16_f32 v27, v35, v37
	v_cvt_pk_bf16_f32 v28, v39, v41
	s_nop 0
	s_nop 0
	v_lshlrev_b64 v[20:21], 7, v[20:21]
	v_cvt_pk_bf16_f32 v29, v43, v45
	ds_read2_b32 v[32:33], v22 offset0:16 offset1:24
	v_lshl_add_u64 v[20:21], v[30:31], 0, v[20:21]
	global_store_dwordx4 v[20:21], v[26:29], off
	ds_read2_b32 v[20:21], v22 offset0:49 offset1:57
	ds_read2_b32 v[34:35], v22 offset0:82 offset1:90
	ds_read2_b32 v[36:37], v22 offset0:115 offset1:123
	s_waitcnt lgkmcnt(3)
	s_nop 0
	s_nop 0
	s_waitcnt lgkmcnt(2)
	ds_read2_b32 v[38:39], v22 offset0:148 offset1:156
	ds_read2_b32 v[40:41], v22 offset0:181 offset1:189
	v_cvt_pk_bf16_f32 v26, v32, v20
	s_waitcnt lgkmcnt(3)
	s_waitcnt lgkmcnt(2)
	ds_read2_b32 v[42:43], v22 offset0:214 offset1:222
	ds_read2_b32 v[44:45], v22 offset0:247 offset1:255
	v_cvt_pk_bf16_f32 v27, v34, v36
	s_waitcnt lgkmcnt(3)
	s_waitcnt lgkmcnt(2)
	v_cvt_pk_bf16_f32 v28, v38, v40
	s_waitcnt lgkmcnt(1)
	s_waitcnt lgkmcnt(0)
	v_or_b32_e32 v46, s4, v24
	v_cvt_pk_bf16_f32 v29, v42, v44
	v_ashrrev_i32_e32 v47, 31, v46
	v_bfe_u32 v3, v33, 16, 1
	v_lshlrev_b64 v[46:47], 7, v[46:47]
	v_add3_u32 v3, v33, v3, s11
	v_bfe_u32 v4, v21, 16, 1
	v_lshl_add_u64 v[46:47], v[30:31], 0, v[46:47]
	v_lshrrev_b32_e32 v3, 16, v3
	v_add3_u32 v4, v21, v4, s11
	global_store_dwordx4 v[46:47], v[26:29], off
	v_or_b32_e32 v20, s4, v25
	v_ashrrev_i32_e32 v21, 31, v20
	v_and_or_b32 v26, v4, s28, v3
	s_nop 0
	s_nop 0
	s_nop 0
	v_cvt_pk_bf16_f32 v27, v35, v37
	v_cvt_pk_bf16_f32 v28, v39, v41
	v_bfe_u32 v3, v43, 16, 1
	v_add3_u32 v3, v43, v3, s11
	v_bfe_u32 v4, v45, 16, 1
	v_lshrrev_b32_e32 v3, 16, v3
	v_add3_u32 v4, v45, v4, s11
	v_lshlrev_b64 v[20:21], 7, v[20:21]
	v_and_or_b32 v29, v4, s28, v3
	v_lshl_add_u64 v[20:21], v[30:31], 0, v[20:21]
	global_store_dwordx4 v[20:21], v[26:29], off
	s_waitcnt lgkmcnt(0)

; __device__ __forceinline__ void transpose_item(const float* W, int K, int N, bf16* WT, int row_off, LAS float* scr, int item, int lane) {
;     ...
; #pragma unroll 8
;     for (int i = 0; i < 32; ++i) { const int kk = 2 * i + (lane >> 5); scr[kk * 33 + (lane & 31)] = W[(size_t)(k0 + kk) * N + n0 + (lane & 31)]; }
.LBB0_1062:
	s_lshl_b32 s2, s0, 1
	s_lshl_b32 s33, s5, 1
	v_or_b32_e32 v26, s33, v4
	s_add_i32 s48, s2, 4
	s_add_i32 s49, s33, 4
	s_add_i32 s52, s2, 8
	s_add_i32 s53, s33, 8
	s_add_i32 s54, s2, 12
	s_add_i32 s55, s33, 12
	s_add_i32 s56, s2, 16
	s_add_i32 s57, s33, 16
	s_add_i32 s58, s2, 20
	s_add_i32 s59, s33, 20
	s_add_i32 s60, s2, 24
	s_add_i32 s61, s33, 24
	s_add_i32 s62, s2, 28
	s_add_i32 s63, s33, 28
	v_or_b32_e32 v28, s2, v3
	v_mad_i64_i32 v[26:27], s[34:35], v26, s30, v[20:21]
	v_or_b32_e32 v32, s48, v3
	v_or_b32_e32 v30, s49, v4
	v_or_b32_e32 v36, s52, v3
	v_or_b32_e32 v34, s53, v4
	v_or_b32_e32 v40, s54, v3
	v_or_b32_e32 v38, s55, v4
	v_or_b32_e32 v44, s56, v3
	v_or_b32_e32 v42, s57, v4
	v_or_b32_e32 v48, s58, v3
	v_or_b32_e32 v46, s59, v4
	v_or_b32_e32 v52, s60, v3
	v_or_b32_e32 v50, s61, v4
	v_or_b32_e32 v56, s62, v3
	v_or_b32_e32 v54, s63, v4
	v_mad_i64_i32 v[28:29], s[34:35], v28, s30, v[20:21]
	v_mad_i64_i32 v[30:31], s[34:35], v30, s30, v[20:21]
	v_mad_i64_i32 v[32:33], s[34:35], v32, s30, v[20:21]
	v_mad_i64_i32 v[34:35], s[34:35], v34, s30, v[20:21]
	v_mad_i64_i32 v[36:37], s[34:35], v36, s30, v[20:21]
	v_mad_i64_i32 v[38:39], s[34:35], v38, s30, v[20:21]
	v_mad_i64_i32 v[40:41], s[34:35], v40, s30, v[20:21]
	v_mad_i64_i32 v[42:43], s[34:35], v42, s30, v[20:21]
	v_mad_i64_i32 v[44:45], s[34:35], v44, s30, v[20:21]
	v_mad_i64_i32 v[46:47], s[34:35], v46, s30, v[20:21]
	v_mad_i64_i32 v[48:49], s[34:35], v48, s30, v[20:21]
	v_mad_i64_i32 v[50:51], s[34:35], v50, s30, v[20:21]
	v_mad_i64_i32 v[52:53], s[34:35], v52, s30, v[20:21]
	v_mad_i64_i32 v[54:55], s[34:35], v54, s30, v[20:21]
	v_mad_i64_i32 v[56:57], s[34:35], v56, s30, v[20:21]
	global_load_dword v58, v[26:27], off
	global_load_dword v59, v[28:29], off
	global_load_dword v60, v[30:31], off
	global_load_dword v61, v[32:33], off
	global_load_dword v62, v[34:35], off
	global_load_dword v63, v[36:37], off
	global_load_dword v64, v[38:39], off
	global_load_dword v65, v[40:41], off
	global_load_dword v66, v[42:43], off
	global_load_dword v67, v[44:45], off
	global_load_dword v68, v[46:47], off
	global_load_dword v69, v[48:49], off
	global_load_dword v70, v[50:51], off
	global_load_dword v72, v[52:53], off
	global_load_dword v73, v[54:55], off
	global_load_dword v74, v[56:57], off
	v_or_b32_e32 v28, s2, v1
	v_or_b32_e32 v26, s33, v0
	s_add_i32 s5, s5, 16
	s_add_i32 s0, s0, 16
	s_add_i32 s9, s9, -16
	v_mad_u64_u32 v[26:27], s[34:35], v26, s7, v[6:7]
	v_mad_u64_u32 v[28:29], s[34:35], v28, s7, v[6:7]
	v_or_b32_e32 v27, s48, v1
	v_or_b32_e32 v29, s49, v0
	v_or_b32_e32 v36, s52, v1
	v_or_b32_e32 v34, s53, v0
	v_or_b32_e32 v40, s54, v1
	v_or_b32_e32 v38, s55, v0
	v_or_b32_e32 v44, s56, v1
	v_or_b32_e32 v42, s57, v0
	v_or_b32_e32 v48, s58, v1
	v_or_b32_e32 v46, s59, v0
	v_or_b32_e32 v52, s60, v1
	v_or_b32_e32 v50, s61, v0
	v_or_b32_e32 v56, s62, v1
	v_or_b32_e32 v54, s63, v0
	s_cmp_lg_u32 s9, 0
	v_mad_u64_u32 v[30:31], s[34:35], v29, s7, v[6:7]
	v_mad_u64_u32 v[32:33], s[34:35], v27, s7, v[6:7]
	v_mad_u64_u32 v[34:35], s[34:35], v34, s7, v[6:7]
	v_mad_u64_u32 v[36:37], s[34:35], v36, s7, v[6:7]
	v_mad_u64_u32 v[38:39], s[34:35], v38, s7, v[6:7]
	v_mad_u64_u32 v[40:41], s[34:35], v40, s7, v[6:7]
	v_mad_u64_u32 v[42:43], s[34:35], v42, s7, v[6:7]
	v_mad_u64_u32 v[44:45], s[34:35], v44, s7, v[6:7]
	v_mad_u64_u32 v[46:47], s[34:35], v46, s7, v[6:7]
	v_mad_u64_u32 v[48:49], s[34:35], v48, s7, v[6:7]
	v_mad_u64_u32 v[50:51], s[34:35], v50, s7, v[6:7]
	v_mad_u64_u32 v[52:53], s[34:35], v52, s7, v[6:7]
	v_mad_u64_u32 v[54:55], s[34:35], v54, s7, v[6:7]
	v_mad_u64_u32 v[56:57], s[34:35], v56, s7, v[6:7]
	s_waitcnt vmcnt(15)
	ds_write_b32 v26, v58
	s_waitcnt vmcnt(14)
	ds_write_b32 v28, v59
	s_waitcnt vmcnt(13)
	ds_write_b32 v30, v60
	s_waitcnt vmcnt(12)
	ds_write_b32 v32, v61
	s_waitcnt vmcnt(11)
	ds_write_b32 v34, v62
	s_waitcnt vmcnt(10)
	ds_write_b32 v36, v63
	s_waitcnt vmcnt(9)
	ds_write_b32 v38, v64
	s_waitcnt vmcnt(8)
	ds_write_b32 v40, v65
	s_waitcnt vmcnt(7)
	ds_write_b32 v42, v66
	s_waitcnt vmcnt(6)
	ds_write_b32 v44, v67
	s_waitcnt vmcnt(5)
	ds_write_b32 v46, v68
	s_waitcnt vmcnt(4)
	ds_write_b32 v48, v69
	s_waitcnt vmcnt(3)
	ds_write_b32 v50, v70
	s_waitcnt vmcnt(2)
	ds_write_b32 v52, v72
	s_waitcnt vmcnt(1)
	ds_write_b32 v54, v73
	s_waitcnt vmcnt(0)
	ds_write_b32 v56, v74
	s_cbranch_scc1 .LBB0_1062
; #define LAS __attribute__((address_space(3)))
; #define LDS_WAIT() asm volatile("s_waitcnt lgkmcnt(0)" ::: "memory")
; __device__ __forceinline__ unsigned pk2(float lo, float hi) { return f2bf(lo) | (f2bf(hi) << 16); }
; __device__ __forceinline__ void transpose_item(const float* W, int K, int N, bf16* WT, int row_off, LAS float* scr, int item, int lane) {
;     ...
;     LDS_WAIT(); asm volatile("" ::: "memory");
;     const int c = lane & 7;
; #pragma unroll
;     for (int j = 0; j < 4; ++j) { const int n = (lane >> 3) + 8 * j; const LAS float* s = scr + (8 * c) * 33 + n;
;         u32x4 o; o.x = pk2(s[0 * 33], s[1 * 33]); o.y = pk2(s[2 * 33], s[3 * 33]); o.z = pk2(s[4 * 33], s[5 * 33]); o.w = pk2(s[6 * 33], s[7 * 33]);
;         *(u32x4*)(WT + (size_t)(row_off + n0 + n) * K + k0 + 8 * c) = o; }
;     LDS_WAIT(); asm volatile("" ::: "memory");
	s_waitcnt lgkmcnt(0)
	ds_read2_b32 v[20:21], v22 offset1:8
	ds_read2_b32 v[32:33], v22 offset0:33 offset1:41
	ds_read2_b32 v[34:35], v22 offset0:66 offset1:74
	ds_read2_b32 v[36:37], v22 offset0:99 offset1:107
	ds_read2_b32 v[38:39], v22 offset0:132 offset1:140
	ds_read2_b32 v[40:41], v22 offset0:165 offset1:173
	s_waitcnt lgkmcnt(5)
	s_waitcnt lgkmcnt(4)
	v_cvt_pk_bf16_f32 v26, v20, v32
	s_waitcnt lgkmcnt(3)
	s_waitcnt lgkmcnt(2)
	ds_read2_b32 v[42:43], v22 offset0:198 offset1:206
	ds_read2_b32 v[44:45], v22 offset0:231 offset1:239
	v_cvt_pk_bf16_f32 v27, v34, v36
	s_waitcnt lgkmcnt(3)
	s_waitcnt lgkmcnt(2)
	v_cvt_pk_bf16_f32 v28, v38, v40
	s_waitcnt lgkmcnt(1)
	s_waitcnt lgkmcnt(0)
	s_nop 0
	v_or_b32_e32 v46, s4, v7
	s_ashr_i32 s9, s8, 31
	v_cvt_pk_bf16_f32 v29, v42, v44
	v_ashrrev_i32_e32 v47, 31, v46
	v_bfe_u32 v3, v21, 16, 1
	v_lshl_add_u64 v[30:31], s[8:9], 1, v[14:15]
	v_lshlrev_b64 v[46:47], 12, v[46:47]
	v_add3_u32 v3, v21, v3, s11
	v_bfe_u32 v4, v33, 16, 1
	v_lshl_add_u64 v[46:47], v[30:31], 0, v[46:47]
	v_lshrrev_b32_e32 v3, 16, v3
	v_add3_u32 v4, v33, v4, s11
	global_store_dwordx4 v[46:47], v[26:29], off
	v_or_b32_e32 v20, s4, v23
	v_ashrrev_i32_e32 v21, 31, v20
	v_and_or_b32 v26, v4, s28, v3
	s_nop 0
	s_nop 0
	s_nop 0
	v_cvt_pk_bf16_f32 v27, v35, v37
	v_cvt_pk_bf16_f32 v28, v39, v41
	s_nop 0
	s_nop 0
	v_lshlrev_b64 v[20:21], 12, v[20:21]
	v_cvt_pk_bf16_f32 v29, v43, v45
	ds_read2_b32 v[32:33], v22 offset0:16 offset1:24
	v_lshl_add_u64 v[20:21], v[30:31], 0, v[20:21]
	global_store_dwordx4 v[20:21], v[26:29], off
	ds_read2_b32 v[20:21], v22 offset0:49 offset1:57
	ds_read2_b32 v[34:35], v22 offset0:82 offset1:90
	ds_read2_b32 v[36:37], v22 offset0:115 offset1:123
	s_waitcnt lgkmcnt(3)
	s_nop 0
	s_nop 0
	s_waitcnt lgkmcnt(2)
	ds_read2_b32 v[38:39], v22 offset0:148 offset1:156
	ds_read2_b32 v[40:41], v22 offset0:181 offset1:189
	v_cvt_pk_bf16_f32 v26, v32, v20
	s_waitcnt lgkmcnt(3)
	s_waitcnt lgkmcnt(2)
	ds_read2_b32 v[42:43], v22 offset0:214 offset1:222
	ds_read2_b32 v[44:45], v22 offset0:247 offset1:255
	v_cvt_pk_bf16_f32 v27, v34, v36
	s_waitcnt lgkmcnt(3)
	s_waitcnt lgkmcnt(2)
	v_cvt_pk_bf16_f32 v28, v38, v40
	s_waitcnt lgkmcnt(1)
	s_waitcnt lgkmcnt(0)
	v_or_b32_e32 v46, s4, v24
	v_cvt_pk_bf16_f32 v29, v42, v44
	v_ashrrev_i32_e32 v47, 31, v46
	v_bfe_u32 v3, v33, 16, 1
	v_lshlrev_b64 v[46:47], 12, v[46:47]
	v_add3_u32 v3, v33, v3, s11
	v_bfe_u32 v4, v21, 16, 1
	v_lshl_add_u64 v[46:47], v[30:31], 0, v[46:47]
	v_lshrrev_b32_e32 v3, 16, v3
	v_add3_u32 v4, v21, v4, s11
	global_store_dwordx4 v[46:47], v[26:29], off
	v_or_b32_e32 v20, s4, v25
	v_ashrrev_i32_e32 v21, 31, v20
	v_and_or_b32 v26, v4, s28, v3
	s_nop 0
	s_nop 0
	s_nop 0
	v_cvt_pk_bf16_f32 v27, v35, v37
	v_cvt_pk_bf16_f32 v28, v39, v41
	v_bfe_u32 v3, v43, 16, 1
	v_add3_u32 v3, v43, v3, s11
	v_bfe_u32 v4, v45, 16, 1
	v_lshrrev_b32_e32 v3, 16, v3
	v_add3_u32 v4, v45, v4, s11
	v_lshlrev_b64 v[20:21], 12, v[20:21]
	v_and_or_b32 v29, v4, s28, v3
	v_lshl_add_u64 v[20:21], v[30:31], 0, v[20:21]
	global_store_dwordx4 v[20:21], v[26:29], off
	s_waitcnt lgkmcnt(0)
	s_branch .LBB0_1043

; __device__ __forceinline__ unsigned pk2(float lo, float hi) { return f2bf(lo) | (f2bf(hi) << 16); }
; __device__ __forceinline__ float sigmoid_f(float x) { return __builtin_amdgcn_rcpf(1.f + __expf(-x)); }
; __device__ __forceinline__ float tanh_f(float x) { const float e = __expf(2.f * x); return 1.f - 2.f * __builtin_amdgcn_rcpf(e + 1.f); }
; __device__ __forceinline__ void rwkv_proj_phase(const bf16* Z, const float* shift, const float* w0, const float* a0, const float* kkp, const float* kap, const float* rkp, ...
;     ...
;         bf16x8 xf[12];
; #pragma unroll
;         for (int ks = 0; ks < 12; ++ks) {
;             const int col = 2304 + 32 * ks + 8 * g;
;             const u32x4 c0 = *(const u32x4*)(zr + col), cm = *(const u32x4*)(zr + offm + col), cp = *(const u32x4*)(zr + offp + col);
;             float val[8];
; #pragma unroll
;             for (int q = 0; q < 2; ++q) { const f32x4 t0 = *(const f32x4*)(shift + col + 4 * q) * fm, t1 = *(const f32x4*)(shift + BCOLS + col + 4 * q), t2 = *(const f32x4*)(shift + 2 * BCOLS + col + 4 * q) * fn;
;                 const unsigned m0 = q ? cm.z : cm.x, m1 = q ? cm.w : cm.y, z0 = q ? c0.z : c0.x, z1 = q ? c0.w : c0.y, p0 = q ? cp.z : cp.x, p1 = q ? cp.w : cp.y;
;                 val[4 * q + 0] = t0.x * bflo(m0) + t1.x * bflo(z0) + t2.x * bflo(p0);
;                 val[4 * q + 1] = t0.y * bfhi(m0) + t1.y * bfhi(z0) + t2.y * bfhi(p0);
;                 val[4 * q + 2] = t0.z * bflo(m1) + t1.z * bflo(z1) + t2.z * bflo(p1);
;                 val[4 * q + 3] = t0.w * bfhi(m1) + t1.w * bfhi(z1) + t2.w * bfhi(p1); }
; #pragma unroll
;             for (int e = 0; e < 8; ++e) { if (ks < 4) val[e] = tanh_f(val[e]); else if (ks >= 8) val[e] = sigmoid_f(val[e]); }
;             u32x4 pk; pk.x = pk2(val[0], val[1]); pk.y = pk2(val[2], val[3]); pk.z = pk2(val[4], val[5]); pk.w = pk2(val[6], val[7]);
;             xf[ks] = __builtin_bit_cast(bf16x8, pk);
;             if (ks & 1) asm volatile("" ::: "memory");
;         }
.LBB0_1326:
	s_or_b64 exec, exec, s[0:1]
	v_lshlrev_b32_e32 v76, 3, v172
	v_cmp_eq_u32_e32 vcc, 0, v1
	v_cmp_lt_u32_e64 s[0:1], v1, v0
	v_add_u32_e32 v4, 0x900, v76
	v_cndmask_b32_e64 v3, -1, 0, vcc
	v_cndmask_b32_e64 v2, v159, 0, vcc
	v_cndmask_b32_e64 v88, 0, v160, s[0:1]
	v_mad_i64_i32 v[0:1], s[28:29], v67, s59, v[96:97]
	v_ashrrev_i32_e32 v5, 31, v4
	v_lshl_add_u64 v[74:75], v[0:1], 0, s[46:47]
	v_lshl_add_u64 v[2:3], v[0:1], 0, v[2:3]
	v_lshl_add_u64 v[0:1], v[0:1], 0, v[88:89]
	s_waitcnt vmcnt(0)
	v_lshlrev_b64 v[28:29], 2, v[4:5]
	v_lshl_add_u64 v[70:71], v[2:3], 0, s[46:47]
	v_lshl_add_u64 v[72:73], v[0:1], 0, s[46:47]
	v_lshlrev_b64 v[12:13], 1, v[4:5]
	v_lshl_add_u64 v[20:21], s[4:5], 0, v[28:29]
	v_lshl_add_u64 v[24:25], s[38:39], 0, v[28:29]
	v_lshl_add_u64 v[0:1], v[74:75], 0, v[12:13]
	global_load_dwordx4 v[4:7], v[20:21], off
	global_load_dwordx4 v[8:11], v[24:25], off
	v_lshl_add_u64 v[16:17], v[70:71], 0, v[12:13]
	v_lshl_add_u64 v[12:13], v[72:73], 0, v[12:13]
	global_load_dwordx4 v[0:3], v[0:1], off
	s_nop 0
	global_load_dwordx4 v[12:15], v[12:13], off
	s_nop 0
	global_load_dwordx4 v[16:19], v[16:17], off
	s_nop 0
	global_load_dwordx4 v[20:23], v[20:21], off offset:16
	s_nop 0
	global_load_dwordx4 v[24:27], v[24:25], off offset:16
	v_lshl_add_u64 v[32:33], s[42:43], 0, v[28:29]
	global_load_dwordx4 v[28:31], v[32:33], off
	s_nop 0
	global_load_dwordx4 v[32:35], v[32:33], off offset:16
	v_cndmask_b32_e64 v68, 1.0, 0, vcc
	v_cndmask_b32_e64 v66, 0, 1.0, s[0:1]
	s_mul_i32 s6, s6, 3
	s_sub_i32 s6, s77, s6
	s_mov_b32 s79, 0
	s_lshl_b32 s6, s6, 2
	v_mul_lo_u32 v173, v69, 12
	s_waitcnt vmcnt(8)
	v_pk_mul_f32 v[4:5], v[68:69], v[4:5] op_sel_hi:[0,1]
	s_waitcnt vmcnt(7)
	v_pk_mul_f32 v[8:9], v[66:67], v[8:9] op_sel_hi:[0,1]
	v_pk_mul_f32 v[6:7], v[68:69], v[6:7] op_sel_hi:[0,1]
	v_pk_mul_f32 v[10:11], v[66:67], v[10:11] op_sel_hi:[0,1]
	s_waitcnt vmcnt(5)
	v_and_b32_e32 v37, 0xffff0000, v12
	s_waitcnt vmcnt(4)
	v_and_b32_e32 v36, 0xffff0000, v16
	s_waitcnt vmcnt(3)
	v_pk_mul_f32 v[20:21], v[68:69], v[20:21] op_sel_hi:[0,1]
	s_waitcnt vmcnt(2)
	v_pk_mul_f32 v[24:25], v[66:67], v[24:25] op_sel_hi:[0,1]
	v_mov_b32_e32 v48, v5
	v_mov_b32_e32 v49, v9
	v_and_b32_e32 v52, 0xffff0000, v0
	v_and_b32_e32 v41, 0xffff0000, v13
	v_and_b32_e32 v40, 0xffff0000, v17
	v_and_b32_e32 v45, 0xffff0000, v14
	v_and_b32_e32 v44, 0xffff0000, v18
	v_mov_b32_e32 v51, v10
	v_mov_b32_e32 v10, v7
	v_mov_b32_e32 v7, v24
	v_mov_b32_e32 v24, v21
	v_pk_mul_f32 v[36:37], v[48:49], v[36:37]
	v_lshlrev_b32_e32 v53, 16, v1
	v_lshlrev_b32_e32 v39, 16, v13
	v_lshlrev_b32_e32 v38, 16, v17
	v_and_b32_e32 v1, 0xffff0000, v1
	v_lshlrev_b32_e32 v13, 16, v2
	v_and_b32_e32 v2, 0xffff0000, v2
	v_mov_b32_e32 v50, v6
	v_pk_mul_f32 v[10:11], v[10:11], v[40:41]
	v_pk_mul_f32 v[24:25], v[24:25], v[44:45]
	s_waitcnt vmcnt(1)
	v_fma_f32 v5, v29, v52, v36
	v_pk_mul_f32 v[22:23], v[68:69], v[22:23] op_sel_hi:[0,1]
	v_pk_mul_f32 v[26:27], v[66:67], v[26:27] op_sel_hi:[0,1]
	v_lshlrev_b32_e32 v43, 16, v14
	v_lshlrev_b32_e32 v42, 16, v18
	v_mov_b32_e32 v6, v20
	v_pk_mul_f32 v[38:39], v[50:51], v[38:39]
	v_fma_f32 v1, v31, v1, v10
	s_waitcnt vmcnt(0)
	v_fma_f32 v2, v33, v2, v24
	v_add_f32_e32 v36, v5, v37
	v_lshlrev_b32_e32 v14, 16, v3
	v_mov_b32_e32 v21, v26
	v_pk_mul_f32 v[6:7], v[6:7], v[42:43]
	v_fma_f32 v9, v30, v53, v38
	v_add_f32_e32 v38, v1, v11
	v_add_f32_e32 v42, v2, v25
	v_and_b32_e32 v1, 0xffff0000, v3
	v_and_b32_e32 v3, 0xffff0000, v15
	v_and_b32_e32 v2, 0xffff0000, v19
	v_mov_b32_e32 v26, v23
	v_add_f32_e32 v36, v36, v36
	v_lshlrev_b32_e32 v47, 16, v15
	v_lshlrev_b32_e32 v46, 16, v19
	v_mov_b32_e32 v20, v22
	v_fma_f32 v6, v32, v13, v6
	v_pk_mul_f32 v[2:3], v[26:27], v[2:3]
	v_mov_b32_e32 v5, v8
	v_add_u32_e32 v8, 0x920, v76
	v_mul_f32_e32 v36, 0x3fb8aa3b, v36
	v_pk_mul_f32 v[20:21], v[20:21], v[46:47]
	v_add_f32_e32 v37, v9, v39
	v_add_f32_e32 v39, v6, v7
	v_fma_f32 v2, v35, v1, v2
	v_lshlrev_b32_e32 v6, 16, v0
	v_lshlrev_b32_e32 v1, 16, v12
	v_lshlrev_b32_e32 v0, 16, v16
	v_ashrrev_i32_e32 v9, 31, v8
	v_exp_f32_e32 v36, v36
	v_fma_f32 v10, v34, v14, v20
	v_pk_mul_f32 v[0:1], v[4:5], v[0:1]
	v_lshlrev_b64 v[24:25], 1, v[8:9]
	v_lshlrev_b64 v[32:33], 2, v[8:9]
	v_add_f32_e32 v43, v10, v21
	v_fma_f32 v0, v28, v6, v0
	v_lshl_add_u64 v[4:5], v[74:75], 0, v[24:25]
	v_lshl_add_u64 v[12:13], s[4:5], 0, v[32:33]
	v_lshl_add_u64 v[20:21], s[38:39], 0, v[32:33]
	global_load_dwordx4 v[4:7], v[4:5], off
	s_nop 0
	global_load_dwordx4 v[8:11], v[12:13], off offset:16
	s_nop 0
	global_load_dwordx4 v[12:15], v[12:13], off
	s_nop 0
	global_load_dwordx4 v[16:19], v[20:21], off offset:16
	s_nop 0
	global_load_dwordx4 v[20:23], v[20:21], off
	v_lshl_add_u64 v[28:29], v[70:71], 0, v[24:25]
	v_lshl_add_u64 v[24:25], v[72:73], 0, v[24:25]
	v_add_f32_e32 v0, v0, v1
	global_load_dwordx4 v[24:27], v[24:25], off
	s_nop 0
	global_load_dwordx4 v[28:31], v[28:29], off
	v_add_f32_e32 v40, v0, v0
	v_add_f32_e32 v44, v2, v3
	v_add_f32_e32 v3, 1.0, v36
	v_add_f32_e32 v36, v37, v37
	v_add_f32_e32 v37, v38, v38
	v_lshl_add_u64 v[0:1], s[42:43], 0, v[32:33]
	v_mul_f32_e32 v40, 0x3fb8aa3b, v40
	v_mul_f32_e32 v36, 0x3fb8aa3b, v36
	v_mul_f32_e32 v37, 0x3fb8aa3b, v37
	global_load_dwordx4 v[32:35], v[0:1], off
	v_exp_f32_e32 v40, v40
	v_exp_f32_e32 v36, v36
	v_exp_f32_e32 v37, v37
	v_add_f32_e32 v2, 1.0, v40
	v_rcp_f32_e32 v40, v3
	v_add_f32_e32 v3, 1.0, v36
	v_add_f32_e32 v36, 1.0, v37
	v_rcp_f32_e32 v41, v36
	v_add_f32_e32 v36, v39, v39
	v_mul_f32_e32 v36, 0x3fb8aa3b, v36
	v_exp_f32_e32 v45, v36
	v_add_f32_e32 v36, v42, v42
	v_mul_f32_e32 v36, 0x3fb8aa3b, v36
	v_exp_f32_e32 v42, v36
	global_load_dwordx4 v[36:39], v[0:1], off offset:16
	v_add_f32_e32 v0, 1.0, v45
	v_rcp_f32_e32 v2, v2
	v_add_f32_e32 v1, 1.0, v42
	v_add_f32_e32 v42, v43, v43
	v_mul_f32_e32 v42, 0x3fb8aa3b, v42
	v_exp_f32_e32 v43, v42
	v_add_f32_e32 v42, v44, v44
	v_mul_f32_e32 v42, 0x3fb8aa3b, v42
	v_exp_f32_e32 v44, v42
	v_rcp_f32_e32 v42, v1
	v_add_f32_e32 v1, 1.0, v43
	v_rcp_f32_e32 v3, v3
	v_add_f32_e32 v43, 1.0, v44
	v_rcp_f32_e32 v43, v43
	v_rcp_f32_e32 v0, v0
	v_rcp_f32_e32 v1, v1
	v_pk_fma_f32 v[40:41], v[40:41], 2.0, 1.0 op_sel_hi:[1,0,0] neg_lo:[1,0,0] neg_hi:[1,0,0]
	v_pk_fma_f32 v[42:43], v[42:43], 2.0, 1.0 op_sel_hi:[1,0,0] neg_lo:[1,0,0] neg_hi:[1,0,0]
	v_pk_fma_f32 v[2:3], v[2:3], 2.0, 1.0 op_sel_hi:[1,0,0] neg_lo:[1,0,0] neg_hi:[1,0,0]
	v_pk_fma_f32 v[0:1], v[0:1], 2.0, 1.0 op_sel_hi:[1,0,0] neg_lo:[1,0,0] neg_hi:[1,0,0]
	s_nop 0
	s_nop 0
	v_bfe_u32 v46, v41, 16, 1
	v_bfe_u32 v47, v40, 16, 1
	v_add3_u32 v40, v40, v47, s61
	v_add3_u32 v41, v41, v46, s61
	v_bfe_u32 v44, v2, 16, 1
	v_bfe_u32 v45, v3, 16, 1
	v_add3_u32 v3, v3, v45, s61
	v_add3_u32 v2, v2, v44, s61
	v_lshrrev_b32_e32 v44, 16, v2
	v_lshrrev_b32_e32 v45, 16, v3
	v_cvt_pk_bf16_f32 v3, v1, v43
	v_cvt_pk_bf16_f32 v2, v0, v42
	v_and_or_b32 v1, v41, s60, v45
	v_and_or_b32 v0, v40, s60, v44
	s_waitcnt vmcnt(7)
; __device__ __forceinline__ unsigned pk2(float lo, float hi) { return f2bf(lo) | (f2bf(hi) << 16); }
; __device__ __forceinline__ float sigmoid_f(float x) { return __builtin_amdgcn_rcpf(1.f + __expf(-x)); }
; __device__ __forceinline__ float tanh_f(float x) { const float e = __expf(2.f * x); return 1.f - 2.f * __builtin_amdgcn_rcpf(e + 1.f); }
; __device__ __forceinline__ void rwkv_proj_phase(const bf16* Z, const float* shift, const float* w0, const float* a0, const float* kkp, const float* kap, const float* rkp, ...
;     ...
;         bf16x8 xf[12];
; #pragma unroll
;         for (int ks = 0; ks < 12; ++ks) {
;             const int col = 2304 + 32 * ks + 8 * g;
;             const u32x4 c0 = *(const u32x4*)(zr + col), cm = *(const u32x4*)(zr + offm + col), cp = *(const u32x4*)(zr + offp + col);
;             float val[8];
; #pragma unroll
;             for (int q = 0; q < 2; ++q) { const f32x4 t0 = *(const f32x4*)(shift + col + 4 * q) * fm, t1 = *(const f32x4*)(shift + BCOLS + col + 4 * q), t2 = *(const f32x4*)(shift + 2 * BCOLS + col + 4 * q) * fn;
;                 const unsigned m0 = q ? cm.z : cm.x, m1 = q ? cm.w : cm.y, z0 = q ? c0.z : c0.x, z1 = q ? c0.w : c0.y, p0 = q ? cp.z : cp.x, p1 = q ? cp.w : cp.y;
;                 val[4 * q + 0] = t0.x * bflo(m0) + t1.x * bflo(z0) + t2.x * bflo(p0);
;                 val[4 * q + 1] = t0.y * bfhi(m0) + t1.y * bfhi(z0) + t2.y * bfhi(p0);
;                 val[4 * q + 2] = t0.z * bflo(m1) + t1.z * bflo(z1) + t2.z * bflo(p1);
;                 val[4 * q + 3] = t0.w * bfhi(m1) + t1.w * bfhi(z1) + t2.w * bfhi(p1); }
; #pragma unroll
;             for (int e = 0; e < 8; ++e) { if (ks < 4) val[e] = tanh_f(val[e]); else if (ks >= 8) val[e] = sigmoid_f(val[e]); }
;             u32x4 pk; pk.x = pk2(val[0], val[1]); pk.y = pk2(val[2], val[3]); pk.z = pk2(val[4], val[5]); pk.w = pk2(val[6], val[7]);
;             xf[ks] = __builtin_bit_cast(bf16x8, pk);
;             if (ks & 1) asm volatile("" ::: "memory");
;         }
	v_pk_mul_f32 v[8:9], v[68:69], v[8:9] op_sel_hi:[0,1]
	s_waitcnt vmcnt(6)
	v_pk_mul_f32 v[12:13], v[68:69], v[12:13] op_sel_hi:[0,1]
	v_mov_b32_e32 v42, v13
	s_waitcnt vmcnt(4)
	v_pk_mul_f32 v[20:21], v[66:67], v[20:21] op_sel_hi:[0,1]
	v_mov_b32_e32 v43, v21
	v_and_b32_e32 v44, 0xffff0000, v4
	s_waitcnt vmcnt(3)
	v_and_b32_e32 v41, 0xffff0000, v24
	s_waitcnt vmcnt(2)
	v_and_b32_e32 v40, 0xffff0000, v28
	v_pk_mul_f32 v[40:41], v[42:43], v[40:41]
	v_pk_mul_f32 v[14:15], v[68:69], v[14:15] op_sel_hi:[0,1]
	v_pk_mul_f32 v[22:23], v[66:67], v[22:23] op_sel_hi:[0,1]
	v_mov_b32_e32 v42, v14
	v_mov_b32_e32 v43, v22
	v_mov_b32_e32 v22, v15
	v_pk_mul_f32 v[16:17], v[66:67], v[16:17] op_sel_hi:[0,1]
	v_pk_mul_f32 v[10:11], v[68:69], v[10:11] op_sel_hi:[0,1]
	s_waitcnt vmcnt(1)
	v_fma_f32 v13, v33, v44, v40
	v_add_f32_e32 v44, v13, v41
	v_lshlrev_b32_e32 v41, 16, v25
	v_lshlrev_b32_e32 v40, 16, v29
	v_lshlrev_b32_e32 v13, 16, v5
	v_pk_mul_f32 v[40:41], v[42:43], v[40:41]
	v_and_b32_e32 v5, 0xffff0000, v5
	v_fma_f32 v13, v34, v13, v40
	v_add_f32_e32 v42, v13, v41
	v_and_b32_e32 v41, 0xffff0000, v25
	v_and_b32_e32 v40, 0xffff0000, v29
	v_pk_mul_f32 v[14:15], v[22:23], v[40:41]
	v_mov_b32_e32 v22, v8
	v_fma_f32 v5, v35, v5, v14
	v_add_f32_e32 v40, v5, v15
	v_pk_mul_f32 v[14:15], v[66:67], v[18:19] op_sel_hi:[0,1]
	v_lshlrev_b32_e32 v19, 16, v26
	v_lshlrev_b32_e32 v18, 16, v30
	v_mov_b32_e32 v23, v16
	v_lshlrev_b32_e32 v5, 16, v6
	v_pk_mul_f32 v[18:19], v[22:23], v[18:19]
	v_mov_b32_e32 v16, v9
	s_waitcnt vmcnt(0)
	v_fma_f32 v5, v36, v5, v18
	v_add_f32_e32 v41, v5, v19
	v_and_b32_e32 v19, 0xffff0000, v26
	v_and_b32_e32 v18, 0xffff0000, v30
	v_and_b32_e32 v5, 0xffff0000, v6
	v_pk_mul_f32 v[8:9], v[16:17], v[18:19]
	v_mov_b32_e32 v16, v10
	v_fma_f32 v5, v37, v5, v8
	v_add_f32_e32 v43, v5, v9
	v_lshlrev_b32_e32 v9, 16, v27
	v_lshlrev_b32_e32 v8, 16, v31
	v_mov_b32_e32 v17, v14
	v_lshlrev_b32_e32 v5, 16, v7
	v_pk_mul_f32 v[8:9], v[16:17], v[8:9]
	v_and_b32_e32 v6, 0xffff0000, v31
	v_fma_f32 v5, v38, v5, v8
	v_add_f32_e32 v46, v5, v9
	v_and_b32_e32 v5, 0xffff0000, v7
	v_and_b32_e32 v7, 0xffff0000, v27
	v_mov_b32_e32 v14, v11
	v_pk_mul_f32 v[6:7], v[14:15], v[6:7]
	v_lshlrev_b32_e32 v8, 16, v4
	v_fma_f32 v6, v39, v5, v6
	v_lshlrev_b32_e32 v5, 16, v24
	v_lshlrev_b32_e32 v4, 16, v28
	v_mov_b32_e32 v13, v20
	v_pk_mul_f32 v[4:5], v[12:13], v[4:5]
	v_add_u32_e32 v12, 0x940, v76
	v_ashrrev_i32_e32 v13, 31, v12
	v_lshlrev_b64 v[28:29], 1, v[12:13]
	v_lshlrev_b64 v[36:37], 2, v[12:13]
	v_fma_f32 v4, v32, v8, v4
	v_lshl_add_u64 v[8:9], v[74:75], 0, v[28:29]
	v_lshl_add_u64 v[16:17], s[4:5], 0, v[36:37]
	v_lshl_add_u64 v[24:25], s[38:39], 0, v[36:37]
	global_load_dwordx4 v[8:11], v[8:9], off
	s_nop 0
	global_load_dwordx4 v[12:15], v[16:17], off offset:16
	s_nop 0
	global_load_dwordx4 v[16:19], v[16:17], off
	s_nop 0
	global_load_dwordx4 v[20:23], v[24:25], off offset:16
	s_nop 0
	global_load_dwordx4 v[24:27], v[24:25], off
	v_lshl_add_u64 v[32:33], v[70:71], 0, v[28:29]
	v_lshl_add_u64 v[28:29], v[72:73], 0, v[28:29]
	global_load_dwordx4 v[28:31], v[28:29], off
	s_nop 0
	global_load_dwordx4 v[32:35], v[32:33], off
	v_add_f32_e32 v4, v4, v5
	v_add_f32_e32 v40, v40, v40
	v_add_f32_e32 v45, v4, v4
	v_lshl_add_u64 v[4:5], s[42:43], 0, v[36:37]
	v_mul_f32_e32 v40, 0x3fb8aa3b, v40
	global_load_dwordx4 v[36:39], v[4:5], off
	v_mul_f32_e32 v45, 0x3fb8aa3b, v45
	v_exp_f32_e32 v40, v40
	v_exp_f32_e32 v45, v45
	v_add_f32_e32 v44, v44, v44
	v_mul_f32_e32 v44, 0x3fb8aa3b, v44
	v_add_f32_e32 v42, v42, v42
	v_exp_f32_e32 v44, v44
	v_mul_f32_e32 v42, 0x3fb8aa3b, v42
	v_add_f32_e32 v40, 1.0, v40
	v_add_f32_e32 v47, v6, v7
	v_add_f32_e32 v6, 1.0, v45
	v_exp_f32_e32 v42, v42
	v_rcp_f32_e32 v45, v40
	v_add_f32_e32 v40, v41, v41
	v_mul_f32_e32 v40, 0x3fb8aa3b, v40
	v_exp_f32_e32 v48, v40
	v_add_f32_e32 v40, v43, v43
	v_add_f32_e32 v7, 1.0, v44
	v_mul_f32_e32 v40, 0x3fb8aa3b, v40
	v_rcp_f32_e32 v44, v7
	v_add_f32_e32 v7, 1.0, v42
	v_exp_f32_e32 v49, v40
	global_load_dwordx4 v[40:43], v[4:5], off offset:16
	v_add_f32_e32 v46, v46, v46
	v_mul_f32_e32 v46, 0x3fb8aa3b, v46
	v_add_f32_e32 v4, 1.0, v48
	v_exp_f32_e32 v48, v46
	v_add_f32_e32 v46, v47, v47
	v_mul_f32_e32 v46, 0x3fb8aa3b, v46
	v_exp_f32_e32 v47, v46
	v_add_f32_e32 v5, 1.0, v49
	v_rcp_f32_e32 v46, v5
	v_add_f32_e32 v5, 1.0, v48
	v_add_f32_e32 v47, 1.0, v47
	v_rcp_f32_e32 v47, v47
	v_rcp_f32_e32 v6, v6
	v_rcp_f32_e32 v7, v7
	v_rcp_f32_e32 v4, v4
	v_rcp_f32_e32 v5, v5
	v_pk_fma_f32 v[44:45], v[44:45], 2.0, 1.0 op_sel_hi:[1,0,0] neg_lo:[1,0,0] neg_hi:[1,0,0]
	v_pk_fma_f32 v[46:47], v[46:47], 2.0, 1.0 op_sel_hi:[1,0,0] neg_lo:[1,0,0] neg_hi:[1,0,0]
	v_pk_fma_f32 v[6:7], v[6:7], 2.0, 1.0 op_sel_hi:[1,0,0] neg_lo:[1,0,0] neg_hi:[1,0,0]
	v_pk_fma_f32 v[4:5], v[4:5], 2.0, 1.0 op_sel_hi:[1,0,0] neg_lo:[1,0,0] neg_hi:[1,0,0]
	s_nop 0
	s_nop 0
	v_bfe_u32 v50, v45, 16, 1
	v_bfe_u32 v51, v44, 16, 1
	v_add3_u32 v44, v44, v51, s61
	v_add3_u32 v45, v45, v50, s61
	v_bfe_u32 v48, v6, 16, 1
	v_bfe_u32 v49, v7, 16, 1
	v_add3_u32 v7, v7, v49, s61
	v_add3_u32 v6, v6, v48, s61
	v_lshrrev_b32_e32 v48, 16, v6
	v_lshrrev_b32_e32 v49, 16, v7
	v_cvt_pk_bf16_f32 v7, v5, v47
	v_cvt_pk_bf16_f32 v6, v4, v46
	v_and_or_b32 v5, v45, s60, v49
	v_and_or_b32 v4, v44, s60, v48
	s_waitcnt vmcnt(7)
	v_pk_mul_f32 v[12:13], v[68:69], v[12:13] op_sel_hi:[0,1]
	s_waitcnt vmcnt(6)
	v_pk_mul_f32 v[16:17], v[68:69], v[16:17] op_sel_hi:[0,1]
	v_mov_b32_e32 v46, v17
	s_waitcnt vmcnt(4)
	v_pk_mul_f32 v[24:25], v[66:67], v[24:25] op_sel_hi:[0,1]
	v_mov_b32_e32 v47, v25
	s_waitcnt vmcnt(3)
	v_and_b32_e32 v45, 0xffff0000, v28
	s_waitcnt vmcnt(2)
; __device__ __forceinline__ unsigned pk2(float lo, float hi) { return f2bf(lo) | (f2bf(hi) << 16); }
; __device__ __forceinline__ float sigmoid_f(float x) { return __builtin_amdgcn_rcpf(1.f + __expf(-x)); }
; __device__ __forceinline__ float tanh_f(float x) { const float e = __expf(2.f * x); return 1.f - 2.f * __builtin_amdgcn_rcpf(e + 1.f); }
; __device__ __forceinline__ void rwkv_proj_phase(const bf16* Z, const float* shift, const float* w0, const float* a0, const float* kkp, const float* kap, const float* rkp, ...
;     ...
;         bf16x8 xf[12];
; #pragma unroll
;         for (int ks = 0; ks < 12; ++ks) {
;             const int col = 2304 + 32 * ks + 8 * g;
;             const u32x4 c0 = *(const u32x4*)(zr + col), cm = *(const u32x4*)(zr + offm + col), cp = *(const u32x4*)(zr + offp + col);
;             float val[8];
; #pragma unroll
;             for (int q = 0; q < 2; ++q) { const f32x4 t0 = *(const f32x4*)(shift + col + 4 * q) * fm, t1 = *(const f32x4*)(shift + BCOLS + col + 4 * q), t2 = *(const f32x4*)(shift + 2 * BCOLS + col + 4 * q) * fn;
;                 const unsigned m0 = q ? cm.z : cm.x, m1 = q ? cm.w : cm.y, z0 = q ? c0.z : c0.x, z1 = q ? c0.w : c0.y, p0 = q ? cp.z : cp.x, p1 = q ? cp.w : cp.y;
;                 val[4 * q + 0] = t0.x * bflo(m0) + t1.x * bflo(z0) + t2.x * bflo(p0);
;                 val[4 * q + 1] = t0.y * bfhi(m0) + t1.y * bfhi(z0) + t2.y * bfhi(p0);
;                 val[4 * q + 2] = t0.z * bflo(m1) + t1.z * bflo(z1) + t2.z * bflo(p1);
;                 val[4 * q + 3] = t0.w * bfhi(m1) + t1.w * bfhi(z1) + t2.w * bfhi(p1); }
; #pragma unroll
;             for (int e = 0; e < 8; ++e) { if (ks < 4) val[e] = tanh_f(val[e]); else if (ks >= 8) val[e] = sigmoid_f(val[e]); }
;             u32x4 pk; pk.x = pk2(val[0], val[1]); pk.y = pk2(val[2], val[3]); pk.z = pk2(val[4], val[5]); pk.w = pk2(val[6], val[7]);
;             xf[ks] = __builtin_bit_cast(bf16x8, pk);
;             if (ks & 1) asm volatile("" ::: "memory");
;         }
	v_and_b32_e32 v44, 0xffff0000, v32
	v_and_b32_e32 v48, 0xffff0000, v8
	v_pk_mul_f32 v[44:45], v[46:47], v[44:45]
	v_pk_mul_f32 v[18:19], v[68:69], v[18:19] op_sel_hi:[0,1]
	v_pk_mul_f32 v[26:27], v[66:67], v[26:27] op_sel_hi:[0,1]
	v_mov_b32_e32 v46, v18
	s_waitcnt vmcnt(1)
	v_fma_f32 v17, v37, v48, v44
	v_add_f32_e32 v48, v17, v45
	v_lshlrev_b32_e32 v45, 16, v29
	v_lshlrev_b32_e32 v44, 16, v33
	v_mov_b32_e32 v47, v26
	v_lshlrev_b32_e32 v17, 16, v9
	v_pk_mul_f32 v[44:45], v[46:47], v[44:45]
	v_mov_b32_e32 v26, v19
	v_fma_f32 v17, v38, v17, v44
	v_add_f32_e32 v46, v17, v45
	v_and_b32_e32 v45, 0xffff0000, v29
	v_and_b32_e32 v44, 0xffff0000, v33
	v_and_b32_e32 v9, 0xffff0000, v9
	v_pk_mul_f32 v[18:19], v[26:27], v[44:45]
	v_pk_mul_f32 v[20:21], v[66:67], v[20:21] op_sel_hi:[0,1]
	v_fma_f32 v9, v39, v9, v18
	v_add_f32_e32 v44, v9, v19
	v_pk_mul_f32 v[18:19], v[66:67], v[22:23] op_sel_hi:[0,1]
	v_lshlrev_b32_e32 v23, 16, v30
	v_lshlrev_b32_e32 v22, 16, v34
	v_mov_b32_e32 v26, v12
	v_mov_b32_e32 v27, v20
	v_lshlrev_b32_e32 v9, 16, v10
	v_pk_mul_f32 v[22:23], v[26:27], v[22:23]
	v_mov_b32_e32 v20, v13
	s_waitcnt vmcnt(0)
	v_fma_f32 v9, v40, v9, v22
	v_add_f32_e32 v45, v9, v23
	v_and_b32_e32 v23, 0xffff0000, v30
	v_and_b32_e32 v22, 0xffff0000, v34
	v_and_b32_e32 v9, 0xffff0000, v10
	v_pk_mul_f32 v[12:13], v[20:21], v[22:23]
	v_pk_mul_f32 v[14:15], v[68:69], v[14:15] op_sel_hi:[0,1]
	v_fma_f32 v9, v41, v9, v12
	v_add_f32_e32 v47, v9, v13
	v_lshlrev_b32_e32 v13, 16, v31
	v_lshlrev_b32_e32 v12, 16, v35
	v_mov_b32_e32 v20, v14
	v_mov_b32_e32 v21, v18
	v_lshlrev_b32_e32 v9, 16, v11
	v_pk_mul_f32 v[12:13], v[20:21], v[12:13]
	v_and_b32_e32 v10, 0xffff0000, v35
	v_fma_f32 v9, v42, v9, v12
	v_add_f32_e32 v50, v9, v13
	v_and_b32_e32 v9, 0xffff0000, v11
	v_and_b32_e32 v11, 0xffff0000, v31
	v_mov_b32_e32 v18, v15
	v_pk_mul_f32 v[10:11], v[18:19], v[10:11]
	v_lshlrev_b32_e32 v12, 16, v8
	v_fma_f32 v10, v43, v9, v10
	v_lshlrev_b32_e32 v9, 16, v28
	v_lshlrev_b32_e32 v8, 16, v32
	v_mov_b32_e32 v17, v24
	v_pk_mul_f32 v[8:9], v[16:17], v[8:9]
	v_add_u32_e32 v16, 0x960, v76
	v_ashrrev_i32_e32 v17, 31, v16
	v_lshlrev_b64 v[32:33], 1, v[16:17]
	v_lshlrev_b64 v[40:41], 2, v[16:17]
	v_fma_f32 v8, v36, v12, v8
	v_lshl_add_u64 v[12:13], v[74:75], 0, v[32:33]
	v_lshl_add_u64 v[20:21], s[4:5], 0, v[40:41]
	v_lshl_add_u64 v[28:29], s[38:39], 0, v[40:41]
	global_load_dwordx4 v[12:15], v[12:13], off
	s_nop 0
	global_load_dwordx4 v[16:19], v[20:21], off offset:16
	s_nop 0
	global_load_dwordx4 v[20:23], v[20:21], off
	s_nop 0
	global_load_dwordx4 v[24:27], v[28:29], off offset:16
	s_nop 0
	global_load_dwordx4 v[28:31], v[28:29], off
	v_lshl_add_u64 v[36:37], v[70:71], 0, v[32:33]
	v_lshl_add_u64 v[32:33], v[72:73], 0, v[32:33]
	global_load_dwordx4 v[32:35], v[32:33], off
	s_nop 0
	global_load_dwordx4 v[36:39], v[36:37], off
	v_add_f32_e32 v8, v8, v9
	v_add_f32_e32 v44, v44, v44
	v_add_f32_e32 v49, v8, v8
	v_lshl_add_u64 v[8:9], s[42:43], 0, v[40:41]
	v_mul_f32_e32 v44, 0x3fb8aa3b, v44
	global_load_dwordx4 v[40:43], v[8:9], off
	v_mul_f32_e32 v49, 0x3fb8aa3b, v49
	v_exp_f32_e32 v44, v44
	v_exp_f32_e32 v49, v49
	v_add_f32_e32 v48, v48, v48
	v_mul_f32_e32 v48, 0x3fb8aa3b, v48
	v_add_f32_e32 v46, v46, v46
	v_exp_f32_e32 v48, v48
	v_mul_f32_e32 v46, 0x3fb8aa3b, v46
	v_add_f32_e32 v44, 1.0, v44
	v_add_f32_e32 v51, v10, v11
	v_add_f32_e32 v10, 1.0, v49
	v_exp_f32_e32 v46, v46
	v_rcp_f32_e32 v49, v44
	v_add_f32_e32 v44, v45, v45
	v_mul_f32_e32 v44, 0x3fb8aa3b, v44
	v_exp_f32_e32 v52, v44
	v_add_f32_e32 v44, v47, v47
	v_add_f32_e32 v11, 1.0, v48
	v_mul_f32_e32 v44, 0x3fb8aa3b, v44
	v_rcp_f32_e32 v48, v11
	v_add_f32_e32 v11, 1.0, v46
	v_exp_f32_e32 v53, v44
	global_load_dwordx4 v[44:47], v[8:9], off offset:16
	v_add_f32_e32 v50, v50, v50
	v_mul_f32_e32 v50, 0x3fb8aa3b, v50
	v_add_f32_e32 v8, 1.0, v52
	v_exp_f32_e32 v52, v50
	v_add_f32_e32 v50, v51, v51
	v_mul_f32_e32 v50, 0x3fb8aa3b, v50
	v_exp_f32_e32 v51, v50
	v_add_f32_e32 v9, 1.0, v53
	v_rcp_f32_e32 v50, v9
	v_add_f32_e32 v9, 1.0, v52
	v_add_f32_e32 v51, 1.0, v51
	v_rcp_f32_e32 v51, v51
	v_rcp_f32_e32 v10, v10
	v_rcp_f32_e32 v11, v11
	v_rcp_f32_e32 v8, v8
	v_rcp_f32_e32 v9, v9
	v_pk_fma_f32 v[48:49], v[48:49], 2.0, 1.0 op_sel_hi:[1,0,0] neg_lo:[1,0,0] neg_hi:[1,0,0]
	v_pk_fma_f32 v[50:51], v[50:51], 2.0, 1.0 op_sel_hi:[1,0,0] neg_lo:[1,0,0] neg_hi:[1,0,0]
	v_pk_fma_f32 v[10:11], v[10:11], 2.0, 1.0 op_sel_hi:[1,0,0] neg_lo:[1,0,0] neg_hi:[1,0,0]
	v_pk_fma_f32 v[8:9], v[8:9], 2.0, 1.0 op_sel_hi:[1,0,0] neg_lo:[1,0,0] neg_hi:[1,0,0]
	s_nop 0
	s_nop 0
	v_bfe_u32 v54, v49, 16, 1
	v_bfe_u32 v55, v48, 16, 1
	v_add3_u32 v48, v48, v55, s61
	v_add3_u32 v49, v49, v54, s61
	v_bfe_u32 v52, v10, 16, 1
	v_bfe_u32 v53, v11, 16, 1
	v_add3_u32 v11, v11, v53, s61
	v_add3_u32 v10, v10, v52, s61
	v_lshrrev_b32_e32 v52, 16, v10
	v_lshrrev_b32_e32 v53, 16, v11
	v_cvt_pk_bf16_f32 v11, v9, v51
	v_cvt_pk_bf16_f32 v10, v8, v50
	v_and_or_b32 v9, v49, s60, v53
	v_and_or_b32 v8, v48, s60, v52
	s_waitcnt vmcnt(7)
	v_pk_mul_f32 v[16:17], v[68:69], v[16:17] op_sel_hi:[0,1]
	s_waitcnt vmcnt(6)
	v_pk_mul_f32 v[20:21], v[68:69], v[20:21] op_sel_hi:[0,1]
	v_mov_b32_e32 v50, v21
	s_waitcnt vmcnt(4)
	v_pk_mul_f32 v[28:29], v[66:67], v[28:29] op_sel_hi:[0,1]
	v_mov_b32_e32 v51, v29
	s_waitcnt vmcnt(3)
	v_and_b32_e32 v49, 0xffff0000, v32
	s_waitcnt vmcnt(2)
	v_and_b32_e32 v48, 0xffff0000, v36
	v_and_b32_e32 v52, 0xffff0000, v12
	v_pk_mul_f32 v[48:49], v[50:51], v[48:49]
	v_pk_mul_f32 v[22:23], v[68:69], v[22:23] op_sel_hi:[0,1]
	v_pk_mul_f32 v[30:31], v[66:67], v[30:31] op_sel_hi:[0,1]
	v_mov_b32_e32 v50, v22
	s_waitcnt vmcnt(1)
; __device__ __forceinline__ unsigned pk2(float lo, float hi) { return f2bf(lo) | (f2bf(hi) << 16); }
; __device__ __forceinline__ float sigmoid_f(float x) { return __builtin_amdgcn_rcpf(1.f + __expf(-x)); }
; __device__ __forceinline__ float tanh_f(float x) { const float e = __expf(2.f * x); return 1.f - 2.f * __builtin_amdgcn_rcpf(e + 1.f); }
; __device__ __forceinline__ void rwkv_proj_phase(const bf16* Z, const float* shift, const float* w0, const float* a0, const float* kkp, const float* kap, const float* rkp, ...
;     ...
;         bf16x8 xf[12];
; #pragma unroll
;         for (int ks = 0; ks < 12; ++ks) {
;             const int col = 2304 + 32 * ks + 8 * g;
;             const u32x4 c0 = *(const u32x4*)(zr + col), cm = *(const u32x4*)(zr + offm + col), cp = *(const u32x4*)(zr + offp + col);
;             float val[8];
; #pragma unroll
;             for (int q = 0; q < 2; ++q) { const f32x4 t0 = *(const f32x4*)(shift + col + 4 * q) * fm, t1 = *(const f32x4*)(shift + BCOLS + col + 4 * q), t2 = *(const f32x4*)(shift + 2 * BCOLS + col + 4 * q) * fn;
;                 const unsigned m0 = q ? cm.z : cm.x, m1 = q ? cm.w : cm.y, z0 = q ? c0.z : c0.x, z1 = q ? c0.w : c0.y, p0 = q ? cp.z : cp.x, p1 = q ? cp.w : cp.y;
;                 val[4 * q + 0] = t0.x * bflo(m0) + t1.x * bflo(z0) + t2.x * bflo(p0);
;                 val[4 * q + 1] = t0.y * bfhi(m0) + t1.y * bfhi(z0) + t2.y * bfhi(p0);
;                 val[4 * q + 2] = t0.z * bflo(m1) + t1.z * bflo(z1) + t2.z * bflo(p1);
;                 val[4 * q + 3] = t0.w * bfhi(m1) + t1.w * bfhi(z1) + t2.w * bfhi(p1); }
; #pragma unroll
;             for (int e = 0; e < 8; ++e) { if (ks < 4) val[e] = tanh_f(val[e]); else if (ks >= 8) val[e] = sigmoid_f(val[e]); }
;             u32x4 pk; pk.x = pk2(val[0], val[1]); pk.y = pk2(val[2], val[3]); pk.z = pk2(val[4], val[5]); pk.w = pk2(val[6], val[7]);
;             xf[ks] = __builtin_bit_cast(bf16x8, pk);
;             if (ks & 1) asm volatile("" ::: "memory");
;         }
	v_fma_f32 v21, v41, v52, v48
	v_add_f32_e32 v41, v21, v49
	v_lshlrev_b32_e32 v49, 16, v33
	v_lshlrev_b32_e32 v48, 16, v37
	v_mov_b32_e32 v51, v30
	v_lshlrev_b32_e32 v21, 16, v13
	v_pk_mul_f32 v[48:49], v[50:51], v[48:49]
	v_mov_b32_e32 v30, v23
	v_fma_f32 v21, v42, v21, v48
	v_add_f32_e32 v52, v21, v49
	v_and_b32_e32 v49, 0xffff0000, v33
	v_and_b32_e32 v48, 0xffff0000, v37
	v_and_b32_e32 v13, 0xffff0000, v13
	v_pk_mul_f32 v[22:23], v[30:31], v[48:49]
	v_pk_mul_f32 v[24:25], v[66:67], v[24:25] op_sel_hi:[0,1]
	v_fma_f32 v13, v43, v13, v22
	v_add_f32_e32 v53, v13, v23
	v_pk_mul_f32 v[22:23], v[66:67], v[26:27] op_sel_hi:[0,1]
	v_lshlrev_b32_e32 v27, 16, v34
	v_lshlrev_b32_e32 v26, 16, v38
	v_mov_b32_e32 v30, v16
	v_mov_b32_e32 v31, v24
	v_lshlrev_b32_e32 v13, 16, v14
	v_pk_mul_f32 v[26:27], v[30:31], v[26:27]
	v_mov_b32_e32 v24, v17
	s_waitcnt vmcnt(0)
	v_fma_f32 v13, v44, v13, v26
	v_add_f32_e32 v54, v13, v27
	v_and_b32_e32 v27, 0xffff0000, v34
	v_and_b32_e32 v26, 0xffff0000, v38
	v_and_b32_e32 v13, 0xffff0000, v14
	v_pk_mul_f32 v[16:17], v[24:25], v[26:27]
	v_pk_mul_f32 v[18:19], v[68:69], v[18:19] op_sel_hi:[0,1]
	v_fma_f32 v13, v45, v13, v16
	v_add_f32_e32 v55, v13, v17
	v_lshlrev_b32_e32 v17, 16, v35
	v_lshlrev_b32_e32 v16, 16, v39
	v_mov_b32_e32 v24, v18
	v_mov_b32_e32 v25, v22
	v_lshlrev_b32_e32 v13, 16, v15
	v_pk_mul_f32 v[16:17], v[24:25], v[16:17]
	v_and_b32_e32 v14, 0xffff0000, v39
	v_fma_f32 v13, v46, v13, v16
	v_add_f32_e32 v56, v13, v17
	v_and_b32_e32 v13, 0xffff0000, v15
	v_and_b32_e32 v15, 0xffff0000, v35
	v_mov_b32_e32 v22, v19
	v_pk_mul_f32 v[14:15], v[22:23], v[14:15]
	v_lshlrev_b32_e32 v16, 16, v12
	v_fma_f32 v14, v47, v13, v14
	v_lshlrev_b32_e32 v13, 16, v32
	v_lshlrev_b32_e32 v12, 16, v36
	v_mov_b32_e32 v21, v28
	v_pk_mul_f32 v[12:13], v[20:21], v[12:13]
	v_add_f32_e32 v57, v14, v15
	v_fma_f32 v12, v40, v16, v12
	v_add_f32_e32 v12, v12, v13
	v_add_f32_e32 v12, v12, v12
	v_mul_f32_e32 v24, 0x3fb8aa3b, v12
	v_add_u32_e32 v12, 0x980, v76
	v_ashrrev_i32_e32 v13, 31, v12
	v_exp_f32_e32 v38, v24
	v_lshlrev_b64 v[36:37], 2, v[12:13]
	v_lshl_add_u64 v[16:17], s[4:5], 0, v[36:37]
	v_lshlrev_b64 v[12:13], 1, v[12:13]
	v_lshl_add_u64 v[18:19], s[38:39], 0, v[36:37]
	global_load_dwordx4 v[20:23], v[16:17], off offset:16
	global_load_dwordx4 v[28:31], v[16:17], off
	global_load_dwordx4 v[32:35], v[18:19], off offset:16
	global_load_dwordx4 v[44:47], v[18:19], off
	v_lshl_add_u64 v[16:17], v[74:75], 0, v[12:13]
	v_lshl_add_u64 v[24:25], v[70:71], 0, v[12:13]
	v_lshl_add_u64 v[14:15], s[42:43], 0, v[36:37]
	global_load_dwordx4 v[16:19], v[16:17], off
	s_nop 0
	global_load_dwordx4 v[24:27], v[24:25], off
	v_add_f32_e32 v58, 1.0, v38
	global_load_dwordx4 v[36:39], v[14:15], off offset:16
	global_load_dwordx4 v[48:51], v[14:15], off
	v_add_f32_e32 v40, v41, v41
	v_lshl_add_u64 v[12:13], v[72:73], 0, v[12:13]
	v_mul_f32_e32 v14, 0x3fb8aa3b, v40
	global_load_dwordx4 v[40:43], v[12:13], off
	v_exp_f32_e32 v14, v14
	v_rcp_f32_e32 v12, v58
	v_add_f32_e32 v13, 1.0, v14
	v_add_f32_e32 v14, v52, v52
	v_mul_f32_e32 v14, 0x3fb8aa3b, v14
	v_exp_f32_e32 v15, v14
	v_add_f32_e32 v14, v53, v53
	v_mul_f32_e32 v14, 0x3fb8aa3b, v14
	v_exp_f32_e32 v52, v14
	v_rcp_f32_e32 v14, v13
	v_add_f32_e32 v13, 1.0, v15
	v_add_f32_e32 v53, v55, v55
	v_add_f32_e32 v15, 1.0, v52
	v_add_f32_e32 v52, v54, v54
	v_add_f32_e32 v54, v56, v56
	v_mul_f32_e32 v54, 0x3fb8aa3b, v54
	v_mul_f32_e32 v53, 0x3fb8aa3b, v53
	v_exp_f32_e32 v55, v54
	v_add_f32_e32 v54, v57, v57
	v_exp_f32_e32 v53, v53
	v_mul_f32_e32 v54, 0x3fb8aa3b, v54
	v_mul_f32_e32 v52, 0x3fb8aa3b, v52
	v_exp_f32_e32 v56, v54
	v_exp_f32_e32 v52, v52
	v_add_f32_e32 v53, 1.0, v53
	v_rcp_f32_e32 v54, v53
	v_add_f32_e32 v53, 1.0, v55
	v_add_f32_e32 v55, 1.0, v56
	v_rcp_f32_e32 v15, v15
	v_add_f32_e32 v52, 1.0, v52
	v_rcp_f32_e32 v55, v55
	v_rcp_f32_e32 v13, v13
	v_rcp_f32_e32 v52, v52
	v_rcp_f32_e32 v53, v53
	v_pk_fma_f32 v[14:15], v[14:15], 2.0, 1.0 op_sel_hi:[1,0,0] neg_lo:[1,0,0] neg_hi:[1,0,0]
	v_pk_fma_f32 v[54:55], v[54:55], 2.0, 1.0 op_sel_hi:[1,0,0] neg_lo:[1,0,0] neg_hi:[1,0,0]
	v_pk_fma_f32 v[12:13], v[12:13], 2.0, 1.0 op_sel_hi:[1,0,0] neg_lo:[1,0,0] neg_hi:[1,0,0]
	v_pk_fma_f32 v[52:53], v[52:53], 2.0, 1.0 op_sel_hi:[1,0,0] neg_lo:[1,0,0] neg_hi:[1,0,0]
	v_bfe_u32 v56, v55, 16, 1
	v_bfe_u32 v57, v54, 16, 1
	v_bfe_u32 v58, v15, 16, 1
	v_bfe_u32 v59, v14, 16, 1
	v_add3_u32 v59, v14, v59, s61
	v_add3_u32 v58, v15, v58, s61
	v_add3_u32 v14, v54, v57, s61
	v_add3_u32 v15, v55, v56, s61
	v_bfe_u32 v54, v12, 16, 1
	v_bfe_u32 v55, v13, 16, 1
	v_bfe_u32 v56, v52, 16, 1
	v_bfe_u32 v57, v53, 16, 1
	v_add3_u32 v53, v53, v57, s61
	v_add3_u32 v52, v52, v56, s61
	v_add3_u32 v13, v13, v55, s61
	v_add3_u32 v12, v12, v54, s61
	v_lshrrev_b32_e32 v12, 16, v12
	v_lshrrev_b32_e32 v13, 16, v13
	v_lshrrev_b32_e32 v52, 16, v52
	v_lshrrev_b32_e32 v53, 16, v53
	v_and_or_b32 v15, v15, s60, v53
	v_and_or_b32 v14, v14, s60, v52
	v_and_or_b32 v13, v58, s60, v13
	v_and_or_b32 v12, v59, s60, v12
	s_waitcnt vmcnt(8)
	v_pk_mul_f32 v[108:109], v[68:69], v[22:23] op_sel_hi:[0,1]
	s_waitcnt vmcnt(7)
	v_pk_mul_f32 v[64:65], v[68:69], v[30:31] op_sel_hi:[0,1]
	v_pk_mul_f32 v[86:87], v[68:69], v[28:29] op_sel_hi:[0,1]
	v_pk_mul_f32 v[110:111], v[68:69], v[20:21] op_sel_hi:[0,1]
	v_mov_b32_e32 v22, v86
	v_mov_b32_e32 v23, v64
	s_waitcnt vmcnt(4)
	v_lshlrev_b32_e32 v29, 16, v17
	v_lshlrev_b32_e32 v28, 16, v16
	s_waitcnt vmcnt(3)
	v_lshlrev_b32_e32 v21, 16, v25
	s_waitcnt vmcnt(1)
; __device__ __forceinline__ unsigned pk2(float lo, float hi) { return f2bf(lo) | (f2bf(hi) << 16); }
; __device__ __forceinline__ float sigmoid_f(float x) { return __builtin_amdgcn_rcpf(1.f + __expf(-x)); }
; __device__ __forceinline__ float tanh_f(float x) { const float e = __expf(2.f * x); return 1.f - 2.f * __builtin_amdgcn_rcpf(e + 1.f); }
; __device__ __forceinline__ void rwkv_proj_phase(const bf16* Z, const float* shift, const float* w0, const float* a0, const float* kkp, const float* kap, const float* rkp, ...
;     ...
;         bf16x8 xf[12];
; #pragma unroll
;         for (int ks = 0; ks < 12; ++ks) {
;             const int col = 2304 + 32 * ks + 8 * g;
;             const u32x4 c0 = *(const u32x4*)(zr + col), cm = *(const u32x4*)(zr + offm + col), cp = *(const u32x4*)(zr + offp + col);
;             float val[8];
; #pragma unroll
;             for (int q = 0; q < 2; ++q) { const f32x4 t0 = *(const f32x4*)(shift + col + 4 * q) * fm, t1 = *(const f32x4*)(shift + BCOLS + col + 4 * q), t2 = *(const f32x4*)(shift + 2 * BCOLS + col + 4 * q) * fn;
;                 const unsigned m0 = q ? cm.z : cm.x, m1 = q ? cm.w : cm.y, z0 = q ? c0.z : c0.x, z1 = q ? c0.w : c0.y, p0 = q ? cp.z : cp.x, p1 = q ? cp.w : cp.y;
;                 val[4 * q + 0] = t0.x * bflo(m0) + t1.x * bflo(z0) + t2.x * bflo(p0);
;                 val[4 * q + 1] = t0.y * bfhi(m0) + t1.y * bfhi(z0) + t2.y * bfhi(p0);
;                 val[4 * q + 2] = t0.z * bflo(m1) + t1.z * bflo(z1) + t2.z * bflo(p1);
;                 val[4 * q + 3] = t0.w * bfhi(m1) + t1.w * bfhi(z1) + t2.w * bfhi(p1); }
; #pragma unroll
;             for (int e = 0; e < 8; ++e) { if (ks < 4) val[e] = tanh_f(val[e]); else if (ks >= 8) val[e] = sigmoid_f(val[e]); }
;             u32x4 pk; pk.x = pk2(val[0], val[1]); pk.y = pk2(val[2], val[3]); pk.z = pk2(val[4], val[5]); pk.w = pk2(val[6], val[7]);
;             xf[ks] = __builtin_bit_cast(bf16x8, pk);
;             if (ks & 1) asm volatile("" ::: "memory");
;         }
	v_mov_b32_e32 v30, v48
	v_mov_b32_e32 v31, v50
	v_lshlrev_b32_e32 v20, 16, v24
	v_pk_mul_f32 v[28:29], v[30:31], v[28:29]
	v_pk_mul_f32 v[114:115], v[66:67], v[32:33] op_sel_hi:[0,1]
	v_pk_fma_f32 v[32:33], v[22:23], v[20:21], v[28:29]
	v_add_u32_e32 v20, 0x9a0, v76
	v_ashrrev_i32_e32 v21, 31, v20
	v_pk_mul_f32 v[106:107], v[66:67], v[44:45] op_sel_hi:[0,1]
	v_lshlrev_b64 v[44:45], 2, v[20:21]
	v_pk_mul_f32 v[104:105], v[66:67], v[46:47] op_sel_hi:[0,1]
	v_lshl_add_u64 v[22:23], s[4:5], 0, v[44:45]
	v_lshl_add_u64 v[28:29], s[38:39], 0, v[44:45]
	v_lshlrev_b64 v[46:47], 1, v[20:21]
	v_pk_mul_f32 v[112:113], v[66:67], v[34:35] op_sel_hi:[0,1]
	s_waitcnt vmcnt(0)
	v_lshlrev_b32_e32 v35, 16, v41
	global_load_dwordx4 v[52:55], v[22:23], off offset:16
	global_load_dwordx4 v[56:59], v[22:23], off
	global_load_dwordx4 v[60:63], v[28:29], off offset:16
	global_load_dwordx4 v[78:81], v[28:29], off
	v_lshlrev_b32_e32 v34, 16, v40
	v_lshl_add_u64 v[20:21], v[74:75], 0, v[46:47]
	v_lshl_add_u64 v[28:29], v[70:71], 0, v[46:47]
	v_mov_b32_e32 v82, v106
	v_mov_b32_e32 v83, v104
	v_lshl_add_u64 v[44:45], s[42:43], 0, v[44:45]
	global_load_dwordx4 v[20:23], v[20:21], off
	s_nop 0
	global_load_dwordx4 v[28:31], v[28:29], off
	v_pk_fma_f32 v[116:117], v[82:83], v[34:35], v[32:33]
	global_load_dwordx4 v[32:35], v[44:45], off offset:16
	global_load_dwordx4 v[82:85], v[44:45], off
	v_lshl_add_u64 v[44:45], v[72:73], 0, v[46:47]
	global_load_dwordx4 v[44:47], v[44:45], off
	v_and_b32_e32 v17, 0xffff0000, v17
	v_and_b32_e32 v16, 0xffff0000, v16
	v_mov_b32_e32 v50, v49
	v_and_b32_e32 v25, 0xffff0000, v25
	v_and_b32_e32 v24, 0xffff0000, v24
	v_mov_b32_e32 v64, v87
	v_pk_mul_f32 v[16:17], v[50:51], v[16:17]
	v_mov_b32_e32 v104, v107
	v_pk_fma_f32 v[16:17], v[64:65], v[24:25], v[16:17]
	v_and_b32_e32 v25, 0xffff0000, v41
	v_and_b32_e32 v24, 0xffff0000, v40
	v_lshlrev_b32_e32 v49, 16, v19
	v_lshlrev_b32_e32 v48, 16, v18
	v_mov_b32_e32 v50, v36
	v_mov_b32_e32 v51, v38
	v_and_b32_e32 v19, 0xffff0000, v19
	v_and_b32_e32 v18, 0xffff0000, v18
	v_mov_b32_e32 v38, v37
	v_pk_fma_f32 v[16:17], v[104:105], v[24:25], v[16:17]
	v_lshlrev_b32_e32 v25, 16, v27
	v_lshlrev_b32_e32 v24, 16, v26
	v_mov_b32_e32 v40, v110
	v_mov_b32_e32 v41, v108
	v_pk_mul_f32 v[48:49], v[50:51], v[48:49]
	v_and_b32_e32 v27, 0xffff0000, v27
	v_and_b32_e32 v26, 0xffff0000, v26
	v_mov_b32_e32 v108, v111
	v_pk_mul_f32 v[18:19], v[38:39], v[18:19]
	v_pk_fma_f32 v[24:25], v[40:41], v[24:25], v[48:49]
	v_mov_b32_e32 v49, v112
	v_pk_fma_f32 v[18:19], v[108:109], v[26:27], v[18:19]
	v_and_b32_e32 v27, 0xffff0000, v43
	v_and_b32_e32 v26, 0xffff0000, v42
	v_mov_b32_e32 v112, v115
	v_lshlrev_b32_e32 v41, 16, v43
	v_lshlrev_b32_e32 v40, 16, v42
	v_mov_b32_e32 v48, v114
	v_pk_fma_f32 v[18:19], v[112:113], v[26:27], v[18:19]
	v_pk_fma_f32 v[24:25], v[48:49], v[40:41], v[24:25]
	v_cvt_pk_bf16_f32 v19, v25, v19
	v_cvt_pk_bf16_f32 v18, v24, v18
	v_cvt_pk_bf16_f32 v17, v117, v17
	v_cvt_pk_bf16_f32 v16, v116, v16
	s_waitcnt vmcnt(8)
	v_pk_mul_f32 v[112:113], v[68:69], v[54:55] op_sel_hi:[0,1]
	s_waitcnt vmcnt(7)
	v_pk_mul_f32 v[64:65], v[68:69], v[58:59] op_sel_hi:[0,1]
	v_pk_mul_f32 v[86:87], v[68:69], v[56:57] op_sel_hi:[0,1]
	v_mov_b32_e32 v26, v86
	v_mov_b32_e32 v27, v64
	s_waitcnt vmcnt(5)
	v_pk_mul_f32 v[108:109], v[66:67], v[80:81] op_sel_hi:[0,1]
	v_pk_mul_f32 v[110:111], v[66:67], v[78:79] op_sel_hi:[0,1]
	v_pk_mul_f32 v[114:115], v[68:69], v[52:53] op_sel_hi:[0,1]
	v_pk_mul_f32 v[116:117], v[66:67], v[62:63] op_sel_hi:[0,1]
	s_waitcnt vmcnt(4)
	v_lshlrev_b32_e32 v37, 16, v21
	v_lshlrev_b32_e32 v36, 16, v20
	s_waitcnt vmcnt(3)
	v_lshlrev_b32_e32 v25, 16, v29
	s_waitcnt vmcnt(1)
	v_mov_b32_e32 v38, v82
	v_mov_b32_e32 v39, v84
	v_lshlrev_b32_e32 v24, 16, v28
	v_pk_mul_f32 v[36:37], v[38:39], v[36:37]
	v_pk_mul_f32 v[118:119], v[66:67], v[60:61] op_sel_hi:[0,1]
	v_pk_fma_f32 v[40:41], v[26:27], v[24:25], v[36:37]
	v_add_u32_e32 v24, 0x9c0, v76
	v_ashrrev_i32_e32 v25, 31, v24
	v_lshlrev_b64 v[48:49], 2, v[24:25]
	v_lshl_add_u64 v[26:27], s[4:5], 0, v[48:49]
	v_lshl_add_u64 v[36:37], s[38:39], 0, v[48:49]
	v_lshlrev_b64 v[50:51], 1, v[24:25]
	s_waitcnt vmcnt(0)
	v_lshlrev_b32_e32 v43, 16, v45
	global_load_dwordx4 v[52:55], v[26:27], off offset:16
	global_load_dwordx4 v[56:59], v[26:27], off
	global_load_dwordx4 v[60:63], v[36:37], off offset:16
	global_load_dwordx4 v[78:81], v[36:37], off
	v_lshlrev_b32_e32 v42, 16, v44
	v_lshl_add_u64 v[24:25], v[74:75], 0, v[50:51]
	v_lshl_add_u64 v[36:37], v[70:71], 0, v[50:51]
	v_mov_b32_e32 v104, v110
	v_mov_b32_e32 v105, v108
	v_lshl_add_u64 v[48:49], s[42:43], 0, v[48:49]
	global_load_dwordx4 v[24:27], v[24:25], off
	s_nop 0
	global_load_dwordx4 v[36:39], v[36:37], off
	v_pk_fma_f32 v[120:121], v[104:105], v[42:43], v[40:41]
	global_load_dwordx4 v[40:43], v[48:49], off offset:16
	global_load_dwordx4 v[104:107], v[48:49], off
	v_lshl_add_u64 v[48:49], v[72:73], 0, v[50:51]
	global_load_dwordx4 v[48:51], v[48:49], off
	v_and_b32_e32 v21, 0xffff0000, v21
	v_and_b32_e32 v20, 0xffff0000, v20
	v_mov_b32_e32 v84, v83
	v_and_b32_e32 v29, 0xffff0000, v29
	v_and_b32_e32 v28, 0xffff0000, v28
	v_mov_b32_e32 v64, v87
	v_pk_mul_f32 v[20:21], v[84:85], v[20:21]
	v_mov_b32_e32 v108, v111
	v_pk_fma_f32 v[20:21], v[64:65], v[28:29], v[20:21]
	v_and_b32_e32 v29, 0xffff0000, v45
	v_and_b32_e32 v28, 0xffff0000, v44
	v_lshlrev_b32_e32 v65, 16, v23
	v_lshlrev_b32_e32 v64, 16, v22
	v_mov_b32_e32 v82, v32
	v_mov_b32_e32 v83, v34
	v_and_b32_e32 v23, 0xffff0000, v23
	v_and_b32_e32 v22, 0xffff0000, v22
	v_mov_b32_e32 v34, v33
	v_pk_fma_f32 v[20:21], v[108:109], v[28:29], v[20:21]
	v_lshlrev_b32_e32 v29, 16, v31
	v_lshlrev_b32_e32 v28, 16, v30
	v_mov_b32_e32 v44, v114
	v_mov_b32_e32 v45, v112
	v_pk_mul_f32 v[64:65], v[82:83], v[64:65]
	v_and_b32_e32 v31, 0xffff0000, v31
	v_and_b32_e32 v30, 0xffff0000, v30
	v_mov_b32_e32 v112, v115
	v_pk_mul_f32 v[22:23], v[34:35], v[22:23]
	v_pk_fma_f32 v[28:29], v[44:45], v[28:29], v[64:65]
	v_mov_b32_e32 v65, v116
	v_pk_fma_f32 v[22:23], v[112:113], v[30:31], v[22:23]
	v_and_b32_e32 v31, 0xffff0000, v47
	v_and_b32_e32 v30, 0xffff0000, v46
	v_mov_b32_e32 v116, v119
	v_lshlrev_b32_e32 v45, 16, v47
	v_lshlrev_b32_e32 v44, 16, v46
	v_mov_b32_e32 v64, v118
	v_pk_fma_f32 v[22:23], v[116:117], v[30:31], v[22:23]
	v_pk_fma_f32 v[28:29], v[64:65], v[44:45], v[28:29]
	v_cvt_pk_bf16_f32 v23, v29, v23
	v_cvt_pk_bf16_f32 v22, v28, v22
	v_cvt_pk_bf16_f32 v21, v121, v21
	v_cvt_pk_bf16_f32 v20, v120, v20
	s_waitcnt vmcnt(8)
; __device__ __forceinline__ unsigned pk2(float lo, float hi) { return f2bf(lo) | (f2bf(hi) << 16); }
; __device__ __forceinline__ float sigmoid_f(float x) { return __builtin_amdgcn_rcpf(1.f + __expf(-x)); }
; __device__ __forceinline__ float tanh_f(float x) { const float e = __expf(2.f * x); return 1.f - 2.f * __builtin_amdgcn_rcpf(e + 1.f); }
; __device__ __forceinline__ void rwkv_proj_phase(const bf16* Z, const float* shift, const float* w0, const float* a0, const float* kkp, const float* kap, const float* rkp, ...
;     ...
;         bf16x8 xf[12];
; #pragma unroll
;         for (int ks = 0; ks < 12; ++ks) {
;             const int col = 2304 + 32 * ks + 8 * g;
;             const u32x4 c0 = *(const u32x4*)(zr + col), cm = *(const u32x4*)(zr + offm + col), cp = *(const u32x4*)(zr + offp + col);
;             float val[8];
; #pragma unroll
;             for (int q = 0; q < 2; ++q) { const f32x4 t0 = *(const f32x4*)(shift + col + 4 * q) * fm, t1 = *(const f32x4*)(shift + BCOLS + col + 4 * q), t2 = *(const f32x4*)(shift + 2 * BCOLS + col + 4 * q) * fn;
;                 const unsigned m0 = q ? cm.z : cm.x, m1 = q ? cm.w : cm.y, z0 = q ? c0.z : c0.x, z1 = q ? c0.w : c0.y, p0 = q ? cp.z : cp.x, p1 = q ? cp.w : cp.y;
;                 val[4 * q + 0] = t0.x * bflo(m0) + t1.x * bflo(z0) + t2.x * bflo(p0);
;                 val[4 * q + 1] = t0.y * bfhi(m0) + t1.y * bfhi(z0) + t2.y * bfhi(p0);
;                 val[4 * q + 2] = t0.z * bflo(m1) + t1.z * bflo(z1) + t2.z * bflo(p1);
;                 val[4 * q + 3] = t0.w * bfhi(m1) + t1.w * bfhi(z1) + t2.w * bfhi(p1); }
; #pragma unroll
;             for (int e = 0; e < 8; ++e) { if (ks < 4) val[e] = tanh_f(val[e]); else if (ks >= 8) val[e] = sigmoid_f(val[e]); }
;             u32x4 pk; pk.x = pk2(val[0], val[1]); pk.y = pk2(val[2], val[3]); pk.z = pk2(val[4], val[5]); pk.w = pk2(val[6], val[7]);
;             xf[ks] = __builtin_bit_cast(bf16x8, pk);
;             if (ks & 1) asm volatile("" ::: "memory");
;         }
	v_pk_mul_f32 v[112:113], v[68:69], v[54:55] op_sel_hi:[0,1]
	s_waitcnt vmcnt(7)
	v_pk_mul_f32 v[86:87], v[68:69], v[58:59] op_sel_hi:[0,1]
	v_pk_mul_f32 v[56:57], v[68:69], v[56:57] op_sel_hi:[0,1]
	v_mov_b32_e32 v30, v56
	v_mov_b32_e32 v31, v86
	s_waitcnt vmcnt(6)
	v_pk_mul_f32 v[116:117], v[66:67], v[62:63] op_sel_hi:[0,1]
	s_waitcnt vmcnt(5)
	v_pk_mul_f32 v[108:109], v[66:67], v[80:81] op_sel_hi:[0,1]
	v_pk_mul_f32 v[110:111], v[66:67], v[78:79] op_sel_hi:[0,1]
	v_pk_mul_f32 v[114:115], v[68:69], v[52:53] op_sel_hi:[0,1]
	s_waitcnt vmcnt(4)
	v_lshlrev_b32_e32 v33, 16, v25
	v_lshlrev_b32_e32 v32, 16, v24
	s_waitcnt vmcnt(3)
	v_lshlrev_b32_e32 v29, 16, v37
	s_waitcnt vmcnt(1)
	v_mov_b32_e32 v34, v104
	v_mov_b32_e32 v35, v106
	v_lshlrev_b32_e32 v28, 16, v36
	v_pk_mul_f32 v[32:33], v[34:35], v[32:33]
	s_waitcnt vmcnt(0)
	v_lshlrev_b32_e32 v65, 16, v49
	v_pk_fma_f32 v[62:63], v[30:31], v[28:29], v[32:33]
	v_add_u32_e32 v28, 0x9e0, v76
	v_ashrrev_i32_e32 v29, 31, v28
	v_lshlrev_b64 v[82:83], 2, v[28:29]
	v_lshl_add_u64 v[30:31], s[4:5], 0, v[82:83]
	v_lshl_add_u64 v[58:59], s[38:39], 0, v[82:83]
	global_load_dwordx4 v[32:35], v[30:31], off offset:16
	global_load_dwordx4 v[44:47], v[30:31], off
	global_load_dwordx4 v[52:55], v[58:59], off offset:16
	global_load_dwordx4 v[78:81], v[58:59], off
	v_lshlrev_b64 v[120:121], 1, v[28:29]
	v_lshlrev_b32_e32 v64, 16, v48
	v_lshl_add_u64 v[28:29], v[74:75], 0, v[120:121]
	v_lshl_add_u64 v[58:59], v[70:71], 0, v[120:121]
	v_mov_b32_e32 v84, v110
	v_mov_b32_e32 v85, v108
	v_lshl_add_u64 v[82:83], s[42:43], 0, v[82:83]
	v_pk_mul_f32 v[118:119], v[66:67], v[60:61] op_sel_hi:[0,1]
	global_load_dwordx4 v[28:31], v[28:29], off
	s_nop 0
	global_load_dwordx4 v[58:61], v[58:59], off
	v_pk_fma_f32 v[122:123], v[84:85], v[64:65], v[62:63]
	global_load_dwordx4 v[62:65], v[82:83], off offset:16
	s_nop 0
	global_load_dwordx4 v[82:85], v[82:83], off
	v_and_b32_e32 v25, 0xffff0000, v25
	v_and_b32_e32 v24, 0xffff0000, v24
	v_mov_b32_e32 v106, v105
	v_and_b32_e32 v37, 0xffff0000, v37
	v_and_b32_e32 v36, 0xffff0000, v36
	v_mov_b32_e32 v86, v57
	v_pk_mul_f32 v[24:25], v[106:107], v[24:25]
	v_mov_b32_e32 v108, v111
	v_pk_fma_f32 v[24:25], v[86:87], v[36:37], v[24:25]
	v_and_b32_e32 v37, 0xffff0000, v49
	v_and_b32_e32 v36, 0xffff0000, v48
	v_lshlrev_b32_e32 v57, 16, v27
	v_lshlrev_b32_e32 v56, 16, v26
	v_mov_b32_e32 v86, v40
	v_mov_b32_e32 v87, v42
	v_pk_fma_f32 v[24:25], v[108:109], v[36:37], v[24:25]
	v_lshlrev_b32_e32 v37, 16, v39
	v_lshlrev_b32_e32 v36, 16, v38
	v_mov_b32_e32 v48, v114
	v_mov_b32_e32 v49, v112
	v_pk_mul_f32 v[56:57], v[86:87], v[56:57]
	v_and_b32_e32 v27, 0xffff0000, v27
	v_pk_fma_f32 v[36:37], v[48:49], v[36:37], v[56:57]
	v_lshl_add_u64 v[48:49], v[72:73], 0, v[120:121]
	global_load_dwordx4 v[104:107], v[48:49], off
	v_and_b32_e32 v26, 0xffff0000, v26
	v_mov_b32_e32 v42, v41
	v_lshlrev_b32_e32 v49, 16, v51
	v_lshlrev_b32_e32 v48, 16, v50
	v_mov_b32_e32 v56, v118
	v_mov_b32_e32 v57, v116
	v_and_b32_e32 v39, 0xffff0000, v39
	v_and_b32_e32 v38, 0xffff0000, v38
	v_mov_b32_e32 v112, v115
	v_pk_mul_f32 v[26:27], v[42:43], v[26:27]
	v_pk_fma_f32 v[36:37], v[56:57], v[48:49], v[36:37]
	v_pk_fma_f32 v[26:27], v[112:113], v[38:39], v[26:27]
	v_and_b32_e32 v39, 0xffff0000, v51
	v_and_b32_e32 v38, 0xffff0000, v50
	v_mov_b32_e32 v116, v119
	v_bfe_u32 v41, v24, 16, 1
	v_pk_fma_f32 v[26:27], v[116:117], v[38:39], v[26:27]
	v_add3_u32 v24, v24, v41, s61
	v_cvt_pk_bf16_f32 v27, v37, v27
	v_cvt_pk_bf16_f32 v26, v36, v26
	v_bfe_u32 v38, v122, 16, 1
	v_add3_u32 v38, v122, v38, s61
	v_lshrrev_b32_e32 v38, 16, v38
	v_cvt_pk_bf16_f32 v25, v123, v25
	s_waitcnt vmcnt(8)
	v_pk_mul_f32 v[124:125], v[68:69], v[32:33] op_sel_hi:[0,1]
	s_waitcnt vmcnt(7)
	v_pk_mul_f32 v[42:43], v[68:69], v[44:45] op_sel_hi:[0,1]
	v_add_u32_e32 v44, 0xa00, v76
	v_ashrrev_i32_e32 v45, 31, v44
	v_pk_mul_f32 v[36:37], v[68:69], v[46:47] op_sel_hi:[0,1]
	v_lshlrev_b64 v[46:47], 1, v[44:45]
	v_lshlrev_b64 v[116:117], 2, v[44:45]
	v_lshl_add_u64 v[32:33], v[74:75], 0, v[46:47]
	v_lshl_add_u64 v[44:45], s[4:5], 0, v[116:117]
	s_waitcnt vmcnt(5)
	v_pk_mul_f32 v[86:87], v[66:67], v[80:81] op_sel_hi:[0,1]
	v_pk_mul_f32 v[120:121], v[66:67], v[78:79] op_sel_hi:[0,1]
	v_pk_mul_f32 v[122:123], v[68:69], v[34:35] op_sel_hi:[0,1]
	v_pk_mul_f32 v[126:127], v[66:67], v[54:55] op_sel_hi:[0,1]
	global_load_dwordx4 v[32:35], v[32:33], off
	v_lshl_add_u64 v[54:55], s[38:39], 0, v[116:117]
	global_load_dwordx4 v[48:51], v[44:45], off offset:16
	global_load_dwordx4 v[78:81], v[44:45], off
	global_load_dwordx4 v[108:111], v[54:55], off offset:16
	global_load_dwordx4 v[112:115], v[54:55], off
	v_lshl_add_u64 v[44:45], v[70:71], 0, v[46:47]
	v_lshl_add_u64 v[46:47], v[72:73], 0, v[46:47]
	global_load_dwordx4 v[54:57], v[46:47], off
	s_nop 0
	global_load_dwordx4 v[44:47], v[44:45], off
	v_and_or_b32 v24, v24, s60, v38
	s_waitcnt vmcnt(11)
	v_lshlrev_b32_e32 v39, 16, v29
	v_lshlrev_b32_e32 v38, 16, v28
	s_waitcnt vmcnt(8)
	v_mov_b32_e32 v40, v82
	v_mov_b32_e32 v41, v84
	v_lshl_add_u64 v[116:117], s[42:43], 0, v[116:117]
	v_pk_mul_f32 v[132:133], v[40:41], v[38:39]
	global_load_dwordx4 v[38:41], v[116:117], off offset:16
	s_nop 0
	global_load_dwordx4 v[116:119], v[116:117], off
	v_and_b32_e32 v29, 0xffff0000, v29
	v_and_b32_e32 v28, 0xffff0000, v28
	v_mov_b32_e32 v84, v83
	v_lshlrev_b32_e32 v129, 16, v59
	v_lshlrev_b32_e32 v128, 16, v58
	v_mov_b32_e32 v130, v42
	v_mov_b32_e32 v131, v36
	v_and_b32_e32 v59, 0xffff0000, v59
	v_and_b32_e32 v58, 0xffff0000, v58
	v_mov_b32_e32 v36, v43
	v_pk_mul_f32 v[28:29], v[84:85], v[28:29]
	v_pk_fma_f32 v[128:129], v[130:131], v[128:129], v[132:133]
	v_mov_b32_e32 v133, v86
	v_pk_fma_f32 v[28:29], v[36:37], v[58:59], v[28:29]
	s_waitcnt vmcnt(9)
; __device__ __forceinline__ unsigned pk2(float lo, float hi) { return f2bf(lo) | (f2bf(hi) << 16); }
; __device__ __forceinline__ float sigmoid_f(float x) { return __builtin_amdgcn_rcpf(1.f + __expf(-x)); }
; __device__ __forceinline__ float tanh_f(float x) { const float e = __expf(2.f * x); return 1.f - 2.f * __builtin_amdgcn_rcpf(e + 1.f); }
; __device__ __forceinline__ void rwkv_proj_phase(const bf16* Z, const float* shift, const float* w0, const float* a0, const float* kkp, const float* kap, const float* rkp, ...
;     ...
;         bf16x8 xf[12];
; #pragma unroll
;         for (int ks = 0; ks < 12; ++ks) {
;             const int col = 2304 + 32 * ks + 8 * g;
;             const u32x4 c0 = *(const u32x4*)(zr + col), cm = *(const u32x4*)(zr + offm + col), cp = *(const u32x4*)(zr + offp + col);
;             float val[8];
; #pragma unroll
;             for (int q = 0; q < 2; ++q) { const f32x4 t0 = *(const f32x4*)(shift + col + 4 * q) * fm, t1 = *(const f32x4*)(shift + BCOLS + col + 4 * q), t2 = *(const f32x4*)(shift + 2 * BCOLS + col + 4 * q) * fn;
;                 const unsigned m0 = q ? cm.z : cm.x, m1 = q ? cm.w : cm.y, z0 = q ? c0.z : c0.x, z1 = q ? c0.w : c0.y, p0 = q ? cp.z : cp.x, p1 = q ? cp.w : cp.y;
;                 val[4 * q + 0] = t0.x * bflo(m0) + t1.x * bflo(z0) + t2.x * bflo(p0);
;                 val[4 * q + 1] = t0.y * bfhi(m0) + t1.y * bfhi(z0) + t2.y * bfhi(p0);
;                 val[4 * q + 2] = t0.z * bflo(m1) + t1.z * bflo(z1) + t2.z * bflo(p1);
;                 val[4 * q + 3] = t0.w * bfhi(m1) + t1.w * bfhi(z1) + t2.w * bfhi(p1); }
; #pragma unroll
;             for (int e = 0; e < 8; ++e) { if (ks < 4) val[e] = tanh_f(val[e]); else if (ks >= 8) val[e] = sigmoid_f(val[e]); }
;             u32x4 pk; pk.x = pk2(val[0], val[1]); pk.y = pk2(val[2], val[3]); pk.z = pk2(val[4], val[5]); pk.w = pk2(val[6], val[7]);
;             xf[ks] = __builtin_bit_cast(bf16x8, pk);
;             if (ks & 1) asm volatile("" ::: "memory");
;         }
	v_and_b32_e32 v37, 0xffff0000, v105
	v_and_b32_e32 v36, 0xffff0000, v104
	v_mov_b32_e32 v86, v121
	v_lshlrev_b32_e32 v59, 16, v31
	v_lshlrev_b32_e32 v58, 16, v30
	v_mov_b32_e32 v82, v62
	v_mov_b32_e32 v83, v64
	v_pk_mul_f32 v[52:53], v[66:67], v[52:53] op_sel_hi:[0,1]
	v_pk_fma_f32 v[28:29], v[86:87], v[36:37], v[28:29]
	v_lshlrev_b32_e32 v37, 16, v61
	v_lshlrev_b32_e32 v36, 16, v60
	v_mov_b32_e32 v42, v124
	v_mov_b32_e32 v43, v122
	v_pk_mul_f32 v[58:59], v[82:83], v[58:59]
	v_and_b32_e32 v31, 0xffff0000, v31
	v_pk_fma_f32 v[36:37], v[42:43], v[36:37], v[58:59]
	v_lshlrev_b32_e32 v43, 16, v107
	v_lshlrev_b32_e32 v42, 16, v106
	v_mov_b32_e32 v58, v52
	v_mov_b32_e32 v59, v126
	v_and_b32_e32 v30, 0xffff0000, v30
	v_mov_b32_e32 v64, v63
	v_pk_fma_f32 v[36:37], v[58:59], v[42:43], v[36:37]
	v_and_b32_e32 v43, 0xffff0000, v61
	v_and_b32_e32 v42, 0xffff0000, v60
	v_mov_b32_e32 v122, v125
	v_pk_mul_f32 v[30:31], v[64:65], v[30:31]
	v_mov_b32_e32 v126, v53
	v_pk_fma_f32 v[30:31], v[122:123], v[42:43], v[30:31]
	v_and_b32_e32 v43, 0xffff0000, v107
	v_and_b32_e32 v42, 0xffff0000, v106
	v_lshlrev_b32_e32 v131, 16, v105
	v_lshlrev_b32_e32 v130, 16, v104
	v_mov_b32_e32 v132, v120
	v_pk_fma_f32 v[30:31], v[126:127], v[42:43], v[30:31]
	v_pk_fma_f32 v[128:129], v[132:133], v[130:131], v[128:129]
	v_cvt_pk_bf16_f32 v29, v129, v29
	v_cvt_pk_bf16_f32 v28, v128, v28
	s_waitcnt vmcnt(6)
	v_pk_mul_f32 v[42:43], v[68:69], v[78:79] op_sel_hi:[0,1]
	v_mov_b32_e32 v62, v42
	s_waitcnt vmcnt(4)
	v_pk_mul_f32 v[58:59], v[66:67], v[112:113] op_sel_hi:[0,1]
	v_mov_b32_e32 v63, v58
	s_waitcnt vmcnt(3)
	v_lshlrev_b32_e32 v61, 16, v54
	s_waitcnt vmcnt(2)
	v_lshlrev_b32_e32 v60, 16, v44
	v_lshlrev_b32_e32 v64, 16, v32
	v_pk_mul_f32 v[60:61], v[62:63], v[60:61]
	v_mov_b32_e32 v58, v43
	s_waitcnt vmcnt(0)
	v_fma_f32 v42, v116, v64, v60
	v_add_f32_e32 v77, v42, v61
	v_and_b32_e32 v61, 0xffff0000, v54
	v_and_b32_e32 v60, 0xffff0000, v44
	v_and_b32_e32 v32, 0xffff0000, v32
	v_pk_mul_f32 v[42:43], v[58:59], v[60:61]
	v_cvt_pk_bf16_f32 v31, v37, v31
	v_cvt_pk_bf16_f32 v30, v36, v30
	v_pk_mul_f32 v[36:37], v[68:69], v[80:81] op_sel_hi:[0,1]
	v_pk_mul_f32 v[52:53], v[66:67], v[114:115] op_sel_hi:[0,1]
	v_fma_f32 v32, v117, v32, v42
	v_add_f32_e32 v88, v32, v43
	v_lshlrev_b32_e32 v43, 16, v55
	v_lshlrev_b32_e32 v42, 16, v45
	v_mov_b32_e32 v58, v36
	v_mov_b32_e32 v59, v52
	v_lshlrev_b32_e32 v32, 16, v33
	v_pk_mul_f32 v[42:43], v[58:59], v[42:43]
	v_and_b32_e32 v36, 0xffff0000, v33
	v_fma_f32 v32, v118, v32, v42
	v_add_f32_e32 v112, v32, v43
	v_and_b32_e32 v33, 0xffff0000, v55
	v_and_b32_e32 v32, 0xffff0000, v45
	v_mov_b32_e32 v52, v37
	v_pk_mul_f32 v[32:33], v[52:53], v[32:33]
	v_pk_mul_f32 v[42:43], v[66:67], v[108:109] op_sel_hi:[0,1]
	v_fma_f32 v32, v119, v36, v32
	v_pk_mul_f32 v[36:37], v[68:69], v[48:49] op_sel_hi:[0,1]
	v_lshlrev_b32_e32 v45, 16, v56
	v_lshlrev_b32_e32 v44, 16, v46
	v_mov_b32_e32 v48, v36
	v_mov_b32_e32 v49, v42
	v_add_f32_e32 v113, v32, v33
	v_pk_mul_f32 v[32:33], v[68:69], v[50:51] op_sel_hi:[0,1]
	v_lshlrev_b32_e32 v50, 16, v34
	v_pk_mul_f32 v[44:45], v[48:49], v[44:45]
	v_mov_b32_e32 v42, v37
	v_fma_f32 v36, v38, v50, v44
	v_add_f32_e32 v114, v36, v45
	v_and_b32_e32 v45, 0xffff0000, v56
	v_and_b32_e32 v44, 0xffff0000, v46
	v_pk_mul_f32 v[36:37], v[42:43], v[44:45]
	v_add_u32_e32 v42, 0xa20, v76
	v_and_b32_e32 v34, 0xffff0000, v34
	v_ashrrev_i32_e32 v43, 31, v42
	v_fma_f32 v34, v39, v34, v36
	v_lshlrev_b64 v[44:45], 1, v[42:43]
	v_lshlrev_b64 v[42:43], 2, v[42:43]
	v_add_f32_e32 v46, v34, v37
	v_lshl_add_u64 v[36:37], v[74:75], 0, v[44:45]
	v_lshl_add_u64 v[48:49], s[4:5], 0, v[42:43]
	global_load_dwordx4 v[36:39], v[36:37], off
	v_lshl_add_u64 v[50:51], s[38:39], 0, v[42:43]
	global_load_dwordx4 v[58:61], v[48:49], off offset:16
	global_load_dwordx4 v[62:65], v[48:49], off
	global_load_dwordx4 v[78:81], v[50:51], off offset:16
	global_load_dwordx4 v[82:85], v[50:51], off
	v_lshl_add_u64 v[48:49], v[70:71], 0, v[44:45]
	v_lshl_add_u64 v[44:45], v[72:73], 0, v[44:45]
	global_load_dwordx4 v[52:55], v[44:45], off
	s_nop 0
	global_load_dwordx4 v[48:51], v[48:49], off
	v_lshl_add_u64 v[104:105], s[42:43], 0, v[42:43]
	global_load_dwordx4 v[42:45], v[104:105], off offset:16
	s_nop 0
	global_load_dwordx4 v[104:107], v[104:105], off
	v_pk_mul_f32 v[86:87], v[66:67], v[110:111] op_sel_hi:[0,1]
	v_lshlrev_b32_e32 v109, 16, v57
	v_lshlrev_b32_e32 v108, 16, v47
	v_mov_b32_e32 v110, v32
	v_mov_b32_e32 v111, v86
	v_lshlrev_b32_e32 v34, 16, v35
	v_pk_mul_f32 v[108:109], v[110:111], v[108:109]
	v_and_b32_e32 v56, 0xffff0000, v35
	v_fma_f32 v32, v40, v34, v108
	v_add_f32_e32 v40, v32, v109
	v_and_b32_e32 v35, 0xffff0000, v57
	v_and_b32_e32 v34, 0xffff0000, v47
	v_mov_b32_e32 v86, v33
	v_mul_f32_e32 v32, 0xbfb8aa3b, v77
	v_exp_f32_e32 v47, v32
	v_pk_mul_f32 v[32:33], v[86:87], v[34:35]
	v_mul_f32_e32 v34, 0xbfb8aa3b, v88
	v_fma_f32 v32, v41, v56, v32
	v_add_f32_e32 v32, v32, v33
	v_mul_f32_e32 v41, 0xbfb8aa3b, v113
	v_mul_f32_e32 v46, 0xbfb8aa3b, v46
	v_mul_f32_e32 v32, 0xbfb8aa3b, v32
	v_add_f32_e32 v33, 1.0, v47
	v_exp_f32_e32 v34, v34
	v_mul_f32_e32 v35, 0xbfb8aa3b, v112
	v_exp_f32_e32 v41, v41
	v_mul_f32_e32 v47, 0xbfb8aa3b, v114
	v_exp_f32_e32 v46, v46
	v_exp_f32_e32 v32, v32
	v_mul_f32_e32 v40, 0xbfb8aa3b, v40
	v_exp_f32_e32 v35, v35
	v_exp_f32_e32 v47, v47
	v_exp_f32_e32 v40, v40
	v_add_f32_e32 v34, 1.0, v34
	v_add_f32_e32 v41, 1.0, v41
	v_add_f32_e32 v46, 1.0, v46
	v_add_f32_e32 v32, 1.0, v32
	v_rcp_f32_e32 v34, v34
	v_add_f32_e32 v35, 1.0, v35
	v_rcp_f32_e32 v41, v41
	v_add_f32_e32 v47, 1.0, v47
	v_rcp_f32_e32 v32, v32
	v_rcp_f32_e32 v46, v46
	v_add_f32_e32 v40, 1.0, v40
	v_rcp_f32_e32 v33, v33
	v_rcp_f32_e32 v35, v35
	v_rcp_f32_e32 v47, v47
	v_rcp_f32_e32 v40, v40
	v_bfe_u32 v56, v32, 16, 1
	v_bfe_u32 v57, v46, 16, 1
	v_bfe_u32 v77, v41, 16, 1
	v_bfe_u32 v86, v34, 16, 1
	v_add3_u32 v86, v34, v86, s61
	v_add3_u32 v41, v41, v77, s61
	v_add3_u32 v34, v46, v57, s61
	v_add3_u32 v32, v32, v56, s61
	v_bfe_u32 v46, v35, 16, 1
	v_bfe_u32 v56, v40, 16, 1
	v_bfe_u32 v57, v33, 16, 1
	v_bfe_u32 v77, v47, 16, 1
	v_add3_u32 v40, v40, v56, s61
	v_add3_u32 v35, v35, v46, s61
	v_add3_u32 v46, v47, v77, s61
	v_add3_u32 v33, v33, v57, s61
	v_lshrrev_b32_e32 v47, 16, v35
	v_lshrrev_b32_e32 v35, 16, v40
	v_lshrrev_b32_e32 v40, 16, v33
	v_lshrrev_b32_e32 v33, 16, v46
	v_and_or_b32 v34, v34, s60, v33
	v_and_or_b32 v33, v41, s60, v47
	v_and_or_b32 v35, v32, s60, v35
	v_and_or_b32 v32, v86, s60, v40
	s_waitcnt vmcnt(6)
; __device__ __forceinline__ unsigned pk2(float lo, float hi) { return f2bf(lo) | (f2bf(hi) << 16); }
; __device__ __forceinline__ float sigmoid_f(float x) { return __builtin_amdgcn_rcpf(1.f + __expf(-x)); }
; __device__ __forceinline__ float tanh_f(float x) { const float e = __expf(2.f * x); return 1.f - 2.f * __builtin_amdgcn_rcpf(e + 1.f); }
; __device__ __forceinline__ void rwkv_proj_phase(const bf16* Z, const float* shift, const float* w0, const float* a0, const float* kkp, const float* kap, const float* rkp, ...
;     ...
;         bf16x8 xf[12];
; #pragma unroll
;         for (int ks = 0; ks < 12; ++ks) {
;             const int col = 2304 + 32 * ks + 8 * g;
;             const u32x4 c0 = *(const u32x4*)(zr + col), cm = *(const u32x4*)(zr + offm + col), cp = *(const u32x4*)(zr + offp + col);
;             float val[8];
; #pragma unroll
;             for (int q = 0; q < 2; ++q) { const f32x4 t0 = *(const f32x4*)(shift + col + 4 * q) * fm, t1 = *(const f32x4*)(shift + BCOLS + col + 4 * q), t2 = *(const f32x4*)(shift + 2 * BCOLS + col + 4 * q) * fn;
;                 const unsigned m0 = q ? cm.z : cm.x, m1 = q ? cm.w : cm.y, z0 = q ? c0.z : c0.x, z1 = q ? c0.w : c0.y, p0 = q ? cp.z : cp.x, p1 = q ? cp.w : cp.y;
;                 val[4 * q + 0] = t0.x * bflo(m0) + t1.x * bflo(z0) + t2.x * bflo(p0);
;                 val[4 * q + 1] = t0.y * bfhi(m0) + t1.y * bfhi(z0) + t2.y * bfhi(p0);
;                 val[4 * q + 2] = t0.z * bflo(m1) + t1.z * bflo(z1) + t2.z * bflo(p1);
;                 val[4 * q + 3] = t0.w * bfhi(m1) + t1.w * bfhi(z1) + t2.w * bfhi(p1); }
; #pragma unroll
;             for (int e = 0; e < 8; ++e) { if (ks < 4) val[e] = tanh_f(val[e]); else if (ks >= 8) val[e] = sigmoid_f(val[e]); }
;             u32x4 pk; pk.x = pk2(val[0], val[1]); pk.y = pk2(val[2], val[3]); pk.z = pk2(val[4], val[5]); pk.w = pk2(val[6], val[7]);
;             xf[ks] = __builtin_bit_cast(bf16x8, pk);
;             if (ks & 1) asm volatile("" ::: "memory");
;         }
	v_pk_mul_f32 v[46:47], v[68:69], v[62:63] op_sel_hi:[0,1]
	v_pk_mul_f32 v[40:41], v[68:69], v[64:65] op_sel_hi:[0,1]
	s_waitcnt vmcnt(4)
	v_pk_mul_f32 v[62:63], v[66:67], v[82:83] op_sel_hi:[0,1]
	v_mov_b32_e32 v82, v46
	s_waitcnt vmcnt(3)
	v_lshlrev_b32_e32 v65, 16, v52
	s_waitcnt vmcnt(2)
	v_lshlrev_b32_e32 v64, 16, v48
	v_mov_b32_e32 v83, v62
	v_lshlrev_b32_e32 v77, 16, v36
	v_pk_mul_f32 v[64:65], v[82:83], v[64:65]
	v_mov_b32_e32 v62, v47
	s_waitcnt vmcnt(0)
	v_fma_f32 v46, v104, v77, v64
	v_add_f32_e32 v77, v46, v65
	v_and_b32_e32 v65, 0xffff0000, v52
	v_and_b32_e32 v64, 0xffff0000, v48
	v_and_b32_e32 v36, 0xffff0000, v36
	v_pk_mul_f32 v[46:47], v[62:63], v[64:65]
	v_pk_mul_f32 v[56:57], v[66:67], v[84:85] op_sel_hi:[0,1]
	v_fma_f32 v36, v105, v36, v46
	v_add_f32_e32 v88, v36, v47
	v_lshlrev_b32_e32 v47, 16, v53
	v_lshlrev_b32_e32 v46, 16, v49
	v_mov_b32_e32 v62, v40
	v_mov_b32_e32 v63, v56
	v_lshlrev_b32_e32 v36, 16, v37
	v_pk_mul_f32 v[46:47], v[62:63], v[46:47]
	v_and_b32_e32 v40, 0xffff0000, v37
	v_fma_f32 v36, v106, v36, v46
	v_add_f32_e32 v116, v36, v47
	v_and_b32_e32 v37, 0xffff0000, v53
	v_and_b32_e32 v36, 0xffff0000, v49
	v_mov_b32_e32 v56, v41
	v_pk_mul_f32 v[36:37], v[56:57], v[36:37]
	v_pk_mul_f32 v[46:47], v[66:67], v[78:79] op_sel_hi:[0,1]
	v_fma_f32 v36, v107, v40, v36
	v_pk_mul_f32 v[40:41], v[68:69], v[58:59] op_sel_hi:[0,1]
	v_lshlrev_b32_e32 v49, 16, v54
	v_lshlrev_b32_e32 v48, 16, v50
	v_mov_b32_e32 v56, v40
	v_mov_b32_e32 v57, v46
	v_lshlrev_b32_e32 v58, 16, v38
	v_pk_mul_f32 v[48:49], v[56:57], v[48:49]
	v_mov_b32_e32 v46, v41
	v_fma_f32 v40, v42, v58, v48
	v_add_f32_e32 v118, v40, v49
	v_and_b32_e32 v49, 0xffff0000, v54
	v_and_b32_e32 v48, 0xffff0000, v50
	v_pk_mul_f32 v[40:41], v[46:47], v[48:49]
	v_add_u32_e32 v46, 0xa40, v76
	v_and_b32_e32 v38, 0xffff0000, v38
	v_ashrrev_i32_e32 v47, 31, v46
	v_fma_f32 v38, v43, v38, v40
	v_lshlrev_b64 v[48:49], 1, v[46:47]
	v_lshlrev_b64 v[46:47], 2, v[46:47]
	v_add_f32_e32 v50, v38, v41
	v_lshl_add_u64 v[40:41], v[74:75], 0, v[48:49]
	v_lshl_add_u64 v[56:57], s[4:5], 0, v[46:47]
	v_pk_mul_f32 v[52:53], v[66:67], v[80:81] op_sel_hi:[0,1]
	global_load_dwordx4 v[40:43], v[40:41], off
	v_lshl_add_u64 v[58:59], s[38:39], 0, v[46:47]
	global_load_dwordx4 v[78:81], v[56:57], off offset:16
	global_load_dwordx4 v[82:85], v[56:57], off
	global_load_dwordx4 v[104:107], v[58:59], off offset:16
	global_load_dwordx4 v[108:111], v[58:59], off
	v_lshl_add_u64 v[56:57], v[70:71], 0, v[48:49]
	v_lshl_add_u64 v[48:49], v[72:73], 0, v[48:49]
	v_add_f32_e32 v117, v36, v37
	v_pk_mul_f32 v[36:37], v[68:69], v[60:61] op_sel_hi:[0,1]
	global_load_dwordx4 v[60:63], v[48:49], off
	s_nop 0
	global_load_dwordx4 v[56:59], v[56:57], off
	v_lshl_add_u64 v[86:87], s[42:43], 0, v[46:47]
	global_load_dwordx4 v[46:49], v[86:87], off offset:16
	global_load_dwordx4 v[112:115], v[86:87], off
	v_lshlrev_b32_e32 v65, 16, v55
	v_lshlrev_b32_e32 v64, 16, v51
	v_mov_b32_e32 v86, v36
	v_mov_b32_e32 v87, v52
	v_lshlrev_b32_e32 v38, 16, v39
	v_pk_mul_f32 v[64:65], v[86:87], v[64:65]
	v_and_b32_e32 v54, 0xffff0000, v39
	v_fma_f32 v36, v44, v38, v64
	v_add_f32_e32 v44, v36, v65
	v_and_b32_e32 v39, 0xffff0000, v55
	v_and_b32_e32 v38, 0xffff0000, v51
	v_mov_b32_e32 v52, v37
	v_mul_f32_e32 v36, 0xbfb8aa3b, v77
	v_exp_f32_e32 v51, v36
	v_pk_mul_f32 v[36:37], v[52:53], v[38:39]
	v_mul_f32_e32 v38, 0xbfb8aa3b, v88
	v_fma_f32 v36, v45, v54, v36
	v_add_f32_e32 v36, v36, v37
	v_mul_f32_e32 v45, 0xbfb8aa3b, v117
	v_mul_f32_e32 v50, 0xbfb8aa3b, v50
	v_mul_f32_e32 v36, 0xbfb8aa3b, v36
	v_add_f32_e32 v37, 1.0, v51
	v_exp_f32_e32 v38, v38
	v_mul_f32_e32 v39, 0xbfb8aa3b, v116
	v_exp_f32_e32 v45, v45
	v_mul_f32_e32 v51, 0xbfb8aa3b, v118
	v_exp_f32_e32 v50, v50
	v_exp_f32_e32 v36, v36
	v_mul_f32_e32 v44, 0xbfb8aa3b, v44
	v_exp_f32_e32 v39, v39
	v_exp_f32_e32 v51, v51
	v_exp_f32_e32 v44, v44
	v_add_f32_e32 v38, 1.0, v38
	v_add_f32_e32 v45, 1.0, v45
	v_add_f32_e32 v50, 1.0, v50
	v_add_f32_e32 v36, 1.0, v36
	v_rcp_f32_e32 v38, v38
	v_add_f32_e32 v39, 1.0, v39
	v_rcp_f32_e32 v45, v45
	v_add_f32_e32 v51, 1.0, v51
	v_rcp_f32_e32 v36, v36
	v_rcp_f32_e32 v50, v50
	v_add_f32_e32 v44, 1.0, v44
	v_rcp_f32_e32 v37, v37
	v_rcp_f32_e32 v39, v39
	v_rcp_f32_e32 v51, v51
	v_rcp_f32_e32 v44, v44
	v_bfe_u32 v52, v36, 16, 1
	v_bfe_u32 v53, v50, 16, 1
	v_bfe_u32 v54, v45, 16, 1
	v_bfe_u32 v55, v38, 16, 1
	v_add3_u32 v55, v38, v55, s61
	v_add3_u32 v45, v45, v54, s61
	v_add3_u32 v38, v50, v53, s61
	v_add3_u32 v36, v36, v52, s61
	v_bfe_u32 v50, v39, 16, 1
	v_bfe_u32 v52, v44, 16, 1
	v_bfe_u32 v53, v37, 16, 1
	v_bfe_u32 v54, v51, 16, 1
	v_add3_u32 v44, v44, v52, s61
	v_add3_u32 v39, v39, v50, s61
	v_add3_u32 v50, v51, v54, s61
	v_add3_u32 v37, v37, v53, s61
	v_lshrrev_b32_e32 v51, 16, v39
	v_lshrrev_b32_e32 v39, 16, v44
	v_lshrrev_b32_e32 v44, 16, v37
	v_lshrrev_b32_e32 v37, 16, v50
	v_and_or_b32 v39, v36, s60, v39
	v_and_or_b32 v38, v38, s60, v37
	v_and_or_b32 v37, v45, s60, v51
	v_and_or_b32 v36, v55, s60, v44
	s_waitcnt vmcnt(6)
	v_pk_mul_f32 v[50:51], v[68:69], v[82:83] op_sel_hi:[0,1]
	s_waitcnt vmcnt(4)
	v_pk_mul_f32 v[54:55], v[66:67], v[108:109] op_sel_hi:[0,1]
	v_mov_b32_e32 v82, v50
	v_mov_b32_e32 v83, v54
	v_lshlrev_b32_e32 v77, 16, v40
	s_waitcnt vmcnt(3)
	v_lshlrev_b32_e32 v65, 16, v60
	s_waitcnt vmcnt(2)
	v_lshlrev_b32_e32 v64, 16, v56
	v_pk_mul_f32 v[64:65], v[82:83], v[64:65]
	v_mov_b32_e32 v54, v51
	s_waitcnt vmcnt(0)
; __device__ __forceinline__ unsigned pk2(float lo, float hi) { return f2bf(lo) | (f2bf(hi) << 16); }
; __device__ __forceinline__ float sigmoid_f(float x) { return __builtin_amdgcn_rcpf(1.f + __expf(-x)); }
; __device__ __forceinline__ float tanh_f(float x) { const float e = __expf(2.f * x); return 1.f - 2.f * __builtin_amdgcn_rcpf(e + 1.f); }
; __device__ __forceinline__ void rwkv_proj_phase(const bf16* Z, const float* shift, const float* w0, const float* a0, const float* kkp, const float* kap, const float* rkp, ...
;     ...
;         bf16x8 xf[12];
; #pragma unroll
;         for (int ks = 0; ks < 12; ++ks) {
;             const int col = 2304 + 32 * ks + 8 * g;
;             const u32x4 c0 = *(const u32x4*)(zr + col), cm = *(const u32x4*)(zr + offm + col), cp = *(const u32x4*)(zr + offp + col);
;             float val[8];
; #pragma unroll
;             for (int q = 0; q < 2; ++q) { const f32x4 t0 = *(const f32x4*)(shift + col + 4 * q) * fm, t1 = *(const f32x4*)(shift + BCOLS + col + 4 * q), t2 = *(const f32x4*)(shift + 2 * BCOLS + col + 4 * q) * fn;
;                 const unsigned m0 = q ? cm.z : cm.x, m1 = q ? cm.w : cm.y, z0 = q ? c0.z : c0.x, z1 = q ? c0.w : c0.y, p0 = q ? cp.z : cp.x, p1 = q ? cp.w : cp.y;
;                 val[4 * q + 0] = t0.x * bflo(m0) + t1.x * bflo(z0) + t2.x * bflo(p0);
;                 val[4 * q + 1] = t0.y * bfhi(m0) + t1.y * bfhi(z0) + t2.y * bfhi(p0);
;                 val[4 * q + 2] = t0.z * bflo(m1) + t1.z * bflo(z1) + t2.z * bflo(p1);
;                 val[4 * q + 3] = t0.w * bfhi(m1) + t1.w * bfhi(z1) + t2.w * bfhi(p1); }
; #pragma unroll
;             for (int e = 0; e < 8; ++e) { if (ks < 4) val[e] = tanh_f(val[e]); else if (ks >= 8) val[e] = sigmoid_f(val[e]); }
;             u32x4 pk; pk.x = pk2(val[0], val[1]); pk.y = pk2(val[2], val[3]); pk.z = pk2(val[4], val[5]); pk.w = pk2(val[6], val[7]);
;             xf[ks] = __builtin_bit_cast(bf16x8, pk);
;             if (ks & 1) asm volatile("" ::: "memory");
;         }
	v_fma_f32 v50, v112, v77, v64
	v_add_f32_e32 v88, v50, v65
	v_and_b32_e32 v65, 0xffff0000, v60
	v_and_b32_e32 v64, 0xffff0000, v56
	v_and_b32_e32 v40, 0xffff0000, v40
	v_pk_mul_f32 v[50:51], v[54:55], v[64:65]
	v_pk_mul_f32 v[44:45], v[68:69], v[84:85] op_sel_hi:[0,1]
	v_pk_mul_f32 v[52:53], v[66:67], v[110:111] op_sel_hi:[0,1]
	v_fma_f32 v40, v113, v40, v50
	v_add_f32_e32 v112, v40, v51
	v_lshlrev_b32_e32 v51, 16, v61
	v_lshlrev_b32_e32 v50, 16, v57
	v_mov_b32_e32 v54, v44
	v_mov_b32_e32 v55, v52
	v_lshlrev_b32_e32 v40, 16, v41
	v_pk_mul_f32 v[50:51], v[54:55], v[50:51]
	v_and_b32_e32 v44, 0xffff0000, v41
	v_fma_f32 v40, v114, v40, v50
	v_add_f32_e32 v113, v40, v51
	v_and_b32_e32 v41, 0xffff0000, v61
	v_and_b32_e32 v40, 0xffff0000, v57
	v_mov_b32_e32 v52, v45
	v_pk_mul_f32 v[40:41], v[52:53], v[40:41]
	v_pk_mul_f32 v[50:51], v[66:67], v[104:105] op_sel_hi:[0,1]
	v_fma_f32 v40, v115, v44, v40
	v_pk_mul_f32 v[44:45], v[68:69], v[78:79] op_sel_hi:[0,1]
	v_lshlrev_b32_e32 v53, 16, v62
	v_lshlrev_b32_e32 v52, 16, v58
	v_mov_b32_e32 v54, v44
	v_mov_b32_e32 v55, v50
	v_lshlrev_b32_e32 v56, 16, v42
	v_pk_mul_f32 v[52:53], v[54:55], v[52:53]
	v_mov_b32_e32 v50, v45
	v_fma_f32 v44, v46, v56, v52
	v_add_f32_e32 v115, v44, v53
	v_and_b32_e32 v53, 0xffff0000, v62
	v_and_b32_e32 v52, 0xffff0000, v58
	v_pk_mul_f32 v[44:45], v[50:51], v[52:53]
	v_add_u32_e32 v50, 0xa60, v76
	v_and_b32_e32 v42, 0xffff0000, v42
	v_ashrrev_i32_e32 v51, 31, v50
	v_fma_f32 v42, v47, v42, v44
	v_lshlrev_b64 v[64:65], 1, v[50:51]
	v_lshlrev_b64 v[86:87], 2, v[50:51]
	v_add_f32_e32 v58, v42, v45
	v_lshl_add_u64 v[44:45], v[74:75], 0, v[64:65]
	v_lshl_add_u64 v[54:55], s[4:5], 0, v[86:87]
	v_lshl_add_u64 v[78:79], s[38:39], 0, v[86:87]
	v_add_f32_e32 v114, v40, v41
	v_pk_mul_f32 v[40:41], v[68:69], v[80:81] op_sel_hi:[0,1]
	global_load_dwordx4 v[44:47], v[44:45], off
	s_nop 0
	global_load_dwordx4 v[50:53], v[54:55], off offset:16
	s_nop 0
	global_load_dwordx4 v[54:57], v[54:55], off
	s_nop 0
	global_load_dwordx4 v[74:77], v[78:79], off offset:16
	s_nop 0
	global_load_dwordx4 v[78:81], v[78:79], off
	v_lshl_add_u64 v[82:83], v[70:71], 0, v[64:65]
	v_lshl_add_u64 v[64:65], v[72:73], 0, v[64:65]
	global_load_dwordx4 v[70:73], v[64:65], off
	s_nop 0
	global_load_dwordx4 v[82:85], v[82:83], off
	v_lshl_add_u64 v[86:87], s[42:43], 0, v[86:87]
	v_pk_mul_f32 v[60:61], v[66:67], v[106:107] op_sel_hi:[0,1]
	global_load_dwordx4 v[104:107], v[86:87], off offset:16
	global_load_dwordx4 v[108:111], v[86:87], off
	v_lshlrev_b32_e32 v65, 16, v63
	v_lshlrev_b32_e32 v64, 16, v59
	v_mov_b32_e32 v86, v40
	v_mov_b32_e32 v87, v60
	v_lshlrev_b32_e32 v42, 16, v43
	v_pk_mul_f32 v[64:65], v[86:87], v[64:65]
	v_and_b32_e32 v62, 0xffff0000, v43
	v_fma_f32 v40, v48, v42, v64
	v_add_f32_e32 v48, v40, v65
	v_and_b32_e32 v43, 0xffff0000, v63
	v_and_b32_e32 v42, 0xffff0000, v59
	v_mov_b32_e32 v60, v41
	v_mul_f32_e32 v40, 0xbfb8aa3b, v88
	v_exp_f32_e32 v59, v40
	v_pk_mul_f32 v[40:41], v[60:61], v[42:43]
	v_mul_f32_e32 v42, 0xbfb8aa3b, v112
	v_fma_f32 v40, v49, v62, v40
	v_add_f32_e32 v40, v40, v41
	v_mul_f32_e32 v49, 0xbfb8aa3b, v114
	v_mul_f32_e32 v58, 0xbfb8aa3b, v58
	v_mul_f32_e32 v40, 0xbfb8aa3b, v40
	v_add_f32_e32 v41, 1.0, v59
	v_exp_f32_e32 v42, v42
	v_mul_f32_e32 v43, 0xbfb8aa3b, v113
	v_exp_f32_e32 v49, v49
	v_mul_f32_e32 v59, 0xbfb8aa3b, v115
	v_exp_f32_e32 v58, v58
	v_exp_f32_e32 v40, v40
	v_mul_f32_e32 v48, 0xbfb8aa3b, v48
	v_exp_f32_e32 v43, v43
	v_exp_f32_e32 v59, v59
	v_exp_f32_e32 v48, v48
	v_add_f32_e32 v42, 1.0, v42
	v_add_f32_e32 v49, 1.0, v49
	v_add_f32_e32 v58, 1.0, v58
	v_add_f32_e32 v40, 1.0, v40
	v_rcp_f32_e32 v42, v42
	v_add_f32_e32 v43, 1.0, v43
	v_rcp_f32_e32 v49, v49
	v_add_f32_e32 v59, 1.0, v59
	v_rcp_f32_e32 v40, v40
	v_rcp_f32_e32 v58, v58
	v_add_f32_e32 v48, 1.0, v48
	v_rcp_f32_e32 v41, v41
	v_rcp_f32_e32 v43, v43
	v_rcp_f32_e32 v59, v59
	v_rcp_f32_e32 v48, v48
	v_bfe_u32 v60, v40, 16, 1
	v_bfe_u32 v61, v58, 16, 1
	v_bfe_u32 v62, v49, 16, 1
	v_bfe_u32 v63, v42, 16, 1
	v_add3_u32 v63, v42, v63, s61
	v_add3_u32 v49, v49, v62, s61
	v_add3_u32 v42, v58, v61, s61
	v_add3_u32 v40, v40, v60, s61
	v_bfe_u32 v58, v43, 16, 1
	v_bfe_u32 v60, v48, 16, 1
	v_bfe_u32 v61, v41, 16, 1
	v_bfe_u32 v62, v59, 16, 1
	v_add3_u32 v48, v48, v60, s61
	v_add3_u32 v43, v43, v58, s61
	v_add3_u32 v58, v59, v62, s61
	v_add3_u32 v41, v41, v61, s61
	v_lshrrev_b32_e32 v59, 16, v43
	v_lshrrev_b32_e32 v43, 16, v48
	v_lshrrev_b32_e32 v48, 16, v41
	v_lshrrev_b32_e32 v41, 16, v58
	v_and_or_b32 v42, v42, s60, v41
	v_and_or_b32 v41, v49, s60, v59
	v_and_or_b32 v43, v40, s60, v43
	v_and_or_b32 v40, v63, s60, v48
	s_waitcnt vmcnt(6)
; __device__ __forceinline__ unsigned pk2(float lo, float hi) { return f2bf(lo) | (f2bf(hi) << 16); }
; __device__ __forceinline__ float sigmoid_f(float x) { return __builtin_amdgcn_rcpf(1.f + __expf(-x)); }
; __device__ __forceinline__ float tanh_f(float x) { const float e = __expf(2.f * x); return 1.f - 2.f * __builtin_amdgcn_rcpf(e + 1.f); }
; __device__ __forceinline__ void rwkv_proj_phase(const bf16* Z, const float* shift, const float* w0, const float* a0, const float* kkp, const float* kap, const float* rkp, ...
;     ...
;         bf16x8 xf[12];
; #pragma unroll
;         for (int ks = 0; ks < 12; ++ks) {
;             const int col = 2304 + 32 * ks + 8 * g;
;             const u32x4 c0 = *(const u32x4*)(zr + col), cm = *(const u32x4*)(zr + offm + col), cp = *(const u32x4*)(zr + offp + col);
;             float val[8];
; #pragma unroll
;             for (int q = 0; q < 2; ++q) { const f32x4 t0 = *(const f32x4*)(shift + col + 4 * q) * fm, t1 = *(const f32x4*)(shift + BCOLS + col + 4 * q), t2 = *(const f32x4*)(shift + 2 * BCOLS + col + 4 * q) * fn;
;                 const unsigned m0 = q ? cm.z : cm.x, m1 = q ? cm.w : cm.y, z0 = q ? c0.z : c0.x, z1 = q ? c0.w : c0.y, p0 = q ? cp.z : cp.x, p1 = q ? cp.w : cp.y;
;                 val[4 * q + 0] = t0.x * bflo(m0) + t1.x * bflo(z0) + t2.x * bflo(p0);
;                 val[4 * q + 1] = t0.y * bfhi(m0) + t1.y * bfhi(z0) + t2.y * bfhi(p0);
;                 val[4 * q + 2] = t0.z * bflo(m1) + t1.z * bflo(z1) + t2.z * bflo(p1);
;                 val[4 * q + 3] = t0.w * bfhi(m1) + t1.w * bfhi(z1) + t2.w * bfhi(p1); }
; #pragma unroll
;             for (int e = 0; e < 8; ++e) { if (ks < 4) val[e] = tanh_f(val[e]); else if (ks >= 8) val[e] = sigmoid_f(val[e]); }
;             u32x4 pk; pk.x = pk2(val[0], val[1]); pk.y = pk2(val[2], val[3]); pk.z = pk2(val[4], val[5]); pk.w = pk2(val[6], val[7]);
;             xf[ks] = __builtin_bit_cast(bf16x8, pk);
;             if (ks & 1) asm volatile("" ::: "memory");
;         }
	v_pk_mul_f32 v[54:55], v[68:69], v[54:55] op_sel_hi:[0,1]
	v_mov_b32_e32 v62, v54
	s_waitcnt vmcnt(4)
	v_pk_mul_f32 v[58:59], v[66:67], v[78:79] op_sel_hi:[0,1]
	v_mov_b32_e32 v63, v58
	s_waitcnt vmcnt(3)
	v_lshlrev_b32_e32 v61, 16, v70
	s_waitcnt vmcnt(2)
	v_lshlrev_b32_e32 v60, 16, v82
	v_lshlrev_b32_e32 v64, 16, v44
	v_pk_mul_f32 v[60:61], v[62:63], v[60:61]
	v_mov_b32_e32 v58, v55
	s_waitcnt vmcnt(0)
	v_fma_f32 v54, v108, v64, v60
	v_add_f32_e32 v62, v54, v61
	v_and_b32_e32 v61, 0xffff0000, v70
	v_and_b32_e32 v60, 0xffff0000, v82
	v_and_b32_e32 v44, 0xffff0000, v44
	v_pk_mul_f32 v[54:55], v[58:59], v[60:61]
	v_pk_mul_f32 v[48:49], v[68:69], v[56:57] op_sel_hi:[0,1]
	v_pk_mul_f32 v[56:57], v[66:67], v[80:81] op_sel_hi:[0,1]
	v_fma_f32 v44, v109, v44, v54
	v_add_f32_e32 v60, v44, v55
	v_lshlrev_b32_e32 v55, 16, v71
	v_lshlrev_b32_e32 v54, 16, v83
	v_mov_b32_e32 v58, v48
	v_mov_b32_e32 v59, v56
	v_lshlrev_b32_e32 v44, 16, v45
	v_pk_mul_f32 v[54:55], v[58:59], v[54:55]
	v_and_b32_e32 v48, 0xffff0000, v45
	v_fma_f32 v44, v110, v44, v54
	v_add_f32_e32 v58, v44, v55
	v_and_b32_e32 v45, 0xffff0000, v71
	v_and_b32_e32 v44, 0xffff0000, v83
	v_mov_b32_e32 v56, v49
	v_pk_mul_f32 v[44:45], v[56:57], v[44:45]
	v_lshlrev_b32_e32 v55, 16, v72
	v_fma_f32 v44, v111, v48, v44
	v_add_f32_e32 v59, v44, v45
	v_pk_mul_f32 v[44:45], v[68:69], v[52:53] op_sel_hi:[0,1]
	v_pk_mul_f32 v[48:49], v[68:69], v[50:51] op_sel_hi:[0,1]
	v_pk_mul_f32 v[52:53], v[66:67], v[74:75] op_sel_hi:[0,1]
	v_lshlrev_b32_e32 v54, 16, v84
	v_mov_b32_e32 v56, v48
	v_mov_b32_e32 v57, v52
	v_lshlrev_b32_e32 v61, 16, v46
	v_pk_mul_f32 v[54:55], v[56:57], v[54:55]
	v_mov_b32_e32 v52, v49
	v_fma_f32 v48, v104, v61, v54
	v_add_f32_e32 v56, v48, v55
	v_and_b32_e32 v55, 0xffff0000, v72
	v_and_b32_e32 v54, 0xffff0000, v84
	v_and_b32_e32 v46, 0xffff0000, v46
	v_pk_mul_f32 v[48:49], v[52:53], v[54:55]
	v_pk_mul_f32 v[50:51], v[66:67], v[76:77] op_sel_hi:[0,1]
	v_fma_f32 v46, v105, v46, v48
	v_add_f32_e32 v54, v46, v49
	v_lshlrev_b32_e32 v49, 16, v73
	v_lshlrev_b32_e32 v48, 16, v85
	v_mov_b32_e32 v52, v44
	v_mov_b32_e32 v53, v50
	v_lshlrev_b32_e32 v46, 16, v47
	v_pk_mul_f32 v[48:49], v[52:53], v[48:49]
	v_mov_b32_e32 v50, v45
	v_fma_f32 v44, v106, v46, v48
	v_add_f32_e32 v48, v44, v49
	v_and_b32_e32 v49, 0xffff0000, v47
	v_and_b32_e32 v47, 0xffff0000, v73
	v_and_b32_e32 v46, 0xffff0000, v85
	v_mul_f32_e32 v44, 0xbfb8aa3b, v62
	v_exp_f32_e32 v52, v44
	v_pk_mul_f32 v[44:45], v[50:51], v[46:47]
	v_mul_f32_e32 v46, 0xbfb8aa3b, v60
	v_fma_f32 v44, v107, v49, v44
	v_add_f32_e32 v44, v44, v45
	v_mul_f32_e32 v49, 0xbfb8aa3b, v59
	v_mul_f32_e32 v51, 0xbfb8aa3b, v54
	v_mul_f32_e32 v44, 0xbfb8aa3b, v44
	v_exp_f32_e32 v46, v46
	v_mul_f32_e32 v47, 0xbfb8aa3b, v58
	v_exp_f32_e32 v49, v49
	v_mul_f32_e32 v50, 0xbfb8aa3b, v56
	v_exp_f32_e32 v51, v51
	v_exp_f32_e32 v44, v44
	v_mul_f32_e32 v48, 0xbfb8aa3b, v48
	v_exp_f32_e32 v47, v47
	v_exp_f32_e32 v50, v50
	v_exp_f32_e32 v48, v48
	v_add_f32_e32 v46, 1.0, v46
	v_add_f32_e32 v49, 1.0, v49
	v_add_f32_e32 v51, 1.0, v51
	v_add_f32_e32 v44, 1.0, v44
	v_add_f32_e32 v45, 1.0, v52
	v_rcp_f32_e32 v46, v46
	v_add_f32_e32 v47, 1.0, v47
	v_rcp_f32_e32 v49, v49
	v_add_f32_e32 v50, 1.0, v50
	v_rcp_f32_e32 v44, v44
	v_rcp_f32_e32 v51, v51
	v_add_f32_e32 v48, 1.0, v48
	v_rcp_f32_e32 v45, v45
	v_rcp_f32_e32 v47, v47
	v_rcp_f32_e32 v50, v50
	v_rcp_f32_e32 v48, v48
	v_bfe_u32 v52, v44, 16, 1
	v_bfe_u32 v53, v51, 16, 1
	v_bfe_u32 v54, v49, 16, 1
	v_bfe_u32 v55, v46, 16, 1
	v_add3_u32 v55, v46, v55, s61
	v_add3_u32 v49, v49, v54, s61
	v_add3_u32 v46, v51, v53, s61
	v_add3_u32 v44, v44, v52, s61
	v_bfe_u32 v51, v47, 16, 1
	v_bfe_u32 v52, v48, 16, 1
	v_bfe_u32 v53, v45, 16, 1
	v_bfe_u32 v54, v50, 16, 1
	v_add3_u32 v48, v48, v52, s61
	v_add3_u32 v47, v47, v51, s61
	v_add3_u32 v50, v50, v54, s61
	v_add3_u32 v45, v45, v53, s61
	v_lshrrev_b32_e32 v51, 16, v47
	v_lshrrev_b32_e32 v47, 16, v48
	v_lshrrev_b32_e32 v48, 16, v45
	v_lshrrev_b32_e32 v45, 16, v50
	v_and_or_b32 v47, v44, s60, v47
	v_and_or_b32 v46, v46, s60, v45
	v_and_or_b32 v45, v49, s60, v51
	v_and_or_b32 v44, v55, s60, v48
	v_mad_i64_i32 v[104:105], s[0:1], v67, s62, v[98:99]
	v_mad_i64_i32 v[106:107], s[0:1], v67, s62, v[100:101]

; #define LAS __attribute__((address_space(3)))
; __device__ __forceinline__ unsigned pk2(float lo, float hi) { return f2bf(lo) | (f2bf(hi) << 16); }
; __device__ __forceinline__ void rwkv_proj_phase(const bf16* Z, const float* shift, const float* w0, const float* a0, const float* kkp, const float* kap, const float* rkp, ...
;     ...
;                 for (int i = 0; i < 6; ++i) { const int cid = tid + 512 * i, tok = cid / 24, ch = cid % 24, wh = ch >> 3, col = wh * BW + h * 64 + (ch & 7) * 8;
;                     const int mm = tt * 128 + tok; int tp, ln; if (mm < ML) { tp = mm & 8191; ln = SEQ; } else { tp = (mm - ML) & 255; ln = CTXL; }
;                     const bool hp_ = tp > 0, hn_ = tp < ln - 1; const float fm_ = hp_ ? 1.f : 0.f, fn_ = hn_ ? 1.f : 0.f;
;                     const bf16* zz = Z + (size_t)mm * INCP + ZB0 + col;
;                     const u32x4 c0 = *(const u32x4*)zz, cm = *(const u32x4*)(zz - (hp_ ? INCP : 0)), cp = *(const u32x4*)(zz + (hn_ ? INCP : 0));
;                     float val[8];
; #pragma unroll
;                     for (int qq = 0; qq < 2; ++qq) { const f32x4 t0 = *(const f32x4*)(shift + col + 4 * qq) * fm_, t1 = *(const f32x4*)(shift + BCOLS + col + 4 * qq), t2 = *(const f32x4*)(shift + 2 * BCOLS + col + 4 * qq) * fn_;
;                         const unsigned m0 = qq ? cm.z : cm.x, m1 = qq ? cm.w : cm.y, z0 = qq ? c0.z : c0.x, z1 = qq ? c0.w : c0.y, p0 = qq ? cp.z : cp.x, p1 = qq ? cp.w : cp.y;
;                         val[4 * qq + 0] = t0.x * bflo(m0) + t1.x * bflo(z0) + t2.x * bflo(p0);
;                         val[4 * qq + 1] = t0.y * bfhi(m0) + t1.y * bfhi(z0) + t2.y * bfhi(p0);
;                         val[4 * qq + 2] = t0.z * bflo(m1) + t1.z * bflo(z1) + t2.z * bflo(p1);
;                         val[4 * qq + 3] = t0.w * bfhi(m1) + t1.w * bfhi(z1) + t2.w * bfhi(p1); }
;                     u32x4 pk; pk.x = pk2(val[0], val[1]); pk.y = pk2(val[2], val[3]); pk.z = pk2(val[4], val[5]); pk.w = pk2(val[6], val[7]);
;                     *(LAS u32x4*)(lds + tok * 400 + ch * 16) = pk; }
.LBB0_1328:
	v_add_u32_e32 v50, s29, v174
	v_mul_hi_u32 v51, v50, s63
	v_add_u32_e32 v52, 0x200, v50
	v_lshrrev_b32_e32 v51, 4, v51
	v_mul_hi_u32 v53, v52, s63
	v_mul_lo_u32 v54, v51, 24
	v_add_u32_e32 v55, s78, v51
	v_lshrrev_b32_e32 v53, 4, v53
	v_sub_u32_e32 v54, v50, v54
	v_cmp_gt_i32_e32 vcc, s64, v55
	v_mul_lo_u32 v58, v53, 24
	v_add_u32_e32 v59, s78, v53
	v_mov_b64_e32 v[48:49], s[30:31]
	v_cndmask_b32_e32 v57, v167, v168, vcc
	v_lshrrev_b32_e32 v61, 3, v54
	v_sub_u32_e32 v58, v52, v58
	v_cmp_gt_i32_e32 vcc, s64, v59
	v_mul_lo_u32 v56, v51, s65
	v_mad_i64_i32 v[50:51], s[0:1], v55, s59, v[48:49]
	v_mul_lo_u32 v60, v53, s65
	v_and_b32_e32 v55, v57, v55
	v_cndmask_b32_e32 v63, v167, v168, vcc
	v_mad_i64_i32 v[52:53], s[0:1], v59, s59, v[48:49]
	v_mul_lo_u32 v48, v61, s54
	v_lshrrev_b32_e32 v49, 3, v58
	v_lshlrev_b32_e32 v62, 3, v54
	v_lshlrev_b32_e32 v54, 4, v54
	v_cmp_eq_u32_e32 vcc, 0, v55
	v_cmp_eq_u32_e64 s[0:1], v55, v57
	v_and_b32_e32 v57, v63, v59
	v_add_u32_e32 v48, s28, v48
	v_mul_lo_u32 v49, v49, s54
	v_cndmask_b32_e64 v140, 1.0, 0, vcc
	v_cndmask_b32_e64 v142, 1.0, 0, s[0:1]
	v_add3_u32 v190, 0, v56, v54
	v_lshlrev_b32_e32 v56, 3, v58
	v_cndmask_b32_e64 v55, -1, 0, vcc
	v_cndmask_b32_e64 v54, v159, 0, vcc
	v_cndmask_b32_e64 v88, v160, 0, s[0:1]
	v_cmp_eq_u32_e32 vcc, 0, v57
	v_cmp_eq_u32_e64 s[0:1], v57, v63
	v_and_or_b32 v48, v62, 56, v48
	v_add_u32_e32 v57, s28, v49
	v_lshlrev_b32_e32 v58, 4, v58
	v_ashrrev_i32_e32 v49, 31, v48
	v_and_or_b32 v56, v56, 56, v57
	v_add3_u32 v191, 0, v60, v58
	v_lshl_add_u64 v[58:59], v[48:49], 1, v[50:51]
	v_ashrrev_i32_e32 v57, 31, v56
	v_cndmask_b32_e64 v109, -1, 0, vcc
	v_cndmask_b32_e64 v108, v159, 0, vcc
	v_lshlrev_b64 v[60:61], 2, v[48:49]
	v_lshl_add_u64 v[76:77], v[58:59], 0, v[88:89]
	v_lshl_add_u64 v[110:111], v[56:57], 1, v[52:53]
	v_cndmask_b32_e64 v88, v160, 0, s[0:1]
	v_lshlrev_b64 v[112:113], 2, v[56:57]
	v_lshl_add_u64 v[68:69], v[58:59], 0, v[54:55]
	v_lshl_add_u64 v[62:63], s[4:5], 0, v[60:61]
	v_lshl_add_u64 v[80:81], s[42:43], 0, v[60:61]
	v_lshl_add_u64 v[64:65], s[38:39], 0, v[60:61]
	v_lshl_add_u64 v[124:125], v[110:111], 0, v[108:109]
	v_lshl_add_u64 v[132:133], v[110:111], 0, v[88:89]
	v_lshl_add_u64 v[116:117], s[4:5], 0, v[112:113]
	v_lshl_add_u64 v[136:137], s[42:43], 0, v[112:113]
	v_lshl_add_u64 v[120:121], s[38:39], 0, v[112:113]
	global_load_dwordx4 v[48:51], v[58:59], off offset:2048
	global_load_dwordx4 v[52:55], v[62:63], off
	s_nop 0
	global_load_dwordx4 v[56:59], v[64:65], off
	s_nop 0
	global_load_dwordx4 v[60:63], v[62:63], off offset:16
	s_nop 0
	global_load_dwordx4 v[64:67], v[64:65], off offset:16
	s_nop 0
	global_load_dwordx4 v[68:71], v[68:69], off offset:2048
	s_nop 0
	global_load_dwordx4 v[72:75], v[80:81], off
	s_nop 0
	global_load_dwordx4 v[76:79], v[76:77], off offset:2048
	s_nop 0
	global_load_dwordx4 v[80:83], v[80:81], off offset:16
	s_nop 0
	global_load_dwordx4 v[84:87], v[110:111], off offset:2048
	s_nop 0
	global_load_dwordx4 v[108:111], v[116:117], off
	global_load_dwordx4 v[112:115], v[120:121], off
	s_nop 0
	global_load_dwordx4 v[116:119], v[116:117], off offset:16
	s_nop 0
	global_load_dwordx4 v[120:123], v[120:121], off offset:16
	s_nop 0
	global_load_dwordx4 v[124:127], v[124:125], off offset:2048
	s_nop 0
	global_load_dwordx4 v[128:131], v[136:137], off
	s_nop 0
	global_load_dwordx4 v[132:135], v[132:133], off offset:2048
	s_nop 0
	global_load_dwordx4 v[136:139], v[136:137], off offset:16
	v_cndmask_b32_e64 v144, 1.0, 0, vcc
	v_cndmask_b32_e64 v146, 1.0, 0, s[0:1]
	s_addk_i32 s29, 0x400
	s_cmpk_eq_i32 s29, 0xc00
	s_waitcnt vmcnt(16)
	v_pk_mul_f32 v[54:55], v[54:55], v[140:141] op_sel_hi:[1,0]
	v_pk_mul_f32 v[52:53], v[52:53], v[140:141] op_sel_hi:[1,0]
	s_waitcnt vmcnt(15)
	v_pk_mul_f32 v[58:59], v[58:59], v[142:143] op_sel_hi:[1,0]
	v_pk_mul_f32 v[56:57], v[56:57], v[142:143] op_sel_hi:[1,0]
	s_waitcnt vmcnt(14)
	v_pk_mul_f32 v[62:63], v[62:63], v[140:141] op_sel_hi:[1,0]
	v_pk_mul_f32 v[60:61], v[60:61], v[140:141] op_sel_hi:[1,0]
	s_waitcnt vmcnt(13)
	v_pk_mul_f32 v[66:67], v[66:67], v[142:143] op_sel_hi:[1,0]
	v_pk_mul_f32 v[64:65], v[64:65], v[142:143] op_sel_hi:[1,0]
	s_waitcnt vmcnt(12)
	v_lshlrev_b32_e32 v141, 16, v69
	v_lshlrev_b32_e32 v140, 16, v68
	s_waitcnt vmcnt(11)
	v_mov_b32_e32 v142, v72
	v_mov_b32_e32 v143, v74
	s_waitcnt vmcnt(10)
	v_lshlrev_b32_e32 v177, 16, v77
	v_lshlrev_b32_e32 v176, 16, v76
	v_and_b32_e32 v69, 0xffff0000, v69
	v_and_b32_e32 v68, 0xffff0000, v68
	v_mov_b32_e32 v74, v73
	v_and_b32_e32 v73, 0xffff0000, v77
	v_and_b32_e32 v72, 0xffff0000, v76
	v_lshlrev_b32_e32 v77, 16, v71
	v_lshlrev_b32_e32 v76, 16, v70
	v_and_b32_e32 v71, 0xffff0000, v71
	v_and_b32_e32 v70, 0xffff0000, v70
	v_mov_b32_e32 v184, v52
	v_mov_b32_e32 v185, v54
	v_mov_b32_e32 v186, v56
	v_mov_b32_e32 v187, v58
	v_mov_b32_e32 v54, v53
	v_mov_b32_e32 v58, v57
	v_mov_b32_e32 v52, v60
	v_mov_b32_e32 v53, v62
	v_mov_b32_e32 v56, v64
	v_mov_b32_e32 v57, v66
	v_mov_b32_e32 v62, v61
	v_mov_b32_e32 v66, v65
	s_waitcnt vmcnt(7)
	v_pk_mul_f32 v[60:61], v[110:111], v[144:145] op_sel_hi:[1,0]
	v_pk_mul_f32 v[64:65], v[108:109], v[144:145] op_sel_hi:[1,0]
	s_waitcnt vmcnt(6)
	v_pk_mul_f32 v[108:109], v[114:115], v[146:147] op_sel_hi:[1,0]
	v_pk_mul_f32 v[110:111], v[112:113], v[146:147] op_sel_hi:[1,0]
	s_waitcnt vmcnt(5)
	v_pk_mul_f32 v[112:113], v[118:119], v[144:145] op_sel_hi:[1,0]
	v_pk_mul_f32 v[114:115], v[116:117], v[144:145] op_sel_hi:[1,0]
	v_lshlrev_b32_e32 v149, 16, v49
	v_lshlrev_b32_e32 v148, 16, v48
	v_and_b32_e32 v49, 0xffff0000, v49
	v_and_b32_e32 v48, 0xffff0000, v48
	v_lshlrev_b32_e32 v151, 16, v51
	v_lshlrev_b32_e32 v150, 16, v50
	v_and_b32_e32 v51, 0xffff0000, v51
	v_and_b32_e32 v50, 0xffff0000, v50
	v_mov_b32_e32 v178, v80
	v_mov_b32_e32 v179, v82
	v_mov_b32_e32 v82, v81
	s_waitcnt vmcnt(4)
; #define LAS __attribute__((address_space(3)))
; __device__ __forceinline__ unsigned pk2(float lo, float hi) { return f2bf(lo) | (f2bf(hi) << 16); }
; __device__ __forceinline__ void rwkv_proj_phase(const bf16* Z, const float* shift, const float* w0, const float* a0, const float* kkp, const float* kap, const float* rkp, ...
;     ...
;                     for (int qq = 0; qq < 2; ++qq) { const f32x4 t0 = *(const f32x4*)(shift + col + 4 * qq) * fm_, t1 = *(const f32x4*)(shift + BCOLS + col + 4 * qq), t2 = *(const f32x4*)(shift + 2 * BCOLS + col + 4 * qq) * fn_;
;                         const unsigned m0 = qq ? cm.z : cm.x, m1 = qq ? cm.w : cm.y, z0 = qq ? c0.z : c0.x, z1 = qq ? c0.w : c0.y, p0 = qq ? cp.z : cp.x, p1 = qq ? cp.w : cp.y;
;                         val[4 * qq + 0] = t0.x * bflo(m0) + t1.x * bflo(z0) + t2.x * bflo(p0);
;                         val[4 * qq + 1] = t0.y * bfhi(m0) + t1.y * bfhi(z0) + t2.y * bfhi(p0);
;                         val[4 * qq + 2] = t0.z * bflo(m1) + t1.z * bflo(z1) + t2.z * bflo(p1);
;                         val[4 * qq + 3] = t0.w * bfhi(m1) + t1.w * bfhi(z1) + t2.w * bfhi(p1); }
;                     u32x4 pk; pk.x = pk2(val[0], val[1]); pk.y = pk2(val[2], val[3]); pk.z = pk2(val[4], val[5]); pk.w = pk2(val[6], val[7]);
;                     *(LAS u32x4*)(lds + tok * 400 + ch * 16) = pk; }
	v_pk_mul_f32 v[116:117], v[122:123], v[146:147] op_sel_hi:[1,0]
	v_pk_mul_f32 v[118:119], v[120:121], v[146:147] op_sel_hi:[1,0]
	s_waitcnt vmcnt(3)
	v_lshlrev_b32_e32 v121, 16, v125
	v_lshlrev_b32_e32 v120, 16, v124
	s_waitcnt vmcnt(2)
	v_mov_b32_e32 v122, v128
	v_mov_b32_e32 v123, v130
	s_waitcnt vmcnt(1)
	v_lshlrev_b32_e32 v145, 16, v133
	v_lshlrev_b32_e32 v144, 16, v132
	v_mov_b32_e32 v130, v129
	v_and_b32_e32 v129, 0xffff0000, v133
	v_and_b32_e32 v128, 0xffff0000, v132
	v_lshlrev_b32_e32 v133, 16, v127
	v_lshlrev_b32_e32 v132, 16, v126
	s_waitcnt vmcnt(0)
	v_mov_b32_e32 v146, v136
	v_mov_b32_e32 v147, v138
	v_mov_b32_e32 v138, v137
	v_pk_mul_f32 v[136:137], v[184:185], v[140:141]
	v_pk_mul_f32 v[54:55], v[54:55], v[68:69]
	v_pk_mul_f32 v[52:53], v[52:53], v[76:77]
	v_pk_mul_f32 v[62:63], v[62:63], v[70:71]
	v_mov_b32_e32 v68, v64
	v_mov_b32_e32 v69, v60
	v_mov_b32_e32 v60, v65
	v_mov_b32_e32 v64, v114
	v_mov_b32_e32 v65, v112
	v_lshlrev_b32_e32 v181, 16, v79
	v_lshlrev_b32_e32 v180, 16, v78
	v_and_b32_e32 v79, 0xffff0000, v79
	v_and_b32_e32 v78, 0xffff0000, v78
	v_lshlrev_b32_e32 v81, 16, v85
	v_lshlrev_b32_e32 v80, 16, v84
	v_lshlrev_b32_e32 v183, 16, v87
	v_lshlrev_b32_e32 v182, 16, v86
	v_and_b32_e32 v125, 0xffff0000, v125
	v_and_b32_e32 v124, 0xffff0000, v124
	v_and_b32_e32 v127, 0xffff0000, v127
	v_and_b32_e32 v126, 0xffff0000, v126
	v_mov_b32_e32 v70, v110
	v_mov_b32_e32 v71, v108
	v_mov_b32_e32 v108, v111
	v_mov_b32_e32 v112, v115
	v_pk_fma_f32 v[110:111], v[142:143], v[148:149], v[136:137]
	v_pk_fma_f32 v[48:49], v[74:75], v[48:49], v[54:55]
	v_pk_fma_f32 v[52:53], v[178:179], v[150:151], v[52:53]
	v_pk_fma_f32 v[50:51], v[82:83], v[50:51], v[62:63]
	v_pk_mul_f32 v[54:55], v[68:69], v[120:121]
	v_pk_mul_f32 v[62:63], v[64:65], v[132:133]
	v_and_b32_e32 v85, 0xffff0000, v85
	v_and_b32_e32 v84, 0xffff0000, v84
	v_and_b32_e32 v87, 0xffff0000, v87
	v_and_b32_e32 v86, 0xffff0000, v86
	v_lshlrev_b32_e32 v189, 16, v135
	v_lshlrev_b32_e32 v188, 16, v134
	v_mov_b32_e32 v76, v118
	v_mov_b32_e32 v77, v116
	v_pk_mul_f32 v[60:61], v[60:61], v[124:125]
	v_pk_mul_f32 v[64:65], v[112:113], v[126:127]
	v_pk_fma_f32 v[68:69], v[186:187], v[176:177], v[110:111]
	v_pk_fma_f32 v[48:49], v[58:59], v[72:73], v[48:49]
	v_pk_fma_f32 v[52:53], v[56:57], v[180:181], v[52:53]
	v_pk_fma_f32 v[50:51], v[66:67], v[78:79], v[50:51]
	v_pk_fma_f32 v[54:55], v[122:123], v[80:81], v[54:55]
	v_pk_fma_f32 v[58:59], v[146:147], v[182:183], v[62:63]
	v_and_b32_e32 v135, 0xffff0000, v135
	v_and_b32_e32 v134, 0xffff0000, v134
	v_mov_b32_e32 v116, v119
	v_pk_fma_f32 v[56:57], v[130:131], v[84:85], v[60:61]
	v_pk_fma_f32 v[60:61], v[138:139], v[86:87], v[64:65]
	v_bfe_u32 v62, v51, 16, 1
	v_bfe_u32 v63, v50, 16, 1
	v_bfe_u32 v66, v68, 16, 1
	v_bfe_u32 v67, v69, 16, 1
	v_bfe_u32 v72, v52, 16, 1
	v_bfe_u32 v73, v53, 16, 1
	v_pk_fma_f32 v[54:55], v[70:71], v[144:145], v[54:55]
	v_pk_fma_f32 v[58:59], v[76:77], v[188:189], v[58:59]
	v_bfe_u32 v64, v49, 16, 1
	v_bfe_u32 v65, v48, 16, 1
	v_pk_fma_f32 v[56:57], v[108:109], v[128:129], v[56:57]
	v_pk_fma_f32 v[60:61], v[116:117], v[134:135], v[60:61]
	v_add3_u32 v50, v50, v63, s61
	v_add3_u32 v51, v51, v62, s61
	v_add3_u32 v53, v53, v73, s61
	v_add3_u32 v52, v52, v72, s61
	v_add3_u32 v62, v69, v67, s61
	v_add3_u32 v63, v68, v66, s61
	v_bfe_u32 v68, v54, 16, 1
	v_bfe_u32 v69, v55, 16, 1
	v_bfe_u32 v70, v58, 16, 1
	v_bfe_u32 v71, v59, 16, 1
	v_add3_u32 v48, v48, v65, s61
	v_add3_u32 v49, v49, v64, s61
	v_bfe_u32 v64, v61, 16, 1
	v_bfe_u32 v65, v60, 16, 1
	v_bfe_u32 v66, v57, 16, 1
	v_bfe_u32 v67, v56, 16, 1
	v_lshrrev_b32_e32 v63, 16, v63
	v_lshrrev_b32_e32 v62, 16, v62
	v_lshrrev_b32_e32 v52, 16, v52
	v_lshrrev_b32_e32 v53, 16, v53
	v_add3_u32 v59, v59, v71, s61
	v_add3_u32 v58, v58, v70, s61
	v_add3_u32 v55, v55, v69, s61
	v_add3_u32 v54, v54, v68, s61
	v_add3_u32 v56, v56, v67, s61
	v_add3_u32 v57, v57, v66, s61
	v_add3_u32 v60, v60, v65, s61
	v_add3_u32 v61, v61, v64, s61
	v_and_or_b32 v51, v51, s60, v53
	v_and_or_b32 v50, v50, s60, v52
	v_and_or_b32 v49, v49, s60, v62
	v_and_or_b32 v48, v48, s60, v63
	v_lshrrev_b32_e32 v52, 16, v54
	v_lshrrev_b32_e32 v53, 16, v55
	v_lshrrev_b32_e32 v54, 16, v58
	v_lshrrev_b32_e32 v55, 16, v59
	ds_write_b128 v190, v[48:51]
	v_and_or_b32 v51, v61, s60, v55
	v_and_or_b32 v50, v60, s60, v54
	v_and_or_b32 v49, v57, s60, v53
	v_and_or_b32 v48, v56, s60, v52
	ds_write_b128 v191, v[48:51]
	s_cbranch_scc0 .LBB0_1328
; #define LAS __attribute__((address_space(3)))
; __device__ __forceinline__ void rwkv_proj_phase(const bf16* Z, const float* shift, const float* w0, const float* a0, const float* kkp, const float* kap, const float* rkp, ...
;     ...
;                 for (int i = 0; i < 6; ++i) { const int cid = tid + 512 * i;
;                     if (i < 4) { const int cc = cid & 1023, dd = cc >> 9, n = (cc >> 3) & 63, c8 = cc & 7; const bf16* src = ((i < 2) ? w2T : a2T) + ((size_t)(dd * BW + h * 64 + n) * 64 + c8 * 8);
;                         *(LAS u32x4*)(lds + 51200 + ((i < 2) ? 0 : 18432) + (dd * 64 + n) * 144 + c8 * 16) = *(const u32x4*)src; }
;                     else { const int cc = cid - 2048, n = cc >> 4, c8 = cc & 15; *(LAS u32x4*)(lds + 51200 + 36864 + n * 272 + c8 * 16) = *(const u32x4*)(g2T + ((size_t)(h * 64 + n) * 128 + c8 * 8)); } }
;             }
;             __syncthreads();
;             const LAS unsigned char* rkv = lds + (wave * 16 + fr) * 400 + 8 * g;
;             f32x4 kc[4]; float ss = 0.f;
; #pragma unroll
;             for (int nb = 0; nb < 4; ++nb) {
;                 const int c = h * 64 + nb * 16 + 4 * g;
;                 kc[nb] = bf4(*(const LAS u32x2*)(rkv + 128 + nb * 32));
;                 const f32x4 t = kc[nb] * *(const f32x4*)(kkp + c);
;                 ss += (t.x * t.x + t.y * t.y) + (t.z * t.z + t.w * t.w);
;             }
;             ss += __shfl_xor(ss, 16); ss += __shfl_xor(ss, 32);
;             const float inv = rsqrtf(fmaxf(ss, 1e-12f));
;             bf16* sp = SOP + ((size_t)((b * NH + h) * SL + s)) * 576 + 4 * g;
;             float bon = 0.f;
; #pragma unroll
;             for (int nb = 0; nb < 4; ++nb) {
;                 const int n = h * 64 + nb * 16 + fr;
;                 f32x4 accw[2], acca[2], accg = (f32x4){0.f, 0.f, 0.f, 0.f};
; #pragma unroll
;                 for (int d = 0; d < 2; ++d) { accw[d] = (f32x4){0.f, 0.f, 0.f, 0.f}; acca[d] = (f32x4){0.f, 0.f, 0.f, 0.f};
; #pragma unroll
;                     for (int ksl = 0; ksl < 2; ++ksl) {
;                         const bf16x8 wf = *(const LAS bf16x8*)(lds + 51200 + (d * 64 + nb * 16 + fr) * 144 + (32 * ksl + 8 * g) * 2);
;                         const bf16x8 af = *(const LAS bf16x8*)(lds + 51200 + 18432 + (d * 64 + nb * 16 + fr) * 144 + (32 * ksl + 8 * g) * 2);
;                         accw[d] = MFMA16(wf, xf[2 * d + ksl], accw[d]);
	v_or_b32_e32 v50, s28, v154
	v_add_u32_e32 v48, v50, v155
	v_add_u32_e32 v50, v50, v156
	v_or_b32_e32 v64, s28, v157
	v_add_u32_e32 v66, s28, v158
	v_ashrrev_i32_e32 v49, 31, v48
	v_ashrrev_i32_e32 v51, 31, v50
	v_ashrrev_i32_e32 v65, 31, v64
	v_ashrrev_i32_e32 v67, 31, v66
	v_lshlrev_b64 v[56:57], 7, v[48:49]
	v_lshlrev_b64 v[58:59], 7, v[50:51]
	v_lshlrev_b64 v[64:65], 8, v[64:65]
	v_lshlrev_b64 v[66:67], 8, v[66:67]
	v_lshl_add_u64 v[48:49], v[92:93], 0, v[56:57]
	v_lshl_add_u64 v[52:53], v[92:93], 0, v[58:59]
	v_lshl_add_u64 v[56:57], v[94:95], 0, v[56:57]
	v_lshl_add_u64 v[60:61], v[94:95], 0, v[58:59]
	v_lshl_add_u64 v[64:65], v[90:91], 0, v[64:65]
	v_lshl_add_u64 v[68:69], v[90:91], 0, v[66:67]
	global_load_dwordx4 v[48:51], v[48:49], off
	s_nop 0
	global_load_dwordx4 v[52:55], v[52:53], off
	s_nop 0
	global_load_dwordx4 v[56:59], v[56:57], off
	s_nop 0
	global_load_dwordx4 v[60:63], v[60:61], off
	s_nop 0
	global_load_dwordx4 v[64:67], v[64:65], off
	s_nop 0
	global_load_dwordx4 v[68:71], v[68:69], off
	v_lshlrev_b32_e32 v72, 2, v172
	v_add_u32_e32 v116, s28, v72
	v_ashrrev_i32_e32 v117, 31, v116
	v_lshlrev_b64 v[74:75], 2, v[116:117]
	v_lshl_add_u64 v[80:81], s[10:11], 0, v[74:75]
	v_lshl_add_u64 v[76:77], s[8:9], 0, v[74:75]
	v_lshl_add_u64 v[78:79], s[40:41], 0, v[74:75]
	v_lshl_add_u64 v[82:83], s[44:45], 0, v[74:75]
	v_lshlrev_b32_e32 v179, 4, v172
	v_mul_lo_u32 v180, v171, s55
	v_add_u32_e32 v181, s56, v179
	v_add3_u32 v183, 0, v180, v179
	v_ashrrev_i32_e32 v73, 31, v72
	v_readlane_b32 s12, v246, 39
	v_lshl_add_u64 v[114:115], s[50:51], 0, v[74:75]
	v_readlane_b32 s13, v246, 40
	v_readlane_b32 s14, v246, 41
	v_readlane_b32 s15, v246, 42
	v_lshl_add_u64 v[112:113], s[12:13], 0, v[74:75]
	v_add_u32_e32 v134, 16, v116
	v_lshl_add_u64 v[110:111], s[14:15], 0, v[74:75]
	v_ashrrev_i32_e32 v135, 31, v134
	s_add_i32 s79, s79, 1
	s_cmp_eq_u32 s79, 4
	v_readlane_b32 s16, v246, 43
	v_readlane_b32 s17, v246, 44
	v_readlane_b32 s18, v246, 45
	v_readlane_b32 s19, v246, 46
	v_readlane_b32 s20, v246, 47
	v_readlane_b32 s21, v246, 48
	v_readlane_b32 s22, v246, 49
	v_readlane_b32 s23, v246, 50
	v_readlane_b32 s24, v246, 51
	v_readlane_b32 s25, v246, 52
	v_readlane_b32 s26, v246, 53
	v_readlane_b32 s27, v246, 54
	s_waitcnt vmcnt(5)
	ds_write_b128 v161, v[48:51] offset:51200
	s_waitcnt vmcnt(4)
	ds_write_b128 v162, v[52:55] offset:51200
	s_waitcnt vmcnt(3)
	ds_write_b128 v163, v[56:59]
	s_waitcnt vmcnt(2)
	ds_write_b128 v164, v[60:63]
	s_waitcnt vmcnt(1)
	ds_write_b128 v165, v[64:67]
	s_waitcnt vmcnt(0)
	ds_write_b128 v166, v[68:71]
	s_waitcnt lgkmcnt(0)
	s_barrier
	global_load_dwordx4 v[118:121], v[80:81], off
	global_load_dwordx4 v[122:125], v[82:83], off
	global_load_dwordx4 v[126:129], v[76:77], off
	global_load_dwordx4 v[130:133], v[78:79], off
	v_and_b32_e32 v51, 64, v169
	v_xor_b32_e32 v53, 16, v169
	v_add_u32_e32 v58, 64, v51
	v_add_u32_e32 v50, s52, v171
	v_xor_b32_e32 v54, 32, v169
	v_add_u32_e32 v55, s7, v173
	v_mul_lo_u32 v56, v171, s57
	v_cmp_lt_i32_e32 vcc, v53, v58
	v_lshlrev_b32_e32 v52, 3, v172
	v_mov_b64_e32 v[48:49], s[34:35]
	v_mul_lo_u32 v57, v50, s65
	v_mad_u64_u32 v[50:51], s[0:1], v55, s66, v[102:103]
	v_add_u32_e32 v55, 0x2400, v180
	v_add3_u32 v178, s53, v179, v56
	v_cndmask_b32_e32 v56, v169, v53, vcc
	v_cmp_lt_i32_e32 vcc, v54, v58
	v_add_u32_e32 v66, v181, v180
	v_add3_u32 v182, 0, v57, v52
	v_cndmask_b32_e32 v57, v169, v54, vcc
	v_mad_i64_i32 v[64:65], s[0:1], v50, s67, v[48:49]
	ds_read_b128 v[48:51], v183 offset:51200
	v_add_u32_e32 v67, v181, v55
	v_add3_u32 v68, s56, v55, v179
	ds_read_b128 v[52:55], v66
	v_lshlrev_b32_e32 v177, 2, v56
	v_lshlrev_b32_e32 v176, 2, v57
	ds_read_b128 v[56:59], v183 offset:51264
	ds_read_b128 v[60:63], v183 offset:60416
	v_lshl_add_u64 v[108:109], v[72:73], 1, v[64:65]
	ds_read_b128 v[80:83], v66 offset:64
	ds_read_b128 v[64:67], v67
	ds_read_b128 v[84:87], v183 offset:60480
	ds_read2_b64 v[76:79], v182 offset0:16 offset1:20
	ds_read_b128 v[140:143], v68 offset:64
	global_load_dwordx4 v[184:187], v[114:115], off offset:3072
	global_load_dwordx4 v[72:75], v[114:115], off offset:3136
	s_waitcnt lgkmcnt(8)
	v_mfma_f32_16x16x32_bf16 v[48:51], v[48:51], v[0:3], 0
	s_waitcnt lgkmcnt(1)
	v_lshlrev_b32_e32 v204, 16, v79
	v_and_b32_e32 v79, 0xffff0000, v79
	v_mfma_f32_16x16x32_bf16 v[52:55], v[52:55], v[16:19], 0
	v_mov_b32_e32 v205, v79
	s_waitcnt vmcnt(0)
	v_pk_mul_f32 v[74:75], v[74:75], v[204:205]
	v_mfma_f32_16x16x32_bf16 v[136:139], v[60:63], v[8:11], 0
	v_mul_f32_e64 v74, v74, v74
	v_mul_f32_e64 v75, v75, v75
	v_mfma_f32_16x16x32_bf16 v[144:147], v[64:67], v[24:27], 0
	ds_read2_b64 v[64:67], v182 offset0:24 offset1:28
	global_load_dwordx4 v[68:71], v[114:115], off offset:3200
	global_load_dwordx4 v[60:63], v[114:115], off offset:3264
	ds_read_b128 v[188:191], v178
	ds_read_b128 v[192:195], v178 offset:64
	v_mfma_f32_16x16x32_bf16 v[148:151], v[56:59], v[4:7], v[48:51]
	v_mfma_f32_16x16x32_bf16 v[196:199], v[80:83], v[20:23], v[52:55]
	ds_read_b128 v[200:203], v178 offset:128
	ds_read_b128 v[80:83], v178 offset:192
	s_nop 0
	ds_read2_b64 v[52:55], v182 offset1:4
	ds_read2_b64 v[48:51], v182 offset0:32 offset1:36
	s_nop 1
	v_add_f32_e32 v127, v149, v127
	v_mfma_f32_16x16x32_bf16 v[136:139], v[84:87], v[12:15], v[136:139]
	global_load_dwordx4 v[84:87], v[112:113], off offset:3072
	global_load_dwordx4 v[56:59], v[110:111], off offset:3072
	v_add_f32_e32 v88, v196, v118
	v_mul_f32_e32 v88, 0xbfb8aa3b, v88
	s_waitcnt lgkmcnt(7)
; #define LAS __attribute__((address_space(3)))
; __device__ __forceinline__ void rwkv_proj_phase(const bf16* Z, const float* shift, const float* w0, const float* a0, const float* kkp, const float* kap, const float* rkp, ...
;     ...
;                         const bf16x8 wf = *(const LAS bf16x8*)(lds + 51200 + (d * 64 + nb * 16 + fr) * 144 + (32 * ksl + 8 * g) * 2);
;                         const bf16x8 af = *(const LAS bf16x8*)(lds + 51200 + 18432 + (d * 64 + nb * 16 + fr) * 144 + (32 * ksl + 8 * g) * 2);
;                         accw[d] = MFMA16(wf, xf[2 * d + ksl], accw[d]);
;                         acca[d] = MFMA16(af, xf[4 + 2 * d + ksl], acca[d]); } }
; #pragma unroll
;                 for (int ksl = 0; ksl < 4; ++ksl) { const bf16x8 gf = *(const LAS bf16x8*)(lds + 51200 + 36864 + (nb * 16 + fr) * 272 + (32 * ksl + 8 * g) * 2); accg = MFMA16(gf, xf[8 + ksl], accg); }
;                 const int c = h * 64 + nb * 16 + 4 * g;
;                 const f32x4 rc = bf4(*(const LAS u32x2*)(rkv + nb * 32)), vc = bf4(*(const LAS u32x2*)(rkv + 256 + nb * 32));
;                 const f32x4 w00 = *(const f32x4*)(w0 + c), w01 = *(const f32x4*)(w0 + BW + c), a00 = *(const f32x4*)(a0 + c), a01 = *(const f32x4*)(a0 + BW + c);
;                 const f32x4 kk4 = *(const f32x4*)(kkp + c), ka4 = *(const f32x4*)(kap + c), rk4 = *(const f32x4*)(rkp + c);
;                 float o[9][4];
; #pragma unroll
;                 for (int e = 0; e < 4; ++e) {
;                     const float ad0 = sigmoid_f(a00[e] + acca[0][e]), ad1 = sigmoid_f(a01[e] + acca[1][e]);
;                     const float lw0 = -0.60653066f * sigmoid_f(w00[e] + accw[0][e]), lw1 = -0.60653066f * sigmoid_f(w01[e] + accw[1][e]);
;                     const float k = kc[nb][e], kk = k * kk4[e] * inv;
;                     const float kd0 = k * (1.f + (ad0 - 1.f) * ka4[e]), kd1 = k * (1.f + (ad1 - 1.f) * ka4[e]);
;                     bon += rc[e] * (kd0 + kd1) * rk4[e];
;                     o[0][e] = rc[e]; o[1][e] = vc[e]; o[2][e] = -kk; o[3][e] = lw0; o[4][e] = kd0; o[5][e] = kk * ad0; o[6][e] = lw1; o[7][e] = kd1; o[8][e] = kk * ad1;
;                 }
; #pragma unroll
;                 for (int vv = 0; vv < 9; ++vv) { u32x2 w; w.x = pk2(o[vv][0], o[vv][1]); w.y = pk2(o[vv][2], o[vv][3]); *(u32x2*)(sp + vv * 64 + nb * 16) = w; }
	v_mfma_f32_16x16x32_bf16 v[142:145], v[140:143], v[28:31], v[144:147]
	v_exp_f32_e32 v88, v88
	v_add_f32_e32 v121, v199, v121
	v_add_f32_e32 v128, v150, v128
	v_mul_f32_e32 v127, 0xbfb8aa3b, v127
	v_add_f32_e32 v88, 1.0, v88
	s_nop 2
	v_add_f32_e32 v118, v142, v122
	v_mul_f32_e32 v118, 0xbfb8aa3b, v118
	v_exp_f32_e32 v118, v118
	v_add_f32_e32 v122, v148, v126
	v_add_f32_e32 v126, v136, v130
	v_rcp_f32_e32 v142, v88
	v_add_f32_e32 v118, 1.0, v118
	v_rcp_f32_e32 v136, v118
	v_mul_f32_e32 v88, 0xbfb8aa3b, v121
	v_add_f32_e32 v118, v145, v125
	v_add_f32_e32 v124, v144, v124
	v_exp_f32_e32 v88, v88
	v_mul_f32_e32 v118, 0xbfb8aa3b, v118
	v_mul_f32_e32 v124, 0xbfb8aa3b, v124
	v_exp_f32_e32 v118, v118
	v_exp_f32_e32 v124, v124
	v_add_f32_e32 v88, 1.0, v88
	v_rcp_f32_e32 v145, v88
	v_add_f32_e32 v88, 1.0, v118
	v_add_f32_e32 v123, v143, v123
	v_add_f32_e32 v124, 1.0, v124
	v_rcp_f32_e32 v141, v88
	v_add_f32_e32 v88, v151, v129
	v_add_f32_e32 v130, v137, v131
	v_mul_f32_e32 v122, 0xbfb8aa3b, v122
	v_mul_f32_e32 v126, 0xbfb8aa3b, v126
	v_mul_f32_e32 v123, 0xbfb8aa3b, v123
	v_mul_f32_e32 v128, 0xbfb8aa3b, v128
	v_rcp_f32_e32 v137, v124
	v_mul_f32_e32 v88, 0xbfb8aa3b, v88
	v_add_f32_e32 v124, v139, v133
	v_mul_f32_e32 v130, 0xbfb8aa3b, v130
	v_exp_f32_e32 v122, v122
	v_exp_f32_e32 v126, v126
	v_exp_f32_e32 v123, v123
	v_exp_f32_e32 v127, v127
	v_exp_f32_e32 v128, v128
	v_exp_f32_e32 v88, v88
	v_mul_f32_e32 v124, 0xbfb8aa3b, v124
	v_exp_f32_e32 v130, v130
	v_exp_f32_e32 v124, v124
	v_add_f32_e32 v120, v198, v120
	v_add_f32_e32 v122, 1.0, v122
	v_add_f32_e32 v126, 1.0, v126
	v_add_f32_e32 v123, 1.0, v123
	v_add_f32_e32 v127, 1.0, v127
	v_add_f32_e32 v128, 1.0, v128
	v_add_f32_e32 v88, 1.0, v88
	v_add_f32_e32 v119, v197, v119
	v_add_f32_e32 v131, v138, v132
	v_mul_f32_e32 v120, 0xbfb8aa3b, v120
	v_add_f32_e32 v132, 1.0, v130
	v_rcp_f32_e32 v122, v122
	v_rcp_f32_e32 v130, v126
	v_rcp_f32_e32 v140, v123
	v_rcp_f32_e32 v126, v127
	v_rcp_f32_e32 v123, v128
	v_rcp_f32_e32 v127, v88
	v_add_f32_e32 v88, 1.0, v124
	v_lshlrev_b32_e32 v124, 16, v76
	v_lshlrev_b32_e32 v128, 16, v77
	v_and_b32_e32 v77, 0xffff0000, v77
	v_and_b32_e32 v76, 0xffff0000, v76
	v_mul_f32_e32 v119, 0xbfb8aa3b, v119
	v_exp_f32_e32 v120, v120
	v_mov_b32_e32 v129, v77
	v_mov_b32_e32 v125, v76
	v_exp_f32_e32 v119, v119
	v_pk_mul_f32 v[138:139], v[186:187], v[128:129]
	v_pk_mul_f32 v[146:147], v[184:185], v[124:125]
	v_pk_mul_f32 v[138:139], v[138:139], v[138:139]
	v_pk_mul_f32 v[146:147], v[146:147], v[146:147]
	v_mov_b32_e32 v125, v128
	v_pk_mov_b32 v[148:149], v[146:147], v[138:139] op_sel:[1,0]
	v_mov_b32_e32 v147, v139
	v_mov_b32_e32 v128, v184
	v_mov_b32_e32 v129, v186
	v_pk_mul_f32 v[122:123], v[122:123], s[48:49] op_sel_hi:[1,0]
	v_add_f32_e32 v120, 1.0, v120
	v_rcp_f32_e32 v133, v88
	v_pk_add_f32 v[138:139], v[148:149], v[146:147]
	v_pk_mul_f32 v[146:147], v[128:129], v[124:125]
	v_pk_mul_f32 v[126:127], v[126:127], s[48:49] op_sel_hi:[1,0]
	s_nop 0
	s_nop 0
	v_add_f32_e32 v119, 1.0, v119
	v_rcp_f32_e32 v143, v120
	s_nop 0
	s_nop 0
	s_nop 0
	s_nop 0
	v_rcp_f32_e32 v144, v119
	s_nop 0
	s_nop 0
	v_mul_f32_e32 v131, 0xbfb8aa3b, v131
	s_nop 0
	s_nop 0
	v_exp_f32_e32 v131, v131
	v_cvt_pk_bf16_f32 v123, v123, v127
	v_cvt_pk_bf16_f32 v122, v122, v126
	s_waitcnt lgkmcnt(1)
	global_store_dwordx2 v[108:109], v[52:53], off
	s_waitcnt lgkmcnt(0)
	global_store_dwordx2 v[108:109], v[48:49], off offset:128
	v_pk_add_f32 v[150:151], v[138:139], v[138:139] op_sel:[0,1] op_sel_hi:[1,0]
	global_store_dwordx2 v[108:109], v[122:123], off offset:384
	v_pk_add_f32 v[122:123], v[142:143], -1.0 op_sel_hi:[1,0]
	s_waitcnt vmcnt(4)
	v_mov_b32_e32 v138, v84
	v_mov_b32_e32 v139, v86
	v_pk_fma_f32 v[126:127], v[138:139], v[122:123], 1.0 op_sel_hi:[1,1,0]
	v_pk_add_f32 v[122:123], v[144:145], -1.0 op_sel_hi:[1,0]
	v_mov_b32_e32 v86, v85
	v_pk_fma_f32 v[128:129], v[86:87], v[122:123], 1.0 op_sel_hi:[1,1,0]
	v_pk_mul_f32 v[84:85], v[126:127], v[124:125]
	v_add_f32_e32 v131, 1.0, v131
	v_pk_mul_f32 v[122:123], v[128:129], v[76:77]
	s_nop 0
	s_nop 0
	v_rcp_f32_e32 v131, v131
	s_nop 0
	s_nop 0
	s_nop 0
	s_nop 0
	v_rcp_f32_e32 v132, v132
	s_nop 0
	s_nop 0
	v_mfma_f32_16x16x32_bf16 v[118:121], v[188:191], v[32:35], 0
	s_nop 0
	s_nop 0
	v_cvt_pk_bf16_f32 v85, v85, v123
	v_cvt_pk_bf16_f32 v84, v84, v122
	global_store_dwordx2 v[108:109], v[84:85], off offset:512
	v_pk_mul_f32 v[84:85], v[130:131], s[48:49] op_sel_hi:[1,0]
	v_pk_mul_f32 v[122:123], v[132:133], s[48:49] op_sel_hi:[1,0]
	s_nop 0
	s_nop 0
	v_mfma_f32_16x16x32_bf16 v[118:121], v[192:195], v[36:39], v[118:121]
	s_nop 0
	s_nop 0
	s_nop 0
	s_nop 0
	s_nop 0
	s_nop 0
	s_nop 0
	s_nop 0
	v_cvt_pk_bf16_f32 v85, v85, v123
	v_cvt_pk_bf16_f32 v84, v84, v122
	v_mfma_f32_16x16x32_bf16 v[118:121], v[200:203], v[40:43], v[118:121]
	global_store_dwordx2 v[108:109], v[84:85], off offset:768
	v_pk_add_f32 v[84:85], v[136:137], -1.0 op_sel_hi:[1,0]
	v_pk_add_f32 v[122:123], v[140:141], -1.0 op_sel_hi:[1,0]
	v_pk_fma_f32 v[84:85], v[138:139], v[84:85], 1.0 op_sel_hi:[1,1,0]
	v_pk_fma_f32 v[86:87], v[86:87], v[122:123], 1.0 op_sel_hi:[1,1,0]
	v_pk_mul_f32 v[132:133], v[84:85], v[124:125]
	v_pk_mul_f32 v[130:131], v[86:87], v[76:77]
	s_nop 0
	s_nop 0
	s_nop 0
	s_nop 0
	v_mfma_f32_16x16x32_bf16 v[80:83], v[80:83], v[44:47], v[118:121]
	s_nop 0
	s_nop 0
	s_nop 0
	s_nop 0
	s_nop 0
	s_nop 0
	v_cvt_pk_bf16_f32 v85, v133, v131
	v_cvt_pk_bf16_f32 v84, v132, v130
	v_lshlrev_b32_e32 v138, 16, v78
	v_and_b32_e32 v78, 0xffff0000, v78
	global_store_dwordx2 v[108:109], v[84:85], off offset:896
	s_nop 0
	v_mov_b32_e32 v139, v78
	s_nop 0
	v_pk_mul_f32 v[72:73], v[72:73], v[138:139]
	v_mov_b32_e32 v186, v185
; __device__ __forceinline__ void rwkv_proj_phase(const bf16* Z, const float* shift, const float* w0, const float* a0, const float* kkp, const float* kap, const float* rkp, ...
;     ...
;             for (int nb = 0; nb < 4; ++nb) {
;                 const int c = h * 64 + nb * 16 + 4 * g;
;                 kc[nb] = bf4(*(const LAS u32x2*)(rkv + 128 + nb * 32));
;                 const f32x4 t = kc[nb] * *(const f32x4*)(kkp + c);
;                 ss += (t.x * t.x + t.y * t.y) + (t.z * t.z + t.w * t.w);
;             }
;             ss += __shfl_xor(ss, 16); ss += __shfl_xor(ss, 32);
;             const float inv = rsqrtf(fmaxf(ss, 1e-12f));
;             bf16* sp = SOP + ((size_t)((b * NH + h) * SL + s)) * 576 + 4 * g;
;             float bon = 0.f;
; #pragma unroll
;             for (int nb = 0; nb < 4; ++nb) {
;                 const int n = h * 64 + nb * 16 + fr;
;                 f32x4 accw[2], acca[2], accg = (f32x4){0.f, 0.f, 0.f, 0.f};
; #pragma unroll
;                 for (int d = 0; d < 2; ++d) { accw[d] = (f32x4){0.f, 0.f, 0.f, 0.f}; acca[d] = (f32x4){0.f, 0.f, 0.f, 0.f};
; #pragma unroll
;                     for (int ksl = 0; ksl < 2; ++ksl) {
;                         const bf16x8 wf = *(const LAS bf16x8*)(lds + 51200 + (d * 64 + nb * 16 + fr) * 144 + (32 * ksl + 8 * g) * 2);
;                         const bf16x8 af = *(const LAS bf16x8*)(lds + 51200 + 18432 + (d * 64 + nb * 16 + fr) * 144 + (32 * ksl + 8 * g) * 2);
;                         accw[d] = MFMA16(wf, xf[2 * d + ksl], accw[d]);
;                         acca[d] = MFMA16(af, xf[4 + 2 * d + ksl], acca[d]); } }
; #pragma unroll
;                 for (int ksl = 0; ksl < 4; ++ksl) { const bf16x8 gf = *(const LAS bf16x8*)(lds + 51200 + 36864 + (nb * 16 + fr) * 272 + (32 * ksl + 8 * g) * 2); accg = MFMA16(gf, xf[8 + ksl], accg); }
;                 const int c = h * 64 + nb * 16 + 4 * g;
;                 const f32x4 rc = bf4(*(const LAS u32x2*)(rkv + nb * 32)), vc = bf4(*(const LAS u32x2*)(rkv + 256 + nb * 32));
;                 const f32x4 w00 = *(const f32x4*)(w0 + c), w01 = *(const f32x4*)(w0 + BW + c), a00 = *(const f32x4*)(a0 + c), a01 = *(const f32x4*)(a0 + BW + c);
;                 const f32x4 kk4 = *(const f32x4*)(kkp + c), ka4 = *(const f32x4*)(kap + c), rk4 = *(const f32x4*)(rkp + c);
;                 float o[9][4];
; #pragma unroll
;                 for (int e = 0; e < 4; ++e) {
	v_add_u32_e32 v84, 0x900, v180
	v_pk_mul_f32 v[72:73], v[72:73], v[72:73]
	v_pk_mul_f32 v[148:149], v[186:187], v[76:77]
	v_add3_u32 v185, 0, v84, v179
	v_add_u32_e32 v186, v181, v84
	v_pk_mov_b32 v[84:85], v[72:73], v[74:75] op_sel:[1,0]
	v_mov_b32_e32 v73, v75
	v_and_b32_e32 v120, 0xffff0000, v64
	v_pk_add_f32 v[72:73], v[84:85], v[72:73]
	v_lshlrev_b32_e32 v122, 16, v64
	v_and_b32_e32 v121, 0xffff0000, v65
	v_mov_b32_e32 v123, v120
	v_pk_add_f32 v[74:75], v[72:73], v[72:73] op_sel:[0,1] op_sel_hi:[1,0]
	v_lshlrev_b32_e32 v72, 16, v65
	v_mov_b32_e32 v73, v121
	v_pk_mul_f32 v[68:69], v[68:69], v[122:123]
	v_pk_mul_f32 v[64:65], v[70:71], v[72:73]
	v_mul_f32_e32 v70, v69, v69
	v_and_b32_e32 v85, 0xffff0000, v67
	v_and_b32_e32 v84, 0xffff0000, v66
	v_pk_fma_f32 v[68:69], v[68:69], v[68:69], v[70:71] op_sel_hi:[1,1,0]
	v_mul_f32_e32 v70, v65, v65
	v_lshlrev_b32_e32 v86, 16, v66
	v_lshlrev_b32_e32 v118, 16, v67
	v_mov_b32_e32 v119, v85
	v_mov_b32_e32 v87, v84
	v_pk_fma_f32 v[64:65], v[64:65], v[64:65], v[70:71] op_sel_hi:[1,1,0]
	v_pk_mul_f32 v[62:63], v[62:63], v[118:119]
	v_pk_mul_f32 v[60:61], v[60:61], v[86:87]
	v_mul_f32_e32 v69, v62, v62
	v_mul_f32_e32 v151, v60, v60
	v_mul_f32_e32 v75, v61, v61
	v_mul_f32_e32 v65, v63, v63
	v_pk_add_f32 v[60:61], v[150:151], v[74:75]
	v_pk_add_f32 v[62:63], v[68:69], v[64:65]
	v_pk_add_f32 v[60:61], v[60:61], v[62:63]
	v_cvt_pk_bf16_f32 v192, v80, v81
	v_add_f32_e32 v73, v60, v61
	ds_bpermute_b32 v74, v177, v73
	v_bfe_u32 v80, v82, 16, 1
	v_add3_u32 v80, v82, v80, s61
	v_lshrrev_b32_e32 v88, 16, v80
	v_bfe_u32 v80, v83, 16, 1
	v_add3_u32 v184, v83, v80, s61
	ds_read_b128 v[80:83], v185 offset:51200
	ds_read_b128 v[64:67], v185 offset:51264
	s_waitcnt lgkmcnt(2)
	v_add_f32_e32 v73, v73, v74
	ds_bpermute_b32 v74, v176, v73
	v_and_or_b32 v193, v184, s60, v88
	s_waitcnt lgkmcnt(2)
	v_mfma_f32_16x16x32_bf16 v[68:71], v[80:83], v[0:3], 0
	s_waitcnt lgkmcnt(0)
	v_add_f32_e32 v73, v73, v74
	v_max_f32_e32 v73, 0x2b8cbccc, v73
	v_rsq_f32_e32 v88, v73
	v_mfma_f32_16x16x32_bf16 v[188:191], v[64:67], v[4:7], v[68:71]
	ds_read_b128 v[60:63], v186
	v_lshlrev_b64 v[74:75], 2, v[134:135]
	v_pk_mul_f32 v[66:67], v[146:147], v[88:89] op_sel_hi:[1,0] neg_lo:[0,1] neg_hi:[0,1]
	v_pk_mul_f32 v[68:69], v[148:149], v[88:89] op_sel_hi:[1,0] neg_lo:[0,1] neg_hi:[0,1]
	s_nop 0
	s_nop 0
	s_nop 0
	s_nop 0
	s_nop 0
	s_nop 0
	s_nop 0
	s_nop 0
	v_cvt_pk_bf16_f32 v71, v67, v69
	v_cvt_pk_bf16_f32 v70, v66, v68
	global_store_dwordx2 v[108:109], v[70:71], off offset:256
	v_pk_mul_f32 v[70:71], v[66:67], v[142:143] neg_lo:[1,0] neg_hi:[1,0]
	v_pk_mul_f32 v[134:135], v[68:69], v[144:145] neg_lo:[1,0] neg_hi:[1,0]
	s_nop 0
	s_nop 0
	s_nop 0
	s_nop 0
	s_nop 0
	s_nop 0
	s_nop 0
	s_nop 0
	ds_read_b128 v[184:187], v186 offset:64
	v_cvt_pk_bf16_f32 v71, v71, v135
	v_cvt_pk_bf16_f32 v70, v70, v134
	v_pk_mul_f32 v[66:67], v[66:67], v[136:137] neg_lo:[1,0] neg_hi:[1,0]
	global_store_dwordx2 v[108:109], v[70:71], off offset:640
	v_pk_mul_f32 v[68:69], v[68:69], v[140:141] neg_lo:[1,0] neg_hi:[1,0]
	s_nop 0
	s_nop 0
	s_nop 0
	s_nop 0
	s_nop 0
	s_nop 0
	s_nop 0
	v_lshlrev_b64 v[80:81], 1, v[116:117]
	s_waitcnt lgkmcnt(1)
	v_mfma_f32_16x16x32_bf16 v[60:63], v[60:63], v[16:19], 0
	v_cvt_pk_bf16_f32 v67, v67, v69
	v_cvt_pk_bf16_f32 v66, v66, v68
	v_lshl_add_u64 v[82:83], v[104:105], 0, v[80:81]
	v_lshl_add_u64 v[64:65], s[10:11], 0, v[74:75]
	global_store_dwordx2 v[108:109], v[66:67], off offset:1024
	global_store_dwordx2 v[82:83], v[192:193], off
	global_load_dwordx4 v[134:137], v[64:65], off
	v_lshl_add_u64 v[68:69], s[44:45], 0, v[74:75]
	v_add_u32_e32 v73, 0x2d00, v180
	global_load_dwordx4 v[140:143], v[68:69], off
	s_waitcnt lgkmcnt(0)
	v_mfma_f32_16x16x32_bf16 v[144:147], v[184:187], v[20:23], v[60:63]
	v_lshl_add_u64 v[148:149], s[8:9], 0, v[74:75]
	ds_read_b128 v[64:67], v183 offset:62720
	v_lshl_add_u64 v[74:75], s[40:41], 0, v[74:75]
	v_add_u32_e32 v60, v181, v73
	ds_read_b128 v[60:63], v60
	ds_read_b128 v[68:71], v183 offset:62784
	global_load_dwordx4 v[148:151], v[148:149], off
	v_add3_u32 v73, s56, v73, v179
	global_load_dwordx4 v[184:187], v[74:75], off
	ds_read_b128 v[192:195], v73 offset:64
	global_load_dwordx4 v[196:199], v[114:115], off offset:3136
	s_waitcnt lgkmcnt(3)
	v_mfma_f32_16x16x32_bf16 v[64:67], v[64:67], v[8:11], 0
	v_mov_b32_e32 v139, v204
	global_load_dwordx4 v[204:207], v[112:113], off offset:3136
	v_and_b32_e32 v123, 0xffff0000, v53
	s_waitcnt lgkmcnt(2)
	v_mfma_f32_16x16x32_bf16 v[60:63], v[60:63], v[24:27], 0
	s_waitcnt lgkmcnt(1)
	v_mfma_f32_16x16x32_bf16 v[200:203], v[68:71], v[12:15], v[64:67]
	ds_read_b128 v[68:71], v178 offset:4480
	s_nop 1
	ds_read_b128 v[64:67], v178 offset:4352
	s_waitcnt lgkmcnt(2)
	v_mfma_f32_16x16x32_bf16 v[192:195], v[192:195], v[28:31], v[60:63]
	s_waitcnt vmcnt(3)
	v_add_f32_e32 v73, v188, v148
	s_nop 0
	ds_read_b128 v[60:63], v178 offset:4416
	s_waitcnt lgkmcnt(1)
	v_mfma_f32_16x16x32_bf16 v[64:67], v[64:67], v[32:35], 0
	v_mul_f32_e32 v73, 0xbfb8aa3b, v73
	s_waitcnt vmcnt(2)
	v_add_f32_e32 v74, v200, v184
	v_exp_f32_e32 v73, v73
	s_waitcnt lgkmcnt(0)
	v_mfma_f32_16x16x32_bf16 v[60:63], v[60:63], v[36:39], v[64:67]
	s_nop 2
	ds_read_b128 v[64:67], v178 offset:4544
	v_mul_f32_e32 v74, 0xbfb8aa3b, v74
	v_exp_f32_e32 v75, v74
	v_mfma_f32_16x16x32_bf16 v[60:63], v[68:71], v[40:43], v[60:63]
	v_add_u32_e32 v70, 32, v116
	v_ashrrev_i32_e32 v71, 31, v70
	s_waitcnt lgkmcnt(0)
; #define LAS __attribute__((address_space(3)))
; __device__ __forceinline__ void rwkv_proj_phase(const bf16* Z, const float* shift, const float* w0, const float* a0, const float* kkp, const float* kap, const float* rkp, ...
;     ...
;             for (int nb = 0; nb < 4; ++nb) {
;                 const int n = h * 64 + nb * 16 + fr;
;                 f32x4 accw[2], acca[2], accg = (f32x4){0.f, 0.f, 0.f, 0.f};
; #pragma unroll
;                 for (int d = 0; d < 2; ++d) { accw[d] = (f32x4){0.f, 0.f, 0.f, 0.f}; acca[d] = (f32x4){0.f, 0.f, 0.f, 0.f};
; #pragma unroll
;                     for (int ksl = 0; ksl < 2; ++ksl) {
;                         const bf16x8 wf = *(const LAS bf16x8*)(lds + 51200 + (d * 64 + nb * 16 + fr) * 144 + (32 * ksl + 8 * g) * 2);
;                         const bf16x8 af = *(const LAS bf16x8*)(lds + 51200 + 18432 + (d * 64 + nb * 16 + fr) * 144 + (32 * ksl + 8 * g) * 2);
;                         accw[d] = MFMA16(wf, xf[2 * d + ksl], accw[d]);
;                         acca[d] = MFMA16(af, xf[4 + 2 * d + ksl], acca[d]); } }
; #pragma unroll
;                 for (int ksl = 0; ksl < 4; ++ksl) { const bf16x8 gf = *(const LAS bf16x8*)(lds + 51200 + 36864 + (nb * 16 + fr) * 272 + (32 * ksl + 8 * g) * 2); accg = MFMA16(gf, xf[8 + ksl], accg); }
;                 const int c = h * 64 + nb * 16 + 4 * g;
;                 const f32x4 rc = bf4(*(const LAS u32x2*)(rkv + nb * 32)), vc = bf4(*(const LAS u32x2*)(rkv + 256 + nb * 32));
;                 const f32x4 w00 = *(const f32x4*)(w0 + c), w01 = *(const f32x4*)(w0 + BW + c), a00 = *(const f32x4*)(a0 + c), a01 = *(const f32x4*)(a0 + BW + c);
;                 const f32x4 kk4 = *(const f32x4*)(kkp + c), ka4 = *(const f32x4*)(kap + c), rk4 = *(const f32x4*)(rkp + c);
;                 float o[9][4];
; #pragma unroll
;                 for (int e = 0; e < 4; ++e) {
;                     const float ad0 = sigmoid_f(a00[e] + acca[0][e]), ad1 = sigmoid_f(a01[e] + acca[1][e]);
;                     const float lw0 = -0.60653066f * sigmoid_f(w00[e] + accw[0][e]), lw1 = -0.60653066f * sigmoid_f(w01[e] + accw[1][e]);
;                     const float k = kc[nb][e], kk = k * kk4[e] * inv;
;                     const float kd0 = k * (1.f + (ad0 - 1.f) * ka4[e]), kd1 = k * (1.f + (ad1 - 1.f) * ka4[e]);
;                     bon += rc[e] * (kd0 + kd1) * rk4[e];
	v_mfma_f32_16x16x32_bf16 v[60:63], v[64:67], v[44:47], v[60:63]
	s_nop 7
	s_nop 0
	s_nop 0
	s_nop 0
	s_nop 0
	s_nop 0
	v_cvt_pk_bf16_f32 v68, v60, v61
	v_add_f32_e32 v64, v144, v134
	s_nop 0
	s_nop 0
	v_mul_f32_e32 v64, 0xbfb8aa3b, v64
	v_cvt_pk_bf16_f32 v69, v62, v63
	v_lshlrev_b64 v[60:61], 2, v[70:71]
	v_exp_f32_e32 v70, v64
	v_add_f32_e32 v64, v192, v140
	v_mul_f32_e32 v64, 0xbfb8aa3b, v64
	v_exp_f32_e32 v71, v64
	s_waitcnt vmcnt(1)
	v_mov_b32_e32 v144, v196
	global_load_dwordx4 v[64:67], v[110:111], off offset:3136
	v_add_f32_e32 v70, 1.0, v70
	v_add_f32_e32 v71, 1.0, v71
	v_rcp_f32_e32 v74, v71
	v_add_f32_e32 v71, 1.0, v73
	v_rcp_f32_e32 v134, v71
	v_add_f32_e32 v71, 1.0, v75
	v_rcp_f32_e32 v140, v71
	v_add_f32_e32 v71, v145, v135
	v_mul_f32_e32 v71, 0xbfb8aa3b, v71
	v_add_f32_e32 v73, v193, v141
	v_exp_f32_e32 v71, v71
	v_mul_f32_e32 v73, 0xbfb8aa3b, v73
	v_exp_f32_e32 v73, v73
	v_add_f32_e32 v75, v201, v185
	v_add_f32_e32 v71, 1.0, v71
	v_rcp_f32_e32 v148, v71
	v_add_f32_e32 v71, 1.0, v73
	v_add_f32_e32 v73, v189, v149
	v_mul_f32_e32 v73, 0xbfb8aa3b, v73
	v_exp_f32_e32 v73, v73
	v_mul_f32_e32 v75, 0xbfb8aa3b, v75
	v_exp_f32_e32 v75, v75
	v_rcp_f32_e32 v184, v71
	v_add_f32_e32 v71, 1.0, v73
	v_rcp_f32_e32 v188, v71
	v_add_f32_e32 v71, 1.0, v75
	v_add_f32_e32 v73, v194, v142
	v_add_f32_e32 v75, v190, v150
	v_mul_f32_e32 v73, 0xbfb8aa3b, v73
	v_mul_f32_e32 v75, 0xbfb8aa3b, v75
	v_exp_f32_e32 v73, v73
	v_exp_f32_e32 v87, v75
	v_add_f32_e32 v75, v202, v186
	v_mul_f32_e32 v75, 0xbfb8aa3b, v75
	v_exp_f32_e32 v117, v75
	v_add_f32_e32 v73, 1.0, v73
	v_rcp_f32_e32 v75, v73
	v_add_f32_e32 v73, 1.0, v87
	v_rcp_f32_e32 v135, v73
	v_add_f32_e32 v73, 1.0, v117
	v_rcp_f32_e32 v141, v73
	v_add_f32_e32 v73, v147, v137
	v_mul_f32_e32 v73, 0xbfb8aa3b, v73
	v_add_f32_e32 v87, v195, v143
	v_exp_f32_e32 v73, v73
	v_mul_f32_e32 v87, 0xbfb8aa3b, v87
	v_exp_f32_e32 v87, v87
	v_add_f32_e32 v117, v203, v187
	v_add_f32_e32 v73, 1.0, v73
	v_rcp_f32_e32 v149, v73
	v_add_f32_e32 v73, 1.0, v87
	v_add_f32_e32 v87, v191, v151
	v_mul_f32_e32 v87, 0xbfb8aa3b, v87
	v_exp_f32_e32 v87, v87
	v_mul_f32_e32 v117, 0xbfb8aa3b, v117
	v_exp_f32_e32 v117, v117
	v_mov_b32_e32 v145, v198
	v_mov_b32_e32 v198, v197
	v_rcp_f32_e32 v192, v71
	v_add_f32_e32 v71, v146, v136
	v_pk_mul_f32 v[144:145], v[144:145], v[138:139] neg_lo:[0,1] neg_hi:[0,1]
	v_pk_mul_f32 v[136:137], v[198:199], v[78:79] neg_lo:[0,1] neg_hi:[0,1]
	v_mul_f32_e32 v71, 0xbfb8aa3b, v71
	v_pk_mul_f32 v[142:143], v[88:89], v[144:145] op_sel_hi:[0,1]
	v_rcp_f32_e32 v185, v73
	v_add_f32_e32 v73, 1.0, v87
	v_pk_mul_f32 v[144:145], v[88:89], v[136:137] op_sel_hi:[0,1]
	v_exp_f32_e32 v71, v71
	v_rcp_f32_e32 v189, v73
	v_add_f32_e32 v73, 1.0, v117
	s_nop 0
	s_nop 0
	v_rcp_f32_e32 v193, v73
	s_nop 0
	s_nop 0
	s_nop 0
	s_nop 0
	s_nop 0
	s_nop 0
	s_nop 0
	s_nop 0
	v_cvt_pk_bf16_f32 v137, v143, v145
	v_cvt_pk_bf16_f32 v136, v142, v144
	v_add_f32_e32 v71, 1.0, v71
	global_store_dwordx2 v[108:109], v[54:55], off offset:32
	global_store_dwordx2 v[108:109], v[50:51], off offset:160
	global_store_dwordx2 v[108:109], v[136:137], off offset:288
	v_pk_mul_f32 v[136:137], v[188:189], s[48:49] op_sel_hi:[1,0]
	v_rcp_f32_e32 v70, v70
	v_rcp_f32_e32 v71, v71
	v_pk_mul_f32 v[134:135], v[134:135], s[48:49] op_sel_hi:[1,0]
	s_nop 0
	s_nop 0
	s_nop 0
	s_nop 0
	s_nop 0
	s_nop 0
	s_nop 0
	s_nop 0
	s_nop 0
	s_nop 0
	v_cvt_pk_bf16_f32 v135, v135, v137
	v_cvt_pk_bf16_f32 v134, v134, v136
	s_waitcnt vmcnt(4)
	v_mov_b32_e32 v147, v206
	v_pk_add_f32 v[136:137], v[148:149], -1.0 op_sel_hi:[1,0]
	v_mov_b32_e32 v206, v205
	global_store_dwordx2 v[108:109], v[134:135], off offset:416
	v_pk_add_f32 v[134:135], v[70:71], -1.0 op_sel_hi:[1,0]
	v_mov_b32_e32 v146, v204
	v_pk_fma_f32 v[136:137], v[206:207], v[136:137], 1.0 op_sel_hi:[1,1,0]
	v_pk_fma_f32 v[134:135], v[146:147], v[134:135], 1.0 op_sel_hi:[1,1,0]
	v_pk_mul_f32 v[136:137], v[136:137], v[78:79]
	v_pk_mul_f32 v[134:135], v[134:135], v[138:139]
	s_nop 0
	s_nop 0
	s_nop 0
	s_nop 0
	s_nop 0
	v_pk_mul_f32 v[70:71], v[142:143], v[70:71] neg_lo:[1,0] neg_hi:[1,0]
	v_cvt_pk_bf16_f32 v151, v135, v137
	v_cvt_pk_bf16_f32 v150, v134, v136
	v_pk_mul_f32 v[148:149], v[144:145], v[148:149] neg_lo:[1,0] neg_hi:[1,0]
	s_nop 0
	s_nop 0
	s_nop 0
	s_nop 0
	s_nop 0
	s_nop 0
	s_nop 0
	s_nop 0
	s_nop 0
	s_nop 0
	v_cvt_pk_bf16_f32 v71, v71, v149
	v_cvt_pk_bf16_f32 v70, v70, v148
	global_store_dwordx2 v[108:109], v[70:71], off offset:672
	v_pk_mul_f32 v[70:71], v[140:141], s[48:49] op_sel_hi:[1,0]
	v_pk_mul_f32 v[140:141], v[192:193], s[48:49] op_sel_hi:[1,0]
	s_nop 0
	s_nop 0
	s_nop 0
	s_nop 0
	s_nop 0
	s_nop 0
	s_nop 0
	s_nop 0
	s_nop 0
	s_nop 0
	v_cvt_pk_bf16_f32 v71, v71, v141
	v_cvt_pk_bf16_f32 v70, v70, v140
	global_store_dwordx2 v[108:109], v[70:71], off offset:800
	v_pk_add_f32 v[70:71], v[74:75], -1.0 op_sel_hi:[1,0]
	v_lshl_add_u64 v[62:63], s[10:11], 0, v[60:61]
	v_pk_fma_f32 v[70:71], v[146:147], v[70:71], 1.0 op_sel_hi:[1,1,0]
	global_store_dwordx2 v[108:109], v[150:151], off offset:544
	v_pk_mul_f32 v[138:139], v[70:71], v[138:139]
	v_pk_add_f32 v[70:71], v[184:185], -1.0 op_sel_hi:[1,0]
	v_and_b32_e32 v87, 0xffff0000, v52
	v_pk_fma_f32 v[70:71], v[206:207], v[70:71], 1.0 op_sel_hi:[1,1,0]
	v_lshlrev_b32_e32 v119, 16, v53
	v_pk_mul_f32 v[140:141], v[70:71], v[78:79]
	s_nop 0
	s_nop 0
	s_nop 0
	s_nop 0
	s_nop 0
	s_nop 0
	v_cvt_pk_bf16_f32 v71, v139, v141
	v_cvt_pk_bf16_f32 v70, v138, v140
	global_store_dwordx2 v[108:109], v[70:71], off offset:928
	v_pk_mul_f32 v[70:71], v[142:143], v[74:75] neg_lo:[1,0] neg_hi:[1,0]
	v_pk_mul_f32 v[74:75], v[144:145], v[184:185] neg_lo:[1,0] neg_hi:[1,0]
	s_nop 0
	s_nop 0
	s_nop 0
	s_nop 0
	s_nop 0
	s_nop 0
	s_nop 0
	s_nop 0
	s_nop 0
	v_cvt_pk_bf16_f32 v71, v71, v75
	v_cvt_pk_bf16_f32 v70, v70, v74
	global_store_dwordx2 v[108:109], v[70:71], off offset:1056
	global_store_dwordx2 v[82:83], v[68:69], off offset:32
	global_load_dwordx4 v[142:145], v[62:63], off
	v_lshl_add_u64 v[62:63], s[44:45], 0, v[60:61]
	global_load_dwordx4 v[146:149], v[62:63], off
	v_lshl_add_u64 v[62:63], s[8:9], 0, v[60:61]
	global_load_dwordx4 v[184:187], v[62:63], off
	v_lshl_add_u64 v[60:61], s[40:41], 0, v[60:61]
	global_load_dwordx4 v[188:191], v[60:61], off
	global_load_dwordx4 v[192:195], v[114:115], off offset:3200
	v_add_u32_e32 v68, 0x1200, v180
	v_add3_u32 v73, 0, v68, v179
	ds_read_b128 v[60:63], v73 offset:51200
	ds_read_b128 v[196:199], v73 offset:51264
	v_add_u32_e32 v74, v181, v68
	ds_read_b128 v[68:71], v74
	ds_read_b128 v[200:203], v74 offset:64
	s_waitcnt lgkmcnt(3)
; #define LAS __attribute__((address_space(3)))
; __device__ __forceinline__ void rwkv_proj_phase(const bf16* Z, const float* shift, const float* w0, const float* a0, const float* kkp, const float* kap, const float* rkp, ...
;     ...
;             for (int nb = 0; nb < 4; ++nb) {
;                 const int n = h * 64 + nb * 16 + fr;
;                 f32x4 accw[2], acca[2], accg = (f32x4){0.f, 0.f, 0.f, 0.f};
; #pragma unroll
;                 for (int d = 0; d < 2; ++d) { accw[d] = (f32x4){0.f, 0.f, 0.f, 0.f}; acca[d] = (f32x4){0.f, 0.f, 0.f, 0.f};
; #pragma unroll
;                     for (int ksl = 0; ksl < 2; ++ksl) {
;                         const bf16x8 wf = *(const LAS bf16x8*)(lds + 51200 + (d * 64 + nb * 16 + fr) * 144 + (32 * ksl + 8 * g) * 2);
;                         const bf16x8 af = *(const LAS bf16x8*)(lds + 51200 + 18432 + (d * 64 + nb * 16 + fr) * 144 + (32 * ksl + 8 * g) * 2);
;                         accw[d] = MFMA16(wf, xf[2 * d + ksl], accw[d]);
;                         acca[d] = MFMA16(af, xf[4 + 2 * d + ksl], acca[d]); } }
; #pragma unroll
;                 for (int ksl = 0; ksl < 4; ++ksl) { const bf16x8 gf = *(const LAS bf16x8*)(lds + 51200 + 36864 + (nb * 16 + fr) * 272 + (32 * ksl + 8 * g) * 2); accg = MFMA16(gf, xf[8 + ksl], accg); }
;                 const int c = h * 64 + nb * 16 + 4 * g;
;                 const f32x4 rc = bf4(*(const LAS u32x2*)(rkv + nb * 32)), vc = bf4(*(const LAS u32x2*)(rkv + 256 + nb * 32));
;                 const f32x4 w00 = *(const f32x4*)(w0 + c), w01 = *(const f32x4*)(w0 + BW + c), a00 = *(const f32x4*)(a0 + c), a01 = *(const f32x4*)(a0 + BW + c);
;                 const f32x4 kk4 = *(const f32x4*)(kkp + c), ka4 = *(const f32x4*)(kap + c), rk4 = *(const f32x4*)(rkp + c);
;                 float o[9][4];
; #pragma unroll
;                 for (int e = 0; e < 4; ++e) {
;                     const float ad0 = sigmoid_f(a00[e] + acca[0][e]), ad1 = sigmoid_f(a01[e] + acca[1][e]);
;                     const float lw0 = -0.60653066f * sigmoid_f(w00[e] + accw[0][e]), lw1 = -0.60653066f * sigmoid_f(w01[e] + accw[1][e]);
;                     const float k = kc[nb][e], kk = k * kk4[e] * inv;
;                     const float kd0 = k * (1.f + (ad0 - 1.f) * ka4[e]), kd1 = k * (1.f + (ad1 - 1.f) * ka4[e]);
;                     bon += rc[e] * (kd0 + kd1) * rk4[e];
	v_mfma_f32_16x16x32_bf16 v[60:63], v[60:63], v[0:3], 0
	v_add_u32_e32 v74, 0x3600, v180
	v_lshlrev_b32_e32 v73, 16, v52
	v_add_u32_e32 v52, v181, v74
	s_waitcnt lgkmcnt(1)
	v_mfma_f32_16x16x32_bf16 v[68:71], v[68:71], v[16:19], 0
	ds_read_b128 v[204:207], v183 offset:65024
	v_add_u32_e32 v78, 48, v116
	v_pk_fma_f32 v[116:117], v[128:129], v[76:77], v[130:131]
	v_mfma_f32_16x16x32_bf16 v[196:199], v[196:199], v[4:7], v[60:63]
	v_ashrrev_i32_e32 v79, 31, v78
	v_mul_f32_e32 v221, v117, v123
	v_mov_b32_e32 v123, v72
	ds_read_b128 v[60:63], v52
	v_pk_fma_f32 v[52:53], v[126:127], v[124:125], v[132:133]
	s_waitcnt lgkmcnt(2)
	v_mfma_f32_16x16x32_bf16 v[200:203], v[200:203], v[20:23], v[68:71]
	v_mul_f32_e32 v220, v52, v73
	v_add3_u32 v52, s56, v74, v179
	ds_read_b128 v[74:77], v52 offset:64
	ds_read_b128 v[68:71], v183 offset:65088
	s_waitcnt lgkmcnt(3)
	v_mfma_f32_16x16x32_bf16 v[124:127], v[204:207], v[8:11], 0
	v_mul_f32_e32 v119, v53, v119
	v_lshlrev_b64 v[52:53], 2, v[78:79]
	v_mul_f32_e32 v87, v116, v87
	s_waitcnt lgkmcnt(2)
	v_mfma_f32_16x16x32_bf16 v[60:63], v[60:63], v[24:27], 0
	v_lshl_add_u64 v[116:117], s[10:11], 0, v[52:53]
	s_waitcnt vmcnt(4)
	v_add_f32_e32 v72, v200, v142
	s_waitcnt lgkmcnt(0)
	v_mfma_f32_16x16x32_bf16 v[124:127], v[68:71], v[12:15], v[124:127]
	v_mul_f32_e32 v72, 0xbfb8aa3b, v72
	v_exp_f32_e32 v132, v72
	s_waitcnt vmcnt(2)
	v_add_f32_e32 v133, v196, v184
	v_mfma_f32_16x16x32_bf16 v[128:131], v[74:77], v[28:31], v[60:63]
	ds_read_b128 v[204:207], v178 offset:8704
	ds_read_b128 v[208:211], v178 offset:8768
	ds_read_b128 v[212:215], v178 offset:8832
	ds_read_b128 v[76:79], v178 offset:8896
	ds_read2_b64 v[68:71], v182 offset0:8 offset1:12
	ds_read2_b64 v[60:63], v182 offset0:40 offset1:44
	global_load_dwordx4 v[216:219], v[112:113], off offset:3200
	v_mul_f32_e32 v133, 0xbfb8aa3b, v133
	v_add_f32_e32 v72, v128, v146
	v_mul_f32_e32 v72, 0xbfb8aa3b, v72
	v_exp_f32_e32 v128, v72
	v_exp_f32_e32 v133, v133
	s_waitcnt vmcnt(2)
	v_add_f32_e32 v124, v124, v188
	v_mul_f32_e32 v124, 0xbfb8aa3b, v124
	v_add_f32_e32 v128, 1.0, v128
	v_exp_f32_e32 v146, v124
	v_rcp_f32_e32 v124, v128
	v_add_f32_e32 v128, 1.0, v133
	v_add_f32_e32 v133, v201, v143
	v_add_f32_e32 v125, v125, v189
	v_mul_f32_e32 v133, 0xbfb8aa3b, v133
	v_add_f32_e32 v129, v129, v147
	v_mul_f32_e32 v125, 0xbfb8aa3b, v125
	v_exp_f32_e32 v133, v133
	v_mul_f32_e32 v129, 0xbfb8aa3b, v129
	v_exp_f32_e32 v125, v125
	v_exp_f32_e32 v143, v129
	v_add_f32_e32 v133, 1.0, v133
	v_rcp_f32_e32 v150, v133
	v_add_f32_e32 v125, 1.0, v125
	v_add_f32_e32 v133, 1.0, v143
	v_add_f32_e32 v143, v197, v185
	v_rcp_f32_e32 v188, v125
	v_add_f32_e32 v125, v202, v144
	v_mul_f32_e32 v143, 0xbfb8aa3b, v143
	v_mul_f32_e32 v125, 0xbfb8aa3b, v125
	v_add_f32_e32 v130, v130, v148
	v_exp_f32_e32 v143, v143
	v_exp_f32_e32 v125, v125
	v_mul_f32_e32 v130, 0xbfb8aa3b, v130
	v_exp_f32_e32 v130, v130
	v_rcp_f32_e32 v182, v133
	v_add_f32_e32 v133, 1.0, v143
	v_add_f32_e32 v125, 1.0, v125
	v_add_f32_e32 v126, v126, v190
	v_rcp_f32_e32 v184, v133
	v_rcp_f32_e32 v133, v125
	v_add_f32_e32 v125, 1.0, v130
	v_add_f32_e32 v130, v198, v186
	v_mul_f32_e32 v126, 0xbfb8aa3b, v126
	v_mul_f32_e32 v130, 0xbfb8aa3b, v130
	v_exp_f32_e32 v126, v126
	v_exp_f32_e32 v130, v130
	v_rcp_f32_e32 v142, v128
	v_add_f32_e32 v128, 1.0, v146
	v_add_f32_e32 v126, 1.0, v126
	v_add_f32_e32 v130, 1.0, v130
	v_rcp_f32_e32 v147, v126
	v_add_f32_e32 v126, v203, v145
	v_rcp_f32_e32 v143, v130
	v_mul_f32_e32 v126, 0xbfb8aa3b, v126
	v_add_f32_e32 v130, v131, v149
	v_exp_f32_e32 v126, v126
	v_mul_f32_e32 v130, 0xbfb8aa3b, v130
	v_exp_f32_e32 v144, v130
	v_rcp_f32_e32 v146, v128
	v_add_f32_e32 v126, 1.0, v126
	v_rcp_f32_e32 v151, v126
	v_add_f32_e32 v126, 1.0, v144
	v_rcp_f32_e32 v183, v126
	v_add_f32_e32 v126, v199, v187
	v_mul_f32_e32 v126, 0xbfb8aa3b, v126
	v_exp_f32_e32 v144, v126
	v_add_f32_e32 v126, v127, v191
	v_mul_f32_e32 v126, 0xbfb8aa3b, v126
	v_exp_f32_e32 v145, v126
	s_waitcnt vmcnt(1)
	v_mov_b32_e32 v128, v192
	v_mov_b32_e32 v129, v194
	v_add_f32_e32 v144, 1.0, v144
	v_mov_b32_e32 v194, v193
	v_pk_mul_f32 v[128:129], v[128:129], v[122:123] neg_lo:[0,1] neg_hi:[0,1]
	v_rcp_f32_e32 v185, v144
	v_add_f32_e32 v144, 1.0, v145
	v_pk_mul_f32 v[130:131], v[88:89], v[128:129] op_sel_hi:[0,1]
	v_rcp_f32_e32 v189, v144
	v_pk_mul_f32 v[144:145], v[194:195], v[120:121] neg_lo:[0,1] neg_hi:[0,1]
	s_nop 0
	v_pk_mul_f32 v[144:145], v[88:89], v[144:145] op_sel_hi:[0,1]
	s_nop 0
	s_nop 0
	s_nop 0
	s_nop 0
	s_nop 0
	s_nop 0
	s_nop 0
	s_nop 0
	s_nop 0
	v_cvt_pk_bf16_f32 v149, v131, v145
	v_cvt_pk_bf16_f32 v148, v130, v144
	v_pk_mul_f32 v[142:143], v[142:143], s[48:49] op_sel_hi:[1,0]
	global_load_dwordx4 v[72:75], v[110:111], off offset:3200
	v_add_f32_e32 v132, 1.0, v132
	s_waitcnt lgkmcnt(1)
	global_store_dwordx2 v[108:109], v[68:69], off offset:64
	s_waitcnt lgkmcnt(0)
	global_store_dwordx2 v[108:109], v[60:61], off offset:192
	global_store_dwordx2 v[108:109], v[148:149], off offset:320
	v_pk_mul_f32 v[148:149], v[184:185], s[48:49] op_sel_hi:[1,0]
	s_nop 0
	s_nop 0
	v_rcp_f32_e32 v132, v132
	s_nop 0
	s_nop 0
	s_nop 0
	s_nop 0
	s_nop 0
	s_nop 0
	s_nop 0
	s_nop 0
	v_cvt_pk_bf16_f32 v143, v143, v149
	v_cvt_pk_bf16_f32 v142, v142, v148
	global_store_dwordx2 v[108:109], v[142:143], off offset:448
	v_pk_add_f32 v[142:143], v[132:133], -1.0 op_sel_hi:[1,0]
	s_waitcnt vmcnt(5)
; #define LAS __attribute__((address_space(3)))
; __device__ __forceinline__ void rwkv_proj_phase(const bf16* Z, const float* shift, const float* w0, const float* a0, const float* kkp, const float* kap, const float* rkp, ...
;     ...
;             for (int nb = 0; nb < 4; ++nb) {
;                 const int n = h * 64 + nb * 16 + fr;
;                 f32x4 accw[2], acca[2], accg = (f32x4){0.f, 0.f, 0.f, 0.f};
; #pragma unroll
;                 for (int d = 0; d < 2; ++d) { accw[d] = (f32x4){0.f, 0.f, 0.f, 0.f}; acca[d] = (f32x4){0.f, 0.f, 0.f, 0.f};
; #pragma unroll
;                     for (int ksl = 0; ksl < 2; ++ksl) {
;                         const bf16x8 wf = *(const LAS bf16x8*)(lds + 51200 + (d * 64 + nb * 16 + fr) * 144 + (32 * ksl + 8 * g) * 2);
;                         const bf16x8 af = *(const LAS bf16x8*)(lds + 51200 + 18432 + (d * 64 + nb * 16 + fr) * 144 + (32 * ksl + 8 * g) * 2);
;                         accw[d] = MFMA16(wf, xf[2 * d + ksl], accw[d]);
;                         acca[d] = MFMA16(af, xf[4 + 2 * d + ksl], acca[d]); } }
; #pragma unroll
;                 for (int ksl = 0; ksl < 4; ++ksl) { const bf16x8 gf = *(const LAS bf16x8*)(lds + 51200 + 36864 + (nb * 16 + fr) * 272 + (32 * ksl + 8 * g) * 2); accg = MFMA16(gf, xf[8 + ksl], accg); }
;                 const int c = h * 64 + nb * 16 + 4 * g;
;                 const f32x4 rc = bf4(*(const LAS u32x2*)(rkv + nb * 32)), vc = bf4(*(const LAS u32x2*)(rkv + 256 + nb * 32));
;                 const f32x4 w00 = *(const f32x4*)(w0 + c), w01 = *(const f32x4*)(w0 + BW + c), a00 = *(const f32x4*)(a0 + c), a01 = *(const f32x4*)(a0 + BW + c);
;                 const f32x4 kk4 = *(const f32x4*)(kkp + c), ka4 = *(const f32x4*)(kap + c), rk4 = *(const f32x4*)(rkp + c);
;                 float o[9][4];
; #pragma unroll
;                 for (int e = 0; e < 4; ++e) {
;                     const float ad0 = sigmoid_f(a00[e] + acca[0][e]), ad1 = sigmoid_f(a01[e] + acca[1][e]);
;                     const float lw0 = -0.60653066f * sigmoid_f(w00[e] + accw[0][e]), lw1 = -0.60653066f * sigmoid_f(w01[e] + accw[1][e]);
;                     const float k = kc[nb][e], kk = k * kk4[e] * inv;
;                     const float kd0 = k * (1.f + (ad0 - 1.f) * ka4[e]), kd1 = k * (1.f + (ad1 - 1.f) * ka4[e]);
;                     bon += rc[e] * (kd0 + kd1) * rk4[e];
	v_mov_b32_e32 v148, v216
	v_mov_b32_e32 v149, v218
	v_pk_fma_f32 v[142:143], v[148:149], v[142:143], 1.0 op_sel_hi:[1,1,0]
	v_pk_add_f32 v[184:185], v[150:151], -1.0 op_sel_hi:[1,0]
	v_mov_b32_e32 v218, v217
	v_pk_mul_f32 v[142:143], v[142:143], v[122:123]
	v_pk_fma_f32 v[184:185], v[218:219], v[184:185], 1.0 op_sel_hi:[1,1,0]
	v_and_b32_sdwa v187, v142, v170 dst_sel:DWORD dst_unused:UNUSED_PAD src0_sel:WORD_1 src1_sel:DWORD
	v_pk_mul_f32 v[184:185], v[184:185], v[120:121]
	v_add3_u32 v190, v142, v187, s61
	s_nop 0
	v_and_b32_sdwa v191, v184, v170 dst_sel:DWORD dst_unused:UNUSED_PAD src0_sel:WORD_1 src1_sel:DWORD
	s_nop 0
	s_nop 0
	v_add3_u32 v191, v184, v191, s61
	s_nop 0
	s_nop 0
	v_and_b32_e32 v191, 0xffff0000, v191
	v_cvt_pk_bf16_f32 v187, v143, v185
	v_or_b32_sdwa v186, v191, v190 dst_sel:DWORD dst_unused:UNUSED_PAD src0_sel:DWORD src1_sel:WORD_1
	v_pk_mul_f32 v[132:133], v[130:131], v[132:133] neg_lo:[1,0] neg_hi:[1,0]
	global_store_dwordx2 v[108:109], v[186:187], off offset:576
	v_pk_mul_f32 v[150:151], v[144:145], v[150:151] neg_lo:[1,0] neg_hi:[1,0]
	v_and_b32_sdwa v186, v133, v170 dst_sel:DWORD dst_unused:UNUSED_PAD src0_sel:WORD_1 src1_sel:DWORD
	v_and_b32_sdwa v187, v132, v170 dst_sel:DWORD dst_unused:UNUSED_PAD src0_sel:WORD_1 src1_sel:DWORD
	v_add3_u32 v132, v132, v187, s61
	v_add3_u32 v133, v133, v186, s61
	v_and_b32_sdwa v186, v151, v170 dst_sel:DWORD dst_unused:UNUSED_PAD src0_sel:WORD_1 src1_sel:DWORD
	v_and_b32_sdwa v187, v150, v170 dst_sel:DWORD dst_unused:UNUSED_PAD src0_sel:WORD_1 src1_sel:DWORD
	v_add3_u32 v151, v151, v186, s61
	v_add3_u32 v150, v150, v187, s61
	v_and_b32_e32 v151, 0xffff0000, v151
	v_and_b32_e32 v150, 0xffff0000, v150
	v_or_b32_sdwa v133, v151, v133 dst_sel:DWORD dst_unused:UNUSED_PAD src0_sel:DWORD src1_sel:WORD_1
	v_or_b32_sdwa v132, v150, v132 dst_sel:DWORD dst_unused:UNUSED_PAD src0_sel:DWORD src1_sel:WORD_1
	global_store_dwordx2 v[108:109], v[132:133], off offset:704
	v_pk_mul_f32 v[132:133], v[146:147], s[48:49] op_sel_hi:[1,0]
	v_pk_mul_f32 v[146:147], v[188:189], s[48:49] op_sel_hi:[1,0]
	s_nop 0
	s_nop 0
	v_rcp_f32_e32 v125, v125
	s_nop 0
	s_nop 0
	s_nop 0
	s_nop 0
	s_nop 0
	s_nop 0
	s_nop 0
	s_nop 0
	v_mfma_f32_16x16x32_bf16 v[126:129], v[204:207], v[32:35], 0
	v_cvt_pk_bf16_f32 v133, v133, v147
	v_cvt_pk_bf16_f32 v132, v132, v146
	global_store_dwordx2 v[108:109], v[132:133], off offset:832
	v_pk_add_f32 v[132:133], v[124:125], -1.0 op_sel_hi:[1,0]
	v_mfma_f32_16x16x32_bf16 v[126:129], v[208:211], v[36:39], v[126:129]
	v_fma_f32 v132, v148, v132, 1.0
	v_fma_f32 v133, v149, v133, 1.0
	v_pk_mul_f32 v[146:147], v[132:133], v[122:123]
	v_pk_add_f32 v[122:123], v[182:183], -1.0 op_sel_hi:[1,0]
	v_mfma_f32_16x16x32_bf16 v[126:129], v[212:215], v[40:43], v[126:129]
	v_fma_f32 v122, v218, v122, 1.0
	v_fma_f32 v123, v219, v123, 1.0
	v_fma_f32 v132, v56, v220, 0
	v_pk_mul_f32 v[148:149], v[122:123], v[120:121]
	s_nop 0
	s_nop 0
	s_nop 0
	s_nop 0
	s_nop 0
	s_nop 0
	s_nop 0
	s_nop 0
	v_cvt_pk_bf16_f32 v121, v147, v149
	v_cvt_pk_bf16_f32 v120, v146, v148
	global_store_dwordx2 v[108:109], v[120:121], off offset:960
	v_pk_mul_f32 v[120:121], v[130:131], v[124:125] neg_lo:[1,0] neg_hi:[1,0]
	v_pk_mul_f32 v[122:123], v[144:145], v[182:183] neg_lo:[1,0] neg_hi:[1,0]
	s_nop 0
	s_nop 0
	s_nop 0
	s_nop 0
	s_nop 0
	s_nop 0
	v_mfma_f32_16x16x32_bf16 v[76:79], v[76:79], v[44:47], v[126:129]
	s_nop 0
	s_nop 0
	s_nop 0
	s_nop 0
	v_cvt_pk_bf16_f32 v121, v121, v123
	v_cvt_pk_bf16_f32 v120, v120, v122
	global_store_dwordx2 v[108:109], v[120:121], off offset:1088
	s_nop 0
	s_nop 0
	s_nop 0
	s_nop 0
	s_nop 0
	s_nop 0
	v_cvt_pk_bf16_f32 v76, v76, v77
	s_nop 0
	s_nop 0
	s_nop 0
	v_cvt_pk_bf16_f32 v77, v78, v79
	global_store_dwordx2 v[82:83], v[76:77], off offset:64
	global_load_dwordx4 v[76:79], v[116:117], off
	v_lshl_add_u64 v[116:117], s[44:45], 0, v[52:53]
	global_load_dwordx4 v[120:123], v[116:117], off
	v_fmac_f32_e32 v132, v57, v87
	v_lshl_add_u64 v[56:57], s[8:9], 0, v[52:53]
	global_load_dwordx4 v[124:127], v[56:57], off
	v_lshl_add_u64 v[52:53], s[40:41], 0, v[52:53]
	global_load_dwordx4 v[128:131], v[52:53], off
	v_add_u32_e32 v56, 0x1b00, v180
	global_load_dwordx4 v[114:117], v[114:115], off offset:3264
	v_add_u32_e32 v52, 0x3f00, v180
	v_fmac_f32_e32 v132, v58, v119
	v_lshlrev_b32_e32 v58, 16, v54
	v_add3_u32 v87, 0, v56, v179
	v_add3_u32 v150, s76, v179, v52
	v_add_u32_e32 v151, v181, v52
	v_add3_u32 v180, s76, v52, v179
	v_add3_u32 v179, s56, v52, v179
	v_add_f32_e32 v52, v134, v138
	v_and_b32_e32 v54, 0xffff0000, v54
	v_mul_f32_e32 v58, v52, v58
	v_add_f32_e32 v52, v136, v140
	v_mov_b32_e32 v136, v135
	v_mov_b32_e32 v140, v139
	v_fmac_f32_e32 v132, v59, v221
	v_mul_f32_e32 v59, v52, v54
	v_and_b32_e32 v53, 0xffff0000, v55
	v_lshlrev_b32_e32 v52, 16, v55
	v_pk_add_f32 v[54:55], v[136:137], v[140:141]
	v_add_u32_e32 v119, v181, v56
	v_pk_mul_f32 v[52:53], v[54:55], v[52:53]
	v_fmac_f32_e32 v132, v64, v58
	v_pk_mul_f32 v[56:57], v[66:67], v[52:53]
	ds_read_b128 v[52:55], v87 offset:51200
	v_fmac_f32_e32 v132, v65, v59
	v_add_f32_e32 v56, v56, v132
	v_add_f32_e32 v181, v57, v56
	ds_read_b128 v[56:59], v119
	ds_read_b128 v[64:67], v87 offset:51264
	v_mov_b32_e32 v132, v142
	v_mov_b32_e32 v133, v184
	v_mov_b32_e32 v134, v146
	v_mov_b32_e32 v135, v148
	v_pk_add_f32 v[138:139], v[132:133], v[134:135]
	ds_read_b128 v[132:135], v119 offset:64
	s_waitcnt lgkmcnt(3)
	v_mfma_f32_16x16x32_bf16 v[52:55], v[52:55], v[0:3], 0
	v_and_b32_e32 v137, 0xffff0000, v68
	v_lshlrev_b32_e32 v136, 16, v68
	v_pk_mul_f32 v[136:137], v[138:139], v[136:137]
	s_waitcnt lgkmcnt(2)
	v_mfma_f32_16x16x32_bf16 v[56:59], v[56:59], v[16:19], 0
	s_waitcnt vmcnt(15)
; #define LAS __attribute__((address_space(3)))
; __device__ __forceinline__ void rwkv_proj_phase(const bf16* Z, const float* shift, const float* w0, const float* a0, const float* kkp, const float* kap, const float* rkp, ...
;     ...
;             for (int nb = 0; nb < 4; ++nb) {
;                 const int n = h * 64 + nb * 16 + fr;
;                 f32x4 accw[2], acca[2], accg = (f32x4){0.f, 0.f, 0.f, 0.f};
; #pragma unroll
;                 for (int d = 0; d < 2; ++d) { accw[d] = (f32x4){0.f, 0.f, 0.f, 0.f}; acca[d] = (f32x4){0.f, 0.f, 0.f, 0.f};
; #pragma unroll
;                     for (int ksl = 0; ksl < 2; ++ksl) {
;                         const bf16x8 wf = *(const LAS bf16x8*)(lds + 51200 + (d * 64 + nb * 16 + fr) * 144 + (32 * ksl + 8 * g) * 2);
;                         const bf16x8 af = *(const LAS bf16x8*)(lds + 51200 + 18432 + (d * 64 + nb * 16 + fr) * 144 + (32 * ksl + 8 * g) * 2);
;                         accw[d] = MFMA16(wf, xf[2 * d + ksl], accw[d]);
;                         acca[d] = MFMA16(af, xf[4 + 2 * d + ksl], acca[d]); } }
; #pragma unroll
;                 for (int ksl = 0; ksl < 4; ++ksl) { const bf16x8 gf = *(const LAS bf16x8*)(lds + 51200 + 36864 + (nb * 16 + fr) * 272 + (32 * ksl + 8 * g) * 2); accg = MFMA16(gf, xf[8 + ksl], accg); }
;                 const int c = h * 64 + nb * 16 + 4 * g;
;                 const f32x4 rc = bf4(*(const LAS u32x2*)(rkv + nb * 32)), vc = bf4(*(const LAS u32x2*)(rkv + 256 + nb * 32));
;                 const f32x4 w00 = *(const f32x4*)(w0 + c), w01 = *(const f32x4*)(w0 + BW + c), a00 = *(const f32x4*)(a0 + c), a01 = *(const f32x4*)(a0 + BW + c);
;                 const f32x4 kk4 = *(const f32x4*)(kkp + c), ka4 = *(const f32x4*)(kap + c), rk4 = *(const f32x4*)(rkp + c);
;                 float o[9][4];
; #pragma unroll
;                 for (int e = 0; e < 4; ++e) {
;                     const float ad0 = sigmoid_f(a00[e] + acca[0][e]), ad1 = sigmoid_f(a01[e] + acca[1][e]);
;                     const float lw0 = -0.60653066f * sigmoid_f(w00[e] + accw[0][e]), lw1 = -0.60653066f * sigmoid_f(w01[e] + accw[1][e]);
;                     const float k = kc[nb][e], kk = k * kk4[e] * inv;
;                     const float kd0 = k * (1.f + (ad0 - 1.f) * ka4[e]), kd1 = k * (1.f + (ad1 - 1.f) * ka4[e]);
;                     bon += rc[e] * (kd0 + kd1) * rk4[e];
	v_pk_mul_f32 v[144:145], v[72:73], v[136:137]
	ds_read_b128 v[136:139], v150
	v_mov_b32_e32 v184, v143
	s_waitcnt lgkmcnt(2)
	v_mfma_f32_16x16x32_bf16 v[64:67], v[64:67], v[4:7], v[52:55]
	ds_read_b128 v[140:143], v179 offset:64
	v_mov_b32_e32 v148, v147
	v_and_b32_e32 v73, 0xffff0000, v69
	ds_read_b128 v[52:55], v151
	s_waitcnt lgkmcnt(3)
	v_mfma_f32_16x16x32_bf16 v[132:135], v[132:135], v[20:23], v[56:59]
	v_lshlrev_b32_e32 v72, 16, v69
	v_pk_add_f32 v[68:69], v[184:185], v[148:149]
	v_add_f32_e32 v87, v181, v144
	ds_read_b128 v[56:59], v180 offset:64
	s_waitcnt lgkmcnt(3)
	v_mfma_f32_16x16x32_bf16 v[136:139], v[136:139], v[8:11], 0
	v_mul_f32_e64 v68, v68, v72
	v_mul_f32_e64 v69, v69, v73
	s_waitcnt vmcnt(2)
	v_add_f32_e32 v64, v64, v124
	s_waitcnt lgkmcnt(1)
	v_mfma_f32_16x16x32_bf16 v[52:55], v[52:55], v[24:27], 0
	v_mul_f32_e64 v68, v74, v68
	v_mul_f32_e64 v69, v75, v69
	v_mul_f32_e32 v64, 0xbfb8aa3b, v64
	v_add_f32_e32 v65, v65, v125
	s_waitcnt lgkmcnt(0)
	v_mfma_f32_16x16x32_bf16 v[72:75], v[56:59], v[12:15], v[136:139]
	v_add_f32_e32 v56, v145, v87
	v_add_f32_e32 v56, v68, v56
	v_add_f32_e32 v182, v69, v56
	v_mfma_f32_16x16x32_bf16 v[136:139], v[140:143], v[28:31], v[52:55]
	ds_read_b128 v[140:143], v178 offset:13056
	ds_read_b128 v[144:147], v178 offset:13120
	ds_read_b128 v[148:151], v178 offset:13184
	ds_read_b128 v[52:55], v178 offset:13248
	global_load_dwordx4 v[178:181], v[112:113], off offset:3264
	v_add_f32_e32 v56, v132, v76
	v_mul_f32_e32 v56, 0xbfb8aa3b, v56
	v_exp_f32_e32 v68, v56
	v_add_f32_e32 v56, v136, v120
	v_mul_f32_e32 v56, 0xbfb8aa3b, v56
	v_exp_f32_e32 v69, v56
	global_load_dwordx4 v[56:59], v[110:111], off offset:3264
	v_add_f32_e32 v68, 1.0, v68
	v_rcp_f32_e32 v76, v68
	v_add_f32_e32 v68, 1.0, v69
	v_exp_f32_e32 v69, v64
	s_waitcnt vmcnt(3)
	v_add_f32_e32 v64, v72, v128
	v_mul_f32_e32 v65, 0xbfb8aa3b, v65
	v_add_f32_e32 v73, v73, v129
	v_mul_f32_e32 v64, 0xbfb8aa3b, v64
	v_exp_f32_e32 v65, v65
	v_mul_f32_e32 v73, 0xbfb8aa3b, v73
	v_exp_f32_e32 v87, v64
	v_exp_f32_e32 v73, v73
	v_rcp_f32_e32 v64, v68
	v_add_f32_e32 v68, 1.0, v69
	v_add_f32_e32 v69, v133, v77
	v_add_f32_e32 v65, 1.0, v65
	v_rcp_f32_e32 v72, v68
	v_add_f32_e32 v68, 1.0, v87
	v_mov_b32_e32 v87, v118
	v_mul_f32_e32 v69, 0xbfb8aa3b, v69
	v_rcp_f32_e32 v118, v65
	v_add_f32_e32 v65, 1.0, v73
	v_exp_f32_e32 v77, v69
	v_add_f32_e32 v69, v137, v121
	v_rcp_f32_e32 v120, v65
	v_add_f32_e32 v65, v134, v78
	v_mul_f32_e32 v69, 0xbfb8aa3b, v69
	v_mul_f32_e32 v65, 0xbfb8aa3b, v65
	v_add_f32_e32 v73, v138, v122
	v_exp_f32_e32 v111, v69
	v_exp_f32_e32 v65, v65
	v_mul_f32_e32 v73, 0xbfb8aa3b, v73
	v_exp_f32_e32 v73, v73
	v_add_f32_e32 v77, 1.0, v77
	v_rcp_f32_e32 v112, v77
	v_add_f32_e32 v77, 1.0, v111
	v_add_f32_e32 v65, 1.0, v65
	v_add_f32_e32 v66, v66, v126
	v_rcp_f32_e32 v110, v68
	s_waitcnt vmcnt(2)
	v_mov_b32_e32 v68, v114
	v_rcp_f32_e32 v114, v77
	v_rcp_f32_e32 v77, v65
	v_add_f32_e32 v65, 1.0, v73
	v_mul_f32_e32 v66, 0xbfb8aa3b, v66
	v_add_f32_e32 v73, v74, v130
	v_exp_f32_e32 v66, v66
	v_mul_f32_e32 v73, 0xbfb8aa3b, v73
	v_exp_f32_e32 v74, v73
	v_mov_b32_e32 v69, v116
	v_add_f32_e32 v66, 1.0, v66
	v_rcp_f32_e32 v73, v66
	v_add_f32_e32 v66, 1.0, v74
	v_rcp_f32_e32 v111, v66
	v_add_f32_e32 v66, v135, v79
	v_mul_f32_e32 v66, 0xbfb8aa3b, v66
	v_add_f32_e32 v74, v139, v123
	v_exp_f32_e32 v66, v66
	v_mul_f32_e32 v74, 0xbfb8aa3b, v74
	v_exp_f32_e32 v74, v74
	v_mov_b32_e32 v116, v115
	v_add_f32_e32 v66, 1.0, v66
	v_rcp_f32_e32 v113, v66
	v_add_f32_e32 v66, 1.0, v74
	v_rcp_f32_e32 v115, v66
	v_add_f32_e32 v66, v67, v127
	v_mul_f32_e32 v66, 0xbfb8aa3b, v66
	v_exp_f32_e32 v74, v66
	v_add_f32_e32 v66, v75, v131
	v_mul_f32_e32 v66, 0xbfb8aa3b, v66
	v_exp_f32_e32 v75, v66
	v_add_f32_e32 v74, 1.0, v74
	v_rcp_f32_e32 v119, v74
	v_pk_mul_f32 v[68:69], v[68:69], v[86:87] neg_lo:[0,1] neg_hi:[0,1]
	v_add_f32_e32 v74, 1.0, v75
	v_rcp_f32_e32 v121, v74
	v_pk_mul_f32 v[74:75], v[116:117], v[84:85] neg_lo:[0,1] neg_hi:[0,1]
	v_pk_mul_f32 v[78:79], v[88:89], v[68:69] op_sel_hi:[0,1]
	v_pk_mul_f32 v[74:75], v[88:89], v[74:75] op_sel_hi:[0,1]
	s_nop 0
	s_nop 0
	s_nop 0
	s_nop 0
	s_nop 0
	s_nop 0
	s_nop 0
	s_nop 0
	s_nop 0
	v_cvt_pk_bf16_f32 v117, v79, v75
	v_cvt_pk_bf16_f32 v116, v78, v74
	v_pk_mul_f32 v[72:73], v[72:73], s[48:49] op_sel_hi:[1,0]
	global_store_dwordx2 v[108:109], v[70:71], off offset:96
	global_store_dwordx2 v[108:109], v[62:63], off offset:224
	global_store_dwordx2 v[108:109], v[116:117], off offset:352
	v_pk_mul_f32 v[116:117], v[118:119], s[48:49] op_sel_hi:[1,0]
	s_nop 0
	s_nop 0
	s_nop 0
	s_nop 0
	s_nop 0
	s_nop 0
	s_nop 0
	s_nop 0
	s_nop 0
	s_nop 0
	v_cvt_pk_bf16_f32 v73, v73, v117
	v_cvt_pk_bf16_f32 v72, v72, v116
	s_waitcnt vmcnt(4)
; #define LAS __attribute__((address_space(3)))
; __device__ __forceinline__ void rwkv_proj_phase(const bf16* Z, const float* shift, const float* w0, const float* a0, const float* kkp, const float* kap, const float* rkp, ...
;     ...
;             for (int nb = 0; nb < 4; ++nb) {
;                 const int n = h * 64 + nb * 16 + fr;
;                 f32x4 accw[2], acca[2], accg = (f32x4){0.f, 0.f, 0.f, 0.f};
; #pragma unroll
;                 for (int d = 0; d < 2; ++d) { accw[d] = (f32x4){0.f, 0.f, 0.f, 0.f}; acca[d] = (f32x4){0.f, 0.f, 0.f, 0.f};
; #pragma unroll
;                     for (int ksl = 0; ksl < 2; ++ksl) {
;                         const bf16x8 wf = *(const LAS bf16x8*)(lds + 51200 + (d * 64 + nb * 16 + fr) * 144 + (32 * ksl + 8 * g) * 2);
;                         const bf16x8 af = *(const LAS bf16x8*)(lds + 51200 + 18432 + (d * 64 + nb * 16 + fr) * 144 + (32 * ksl + 8 * g) * 2);
;                         accw[d] = MFMA16(wf, xf[2 * d + ksl], accw[d]);
;                         acca[d] = MFMA16(af, xf[4 + 2 * d + ksl], acca[d]); } }
; #pragma unroll
;                 for (int ksl = 0; ksl < 4; ++ksl) { const bf16x8 gf = *(const LAS bf16x8*)(lds + 51200 + 36864 + (nb * 16 + fr) * 272 + (32 * ksl + 8 * g) * 2); accg = MFMA16(gf, xf[8 + ksl], accg); }
;                 const int c = h * 64 + nb * 16 + 4 * g;
;                 const f32x4 rc = bf4(*(const LAS u32x2*)(rkv + nb * 32)), vc = bf4(*(const LAS u32x2*)(rkv + 256 + nb * 32));
;                 const f32x4 w00 = *(const f32x4*)(w0 + c), w01 = *(const f32x4*)(w0 + BW + c), a00 = *(const f32x4*)(a0 + c), a01 = *(const f32x4*)(a0 + BW + c);
;                 const f32x4 kk4 = *(const f32x4*)(kkp + c), ka4 = *(const f32x4*)(kap + c), rk4 = *(const f32x4*)(rkp + c);
;                 float o[9][4];
; #pragma unroll
;                 for (int e = 0; e < 4; ++e) {
;                     const float ad0 = sigmoid_f(a00[e] + acca[0][e]), ad1 = sigmoid_f(a01[e] + acca[1][e]);
;                     const float lw0 = -0.60653066f * sigmoid_f(w00[e] + accw[0][e]), lw1 = -0.60653066f * sigmoid_f(w01[e] + accw[1][e]);
;                     const float k = kc[nb][e], kk = k * kk4[e] * inv;
;                     const float kd0 = k * (1.f + (ad0 - 1.f) * ka4[e]), kd1 = k * (1.f + (ad1 - 1.f) * ka4[e]);
;                     bon += rc[e] * (kd0 + kd1) * rk4[e];
	v_mov_b32_e32 v117, v180
	v_pk_add_f32 v[118:119], v[112:113], -1.0 op_sel_hi:[1,0]
	v_mov_b32_e32 v180, v179
	global_store_dwordx2 v[108:109], v[72:73], off offset:480
	v_pk_add_f32 v[72:73], v[76:77], -1.0 op_sel_hi:[1,0]
	v_mov_b32_e32 v116, v178
	v_pk_fma_f32 v[118:119], v[180:181], v[118:119], 1.0 op_sel_hi:[1,1,0]
	v_pk_fma_f32 v[72:73], v[116:117], v[72:73], 1.0 op_sel_hi:[1,1,0]
	v_pk_mul_f32 v[118:119], v[118:119], v[84:85]
	v_pk_mul_f32 v[72:73], v[72:73], v[86:87]
	s_nop 0
	v_and_b32_sdwa v124, v118, v170 dst_sel:DWORD dst_unused:UNUSED_PAD src0_sel:WORD_1 src1_sel:DWORD
	s_nop 0
	v_and_b32_sdwa v122, v72, v170 dst_sel:DWORD dst_unused:UNUSED_PAD src0_sel:WORD_1 src1_sel:DWORD
	s_nop 0
	v_add3_u32 v124, v118, v124, s61
	v_add3_u32 v122, v72, v122, s61
	s_nop 0
	s_nop 0
	v_and_b32_e32 v124, 0xffff0000, v124
	v_cvt_pk_bf16_f32 v123, v73, v119
	v_or_b32_sdwa v122, v124, v122 dst_sel:DWORD dst_unused:UNUSED_PAD src0_sel:DWORD src1_sel:WORD_1
	v_pk_mul_f32 v[76:77], v[78:79], v[76:77] neg_lo:[1,0] neg_hi:[1,0]
	global_store_dwordx2 v[108:109], v[122:123], off offset:608
	v_pk_mul_f32 v[112:113], v[74:75], v[112:113] neg_lo:[1,0] neg_hi:[1,0]
	s_nop 0
	v_and_b32_sdwa v122, v76, v170 dst_sel:DWORD dst_unused:UNUSED_PAD src0_sel:WORD_1 src1_sel:DWORD
	v_add3_u32 v76, v76, v122, s61
	s_nop 0
	s_nop 0
	v_and_b32_sdwa v122, v112, v170 dst_sel:DWORD dst_unused:UNUSED_PAD src0_sel:WORD_1 src1_sel:DWORD
	s_nop 0
	v_add3_u32 v112, v112, v122, s61
	s_nop 0
	v_and_b32_e32 v112, 0xffff0000, v112
	v_cvt_pk_bf16_f32 v77, v77, v113
	v_or_b32_sdwa v76, v112, v76 dst_sel:DWORD dst_unused:UNUSED_PAD src0_sel:DWORD src1_sel:WORD_1
	global_store_dwordx2 v[108:109], v[76:77], off offset:736
	v_pk_mul_f32 v[76:77], v[110:111], s[48:49] op_sel_hi:[1,0]
	v_pk_mul_f32 v[110:111], v[120:121], s[48:49] op_sel_hi:[1,0]
	v_and_b32_sdwa v88, v77, v170 dst_sel:DWORD dst_unused:UNUSED_PAD src0_sel:WORD_1 src1_sel:DWORD
	s_nop 0
	v_rcp_f32_e32 v65, v65
	s_waitcnt lgkmcnt(3)
	v_mfma_f32_16x16x32_bf16 v[66:69], v[140:143], v[32:35], 0
	s_nop 0
	v_add3_u32 v77, v77, v88, s61
	v_and_b32_sdwa v88, v111, v170 dst_sel:DWORD dst_unused:UNUSED_PAD src0_sel:WORD_1 src1_sel:DWORD
	s_nop 0
	v_add3_u32 v88, v111, v88, s61
	s_nop 0
	v_and_b32_e32 v88, 0xffff0000, v88
	s_nop 0
	v_or_b32_sdwa v77, v88, v77 dst_sel:DWORD dst_unused:UNUSED_PAD src0_sel:DWORD src1_sel:WORD_1
	v_cvt_pk_bf16_f32 v76, v76, v110
	s_waitcnt lgkmcnt(2)
	v_mfma_f32_16x16x32_bf16 v[66:69], v[144:147], v[36:39], v[66:69]
	global_store_dwordx2 v[108:109], v[76:77], off offset:864
	v_pk_add_f32 v[76:77], v[64:65], -1.0 op_sel_hi:[1,0]
	v_mov_b32_e32 v110, v72
	v_pk_fma_f32 v[76:77], v[116:117], v[76:77], 1.0 op_sel_hi:[1,1,0]
	s_waitcnt lgkmcnt(1)
	v_mfma_f32_16x16x32_bf16 v[66:69], v[148:151], v[40:43], v[66:69]
	v_mul_f32_e64 v76, v76, v86
	v_mul_f32_e64 v77, v77, v87
	v_pk_add_f32 v[86:87], v[114:115], -1.0 op_sel_hi:[1,0]
	v_mov_b32_e32 v111, v118
	v_pk_fma_f32 v[86:87], v[180:181], v[86:87], 1.0 op_sel_hi:[1,1,0]
	v_mov_b32_e32 v112, v76
	v_pk_mul_f32 v[84:85], v[86:87], v[84:85]
	v_and_b32_e32 v87, 0xffff0000, v70
	v_mov_b32_e32 v113, v84
	v_lshlrev_b32_e32 v86, 16, v70
	v_pk_add_f32 v[110:111], v[110:111], v[112:113]
	v_mov_b32_e32 v118, v73
	v_pk_mul_f32 v[86:87], v[110:111], v[86:87]
	v_mov_b32_e32 v70, v77
	s_waitcnt vmcnt(7)
	v_pk_mul_f32 v[56:57], v[56:57], v[86:87]
	v_and_b32_e32 v87, 0xffff0000, v71
	v_lshlrev_b32_e32 v86, 16, v71
	v_mov_b32_e32 v71, v85
	s_waitcnt lgkmcnt(0)
	v_mfma_f32_16x16x32_bf16 v[52:55], v[52:55], v[44:47], v[66:69]
	v_add_f32_e64 v70, v118, v70
	v_add_f32_e64 v71, v119, v71
	v_add_f32_e32 v56, v182, v56
	v_pk_mul_f32 v[70:71], v[70:71], v[86:87]
	v_add_f32_e32 v56, v57, v56
	v_pk_mul_f32 v[58:59], v[58:59], v[70:71]
	s_nop 1
	s_nop 0
	v_add_f32_e32 v56, v58, v56
	v_add_f32_e32 v56, v59, v56
	s_nop 0
	s_nop 0
	s_nop 0
	ds_bpermute_b32 v57, v177, v56
	s_nop 0
	s_nop 0
	s_nop 0
	s_nop 0
	v_cvt_pk_bf16_f32 v52, v52, v53
	v_bfe_u32 v53, v54, 16, 1
	v_cvt_pk_bf16_f32 v71, v77, v85
	v_cvt_pk_bf16_f32 v70, v76, v84
	v_pk_mul_f32 v[64:65], v[78:79], v[64:65] neg_lo:[1,0] neg_hi:[1,0]
	v_add3_u32 v53, v54, v53, s61
	s_waitcnt lgkmcnt(0)
; #define LAS __attribute__((address_space(3)))
; __device__ __forceinline__ unsigned pk2(float lo, float hi) { return f2bf(lo) | (f2bf(hi) << 16); }
; __device__ __forceinline__ f32x4 bf4(u32x2 w) { return (f32x4){bflo(w.x), bfhi(w.x), bflo(w.y), bfhi(w.y)}; }
; __device__ __forceinline__ void rwkv_proj_phase(const bf16* Z, const float* shift, const float* w0, const float* a0, const float* kkp, const float* kap, const float* rkp, ...
;     ...
;                 for (int vv = 0; vv < 9; ++vv) { u32x2 w; w.x = pk2(o[vv][0], o[vv][1]); w.y = pk2(o[vv][2], o[vv][3]); *(u32x2*)(sp + vv * 64 + nb * 16) = w; }
;                 { u32x2 w; w.x = pk2(accg[0], accg[1]); w.y = pk2(accg[2], accg[3]); *(u32x2*)(G + (size_t)m * BW + c) = w; }
;             }
;             bon += __shfl_xor(bon, 16); bon += __shfl_xor(bon, 32);
; #pragma unroll
;             for (int nb = 0; nb < 4; ++nb) { const int c = h * 64 + nb * 16 + 4 * g;
;                 const f32x4 t = bf4(*(const LAS u32x2*)(rkv + 256 + nb * 32)) * bon;
;                 u32x2 w; w.x = pk2(t.x, t.y); w.y = pk2(t.z, t.w); *(u32x2*)(BV + (size_t)m * BW + c) = w; }
	v_add_f32_e32 v54, v56, v57
	global_store_dwordx2 v[108:109], v[70:71], off offset:992
	v_pk_mul_f32 v[70:71], v[74:75], v[114:115] neg_lo:[1,0] neg_hi:[1,0]
	v_and_b32_sdwa v72, v65, v170 dst_sel:DWORD dst_unused:UNUSED_PAD src0_sel:WORD_1 src1_sel:DWORD
	v_and_b32_sdwa v73, v64, v170 dst_sel:DWORD dst_unused:UNUSED_PAD src0_sel:WORD_1 src1_sel:DWORD
	ds_bpermute_b32 v56, v176, v54
	v_add3_u32 v64, v64, v73, s61
	v_add3_u32 v65, v65, v72, s61
	v_and_b32_sdwa v72, v71, v170 dst_sel:DWORD dst_unused:UNUSED_PAD src0_sel:WORD_1 src1_sel:DWORD
	v_and_b32_sdwa v73, v70, v170 dst_sel:DWORD dst_unused:UNUSED_PAD src0_sel:WORD_1 src1_sel:DWORD
	v_add3_u32 v71, v71, v72, s61
	v_add3_u32 v70, v70, v73, s61
	v_bfe_u32 v57, v55, 16, 1
	v_and_b32_e32 v71, 0xffff0000, v71
	v_and_b32_e32 v70, 0xffff0000, v70
	v_lshrrev_b32_e32 v53, 16, v53
	v_add3_u32 v55, v55, v57, s61
	v_or_b32_sdwa v65, v71, v65 dst_sel:DWORD dst_unused:UNUSED_PAD src0_sel:DWORD src1_sel:WORD_1
	v_or_b32_sdwa v64, v70, v64 dst_sel:DWORD dst_unused:UNUSED_PAD src0_sel:DWORD src1_sel:WORD_1
	v_and_or_b32 v53, v55, s60, v53
	global_store_dwordx2 v[108:109], v[64:65], off offset:1120
	global_store_dwordx2 v[82:83], v[52:53], off offset:96
	s_waitcnt lgkmcnt(0)
	v_add_f32_e32 v52, v54, v56
	v_lshlrev_b32_e32 v54, 16, v48
	v_and_b32_e32 v55, 0xffff0000, v48
	v_lshlrev_b32_e32 v48, 16, v49
	v_and_b32_e32 v49, 0xffff0000, v49
	v_pk_mul_f32 v[54:55], v[52:53], v[54:55] op_sel_hi:[0,1]
	v_pk_mul_f32 v[48:49], v[52:53], v[48:49] op_sel_hi:[0,1]
	v_cvt_pk_bf16_f32 v54, v54, v55
	v_bfe_u32 v53, v48, 16, 1
	v_add3_u32 v48, v48, v53, s61
	v_bfe_u32 v53, v49, 16, 1
	v_lshrrev_b32_e32 v48, 16, v48
	v_add3_u32 v49, v49, v53, s61
	v_and_or_b32 v55, v49, s60, v48
	v_lshl_add_u64 v[48:49], v[106:107], 0, v[80:81]
	global_store_dwordx2 v[48:49], v[54:55], off
	v_lshlrev_b32_e32 v54, 16, v50
	v_and_b32_e32 v55, 0xffff0000, v50
	v_lshlrev_b32_e32 v50, 16, v51
	v_and_b32_e32 v51, 0xffff0000, v51
	v_pk_mul_f32 v[54:55], v[52:53], v[54:55] op_sel_hi:[0,1]
	v_pk_mul_f32 v[50:51], v[52:53], v[50:51] op_sel_hi:[0,1]
	v_cvt_pk_bf16_f32 v54, v54, v55
	v_bfe_u32 v53, v50, 16, 1
	v_add3_u32 v50, v50, v53, s61
	v_bfe_u32 v53, v51, 16, 1
	v_lshrrev_b32_e32 v50, 16, v50
	v_add3_u32 v51, v51, v53, s61
	v_and_or_b32 v55, v51, s60, v50
	v_lshlrev_b32_e32 v50, 16, v60
	v_and_b32_e32 v51, 0xffff0000, v60
	global_store_dwordx2 v[48:49], v[54:55], off offset:32
	v_lshlrev_b32_e32 v54, 16, v61
	v_and_b32_e32 v55, 0xffff0000, v61
	v_pk_mul_f32 v[50:51], v[52:53], v[50:51] op_sel_hi:[0,1]
	v_pk_mul_f32 v[54:55], v[52:53], v[54:55] op_sel_hi:[0,1]
	v_cvt_pk_bf16_f32 v50, v50, v51
	v_bfe_u32 v51, v54, 16, 1
	v_add3_u32 v51, v54, v51, s61
	v_bfe_u32 v53, v55, 16, 1
	v_lshrrev_b32_e32 v51, 16, v51
	v_add3_u32 v53, v55, v53, s61
	v_and_or_b32 v51, v53, s60, v51
	global_store_dwordx2 v[48:49], v[50:51], off offset:64
	v_lshlrev_b32_e32 v50, 16, v62
	v_and_b32_e32 v51, 0xffff0000, v62
	v_lshlrev_b32_e32 v54, 16, v63
	v_and_b32_e32 v55, 0xffff0000, v63
	v_pk_mul_f32 v[50:51], v[52:53], v[50:51] op_sel_hi:[0,1]
	v_pk_mul_f32 v[54:55], v[52:53], v[54:55] op_sel_hi:[0,1]
	v_cvt_pk_bf16_f32 v50, v50, v51
	v_bfe_u32 v51, v54, 16, 1
	v_add3_u32 v51, v54, v51, s61
	v_bfe_u32 v52, v55, 16, 1
	v_lshrrev_b32_e32 v51, 16, v51
	v_add3_u32 v52, v55, v52, s61
	v_and_or_b32 v51, v52, s60, v51
	global_store_dwordx2 v[48:49], v[50:51], off offset:96
	s_cbranch_scc0 .LBB0_1327
	s_add_i32 s77, s77, s74
	s_cmpk_gt_i32 s77, 0x18b
	s_cbranch_scc0 .LBB0_1322

; __device__ __forceinline__ unsigned pk2(float lo, float hi) { return f2bf(lo) | (f2bf(hi) << 16); }
; __device__ __forceinline__ void na_item(int item, const bf16* Z, const float* rpb, bf16* CC, LAS unsigned char* lds, int tid, int wave, int lane) {
;     ...
;     lrun += __shfl_xor(lrun, 16); lrun += __shfl_xor(lrun, 32);
;     const float il = 1.f / lrun;
;     bf16* op = CC + mq * D + 1280 + h * 64 + 4 * g;
; #pragma unroll
;     for (int nb = 0; nb < 4; ++nb) { u32x2 w; w.x = pk2(oacc[nb][0] * il, oacc[nb][1] * il); w.y = pk2(oacc[nb][2] * il, oacc[nb][3] * il); *(u32x2*)(op + nb * 16) = w; }
.LBB0_1333:
	s_waitcnt vmcnt(2)
	ds_bpermute_b32 v3, v123, v87
	v_mov_b32_e32 v2, v44
	v_lshlrev_b64 v[0:1], 12, v[88:89]
	v_lshl_add_u64 v[0:1], s[70:71], 0, v[0:1]
	v_lshl_add_u64 v[0:1], s[46:47], 1, v[0:1]
	s_waitcnt lgkmcnt(0)
	v_add_f32_e32 v4, v87, v3
	ds_bpermute_b32 v5, v124, v4
	v_mov_b32_e32 v3, v46
	v_mov_b32_e32 v46, v45
	v_lshl_add_u64 v[0:1], v[70:71], 1, v[0:1]
	s_add_i32 s6, s28, s6
	s_waitcnt lgkmcnt(0)
	v_add_f32_e32 v6, v4, v5
	v_div_scale_f32 v7, s[4:5], v6, v6, 1.0
	v_rcp_f32_e32 v8, v7
	v_div_scale_f32 v9, vcc, 1.0, v6, 1.0
	v_lshl_add_u64 v[4:5], v[0:1], 0, s[44:45]
	v_fma_f32 v10, -v7, v8, 1.0
	v_fmac_f32_e32 v8, v10, v8
	v_mul_f32_e32 v10, v9, v8
	v_fma_f32 v11, -v7, v10, v9
	v_fmac_f32_e32 v10, v11, v8
	v_fma_f32 v7, -v7, v10, v9
	v_div_fmas_f32 v7, v7, v8, v10
	v_div_fixup_f32 v6, v7, v6, 1.0
	v_pk_mul_f32 v[2:3], v[2:3], v[6:7] op_sel_hi:[1,0]
	v_pk_mul_f32 v[8:9], v[46:47], v[6:7] op_sel_hi:[1,0]
	v_and_b32_sdwa v7, v3, v127 dst_sel:DWORD dst_unused:UNUSED_PAD src0_sel:WORD_1 src1_sel:DWORD
	v_and_b32_sdwa v10, v2, v127 dst_sel:DWORD dst_unused:UNUSED_PAD src0_sel:WORD_1 src1_sel:DWORD
	v_add3_u32 v2, v2, v10, s33
	v_add3_u32 v3, v3, v7, s33
	v_and_b32_sdwa v7, v9, v127 dst_sel:DWORD dst_unused:UNUSED_PAD src0_sel:WORD_1 src1_sel:DWORD
	v_and_b32_sdwa v10, v8, v127 dst_sel:DWORD dst_unused:UNUSED_PAD src0_sel:WORD_1 src1_sel:DWORD
	v_add3_u32 v7, v9, v7, s33
	v_add3_u32 v8, v8, v10, s33
	v_and_b32_e32 v7, 0xffff0000, v7
	v_and_b32_e32 v8, 0xffff0000, v8
	v_add_co_u32_e32 v0, vcc, s60, v0
	v_or_b32_sdwa v3, v7, v3 dst_sel:DWORD dst_unused:UNUSED_PAD src0_sel:DWORD src1_sel:WORD_1
	v_or_b32_sdwa v2, v8, v2 dst_sel:DWORD dst_unused:UNUSED_PAD src0_sel:DWORD src1_sel:WORD_1
	v_addc_co_u32_e32 v1, vcc, 0, v1, vcc
	global_store_dwordx2 v[0:1], v[2:3], off offset:2560
	v_mov_b32_e32 v0, v40
	v_mov_b32_e32 v1, v42
	v_pk_mul_f32 v[0:1], v[0:1], v[6:7] op_sel_hi:[1,0]
	v_mov_b32_e32 v42, v41
	v_pk_mul_f32 v[2:3], v[42:43], v[6:7] op_sel_hi:[1,0]
	v_and_b32_sdwa v7, v1, v127 dst_sel:DWORD dst_unused:UNUSED_PAD src0_sel:WORD_1 src1_sel:DWORD
	s_nop 0
	s_nop 0
	v_add3_u32 v1, v1, v7, s33
	v_and_b32_sdwa v7, v3, v127 dst_sel:DWORD dst_unused:UNUSED_PAD src0_sel:WORD_1 src1_sel:DWORD
	s_nop 0
	v_add3_u32 v3, v3, v7, s33
	s_nop 0
	v_and_b32_e32 v3, 0xffff0000, v3
	s_nop 0
	v_or_b32_sdwa v1, v3, v1 dst_sel:DWORD dst_unused:UNUSED_PAD src0_sel:DWORD src1_sel:WORD_1
	v_cvt_pk_bf16_f32 v0, v0, v2
	global_store_dwordx2 v[4:5], v[0:1], off offset:32
	v_mov_b32_e32 v0, v28
	v_mov_b32_e32 v1, v30
	v_pk_mul_f32 v[0:1], v[0:1], v[6:7] op_sel_hi:[1,0]
	v_mov_b32_e32 v30, v29
	v_pk_mul_f32 v[2:3], v[30:31], v[6:7] op_sel_hi:[1,0]
	v_and_b32_sdwa v7, v1, v127 dst_sel:DWORD dst_unused:UNUSED_PAD src0_sel:WORD_1 src1_sel:DWORD
	v_and_b32_sdwa v8, v0, v127 dst_sel:DWORD dst_unused:UNUSED_PAD src0_sel:WORD_1 src1_sel:DWORD
	v_add3_u32 v0, v0, v8, s33
	v_add3_u32 v1, v1, v7, s33
	v_and_b32_sdwa v7, v3, v127 dst_sel:DWORD dst_unused:UNUSED_PAD src0_sel:WORD_1 src1_sel:DWORD
	v_and_b32_sdwa v8, v2, v127 dst_sel:DWORD dst_unused:UNUSED_PAD src0_sel:WORD_1 src1_sel:DWORD
	v_add3_u32 v3, v3, v7, s33
	v_add3_u32 v2, v2, v8, s33
	v_and_b32_e32 v3, 0xffff0000, v3
	v_and_b32_e32 v2, 0xffff0000, v2
	v_or_b32_sdwa v1, v3, v1 dst_sel:DWORD dst_unused:UNUSED_PAD src0_sel:DWORD src1_sel:WORD_1
	v_or_b32_sdwa v0, v2, v0 dst_sel:DWORD dst_unused:UNUSED_PAD src0_sel:DWORD src1_sel:WORD_1
	global_store_dwordx2 v[4:5], v[0:1], off offset:64
	v_mov_b32_e32 v0, v24
	v_mov_b32_e32 v1, v26
	v_pk_mul_f32 v[0:1], v[0:1], v[6:7] op_sel_hi:[1,0]
	v_mov_b32_e32 v26, v25
	v_pk_mul_f32 v[2:3], v[26:27], v[6:7] op_sel_hi:[1,0]
	v_and_b32_sdwa v6, v1, v127 dst_sel:DWORD dst_unused:UNUSED_PAD src0_sel:WORD_1 src1_sel:DWORD
	v_and_b32_sdwa v7, v0, v127 dst_sel:DWORD dst_unused:UNUSED_PAD src0_sel:WORD_1 src1_sel:DWORD
	v_add3_u32 v0, v0, v7, s33
	v_add3_u32 v1, v1, v6, s33
	v_and_b32_sdwa v6, v3, v127 dst_sel:DWORD dst_unused:UNUSED_PAD src0_sel:WORD_1 src1_sel:DWORD
	v_and_b32_sdwa v7, v2, v127 dst_sel:DWORD dst_unused:UNUSED_PAD src0_sel:WORD_1 src1_sel:DWORD
	v_add3_u32 v3, v3, v6, s33
	v_add3_u32 v2, v2, v7, s33
	v_and_b32_e32 v3, 0xffff0000, v3
	v_and_b32_e32 v2, 0xffff0000, v2
	v_or_b32_sdwa v1, v3, v1 dst_sel:DWORD dst_unused:UNUSED_PAD src0_sel:DWORD src1_sel:WORD_1
	v_or_b32_sdwa v0, v2, v0 dst_sel:DWORD dst_unused:UNUSED_PAD src0_sel:DWORD src1_sel:WORD_1
	s_cmpk_lt_i32 s6, 0x1d0
	global_store_dwordx2 v[4:5], v[0:1], off offset:96
	s_cbranch_scc0 .LBB0_1410

; #define LAS __attribute__((address_space(3)))
; __device__ __forceinline__ unsigned pk2(float lo, float hi) { return f2bf(lo) | (f2bf(hi) << 16); }
; #define MFMA16(a, b, c) __builtin_amdgcn_mfma_f32_16x16x32_bf16((a), (b), (c), 0, 0, 0)
; __device__ __forceinline__ void na_item(int item, const bf16* Z, const float* rpb, bf16* CC, LAS unsigned char* lds, int tid, int wave, int lane) {
;     ...
;             bf16x8 pf[2];
; #pragma unroll
;             for (int ks = 0; ks < 2; ++ks) { u32x4 w; w.x = pk2(sc[2 * ks][0], sc[2 * ks][1]); w.y = pk2(sc[2 * ks][2], sc[2 * ks][3]); w.z = pk2(sc[2 * ks + 1][0], sc[2 * ks + 1][1]); w.w = pk2(sc[2 * ks + 1][2], sc[2 * ks + 1][3]);
;                 pf[ks] = __builtin_bit_cast(bf16x8, w); }
; #pragma unroll
;             for (int nb = 0; nb < 4; ++nb) oacc[nb] = oacc[nb] * alpha;
; #pragma unroll
;             for (int ks = 0; ks < 2; ++ks) {
;                 const bool kson = !loc || (2 * ks + 1 >= nlo && 2 * ks <= nhi);
;                 if (kson) {
; #pragma unroll
;                     for (int nb = 0; nb < 4; ++nb) { const LAS bf16* vp = Vt + (nb * 16 + fr) * KSTR + 32 * ks + 4 * g;
;                         const u32x2 lo = *(const LAS u32x2*)vp, hi = *(const LAS u32x2*)(vp + 16);
;                         u32x4 w; w.x = lo.x; w.y = lo.y; w.z = hi.x; w.w = hi.y;
;                         oacc[nb] = MFMA16(__builtin_bit_cast(bf16x8, w), pf[ks], oacc[nb]); }
;                 }
;             }
.LBB0_1405:
	v_add_u32_e32 v95, v120, v122
	v_add_u32_e32 v131, v120, v103
	s_andn2_b64 vcc, exec, s[48:49]
	v_add_u32_e32 v130, 0x2000, v95
	v_add_u32_e32 v129, 0x2800, v95
	v_add_u32_e32 v128, 0x3000, v95
	v_add_u32_e32 v95, 0x2000, v131
	s_cbranch_vccnz .LBB0_1407
	v_bfe_u32 v131, v0, 16, 1
	v_add3_u32 v0, v0, v131, s33
	v_bfe_u32 v131, v1, 16, 1
	v_lshrrev_b32_e32 v0, 16, v0
	v_add3_u32 v1, v1, v131, s33
	v_and_or_b32 v0, v1, s43, v0
	v_cvt_pk_bf16_f32 v1, v2, v3
	v_cvt_pk_bf16_f32 v2, v4, v5
	s_nop 0
	s_nop 0
	v_cvt_pk_bf16_f32 v3, v6, v7
	ds_read2_b64 v[4:7], v129 offset0:160 offset1:164
	ds_read2_b64 v[132:135], v130 offset0:128 offset1:132
	s_waitcnt lgkmcnt(1)
	v_mfma_f32_16x16x32_bf16 v[40:43], v[4:7], v[0:3], v[40:43]
	ds_read2_b64 v[4:7], v128 offset0:192 offset1:196
	s_waitcnt lgkmcnt(0)
	v_mfma_f32_16x16x32_bf16 v[28:31], v[4:7], v[0:3], v[28:31]
	ds_read2_b64 v[4:7], v95 offset0:128 offset1:132
	v_mfma_f32_16x16x32_bf16 v[44:47], v[132:135], v[0:3], v[44:47]
	s_waitcnt lgkmcnt(0)
	v_mfma_f32_16x16x32_bf16 v[24:27], v[4:7], v[0:3], v[24:27]
.LBB0_1407:
	s_andn2_b64 vcc, exec, s[50:51]
	s_cbranch_vccnz .LBB0_1409
	s_nop 0
	s_nop 0
	s_nop 0
	s_nop 0
	s_nop 0
	v_cvt_pk_bf16_f32 v0, v8, v9
	ds_read2_b64 v[4:7], v130 offset0:136 offset1:140
	v_cvt_pk_bf16_f32 v1, v10, v11
	v_cvt_pk_bf16_f32 v2, v12, v13
	v_bfe_u32 v3, v14, 16, 1
	v_add3_u32 v3, v14, v3, s33
	v_bfe_u32 v8, v15, 16, 1
	v_lshrrev_b32_e32 v3, 16, v3
	v_add3_u32 v8, v15, v8, s33
	v_and_or_b32 v3, v8, s43, v3
	s_waitcnt lgkmcnt(0)
	s_nop 0
	v_mfma_f32_16x16x32_bf16 v[44:47], v[4:7], v[0:3], v[44:47]
	ds_read2_b64 v[4:7], v129 offset0:168 offset1:172
	s_waitcnt lgkmcnt(0)
	v_mfma_f32_16x16x32_bf16 v[40:43], v[4:7], v[0:3], v[40:43]
	ds_read2_b64 v[4:7], v128 offset0:200 offset1:204
	s_waitcnt lgkmcnt(0)
	v_mfma_f32_16x16x32_bf16 v[28:31], v[4:7], v[0:3], v[28:31]
	ds_read2_b64 v[4:7], v95 offset0:136 offset1:140
	s_waitcnt lgkmcnt(0)
	v_mfma_f32_16x16x32_bf16 v[24:27], v[4:7], v[0:3], v[24:27]

; __device__ __forceinline__ unsigned pk2(float lo, float hi) { return f2bf(lo) | (f2bf(hi) << 16); }
; __device__ __forceinline__ void na_item(int item, const bf16* Z, const float* rpb, bf16* CC, LAS unsigned char* lds, int tid, int wave, int lane) {
;     ...
;     lrun += __shfl_xor(lrun, 16); lrun += __shfl_xor(lrun, 32);
;     const float il = 1.f / lrun;
;     bf16* op = CC + mq * D + 1280 + h * 64 + 4 * g;
; #pragma unroll
;     for (int nb = 0; nb < 4; ++nb) { u32x2 w; w.x = pk2(oacc[nb][0] * il, oacc[nb][1] * il); w.y = pk2(oacc[nb][2] * il, oacc[nb][3] * il); *(u32x2*)(op + nb * 16) = w; }
.LBB0_1468:
	s_waitcnt vmcnt(2)
	v_and_b32_e32 v1, 64, v142
	v_xor_b32_e32 v0, 16, v142
	v_add_u32_e32 v1, 64, v1
	v_cmp_lt_i32_e32 vcc, v0, v1
	v_xor_b32_e32 v2, 32, v142
	s_nop 0
	v_cndmask_b32_e32 v0, v142, v0, vcc
	v_lshlrev_b32_e32 v0, 2, v0
	ds_bpermute_b32 v0, v0, v91
	v_cmp_lt_i32_e32 vcc, v2, v1
	s_waitcnt lgkmcnt(0)
	v_add_f32_e32 v0, v91, v0
	v_cndmask_b32_e32 v1, v142, v2, vcc
	v_lshlrev_b32_e32 v1, 2, v1
	ds_bpermute_b32 v1, v1, v0
	s_waitcnt lgkmcnt(0)
	v_add_f32_e32 v2, v0, v1
	v_div_scale_f32 v3, s[4:5], v2, v2, 1.0
	v_rcp_f32_e32 v4, v3
	v_div_scale_f32 v5, vcc, 1.0, v2, 1.0
	v_lshlrev_b64 v[0:1], 12, v[96:97]
	v_fma_f32 v6, -v3, v4, 1.0
	v_fmac_f32_e32 v4, v6, v4
	v_mul_f32_e32 v6, v5, v4
	v_fma_f32 v7, -v3, v6, v5
	v_fmac_f32_e32 v6, v7, v4
	v_fma_f32 v3, -v3, v6, v5
	v_div_fmas_f32 v3, v3, v4, v6
	v_div_fixup_f32 v2, v3, v2, 1.0
	v_mov_b32_e32 v4, v44
	v_mov_b32_e32 v5, v46
	v_pk_mul_f32 v[4:5], v[4:5], v[2:3] op_sel_hi:[1,0]
	v_mov_b32_e32 v46, v45
	v_pk_mul_f32 v[6:7], v[46:47], v[2:3] op_sel_hi:[1,0]
	v_and_b32_sdwa v3, v5, v140 dst_sel:DWORD dst_unused:UNUSED_PAD src0_sel:WORD_1 src1_sel:DWORD
	s_nop 0
	s_nop 0
	v_add3_u32 v3, v5, v3, s60
	v_and_b32_sdwa v5, v7, v140 dst_sel:DWORD dst_unused:UNUSED_PAD src0_sel:WORD_1 src1_sel:DWORD
	s_nop 0
	v_lshl_add_u64 v[0:1], s[12:13], 0, v[0:1]
	v_add3_u32 v5, v7, v5, s60
	s_nop 0
	v_lshl_add_u64 v[0:1], s[44:45], 1, v[0:1]
	v_and_b32_e32 v5, 0xffff0000, v5
	s_nop 0
	v_lshl_add_u64 v[0:1], v[74:75], 1, v[0:1]
	v_or_b32_sdwa v5, v5, v3 dst_sel:DWORD dst_unused:UNUSED_PAD src0_sel:DWORD src1_sel:WORD_1
	v_cvt_pk_bf16_f32 v4, v4, v6
	global_store_dwordx2 v[0:1], v[4:5], off offset:2560
	v_mov_b32_e32 v4, v40
	v_mov_b32_e32 v5, v42
	v_pk_mul_f32 v[4:5], v[4:5], v[2:3] op_sel_hi:[1,0]
	v_mov_b32_e32 v42, v41
	v_pk_mul_f32 v[6:7], v[42:43], v[2:3] op_sel_hi:[1,0]
	v_and_b32_sdwa v3, v5, v140 dst_sel:DWORD dst_unused:UNUSED_PAD src0_sel:WORD_1 src1_sel:DWORD
	s_nop 0
	s_nop 0
	v_add3_u32 v3, v5, v3, s60
	v_and_b32_sdwa v5, v7, v140 dst_sel:DWORD dst_unused:UNUSED_PAD src0_sel:WORD_1 src1_sel:DWORD
	s_nop 0
	v_add3_u32 v5, v7, v5, s60
	s_nop 0
	v_and_b32_e32 v5, 0xffff0000, v5
	s_nop 0
	v_or_b32_sdwa v5, v5, v3 dst_sel:DWORD dst_unused:UNUSED_PAD src0_sel:DWORD src1_sel:WORD_1
	v_cvt_pk_bf16_f32 v4, v4, v6
	global_store_dwordx2 v[0:1], v[4:5], off offset:2592
	v_mov_b32_e32 v4, v28
	v_mov_b32_e32 v5, v30
	v_pk_mul_f32 v[4:5], v[4:5], v[2:3] op_sel_hi:[1,0]
	v_mov_b32_e32 v30, v29
	v_pk_mul_f32 v[6:7], v[30:31], v[2:3] op_sel_hi:[1,0]
	v_and_b32_sdwa v3, v5, v140 dst_sel:DWORD dst_unused:UNUSED_PAD src0_sel:WORD_1 src1_sel:DWORD
	v_and_b32_sdwa v8, v4, v140 dst_sel:DWORD dst_unused:UNUSED_PAD src0_sel:WORD_1 src1_sel:DWORD
	v_add3_u32 v4, v4, v8, s60
	v_add3_u32 v3, v5, v3, s60
	v_and_b32_sdwa v5, v7, v140 dst_sel:DWORD dst_unused:UNUSED_PAD src0_sel:WORD_1 src1_sel:DWORD
	v_and_b32_sdwa v8, v6, v140 dst_sel:DWORD dst_unused:UNUSED_PAD src0_sel:WORD_1 src1_sel:DWORD
	v_add3_u32 v5, v7, v5, s60
	v_add3_u32 v6, v6, v8, s60
	v_and_b32_e32 v5, 0xffff0000, v5
	v_and_b32_e32 v6, 0xffff0000, v6
	v_or_b32_sdwa v5, v5, v3 dst_sel:DWORD dst_unused:UNUSED_PAD src0_sel:DWORD src1_sel:WORD_1
	v_or_b32_sdwa v4, v6, v4 dst_sel:DWORD dst_unused:UNUSED_PAD src0_sel:DWORD src1_sel:WORD_1
	global_store_dwordx2 v[0:1], v[4:5], off offset:2624
	v_mov_b32_e32 v4, v24
	v_mov_b32_e32 v5, v26
	v_pk_mul_f32 v[4:5], v[4:5], v[2:3] op_sel_hi:[1,0]
	v_mov_b32_e32 v26, v25
	v_pk_mul_f32 v[2:3], v[26:27], v[2:3] op_sel_hi:[1,0]
	v_and_b32_sdwa v6, v5, v140 dst_sel:DWORD dst_unused:UNUSED_PAD src0_sel:WORD_1 src1_sel:DWORD
	v_and_b32_sdwa v7, v4, v140 dst_sel:DWORD dst_unused:UNUSED_PAD src0_sel:WORD_1 src1_sel:DWORD
	v_add3_u32 v4, v4, v7, s60
	v_add3_u32 v5, v5, v6, s60
	v_and_b32_sdwa v6, v3, v140 dst_sel:DWORD dst_unused:UNUSED_PAD src0_sel:WORD_1 src1_sel:DWORD
	v_and_b32_sdwa v7, v2, v140 dst_sel:DWORD dst_unused:UNUSED_PAD src0_sel:WORD_1 src1_sel:DWORD
	v_add3_u32 v3, v3, v6, s60
	v_add3_u32 v2, v2, v7, s60
	v_and_b32_e32 v3, 0xffff0000, v3
	v_and_b32_e32 v2, 0xffff0000, v2
	v_or_b32_sdwa v3, v3, v5 dst_sel:DWORD dst_unused:UNUSED_PAD src0_sel:DWORD src1_sel:WORD_1
	v_or_b32_sdwa v2, v2, v4 dst_sel:DWORD dst_unused:UNUSED_PAD src0_sel:DWORD src1_sel:WORD_1
	global_store_dwordx2 v[0:1], v[2:3], off offset:2656

; __device__ __forceinline__ float gelu_f(float x) { const float y = 0.7978845608f * (x + 0.044715f * x * x * x); return 0.5f * x * (1.f + tanh_f(y)); }
; __device__ __forceinline__ void gmlp_item(int item, const bf16* Z, const bf16* gmws, const float* gmbs, bf16* CC, LAS unsigned char* lds, int tid, int wave, int lane) {
;     ...
;     const int cidx = item >> 3, gi = item & 7, fr = lane & 15, g = lane >> 4;
;     __syncthreads();
;     { const int j = tid >> 2, part = tid & 3; const bf16* zp = Z + (size_t)(cidx * 128 + j) * INCP + 512 + gi * 64 + 16 * part;
;       const u32x4 a = *(const u32x4*)zp, bq = *(const u32x4*)(zp + 8);
;       float x[16]; const unsigned w[8] = {a.x, a.y, a.z, a.w, bq.x, bq.y, bq.z, bq.w};
;       float s = 0.f;
; #pragma unroll
;       for (int e = 0; e < 8; ++e) { x[2 * e] = gelu_f(bflo(w[e])); x[2 * e + 1] = gelu_f(bfhi(w[e])); s += x[2 * e] + x[2 * e + 1]; }
;       s += __shfl_xor(s, 1); s += __shfl_xor(s, 2); const float mu = s * (1.f / 64.f); float s2 = 0.f;
.LBB0_1470:
	s_cmpk_gt_i32 s6, 0x5ff
	v_mbcnt_hi_u32_b32 v142, -1, v139
	s_mov_b64 s[4:5], -1
	s_cbranch_scc0 .LBB0_1472
	s_lshl_b32 s2, s6, 4
	s_addk_i32 s2, 0x2000
	s_and_b32 s4, s2, 0x7f80
	v_add_u32_e32 v0, s4, v73
	v_mul_u32_u24_e32 v0, 0x1800, v0
	v_lshlrev_b32_e32 v64, 1, v0
	s_lshl_b32 s2, s6, 7
	v_lshl_add_u64 v[0:1], s[14:15], 0, v[64:65]
	s_and_b32 s30, s2, 0x380
	v_lshl_add_u64 v[0:1], v[0:1], 0, s[30:31]
	v_mov_b32_e32 v91, v65
	v_lshl_add_u64 v[0:1], v[0:1], 0, v[90:91]
	s_barrier
	global_load_dwordx4 v[4:7], v[0:1], off offset:1024
	s_nop 0
	global_load_dwordx4 v[0:3], v[0:1], off offset:1040
	v_add_u32_e32 v64, s30, v107
	s_waitcnt vmcnt(1)
	v_lshlrev_b32_e32 v9, 16, v5
	v_lshlrev_b32_e32 v8, 16, v4
	v_and_b32_e32 v10, 0xffff0000, v4
	v_and_b32_e32 v11, 0xffff0000, v5
	v_mul_f32_e32 v16, 0x3d372713, v8
	v_mul_f32_e32 v18, 0x3d372713, v10
	v_mul_f32_e32 v20, 0x3d372713, v9
	v_lshlrev_b32_e32 v13, 16, v7
	v_lshlrev_b32_e32 v12, 16, v6
	v_and_b32_e32 v15, 0xffff0000, v7
	v_and_b32_e32 v14, 0xffff0000, v6
	v_mov_b32_e32 v17, v8
	v_mov_b32_e32 v19, v10
	v_mov_b32_e32 v21, v9
	v_pk_mul_f32 v[6:7], v[8:9], 0.5 op_sel_hi:[1,0]
	v_mul_f32_e32 v22, 0x3d372713, v11
	v_pk_mul_f32 v[4:5], v[10:11], 0.5 op_sel_hi:[1,0]
	v_mul_f32_e32 v8, v16, v8
	v_mul_f32_e32 v10, v18, v10
	v_mul_f32_e32 v9, v20, v9
	v_mov_b32_e32 v23, v11
	v_mul_f32_e32 v11, v22, v11
	v_fmac_f32_e32 v17, v8, v17
	v_fmac_f32_e32 v19, v10, v19
	v_fmac_f32_e32 v21, v9, v21
	v_fmac_f32_e32 v23, v11, v23
	v_mul_f32_e32 v8, 0x3f4c422a, v17
	v_mul_f32_e32 v9, 0x3f4c422a, v19
	v_mul_f32_e32 v10, 0x3f4c422a, v21
	v_mul_f32_e32 v11, 0x3f4c422a, v23
	v_add_f32_e32 v8, v8, v8
	v_add_f32_e32 v9, v9, v9
	v_add_f32_e32 v10, v10, v10
	v_mul_f32_e32 v24, 0x3d372713, v12
	v_mul_f32_e32 v26, 0x3d372713, v14
	v_mul_f32_e32 v28, 0x3d372713, v13
	v_add_f32_e32 v11, v11, v11
	v_mul_f32_e32 v8, 0x3fb8aa3b, v8
	v_mul_f32_e32 v9, 0x3fb8aa3b, v9
	v_mul_f32_e32 v10, 0x3fb8aa3b, v10
	v_mov_b32_e32 v25, v12
	v_mov_b32_e32 v27, v14
	v_mov_b32_e32 v29, v13
	v_mul_f32_e32 v16, v24, v12
	v_mul_f32_e32 v18, v26, v14
	v_mul_f32_e32 v20, v28, v13
	v_mul_f32_e32 v11, 0x3fb8aa3b, v11
	v_exp_f32_e32 v8, v8
	v_exp_f32_e32 v9, v9
	v_exp_f32_e32 v10, v10
	v_fmac_f32_e32 v25, v16, v25
	v_fmac_f32_e32 v27, v18, v27
	v_fmac_f32_e32 v29, v20, v29
	v_exp_f32_e32 v11, v11
	v_mul_f32_e32 v16, 0x3f4c422a, v25
	v_mul_f32_e32 v17, 0x3f4c422a, v27
	v_mul_f32_e32 v18, 0x3f4c422a, v29
	v_add_f32_e32 v16, v16, v16
	v_add_f32_e32 v17, v17, v17
	v_add_f32_e32 v18, v18, v18
	v_mul_f32_e32 v30, 0x3d372713, v15
	v_mul_f32_e32 v16, 0x3fb8aa3b, v16
	v_mul_f32_e32 v17, 0x3fb8aa3b, v17
	v_mul_f32_e32 v18, 0x3fb8aa3b, v18
	v_add_f32_e32 v8, 1.0, v8
	v_add_f32_e32 v9, 1.0, v9
	v_add_f32_e32 v20, 1.0, v10
	v_mov_b32_e32 v31, v15
	v_mul_f32_e32 v22, v30, v15
	v_exp_f32_e32 v16, v16
	v_exp_f32_e32 v17, v17
	v_exp_f32_e32 v18, v18
	v_add_f32_e32 v11, 1.0, v11
	v_rcp_f32_e32 v8, v8
	v_rcp_f32_e32 v10, v9
	v_rcp_f32_e32 v9, v20
	v_fmac_f32_e32 v31, v22, v31
	v_rcp_f32_e32 v11, v11
	v_mul_f32_e32 v19, 0x3f4c422a, v31
	v_add_f32_e32 v19, v19, v19
	v_mul_f32_e32 v19, 0x3fb8aa3b, v19
	v_add_f32_e32 v16, 1.0, v16
	v_add_f32_e32 v21, 1.0, v17
	v_add_f32_e32 v17, 1.0, v18
	v_pk_fma_f32 v[8:9], v[8:9], 2.0, 1.0 op_sel_hi:[1,0,0] neg_lo:[1,0,0] neg_hi:[1,0,0]
	v_rcp_f32_e32 v16, v16
	v_rcp_f32_e32 v17, v17
	v_pk_fma_f32 v[10:11], v[10:11], 2.0, 1.0 op_sel_hi:[1,0,0] neg_lo:[1,0,0] neg_hi:[1,0,0]
	v_pk_add_f32 v[8:9], v[8:9], 1.0 op_sel_hi:[1,0]
	v_exp_f32_e32 v19, v19
	v_pk_add_f32 v[10:11], v[10:11], 1.0 op_sel_hi:[1,0]
	v_pk_mul_f32 v[8:9], v[6:7], v[8:9]
	v_rcp_f32_e32 v18, v21
	v_pk_fma_f32 v[6:7], v[4:5], v[10:11], v[8:9]
	s_waitcnt vmcnt(0)
	v_lshlrev_b32_e32 v21, 16, v2
	v_add_f32_e32 v6, 0, v6
	v_add_f32_e32 v20, v7, v6
	v_pk_mul_f32 v[6:7], v[12:13], 0.5 op_sel_hi:[1,0]
	v_pk_fma_f32 v[12:13], v[16:17], 2.0, 1.0 op_sel_hi:[1,0,0] neg_lo:[1,0,0] neg_hi:[1,0,0]
	v_add_f32_e32 v16, 1.0, v19
	v_rcp_f32_e32 v19, v16
	v_pk_add_f32 v[12:13], v[12:13], 1.0 op_sel_hi:[1,0]
	v_lshlrev_b32_e32 v29, 16, v0
	v_pk_mul_f32 v[6:7], v[6:7], v[12:13]
	v_pk_mul_f32 v[12:13], v[14:15], 0.5 op_sel_hi:[1,0]
	v_pk_fma_f32 v[14:15], v[18:19], 2.0, 1.0 op_sel_hi:[1,0,0] neg_lo:[1,0,0] neg_hi:[1,0,0]
	v_and_b32_e32 v28, 0xffff0000, v0
	v_pk_add_f32 v[14:15], v[14:15], 1.0 op_sel_hi:[1,0]
	v_mul_f32_e32 v0, 0x3d372713, v29
	v_pk_fma_f32 v[16:17], v[12:13], v[14:15], v[6:7]
	v_mul_f32_e32 v0, v0, v29
	v_add_f32_e32 v16, v16, v20
	v_add_f32_e32 v36, v17, v16
	v_and_b32_e32 v17, 64, v142
	v_xor_b32_e32 v16, 1, v142
	v_add_u32_e32 v37, 64, v17
	v_cmp_lt_i32_e32 vcc, v16, v37
	v_lshlrev_b32_e32 v17, 16, v3
	v_mov_b32_e32 v18, v17
	v_cndmask_b32_e32 v16, v142, v16, vcc
	v_lshlrev_b32_e32 v38, 2, v16
	v_and_b32_e32 v16, 0xffff0000, v3
	v_mul_f32_e32 v3, 0x3d372713, v17
	v_mul_f32_e32 v3, v3, v17
	v_fmac_f32_e32 v18, v3, v18
	v_mul_f32_e32 v3, 0x3f4c422a, v18
	v_mul_f32_e32 v18, 0x3d372713, v16
	v_mul_f32_e32 v18, v18, v16
	v_mov_b32_e32 v19, v16
	v_fmac_f32_e32 v19, v18, v19
	v_add_f32_e32 v3, v3, v3
	v_mul_f32_e32 v18, 0x3f4c422a, v19
	v_mul_f32_e32 v3, 0x3fb8aa3b, v3
	v_add_f32_e32 v18, v18, v18
	v_exp_f32_e32 v3, v3
	v_mul_f32_e32 v18, 0x3fb8aa3b, v18
	v_exp_f32_e32 v18, v18
	v_and_b32_e32 v20, 0xffff0000, v2
	v_add_f32_e32 v3, 1.0, v3
	v_rcp_f32_e32 v19, v3
	v_add_f32_e32 v3, 1.0, v18
	v_mul_f32_e32 v2, 0x3d372713, v21
	v_rcp_f32_e32 v18, v3
	v_mul_f32_e32 v2, v2, v21
	v_mov_b32_e32 v3, v21
	v_fmac_f32_e32 v3, v2, v3
	v_mul_f32_e32 v2, 0x3f4c422a, v3
	v_add_f32_e32 v2, v2, v2
	v_mul_f32_e32 v2, 0x3fb8aa3b, v2
	v_exp_f32_e32 v22, v2
	v_mul_f32_e32 v2, 0x3d372713, v20
; __device__ __forceinline__ unsigned f2bf(float f) { unsigned u = __builtin_bit_cast(unsigned, f); return (u + 0x7fffu + ((u >> 16) & 1u)) >> 16; }
; __device__ __forceinline__ float gelu_f(float x) { const float y = 0.7978845608f * (x + 0.044715f * x * x * x); return 0.5f * x * (1.f + tanh_f(y)); }
; __device__ __forceinline__ void gmlp_item(int item, const bf16* Z, const bf16* gmws, const float* gmbs, bf16* CC, LAS unsigned char* lds, int tid, int wave, int lane) {
;     ...
;       float s = 0.f;
; #pragma unroll
;       for (int e = 0; e < 8; ++e) { x[2 * e] = gelu_f(bflo(w[e])); x[2 * e + 1] = gelu_f(bfhi(w[e])); s += x[2 * e] + x[2 * e + 1]; }
;       s += __shfl_xor(s, 1); s += __shfl_xor(s, 2); const float mu = s * (1.f / 64.f); float s2 = 0.f;
; #pragma unroll
;       for (int e = 0; e < 16; ++e) { x[e] -= mu; s2 += x[e] * x[e]; }
;       s2 += __shfl_xor(s2, 1); s2 += __shfl_xor(s2, 2); const float rstd = rsqrtf(s2 * (1.f / 64.f) + LN_EPS);
; #pragma unroll
;       for (int e = 0; e < 16; ++e) vt[(16 * part + e) * VSTR + j] = (bf16)f2bf(x[e] * rstd); }
	v_mul_f32_e32 v2, v2, v20
	v_mov_b32_e32 v3, v20
	v_fmac_f32_e32 v3, v2, v3
	v_mul_f32_e32 v2, 0x3f4c422a, v3
	v_add_f32_e32 v2, v2, v2
	v_mul_f32_e32 v2, 0x3fb8aa3b, v2
	v_exp_f32_e32 v23, v2
	v_pk_fma_f32 v[2:3], v[18:19], 2.0, 1.0 op_sel_hi:[1,0,0] neg_lo:[1,0,0] neg_hi:[1,0,0]
	v_add_f32_e32 v18, 1.0, v22
	v_rcp_f32_e32 v19, v18
	v_add_f32_e32 v18, 1.0, v23
	v_rcp_f32_e32 v18, v18
	v_pk_mul_f32 v[16:17], v[16:17], 0.5 op_sel_hi:[1,0]
	v_pk_add_f32 v[2:3], v[2:3], 1.0 op_sel_hi:[1,0]
	v_pk_mul_f32 v[20:21], v[20:21], 0.5 op_sel_hi:[1,0]
	v_pk_fma_f32 v[18:19], v[18:19], 2.0, 1.0 op_sel_hi:[1,0,0] neg_lo:[1,0,0] neg_hi:[1,0,0]
	v_pk_mul_f32 v[22:23], v[16:17], v[2:3]
	v_pk_add_f32 v[18:19], v[18:19], 1.0 op_sel_hi:[1,0]
	v_mov_b32_e32 v26, v22
	v_pk_mul_f32 v[24:25], v[20:21], v[18:19]
	v_pk_mul_f32 v[4:5], v[4:5], v[10:11]
	v_mov_b32_e32 v27, v24
	v_mov_b32_e32 v24, v23
	v_pk_add_f32 v[22:23], v[26:27], v[24:25]
	v_lshlrev_b32_e32 v25, 16, v1
	v_and_b32_e32 v24, 0xffff0000, v1
	v_mul_f32_e32 v1, 0x3d372713, v25
	v_mul_f32_e32 v1, v1, v25
	v_mov_b32_e32 v26, v25
	v_fmac_f32_e32 v26, v1, v26
	v_mul_f32_e32 v1, 0x3f4c422a, v26
	v_mul_f32_e32 v26, 0x3d372713, v24
	v_mul_f32_e32 v26, v26, v24
	v_mov_b32_e32 v27, v24
	v_fmac_f32_e32 v27, v26, v27
	v_add_f32_e32 v1, v1, v1
	v_mul_f32_e32 v26, 0x3f4c422a, v27
	v_mul_f32_e32 v1, 0x3fb8aa3b, v1
	v_add_f32_e32 v26, v26, v26
	v_exp_f32_e32 v1, v1
	v_mul_f32_e32 v26, 0x3fb8aa3b, v26
	v_exp_f32_e32 v26, v26
	v_pk_mul_f32 v[24:25], v[24:25], 0.5 op_sel_hi:[1,0]
	v_add_f32_e32 v1, 1.0, v1
	v_rcp_f32_e32 v27, v1
	v_add_f32_e32 v1, 1.0, v26
	v_rcp_f32_e32 v26, v1
	v_mov_b32_e32 v1, v29
	v_fmac_f32_e32 v1, v0, v1
	v_mul_f32_e32 v0, 0x3f4c422a, v1
	v_add_f32_e32 v0, v0, v0
	v_mul_f32_e32 v0, 0x3fb8aa3b, v0
	v_exp_f32_e32 v30, v0
	v_mul_f32_e32 v0, 0x3d372713, v28
	v_mul_f32_e32 v0, v0, v28
	v_mov_b32_e32 v1, v28
	v_fmac_f32_e32 v1, v0, v1
	v_mul_f32_e32 v0, 0x3f4c422a, v1
	v_add_f32_e32 v0, v0, v0
	v_mul_f32_e32 v0, 0x3fb8aa3b, v0
	v_exp_f32_e32 v31, v0
	v_pk_fma_f32 v[0:1], v[26:27], 2.0, 1.0 op_sel_hi:[1,0,0] neg_lo:[1,0,0] neg_hi:[1,0,0]
	v_add_f32_e32 v26, 1.0, v30
	v_rcp_f32_e32 v27, v26
	v_add_f32_e32 v26, 1.0, v31
	v_rcp_f32_e32 v26, v26
	v_pk_add_f32 v[0:1], v[0:1], 1.0 op_sel_hi:[1,0]
	v_pk_mul_f32 v[28:29], v[28:29], 0.5 op_sel_hi:[1,0]
	v_pk_mul_f32 v[30:31], v[24:25], v[0:1]
	v_pk_fma_f32 v[26:27], v[26:27], 2.0, 1.0 op_sel_hi:[1,0,0] neg_lo:[1,0,0] neg_hi:[1,0,0]
	v_mov_b32_e32 v34, v30
	v_pk_add_f32 v[26:27], v[26:27], 1.0 op_sel_hi:[1,0]
	v_pk_mul_f32 v[10:11], v[12:13], v[14:15]
	v_pk_mul_f32 v[32:33], v[28:29], v[26:27]
	s_nop 0
	v_mov_b32_e32 v35, v32
	v_mov_b32_e32 v32, v31
	v_pk_add_f32 v[30:31], v[34:35], v[32:33]
	s_nop 0
	v_add_f32_e32 v31, v31, v36
	v_add_f32_e32 v30, v30, v31
	v_add_f32_e32 v23, v23, v30
	v_add_f32_e32 v22, v22, v23
	ds_bpermute_b32 v23, v38, v22
	v_xor_b32_e32 v30, 2, v142
	v_cmp_lt_i32_e32 vcc, v30, v37
	s_waitcnt lgkmcnt(0)
	v_add_f32_e32 v22, v22, v23
	v_cndmask_b32_e32 v30, v142, v30, vcc
	v_lshlrev_b32_e32 v30, 2, v30
	ds_bpermute_b32 v23, v30, v22
	s_waitcnt lgkmcnt(0)
	v_add_f32_e32 v13, v22, v23
	v_fmamk_f32 v4, v13, 0xbc800000, v4
	v_fmamk_f32 v8, v13, 0xbc800000, v8
	v_mul_f32_e32 v31, v4, v4
	v_fmac_f32_e32 v31, v8, v8
	v_fmac_f32_e32 v9, 0xbc800000, v13
	v_fmac_f32_e32 v31, v9, v9
	v_fmac_f32_e32 v5, 0xbc800000, v13
	v_fmac_f32_e32 v31, v5, v5
	v_fmamk_f32 v6, v13, 0xbc800000, v6
	v_fmac_f32_e32 v31, v6, v6
	v_fmamk_f32 v10, v13, 0xbc800000, v10
	v_mul_f32_e32 v12, 0x3c800000, v13
	v_fmac_f32_e32 v31, v10, v10
	v_fmac_f32_e32 v7, 0xbc800000, v13
	v_fmac_f32_e32 v31, v7, v7
	v_fmac_f32_e32 v11, 0xbc800000, v13
	v_pk_fma_f32 v[14:15], v[28:29], v[26:27], v[12:13] op_sel_hi:[1,1,0] neg_lo:[0,0,1] neg_hi:[0,0,1]
	v_fmac_f32_e32 v31, v11, v11
	v_pk_mul_f32 v[22:23], v[14:15], v[14:15]
	s_nop 0
	v_add_f32_e32 v13, v23, v31
	v_add_f32_e32 v13, v22, v13
	v_pk_fma_f32 v[0:1], v[24:25], v[0:1], v[12:13] op_sel_hi:[1,1,0] neg_lo:[0,0,1] neg_hi:[0,0,1]
	s_nop 0
	v_pk_mul_f32 v[22:23], v[0:1], v[0:1]
	s_nop 0
	v_add_f32_e32 v13, v23, v13
	v_add_f32_e32 v13, v22, v13
	v_pk_fma_f32 v[18:19], v[20:21], v[18:19], v[12:13] op_sel_hi:[1,1,0] neg_lo:[0,0,1] neg_hi:[0,0,1]
	s_nop 0
	v_pk_mul_f32 v[20:21], v[18:19], v[18:19]
	s_nop 0
	v_add_f32_e32 v13, v21, v13
	v_pk_fma_f32 v[2:3], v[16:17], v[2:3], v[12:13] op_sel_hi:[1,1,0] neg_lo:[0,0,1] neg_hi:[0,0,1]
	v_add_f32_e32 v20, v20, v13
	v_pk_mul_f32 v[12:13], v[2:3], v[2:3]
	s_nop 0
	v_add_f32_e32 v13, v13, v20
	v_add_f32_e32 v12, v12, v13
	ds_bpermute_b32 v13, v38, v12
	s_waitcnt lgkmcnt(0)
	v_add_f32_e32 v12, v12, v13
	ds_bpermute_b32 v13, v30, v12
	s_waitcnt lgkmcnt(0)
	v_add_f32_e32 v12, v12, v13
	v_fmamk_f32 v12, v12, 0x3c800000, v134
	v_mul_f32_e32 v13, 0x4b800000, v12
	v_cmp_gt_f32_e32 vcc, s59, v12
	s_nop 1
	v_cndmask_b32_e32 v12, v12, v13, vcc
	v_rsq_f32_e32 v12, v12
	s_nop 0
	v_mul_f32_e32 v13, 0x45800000, v12
	v_cndmask_b32_e32 v12, v12, v13, vcc
	v_mul_f32_e32 v8, v8, v12
	v_bfe_u32 v13, v8, 16, 1
	v_add3_u32 v8, v8, v13, s60
	v_mul_f32_e32 v4, v4, v12
	ds_write_b16_d16_hi v135, v8
	v_bfe_u32 v8, v4, 16, 1
	v_add3_u32 v4, v4, v8, s60
	ds_write_b16_d16_hi v135, v4 offset:272
	v_mul_f32_e32 v4, v9, v12
	v_bfe_u32 v8, v4, 16, 1
	v_add3_u32 v4, v4, v8, s60
	ds_write_b16_d16_hi v135, v4 offset:544
	v_mul_f32_e32 v4, v5, v12
	v_bfe_u32 v5, v4, 16, 1
	v_add3_u32 v4, v4, v5, s60
	ds_write_b16_d16_hi v135, v4 offset:816
	v_mul_f32_e32 v4, v6, v12
	v_bfe_u32 v5, v4, 16, 1
	v_add3_u32 v4, v4, v5, s60
	ds_write_b16_d16_hi v135, v4 offset:1088
	v_mul_f32_e32 v4, v10, v12
	v_bfe_u32 v5, v4, 16, 1
	v_add3_u32 v4, v4, v5, s60
	ds_write_b16_d16_hi v135, v4 offset:1360
	v_mul_f32_e32 v4, v7, v12
	v_bfe_u32 v5, v4, 16, 1
	v_add3_u32 v4, v4, v5, s60
	ds_write_b16_d16_hi v135, v4 offset:1632
	v_mul_f32_e32 v4, v11, v12
	v_bfe_u32 v5, v4, 16, 1
	v_add3_u32 v4, v4, v5, s60
	ds_write_b16_d16_hi v135, v4 offset:1904
	v_mul_f32_e32 v4, v15, v12
	v_bfe_u32 v5, v4, 16, 1
	v_add3_u32 v4, v4, v5, s60
	ds_write_b16_d16_hi v135, v4 offset:2176
	v_mul_f32_e32 v4, v14, v12
	v_bfe_u32 v5, v4, 16, 1
	v_add3_u32 v4, v4, v5, s60
	v_mul_f32_e32 v1, v1, v12
	ds_write_b16_d16_hi v135, v4 offset:2448
	v_bfe_u32 v4, v1, 16, 1
	v_add3_u32 v1, v1, v4, s60
	v_mul_f32_e32 v0, v0, v12
	ds_write_b16_d16_hi v135, v1 offset:2720
	v_bfe_u32 v1, v0, 16, 1
	v_add3_u32 v0, v0, v1, s60
	ds_write_b16_d16_hi v135, v0 offset:2992
	v_mul_f32_e32 v0, v19, v12
	v_bfe_u32 v1, v0, 16, 1
	v_add3_u32 v0, v0, v1, s60
	ds_write_b16_d16_hi v135, v0 offset:3264
	v_mul_f32_e32 v0, v18, v12
	v_bfe_u32 v1, v0, 16, 1
	v_add3_u32 v0, v0, v1, s60
	ds_write_b16_d16_hi v135, v0 offset:3536
	v_mul_f32_e32 v0, v3, v12
	v_bfe_u32 v1, v0, 16, 1
	v_add3_u32 v0, v0, v1, s60
	ds_write_b16_d16_hi v135, v0 offset:3808
	v_mul_f32_e32 v0, v2, v12
	v_bfe_u32 v1, v0, 16, 1
	v_add3_u32 v0, v0, v1, s60
	ds_write_b16_d16_hi v135, v0 offset:4080
	v_lshlrev_b64 v[0:1], 8, v[64:65]
	v_lshl_add_u64 v[40:41], v[66:67], 0, v[0:1]
	s_waitcnt lgkmcnt(0)
	s_barrier
; #define LAS __attribute__((address_space(3)))
; __device__ __forceinline__ unsigned pk2(float lo, float hi) { return f2bf(lo) | (f2bf(hi) << 16); }
; __device__ __forceinline__ float gelu_f(float x) { const float y = 0.7978845608f * (x + 0.044715f * x * x * x); return 0.5f * x * (1.f + tanh_f(y)); }
; #define MFMA16(a, b, c) __builtin_amdgcn_mfma_f32_16x16x32_bf16((a), (b), (c), 0, 0, 0)
; __device__ __forceinline__ f32x4 bf4(u32x2 w) { return (f32x4){bflo(w.x), bfhi(w.x), bflo(w.y), bfhi(w.y)}; }
; __device__ __forceinline__ void gmlp_item(int item, const bf16* Z, const bf16* gmws, const float* gmbs, bf16* CC, LAS unsigned char* lds, int tid, int wave, int lane) {
;     ...
;     f32x4 acc[4];
; #pragma unroll
;     for (int nb = 0; nb < 4; ++nb) acc[nb] = (f32x4){0.f, 0.f, 0.f, 0.f};
;     const int i = wave * 16 + fr;
; #pragma unroll
;     for (int ks = 0; ks < 4; ++ks) { const bf16x8 wf = *(const bf16x8*)(gmws + (size_t)(gi * 128 + i) * 128 + 32 * ks + 8 * g);
; #pragma unroll
;         for (int nb = 0; nb < 4; ++nb) { const bf16x8 vf = *(const LAS bf16x8*)(vt + (nb * 16 + fr) * VSTR + 32 * ks + 8 * g); acc[nb] = MFMA16(vf, wf, acc[nb]); } }
;     const float bs = gmbs[gi * 128 + i];
;     const size_t m = (size_t)cidx * 128 + i;
; #pragma unroll
;     for (int nb = 0; nb < 4; ++nb) { const int c = nb * 16 + 4 * g; const f32x4 u = bf4(*(const u32x2*)(Z + m * INCP + gi * 64 + c));
;         u32x2 w; w.x = pk2(gelu_f(u.x) * (acc[nb][0] + bs), gelu_f(u.y) * (acc[nb][1] + bs)); w.y = pk2(gelu_f(u.z) * (acc[nb][2] + bs), gelu_f(u.w) * (acc[nb][3] + bs));
;         *(u32x2*)(CC + m * D + gi * 64 + c) = w; }
	global_load_dwordx4 v[0:3], v[40:41], off
	global_load_dwordx4 v[4:7], v[40:41], off offset:64
	ds_read_b128 v[8:11], v136
	ds_read_b128 v[12:15], v136 offset:64
	ds_read_b128 v[16:19], v136 offset:4352
	ds_read_b128 v[20:23], v136 offset:4416
	s_waitcnt vmcnt(1) lgkmcnt(3)
	v_mfma_f32_16x16x32_bf16 v[8:11], v[8:11], v[0:3], 0
	ds_read_b128 v[24:27], v136 offset:8704
	ds_read_b128 v[28:31], v136 offset:8768
	ds_read_b128 v[32:35], v137
	ds_read_b128 v[36:39], v137 offset:64
	s_waitcnt lgkmcnt(5)
	v_mfma_f32_16x16x32_bf16 v[16:19], v[16:19], v[0:3], 0
	s_waitcnt vmcnt(0)
	v_mfma_f32_16x16x32_bf16 v[8:11], v[12:15], v[4:7], v[8:11]
	s_waitcnt lgkmcnt(4)
	v_mfma_f32_16x16x32_bf16 v[12:15], v[20:23], v[4:7], v[16:19]
	s_nop 3
	global_load_dwordx4 v[16:19], v[40:41], off offset:128
	s_waitcnt lgkmcnt(3)
	v_mfma_f32_16x16x32_bf16 v[24:27], v[24:27], v[0:3], 0
	s_waitcnt lgkmcnt(2)
	v_mfma_f32_16x16x32_bf16 v[20:23], v[28:31], v[4:7], v[24:27]
	global_load_dwordx4 v[28:31], v[40:41], off offset:192
	s_waitcnt lgkmcnt(1)
	v_mfma_f32_16x16x32_bf16 v[0:3], v[32:35], v[0:3], 0
	s_waitcnt lgkmcnt(0)
	v_mfma_f32_16x16x32_bf16 v[0:3], v[36:39], v[4:7], v[0:3]
	ds_read_b128 v[4:7], v136 offset:128
	ds_read_b128 v[24:27], v136 offset:192
	s_waitcnt vmcnt(1) lgkmcnt(1)
	v_mfma_f32_16x16x32_bf16 v[4:7], v[4:7], v[16:19], v[8:11]
	s_nop 2
	ds_read_b128 v[8:11], v136 offset:4480
	ds_read_b128 v[32:35], v136 offset:4544
	s_waitcnt lgkmcnt(1)
	v_mfma_f32_16x16x32_bf16 v[8:11], v[8:11], v[16:19], v[12:15]
	s_nop 2
	ds_read_b128 v[12:15], v136 offset:8832
	ds_read_b128 v[36:39], v136 offset:8896
	s_waitcnt lgkmcnt(1)
	v_mfma_f32_16x16x32_bf16 v[40:43], v[12:15], v[16:19], v[20:23]
	ds_read_b128 v[12:15], v137 offset:128
	ds_read_b128 v[44:47], v137 offset:192
	s_nop 0
	v_lshlrev_b64 v[20:21], 1, v[74:75]
	s_waitcnt lgkmcnt(1)
	v_mfma_f32_16x16x32_bf16 v[0:3], v[12:15], v[16:19], v[0:3]
	v_lshl_add_u64 v[16:17], v[64:65], 2, s[36:37]
	v_add_u32_e32 v64, s4, v107
	global_load_dword v16, v[16:17], off
	s_waitcnt vmcnt(1)
	v_mfma_f32_16x16x32_bf16 v[12:15], v[24:27], v[28:31], v[4:7]
	v_lshlrev_b64 v[18:19], 12, v[64:65]
	v_lshl_add_u64 v[18:19], s[12:13], 0, v[18:19]
	v_lshl_add_u64 v[18:19], v[18:19], 0, s[30:31]
	v_mov_b64_e32 v[4:5], s[14:15]
	v_mad_u64_u32 v[4:5], s[4:5], v64, s61, v[4:5]
	v_lshl_add_u64 v[24:25], v[4:5], 0, s[30:31]
	v_lshl_add_u64 v[26:27], v[24:25], 0, v[20:21]
	global_load_dwordx2 v[22:23], v[26:27], off
	v_mfma_f32_16x16x32_bf16 v[8:11], v[32:35], v[28:31], v[8:11]
	v_lshl_add_u64 v[24:25], v[24:25], 0, v[92:93]
	v_mfma_f32_16x16x32_bf16 v[4:7], v[36:39], v[28:31], v[40:43]
	s_waitcnt lgkmcnt(0)
	v_mfma_f32_16x16x32_bf16 v[0:3], v[44:47], v[28:31], v[0:3]
	global_load_dwordx2 v[28:29], v[26:27], off offset:32
	s_nop 0
	global_load_dwordx2 v[26:27], v[26:27], off offset:64
	s_nop 0
	global_load_dwordx2 v[24:25], v[24:25], off
	s_waitcnt vmcnt(3)
	v_lshlrev_b32_e32 v30, 16, v22
	v_mul_f32_e32 v17, 0x3d372713, v30
	v_and_b32_e32 v22, 0xffff0000, v22
	v_mul_f32_e32 v17, v17, v30
	v_mov_b32_e32 v31, v30
	v_mul_f32_e32 v32, 0x3d372713, v22
	v_fmac_f32_e32 v31, v17, v31
	v_mul_f32_e32 v32, v32, v22
	v_mov_b32_e32 v33, v22
	v_mul_f32_e32 v17, 0x3f4c422a, v31
	v_lshlrev_b32_e32 v31, 16, v23
	v_fmac_f32_e32 v33, v32, v33
	v_mul_f32_e32 v32, 0x3f4c422a, v33
	v_mul_f32_e32 v33, 0x3d372713, v31
	v_mul_f32_e32 v33, v33, v31
	v_mov_b32_e32 v34, v31
	v_fmac_f32_e32 v34, v33, v34
	v_add_f32_e32 v17, v17, v17
	v_mul_f32_e32 v33, 0x3f4c422a, v34
	v_mul_f32_e32 v17, 0x3fb8aa3b, v17
	v_add_f32_e32 v33, v33, v33
	v_exp_f32_e32 v17, v17
	v_add_f32_e32 v32, v32, v32
	v_mul_f32_e32 v33, 0x3fb8aa3b, v33
	v_exp_f32_e32 v33, v33
	v_mul_f32_e32 v32, 0x3fb8aa3b, v32
	v_exp_f32_e32 v34, v32
	v_add_f32_e32 v17, 1.0, v17
	v_rcp_f32_e32 v32, v17
	v_add_f32_e32 v17, 1.0, v33
	v_and_b32_e32 v23, 0xffff0000, v23
	v_rcp_f32_e32 v33, v17
	v_add_f32_e32 v17, 1.0, v34
	v_rcp_f32_e32 v34, v17
	v_mul_f32_e32 v17, 0x3d372713, v23
	v_mul_f32_e32 v17, v17, v23
	v_mov_b32_e32 v35, v23
	v_fmac_f32_e32 v35, v17, v35
	v_mul_f32_e32 v17, 0x3f4c422a, v35
	v_add_f32_e32 v17, v17, v17
	v_mul_f32_e32 v17, 0x3fb8aa3b, v17
	v_exp_f32_e32 v17, v17
	v_pk_fma_f32 v[32:33], v[32:33], 2.0, 1.0 op_sel_hi:[1,0,0] neg_lo:[1,0,0] neg_hi:[1,0,0]
	v_pk_mul_f32 v[30:31], v[30:31], 0.5 op_sel_hi:[1,0]
	v_pk_add_f32 v[32:33], v[32:33], 1.0 op_sel_hi:[1,0]
	v_pk_mul_f32 v[22:23], v[22:23], 0.5 op_sel_hi:[1,0]
	v_pk_mul_f32 v[30:31], v[30:31], v[32:33]
	v_mov_b32_e32 v32, v12
	v_add_f32_e32 v12, 1.0, v17
	v_rcp_f32_e32 v35, v12
	v_mov_b32_e32 v33, v14
	v_pk_add_f32 v[32:33], v[32:33], v[16:17] op_sel_hi:[1,0]
	v_mov_b32_e32 v14, v13
	v_pk_mul_f32 v[30:31], v[32:33], v[30:31]
	v_pk_fma_f32 v[32:33], v[34:35], 2.0, 1.0 op_sel_hi:[1,0,0] neg_lo:[1,0,0] neg_hi:[1,0,0]
	v_pk_add_f32 v[12:13], v[14:15], v[16:17] op_sel_hi:[1,0]
	v_pk_add_f32 v[32:33], v[32:33], 1.0 op_sel_hi:[1,0]
	v_pk_mul_f32 v[22:23], v[22:23], v[32:33]
	v_pk_mul_f32 v[12:13], v[12:13], v[22:23]
	s_nop 0
	s_nop 0
	s_nop 0
	s_nop 0
	s_nop 0
	s_nop 0
	v_cvt_pk_bf16_f32 v13, v31, v13
	v_cvt_pk_bf16_f32 v12, v30, v12
	v_lshl_add_u64 v[14:15], v[18:19], 0, v[20:21]
	global_store_dwordx2 v[14:15], v[12:13], off
	s_waitcnt vmcnt(3)
; __device__ __forceinline__ unsigned pk2(float lo, float hi) { return f2bf(lo) | (f2bf(hi) << 16); }
; __device__ __forceinline__ float gelu_f(float x) { const float y = 0.7978845608f * (x + 0.044715f * x * x * x); return 0.5f * x * (1.f + tanh_f(y)); }
; __device__ __forceinline__ f32x4 bf4(u32x2 w) { return (f32x4){bflo(w.x), bfhi(w.x), bflo(w.y), bfhi(w.y)}; }
; __device__ __forceinline__ void gmlp_item(int item, const bf16* Z, const bf16* gmws, const float* gmbs, bf16* CC, LAS unsigned char* lds, int tid, int wave, int lane) {
;     ...
; #pragma unroll
;     for (int nb = 0; nb < 4; ++nb) { const int c = nb * 16 + 4 * g; const f32x4 u = bf4(*(const u32x2*)(Z + m * INCP + gi * 64 + c));
;         u32x2 w; w.x = pk2(gelu_f(u.x) * (acc[nb][0] + bs), gelu_f(u.y) * (acc[nb][1] + bs)); w.y = pk2(gelu_f(u.z) * (acc[nb][2] + bs), gelu_f(u.w) * (acc[nb][3] + bs));
;         *(u32x2*)(CC + m * D + gi * 64 + c) = w; }
	v_lshlrev_b32_e32 v12, 16, v28
	v_mul_f32_e32 v13, 0x3d372713, v12
	v_mul_f32_e32 v13, v13, v12
	v_mov_b32_e32 v17, v12
	v_fmac_f32_e32 v17, v13, v17
	v_mul_f32_e32 v13, 0x3f4c422a, v17
	v_and_b32_e32 v20, 0xffff0000, v28
	v_add_f32_e32 v13, v13, v13
	v_mul_f32_e32 v22, 0x3d372713, v20
	v_mul_f32_e32 v13, 0x3fb8aa3b, v13
	v_mul_f32_e32 v22, v22, v20
	v_mov_b32_e32 v23, v20
	v_exp_f32_e32 v17, v13
	v_lshlrev_b32_e32 v13, 16, v29
	v_fmac_f32_e32 v23, v22, v23
	v_mul_f32_e32 v22, 0x3f4c422a, v23
	v_mul_f32_e32 v23, 0x3d372713, v13
	v_mul_f32_e32 v23, v23, v13
	v_mov_b32_e32 v28, v13
	v_fmac_f32_e32 v28, v23, v28
	v_mul_f32_e32 v23, 0x3f4c422a, v28
	v_add_f32_e32 v23, v23, v23
	v_add_f32_e32 v22, v22, v22
	v_mul_f32_e32 v23, 0x3fb8aa3b, v23
	v_exp_f32_e32 v23, v23
	v_mul_f32_e32 v22, 0x3fb8aa3b, v22
	v_exp_f32_e32 v28, v22
	v_add_f32_e32 v17, 1.0, v17
	v_rcp_f32_e32 v22, v17
	v_add_f32_e32 v17, 1.0, v23
	v_and_b32_e32 v21, 0xffff0000, v29
	v_rcp_f32_e32 v23, v17
	v_add_f32_e32 v17, 1.0, v28
	v_rcp_f32_e32 v28, v17
	v_mul_f32_e32 v17, 0x3d372713, v21
	v_mul_f32_e32 v17, v17, v21
	v_mov_b32_e32 v29, v21
	v_fmac_f32_e32 v29, v17, v29
	v_mul_f32_e32 v17, 0x3f4c422a, v29
	v_add_f32_e32 v17, v17, v17
	v_mul_f32_e32 v17, 0x3fb8aa3b, v17
	v_exp_f32_e32 v17, v17
	v_pk_fma_f32 v[22:23], v[22:23], 2.0, 1.0 op_sel_hi:[1,0,0] neg_lo:[1,0,0] neg_hi:[1,0,0]
	v_pk_mul_f32 v[12:13], v[12:13], 0.5 op_sel_hi:[1,0]
	v_pk_add_f32 v[22:23], v[22:23], 1.0 op_sel_hi:[1,0]
	v_pk_mul_f32 v[20:21], v[20:21], 0.5 op_sel_hi:[1,0]
	v_pk_mul_f32 v[12:13], v[12:13], v[22:23]
	v_mov_b32_e32 v22, v8
	v_add_f32_e32 v8, 1.0, v17
	v_rcp_f32_e32 v29, v8
	v_mov_b32_e32 v23, v10
	v_pk_add_f32 v[22:23], v[22:23], v[16:17] op_sel_hi:[1,0]
	v_mov_b32_e32 v10, v9
	v_pk_mul_f32 v[12:13], v[22:23], v[12:13]
	v_pk_fma_f32 v[22:23], v[28:29], 2.0, 1.0 op_sel_hi:[1,0,0] neg_lo:[1,0,0] neg_hi:[1,0,0]
	v_pk_add_f32 v[8:9], v[10:11], v[16:17] op_sel_hi:[1,0]
	v_pk_add_f32 v[22:23], v[22:23], 1.0 op_sel_hi:[1,0]
	v_and_b32_sdwa v10, v13, v140 dst_sel:DWORD dst_unused:UNUSED_PAD src0_sel:WORD_1 src1_sel:DWORD
	v_pk_mul_f32 v[20:21], v[20:21], v[22:23]
	v_and_b32_sdwa v11, v12, v140 dst_sel:DWORD dst_unused:UNUSED_PAD src0_sel:WORD_1 src1_sel:DWORD
	v_pk_mul_f32 v[8:9], v[8:9], v[20:21]
	v_add3_u32 v11, v12, v11, s60
	v_add3_u32 v10, v13, v10, s60
	v_and_b32_sdwa v12, v9, v140 dst_sel:DWORD dst_unused:UNUSED_PAD src0_sel:WORD_1 src1_sel:DWORD
	v_and_b32_sdwa v13, v8, v140 dst_sel:DWORD dst_unused:UNUSED_PAD src0_sel:WORD_1 src1_sel:DWORD
	v_add3_u32 v9, v9, v12, s60
	v_add3_u32 v8, v8, v13, s60
	v_and_b32_e32 v9, 0xffff0000, v9
	v_and_b32_e32 v8, 0xffff0000, v8
	v_or_b32_sdwa v9, v9, v10 dst_sel:DWORD dst_unused:UNUSED_PAD src0_sel:DWORD src1_sel:WORD_1
	v_or_b32_sdwa v8, v8, v11 dst_sel:DWORD dst_unused:UNUSED_PAD src0_sel:DWORD src1_sel:WORD_1
	global_store_dwordx2 v[14:15], v[8:9], off offset:32
	s_waitcnt vmcnt(3)
; __device__ __forceinline__ unsigned pk2(float lo, float hi) { return f2bf(lo) | (f2bf(hi) << 16); }
; __device__ __forceinline__ float gelu_f(float x) { const float y = 0.7978845608f * (x + 0.044715f * x * x * x); return 0.5f * x * (1.f + tanh_f(y)); }
; __device__ __forceinline__ f32x4 bf4(u32x2 w) { return (f32x4){bflo(w.x), bfhi(w.x), bflo(w.y), bfhi(w.y)}; }
; __device__ __forceinline__ void gmlp_item(int item, const bf16* Z, const bf16* gmws, const float* gmbs, bf16* CC, LAS unsigned char* lds, int tid, int wave, int lane) {
;     ...
; #pragma unroll
;     for (int nb = 0; nb < 4; ++nb) { const int c = nb * 16 + 4 * g; const f32x4 u = bf4(*(const u32x2*)(Z + m * INCP + gi * 64 + c));
;         u32x2 w; w.x = pk2(gelu_f(u.x) * (acc[nb][0] + bs), gelu_f(u.y) * (acc[nb][1] + bs)); w.y = pk2(gelu_f(u.z) * (acc[nb][2] + bs), gelu_f(u.w) * (acc[nb][3] + bs));
;         *(u32x2*)(CC + m * D + gi * 64 + c) = w; }
	v_lshlrev_b32_e32 v8, 16, v26
	v_mul_f32_e32 v9, 0x3d372713, v8
	v_mul_f32_e32 v9, v9, v8
	v_mov_b32_e32 v10, v8
	v_fmac_f32_e32 v10, v9, v10
	v_mul_f32_e32 v9, 0x3f4c422a, v10
	v_and_b32_e32 v10, 0xffff0000, v26
	v_add_f32_e32 v9, v9, v9
	v_mul_f32_e32 v13, 0x3d372713, v10
	v_mul_f32_e32 v9, 0x3fb8aa3b, v9
	v_mul_f32_e32 v13, v13, v10
	v_mov_b32_e32 v17, v10
	v_exp_f32_e32 v12, v9
	v_lshlrev_b32_e32 v9, 16, v27
	v_fmac_f32_e32 v17, v13, v17
	v_mul_f32_e32 v13, 0x3f4c422a, v17
	v_mul_f32_e32 v17, 0x3d372713, v9
	v_mul_f32_e32 v17, v17, v9
	v_mov_b32_e32 v20, v9
	v_fmac_f32_e32 v20, v17, v20
	v_mul_f32_e32 v17, 0x3f4c422a, v20
	v_add_f32_e32 v13, v13, v13
	v_add_f32_e32 v17, v17, v17
	v_mul_f32_e32 v17, 0x3fb8aa3b, v17
	v_mul_f32_e32 v13, 0x3fb8aa3b, v13
	v_exp_f32_e32 v17, v17
	v_exp_f32_e32 v20, v13
	v_and_b32_e32 v11, 0xffff0000, v27
	v_mov_b32_e32 v21, v11
	v_add_f32_e32 v13, 1.0, v17
	v_add_f32_e32 v17, 1.0, v20
	v_rcp_f32_e32 v20, v17
	v_mul_f32_e32 v17, 0x3d372713, v11
	v_mul_f32_e32 v17, v17, v11
	v_fmac_f32_e32 v21, v17, v21
	v_add_f32_e32 v12, 1.0, v12
	v_mul_f32_e32 v17, 0x3f4c422a, v21
	v_rcp_f32_e32 v12, v12
	v_rcp_f32_e32 v13, v13
	v_add_f32_e32 v17, v17, v17
	v_mul_f32_e32 v17, 0x3fb8aa3b, v17
	v_exp_f32_e32 v17, v17
	v_pk_fma_f32 v[12:13], v[12:13], 2.0, 1.0 op_sel_hi:[1,0,0] neg_lo:[1,0,0] neg_hi:[1,0,0]
	v_pk_mul_f32 v[8:9], v[8:9], 0.5 op_sel_hi:[1,0]
	v_pk_add_f32 v[12:13], v[12:13], 1.0 op_sel_hi:[1,0]
	v_pk_mul_f32 v[10:11], v[10:11], 0.5 op_sel_hi:[1,0]
	v_pk_mul_f32 v[8:9], v[8:9], v[12:13]
	v_mov_b32_e32 v12, v4
	v_add_f32_e32 v4, 1.0, v17
	v_rcp_f32_e32 v21, v4
	v_mov_b32_e32 v13, v6
	v_pk_add_f32 v[12:13], v[12:13], v[16:17] op_sel_hi:[1,0]
	v_mov_b32_e32 v6, v5
	v_pk_mul_f32 v[8:9], v[12:13], v[8:9]
	v_pk_fma_f32 v[12:13], v[20:21], 2.0, 1.0 op_sel_hi:[1,0,0] neg_lo:[1,0,0] neg_hi:[1,0,0]
	v_pk_add_f32 v[4:5], v[6:7], v[16:17] op_sel_hi:[1,0]
	v_pk_add_f32 v[12:13], v[12:13], 1.0 op_sel_hi:[1,0]
	v_and_b32_sdwa v6, v9, v140 dst_sel:DWORD dst_unused:UNUSED_PAD src0_sel:WORD_1 src1_sel:DWORD
	v_pk_mul_f32 v[10:11], v[10:11], v[12:13]
	v_and_b32_sdwa v7, v8, v140 dst_sel:DWORD dst_unused:UNUSED_PAD src0_sel:WORD_1 src1_sel:DWORD
	v_pk_mul_f32 v[4:5], v[4:5], v[10:11]
	v_add3_u32 v7, v8, v7, s60
	v_add3_u32 v6, v9, v6, s60
	v_and_b32_sdwa v8, v5, v140 dst_sel:DWORD dst_unused:UNUSED_PAD src0_sel:WORD_1 src1_sel:DWORD
	v_and_b32_sdwa v9, v4, v140 dst_sel:DWORD dst_unused:UNUSED_PAD src0_sel:WORD_1 src1_sel:DWORD
	v_add3_u32 v5, v5, v8, s60
	v_add3_u32 v4, v4, v9, s60
	v_and_b32_e32 v5, 0xffff0000, v5
	v_and_b32_e32 v4, 0xffff0000, v4
	v_or_b32_sdwa v5, v5, v6 dst_sel:DWORD dst_unused:UNUSED_PAD src0_sel:DWORD src1_sel:WORD_1
	v_or_b32_sdwa v4, v4, v7 dst_sel:DWORD dst_unused:UNUSED_PAD src0_sel:DWORD src1_sel:WORD_1
	global_store_dwordx2 v[14:15], v[4:5], off offset:64
	s_waitcnt vmcnt(3)
	v_lshlrev_b32_e32 v4, 16, v24
	v_mul_f32_e32 v5, 0x3d372713, v4
	v_mul_f32_e32 v5, v5, v4
	v_mov_b32_e32 v6, v4
	v_fmac_f32_e32 v6, v5, v6
	v_mul_f32_e32 v5, 0x3f4c422a, v6
	v_and_b32_e32 v6, 0xffff0000, v24
	v_add_f32_e32 v5, v5, v5
	v_mul_f32_e32 v9, 0x3d372713, v6
	v_mul_f32_e32 v5, 0x3fb8aa3b, v5
	v_mul_f32_e32 v9, v9, v6
	v_mov_b32_e32 v10, v6
	v_exp_f32_e32 v8, v5
	v_lshlrev_b32_e32 v5, 16, v25
	v_fmac_f32_e32 v10, v9, v10
	v_mul_f32_e32 v9, 0x3f4c422a, v10
	v_mul_f32_e32 v10, 0x3d372713, v5
	v_mul_f32_e32 v10, v10, v5
	v_mov_b32_e32 v11, v5
	v_fmac_f32_e32 v11, v10, v11
	v_mul_f32_e32 v10, 0x3f4c422a, v11
	v_add_f32_e32 v9, v9, v9
	v_add_f32_e32 v10, v10, v10
	v_mul_f32_e32 v10, 0x3fb8aa3b, v10
	v_mul_f32_e32 v9, 0x3fb8aa3b, v9
	v_exp_f32_e32 v10, v10
	v_exp_f32_e32 v11, v9
	v_and_b32_e32 v7, 0xffff0000, v25
	v_mov_b32_e32 v12, v7
	v_add_f32_e32 v9, 1.0, v10
	v_add_f32_e32 v10, 1.0, v11
	v_mul_f32_e32 v11, 0x3d372713, v7
	v_mul_f32_e32 v11, v11, v7
	v_fmac_f32_e32 v12, v11, v12
	v_add_f32_e32 v8, 1.0, v8
	v_mul_f32_e32 v11, 0x3f4c422a, v12
	v_rcp_f32_e32 v8, v8
	v_rcp_f32_e32 v9, v9
	v_add_f32_e32 v11, v11, v11
	v_mul_f32_e32 v11, 0x3fb8aa3b, v11
	v_exp_f32_e32 v11, v11
	v_pk_fma_f32 v[8:9], v[8:9], 2.0, 1.0 op_sel_hi:[1,0,0] neg_lo:[1,0,0] neg_hi:[1,0,0]
	v_pk_mul_f32 v[4:5], v[4:5], 0.5 op_sel_hi:[1,0]
	v_pk_add_f32 v[8:9], v[8:9], 1.0 op_sel_hi:[1,0]
	v_rcp_f32_e32 v10, v10
	v_pk_mul_f32 v[4:5], v[4:5], v[8:9]
	v_mov_b32_e32 v8, v0
	v_add_f32_e32 v0, 1.0, v11
	v_rcp_f32_e32 v11, v0
	v_mov_b32_e32 v9, v2
	v_pk_add_f32 v[8:9], v[16:17], v[8:9] op_sel_hi:[0,1]
	v_pk_mul_f32 v[4:5], v[8:9], v[4:5]
	v_pk_fma_f32 v[8:9], v[10:11], 2.0, 1.0 op_sel_hi:[1,0,0] neg_lo:[1,0,0] neg_hi:[1,0,0]
	v_pk_mul_f32 v[6:7], v[6:7], 0.5 op_sel_hi:[1,0]
	v_pk_add_f32 v[8:9], v[8:9], 1.0 op_sel_hi:[1,0]
	v_mov_b32_e32 v2, v1
	v_pk_mul_f32 v[6:7], v[6:7], v[8:9]
	v_pk_add_f32 v[0:1], v[16:17], v[2:3] op_sel_hi:[0,1]
	v_pk_mul_f32 v[0:1], v[0:1], v[6:7]
	v_and_b32_sdwa v2, v5, v140 dst_sel:DWORD dst_unused:UNUSED_PAD src0_sel:WORD_1 src1_sel:DWORD
	v_and_b32_sdwa v3, v4, v140 dst_sel:DWORD dst_unused:UNUSED_PAD src0_sel:WORD_1 src1_sel:DWORD
	v_add3_u32 v3, v4, v3, s60
	v_add3_u32 v2, v5, v2, s60
	v_and_b32_sdwa v4, v1, v140 dst_sel:DWORD dst_unused:UNUSED_PAD src0_sel:WORD_1 src1_sel:DWORD
	v_and_b32_sdwa v5, v0, v140 dst_sel:DWORD dst_unused:UNUSED_PAD src0_sel:WORD_1 src1_sel:DWORD
	v_add3_u32 v1, v1, v4, s60
	v_add3_u32 v0, v0, v5, s60
	v_and_b32_e32 v1, 0xffff0000, v1
	v_and_b32_e32 v0, 0xffff0000, v0
	v_or_b32_sdwa v1, v1, v2 dst_sel:DWORD dst_unused:UNUSED_PAD src0_sel:DWORD src1_sel:WORD_1
	v_or_b32_sdwa v0, v0, v3 dst_sel:DWORD dst_unused:UNUSED_PAD src0_sel:DWORD src1_sel:WORD_1
	v_lshl_add_u64 v[2:3], v[18:19], 0, v[92:93]
	global_store_dwordx2 v[2:3], v[0:1], off
	s_cbranch_execnz .LBB0_1469
	s_branch .LBB0_1473

; #define LAS __attribute__((address_space(3)))
; __device__ __forceinline__ unsigned pk2(float lo, float hi) { return f2bf(lo) | (f2bf(hi) << 16); }
; #define MFMA16(a, b, c) __builtin_amdgcn_mfma_f32_16x16x32_bf16((a), (b), (c), 0, 0, 0)
; __device__ __forceinline__ void na_item(int item, const bf16* Z, const float* rpb, bf16* CC, LAS unsigned char* lds, int tid, int wave, int lane) {
;     ...
;             bf16x8 pf[2];
; #pragma unroll
;             for (int ks = 0; ks < 2; ++ks) { u32x4 w; w.x = pk2(sc[2 * ks][0], sc[2 * ks][1]); w.y = pk2(sc[2 * ks][2], sc[2 * ks][3]); w.z = pk2(sc[2 * ks + 1][0], sc[2 * ks + 1][1]); w.w = pk2(sc[2 * ks + 1][2], sc[2 * ks + 1][3]);
;                 pf[ks] = __builtin_bit_cast(bf16x8, w); }
; #pragma unroll
;             for (int nb = 0; nb < 4; ++nb) oacc[nb] = oacc[nb] * alpha;
; #pragma unroll
;             for (int ks = 0; ks < 2; ++ks) {
;                 const bool kson = !loc || (2 * ks + 1 >= nlo && 2 * ks <= nhi);
;                 if (kson) {
; #pragma unroll
;                     for (int nb = 0; nb < 4; ++nb) { const LAS bf16* vp = Vt + (nb * 16 + fr) * KSTR + 32 * ks + 4 * g;
;                         const u32x2 lo = *(const LAS u32x2*)vp, hi = *(const LAS u32x2*)(vp + 16);
;                         u32x4 w; w.x = lo.x; w.y = lo.y; w.z = hi.x; w.w = hi.y;
;                         oacc[nb] = MFMA16(__builtin_bit_cast(bf16x8, w), pf[ks], oacc[nb]); }
;                 }
;             }
.LBB0_1544:
	v_add_u32_e32 v95, v130, v132
	v_add_u32_e32 v145, v130, v133
	s_andn2_b64 vcc, exec, s[46:47]
	v_add_u32_e32 v144, 0x2000, v95
	v_add_u32_e32 v143, 0x2800, v95
	v_add_u32_e32 v103, 0x3000, v95
	v_add_u32_e32 v95, 0x2000, v145
	s_cbranch_vccnz .LBB0_1546
	v_bfe_u32 v145, v0, 16, 1
	v_add3_u32 v0, v0, v145, s60
	v_bfe_u32 v145, v1, 16, 1
	v_lshrrev_b32_e32 v0, 16, v0
	v_add3_u32 v1, v1, v145, s60
	v_and_or_b32 v0, v1, s58, v0
	v_cvt_pk_bf16_f32 v1, v2, v3
	v_cvt_pk_bf16_f32 v2, v4, v5
	s_nop 0
	s_nop 0
	v_cvt_pk_bf16_f32 v3, v6, v7
	ds_read2_b64 v[4:7], v143 offset0:160 offset1:164
	ds_read2_b64 v[146:149], v144 offset0:128 offset1:132
	s_waitcnt lgkmcnt(1)
	v_mfma_f32_16x16x32_bf16 v[40:43], v[4:7], v[0:3], v[40:43]
	ds_read2_b64 v[4:7], v103 offset0:192 offset1:196
	s_waitcnt lgkmcnt(0)
	v_mfma_f32_16x16x32_bf16 v[28:31], v[4:7], v[0:3], v[28:31]
	ds_read2_b64 v[4:7], v95 offset0:128 offset1:132
	v_mfma_f32_16x16x32_bf16 v[44:47], v[146:149], v[0:3], v[44:47]
	s_waitcnt lgkmcnt(0)
	v_mfma_f32_16x16x32_bf16 v[24:27], v[4:7], v[0:3], v[24:27]
.LBB0_1546:
	s_andn2_b64 vcc, exec, s[48:49]
	s_cbranch_vccnz .LBB0_1548
	s_nop 0
	s_nop 0
	s_nop 0
	s_nop 0
	s_nop 0
	v_cvt_pk_bf16_f32 v0, v8, v9
	ds_read2_b64 v[4:7], v144 offset0:136 offset1:140
	v_cvt_pk_bf16_f32 v1, v10, v11
	v_cvt_pk_bf16_f32 v2, v12, v13
	v_bfe_u32 v3, v14, 16, 1
	v_add3_u32 v3, v14, v3, s60
	v_bfe_u32 v8, v15, 16, 1
	v_lshrrev_b32_e32 v3, 16, v3
	v_add3_u32 v8, v15, v8, s60
	v_and_or_b32 v3, v8, s58, v3
	s_waitcnt lgkmcnt(0)
	s_nop 0
	v_mfma_f32_16x16x32_bf16 v[44:47], v[4:7], v[0:3], v[44:47]
	ds_read2_b64 v[4:7], v143 offset0:168 offset1:172
	s_waitcnt lgkmcnt(0)
	v_mfma_f32_16x16x32_bf16 v[40:43], v[4:7], v[0:3], v[40:43]
	ds_read2_b64 v[4:7], v103 offset0:200 offset1:204
	s_waitcnt lgkmcnt(0)
	v_mfma_f32_16x16x32_bf16 v[28:31], v[4:7], v[0:3], v[28:31]
	ds_read2_b64 v[4:7], v95 offset0:136 offset1:140
	s_waitcnt lgkmcnt(0)
	v_mfma_f32_16x16x32_bf16 v[24:27], v[4:7], v[0:3], v[24:27]

; #define LAS __attribute__((address_space(3)))
; #define LDS_WAIT() asm volatile("s_waitcnt lgkmcnt(0)" ::: "memory")
; __device__ __forceinline__ void transpose_item(const float* W, int K, int N, bf16* WT, int row_off, LAS float* scr, int item, int lane) {
;     const int nblk = N / 32, kb = item / nblk, nb = item % nblk, k0 = 64 * kb, n0 = 32 * nb;
; #pragma unroll 8
;     for (int i = 0; i < 32; ++i) { const int kk = 2 * i + (lane >> 5); scr[kk * 33 + (lane & 31)] = W[(size_t)(k0 + kk) * N + n0 + (lane & 31)]; }
;     LDS_WAIT(); asm volatile("" ::: "memory");
.LBB0_1561:
	s_lshl_b32 s13, s0, 1
	s_lshl_b32 s14, s8, 1
	v_or_b32_e32 v4, s14, v20
	s_add_i32 s2, s13, 4
	s_add_i32 s20, s14, 4
	v_mov_b32_e32 v29, v5
	s_add_i32 s22, s14, 8
	v_lshlrev_b64 v[42:43], 13, v[4:5]
	v_or_b32_e32 v28, s2, v3
	v_or_b32_e32 v4, s20, v20
	v_mov_b32_e32 v27, v5
	v_or_b32_e32 v26, s13, v3
	s_add_i32 s28, s14, 12
	v_lshlrev_b64 v[28:29], 13, v[28:29]
	v_lshlrev_b64 v[44:45], 13, v[4:5]
	v_or_b32_e32 v4, s22, v20
	s_add_i32 s21, s13, 8
	s_add_i32 s23, s13, 12
	s_add_i32 s30, s14, 16
	v_lshlrev_b64 v[26:27], 13, v[26:27]
	v_lshl_add_u64 v[42:43], v[18:19], 0, v[42:43]
	v_lshl_add_u64 v[28:29], v[18:19], 0, v[28:29]
	v_lshlrev_b64 v[46:47], 13, v[4:5]
	v_or_b32_e32 v4, s28, v20
	v_mov_b32_e32 v31, v5
	s_waitcnt vmcnt(5)
	v_mov_b32_e32 v33, v5
	s_add_i32 s33, s14, 20
	v_or_b32_e32 v30, s21, v3
	v_or_b32_e32 v32, s23, v3
	v_lshl_add_u64 v[26:27], v[18:19], 0, v[26:27]
	v_lshl_add_u64 v[44:45], v[18:19], 0, v[44:45]
	global_load_dword v58, v[42:43], off
	global_load_dword v59, v[26:27], off
	global_load_dword v60, v[44:45], off
	global_load_dword v61, v[28:29], off
	v_lshlrev_b64 v[28:29], 13, v[4:5]
	v_or_b32_e32 v4, s30, v20
	s_add_i32 s29, s13, 16
	s_add_i32 s31, s13, 20
	s_add_i32 s35, s14, 24
	v_lshlrev_b64 v[30:31], 13, v[30:31]
	v_lshlrev_b64 v[32:33], 13, v[32:33]
	v_lshl_add_u64 v[26:27], v[18:19], 0, v[46:47]
	v_lshl_add_u64 v[28:29], v[18:19], 0, v[28:29]
	v_lshlrev_b64 v[42:43], 13, v[4:5]
	v_or_b32_e32 v4, s33, v20
	v_mov_b32_e32 v35, v5
	s_waitcnt vmcnt(8)
	v_mov_b32_e32 v37, v5
	s_add_i32 s34, s13, 24
	s_add_i32 s36, s13, 28
	s_add_i32 s37, s14, 28
	v_or_b32_e32 v34, s29, v3
	v_or_b32_e32 v36, s31, v3
	v_lshl_add_u64 v[30:31], v[18:19], 0, v[30:31]
	v_lshl_add_u64 v[32:33], v[18:19], 0, v[32:33]
	global_load_dword v62, v[26:27], off
	global_load_dword v63, v[30:31], off
	global_load_dword v64, v[28:29], off
	global_load_dword v65, v[32:33], off
	v_lshlrev_b64 v[28:29], 13, v[4:5]
	v_or_b32_e32 v4, s35, v20
	v_mov_b32_e32 v39, v5
	v_mov_b32_e32 v41, v5
	v_or_b32_e32 v38, s34, v3
	v_or_b32_e32 v40, s36, v3
	v_lshlrev_b64 v[34:35], 13, v[34:35]
	v_lshlrev_b64 v[36:37], 13, v[36:37]
	v_lshl_add_u64 v[26:27], v[18:19], 0, v[42:43]
	v_lshl_add_u64 v[28:29], v[18:19], 0, v[28:29]
	v_lshlrev_b64 v[30:31], 13, v[4:5]
	v_or_b32_e32 v4, s37, v20
	v_lshlrev_b64 v[38:39], 13, v[38:39]
	v_lshlrev_b64 v[40:41], 13, v[40:41]
	v_lshl_add_u64 v[34:35], v[18:19], 0, v[34:35]
	v_lshl_add_u64 v[36:37], v[18:19], 0, v[36:37]
	global_load_dword v66, v[26:27], off
	global_load_dword v67, v[34:35], off
	global_load_dword v68, v[28:29], off
	global_load_dword v69, v[36:37], off
	v_lshl_add_u64 v[26:27], v[18:19], 0, v[30:31]
	v_lshlrev_b64 v[28:29], 13, v[4:5]
	v_lshl_add_u64 v[38:39], v[18:19], 0, v[38:39]
	v_lshl_add_u64 v[40:41], v[18:19], 0, v[40:41]
	v_lshl_add_u64 v[28:29], v[18:19], 0, v[28:29]
	global_load_dword v4, v[26:27], off
	global_load_dword v70, v[38:39], off
	global_load_dword v71, v[28:29], off
	global_load_dword v72, v[40:41], off
	v_or_b32_e32 v28, s13, v1
	v_or_b32_e32 v26, s14, v0
	s_add_i32 s8, s8, 16
	s_add_i32 s0, s0, 16
	s_add_i32 s9, s9, -16
	v_mad_u64_u32 v[26:27], s[14:15], v26, s10, v[2:3]
	v_mad_u64_u32 v[28:29], s[14:15], v28, s10, v[2:3]
	v_or_b32_e32 v27, s2, v1
	v_or_b32_e32 v29, s20, v0
	v_or_b32_e32 v36, s21, v1
	v_or_b32_e32 v34, s22, v0
	v_or_b32_e32 v40, s23, v1
	v_or_b32_e32 v38, s28, v0
	v_or_b32_e32 v44, s29, v1
	v_or_b32_e32 v42, s30, v0
	v_or_b32_e32 v48, s31, v1
	v_or_b32_e32 v46, s33, v0
	v_or_b32_e32 v52, s34, v1
	v_or_b32_e32 v50, s35, v0
	v_or_b32_e32 v56, s36, v1
	v_or_b32_e32 v54, s37, v0
	s_cmp_lg_u32 s9, 0
	v_mad_u64_u32 v[30:31], s[14:15], v29, s10, v[2:3]
	v_mad_u64_u32 v[32:33], s[14:15], v27, s10, v[2:3]
	v_mad_u64_u32 v[34:35], s[14:15], v34, s10, v[2:3]
	v_mad_u64_u32 v[36:37], s[14:15], v36, s10, v[2:3]
	v_mad_u64_u32 v[38:39], s[14:15], v38, s10, v[2:3]
	v_mad_u64_u32 v[40:41], s[14:15], v40, s10, v[2:3]
	v_mad_u64_u32 v[42:43], s[14:15], v42, s10, v[2:3]
	v_mad_u64_u32 v[44:45], s[14:15], v44, s10, v[2:3]
	v_mad_u64_u32 v[46:47], s[14:15], v46, s10, v[2:3]
	v_mad_u64_u32 v[48:49], s[14:15], v48, s10, v[2:3]
	v_mad_u64_u32 v[50:51], s[14:15], v50, s10, v[2:3]
	v_mad_u64_u32 v[52:53], s[14:15], v52, s10, v[2:3]
	v_mad_u64_u32 v[54:55], s[14:15], v54, s10, v[2:3]
	v_mad_u64_u32 v[56:57], s[14:15], v56, s10, v[2:3]
	s_waitcnt vmcnt(15)
	ds_write_b32 v26, v58
	s_waitcnt vmcnt(14)
	ds_write_b32 v28, v59
	s_waitcnt vmcnt(13)
	ds_write_b32 v30, v60
	s_waitcnt vmcnt(12)
	ds_write_b32 v32, v61
	s_waitcnt vmcnt(11)
	ds_write_b32 v34, v62
	s_waitcnt vmcnt(10)
	ds_write_b32 v36, v63
	s_waitcnt vmcnt(9)
	ds_write_b32 v38, v64
	s_waitcnt vmcnt(8)
	ds_write_b32 v40, v65
	s_waitcnt vmcnt(7)
	ds_write_b32 v42, v66
	s_waitcnt vmcnt(6)
	ds_write_b32 v44, v67
	s_waitcnt vmcnt(5)
	ds_write_b32 v46, v68
	s_waitcnt vmcnt(4)
	ds_write_b32 v48, v69
	s_waitcnt vmcnt(3)
	ds_write_b32 v50, v4
	s_waitcnt vmcnt(2)
	ds_write_b32 v52, v70
	s_waitcnt vmcnt(1)
	ds_write_b32 v54, v71
	s_waitcnt vmcnt(0)
	ds_write_b32 v56, v72
	s_cbranch_scc1 .LBB0_1561
; #define LAS __attribute__((address_space(3)))
; #define LDS_WAIT() asm volatile("s_waitcnt lgkmcnt(0)" ::: "memory")
; __device__ __forceinline__ unsigned pk2(float lo, float hi) { return f2bf(lo) | (f2bf(hi) << 16); }
; __device__ __forceinline__ void transpose_item(const float* W, int K, int N, bf16* WT, int row_off, LAS float* scr, int item, int lane) {
;     ...
;     const int c = lane & 7;
; #pragma unroll
;     for (int j = 0; j < 4; ++j) { const int n = (lane >> 3) + 8 * j; const LAS float* s = scr + (8 * c) * 33 + n;
;         u32x4 o; o.x = pk2(s[0 * 33], s[1 * 33]); o.y = pk2(s[2 * 33], s[3 * 33]); o.z = pk2(s[4 * 33], s[5 * 33]); o.w = pk2(s[6 * 33], s[7 * 33]);
;         *(u32x4*)(WT + (size_t)(row_off + n0 + n) * K + k0 + 8 * c) = o; }
;     LDS_WAIT(); asm volatile("" ::: "memory");
	s_waitcnt lgkmcnt(0)
	ds_read2_b32 v[18:19], v22 offset1:8
	ds_read2_b32 v[32:33], v22 offset0:33 offset1:41
	ds_read2_b32 v[34:35], v22 offset0:66 offset1:74
	ds_read2_b32 v[36:37], v22 offset0:99 offset1:107
	ds_read2_b32 v[38:39], v22 offset0:132 offset1:140
	ds_read2_b32 v[40:41], v22 offset0:165 offset1:173
	s_waitcnt lgkmcnt(5)
	s_waitcnt lgkmcnt(4)
	v_cvt_pk_bf16_f32 v26, v18, v32
	s_waitcnt lgkmcnt(3)
	s_waitcnt lgkmcnt(2)
	ds_read2_b32 v[42:43], v22 offset0:198 offset1:206
	ds_read2_b32 v[44:45], v22 offset0:231 offset1:239
	v_cvt_pk_bf16_f32 v27, v34, v36
	s_waitcnt lgkmcnt(3)
	s_waitcnt lgkmcnt(2)
	v_cvt_pk_bf16_f32 v28, v38, v40
	s_waitcnt lgkmcnt(1)
	s_waitcnt lgkmcnt(0)
	s_nop 0
	s_nop 0
	s_nop 0
	s_lshl_b32 s0, s5, 1
	v_cvt_pk_bf16_f32 v29, v42, v44
	v_or_b32_e32 v3, s4, v21
	v_lshl_add_u64 v[30:31], v[6:7], 0, s[0:1]
	v_lshlrev_b32_e32 v4, 14, v3
	v_bfe_u32 v3, v19, 16, 1
	v_lshl_add_u64 v[46:47], v[30:31], 0, v[4:5]
	v_add3_u32 v3, v19, v3, s11
	v_bfe_u32 v4, v33, 16, 1
	v_lshrrev_b32_e32 v3, 16, v3
	v_add3_u32 v4, v33, v4, s11
	global_store_dwordx4 v[46:47], v[26:29], off
	ds_read2_b32 v[18:19], v22 offset0:16 offset1:24
	s_nop 0
	v_and_or_b32 v26, v4, s12, v3
	s_nop 0
	s_nop 0
	s_nop 0
	s_nop 0
	s_nop 0
	v_cvt_pk_bf16_f32 v27, v35, v37
	v_cvt_pk_bf16_f32 v28, v39, v41
	s_nop 0
	s_nop 0
	v_cvt_pk_bf16_f32 v29, v43, v45
	v_or_b32_e32 v3, s4, v23
	v_lshlrev_b32_e32 v4, 14, v3
	v_lshl_add_u64 v[32:33], v[30:31], 0, v[4:5]
	global_store_dwordx4 v[32:33], v[26:29], off
	ds_read2_b32 v[32:33], v22 offset0:49 offset1:57
	ds_read2_b32 v[34:35], v22 offset0:82 offset1:90
	ds_read2_b32 v[36:37], v22 offset0:115 offset1:123
	s_waitcnt lgkmcnt(3)
	s_nop 0
	s_nop 0
	s_waitcnt lgkmcnt(2)
	ds_read2_b32 v[38:39], v22 offset0:148 offset1:156
	ds_read2_b32 v[40:41], v22 offset0:181 offset1:189
	v_cvt_pk_bf16_f32 v26, v18, v32
	s_waitcnt lgkmcnt(3)
	s_waitcnt lgkmcnt(2)
	ds_read2_b32 v[42:43], v22 offset0:214 offset1:222
	ds_read2_b32 v[44:45], v22 offset0:247 offset1:255
	v_cvt_pk_bf16_f32 v27, v34, v36
	s_waitcnt lgkmcnt(3)
	s_waitcnt lgkmcnt(2)
	v_cvt_pk_bf16_f32 v28, v38, v40
	s_waitcnt lgkmcnt(1)
	s_waitcnt lgkmcnt(0)
	v_cvt_pk_bf16_f32 v29, v42, v44
	v_or_b32_e32 v3, s4, v24
	v_lshlrev_b32_e32 v4, 14, v3
	s_nop 0
	v_lshl_add_u64 v[46:47], v[30:31], 0, v[4:5]
	s_nop 0
	s_nop 0
	s_nop 0
	s_nop 0
	global_store_dwordx4 v[46:47], v[26:29], off
	s_nop 1
	v_cvt_pk_bf16_f32 v26, v19, v33
	s_nop 0
	s_nop 0
	s_nop 0
	s_nop 0
	s_nop 0
	v_cvt_pk_bf16_f32 v27, v35, v37
	v_cvt_pk_bf16_f32 v28, v39, v41
	s_nop 0
	s_nop 0
	v_cvt_pk_bf16_f32 v29, v43, v45
	v_or_b32_e32 v3, s4, v25
	v_lshlrev_b32_e32 v4, 14, v3
	v_lshl_add_u64 v[18:19], v[30:31], 0, v[4:5]
	global_store_dwordx4 v[18:19], v[26:29], off
	s_waitcnt lgkmcnt(0)
	s_mov_b64 s[4:5], 0

; #define LAS __attribute__((address_space(3)))
; #define LDS_WAIT() asm volatile("s_waitcnt lgkmcnt(0)" ::: "memory")
; __device__ __forceinline__ void transpose_item(const float* W, int K, int N, bf16* WT, int row_off, LAS float* scr, int item, int lane) {
;     const int nblk = N / 32, kb = item / nblk, nb = item % nblk, k0 = 64 * kb, n0 = 32 * nb;
; #pragma unroll 8
;     for (int i = 0; i < 32; ++i) { const int kk = 2 * i + (lane >> 5); scr[kk * 33 + (lane & 31)] = W[(size_t)(k0 + kk) * N + n0 + (lane & 31)]; }
;     LDS_WAIT(); asm volatile("" ::: "memory");
.LBB0_1565:
	s_lshl_b32 s13, s0, 1
	s_lshl_b32 s14, s8, 1
	v_or_b32_e32 v4, s14, v20
	s_add_i32 s2, s13, 4
	s_add_i32 s20, s14, 4
	v_mov_b32_e32 v29, v5
	s_add_i32 s22, s14, 8
	v_lshlrev_b64 v[42:43], 15, v[4:5]
	v_or_b32_e32 v28, s2, v3
	v_or_b32_e32 v4, s20, v20
	v_mov_b32_e32 v27, v5
	v_or_b32_e32 v26, s13, v3
	s_add_i32 s28, s14, 12
	v_lshlrev_b64 v[28:29], 15, v[28:29]
	v_lshlrev_b64 v[44:45], 15, v[4:5]
	v_or_b32_e32 v4, s22, v20
	s_add_i32 s21, s13, 8
	s_add_i32 s23, s13, 12
	s_add_i32 s30, s14, 16
	v_lshlrev_b64 v[26:27], 15, v[26:27]
	v_lshl_add_u64 v[42:43], v[18:19], 0, v[42:43]
	v_lshl_add_u64 v[28:29], v[18:19], 0, v[28:29]
	v_lshlrev_b64 v[46:47], 15, v[4:5]
	v_or_b32_e32 v4, s28, v20
	v_mov_b32_e32 v31, v5
	s_waitcnt vmcnt(5)
	v_mov_b32_e32 v33, v5
	s_add_i32 s33, s14, 20
	v_or_b32_e32 v30, s21, v3
	v_or_b32_e32 v32, s23, v3
	v_lshl_add_u64 v[26:27], v[18:19], 0, v[26:27]
	v_lshl_add_u64 v[44:45], v[18:19], 0, v[44:45]
	global_load_dword v58, v[42:43], off
	global_load_dword v59, v[26:27], off
	global_load_dword v60, v[44:45], off
	global_load_dword v61, v[28:29], off
	v_lshlrev_b64 v[28:29], 15, v[4:5]
	v_or_b32_e32 v4, s30, v20
	s_add_i32 s29, s13, 16
	s_add_i32 s31, s13, 20
	s_add_i32 s35, s14, 24
	v_lshlrev_b64 v[30:31], 15, v[30:31]
	v_lshlrev_b64 v[32:33], 15, v[32:33]
	v_lshl_add_u64 v[26:27], v[18:19], 0, v[46:47]
	v_lshl_add_u64 v[28:29], v[18:19], 0, v[28:29]
	v_lshlrev_b64 v[42:43], 15, v[4:5]
	v_or_b32_e32 v4, s33, v20
	v_mov_b32_e32 v35, v5
	s_waitcnt vmcnt(8)
	v_mov_b32_e32 v37, v5
	s_add_i32 s34, s13, 24
	s_add_i32 s36, s13, 28
	s_add_i32 s37, s14, 28
	v_or_b32_e32 v34, s29, v3
	v_or_b32_e32 v36, s31, v3
	v_lshl_add_u64 v[30:31], v[18:19], 0, v[30:31]
	v_lshl_add_u64 v[32:33], v[18:19], 0, v[32:33]
	global_load_dword v62, v[26:27], off
	global_load_dword v63, v[30:31], off
	global_load_dword v64, v[28:29], off
	global_load_dword v65, v[32:33], off
	v_lshlrev_b64 v[28:29], 15, v[4:5]
	v_or_b32_e32 v4, s35, v20
	v_mov_b32_e32 v39, v5
	v_mov_b32_e32 v41, v5
	v_or_b32_e32 v38, s34, v3
	v_or_b32_e32 v40, s36, v3
	v_lshlrev_b64 v[34:35], 15, v[34:35]
	v_lshlrev_b64 v[36:37], 15, v[36:37]
	v_lshl_add_u64 v[26:27], v[18:19], 0, v[42:43]
	v_lshl_add_u64 v[28:29], v[18:19], 0, v[28:29]
	v_lshlrev_b64 v[30:31], 15, v[4:5]
	v_or_b32_e32 v4, s37, v20
	v_lshlrev_b64 v[38:39], 15, v[38:39]
	v_lshlrev_b64 v[40:41], 15, v[40:41]
	v_lshl_add_u64 v[34:35], v[18:19], 0, v[34:35]
	v_lshl_add_u64 v[36:37], v[18:19], 0, v[36:37]
	global_load_dword v66, v[26:27], off
	global_load_dword v67, v[34:35], off
	global_load_dword v68, v[28:29], off
	global_load_dword v69, v[36:37], off
	v_lshl_add_u64 v[26:27], v[18:19], 0, v[30:31]
	v_lshlrev_b64 v[28:29], 15, v[4:5]
	v_lshl_add_u64 v[38:39], v[18:19], 0, v[38:39]
	v_lshl_add_u64 v[40:41], v[18:19], 0, v[40:41]
	v_lshl_add_u64 v[28:29], v[18:19], 0, v[28:29]
	global_load_dword v4, v[26:27], off
	global_load_dword v70, v[38:39], off
	global_load_dword v71, v[28:29], off
	global_load_dword v72, v[40:41], off
	v_or_b32_e32 v28, s13, v1
	v_or_b32_e32 v26, s14, v0
	s_add_i32 s8, s8, 16
	s_add_i32 s0, s0, 16
	s_add_i32 s9, s9, -16
	v_mad_u64_u32 v[26:27], s[14:15], v26, s10, v[2:3]
	v_mad_u64_u32 v[28:29], s[14:15], v28, s10, v[2:3]
	v_or_b32_e32 v27, s2, v1
	v_or_b32_e32 v29, s20, v0
	v_or_b32_e32 v36, s21, v1
	v_or_b32_e32 v34, s22, v0
	v_or_b32_e32 v40, s23, v1
	v_or_b32_e32 v38, s28, v0
	v_or_b32_e32 v44, s29, v1
	v_or_b32_e32 v42, s30, v0
	v_or_b32_e32 v48, s31, v1
	v_or_b32_e32 v46, s33, v0
	v_or_b32_e32 v52, s34, v1
	v_or_b32_e32 v50, s35, v0
	v_or_b32_e32 v56, s36, v1
	v_or_b32_e32 v54, s37, v0
	s_cmp_lg_u32 s9, 0
	v_mad_u64_u32 v[30:31], s[14:15], v29, s10, v[2:3]
	v_mad_u64_u32 v[32:33], s[14:15], v27, s10, v[2:3]
	v_mad_u64_u32 v[34:35], s[14:15], v34, s10, v[2:3]
	v_mad_u64_u32 v[36:37], s[14:15], v36, s10, v[2:3]
	v_mad_u64_u32 v[38:39], s[14:15], v38, s10, v[2:3]
	v_mad_u64_u32 v[40:41], s[14:15], v40, s10, v[2:3]
	v_mad_u64_u32 v[42:43], s[14:15], v42, s10, v[2:3]
	v_mad_u64_u32 v[44:45], s[14:15], v44, s10, v[2:3]
	v_mad_u64_u32 v[46:47], s[14:15], v46, s10, v[2:3]
	v_mad_u64_u32 v[48:49], s[14:15], v48, s10, v[2:3]
	v_mad_u64_u32 v[50:51], s[14:15], v50, s10, v[2:3]
	v_mad_u64_u32 v[52:53], s[14:15], v52, s10, v[2:3]
	v_mad_u64_u32 v[54:55], s[14:15], v54, s10, v[2:3]
	v_mad_u64_u32 v[56:57], s[14:15], v56, s10, v[2:3]
	s_waitcnt vmcnt(15)
	ds_write_b32 v26, v58
	s_waitcnt vmcnt(14)
	ds_write_b32 v28, v59
	s_waitcnt vmcnt(13)
	ds_write_b32 v30, v60
	s_waitcnt vmcnt(12)
	ds_write_b32 v32, v61
	s_waitcnt vmcnt(11)
	ds_write_b32 v34, v62
	s_waitcnt vmcnt(10)
	ds_write_b32 v36, v63
	s_waitcnt vmcnt(9)
	ds_write_b32 v38, v64
	s_waitcnt vmcnt(8)
	ds_write_b32 v40, v65
	s_waitcnt vmcnt(7)
	ds_write_b32 v42, v66
	s_waitcnt vmcnt(6)
	ds_write_b32 v44, v67
	s_waitcnt vmcnt(5)
	ds_write_b32 v46, v68
	s_waitcnt vmcnt(4)
	ds_write_b32 v48, v69
	s_waitcnt vmcnt(3)
	ds_write_b32 v50, v4
	s_waitcnt vmcnt(2)
	ds_write_b32 v52, v70
	s_waitcnt vmcnt(1)
	ds_write_b32 v54, v71
	s_waitcnt vmcnt(0)
	ds_write_b32 v56, v72
	s_cbranch_scc1 .LBB0_1565
; #define LAS __attribute__((address_space(3)))
; __device__ __forceinline__ unsigned pk2(float lo, float hi) { return f2bf(lo) | (f2bf(hi) << 16); }
; __device__ __forceinline__ void transpose_item(const float* W, int K, int N, bf16* WT, int row_off, LAS float* scr, int item, int lane) {
;     ...
;     const int c = lane & 7;
; #pragma unroll
;     for (int j = 0; j < 4; ++j) { const int n = (lane >> 3) + 8 * j; const LAS float* s = scr + (8 * c) * 33 + n;
;         u32x4 o; o.x = pk2(s[0 * 33], s[1 * 33]); o.y = pk2(s[2 * 33], s[3 * 33]); o.z = pk2(s[4 * 33], s[5 * 33]); o.w = pk2(s[6 * 33], s[7 * 33]);
;         *(u32x4*)(WT + (size_t)(row_off + n0 + n) * K + k0 + 8 * c) = o; }
	s_waitcnt lgkmcnt(0)
	ds_read2_b32 v[18:19], v22 offset1:8
	ds_read2_b32 v[32:33], v22 offset0:33 offset1:41
	ds_read2_b32 v[34:35], v22 offset0:66 offset1:74
	ds_read2_b32 v[36:37], v22 offset0:99 offset1:107
	ds_read2_b32 v[38:39], v22 offset0:132 offset1:140
	ds_read2_b32 v[40:41], v22 offset0:165 offset1:173
	s_waitcnt lgkmcnt(5)
	s_waitcnt lgkmcnt(4)
	v_cvt_pk_bf16_f32 v26, v18, v32
	s_waitcnt lgkmcnt(3)
	s_waitcnt lgkmcnt(2)
	ds_read2_b32 v[42:43], v22 offset0:198 offset1:206
	ds_read2_b32 v[44:45], v22 offset0:231 offset1:239
	v_cvt_pk_bf16_f32 v27, v34, v36
	s_waitcnt lgkmcnt(3)
	s_waitcnt lgkmcnt(2)
	v_cvt_pk_bf16_f32 v28, v38, v40
	s_waitcnt lgkmcnt(1)
	s_waitcnt lgkmcnt(0)
	s_nop 0
	s_nop 0
	s_nop 0
	s_lshl_b32 s0, s5, 1
	v_cvt_pk_bf16_f32 v29, v42, v44
	v_or_b32_e32 v3, s4, v21
	v_lshl_add_u64 v[30:31], v[8:9], 0, s[0:1]
	v_lshlrev_b32_e32 v4, 12, v3
	v_bfe_u32 v3, v19, 16, 1
	v_lshl_add_u64 v[46:47], v[30:31], 0, v[4:5]
	v_add3_u32 v3, v19, v3, s11
	v_bfe_u32 v4, v33, 16, 1
	v_lshrrev_b32_e32 v3, 16, v3
	v_add3_u32 v4, v33, v4, s11
	global_store_dwordx4 v[46:47], v[26:29], off
	ds_read2_b32 v[18:19], v22 offset0:16 offset1:24
	s_nop 0
	v_and_or_b32 v26, v4, s12, v3
	s_nop 0
	s_nop 0
	s_nop 0
	s_nop 0
	s_nop 0
	v_cvt_pk_bf16_f32 v27, v35, v37
	v_cvt_pk_bf16_f32 v28, v39, v41
	s_nop 0
	s_nop 0
	v_cvt_pk_bf16_f32 v29, v43, v45
	v_or_b32_e32 v3, s4, v23
	v_lshlrev_b32_e32 v4, 12, v3
	v_lshl_add_u64 v[32:33], v[30:31], 0, v[4:5]
	global_store_dwordx4 v[32:33], v[26:29], off
	ds_read2_b32 v[32:33], v22 offset0:49 offset1:57
	ds_read2_b32 v[34:35], v22 offset0:82 offset1:90
	ds_read2_b32 v[36:37], v22 offset0:115 offset1:123
	s_waitcnt lgkmcnt(3)
	s_nop 0
	s_nop 0
	s_waitcnt lgkmcnt(2)
	ds_read2_b32 v[38:39], v22 offset0:148 offset1:156
	ds_read2_b32 v[40:41], v22 offset0:181 offset1:189
	v_cvt_pk_bf16_f32 v26, v18, v32
	s_waitcnt lgkmcnt(3)
	s_waitcnt lgkmcnt(2)
	ds_read2_b32 v[42:43], v22 offset0:214 offset1:222
	ds_read2_b32 v[44:45], v22 offset0:247 offset1:255
	v_cvt_pk_bf16_f32 v27, v34, v36
	s_waitcnt lgkmcnt(3)
	s_waitcnt lgkmcnt(2)
	v_cvt_pk_bf16_f32 v28, v38, v40
	s_waitcnt lgkmcnt(1)
	s_waitcnt lgkmcnt(0)
	v_cvt_pk_bf16_f32 v29, v42, v44
	v_or_b32_e32 v3, s4, v24
	v_lshlrev_b32_e32 v4, 12, v3
	s_nop 0
	v_lshl_add_u64 v[46:47], v[30:31], 0, v[4:5]
	s_nop 0
	s_nop 0
	s_nop 0
	s_nop 0
	global_store_dwordx4 v[46:47], v[26:29], off
	s_nop 1
	v_cvt_pk_bf16_f32 v26, v19, v33
	s_nop 0
	s_nop 0
	s_nop 0
	s_nop 0
	s_nop 0
	v_cvt_pk_bf16_f32 v27, v35, v37
	v_cvt_pk_bf16_f32 v28, v39, v41
	s_nop 0
	s_nop 0
	v_cvt_pk_bf16_f32 v29, v43, v45
	v_or_b32_e32 v3, s4, v25
	v_lshlrev_b32_e32 v4, 12, v3
	v_lshl_add_u64 v[18:19], v[30:31], 0, v[4:5]
	global_store_dwordx4 v[18:19], v[26:29], off
	s_waitcnt lgkmcnt(0)

; #define LAS __attribute__((address_space(3)))
; #define LDS_WAIT() asm volatile("s_waitcnt lgkmcnt(0)" ::: "memory")
; __device__ __forceinline__ void transpose_item(const float* W, int K, int N, bf16* WT, int row_off, LAS float* scr, int item, int lane) {
;     const int nblk = N / 32, kb = item / nblk, nb = item % nblk, k0 = 64 * kb, n0 = 32 * nb;
; #pragma unroll 8
;     for (int i = 0; i < 32; ++i) { const int kk = 2 * i + (lane >> 5); scr[kk * 33 + (lane & 31)] = W[(size_t)(k0 + kk) * N + n0 + (lane & 31)]; }
;     LDS_WAIT(); asm volatile("" ::: "memory");
.LBB0_1570:
	s_lshl_b32 s13, s0, 1
	s_lshl_b32 s14, s5, 1
	v_or_b32_e32 v28, s14, v4
	s_add_i32 s15, s13, 4
	s_add_i32 s20, s14, 4
	s_add_i32 s21, s13, 8
	s_add_i32 s22, s14, 8
	s_add_i32 s2, s13, 12
	s_add_i32 s23, s14, 12
	s_add_i32 s30, s13, 16
	s_add_i32 s31, s14, 16
	s_add_i32 s33, s13, 20
	s_add_i32 s34, s14, 20
	s_add_i32 s35, s13, 24
	s_add_i32 s36, s14, 24
	s_add_i32 s37, s13, 28
	s_add_i32 s38, s14, 28
	v_or_b32_e32 v26, s13, v3
	v_ashrrev_i32_e32 v29, 31, v28
	v_or_b32_e32 v30, s15, v3
	s_waitcnt vmcnt(5)
	v_or_b32_e32 v32, s20, v4
	v_or_b32_e32 v34, s21, v3
	s_waitcnt vmcnt(4)
	v_or_b32_e32 v36, s22, v4
	v_or_b32_e32 v38, s2, v3
	v_or_b32_e32 v40, s23, v4
	v_or_b32_e32 v42, s30, v3
	v_or_b32_e32 v44, s31, v4
	v_or_b32_e32 v46, s33, v3
	v_or_b32_e32 v48, s34, v4
	v_or_b32_e32 v50, s35, v3
	v_or_b32_e32 v52, s36, v4
	v_or_b32_e32 v54, s37, v3
	v_or_b32_e32 v56, s38, v4
	v_ashrrev_i32_e32 v27, 31, v26
	v_lshlrev_b64 v[28:29], 13, v[28:29]
	v_ashrrev_i32_e32 v33, 31, v32
	v_ashrrev_i32_e32 v31, 31, v30
	v_ashrrev_i32_e32 v37, 31, v36
	v_ashrrev_i32_e32 v35, 31, v34
	v_ashrrev_i32_e32 v41, 31, v40
	v_ashrrev_i32_e32 v39, 31, v38
	v_ashrrev_i32_e32 v45, 31, v44
	v_ashrrev_i32_e32 v43, 31, v42
	v_ashrrev_i32_e32 v49, 31, v48
	v_ashrrev_i32_e32 v47, 31, v46
	v_ashrrev_i32_e32 v53, 31, v52
	v_ashrrev_i32_e32 v51, 31, v50
	v_ashrrev_i32_e32 v57, 31, v56
	v_ashrrev_i32_e32 v55, 31, v54
	v_lshlrev_b64 v[26:27], 13, v[26:27]
	v_lshl_add_u64 v[28:29], v[18:19], 0, v[28:29]
	v_lshlrev_b64 v[30:31], 13, v[30:31]
	v_lshlrev_b64 v[32:33], 13, v[32:33]
	v_lshlrev_b64 v[34:35], 13, v[34:35]
	v_lshlrev_b64 v[36:37], 13, v[36:37]
	v_lshlrev_b64 v[38:39], 13, v[38:39]
	v_lshlrev_b64 v[40:41], 13, v[40:41]
	v_lshlrev_b64 v[42:43], 13, v[42:43]
	v_lshlrev_b64 v[44:45], 13, v[44:45]
	v_lshlrev_b64 v[46:47], 13, v[46:47]
	v_lshlrev_b64 v[48:49], 13, v[48:49]
	v_lshlrev_b64 v[50:51], 13, v[50:51]
	v_lshlrev_b64 v[52:53], 13, v[52:53]
	v_lshlrev_b64 v[54:55], 13, v[54:55]
	v_lshlrev_b64 v[56:57], 13, v[56:57]
	v_lshl_add_u64 v[26:27], v[18:19], 0, v[26:27]
	v_lshl_add_u64 v[32:33], v[18:19], 0, v[32:33]
	v_lshl_add_u64 v[30:31], v[18:19], 0, v[30:31]
	v_lshl_add_u64 v[36:37], v[18:19], 0, v[36:37]
	v_lshl_add_u64 v[34:35], v[18:19], 0, v[34:35]
	v_lshl_add_u64 v[40:41], v[18:19], 0, v[40:41]
	v_lshl_add_u64 v[38:39], v[18:19], 0, v[38:39]
	v_lshl_add_u64 v[44:45], v[18:19], 0, v[44:45]
	v_lshl_add_u64 v[42:43], v[18:19], 0, v[42:43]
	v_lshl_add_u64 v[48:49], v[18:19], 0, v[48:49]
	v_lshl_add_u64 v[46:47], v[18:19], 0, v[46:47]
	v_lshl_add_u64 v[52:53], v[18:19], 0, v[52:53]
	v_lshl_add_u64 v[50:51], v[18:19], 0, v[50:51]
	v_lshl_add_u64 v[56:57], v[18:19], 0, v[56:57]
	v_lshl_add_u64 v[54:55], v[18:19], 0, v[54:55]
	global_load_dword v20, v[28:29], off
	global_load_dword v58, v[26:27], off
	global_load_dword v59, v[32:33], off
	global_load_dword v60, v[30:31], off
	global_load_dword v61, v[36:37], off
	global_load_dword v62, v[34:35], off
	global_load_dword v63, v[40:41], off
	global_load_dword v64, v[38:39], off
	global_load_dword v65, v[44:45], off
	global_load_dword v66, v[42:43], off
	global_load_dword v67, v[48:49], off
	global_load_dword v68, v[46:47], off
	global_load_dword v69, v[52:53], off
	global_load_dword v70, v[50:51], off
	global_load_dword v71, v[56:57], off
	global_load_dword v72, v[54:55], off
	v_or_b32_e32 v28, s13, v1
	v_or_b32_e32 v26, s14, v0
	s_add_i32 s5, s5, 16
	s_add_i32 s0, s0, 16
	s_add_i32 s9, s9, -16
	v_mad_u64_u32 v[26:27], s[28:29], v26, s10, v[2:3]
	v_mad_u64_u32 v[28:29], s[28:29], v28, s10, v[2:3]
	v_or_b32_e32 v27, s15, v1
	v_or_b32_e32 v29, s20, v0
	v_or_b32_e32 v36, s21, v1
	v_or_b32_e32 v34, s22, v0
	v_or_b32_e32 v40, s2, v1
	v_or_b32_e32 v38, s23, v0
	v_or_b32_e32 v44, s30, v1
	v_or_b32_e32 v42, s31, v0
	v_or_b32_e32 v48, s33, v1
	v_or_b32_e32 v46, s34, v0
	v_or_b32_e32 v52, s35, v1
	v_or_b32_e32 v50, s36, v0
	v_or_b32_e32 v56, s37, v1
	v_or_b32_e32 v54, s38, v0
	s_cmp_lg_u32 s9, 0
	v_mad_u64_u32 v[30:31], s[14:15], v29, s10, v[2:3]
	v_mad_u64_u32 v[32:33], s[14:15], v27, s10, v[2:3]
	v_mad_u64_u32 v[34:35], s[14:15], v34, s10, v[2:3]
	v_mad_u64_u32 v[36:37], s[14:15], v36, s10, v[2:3]
	v_mad_u64_u32 v[38:39], s[14:15], v38, s10, v[2:3]
	v_mad_u64_u32 v[40:41], s[14:15], v40, s10, v[2:3]
	v_mad_u64_u32 v[42:43], s[14:15], v42, s10, v[2:3]
	v_mad_u64_u32 v[44:45], s[14:15], v44, s10, v[2:3]
	v_mad_u64_u32 v[46:47], s[14:15], v46, s10, v[2:3]
	v_mad_u64_u32 v[48:49], s[14:15], v48, s10, v[2:3]
	v_mad_u64_u32 v[50:51], s[14:15], v50, s10, v[2:3]
	v_mad_u64_u32 v[52:53], s[14:15], v52, s10, v[2:3]
	v_mad_u64_u32 v[54:55], s[14:15], v54, s10, v[2:3]
	v_mad_u64_u32 v[56:57], s[14:15], v56, s10, v[2:3]
	s_waitcnt vmcnt(15)
	ds_write_b32 v26, v20
	s_waitcnt vmcnt(14)
	ds_write_b32 v28, v58
	s_waitcnt vmcnt(13)
	ds_write_b32 v30, v59
	s_waitcnt vmcnt(12)
	ds_write_b32 v32, v60
	s_waitcnt vmcnt(11)
	ds_write_b32 v34, v61
	s_waitcnt vmcnt(10)
	ds_write_b32 v36, v62
	s_waitcnt vmcnt(9)
	ds_write_b32 v38, v63
	s_waitcnt vmcnt(8)
	ds_write_b32 v40, v64
	s_waitcnt vmcnt(7)
	ds_write_b32 v42, v65
	s_waitcnt vmcnt(6)
	ds_write_b32 v44, v66
	s_waitcnt vmcnt(5)
	ds_write_b32 v46, v67
	s_waitcnt vmcnt(4)
	ds_write_b32 v48, v68
	s_waitcnt vmcnt(3)
	ds_write_b32 v50, v69
	s_waitcnt vmcnt(2)
	ds_write_b32 v52, v70
	s_waitcnt vmcnt(1)
	ds_write_b32 v54, v71
	s_waitcnt vmcnt(0)
	ds_write_b32 v56, v72
	s_cbranch_scc1 .LBB0_1570
; #define LAS __attribute__((address_space(3)))
; #define LDS_WAIT() asm volatile("s_waitcnt lgkmcnt(0)" ::: "memory")
; __device__ __forceinline__ unsigned pk2(float lo, float hi) { return f2bf(lo) | (f2bf(hi) << 16); }
; __device__ __forceinline__ void transpose_item(const float* W, int K, int N, bf16* WT, int row_off, LAS float* scr, int item, int lane) {
;     ...
;     const int c = lane & 7;
; #pragma unroll
;     for (int j = 0; j < 4; ++j) { const int n = (lane >> 3) + 8 * j; const LAS float* s = scr + (8 * c) * 33 + n;
;         u32x4 o; o.x = pk2(s[0 * 33], s[1 * 33]); o.y = pk2(s[2 * 33], s[3 * 33]); o.z = pk2(s[4 * 33], s[5 * 33]); o.w = pk2(s[6 * 33], s[7 * 33]);
;         *(u32x4*)(WT + (size_t)(row_off + n0 + n) * K + k0 + 8 * c) = o; }
;     LDS_WAIT(); asm volatile("" ::: "memory");
	s_waitcnt lgkmcnt(0)
	ds_read2_b32 v[18:19], v22 offset1:8
	ds_read2_b32 v[32:33], v22 offset0:33 offset1:41
	ds_read2_b32 v[34:35], v22 offset0:66 offset1:74
	ds_read2_b32 v[36:37], v22 offset0:99 offset1:107
	ds_read2_b32 v[38:39], v22 offset0:132 offset1:140
	ds_read2_b32 v[40:41], v22 offset0:165 offset1:173
	s_waitcnt lgkmcnt(5)
	s_waitcnt lgkmcnt(4)
	v_cvt_pk_bf16_f32 v26, v18, v32
	s_waitcnt lgkmcnt(3)
	s_waitcnt lgkmcnt(2)
	ds_read2_b32 v[42:43], v22 offset0:198 offset1:206
	ds_read2_b32 v[44:45], v22 offset0:231 offset1:239
	v_cvt_pk_bf16_f32 v27, v34, v36
	s_waitcnt lgkmcnt(3)
	s_waitcnt lgkmcnt(2)
	v_cvt_pk_bf16_f32 v28, v38, v40
	s_waitcnt lgkmcnt(1)
	s_waitcnt lgkmcnt(0)
	s_nop 0
	v_or_b32_e32 v46, s4, v21
	s_ashr_i32 s9, s8, 31
	v_cvt_pk_bf16_f32 v29, v42, v44
	v_ashrrev_i32_e32 v47, 31, v46
	v_bfe_u32 v3, v19, 16, 1
	v_lshl_add_u64 v[30:31], s[8:9], 1, v[10:11]
	v_lshlrev_b64 v[46:47], 12, v[46:47]
	v_add3_u32 v3, v19, v3, s11
	v_bfe_u32 v4, v33, 16, 1
	v_lshl_add_u64 v[46:47], v[30:31], 0, v[46:47]
	v_lshrrev_b32_e32 v3, 16, v3
	v_add3_u32 v4, v33, v4, s11
	global_store_dwordx4 v[46:47], v[26:29], off
	v_or_b32_e32 v18, s4, v23
	v_ashrrev_i32_e32 v19, 31, v18
	v_and_or_b32 v26, v4, s12, v3
	s_nop 0
	s_nop 0
	s_nop 0
	v_cvt_pk_bf16_f32 v27, v35, v37
	v_cvt_pk_bf16_f32 v28, v39, v41
	s_nop 0
	s_nop 0
	v_lshlrev_b64 v[18:19], 12, v[18:19]
	v_cvt_pk_bf16_f32 v29, v43, v45
	ds_read2_b32 v[32:33], v22 offset0:16 offset1:24
	v_lshl_add_u64 v[18:19], v[30:31], 0, v[18:19]
	global_store_dwordx4 v[18:19], v[26:29], off
	ds_read2_b32 v[18:19], v22 offset0:49 offset1:57
	ds_read2_b32 v[34:35], v22 offset0:82 offset1:90
	ds_read2_b32 v[36:37], v22 offset0:115 offset1:123
	s_waitcnt lgkmcnt(3)
	s_nop 0
	s_nop 0
	s_waitcnt lgkmcnt(2)
	ds_read2_b32 v[38:39], v22 offset0:148 offset1:156
	ds_read2_b32 v[40:41], v22 offset0:181 offset1:189
	v_cvt_pk_bf16_f32 v26, v32, v18
	s_waitcnt lgkmcnt(3)
	s_waitcnt lgkmcnt(2)
	ds_read2_b32 v[42:43], v22 offset0:214 offset1:222
	ds_read2_b32 v[44:45], v22 offset0:247 offset1:255
	v_cvt_pk_bf16_f32 v27, v34, v36
	s_waitcnt lgkmcnt(3)
	s_waitcnt lgkmcnt(2)
	v_cvt_pk_bf16_f32 v28, v38, v40
	s_waitcnt lgkmcnt(1)
	s_waitcnt lgkmcnt(0)
	v_or_b32_e32 v46, s4, v24
	v_cvt_pk_bf16_f32 v29, v42, v44
	v_ashrrev_i32_e32 v47, 31, v46
	v_bfe_u32 v3, v33, 16, 1
	v_lshlrev_b64 v[46:47], 12, v[46:47]
	v_add3_u32 v3, v33, v3, s11
	v_bfe_u32 v4, v19, 16, 1
	v_lshl_add_u64 v[46:47], v[30:31], 0, v[46:47]
	v_lshrrev_b32_e32 v3, 16, v3
	v_add3_u32 v4, v19, v4, s11
	global_store_dwordx4 v[46:47], v[26:29], off
	v_or_b32_e32 v18, s4, v25
	v_ashrrev_i32_e32 v19, 31, v18
	v_and_or_b32 v26, v4, s12, v3
	s_nop 0
	s_nop 0
	s_nop 0
	v_cvt_pk_bf16_f32 v27, v35, v37
	v_cvt_pk_bf16_f32 v28, v39, v41
	v_bfe_u32 v3, v43, 16, 1
	v_add3_u32 v3, v43, v3, s11
	v_bfe_u32 v4, v45, 16, 1
	v_lshrrev_b32_e32 v3, 16, v3
	v_add3_u32 v4, v45, v4, s11
	v_lshlrev_b64 v[18:19], 12, v[18:19]
	v_and_or_b32 v29, v4, s12, v3
	v_lshl_add_u64 v[18:19], v[30:31], 0, v[18:19]
	global_store_dwordx4 v[18:19], v[26:29], off
	s_waitcnt lgkmcnt(0)
	s_branch .LBB0_1557

;     ...
;         if (do_ln) {
;             float s = 0.f;
; #pragma unroll
;             for (int j = 0; j < 8; ++j) s += (v[j].x + v[j].y) + (v[j].z + v[j].w);
;             const float mean = wave_sum(s) * (1.f / D); float s2 = 0.f;
; #pragma unroll
;             for (int j = 0; j < 8; ++j) { v[j] = v[j] - mean; s2 += (v[j].x * v[j].x + v[j].y * v[j].y) + (v[j].z * v[j].z + v[j].w * v[j].w); }
;             const float rstd = rsqrtf(wave_sum(s2) * (1.f / D) + LN_EPS);
; #pragma unroll
;             for (int j = 0; j < 8; ++j) { const f32x4 gg = *(const f32x4*)(lng + lane * 4 + 256 * j), bb = *(const f32x4*)(lnb + lane * 4 + 256 * j);
;                 v[j] = v[j] * rstd * gg + bb; *(f32x4*)(dst + lane * 4 + 256 * j) = v[j]; }
.LBB0_1833:
	v_mov_b32_e32 v64, v56
	v_mov_b32_e32 v65, v60
	v_mov_b32_e32 v66, v57
	v_mov_b32_e32 v67, v61
	v_pk_add_f32 v[64:65], v[64:65], v[66:67]
	v_mov_b32_e32 v66, v58
	v_mov_b32_e32 v67, v62
	v_mov_b32_e32 v102, v59
	v_mov_b32_e32 v103, v63
	v_pk_add_f32 v[66:67], v[66:67], v[102:103]
	v_mov_b32_e32 v102, v52
	v_pk_add_f32 v[64:65], v[64:65], v[66:67]
	v_mov_b32_e32 v66, v53
	v_mov_b32_e32 v67, v54
	v_mov_b32_e32 v103, v55
	v_pk_add_f32 v[66:67], v[66:67], v[102:103]
	v_add_f32_e32 v65, 0, v65
	v_pk_add_f32 v[66:67], v[66:67], v[66:67] op_sel_hi:[0,1]
	v_add_f32_e32 v65, v64, v65
	v_add_f32_e32 v103, v48, v49
	v_add_f32_e32 v105, v50, v51
	v_mov_b32_e32 v102, v44
	v_mov_b32_e32 v104, v45
	v_mov_b32_e32 v66, v46
	v_mov_b32_e32 v64, v47
	v_pk_add_f32 v[102:103], v[102:103], v[104:105]
	v_pk_add_f32 v[64:65], v[66:67], v[64:65]
	v_mov_b32_e32 v66, v41
	v_pk_add_f32 v[64:65], v[102:103], v[64:65]
	v_mov_b32_e32 v67, v42
	v_mov_b32_e32 v102, v40
	v_mov_b32_e32 v103, v43
	v_pk_add_f32 v[66:67], v[66:67], v[102:103]
	v_pk_add_f32 v[64:65], v[64:65], v[64:65] op_sel_hi:[0,1]
	v_pk_add_f32 v[66:67], v[66:67], v[66:67] op_sel_hi:[0,1]
	v_add_f32_e32 v103, v36, v37
	v_add_f32_e32 v105, v38, v39
	v_mov_b32_e32 v102, v32
	v_mov_b32_e32 v104, v33
	v_mov_b32_e32 v66, v34
	v_mov_b32_e32 v64, v35
	v_pk_add_f32 v[102:103], v[102:103], v[104:105]
	v_pk_add_f32 v[64:65], v[66:67], v[64:65]
	s_cmpk_gt_i32 s20, 0x1fff
	v_pk_add_f32 v[64:65], v[102:103], v[64:65]
	s_cselect_b32 s2, 0xc000, 0
	v_add_f32_e32 v64, v64, v65
	ds_bpermute_b32 v65, v94, v64
	s_add_u32 s26, s3, s2
	s_addc_u32 s27, s6, 0
	s_add_u32 s8, s8, s10
	s_addc_u32 s9, s9, s11
	s_waitcnt lgkmcnt(0)
	v_add_f32_e32 v64, v64, v65
	ds_bpermute_b32 v65, v95, v64
	s_mov_b32 s20, s25
	s_waitcnt lgkmcnt(0)
	v_add_f32_e32 v64, v64, v65
	ds_bpermute_b32 v65, v96, v64
	s_waitcnt lgkmcnt(0)
	v_add_f32_e32 v64, v64, v65
	ds_bpermute_b32 v65, v97, v64
	s_waitcnt lgkmcnt(0)
	v_add_f32_e32 v64, v64, v65
	ds_bpermute_b32 v65, v98, v64
	s_waitcnt lgkmcnt(0)
	v_add_f32_e32 v64, v64, v65
	ds_bpermute_b32 v65, v99, v64
	s_waitcnt lgkmcnt(0)
	v_add_f32_e32 v101, v64, v65
	v_fmamk_f32 v61, v101, 0xba000000, v61
	v_fmamk_f32 v57, v101, 0xba000000, v57
	v_fmamk_f32 v67, v101, 0xba000000, v63
	v_fmamk_f32 v66, v101, 0xba000000, v62
	v_fmac_f32_e32 v60, 0xba000000, v101
	v_fmamk_f32 v103, v101, 0xba000000, v59
	v_fmac_f32_e32 v56, 0xba000000, v101
	v_mov_b32_e32 v62, v61
	v_mov_b32_e32 v63, v57
	v_fmamk_f32 v102, v101, 0xba000000, v58
	v_mov_b32_e32 v58, v60
	v_mov_b32_e32 v59, v56
	v_pk_mul_f32 v[62:63], v[62:63], v[62:63]
	v_mov_b32_e32 v64, v67
	v_mov_b32_e32 v65, v103
	v_pk_fma_f32 v[58:59], v[58:59], v[58:59], v[62:63]
	v_mov_b32_e32 v62, v66
	v_mov_b32_e32 v63, v102
	v_pk_mul_f32 v[64:65], v[64:65], v[64:65]
	v_fmamk_f32 v53, v101, 0xba000000, v53
	v_pk_fma_f32 v[62:63], v[62:63], v[62:63], v[64:65]
	v_fmamk_f32 v52, v101, 0xba000000, v52
	v_fmamk_f32 v55, v101, 0xba000000, v55
	v_fmac_f32_e32 v54, 0xba000000, v101
	v_pk_add_f32 v[58:59], v[58:59], v[62:63]
	v_pk_mul_f32 v[62:63], v[54:55], v[54:55]
	v_pk_mul_f32 v[64:65], v[52:53], v[52:53]
	v_fmac_f32_e32 v50, 0xba000000, v101
	v_pk_mov_b32 v[104:105], v[64:65], v[62:63] op_sel:[1,0]
	v_mov_b32_e32 v65, v63
	v_pk_add_f32 v[62:63], v[104:105], v[64:65]
	v_fmamk_f32 v104, v101, 0xba000000, v48
	v_fmamk_f32 v105, v101, 0xba000000, v49
	v_mul_f32_e32 v48, v104, v104
	v_pk_fma_f32 v[48:49], v[104:105], v[104:105], v[48:49] op_sel_hi:[1,1,0]
	v_fmamk_f32 v51, v101, 0xba000000, v51
	v_mul_f32_e32 v48, v50, v50
	v_pk_add_f32 v[58:59], v[58:59], v[58:59] op_sel_hi:[0,1]
	v_pk_add_f32 v[62:63], v[62:63], v[62:63] op_sel_hi:[0,1]
	v_pk_fma_f32 v[64:65], v[50:51], v[50:51], v[48:49] op_sel_hi:[1,1,0]
	v_fmamk_f32 v107, v101, 0xba000000, v47
	v_fmamk_f32 v106, v101, 0xba000000, v46
	v_fmamk_f32 v45, v101, 0xba000000, v45
	v_fmac_f32_e32 v44, 0xba000000, v101
	v_mul_f32_e32 v48, v44, v44
	v_mul_f32_e32 v64, v45, v45
	v_mul_f32_e32 v62, v106, v106
	v_mul_f32_e32 v58, v107, v107
	v_pk_add_f32 v[46:47], v[48:49], v[64:65]
	v_pk_add_f32 v[48:49], v[62:63], v[58:59]
	v_fmamk_f32 v41, v101, 0xba000000, v41
	v_pk_add_f32 v[46:47], v[46:47], v[48:49]
	v_fmamk_f32 v40, v101, 0xba000000, v40
	v_pk_add_f32 v[58:59], v[46:47], v[46:47] op_sel_hi:[0,1]
	global_load_dwordx4 v[46:49], v[70:71], off
	global_load_dwordx4 v[62:65], v[72:73], off
	v_fmamk_f32 v43, v101, 0xba000000, v43
	v_fmac_f32_e32 v42, 0xba000000, v101
	v_pk_mul_f32 v[108:109], v[42:43], v[42:43]
	v_pk_mul_f32 v[110:111], v[40:41], v[40:41]
	v_fmac_f32_e32 v38, 0xba000000, v101
	v_pk_mov_b32 v[112:113], v[110:111], v[108:109] op_sel:[1,0]
	v_mov_b32_e32 v111, v109
	v_pk_add_f32 v[108:109], v[112:113], v[110:111]
	v_fmamk_f32 v110, v101, 0xba000000, v36
	v_fmamk_f32 v111, v101, 0xba000000, v37
	v_mul_f32_e32 v36, v110, v110
	v_pk_fma_f32 v[36:37], v[110:111], v[110:111], v[36:37] op_sel_hi:[1,1,0]
	v_fmamk_f32 v39, v101, 0xba000000, v39
	v_mul_f32_e32 v36, v38, v38
	v_pk_add_f32 v[108:109], v[108:109], v[108:109] op_sel_hi:[0,1]
	v_pk_fma_f32 v[112:113], v[38:39], v[38:39], v[36:37] op_sel_hi:[1,1,0]
	v_fmamk_f32 v115, v101, 0xba000000, v35
	v_fmamk_f32 v114, v101, 0xba000000, v34
	v_fmamk_f32 v33, v101, 0xba000000, v33
	v_fmac_f32_e32 v32, 0xba000000, v101
	v_mul_f32_e32 v36, v32, v32
	v_mul_f32_e32 v112, v33, v33
	v_mul_f32_e32 v108, v114, v114
	v_mul_f32_e32 v58, v115, v115
	v_pk_add_f32 v[34:35], v[36:37], v[112:113]
	v_pk_add_f32 v[36:37], v[108:109], v[58:59]
	v_lshl_add_u64 v[108:109], s[4:5], 0, v[90:91]
	v_pk_add_f32 v[34:35], v[34:35], v[36:37]
	s_add_u32 s4, s4, s10
	v_add_f32_e32 v34, v34, v35
	ds_bpermute_b32 v35, v94, v34
	s_addc_u32 s5, s5, s11
	s_waitcnt lgkmcnt(0)
; __device__ __forceinline__ unsigned pk2(float lo, float hi) { return f2bf(lo) | (f2bf(hi) << 16); }
;     ...
;             for (int j = 0; j < 8; ++j) { v[j] = v[j] - mean; s2 += (v[j].x * v[j].x + v[j].y * v[j].y) + (v[j].z * v[j].z + v[j].w * v[j].w); }
;             const float rstd = rsqrtf(wave_sum(s2) * (1.f / D) + LN_EPS);
; #pragma unroll
;             for (int j = 0; j < 8; ++j) { const f32x4 gg = *(const f32x4*)(lng + lane * 4 + 256 * j), bb = *(const f32x4*)(lnb + lane * 4 + 256 * j);
;                 v[j] = v[j] * rstd * gg + bb; *(f32x4*)(dst + lane * 4 + 256 * j) = v[j]; }
;         }
;         if (do_mod) {
;             const float* sh = modl + mv * NMOD + shc * D; const float* sc = modl + mv * NMOD + scc * D;
; #pragma unroll
;             for (int j = 0; j < 8; ++j) { const f32x4 s1 = *(const f32x4*)(sc + lane * 4 + 256 * j), h1 = *(const f32x4*)(sh + lane * 4 + 256 * j);
;                 const f32x4 a = v[j] * (s1 + 1.f) + h1; u32x2 o; o.x = pk2(a.x, a.y); o.y = pk2(a.z, a.w);
;                 *(u32x2*)(aout + (size_t)m * D + lane * 4 + 256 * j) = o; }
	v_add_f32_e32 v34, v34, v35
	ds_bpermute_b32 v35, v95, v34
	s_waitcnt lgkmcnt(0)
	v_add_f32_e32 v34, v34, v35
	ds_bpermute_b32 v35, v96, v34
	s_waitcnt lgkmcnt(0)
	v_add_f32_e32 v34, v34, v35
	ds_bpermute_b32 v35, v97, v34
	s_waitcnt lgkmcnt(0)
	v_add_f32_e32 v34, v34, v35
	ds_bpermute_b32 v35, v98, v34
	s_waitcnt lgkmcnt(0)
	v_add_f32_e32 v34, v34, v35
	ds_bpermute_b32 v35, v99, v34
	s_waitcnt lgkmcnt(0)
	v_add_f32_e32 v34, v34, v35
	v_fmamk_f32 v34, v34, 0x3a000000, v100
	v_mul_f32_e32 v35, 0x4b800000, v34
	v_cmp_gt_f32_e32 vcc, s1, v34
	s_nop 1
	v_cndmask_b32_e32 v34, v34, v35, vcc
	v_rsq_f32_e32 v34, v34
	s_nop 0
	v_mul_f32_e32 v35, 0x45800000, v34
	v_cndmask_b32_e32 v112, v34, v35, vcc
	v_pk_mul_f32 v[34:35], v[60:61], v[112:113] op_sel_hi:[1,0]
	v_pk_mul_f32 v[36:37], v[66:67], v[112:113] op_sel_hi:[1,0]
	s_waitcnt vmcnt(0)
	v_pk_fma_f32 v[46:47], v[46:47], v[34:35], v[62:63]
	v_pk_fma_f32 v[48:49], v[48:49], v[36:37], v[64:65]
	global_store_dwordx4 v[108:109], v[46:49], off
	global_load_dwordx4 v[34:37], v[70:71], off offset:1024
	global_load_dwordx4 v[58:61], v[72:73], off offset:1024
	v_pk_mul_f32 v[62:63], v[102:103], v[112:113] op_sel_hi:[1,0]
	v_pk_mul_f32 v[56:57], v[56:57], v[112:113] op_sel_hi:[1,0]
	v_pk_mul_f32 v[54:55], v[54:55], v[112:113] op_sel_hi:[1,0]
	v_pk_mul_f32 v[52:53], v[52:53], v[112:113] op_sel_hi:[1,0]
	v_pk_mul_f32 v[50:51], v[50:51], v[112:113] op_sel_hi:[1,0]
	v_pk_mul_f32 v[64:65], v[104:105], v[112:113] op_sel_hi:[1,0]
	v_pk_mul_f32 v[104:105], v[106:107], v[112:113] op_sel_hi:[1,0]
	v_pk_mul_f32 v[44:45], v[44:45], v[112:113] op_sel_hi:[1,0]
	v_pk_mul_f32 v[42:43], v[42:43], v[112:113] op_sel_hi:[1,0]
	v_pk_mul_f32 v[40:41], v[40:41], v[112:113] op_sel_hi:[1,0]
	v_pk_mul_f32 v[38:39], v[38:39], v[112:113] op_sel_hi:[1,0]
	v_pk_mul_f32 v[32:33], v[32:33], v[112:113] op_sel_hi:[1,0]
	s_waitcnt vmcnt(0)
	v_pk_fma_f32 v[56:57], v[34:35], v[56:57], v[58:59]
	v_pk_fma_f32 v[58:59], v[36:37], v[62:63], v[60:61]
	global_store_dwordx4 v[108:109], v[56:59], off offset:1024
	global_load_dwordx4 v[34:37], v[70:71], off offset:2048
	global_load_dwordx4 v[60:63], v[72:73], off offset:2048
	s_waitcnt vmcnt(0)
	v_pk_fma_f32 v[52:53], v[34:35], v[52:53], v[60:61]
	v_pk_fma_f32 v[54:55], v[36:37], v[54:55], v[62:63]
	global_store_dwordx4 v[108:109], v[52:55], off offset:2048
	global_load_dwordx4 v[34:37], v[70:71], off offset:3072
	global_load_dwordx4 v[60:63], v[72:73], off offset:3072
	s_waitcnt vmcnt(0)
	v_pk_fma_f32 v[60:61], v[34:35], v[64:65], v[60:61]
	v_pk_fma_f32 v[62:63], v[36:37], v[50:51], v[62:63]
	global_store_dwordx4 v[108:109], v[60:63], off offset:3072
	global_load_dwordx4 v[34:37], v[74:75], off
	global_load_dwordx4 v[64:67], v[76:77], off
	v_add_co_u32_e32 v50, vcc, s7, v108
	s_waitcnt vmcnt(0)
	v_pk_fma_f32 v[102:103], v[34:35], v[44:45], v[64:65]
	v_addc_co_u32_e32 v51, vcc, 0, v109, vcc
	v_pk_fma_f32 v[104:105], v[36:37], v[104:105], v[66:67]
	global_store_dwordx4 v[50:51], v[102:105], off
	global_load_dwordx4 v[34:37], v[78:79], off
	global_load_dwordx4 v[64:67], v[80:81], off
	v_pk_mul_f32 v[44:45], v[110:111], v[112:113] op_sel_hi:[1,0]
	s_waitcnt vmcnt(0)
	v_pk_fma_f32 v[40:41], v[34:35], v[40:41], v[64:65]
	v_pk_fma_f32 v[42:43], v[36:37], v[42:43], v[66:67]
	global_store_dwordx4 v[50:51], v[40:43], off offset:1024
	global_load_dwordx4 v[34:37], v[82:83], off
	global_load_dwordx4 v[64:67], v[84:85], off
	s_waitcnt vmcnt(0)
	v_pk_fma_f32 v[34:35], v[34:35], v[44:45], v[64:65]
	v_pk_fma_f32 v[36:37], v[36:37], v[38:39], v[66:67]
	global_store_dwordx4 v[50:51], v[34:37], off offset:2048
	global_load_dwordx4 v[64:67], v[86:87], off
	global_load_dwordx4 v[106:109], v[88:89], off
	v_lshl_add_u64 v[38:39], s[26:27], 0, v[68:69]
	v_add_co_u32_e32 v116, vcc, s23, v38
	v_pk_mul_f32 v[44:45], v[114:115], v[112:113] op_sel_hi:[1,0]
	s_nop 0
	v_addc_co_u32_e32 v117, vcc, 0, v39, vcc
	v_lshl_add_u64 v[114:115], v[38:39], 0, s[14:15]
	s_waitcnt vmcnt(0)
	v_pk_fma_f32 v[64:65], v[64:65], v[32:33], v[106:107]
	v_pk_fma_f32 v[66:67], v[66:67], v[44:45], v[108:109]
	global_store_dwordx4 v[50:51], v[64:67], off offset:3072
	v_add_co_u32_e32 v32, vcc, s24, v38
	global_load_dwordx4 v[106:109], v[116:117], off offset:-4096
	s_nop 0
	v_addc_co_u32_e32 v33, vcc, 0, v39, vcc
	global_load_dwordx4 v[110:113], v[32:33], off offset:-4096
	v_lshl_add_u64 v[38:39], v[38:39], 0, s[16:17]
	s_andn2_b64 vcc, exec, s[18:19]
	s_waitcnt vmcnt(1)
	v_pk_add_f32 v[44:45], v[108:109], 1.0 op_sel_hi:[1,0]
	v_pk_add_f32 v[50:51], v[106:107], 1.0 op_sel_hi:[1,0]
	s_waitcnt vmcnt(0)
	v_pk_fma_f32 v[44:45], v[44:45], v[48:49], v[112:113]
	v_pk_fma_f32 v[46:47], v[50:51], v[46:47], v[110:111]
	v_bfe_u32 v50, v44, 16, 1
	v_bfe_u32 v51, v45, 16, 1
	v_add3_u32 v44, v44, v50, s21
	v_add3_u32 v45, v45, v51, s21
	s_nop 0
	v_lshrrev_b32_e32 v48, 16, v44
	v_cvt_pk_bf16_f32 v44, v46, v47
	v_and_or_b32 v45, v45, s22, v48
	global_store_dwordx2 v[92:93], v[44:45], off
	global_load_dwordx4 v[44:47], v[114:115], off offset:1024
	s_nop 0
	global_load_dwordx4 v[48:51], v[38:39], off offset:1024
	s_waitcnt vmcnt(1)
; __device__ __forceinline__ unsigned pk2(float lo, float hi) { return f2bf(lo) | (f2bf(hi) << 16); }
;     ...
;         if (do_mod) {
;             const float* sh = modl + mv * NMOD + shc * D; const float* sc = modl + mv * NMOD + scc * D;
; #pragma unroll
;             for (int j = 0; j < 8; ++j) { const f32x4 s1 = *(const f32x4*)(sc + lane * 4 + 256 * j), h1 = *(const f32x4*)(sh + lane * 4 + 256 * j);
;                 const f32x4 a = v[j] * (s1 + 1.f) + h1; u32x2 o; o.x = pk2(a.x, a.y); o.y = pk2(a.z, a.w);
;                 *(u32x2*)(aout + (size_t)m * D + lane * 4 + 256 * j) = o; }
;         }
	v_pk_add_f32 v[46:47], v[46:47], 1.0 op_sel_hi:[1,0]
	v_pk_add_f32 v[44:45], v[44:45], 1.0 op_sel_hi:[1,0]
	s_waitcnt vmcnt(0)
	v_pk_fma_f32 v[46:47], v[58:59], v[46:47], v[50:51]
	v_pk_fma_f32 v[44:45], v[56:57], v[44:45], v[48:49]
	s_nop 0
	s_nop 0
	v_cvt_pk_bf16_f32 v44, v44, v45
	v_cvt_pk_bf16_f32 v45, v46, v47
	global_store_dwordx2 v[92:93], v[44:45], off offset:512
	global_load_dwordx4 v[44:47], v[114:115], off offset:2048
	s_nop 0
	global_load_dwordx4 v[48:51], v[38:39], off offset:2048
	v_mov_b64_e32 v[58:59], v[10:11]
	v_mov_b64_e32 v[56:57], v[8:9]
	s_waitcnt vmcnt(1)
	v_pk_add_f32 v[46:47], v[46:47], 1.0 op_sel_hi:[1,0]
	v_pk_add_f32 v[44:45], v[44:45], 1.0 op_sel_hi:[1,0]
	s_waitcnt vmcnt(0)
	v_pk_fma_f32 v[46:47], v[54:55], v[46:47], v[50:51]
	v_pk_fma_f32 v[44:45], v[52:53], v[44:45], v[48:49]
	s_nop 0
	s_nop 0
	v_cvt_pk_bf16_f32 v44, v44, v45
	v_cvt_pk_bf16_f32 v45, v46, v47
	global_store_dwordx2 v[92:93], v[44:45], off offset:1024
	global_load_dwordx4 v[44:47], v[114:115], off offset:3072
	s_nop 0
	global_load_dwordx4 v[48:51], v[38:39], off offset:3072
	v_mov_b64_e32 v[54:55], v[6:7]
	v_mov_b64_e32 v[52:53], v[4:5]
	s_waitcnt vmcnt(1)
	v_pk_add_f32 v[38:39], v[46:47], 1.0 op_sel_hi:[1,0]
	v_pk_add_f32 v[44:45], v[44:45], 1.0 op_sel_hi:[1,0]
	s_waitcnt vmcnt(0)
	v_pk_fma_f32 v[38:39], v[62:63], v[38:39], v[50:51]
	v_pk_fma_f32 v[44:45], v[60:61], v[44:45], v[48:49]
	v_bfe_u32 v48, v38, 16, 1
	v_bfe_u32 v49, v39, 16, 1
	v_add3_u32 v38, v38, v48, s21
	v_add3_u32 v39, v39, v49, s21
	v_lshrrev_b32_e32 v46, 16, v38
	v_cvt_pk_bf16_f32 v38, v44, v45
	v_and_or_b32 v39, v39, s22, v46
	global_store_dwordx2 v[92:93], v[38:39], off offset:1536
	global_load_dwordx4 v[44:47], v[116:117], off
	global_load_dwordx4 v[48:51], v[32:33], off
	v_mov_b64_e32 v[62:63], v[14:15]
	v_mov_b64_e32 v[60:61], v[12:13]
	s_waitcnt vmcnt(1)
	v_pk_add_f32 v[38:39], v[46:47], 1.0 op_sel_hi:[1,0]
	v_pk_add_f32 v[44:45], v[44:45], 1.0 op_sel_hi:[1,0]
	s_waitcnt vmcnt(0)
	v_pk_fma_f32 v[38:39], v[104:105], v[38:39], v[50:51]
	v_pk_fma_f32 v[44:45], v[102:103], v[44:45], v[48:49]
	v_bfe_u32 v48, v38, 16, 1
	v_bfe_u32 v49, v39, 16, 1
	v_add3_u32 v38, v38, v48, s21
	v_add3_u32 v39, v39, v49, s21
	v_lshrrev_b32_e32 v46, 16, v38
	v_cvt_pk_bf16_f32 v38, v44, v45
	v_and_or_b32 v39, v39, s22, v46
	global_store_dwordx2 v[92:93], v[38:39], off offset:2048
	global_load_dwordx4 v[44:47], v[116:117], off offset:1024
	global_load_dwordx4 v[48:51], v[32:33], off offset:1024
	s_waitcnt vmcnt(1)
	v_pk_add_f32 v[38:39], v[46:47], 1.0 op_sel_hi:[1,0]
	v_pk_add_f32 v[44:45], v[44:45], 1.0 op_sel_hi:[1,0]
	s_waitcnt vmcnt(0)
	v_pk_fma_f32 v[38:39], v[42:43], v[38:39], v[50:51]
	v_pk_fma_f32 v[40:41], v[40:41], v[44:45], v[48:49]
	v_bfe_u32 v44, v38, 16, 1
	v_bfe_u32 v45, v39, 16, 1
	v_add3_u32 v38, v38, v44, s21
	v_add3_u32 v39, v39, v45, s21
	s_nop 0
	v_lshrrev_b32_e32 v42, 16, v38
	v_cvt_pk_bf16_f32 v38, v40, v41
	v_and_or_b32 v39, v39, s22, v42
	global_store_dwordx2 v[92:93], v[38:39], off offset:2560
	global_load_dwordx4 v[38:41], v[116:117], off offset:2048
	s_nop 0
	global_load_dwordx4 v[42:45], v[32:33], off offset:2048
	v_mov_b64_e32 v[50:51], v[2:3]
	v_mov_b64_e32 v[48:49], v[0:1]
	s_waitcnt vmcnt(1)
	v_pk_add_f32 v[40:41], v[40:41], 1.0 op_sel_hi:[1,0]
	v_pk_add_f32 v[38:39], v[38:39], 1.0 op_sel_hi:[1,0]
	s_waitcnt vmcnt(0)
	v_pk_fma_f32 v[36:37], v[36:37], v[40:41], v[44:45]
	v_pk_fma_f32 v[34:35], v[34:35], v[38:39], v[42:43]
	v_cvt_pk_bf16_f32 v34, v34, v35
	v_cvt_pk_bf16_f32 v35, v36, v37
	global_store_dwordx2 v[92:93], v[34:35], off offset:3072
	global_load_dwordx4 v[102:105], v[116:117], off offset:3072
	global_load_dwordx4 v[106:109], v[32:33], off offset:3072
	v_mov_b64_e32 v[34:35], v[18:19]
	v_mov_b64_e32 v[38:39], v[22:23]
	v_mov_b64_e32 v[42:43], v[26:27]
	v_mov_b64_e32 v[46:47], v[30:31]
	v_mov_b64_e32 v[32:33], v[16:17]
	v_mov_b64_e32 v[36:37], v[20:21]
	v_mov_b64_e32 v[40:41], v[24:25]
	v_mov_b64_e32 v[44:45], v[28:29]
	s_waitcnt vmcnt(1)
	v_pk_add_f32 v[104:105], v[104:105], 1.0 op_sel_hi:[1,0]
	v_pk_add_f32 v[102:103], v[102:103], 1.0 op_sel_hi:[1,0]
	s_waitcnt vmcnt(0)
	v_pk_fma_f32 v[66:67], v[66:67], v[104:105], v[108:109]
	v_pk_fma_f32 v[64:65], v[64:65], v[102:103], v[106:107]
	v_bfe_u32 v103, v66, 16, 1
	v_bfe_u32 v101, v64, 16, 1
	v_bfe_u32 v102, v65, 16, 1
	v_bfe_u32 v104, v67, 16, 1
	v_add3_u32 v64, v64, v101, s21
	v_add3_u32 v66, v66, v103, s21
	v_add3_u32 v65, v65, v102, s21
	v_add3_u32 v67, v67, v104, s21
	v_lshrrev_b32_e32 v64, 16, v64
	v_lshrrev_b32_e32 v66, 16, v66
	v_and_or_b32 v64, v65, s22, v64
	v_and_or_b32 v65, v67, s22, v66
	global_store_dwordx2 v[92:93], v[64:65], off offset:3584
	v_lshl_add_u64 v[92:93], v[92:93], 0, s[12:13]
	s_cbranch_vccz .LBB0_1836
